# load segments issue all fragment ds_reads first (before the address SALU and the LDS-DMAs); on top of the v54 stack
# speedup vs baseline: 1.0107x; 1.0107x over previous
; #define PG8_STAGE(bufoff, gbase, voff) do { _Pragma("unroll") for (int _i = 0; _i < 2; ++_i) \
;         __builtin_amdgcn_global_load_lds((const unsigned*)((const char*)(gbase) + (voff)[_i]), (LAS unsigned*)(lds + (bufoff) + ldsw + _i * 8192), 16, 0, 0); } while (0)
; #define PG8_LDA(dst, b, h) do { _Pragma("unroll") for (int m = 0; m < 4; ++m) _Pragma("unroll") for (int k = 0; k < 2; ++k) dst[m][k] = *(const LAS bf16x8*)(lds + PG8_SA(b, h) + aoff + m * 2048 + k * 1024); } while (0)
; #define PG8_LDB(dst, b, h) do { _Pragma("unroll") for (int n = 0; n < 2; ++n) _Pragma("unroll") for (int k = 0; k < 2; ++k) dst[n][k] = *(const LAS bf16x8*)(lds + PG8_SB(b, h) + boff + n * 2048 + k * 1024); } while (0)
; #define PG8_WAIT_V(n) asm volatile("s_waitcnt vmcnt(" #n ")" ::: "memory")
; #define PG8_WAIT_L(n) asm volatile("s_waitcnt lgkmcnt(" #n ")" ::: "memory")
; #define PG8_BAR __builtin_amdgcn_s_barrier()
; #define PG8_SCHED __builtin_amdgcn_sched_barrier(0)
; template <class Epi, class Sched, bool ABLK = false, bool ALIGN_EPI = true, bool SP2 = true, bool BBLK = true>
; __device__ __forceinline__ void gemm_phase(LAS unsigned char* lds, const Gemm g, const Sched& S, const Epi& E) {
;     ...
;         const bool has_next = S.next(ui + 1, nxt);
;         const int nt = cur.nt;
;         const char* nuA = has_next ? a_unit(nxt) : uA; const int ntbA = has_next ? nxt.k0 / BK : tbA; const char* nB = has_next ? (const char*)g.Bt + (size_t)nxt.pn * tstepB + b_k0(nxt.k0) : cB;
;         for (int t = 0; t < nt; t += 2) {
;             const bool last = (t == nt - 2);
;             const char* a1 = a_tile(uA, tbA + t + 1);
;             const char* a2 = last ? a_tile(nuA, ntbA) : a_tile(uA, tbA + t + 2); const char* b2 = last ? nB : cB + (size_t)(t + 2) * kstepB;
;             const char* a3 = last ? a_tile(nuA, ntbA + 1) : a_tile(uA, tbA + t + 3); const char* b3 = b2 + kstepB;
;             if (last && has_next) S.a_ready(nxt);
;             if constexpr (SP2) {
;             PG8_LDB(B0, 0, 0); PG8_LDB(B1, 0, 1); PG8_SCHED; PG8_LDA(At, 0, 0); PG8_STAGE(PG8_SA(1, 1), a1 + hstepA, voffA);
;             PG8_WAIT_V(8); PG8_WAIT_L(0); PG8_BAR; PG8_MMA(0, 0, At, B0); PG8_MMA(0, 1, At, B1); PG8_BAR; PG8_SCHED;
;             PG8_LDA(At, 0, 1); PG8_STAGE(PG8_SB(0, 0), b2, voffB); PG8_STAGE(PG8_SB(0, 1), b2 + hstepB, voffB); PG8_STAGE(PG8_SA(0, 0), a2, voffA);
.LBB0_349:
	ds_read_b128 v[152:155], v148
	ds_read_b128 v[156:159], v148 offset:1024
	ds_read_b128 v[160:163], v148 offset:2048
	ds_read_b128 v[164:167], v148 offset:3072
	ds_read_b128 v[168:171], v149
	ds_read_b128 v[172:175], v149 offset:1024
	ds_read_b128 v[176:179], v149 offset:2048
	ds_read_b128 v[180:183], v149 offset:3072
	ds_read_b128 v[184:187], v150
	ds_read_b128 v[188:191], v150 offset:1024
	ds_read_b128 v[192:195], v150 offset:2048
	ds_read_b128 v[196:199], v150 offset:3072
	ds_read_b128 v[200:203], v150 offset:4096
	ds_read_b128 v[204:207], v150 offset:5120
	ds_read_b128 v[208:211], v150 offset:6144
	ds_read_b128 v[212:215], v150 offset:7168
	s_ashr_i32 s9, s8, 31
	s_lshl_b64 s[4:5], s[8:9], 20
	s_add_u32 s12, s36, s4
	s_addc_u32 s13, s37, s5
	s_and_b64 s[4:5], s[14:15], exec
	s_cselect_b32 s4, s13, s25
	s_cselect_b32 s5, s12, s24
	s_ashr_i32 s11, s10, 31
	s_lshl_b64 s[18:19], s[10:11], 20
	s_add_u32 s18, s0, s18
	s_addc_u32 s19, s1, s19
	s_and_b64 s[28:29], s[14:15], exec
	s_cselect_b32 s9, s19, s27
	s_cselect_b32 s11, s18, s26
	s_add_u32 s50, s5, 0x80
	s_addc_u32 s51, s4, 0
	s_add_u32 s52, s26, 0x10000
	v_mov_b32_e32 v2, 0
	s_addc_u32 s53, s27, 0
	v_lshl_add_u64 v[142:143], s[24:25], 0, v[138:139]
	v_lshl_add_u64 v[144:145], s[24:25], 0, v[140:141]
	s_mov_b32 s54, -2
	s_mov_b64 s[26:27], 0
	s_add_u32 s28, s24, s26
	s_addc_u32 s29, s25, s27
	s_add_u32 s34, s28, 0x100
	s_addc_u32 s35, s29, 0
	s_add_u32 s28, s28, 0x180
	s_addc_u32 s29, s29, 0
	s_cmpk_eq_i32 s26, 0xf00
	s_cselect_b32 s29, s51, s29
	s_cselect_b32 s28, s50, s28
	s_cselect_b32 s31, s9, s53
	s_cselect_b32 s30, s11, s52
	s_cselect_b32 s35, s4, s35
	s_cselect_b32 s34, s5, s34
	s_mov_b32 m0, s49
	v_lshl_add_u64 v[216:217], v[142:143], 0, s[26:27]
	global_load_lds_dwordx4 v[216:217], off
	v_lshl_add_u64 v[216:217], v[144:145], 0, s[26:27]
	s_add_i32 m0, s21, 0xe000
	s_nop 0
	global_load_lds_dwordx4 v[216:217], off
	s_waitcnt vmcnt(8) lgkmcnt(0)
	s_barrier
	v_mfma_f32_16x16x32_bf16 v[122:125], v[152:155], v[184:187], 0
	v_mfma_f32_16x16x32_bf16 v[118:121], v[160:163], v[184:187], 0
	v_mfma_f32_16x16x32_bf16 v[106:109], v[152:155], v[192:195], 0
	v_mfma_f32_16x16x32_bf16 v[102:105], v[160:163], v[192:195], 0
	v_mfma_f32_16x16x32_bf16 v[90:93], v[152:155], v[200:203], 0
	v_mfma_f32_16x16x32_bf16 v[86:89], v[160:163], v[200:203], 0
	v_mfma_f32_16x16x32_bf16 v[74:77], v[152:155], v[208:211], 0
	v_mfma_f32_16x16x32_bf16 v[70:73], v[160:163], v[208:211], 0
	v_mfma_f32_16x16x32_bf16 v[122:125], v[156:159], v[188:191], v[122:125]
	v_mfma_f32_16x16x32_bf16 v[118:121], v[164:167], v[188:191], v[118:121]
	v_mfma_f32_16x16x32_bf16 v[106:109], v[156:159], v[196:199], v[106:109]
	v_mfma_f32_16x16x32_bf16 v[102:105], v[164:167], v[196:199], v[102:105]
	v_mfma_f32_16x16x32_bf16 v[90:93], v[156:159], v[204:207], v[90:93]
	v_mfma_f32_16x16x32_bf16 v[86:89], v[164:167], v[204:207], v[86:89]
	v_mfma_f32_16x16x32_bf16 v[74:77], v[156:159], v[212:215], v[74:77]
	v_mfma_f32_16x16x32_bf16 v[70:73], v[164:167], v[212:215], v[70:73]
	v_mfma_f32_16x16x32_bf16 v[126:129], v[168:171], v[184:187], 0
	v_mfma_f32_16x16x32_bf16 v[114:117], v[176:179], v[184:187], 0
	v_mfma_f32_16x16x32_bf16 v[110:113], v[168:171], v[192:195], 0
	v_mfma_f32_16x16x32_bf16 v[98:101], v[176:179], v[192:195], 0
	v_mfma_f32_16x16x32_bf16 v[94:97], v[168:171], v[200:203], 0
	v_mfma_f32_16x16x32_bf16 v[82:85], v[176:179], v[200:203], 0
	v_mfma_f32_16x16x32_bf16 v[78:81], v[168:171], v[208:211], 0
	v_mfma_f32_16x16x32_bf16 v[66:69], v[176:179], v[208:211], 0
	v_mfma_f32_16x16x32_bf16 v[126:129], v[172:175], v[188:191], v[126:129]
	v_mfma_f32_16x16x32_bf16 v[114:117], v[180:183], v[188:191], v[114:117]
	v_mfma_f32_16x16x32_bf16 v[110:113], v[172:175], v[196:199], v[110:113]
	v_mfma_f32_16x16x32_bf16 v[98:101], v[180:183], v[196:199], v[98:101]
	v_mfma_f32_16x16x32_bf16 v[94:97], v[172:175], v[204:207], v[94:97]
	v_mfma_f32_16x16x32_bf16 v[82:85], v[180:183], v[204:207], v[82:85]
	v_mfma_f32_16x16x32_bf16 v[78:81], v[172:175], v[212:215], v[78:81]
	v_mfma_f32_16x16x32_bf16 v[66:69], v[180:183], v[212:215], v[66:69]
	s_barrier
	ds_read_b128 v[184:187], v150 offset:16384
	ds_read_b128 v[188:191], v150 offset:17408
	ds_read_b128 v[192:195], v150 offset:18432
	ds_read_b128 v[196:199], v150 offset:19456
	ds_read_b128 v[200:203], v150 offset:20480
	ds_read_b128 v[204:207], v150 offset:21504
	ds_read_b128 v[208:211], v150 offset:22528
	ds_read_b128 v[212:215], v150 offset:23552
	s_add_i32 s55, s44, s33
	s_mov_b32 m0, s55
	s_nop 0
	global_load_lds_dwordx4 v134, s[30:31]
	s_add_i32 m0, s55, 0x2000
	s_add_u32 s56, s30, 0x4000
	s_addc_u32 s57, s31, 0
	s_add_i32 s55, s45, s33
	global_load_lds_dwordx4 v130, s[30:31]
	s_mov_b32 m0, s55
	s_nop 0
	global_load_lds_dwordx4 v134, s[56:57]
	s_add_i32 m0, s55, 0x2000
	s_nop 0
	global_load_lds_dwordx4 v130, s[56:57]
	s_mov_b32 m0, s21
	s_nop 0
	global_load_lds_dwordx4 v136, s[34:35]
	s_mov_b32 m0, s23
	s_nop 0
	global_load_lds_dwordx4 v132, s[34:35]
	s_waitcnt vmcnt(8) lgkmcnt(0)
	s_barrier
; #define PG8_STAGE(bufoff, gbase, voff) do { _Pragma("unroll") for (int _i = 0; _i < 2; ++_i) \
;         __builtin_amdgcn_global_load_lds((const unsigned*)((const char*)(gbase) + (voff)[_i]), (LAS unsigned*)(lds + (bufoff) + ldsw + _i * 8192), 16, 0, 0); } while (0)
; #define PG8_LDA(dst, b, h) do { _Pragma("unroll") for (int m = 0; m < 4; ++m) _Pragma("unroll") for (int k = 0; k < 2; ++k) dst[m][k] = *(const LAS bf16x8*)(lds + PG8_SA(b, h) + aoff + m * 2048 + k * 1024); } while (0)
; #define PG8_LDB(dst, b, h) do { _Pragma("unroll") for (int n = 0; n < 2; ++n) _Pragma("unroll") for (int k = 0; k < 2; ++k) dst[n][k] = *(const LAS bf16x8*)(lds + PG8_SB(b, h) + boff + n * 2048 + k * 1024); } while (0)
; #define PG8_MMA(ai, bj, At, Bt) do { __builtin_amdgcn_s_setprio(1); _Pragma("unroll") for (int m = 0; m < 4; ++m) _Pragma("unroll") for (int n = 0; n < 2; ++n) _Pragma("unroll") for (int k = 0; k < 2; ++k) \
;         acc[ai][bj][m][n] = __builtin_amdgcn_mfma_f32_16x16x32_bf16(Bt[n][k], At[m][k], acc[ai][bj][m][n], 0, 0, 0); __builtin_amdgcn_s_setprio(0); } while (0)
; #define PG8_WAIT_V(n) asm volatile("s_waitcnt vmcnt(" #n ")" ::: "memory")
; #define PG8_WAIT_L(n) asm volatile("s_waitcnt lgkmcnt(" #n ")" ::: "memory")
; #define PG8_BAR __builtin_amdgcn_s_barrier()
; #define PG8_SCHED __builtin_amdgcn_sched_barrier(0)
; template <class Epi, class Sched, bool ABLK = false, bool ALIGN_EPI = true, bool SP2 = true, bool BBLK = true>
; __device__ __forceinline__ void gemm_phase(LAS unsigned char* lds, const Gemm g, const Sched& S, const Epi& E) {
;     ...
;             PG8_WAIT_V(8); PG8_WAIT_L(0); PG8_BAR; PG8_MMA(1, 0, At, B0); PG8_MMA(1, 1, At, B1); PG8_BAR; PG8_SCHED;
;             PG8_LDB(B0, 1, 0); PG8_LDB(B1, 1, 1); PG8_SCHED; PG8_LDA(At, 1, 0); PG8_STAGE(PG8_SA(0, 1), a2 + hstepA, voffA);
;             PG8_WAIT_V(8); PG8_WAIT_L(0); PG8_BAR; PG8_MMA(0, 0, At, B0); PG8_MMA(0, 1, At, B1); PG8_BAR; PG8_SCHED;
	v_mfma_f32_16x16x32_bf16 v[58:61], v[152:155], v[184:187], 0
	v_mfma_f32_16x16x32_bf16 v[54:57], v[160:163], v[184:187], 0
	v_mfma_f32_16x16x32_bf16 v[42:45], v[152:155], v[192:195], 0
	v_mfma_f32_16x16x32_bf16 v[38:41], v[160:163], v[192:195], 0
	v_mfma_f32_16x16x32_bf16 v[26:29], v[152:155], v[200:203], 0
	v_mfma_f32_16x16x32_bf16 v[22:25], v[160:163], v[200:203], 0
	v_mfma_f32_16x16x32_bf16 v[10:13], v[152:155], v[208:211], 0
	v_mfma_f32_16x16x32_bf16 v[6:9], v[160:163], v[208:211], 0
	v_mfma_f32_16x16x32_bf16 v[58:61], v[156:159], v[188:191], v[58:61]
	v_mfma_f32_16x16x32_bf16 v[54:57], v[164:167], v[188:191], v[54:57]
	v_mfma_f32_16x16x32_bf16 v[42:45], v[156:159], v[196:199], v[42:45]
	v_mfma_f32_16x16x32_bf16 v[38:41], v[164:167], v[196:199], v[38:41]
	v_mfma_f32_16x16x32_bf16 v[26:29], v[156:159], v[204:207], v[26:29]
	v_mfma_f32_16x16x32_bf16 v[22:25], v[164:167], v[204:207], v[22:25]
	v_mfma_f32_16x16x32_bf16 v[10:13], v[156:159], v[212:215], v[10:13]
	v_mfma_f32_16x16x32_bf16 v[6:9], v[164:167], v[212:215], v[6:9]
	v_mfma_f32_16x16x32_bf16 v[62:65], v[168:171], v[184:187], 0
	v_mfma_f32_16x16x32_bf16 v[50:53], v[176:179], v[184:187], 0
	v_mfma_f32_16x16x32_bf16 v[46:49], v[168:171], v[192:195], 0
	v_mfma_f32_16x16x32_bf16 v[34:37], v[176:179], v[192:195], 0
	v_mfma_f32_16x16x32_bf16 v[30:33], v[168:171], v[200:203], 0
	v_mfma_f32_16x16x32_bf16 v[18:21], v[176:179], v[200:203], 0
	v_mfma_f32_16x16x32_bf16 v[14:17], v[168:171], v[208:211], 0
	v_mfma_f32_16x16x32_bf16 v[2:5], v[176:179], v[208:211], 0
	v_mfma_f32_16x16x32_bf16 v[62:65], v[172:175], v[188:191], v[62:65]
	v_mfma_f32_16x16x32_bf16 v[50:53], v[180:183], v[188:191], v[50:53]
	v_mfma_f32_16x16x32_bf16 v[46:49], v[172:175], v[196:199], v[46:49]
	v_mfma_f32_16x16x32_bf16 v[34:37], v[180:183], v[196:199], v[34:37]
	v_mfma_f32_16x16x32_bf16 v[30:33], v[172:175], v[204:207], v[30:33]
	v_mfma_f32_16x16x32_bf16 v[18:21], v[180:183], v[204:207], v[18:21]
	v_mfma_f32_16x16x32_bf16 v[14:17], v[172:175], v[212:215], v[14:17]
	v_mfma_f32_16x16x32_bf16 v[2:5], v[180:183], v[212:215], v[2:5]
	s_barrier
	s_add_i32 s55, 0, 0x18000
	v_add_u32_e32 v151, s55, v146
	s_add_i32 s56, 0, 0x1c000
	ds_read_b128 v[152:155], v151
	ds_read_b128 v[156:159], v151 offset:1024
	ds_read_b128 v[160:163], v151 offset:2048
	ds_read_b128 v[164:167], v151 offset:3072
	v_add_u32_e32 v151, s56, v146
	ds_read_b128 v[168:171], v151
	ds_read_b128 v[172:175], v151 offset:1024
	ds_read_b128 v[176:179], v151 offset:2048
	ds_read_b128 v[180:183], v151 offset:3072
	ds_read_b128 v[184:187], v150 offset:32768
	ds_read_b128 v[188:191], v150 offset:33792
	ds_read_b128 v[192:195], v150 offset:34816
	ds_read_b128 v[196:199], v150 offset:35840
	ds_read_b128 v[200:203], v150 offset:36864
	ds_read_b128 v[204:207], v150 offset:37888
	ds_read_b128 v[208:211], v150 offset:38912
	ds_read_b128 v[212:215], v150 offset:39936
	s_add_u32 s34, s34, 0x80000
	s_addc_u32 s35, s35, 0
	s_mov_b32 m0, s39
	s_nop 0
	global_load_lds_dwordx4 v136, s[34:35]
	s_mov_b32 m0, s40
	s_nop 0
	global_load_lds_dwordx4 v132, s[34:35]
	s_waitcnt vmcnt(8) lgkmcnt(0)
	s_barrier
	v_mfma_f32_16x16x32_bf16 v[122:125], v[152:155], v[184:187], v[122:125]
	v_mfma_f32_16x16x32_bf16 v[118:121], v[160:163], v[184:187], v[118:121]
	v_mfma_f32_16x16x32_bf16 v[106:109], v[152:155], v[192:195], v[106:109]
	v_mfma_f32_16x16x32_bf16 v[102:105], v[160:163], v[192:195], v[102:105]
	v_mfma_f32_16x16x32_bf16 v[90:93], v[152:155], v[200:203], v[90:93]
	v_mfma_f32_16x16x32_bf16 v[86:89], v[160:163], v[200:203], v[86:89]
	v_mfma_f32_16x16x32_bf16 v[74:77], v[152:155], v[208:211], v[74:77]
	v_mfma_f32_16x16x32_bf16 v[70:73], v[160:163], v[208:211], v[70:73]
	v_mfma_f32_16x16x32_bf16 v[122:125], v[156:159], v[188:191], v[122:125]
	v_mfma_f32_16x16x32_bf16 v[118:121], v[164:167], v[188:191], v[118:121]
	v_mfma_f32_16x16x32_bf16 v[106:109], v[156:159], v[196:199], v[106:109]
	v_mfma_f32_16x16x32_bf16 v[102:105], v[164:167], v[196:199], v[102:105]
	v_mfma_f32_16x16x32_bf16 v[90:93], v[156:159], v[204:207], v[90:93]
	v_mfma_f32_16x16x32_bf16 v[86:89], v[164:167], v[204:207], v[86:89]
	v_mfma_f32_16x16x32_bf16 v[74:77], v[156:159], v[212:215], v[74:77]
	v_mfma_f32_16x16x32_bf16 v[70:73], v[164:167], v[212:215], v[70:73]
	v_mfma_f32_16x16x32_bf16 v[126:129], v[168:171], v[184:187], v[126:129]
	v_mfma_f32_16x16x32_bf16 v[114:117], v[176:179], v[184:187], v[114:117]
	v_mfma_f32_16x16x32_bf16 v[110:113], v[168:171], v[192:195], v[110:113]
	v_mfma_f32_16x16x32_bf16 v[98:101], v[176:179], v[192:195], v[98:101]
	v_mfma_f32_16x16x32_bf16 v[94:97], v[168:171], v[200:203], v[94:97]
	v_mfma_f32_16x16x32_bf16 v[82:85], v[176:179], v[200:203], v[82:85]
	v_mfma_f32_16x16x32_bf16 v[78:81], v[168:171], v[208:211], v[78:81]
	v_mfma_f32_16x16x32_bf16 v[66:69], v[176:179], v[208:211], v[66:69]
	v_mfma_f32_16x16x32_bf16 v[126:129], v[172:175], v[188:191], v[126:129]
	v_mfma_f32_16x16x32_bf16 v[114:117], v[180:183], v[188:191], v[114:117]
	v_mfma_f32_16x16x32_bf16 v[110:113], v[172:175], v[196:199], v[110:113]
	v_mfma_f32_16x16x32_bf16 v[98:101], v[180:183], v[196:199], v[98:101]
	v_mfma_f32_16x16x32_bf16 v[94:97], v[172:175], v[204:207], v[94:97]
	v_mfma_f32_16x16x32_bf16 v[82:85], v[180:183], v[204:207], v[82:85]
	v_mfma_f32_16x16x32_bf16 v[78:81], v[172:175], v[212:215], v[78:81]
	v_mfma_f32_16x16x32_bf16 v[66:69], v[180:183], v[212:215], v[66:69]
	s_barrier
; #define PG8_STAGE(bufoff, gbase, voff) do { _Pragma("unroll") for (int _i = 0; _i < 2; ++_i) \
;         __builtin_amdgcn_global_load_lds((const unsigned*)((const char*)(gbase) + (voff)[_i]), (LAS unsigned*)(lds + (bufoff) + ldsw + _i * 8192), 16, 0, 0); } while (0)
; #define PG8_LDA(dst, b, h) do { _Pragma("unroll") for (int m = 0; m < 4; ++m) _Pragma("unroll") for (int k = 0; k < 2; ++k) dst[m][k] = *(const LAS bf16x8*)(lds + PG8_SA(b, h) + aoff + m * 2048 + k * 1024); } while (0)
; #define PG8_WAIT_V(n) asm volatile("s_waitcnt vmcnt(" #n ")" ::: "memory")
; #define PG8_WAIT_L(n) asm volatile("s_waitcnt lgkmcnt(" #n ")" ::: "memory")
; template <class Epi, class Sched, bool ABLK = false, bool ALIGN_EPI = true, bool SP2 = true, bool BBLK = true>
; __device__ __forceinline__ void gemm_phase(LAS unsigned char* lds, const Gemm g, const Sched& S, const Epi& E) {
;     ...
;         for (int t = 0; t < nt; t += 2) {
;             const bool last = (t == nt - 2);
;             const char* a1 = a_tile(uA, tbA + t + 1);
;             const char* a2 = last ? a_tile(nuA, ntbA) : a_tile(uA, tbA + t + 2); const char* b2 = last ? nB : cB + (size_t)(t + 2) * kstepB;
;             const char* a3 = last ? a_tile(nuA, ntbA + 1) : a_tile(uA, tbA + t + 3); const char* b3 = b2 + kstepB;
;             if (last && has_next) S.a_ready(nxt);
;             if constexpr (SP2) {
;             PG8_LDB(B0, 0, 0); PG8_LDB(B1, 0, 1); PG8_SCHED; PG8_LDA(At, 0, 0); PG8_STAGE(PG8_SA(1, 1), a1 + hstepA, voffA);
;             PG8_WAIT_V(8); PG8_WAIT_L(0); PG8_BAR; PG8_MMA(0, 0, At, B0); PG8_MMA(0, 1, At, B1); PG8_BAR; PG8_SCHED;
;             PG8_LDA(At, 0, 1); PG8_STAGE(PG8_SB(0, 0), b2, voffB); PG8_STAGE(PG8_SB(0, 1), b2 + hstepB, voffB); PG8_STAGE(PG8_SA(0, 0), a2, voffA);
;             PG8_WAIT_V(8); PG8_WAIT_L(0); PG8_BAR; PG8_MMA(1, 0, At, B0); PG8_MMA(1, 1, At, B1); PG8_BAR; PG8_SCHED;
;             PG8_LDB(B0, 1, 0); PG8_LDB(B1, 1, 1); PG8_SCHED; PG8_LDA(At, 1, 0); PG8_STAGE(PG8_SA(0, 1), a2 + hstepA, voffA);
;             PG8_WAIT_V(8); PG8_WAIT_L(0); PG8_BAR; PG8_MMA(0, 0, At, B0); PG8_MMA(0, 1, At, B1); PG8_BAR; PG8_SCHED;
;             PG8_LDA(At, 1, 1); PG8_STAGE(PG8_SB(1, 0), b3, voffB); PG8_STAGE(PG8_SB(1, 1), b3 + hstepB, voffB); PG8_STAGE(PG8_SA(1, 0), a3, voffA);
;             PG8_WAIT_V(8); PG8_WAIT_L(0); PG8_BAR; PG8_MMA(1, 0, At, B0); PG8_MMA(1, 1, At, B1); PG8_BAR; PG8_SCHED;
	ds_read_b128 v[184:187], v150 offset:49152
	ds_read_b128 v[188:191], v150 offset:50176
	ds_read_b128 v[192:195], v150 offset:51200
	ds_read_b128 v[196:199], v150 offset:52224
	ds_read_b128 v[200:203], v150 offset:53248
	ds_read_b128 v[204:207], v150 offset:54272
	ds_read_b128 v[208:211], v150 offset:55296
	ds_read_b128 v[212:215], v150 offset:56320
	s_add_u32 s34, s30, 0x8000
	s_addc_u32 s35, s31, 0
	s_add_i32 s55, s55, s33
	s_mov_b32 m0, s55
	s_nop 0
	global_load_lds_dwordx4 v134, s[34:35]
	s_add_i32 m0, s55, 0x2000
	s_add_u32 s30, s30, 0xc000
	v_lshl_add_u64 v[216:217], s[34:35], 0, v[130:131]
	s_addc_u32 s31, s31, 0
	s_add_i32 s34, s56, s33
	global_load_lds_dwordx4 v[216:217], off
	s_mov_b32 m0, s34
	s_nop 0
	global_load_lds_dwordx4 v134, s[30:31]
	s_add_i32 m0, s34, 0x2000
	s_nop 0
	global_load_lds_dwordx4 v130, s[30:31]
	s_mov_b32 m0, s42
	s_nop 0
	global_load_lds_dwordx4 v136, s[28:29]
	s_mov_b32 m0, s43
	s_nop 0
	global_load_lds_dwordx4 v132, s[28:29]
	s_waitcnt vmcnt(8) lgkmcnt(0)
	s_barrier
	v_mfma_f32_16x16x32_bf16 v[58:61], v[152:155], v[184:187], v[58:61]
	v_mfma_f32_16x16x32_bf16 v[54:57], v[160:163], v[184:187], v[54:57]
	v_mfma_f32_16x16x32_bf16 v[42:45], v[152:155], v[192:195], v[42:45]
	v_mfma_f32_16x16x32_bf16 v[38:41], v[160:163], v[192:195], v[38:41]
	v_mfma_f32_16x16x32_bf16 v[26:29], v[152:155], v[200:203], v[26:29]
	v_mfma_f32_16x16x32_bf16 v[22:25], v[160:163], v[200:203], v[22:25]
	v_mfma_f32_16x16x32_bf16 v[10:13], v[152:155], v[208:211], v[10:13]
	v_mfma_f32_16x16x32_bf16 v[6:9], v[160:163], v[208:211], v[6:9]
	v_mfma_f32_16x16x32_bf16 v[58:61], v[156:159], v[188:191], v[58:61]
	v_mfma_f32_16x16x32_bf16 v[54:57], v[164:167], v[188:191], v[54:57]
	v_mfma_f32_16x16x32_bf16 v[42:45], v[156:159], v[196:199], v[42:45]
	v_mfma_f32_16x16x32_bf16 v[38:41], v[164:167], v[196:199], v[38:41]
	v_mfma_f32_16x16x32_bf16 v[26:29], v[156:159], v[204:207], v[26:29]
	v_mfma_f32_16x16x32_bf16 v[22:25], v[164:167], v[204:207], v[22:25]
	v_mfma_f32_16x16x32_bf16 v[10:13], v[156:159], v[212:215], v[10:13]
	v_mfma_f32_16x16x32_bf16 v[6:9], v[164:167], v[212:215], v[6:9]
	v_mfma_f32_16x16x32_bf16 v[62:65], v[168:171], v[184:187], v[62:65]
	v_mfma_f32_16x16x32_bf16 v[50:53], v[176:179], v[184:187], v[50:53]
	v_mfma_f32_16x16x32_bf16 v[46:49], v[168:171], v[192:195], v[46:49]
	v_mfma_f32_16x16x32_bf16 v[34:37], v[176:179], v[192:195], v[34:37]
	v_mfma_f32_16x16x32_bf16 v[30:33], v[168:171], v[200:203], v[30:33]
	v_mfma_f32_16x16x32_bf16 v[18:21], v[176:179], v[200:203], v[18:21]
	v_mfma_f32_16x16x32_bf16 v[14:17], v[168:171], v[208:211], v[14:17]
	v_mfma_f32_16x16x32_bf16 v[2:5], v[176:179], v[208:211], v[2:5]
	v_mfma_f32_16x16x32_bf16 v[62:65], v[172:175], v[188:191], v[62:65]
	v_mfma_f32_16x16x32_bf16 v[50:53], v[180:183], v[188:191], v[50:53]
	v_mfma_f32_16x16x32_bf16 v[46:49], v[172:175], v[196:199], v[46:49]
	v_mfma_f32_16x16x32_bf16 v[34:37], v[180:183], v[196:199], v[34:37]
	v_mfma_f32_16x16x32_bf16 v[30:33], v[172:175], v[204:207], v[30:33]
	v_mfma_f32_16x16x32_bf16 v[18:21], v[180:183], v[204:207], v[18:21]
	v_mfma_f32_16x16x32_bf16 v[14:17], v[172:175], v[212:215], v[14:17]
	v_mfma_f32_16x16x32_bf16 v[2:5], v[180:183], v[212:215], v[2:5]
	s_barrier
	s_add_i32 s54, s54, 2
	s_add_u32 s26, s26, 0x100
	s_addc_u32 s27, s27, 0
	s_add_u32 s52, s52, 0x10000
	s_addc_u32 s53, s53, 0
	s_cmp_gt_u32 s54, 29
.LBB0_350:
	ds_read_b128 v[152:155], v148
	ds_read_b128 v[156:159], v148 offset:1024
	ds_read_b128 v[160:163], v148 offset:2048
	ds_read_b128 v[164:167], v148 offset:3072
	ds_read_b128 v[168:171], v149
	ds_read_b128 v[172:175], v149 offset:1024
	ds_read_b128 v[176:179], v149 offset:2048
	ds_read_b128 v[180:183], v149 offset:3072
	ds_read_b128 v[184:187], v150
	ds_read_b128 v[188:191], v150 offset:1024
	ds_read_b128 v[192:195], v150 offset:2048
	ds_read_b128 v[196:199], v150 offset:3072
	ds_read_b128 v[200:203], v150 offset:4096
	ds_read_b128 v[204:207], v150 offset:5120
	ds_read_b128 v[208:211], v150 offset:6144
	ds_read_b128 v[212:215], v150 offset:7168
	s_add_u32 s28, s24, s26
	s_addc_u32 s29, s25, s27
	s_add_u32 s34, s28, 0x100
	s_addc_u32 s35, s29, 0
	s_add_u32 s28, s28, 0x180
	s_addc_u32 s29, s29, 0
	s_cmpk_eq_i32 s26, 0xf00
	s_cselect_b32 s29, s51, s29
	s_cselect_b32 s28, s50, s28
	s_cselect_b32 s31, s9, s53
	s_cselect_b32 s30, s11, s52
	s_cselect_b32 s35, s4, s35
	s_cselect_b32 s34, s5, s34
	s_mov_b32 m0, s49
	v_lshl_add_u64 v[216:217], v[142:143], 0, s[26:27]
	global_load_lds_dwordx4 v[216:217], off
	v_lshl_add_u64 v[216:217], v[144:145], 0, s[26:27]
	s_add_i32 m0, s21, 0xe000
	s_nop 0
	global_load_lds_dwordx4 v[216:217], off
	s_waitcnt vmcnt(8) lgkmcnt(0)
	s_barrier
; #define PG8_STAGE(bufoff, gbase, voff) do { _Pragma("unroll") for (int _i = 0; _i < 2; ++_i) \
;         __builtin_amdgcn_global_load_lds((const unsigned*)((const char*)(gbase) + (voff)[_i]), (LAS unsigned*)(lds + (bufoff) + ldsw + _i * 8192), 16, 0, 0); } while (0)
; #define PG8_LDA(dst, b, h) do { _Pragma("unroll") for (int m = 0; m < 4; ++m) _Pragma("unroll") for (int k = 0; k < 2; ++k) dst[m][k] = *(const LAS bf16x8*)(lds + PG8_SA(b, h) + aoff + m * 2048 + k * 1024); } while (0)
; #define PG8_MMA(ai, bj, At, Bt) do { __builtin_amdgcn_s_setprio(1); _Pragma("unroll") for (int m = 0; m < 4; ++m) _Pragma("unroll") for (int n = 0; n < 2; ++n) _Pragma("unroll") for (int k = 0; k < 2; ++k) \
;         acc[ai][bj][m][n] = __builtin_amdgcn_mfma_f32_16x16x32_bf16(Bt[n][k], At[m][k], acc[ai][bj][m][n], 0, 0, 0); __builtin_amdgcn_s_setprio(0); } while (0)
; #define PG8_WAIT_V(n) asm volatile("s_waitcnt vmcnt(" #n ")" ::: "memory")
; #define PG8_WAIT_L(n) asm volatile("s_waitcnt lgkmcnt(" #n ")" ::: "memory")
; #define PG8_BAR __builtin_amdgcn_s_barrier()
; #define PG8_SCHED __builtin_amdgcn_sched_barrier(0)
; template <class Epi, class Sched, bool ABLK = false, bool ALIGN_EPI = true, bool SP2 = true, bool BBLK = true>
; __device__ __forceinline__ void gemm_phase(LAS unsigned char* lds, const Gemm g, const Sched& S, const Epi& E) {
;     ...
;             PG8_WAIT_V(8); PG8_WAIT_L(0); PG8_BAR; PG8_MMA(0, 0, At, B0); PG8_MMA(0, 1, At, B1); PG8_BAR; PG8_SCHED;
;             PG8_LDA(At, 0, 1); PG8_STAGE(PG8_SB(0, 0), b2, voffB); PG8_STAGE(PG8_SB(0, 1), b2 + hstepB, voffB); PG8_STAGE(PG8_SA(0, 0), a2, voffA);
;             PG8_WAIT_V(8); PG8_WAIT_L(0); PG8_BAR; PG8_MMA(1, 0, At, B0); PG8_MMA(1, 1, At, B1); PG8_BAR; PG8_SCHED;
	v_mfma_f32_16x16x32_bf16 v[122:125], v[152:155], v[184:187], v[122:125]
	v_mfma_f32_16x16x32_bf16 v[118:121], v[160:163], v[184:187], v[118:121]
	v_mfma_f32_16x16x32_bf16 v[106:109], v[152:155], v[192:195], v[106:109]
	v_mfma_f32_16x16x32_bf16 v[102:105], v[160:163], v[192:195], v[102:105]
	v_mfma_f32_16x16x32_bf16 v[90:93], v[152:155], v[200:203], v[90:93]
	v_mfma_f32_16x16x32_bf16 v[86:89], v[160:163], v[200:203], v[86:89]
	v_mfma_f32_16x16x32_bf16 v[74:77], v[152:155], v[208:211], v[74:77]
	v_mfma_f32_16x16x32_bf16 v[70:73], v[160:163], v[208:211], v[70:73]
	v_mfma_f32_16x16x32_bf16 v[122:125], v[156:159], v[188:191], v[122:125]
	v_mfma_f32_16x16x32_bf16 v[118:121], v[164:167], v[188:191], v[118:121]
	v_mfma_f32_16x16x32_bf16 v[106:109], v[156:159], v[196:199], v[106:109]
	v_mfma_f32_16x16x32_bf16 v[102:105], v[164:167], v[196:199], v[102:105]
	v_mfma_f32_16x16x32_bf16 v[90:93], v[156:159], v[204:207], v[90:93]
	v_mfma_f32_16x16x32_bf16 v[86:89], v[164:167], v[204:207], v[86:89]
	v_mfma_f32_16x16x32_bf16 v[74:77], v[156:159], v[212:215], v[74:77]
	v_mfma_f32_16x16x32_bf16 v[70:73], v[164:167], v[212:215], v[70:73]
	v_mfma_f32_16x16x32_bf16 v[126:129], v[168:171], v[184:187], v[126:129]
	v_mfma_f32_16x16x32_bf16 v[114:117], v[176:179], v[184:187], v[114:117]
	v_mfma_f32_16x16x32_bf16 v[110:113], v[168:171], v[192:195], v[110:113]
	v_mfma_f32_16x16x32_bf16 v[98:101], v[176:179], v[192:195], v[98:101]
	v_mfma_f32_16x16x32_bf16 v[94:97], v[168:171], v[200:203], v[94:97]
	v_mfma_f32_16x16x32_bf16 v[82:85], v[176:179], v[200:203], v[82:85]
	v_mfma_f32_16x16x32_bf16 v[78:81], v[168:171], v[208:211], v[78:81]
	v_mfma_f32_16x16x32_bf16 v[66:69], v[176:179], v[208:211], v[66:69]
	v_mfma_f32_16x16x32_bf16 v[126:129], v[172:175], v[188:191], v[126:129]
	v_mfma_f32_16x16x32_bf16 v[114:117], v[180:183], v[188:191], v[114:117]
	v_mfma_f32_16x16x32_bf16 v[110:113], v[172:175], v[196:199], v[110:113]
	v_mfma_f32_16x16x32_bf16 v[98:101], v[180:183], v[196:199], v[98:101]
	v_mfma_f32_16x16x32_bf16 v[94:97], v[172:175], v[204:207], v[94:97]
	v_mfma_f32_16x16x32_bf16 v[82:85], v[180:183], v[204:207], v[82:85]
	v_mfma_f32_16x16x32_bf16 v[78:81], v[172:175], v[212:215], v[78:81]
	v_mfma_f32_16x16x32_bf16 v[66:69], v[180:183], v[212:215], v[66:69]
	s_barrier
	ds_read_b128 v[184:187], v150 offset:16384
	ds_read_b128 v[188:191], v150 offset:17408
	ds_read_b128 v[192:195], v150 offset:18432
	ds_read_b128 v[196:199], v150 offset:19456
	ds_read_b128 v[200:203], v150 offset:20480
	ds_read_b128 v[204:207], v150 offset:21504
	ds_read_b128 v[208:211], v150 offset:22528
	ds_read_b128 v[212:215], v150 offset:23552
	s_add_i32 s55, s44, s33
	s_mov_b32 m0, s55
	s_nop 0
	global_load_lds_dwordx4 v134, s[30:31]
	s_add_i32 m0, s55, 0x2000
	s_add_u32 s56, s30, 0x4000
	s_addc_u32 s57, s31, 0
	s_add_i32 s55, s45, s33
	global_load_lds_dwordx4 v130, s[30:31]
	s_mov_b32 m0, s55
	s_nop 0
	global_load_lds_dwordx4 v134, s[56:57]
	s_add_i32 m0, s55, 0x2000
	s_nop 0
	global_load_lds_dwordx4 v130, s[56:57]
	s_mov_b32 m0, s21
	s_nop 0
	global_load_lds_dwordx4 v136, s[34:35]
	s_mov_b32 m0, s23
	s_nop 0
	global_load_lds_dwordx4 v132, s[34:35]
	s_waitcnt vmcnt(8) lgkmcnt(0)
	s_barrier
	v_mfma_f32_16x16x32_bf16 v[58:61], v[152:155], v[184:187], v[58:61]
	v_mfma_f32_16x16x32_bf16 v[54:57], v[160:163], v[184:187], v[54:57]
	v_mfma_f32_16x16x32_bf16 v[42:45], v[152:155], v[192:195], v[42:45]
	v_mfma_f32_16x16x32_bf16 v[38:41], v[160:163], v[192:195], v[38:41]
	v_mfma_f32_16x16x32_bf16 v[26:29], v[152:155], v[200:203], v[26:29]
	v_mfma_f32_16x16x32_bf16 v[22:25], v[160:163], v[200:203], v[22:25]
	v_mfma_f32_16x16x32_bf16 v[10:13], v[152:155], v[208:211], v[10:13]
	v_mfma_f32_16x16x32_bf16 v[6:9], v[160:163], v[208:211], v[6:9]
	v_mfma_f32_16x16x32_bf16 v[58:61], v[156:159], v[188:191], v[58:61]
	v_mfma_f32_16x16x32_bf16 v[54:57], v[164:167], v[188:191], v[54:57]
	v_mfma_f32_16x16x32_bf16 v[42:45], v[156:159], v[196:199], v[42:45]
	v_mfma_f32_16x16x32_bf16 v[38:41], v[164:167], v[196:199], v[38:41]
	v_mfma_f32_16x16x32_bf16 v[26:29], v[156:159], v[204:207], v[26:29]
	v_mfma_f32_16x16x32_bf16 v[22:25], v[164:167], v[204:207], v[22:25]
	v_mfma_f32_16x16x32_bf16 v[10:13], v[156:159], v[212:215], v[10:13]
	v_mfma_f32_16x16x32_bf16 v[6:9], v[164:167], v[212:215], v[6:9]
	v_mfma_f32_16x16x32_bf16 v[62:65], v[168:171], v[184:187], v[62:65]
	v_mfma_f32_16x16x32_bf16 v[50:53], v[176:179], v[184:187], v[50:53]
	v_mfma_f32_16x16x32_bf16 v[46:49], v[168:171], v[192:195], v[46:49]
	v_mfma_f32_16x16x32_bf16 v[34:37], v[176:179], v[192:195], v[34:37]
	v_mfma_f32_16x16x32_bf16 v[30:33], v[168:171], v[200:203], v[30:33]
	v_mfma_f32_16x16x32_bf16 v[18:21], v[176:179], v[200:203], v[18:21]
	v_mfma_f32_16x16x32_bf16 v[14:17], v[168:171], v[208:211], v[14:17]
	v_mfma_f32_16x16x32_bf16 v[2:5], v[176:179], v[208:211], v[2:5]
	v_mfma_f32_16x16x32_bf16 v[62:65], v[172:175], v[188:191], v[62:65]
	v_mfma_f32_16x16x32_bf16 v[50:53], v[180:183], v[188:191], v[50:53]
	v_mfma_f32_16x16x32_bf16 v[46:49], v[172:175], v[196:199], v[46:49]
	v_mfma_f32_16x16x32_bf16 v[34:37], v[180:183], v[196:199], v[34:37]
	v_mfma_f32_16x16x32_bf16 v[30:33], v[172:175], v[204:207], v[30:33]
	v_mfma_f32_16x16x32_bf16 v[18:21], v[180:183], v[204:207], v[18:21]
	v_mfma_f32_16x16x32_bf16 v[14:17], v[172:175], v[212:215], v[14:17]
	v_mfma_f32_16x16x32_bf16 v[2:5], v[180:183], v[212:215], v[2:5]
	s_barrier
; #define PG8_STAGE(bufoff, gbase, voff) do { _Pragma("unroll") for (int _i = 0; _i < 2; ++_i) \
;         __builtin_amdgcn_global_load_lds((const unsigned*)((const char*)(gbase) + (voff)[_i]), (LAS unsigned*)(lds + (bufoff) + ldsw + _i * 8192), 16, 0, 0); } while (0)
; #define PG8_LDA(dst, b, h) do { _Pragma("unroll") for (int m = 0; m < 4; ++m) _Pragma("unroll") for (int k = 0; k < 2; ++k) dst[m][k] = *(const LAS bf16x8*)(lds + PG8_SA(b, h) + aoff + m * 2048 + k * 1024); } while (0)
; #define PG8_LDB(dst, b, h) do { _Pragma("unroll") for (int n = 0; n < 2; ++n) _Pragma("unroll") for (int k = 0; k < 2; ++k) dst[n][k] = *(const LAS bf16x8*)(lds + PG8_SB(b, h) + boff + n * 2048 + k * 1024); } while (0)
; #define PG8_MMA(ai, bj, At, Bt) do { __builtin_amdgcn_s_setprio(1); _Pragma("unroll") for (int m = 0; m < 4; ++m) _Pragma("unroll") for (int n = 0; n < 2; ++n) _Pragma("unroll") for (int k = 0; k < 2; ++k) \
;         acc[ai][bj][m][n] = __builtin_amdgcn_mfma_f32_16x16x32_bf16(Bt[n][k], At[m][k], acc[ai][bj][m][n], 0, 0, 0); __builtin_amdgcn_s_setprio(0); } while (0)
; #define PG8_WAIT_V(n) asm volatile("s_waitcnt vmcnt(" #n ")" ::: "memory")
; #define PG8_WAIT_L(n) asm volatile("s_waitcnt lgkmcnt(" #n ")" ::: "memory")
; #define PG8_BAR __builtin_amdgcn_s_barrier()
; #define PG8_SCHED __builtin_amdgcn_sched_barrier(0)
; template <class Epi, class Sched, bool ABLK = false, bool ALIGN_EPI = true, bool SP2 = true, bool BBLK = true>
; __device__ __forceinline__ void gemm_phase(LAS unsigned char* lds, const Gemm g, const Sched& S, const Epi& E) {
;     ...
;             PG8_LDB(B0, 1, 0); PG8_LDB(B1, 1, 1); PG8_SCHED; PG8_LDA(At, 1, 0); PG8_STAGE(PG8_SA(0, 1), a2 + hstepA, voffA);
;             PG8_WAIT_V(8); PG8_WAIT_L(0); PG8_BAR; PG8_MMA(0, 0, At, B0); PG8_MMA(0, 1, At, B1); PG8_BAR; PG8_SCHED;
;             PG8_LDA(At, 1, 1); PG8_STAGE(PG8_SB(1, 0), b3, voffB); PG8_STAGE(PG8_SB(1, 1), b3 + hstepB, voffB); PG8_STAGE(PG8_SA(1, 0), a3, voffA);
;             PG8_WAIT_V(8); PG8_WAIT_L(0); PG8_BAR; PG8_MMA(1, 0, At, B0); PG8_MMA(1, 1, At, B1); PG8_BAR; PG8_SCHED;
;     ...
;         }
;         if constexpr (ALIGN_EPI) { if (wr == 0) PG8_BAR; }
	s_add_i32 s55, 0, 0x18000
	v_add_u32_e32 v151, s55, v146
	s_add_i32 s56, 0, 0x1c000
	ds_read_b128 v[152:155], v151
	ds_read_b128 v[156:159], v151 offset:1024
	ds_read_b128 v[160:163], v151 offset:2048
	ds_read_b128 v[164:167], v151 offset:3072
	v_add_u32_e32 v151, s56, v146
	ds_read_b128 v[168:171], v151
	ds_read_b128 v[172:175], v151 offset:1024
	ds_read_b128 v[176:179], v151 offset:2048
	ds_read_b128 v[180:183], v151 offset:3072
	ds_read_b128 v[184:187], v150 offset:32768
	ds_read_b128 v[188:191], v150 offset:33792
	ds_read_b128 v[192:195], v150 offset:34816
	ds_read_b128 v[196:199], v150 offset:35840
	ds_read_b128 v[200:203], v150 offset:36864
	ds_read_b128 v[204:207], v150 offset:37888
	ds_read_b128 v[208:211], v150 offset:38912
	ds_read_b128 v[212:215], v150 offset:39936
	s_add_u32 s34, s34, 0x80000
	s_addc_u32 s35, s35, 0
	s_mov_b32 m0, s39
	s_nop 0
	global_load_lds_dwordx4 v136, s[34:35]
	s_mov_b32 m0, s40
	s_nop 0
	global_load_lds_dwordx4 v132, s[34:35]
	s_waitcnt vmcnt(8) lgkmcnt(0)
	s_barrier
	v_mfma_f32_16x16x32_bf16 v[122:125], v[152:155], v[184:187], v[122:125]
	v_mfma_f32_16x16x32_bf16 v[118:121], v[160:163], v[184:187], v[118:121]
	v_mfma_f32_16x16x32_bf16 v[106:109], v[152:155], v[192:195], v[106:109]
	v_mfma_f32_16x16x32_bf16 v[102:105], v[160:163], v[192:195], v[102:105]
	v_mfma_f32_16x16x32_bf16 v[90:93], v[152:155], v[200:203], v[90:93]
	v_mfma_f32_16x16x32_bf16 v[86:89], v[160:163], v[200:203], v[86:89]
	v_mfma_f32_16x16x32_bf16 v[74:77], v[152:155], v[208:211], v[74:77]
	v_mfma_f32_16x16x32_bf16 v[70:73], v[160:163], v[208:211], v[70:73]
	v_mfma_f32_16x16x32_bf16 v[122:125], v[156:159], v[188:191], v[122:125]
	v_mfma_f32_16x16x32_bf16 v[118:121], v[164:167], v[188:191], v[118:121]
	v_mfma_f32_16x16x32_bf16 v[106:109], v[156:159], v[196:199], v[106:109]
	v_mfma_f32_16x16x32_bf16 v[102:105], v[164:167], v[196:199], v[102:105]
	v_mfma_f32_16x16x32_bf16 v[90:93], v[156:159], v[204:207], v[90:93]
	v_mfma_f32_16x16x32_bf16 v[86:89], v[164:167], v[204:207], v[86:89]
	v_mfma_f32_16x16x32_bf16 v[74:77], v[156:159], v[212:215], v[74:77]
	v_mfma_f32_16x16x32_bf16 v[70:73], v[164:167], v[212:215], v[70:73]
	v_mfma_f32_16x16x32_bf16 v[126:129], v[168:171], v[184:187], v[126:129]
	v_mfma_f32_16x16x32_bf16 v[114:117], v[176:179], v[184:187], v[114:117]
	v_mfma_f32_16x16x32_bf16 v[110:113], v[168:171], v[192:195], v[110:113]
	v_mfma_f32_16x16x32_bf16 v[98:101], v[176:179], v[192:195], v[98:101]
	v_mfma_f32_16x16x32_bf16 v[94:97], v[168:171], v[200:203], v[94:97]
	v_mfma_f32_16x16x32_bf16 v[82:85], v[176:179], v[200:203], v[82:85]
	v_mfma_f32_16x16x32_bf16 v[78:81], v[168:171], v[208:211], v[78:81]
	v_mfma_f32_16x16x32_bf16 v[66:69], v[176:179], v[208:211], v[66:69]
	v_mfma_f32_16x16x32_bf16 v[126:129], v[172:175], v[188:191], v[126:129]
	v_mfma_f32_16x16x32_bf16 v[114:117], v[180:183], v[188:191], v[114:117]
	v_mfma_f32_16x16x32_bf16 v[110:113], v[172:175], v[196:199], v[110:113]
	v_mfma_f32_16x16x32_bf16 v[98:101], v[180:183], v[196:199], v[98:101]
	v_mfma_f32_16x16x32_bf16 v[94:97], v[172:175], v[204:207], v[94:97]
	v_mfma_f32_16x16x32_bf16 v[82:85], v[180:183], v[204:207], v[82:85]
	v_mfma_f32_16x16x32_bf16 v[78:81], v[172:175], v[212:215], v[78:81]
	v_mfma_f32_16x16x32_bf16 v[66:69], v[180:183], v[212:215], v[66:69]
	s_barrier
	ds_read_b128 v[184:187], v150 offset:49152
	ds_read_b128 v[188:191], v150 offset:50176
	ds_read_b128 v[192:195], v150 offset:51200
	ds_read_b128 v[196:199], v150 offset:52224
	ds_read_b128 v[200:203], v150 offset:53248
	ds_read_b128 v[204:207], v150 offset:54272
	ds_read_b128 v[208:211], v150 offset:55296
	ds_read_b128 v[212:215], v150 offset:56320
	s_add_u32 s34, s30, 0x8000
	s_addc_u32 s35, s31, 0
	s_add_i32 s55, s55, s33
	s_mov_b32 m0, s55
	s_nop 0
	global_load_lds_dwordx4 v134, s[34:35]
	s_add_i32 m0, s55, 0x2000
	s_add_u32 s30, s30, 0xc000
	v_lshl_add_u64 v[216:217], s[34:35], 0, v[130:131]
	s_addc_u32 s31, s31, 0
	s_add_i32 s34, s56, s33
	global_load_lds_dwordx4 v[216:217], off
	s_mov_b32 m0, s34
	s_nop 0
	global_load_lds_dwordx4 v134, s[30:31]
	s_add_i32 m0, s34, 0x2000
	s_nop 0
	global_load_lds_dwordx4 v130, s[30:31]
	s_mov_b32 m0, s42
	s_nop 0
	global_load_lds_dwordx4 v136, s[28:29]
	s_mov_b32 m0, s43
	s_nop 0
	global_load_lds_dwordx4 v132, s[28:29]
	s_waitcnt vmcnt(8) lgkmcnt(0)
	s_barrier
	v_mfma_f32_16x16x32_bf16 v[58:61], v[152:155], v[184:187], v[58:61]
	v_mfma_f32_16x16x32_bf16 v[54:57], v[160:163], v[184:187], v[54:57]
	v_mfma_f32_16x16x32_bf16 v[42:45], v[152:155], v[192:195], v[42:45]
	v_mfma_f32_16x16x32_bf16 v[38:41], v[160:163], v[192:195], v[38:41]
	v_mfma_f32_16x16x32_bf16 v[26:29], v[152:155], v[200:203], v[26:29]
	v_mfma_f32_16x16x32_bf16 v[22:25], v[160:163], v[200:203], v[22:25]
	v_mfma_f32_16x16x32_bf16 v[10:13], v[152:155], v[208:211], v[10:13]
	v_mfma_f32_16x16x32_bf16 v[6:9], v[160:163], v[208:211], v[6:9]
	v_mfma_f32_16x16x32_bf16 v[58:61], v[156:159], v[188:191], v[58:61]
	v_mfma_f32_16x16x32_bf16 v[54:57], v[164:167], v[188:191], v[54:57]
	v_mfma_f32_16x16x32_bf16 v[42:45], v[156:159], v[196:199], v[42:45]
	v_mfma_f32_16x16x32_bf16 v[38:41], v[164:167], v[196:199], v[38:41]
	v_mfma_f32_16x16x32_bf16 v[26:29], v[156:159], v[204:207], v[26:29]
	v_mfma_f32_16x16x32_bf16 v[22:25], v[164:167], v[204:207], v[22:25]
	v_mfma_f32_16x16x32_bf16 v[10:13], v[156:159], v[212:215], v[10:13]
	v_mfma_f32_16x16x32_bf16 v[6:9], v[164:167], v[212:215], v[6:9]
	v_mfma_f32_16x16x32_bf16 v[62:65], v[168:171], v[184:187], v[62:65]
	v_mfma_f32_16x16x32_bf16 v[50:53], v[176:179], v[184:187], v[50:53]
	v_mfma_f32_16x16x32_bf16 v[46:49], v[168:171], v[192:195], v[46:49]
	v_mfma_f32_16x16x32_bf16 v[34:37], v[176:179], v[192:195], v[34:37]
	v_mfma_f32_16x16x32_bf16 v[30:33], v[168:171], v[200:203], v[30:33]
	v_mfma_f32_16x16x32_bf16 v[18:21], v[176:179], v[200:203], v[18:21]
	v_mfma_f32_16x16x32_bf16 v[14:17], v[168:171], v[208:211], v[14:17]
	v_mfma_f32_16x16x32_bf16 v[2:5], v[176:179], v[208:211], v[2:5]
	v_mfma_f32_16x16x32_bf16 v[62:65], v[172:175], v[188:191], v[62:65]
	v_mfma_f32_16x16x32_bf16 v[50:53], v[180:183], v[188:191], v[50:53]
	v_mfma_f32_16x16x32_bf16 v[46:49], v[172:175], v[196:199], v[46:49]
	v_mfma_f32_16x16x32_bf16 v[34:37], v[180:183], v[196:199], v[34:37]
	v_mfma_f32_16x16x32_bf16 v[30:33], v[172:175], v[204:207], v[30:33]
	v_mfma_f32_16x16x32_bf16 v[18:21], v[180:183], v[204:207], v[18:21]
	v_mfma_f32_16x16x32_bf16 v[14:17], v[172:175], v[212:215], v[14:17]
	v_mfma_f32_16x16x32_bf16 v[2:5], v[180:183], v[212:215], v[2:5]
	s_barrier
	s_add_i32 s54, s54, 2
	s_add_u32 s26, s26, 0x100
	s_addc_u32 s27, s27, 0
	s_add_u32 s52, s52, 0x10000
	s_addc_u32 s53, s53, 0
	s_cmp_gt_u32 s54, 29
	s_cbranch_scc0 .LBB0_350
	s_and_b64 vcc, exec, s[6:7]
	s_cbranch_vccz .LBB0_353
	s_barrier

; #define PG8_STAGE(bufoff, gbase, voff) do { _Pragma("unroll") for (int _i = 0; _i < 2; ++_i) \
;         __builtin_amdgcn_global_load_lds((const unsigned*)((const char*)(gbase) + (voff)[_i]), (LAS unsigned*)(lds + (bufoff) + ldsw + _i * 8192), 16, 0, 0); } while (0)
; #define PG8_LDA(dst, b, h) do { _Pragma("unroll") for (int m = 0; m < 4; ++m) _Pragma("unroll") for (int k = 0; k < 2; ++k) dst[m][k] = *(const LAS bf16x8*)(lds + PG8_SA(b, h) + aoff + m * 2048 + k * 1024); } while (0)
; #define PG8_LDB(dst, b, h) do { _Pragma("unroll") for (int n = 0; n < 2; ++n) _Pragma("unroll") for (int k = 0; k < 2; ++k) dst[n][k] = *(const LAS bf16x8*)(lds + PG8_SB(b, h) + boff + n * 2048 + k * 1024); } while (0)
; #define PG8_WAIT_V(n) asm volatile("s_waitcnt vmcnt(" #n ")" ::: "memory")
; #define PG8_WAIT_L(n) asm volatile("s_waitcnt lgkmcnt(" #n ")" ::: "memory")
; template <class Epi, class Sched, bool ABLK = false, bool ALIGN_EPI = true, bool SP2 = true, bool BBLK = true>
; __device__ __forceinline__ void gemm_phase(LAS unsigned char* lds, const Gemm g, const Sched& S, const Epi& E) {
;     ...
;         const bool has_next = S.next(ui + 1, nxt);
;         const int nt = cur.nt;
;         const char* nuA = has_next ? a_unit(nxt) : uA; const int ntbA = has_next ? nxt.k0 / BK : tbA; const char* nB = has_next ? (const char*)g.Bt + (size_t)nxt.pn * tstepB + b_k0(nxt.k0) : cB;
;         for (int t = 0; t < nt; t += 2) {
;             const bool last = (t == nt - 2);
;             const char* a1 = a_tile(uA, tbA + t + 1);
;             const char* a2 = last ? a_tile(nuA, ntbA) : a_tile(uA, tbA + t + 2); const char* b2 = last ? nB : cB + (size_t)(t + 2) * kstepB;
;             const char* a3 = last ? a_tile(nuA, ntbA + 1) : a_tile(uA, tbA + t + 3); const char* b3 = b2 + kstepB;
;             if (last && has_next) S.a_ready(nxt);
;             if constexpr (SP2) {
;             PG8_LDB(B0, 0, 0); PG8_LDB(B1, 0, 1); PG8_SCHED; PG8_LDA(At, 0, 0); PG8_STAGE(PG8_SA(1, 1), a1 + hstepA, voffA);
;             PG8_WAIT_V(8); PG8_WAIT_L(0); PG8_BAR; PG8_MMA(0, 0, At, B0); PG8_MMA(0, 1, At, B1); PG8_BAR; PG8_SCHED;
;             PG8_LDA(At, 0, 1); PG8_STAGE(PG8_SB(0, 0), b2, voffB); PG8_STAGE(PG8_SB(0, 1), b2 + hstepB, voffB); PG8_STAGE(PG8_SA(0, 0), a2, voffA);
;             PG8_WAIT_V(8); PG8_WAIT_L(0); PG8_BAR; PG8_MMA(1, 0, At, B0); PG8_MMA(1, 1, At, B1); PG8_BAR; PG8_SCHED;
.LBB0_474:
	ds_read_b128 v[172:175], v168
	ds_read_b128 v[176:179], v168 offset:1024
	ds_read_b128 v[180:183], v168 offset:2048
	ds_read_b128 v[184:187], v168 offset:3072
	ds_read_b128 v[188:191], v169
	ds_read_b128 v[192:195], v169 offset:1024
	ds_read_b128 v[196:199], v169 offset:2048
	ds_read_b128 v[200:203], v169 offset:3072
	ds_read_b128 v[204:207], v170
	ds_read_b128 v[208:211], v170 offset:1024
	ds_read_b128 v[212:215], v170 offset:2048
	ds_read_b128 v[216:219], v170 offset:3072
	ds_read_b128 v[220:223], v170 offset:4096
	ds_read_b128 v[224:227], v170 offset:5120
	ds_read_b128 v[228:231], v170 offset:6144
	ds_read_b128 v[232:235], v170 offset:7168
	s_ashr_i32 s11, s10, 31
	s_lshl_b64 s[4:5], s[10:11], 20
	s_add_u32 s14, s41, s4
	s_addc_u32 s15, s42, s5
	s_and_b64 s[4:5], s[18:19], exec
	s_cselect_b32 s4, s15, s27
	s_cselect_b32 s5, s14, s26
	s_ashr_i32 s13, s12, 31
	s_lshl_b64 s[20:21], s[12:13], 20
	s_add_u32 s20, s0, s20
	s_addc_u32 s21, s39, s21
	s_and_b64 s[30:31], s[18:19], exec
	s_cselect_b32 s11, s21, s29
	s_cselect_b32 s13, s20, s28
	s_add_u32 s23, s5, 0x80
	s_addc_u32 s57, s4, 0
	s_add_u32 s58, s28, 0x10000
	v_mov_b32_e32 v2, 0
	s_addc_u32 s59, s29, 0
	v_lshl_add_u64 v[164:165], s[26:27], 0, v[160:161]
	v_lshl_add_u64 v[166:167], s[26:27], 0, v[162:163]
	s_mov_b32 s60, -2
	s_mov_b64 s[28:29], 0
	s_add_u32 s30, s26, s28
	s_addc_u32 s31, s27, s29
	s_add_u32 s36, s30, 0x100
	s_addc_u32 s37, s31, 0
	s_add_u32 s30, s30, 0x180
	s_addc_u32 s31, s31, 0
	s_cmpk_eq_i32 s28, 0xf00
	s_cselect_b32 s31, s57, s31
	s_cselect_b32 s30, s23, s30
	s_cselect_b32 s35, s11, s59
	s_cselect_b32 s34, s13, s58
	s_cselect_b32 s37, s4, s37
	s_cselect_b32 s36, s5, s36
	s_mov_b32 m0, s53
	v_lshl_add_u64 v[236:237], v[164:165], 0, s[28:29]
	global_load_lds_dwordx4 v[236:237], off
	v_lshl_add_u64 v[236:237], v[166:167], 0, s[28:29]
	s_mov_b32 m0, s54
	s_nop 0
	global_load_lds_dwordx4 v[236:237], off
	s_waitcnt vmcnt(8) lgkmcnt(0)
	s_barrier
	v_mfma_f32_16x16x32_bf16 v[126:129], v[172:175], v[204:207], 0
	v_mfma_f32_16x16x32_bf16 v[122:125], v[180:183], v[204:207], 0
	v_mfma_f32_16x16x32_bf16 v[110:113], v[172:175], v[212:215], 0
	v_mfma_f32_16x16x32_bf16 v[106:109], v[180:183], v[212:215], 0
	v_mfma_f32_16x16x32_bf16 v[94:97], v[172:175], v[220:223], 0
	v_mfma_f32_16x16x32_bf16 v[90:93], v[180:183], v[220:223], 0
	v_mfma_f32_16x16x32_bf16 v[78:81], v[172:175], v[228:231], 0
	v_mfma_f32_16x16x32_bf16 v[74:77], v[180:183], v[228:231], 0
	v_mfma_f32_16x16x32_bf16 v[126:129], v[176:179], v[208:211], v[126:129]
	v_mfma_f32_16x16x32_bf16 v[122:125], v[184:187], v[208:211], v[122:125]
	v_mfma_f32_16x16x32_bf16 v[110:113], v[176:179], v[216:219], v[110:113]
	v_mfma_f32_16x16x32_bf16 v[106:109], v[184:187], v[216:219], v[106:109]
	v_mfma_f32_16x16x32_bf16 v[94:97], v[176:179], v[224:227], v[94:97]
	v_mfma_f32_16x16x32_bf16 v[90:93], v[184:187], v[224:227], v[90:93]
	v_mfma_f32_16x16x32_bf16 v[78:81], v[176:179], v[232:235], v[78:81]
	v_mfma_f32_16x16x32_bf16 v[74:77], v[184:187], v[232:235], v[74:77]
	v_mfma_f32_16x16x32_bf16 v[118:121], v[188:191], v[204:207], 0
	v_mfma_f32_16x16x32_bf16 v[114:117], v[196:199], v[204:207], 0
	v_mfma_f32_16x16x32_bf16 v[102:105], v[188:191], v[212:215], 0
	v_mfma_f32_16x16x32_bf16 v[98:101], v[196:199], v[212:215], 0
	v_mfma_f32_16x16x32_bf16 v[86:89], v[188:191], v[220:223], 0
	v_mfma_f32_16x16x32_bf16 v[82:85], v[196:199], v[220:223], 0
	v_mfma_f32_16x16x32_bf16 v[70:73], v[188:191], v[228:231], 0
	v_mfma_f32_16x16x32_bf16 v[66:69], v[196:199], v[228:231], 0
	v_mfma_f32_16x16x32_bf16 v[118:121], v[192:195], v[208:211], v[118:121]
	v_mfma_f32_16x16x32_bf16 v[114:117], v[200:203], v[208:211], v[114:117]
	v_mfma_f32_16x16x32_bf16 v[102:105], v[192:195], v[216:219], v[102:105]
	v_mfma_f32_16x16x32_bf16 v[98:101], v[200:203], v[216:219], v[98:101]
	v_mfma_f32_16x16x32_bf16 v[86:89], v[192:195], v[224:227], v[86:89]
	v_mfma_f32_16x16x32_bf16 v[82:85], v[200:203], v[224:227], v[82:85]
	v_mfma_f32_16x16x32_bf16 v[70:73], v[192:195], v[232:235], v[70:73]
	v_mfma_f32_16x16x32_bf16 v[66:69], v[200:203], v[232:235], v[66:69]
	s_barrier
	ds_read_b128 v[204:207], v170 offset:16384
	ds_read_b128 v[208:211], v170 offset:17408
	ds_read_b128 v[212:215], v170 offset:18432
	ds_read_b128 v[216:219], v170 offset:19456
	ds_read_b128 v[220:223], v170 offset:20480
	ds_read_b128 v[224:227], v170 offset:21504
	ds_read_b128 v[228:231], v170 offset:22528
	ds_read_b128 v[232:235], v170 offset:23552
	s_mov_b32 m0, s55
	s_add_u32 s62, s34, 0x4000
	global_load_lds_dwordx4 v134, s[34:35]
	s_mov_b32 m0, s56
	s_addc_u32 s63, s35, 0
	s_add_i32 s61, s52, s40
	global_load_lds_dwordx4 v130, s[34:35]
	s_mov_b32 m0, s61
	s_nop 0
	global_load_lds_dwordx4 v134, s[62:63]
	s_add_i32 m0, s61, 0x2000
	s_nop 0
	global_load_lds_dwordx4 v130, s[62:63]
	s_mov_b32 m0, s25
	s_nop 0
	global_load_lds_dwordx4 v136, s[36:37]
	s_mov_b32 m0, s43
	s_nop 0
	global_load_lds_dwordx4 v132, s[36:37]
	s_waitcnt vmcnt(8) lgkmcnt(0)
	s_barrier
; #define PG8_STAGE(bufoff, gbase, voff) do { _Pragma("unroll") for (int _i = 0; _i < 2; ++_i) \
;         __builtin_amdgcn_global_load_lds((const unsigned*)((const char*)(gbase) + (voff)[_i]), (LAS unsigned*)(lds + (bufoff) + ldsw + _i * 8192), 16, 0, 0); } while (0)
; #define PG8_LDA(dst, b, h) do { _Pragma("unroll") for (int m = 0; m < 4; ++m) _Pragma("unroll") for (int k = 0; k < 2; ++k) dst[m][k] = *(const LAS bf16x8*)(lds + PG8_SA(b, h) + aoff + m * 2048 + k * 1024); } while (0)
; #define PG8_LDB(dst, b, h) do { _Pragma("unroll") for (int n = 0; n < 2; ++n) _Pragma("unroll") for (int k = 0; k < 2; ++k) dst[n][k] = *(const LAS bf16x8*)(lds + PG8_SB(b, h) + boff + n * 2048 + k * 1024); } while (0)
; #define PG8_MMA(ai, bj, At, Bt) do { __builtin_amdgcn_s_setprio(1); _Pragma("unroll") for (int m = 0; m < 4; ++m) _Pragma("unroll") for (int n = 0; n < 2; ++n) _Pragma("unroll") for (int k = 0; k < 2; ++k) \
;         acc[ai][bj][m][n] = __builtin_amdgcn_mfma_f32_16x16x32_bf16(Bt[n][k], At[m][k], acc[ai][bj][m][n], 0, 0, 0); __builtin_amdgcn_s_setprio(0); } while (0)
; #define PG8_WAIT_V(n) asm volatile("s_waitcnt vmcnt(" #n ")" ::: "memory")
; #define PG8_WAIT_L(n) asm volatile("s_waitcnt lgkmcnt(" #n ")" ::: "memory")
; #define PG8_BAR __builtin_amdgcn_s_barrier()
; #define PG8_SCHED __builtin_amdgcn_sched_barrier(0)
; template <class Epi, class Sched, bool ABLK = false, bool ALIGN_EPI = true, bool SP2 = true, bool BBLK = true>
; __device__ __forceinline__ void gemm_phase(LAS unsigned char* lds, const Gemm g, const Sched& S, const Epi& E) {
;     ...
;             PG8_WAIT_V(8); PG8_WAIT_L(0); PG8_BAR; PG8_MMA(1, 0, At, B0); PG8_MMA(1, 1, At, B1); PG8_BAR; PG8_SCHED;
;             PG8_LDB(B0, 1, 0); PG8_LDB(B1, 1, 1); PG8_SCHED; PG8_LDA(At, 1, 0); PG8_STAGE(PG8_SA(0, 1), a2 + hstepA, voffA);
;             PG8_WAIT_V(8); PG8_WAIT_L(0); PG8_BAR; PG8_MMA(0, 0, At, B0); PG8_MMA(0, 1, At, B1); PG8_BAR; PG8_SCHED;
	v_mfma_f32_16x16x32_bf16 v[62:65], v[172:175], v[204:207], 0
	v_mfma_f32_16x16x32_bf16 v[58:61], v[180:183], v[204:207], 0
	v_mfma_f32_16x16x32_bf16 v[46:49], v[172:175], v[212:215], 0
	v_mfma_f32_16x16x32_bf16 v[42:45], v[180:183], v[212:215], 0
	v_mfma_f32_16x16x32_bf16 v[30:33], v[172:175], v[220:223], 0
	v_mfma_f32_16x16x32_bf16 v[26:29], v[180:183], v[220:223], 0
	v_mfma_f32_16x16x32_bf16 v[14:17], v[172:175], v[228:231], 0
	v_mfma_f32_16x16x32_bf16 v[10:13], v[180:183], v[228:231], 0
	v_mfma_f32_16x16x32_bf16 v[62:65], v[176:179], v[208:211], v[62:65]
	v_mfma_f32_16x16x32_bf16 v[58:61], v[184:187], v[208:211], v[58:61]
	v_mfma_f32_16x16x32_bf16 v[46:49], v[176:179], v[216:219], v[46:49]
	v_mfma_f32_16x16x32_bf16 v[42:45], v[184:187], v[216:219], v[42:45]
	v_mfma_f32_16x16x32_bf16 v[30:33], v[176:179], v[224:227], v[30:33]
	v_mfma_f32_16x16x32_bf16 v[26:29], v[184:187], v[224:227], v[26:29]
	v_mfma_f32_16x16x32_bf16 v[14:17], v[176:179], v[232:235], v[14:17]
	v_mfma_f32_16x16x32_bf16 v[10:13], v[184:187], v[232:235], v[10:13]
	v_mfma_f32_16x16x32_bf16 v[54:57], v[188:191], v[204:207], 0
	v_mfma_f32_16x16x32_bf16 v[50:53], v[196:199], v[204:207], 0
	v_mfma_f32_16x16x32_bf16 v[38:41], v[188:191], v[212:215], 0
	v_mfma_f32_16x16x32_bf16 v[34:37], v[196:199], v[212:215], 0
	v_mfma_f32_16x16x32_bf16 v[22:25], v[188:191], v[220:223], 0
	v_mfma_f32_16x16x32_bf16 v[18:21], v[196:199], v[220:223], 0
	v_mfma_f32_16x16x32_bf16 v[6:9], v[188:191], v[228:231], 0
	v_mfma_f32_16x16x32_bf16 v[2:5], v[196:199], v[228:231], 0
	v_mfma_f32_16x16x32_bf16 v[54:57], v[192:195], v[208:211], v[54:57]
	v_mfma_f32_16x16x32_bf16 v[50:53], v[200:203], v[208:211], v[50:53]
	v_mfma_f32_16x16x32_bf16 v[38:41], v[192:195], v[216:219], v[38:41]
	v_mfma_f32_16x16x32_bf16 v[34:37], v[200:203], v[216:219], v[34:37]
	v_mfma_f32_16x16x32_bf16 v[22:25], v[192:195], v[224:227], v[22:25]
	v_mfma_f32_16x16x32_bf16 v[18:21], v[200:203], v[224:227], v[18:21]
	v_mfma_f32_16x16x32_bf16 v[6:9], v[192:195], v[232:235], v[6:9]
	v_mfma_f32_16x16x32_bf16 v[2:5], v[200:203], v[232:235], v[2:5]
	s_barrier
	s_add_i32 s61, 0, 0x18000
	v_add_u32_e32 v171, s61, v1
	s_add_i32 s62, 0, 0x1c000
	ds_read_b128 v[172:175], v171
	ds_read_b128 v[176:179], v171 offset:1024
	ds_read_b128 v[180:183], v171 offset:2048
	ds_read_b128 v[184:187], v171 offset:3072
	v_add_u32_e32 v171, s62, v1
	ds_read_b128 v[188:191], v171
	ds_read_b128 v[192:195], v171 offset:1024
	ds_read_b128 v[196:199], v171 offset:2048
	ds_read_b128 v[200:203], v171 offset:3072
	ds_read_b128 v[204:207], v170 offset:32768
	ds_read_b128 v[208:211], v170 offset:33792
	ds_read_b128 v[212:215], v170 offset:34816
	ds_read_b128 v[216:219], v170 offset:35840
	ds_read_b128 v[220:223], v170 offset:36864
	ds_read_b128 v[224:227], v170 offset:37888
	ds_read_b128 v[228:231], v170 offset:38912
	ds_read_b128 v[232:235], v170 offset:39936
	s_add_u32 s36, s36, 0x80000
	s_addc_u32 s37, s37, 0
	s_mov_b32 m0, s46
	s_nop 0
	global_load_lds_dwordx4 v136, s[36:37]
	s_mov_b32 m0, s47
	s_nop 0
	global_load_lds_dwordx4 v132, s[36:37]
	s_waitcnt vmcnt(8) lgkmcnt(0)
	s_barrier
	v_mfma_f32_16x16x32_bf16 v[126:129], v[172:175], v[204:207], v[126:129]
	v_mfma_f32_16x16x32_bf16 v[122:125], v[180:183], v[204:207], v[122:125]
	v_mfma_f32_16x16x32_bf16 v[110:113], v[172:175], v[212:215], v[110:113]
	v_mfma_f32_16x16x32_bf16 v[106:109], v[180:183], v[212:215], v[106:109]
	v_mfma_f32_16x16x32_bf16 v[94:97], v[172:175], v[220:223], v[94:97]
	v_mfma_f32_16x16x32_bf16 v[90:93], v[180:183], v[220:223], v[90:93]
	v_mfma_f32_16x16x32_bf16 v[78:81], v[172:175], v[228:231], v[78:81]
	v_mfma_f32_16x16x32_bf16 v[74:77], v[180:183], v[228:231], v[74:77]
	v_mfma_f32_16x16x32_bf16 v[126:129], v[176:179], v[208:211], v[126:129]
	v_mfma_f32_16x16x32_bf16 v[122:125], v[184:187], v[208:211], v[122:125]
	v_mfma_f32_16x16x32_bf16 v[110:113], v[176:179], v[216:219], v[110:113]
	v_mfma_f32_16x16x32_bf16 v[106:109], v[184:187], v[216:219], v[106:109]
	v_mfma_f32_16x16x32_bf16 v[94:97], v[176:179], v[224:227], v[94:97]
	v_mfma_f32_16x16x32_bf16 v[90:93], v[184:187], v[224:227], v[90:93]
	v_mfma_f32_16x16x32_bf16 v[78:81], v[176:179], v[232:235], v[78:81]
	v_mfma_f32_16x16x32_bf16 v[74:77], v[184:187], v[232:235], v[74:77]
	v_mfma_f32_16x16x32_bf16 v[118:121], v[188:191], v[204:207], v[118:121]
	v_mfma_f32_16x16x32_bf16 v[114:117], v[196:199], v[204:207], v[114:117]
	v_mfma_f32_16x16x32_bf16 v[102:105], v[188:191], v[212:215], v[102:105]
	v_mfma_f32_16x16x32_bf16 v[98:101], v[196:199], v[212:215], v[98:101]
	v_mfma_f32_16x16x32_bf16 v[86:89], v[188:191], v[220:223], v[86:89]
	v_mfma_f32_16x16x32_bf16 v[82:85], v[196:199], v[220:223], v[82:85]
	v_mfma_f32_16x16x32_bf16 v[70:73], v[188:191], v[228:231], v[70:73]
	v_mfma_f32_16x16x32_bf16 v[66:69], v[196:199], v[228:231], v[66:69]
	v_mfma_f32_16x16x32_bf16 v[118:121], v[192:195], v[208:211], v[118:121]
	v_mfma_f32_16x16x32_bf16 v[114:117], v[200:203], v[208:211], v[114:117]
	v_mfma_f32_16x16x32_bf16 v[102:105], v[192:195], v[216:219], v[102:105]
	v_mfma_f32_16x16x32_bf16 v[98:101], v[200:203], v[216:219], v[98:101]
	v_mfma_f32_16x16x32_bf16 v[86:89], v[192:195], v[224:227], v[86:89]
	v_mfma_f32_16x16x32_bf16 v[82:85], v[200:203], v[224:227], v[82:85]
	v_mfma_f32_16x16x32_bf16 v[70:73], v[192:195], v[232:235], v[70:73]
	v_mfma_f32_16x16x32_bf16 v[66:69], v[200:203], v[232:235], v[66:69]
	s_barrier
; #define PG8_STAGE(bufoff, gbase, voff) do { _Pragma("unroll") for (int _i = 0; _i < 2; ++_i) \
;         __builtin_amdgcn_global_load_lds((const unsigned*)((const char*)(gbase) + (voff)[_i]), (LAS unsigned*)(lds + (bufoff) + ldsw + _i * 8192), 16, 0, 0); } while (0)
; #define PG8_LDA(dst, b, h) do { _Pragma("unroll") for (int m = 0; m < 4; ++m) _Pragma("unroll") for (int k = 0; k < 2; ++k) dst[m][k] = *(const LAS bf16x8*)(lds + PG8_SA(b, h) + aoff + m * 2048 + k * 1024); } while (0)
; #define PG8_WAIT_V(n) asm volatile("s_waitcnt vmcnt(" #n ")" ::: "memory")
; #define PG8_WAIT_L(n) asm volatile("s_waitcnt lgkmcnt(" #n ")" ::: "memory")
; template <class Epi, class Sched, bool ABLK = false, bool ALIGN_EPI = true, bool SP2 = true, bool BBLK = true>
; __device__ __forceinline__ void gemm_phase(LAS unsigned char* lds, const Gemm g, const Sched& S, const Epi& E) {
;     ...
;             const bool last = (t == nt - 2);
;             const char* a1 = a_tile(uA, tbA + t + 1);
;             const char* a2 = last ? a_tile(nuA, ntbA) : a_tile(uA, tbA + t + 2); const char* b2 = last ? nB : cB + (size_t)(t + 2) * kstepB;
;             const char* a3 = last ? a_tile(nuA, ntbA + 1) : a_tile(uA, tbA + t + 3); const char* b3 = b2 + kstepB;
;             if (last && has_next) S.a_ready(nxt);
;             if constexpr (SP2) {
;             PG8_LDB(B0, 0, 0); PG8_LDB(B1, 0, 1); PG8_SCHED; PG8_LDA(At, 0, 0); PG8_STAGE(PG8_SA(1, 1), a1 + hstepA, voffA);
;             PG8_WAIT_V(8); PG8_WAIT_L(0); PG8_BAR; PG8_MMA(0, 0, At, B0); PG8_MMA(0, 1, At, B1); PG8_BAR; PG8_SCHED;
;             PG8_LDA(At, 0, 1); PG8_STAGE(PG8_SB(0, 0), b2, voffB); PG8_STAGE(PG8_SB(0, 1), b2 + hstepB, voffB); PG8_STAGE(PG8_SA(0, 0), a2, voffA);
;             PG8_WAIT_V(8); PG8_WAIT_L(0); PG8_BAR; PG8_MMA(1, 0, At, B0); PG8_MMA(1, 1, At, B1); PG8_BAR; PG8_SCHED;
;             PG8_LDB(B0, 1, 0); PG8_LDB(B1, 1, 1); PG8_SCHED; PG8_LDA(At, 1, 0); PG8_STAGE(PG8_SA(0, 1), a2 + hstepA, voffA);
;             PG8_WAIT_V(8); PG8_WAIT_L(0); PG8_BAR; PG8_MMA(0, 0, At, B0); PG8_MMA(0, 1, At, B1); PG8_BAR; PG8_SCHED;
;             PG8_LDA(At, 1, 1); PG8_STAGE(PG8_SB(1, 0), b3, voffB); PG8_STAGE(PG8_SB(1, 1), b3 + hstepB, voffB); PG8_STAGE(PG8_SA(1, 0), a3, voffA);
;             PG8_WAIT_V(8); PG8_WAIT_L(0); PG8_BAR; PG8_MMA(1, 0, At, B0); PG8_MMA(1, 1, At, B1); PG8_BAR; PG8_SCHED;
	ds_read_b128 v[204:207], v170 offset:49152
	ds_read_b128 v[208:211], v170 offset:50176
	ds_read_b128 v[212:215], v170 offset:51200
	ds_read_b128 v[216:219], v170 offset:52224
	ds_read_b128 v[220:223], v170 offset:53248
	ds_read_b128 v[224:227], v170 offset:54272
	ds_read_b128 v[228:231], v170 offset:55296
	ds_read_b128 v[232:235], v170 offset:56320
	s_add_u32 s36, s34, 0x8000
	s_addc_u32 s37, s35, 0
	s_add_i32 s61, s61, s40
	s_mov_b32 m0, s61
	s_nop 0
	global_load_lds_dwordx4 v134, s[36:37]
	s_add_i32 m0, s61, 0x2000
	s_add_u32 s34, s34, 0xc000
	v_lshl_add_u64 v[236:237], s[36:37], 0, v[130:131]
	s_addc_u32 s35, s35, 0
	s_add_i32 s36, s62, s40
	global_load_lds_dwordx4 v[236:237], off
	s_mov_b32 m0, s36
	s_nop 0
	global_load_lds_dwordx4 v134, s[34:35]
	s_add_i32 m0, s36, 0x2000
	s_nop 0
	global_load_lds_dwordx4 v130, s[34:35]
	s_mov_b32 m0, s50
	s_nop 0
	global_load_lds_dwordx4 v136, s[30:31]
	s_mov_b32 m0, s51
	s_nop 0
	global_load_lds_dwordx4 v132, s[30:31]
	s_waitcnt vmcnt(8) lgkmcnt(0)
	s_barrier
	v_mfma_f32_16x16x32_bf16 v[62:65], v[172:175], v[204:207], v[62:65]
	v_mfma_f32_16x16x32_bf16 v[58:61], v[180:183], v[204:207], v[58:61]
	v_mfma_f32_16x16x32_bf16 v[46:49], v[172:175], v[212:215], v[46:49]
	v_mfma_f32_16x16x32_bf16 v[42:45], v[180:183], v[212:215], v[42:45]
	v_mfma_f32_16x16x32_bf16 v[30:33], v[172:175], v[220:223], v[30:33]
	v_mfma_f32_16x16x32_bf16 v[26:29], v[180:183], v[220:223], v[26:29]
	v_mfma_f32_16x16x32_bf16 v[14:17], v[172:175], v[228:231], v[14:17]
	v_mfma_f32_16x16x32_bf16 v[10:13], v[180:183], v[228:231], v[10:13]
	v_mfma_f32_16x16x32_bf16 v[62:65], v[176:179], v[208:211], v[62:65]
	v_mfma_f32_16x16x32_bf16 v[58:61], v[184:187], v[208:211], v[58:61]
	v_mfma_f32_16x16x32_bf16 v[46:49], v[176:179], v[216:219], v[46:49]
	v_mfma_f32_16x16x32_bf16 v[42:45], v[184:187], v[216:219], v[42:45]
	v_mfma_f32_16x16x32_bf16 v[30:33], v[176:179], v[224:227], v[30:33]
	v_mfma_f32_16x16x32_bf16 v[26:29], v[184:187], v[224:227], v[26:29]
	v_mfma_f32_16x16x32_bf16 v[14:17], v[176:179], v[232:235], v[14:17]
	v_mfma_f32_16x16x32_bf16 v[10:13], v[184:187], v[232:235], v[10:13]
	v_mfma_f32_16x16x32_bf16 v[54:57], v[188:191], v[204:207], v[54:57]
	v_mfma_f32_16x16x32_bf16 v[50:53], v[196:199], v[204:207], v[50:53]
	v_mfma_f32_16x16x32_bf16 v[38:41], v[188:191], v[212:215], v[38:41]
	v_mfma_f32_16x16x32_bf16 v[34:37], v[196:199], v[212:215], v[34:37]
	v_mfma_f32_16x16x32_bf16 v[22:25], v[188:191], v[220:223], v[22:25]
	v_mfma_f32_16x16x32_bf16 v[18:21], v[196:199], v[220:223], v[18:21]
	v_mfma_f32_16x16x32_bf16 v[6:9], v[188:191], v[228:231], v[6:9]
	v_mfma_f32_16x16x32_bf16 v[2:5], v[196:199], v[228:231], v[2:5]
	v_mfma_f32_16x16x32_bf16 v[54:57], v[192:195], v[208:211], v[54:57]
	v_mfma_f32_16x16x32_bf16 v[50:53], v[200:203], v[208:211], v[50:53]
	v_mfma_f32_16x16x32_bf16 v[38:41], v[192:195], v[216:219], v[38:41]
	v_mfma_f32_16x16x32_bf16 v[34:37], v[200:203], v[216:219], v[34:37]
	v_mfma_f32_16x16x32_bf16 v[22:25], v[192:195], v[224:227], v[22:25]
	v_mfma_f32_16x16x32_bf16 v[18:21], v[200:203], v[224:227], v[18:21]
	v_mfma_f32_16x16x32_bf16 v[6:9], v[192:195], v[232:235], v[6:9]
	v_mfma_f32_16x16x32_bf16 v[2:5], v[200:203], v[232:235], v[2:5]
	s_barrier
	s_add_i32 s60, s60, 2
	s_add_u32 s28, s28, 0x100
	s_addc_u32 s29, s29, 0
	s_add_u32 s58, s58, 0x10000
	s_addc_u32 s59, s59, 0
	s_cmp_gt_u32 s60, 29
.LBB0_475:
	ds_read_b128 v[172:175], v168
	ds_read_b128 v[176:179], v168 offset:1024
	ds_read_b128 v[180:183], v168 offset:2048
	ds_read_b128 v[184:187], v168 offset:3072
	ds_read_b128 v[188:191], v169
	ds_read_b128 v[192:195], v169 offset:1024
	ds_read_b128 v[196:199], v169 offset:2048
	ds_read_b128 v[200:203], v169 offset:3072
	ds_read_b128 v[204:207], v170
	ds_read_b128 v[208:211], v170 offset:1024
	ds_read_b128 v[212:215], v170 offset:2048
	ds_read_b128 v[216:219], v170 offset:3072
	ds_read_b128 v[220:223], v170 offset:4096
	ds_read_b128 v[224:227], v170 offset:5120
	ds_read_b128 v[228:231], v170 offset:6144
	ds_read_b128 v[232:235], v170 offset:7168
	s_add_u32 s30, s26, s28
	s_addc_u32 s31, s27, s29
	s_add_u32 s36, s30, 0x100
	s_addc_u32 s37, s31, 0
	s_add_u32 s30, s30, 0x180
	s_addc_u32 s31, s31, 0
	s_cmpk_eq_i32 s28, 0xf00
	s_cselect_b32 s31, s57, s31
	s_cselect_b32 s30, s23, s30
	s_cselect_b32 s35, s11, s59
	s_cselect_b32 s34, s13, s58
	s_cselect_b32 s37, s4, s37
	s_cselect_b32 s36, s5, s36
	s_mov_b32 m0, s53
	v_lshl_add_u64 v[236:237], v[164:165], 0, s[28:29]
	global_load_lds_dwordx4 v[236:237], off
	v_lshl_add_u64 v[236:237], v[166:167], 0, s[28:29]
	s_mov_b32 m0, s54
	s_nop 0
	global_load_lds_dwordx4 v[236:237], off
	s_waitcnt vmcnt(8) lgkmcnt(0)
	s_barrier
; #define PG8_STAGE(bufoff, gbase, voff) do { _Pragma("unroll") for (int _i = 0; _i < 2; ++_i) \
;         __builtin_amdgcn_global_load_lds((const unsigned*)((const char*)(gbase) + (voff)[_i]), (LAS unsigned*)(lds + (bufoff) + ldsw + _i * 8192), 16, 0, 0); } while (0)
; #define PG8_LDA(dst, b, h) do { _Pragma("unroll") for (int m = 0; m < 4; ++m) _Pragma("unroll") for (int k = 0; k < 2; ++k) dst[m][k] = *(const LAS bf16x8*)(lds + PG8_SA(b, h) + aoff + m * 2048 + k * 1024); } while (0)
; #define PG8_LDB(dst, b, h) do { _Pragma("unroll") for (int n = 0; n < 2; ++n) _Pragma("unroll") for (int k = 0; k < 2; ++k) dst[n][k] = *(const LAS bf16x8*)(lds + PG8_SB(b, h) + boff + n * 2048 + k * 1024); } while (0)
; #define PG8_MMA(ai, bj, At, Bt) do { __builtin_amdgcn_s_setprio(1); _Pragma("unroll") for (int m = 0; m < 4; ++m) _Pragma("unroll") for (int n = 0; n < 2; ++n) _Pragma("unroll") for (int k = 0; k < 2; ++k) \
;         acc[ai][bj][m][n] = __builtin_amdgcn_mfma_f32_16x16x32_bf16(Bt[n][k], At[m][k], acc[ai][bj][m][n], 0, 0, 0); __builtin_amdgcn_s_setprio(0); } while (0)
; #define PG8_WAIT_V(n) asm volatile("s_waitcnt vmcnt(" #n ")" ::: "memory")
; #define PG8_WAIT_L(n) asm volatile("s_waitcnt lgkmcnt(" #n ")" ::: "memory")
; #define PG8_BAR __builtin_amdgcn_s_barrier()
; #define PG8_SCHED __builtin_amdgcn_sched_barrier(0)
; template <class Epi, class Sched, bool ABLK = false, bool ALIGN_EPI = true, bool SP2 = true, bool BBLK = true>
; __device__ __forceinline__ void gemm_phase(LAS unsigned char* lds, const Gemm g, const Sched& S, const Epi& E) {
;     ...
;             PG8_LDB(B0, 0, 0); PG8_LDB(B1, 0, 1); PG8_SCHED; PG8_LDA(At, 0, 0); PG8_STAGE(PG8_SA(1, 1), a1 + hstepA, voffA);
;             PG8_WAIT_V(8); PG8_WAIT_L(0); PG8_BAR; PG8_MMA(0, 0, At, B0); PG8_MMA(0, 1, At, B1); PG8_BAR; PG8_SCHED;
;             PG8_LDA(At, 0, 1); PG8_STAGE(PG8_SB(0, 0), b2, voffB); PG8_STAGE(PG8_SB(0, 1), b2 + hstepB, voffB); PG8_STAGE(PG8_SA(0, 0), a2, voffA);
;             PG8_WAIT_V(8); PG8_WAIT_L(0); PG8_BAR; PG8_MMA(1, 0, At, B0); PG8_MMA(1, 1, At, B1); PG8_BAR; PG8_SCHED;
	v_mfma_f32_16x16x32_bf16 v[126:129], v[172:175], v[204:207], v[126:129]
	v_mfma_f32_16x16x32_bf16 v[122:125], v[180:183], v[204:207], v[122:125]
	v_mfma_f32_16x16x32_bf16 v[110:113], v[172:175], v[212:215], v[110:113]
	v_mfma_f32_16x16x32_bf16 v[106:109], v[180:183], v[212:215], v[106:109]
	v_mfma_f32_16x16x32_bf16 v[94:97], v[172:175], v[220:223], v[94:97]
	v_mfma_f32_16x16x32_bf16 v[90:93], v[180:183], v[220:223], v[90:93]
	v_mfma_f32_16x16x32_bf16 v[78:81], v[172:175], v[228:231], v[78:81]
	v_mfma_f32_16x16x32_bf16 v[74:77], v[180:183], v[228:231], v[74:77]
	v_mfma_f32_16x16x32_bf16 v[126:129], v[176:179], v[208:211], v[126:129]
	v_mfma_f32_16x16x32_bf16 v[122:125], v[184:187], v[208:211], v[122:125]
	v_mfma_f32_16x16x32_bf16 v[110:113], v[176:179], v[216:219], v[110:113]
	v_mfma_f32_16x16x32_bf16 v[106:109], v[184:187], v[216:219], v[106:109]
	v_mfma_f32_16x16x32_bf16 v[94:97], v[176:179], v[224:227], v[94:97]
	v_mfma_f32_16x16x32_bf16 v[90:93], v[184:187], v[224:227], v[90:93]
	v_mfma_f32_16x16x32_bf16 v[78:81], v[176:179], v[232:235], v[78:81]
	v_mfma_f32_16x16x32_bf16 v[74:77], v[184:187], v[232:235], v[74:77]
	v_mfma_f32_16x16x32_bf16 v[118:121], v[188:191], v[204:207], v[118:121]
	v_mfma_f32_16x16x32_bf16 v[114:117], v[196:199], v[204:207], v[114:117]
	v_mfma_f32_16x16x32_bf16 v[102:105], v[188:191], v[212:215], v[102:105]
	v_mfma_f32_16x16x32_bf16 v[98:101], v[196:199], v[212:215], v[98:101]
	v_mfma_f32_16x16x32_bf16 v[86:89], v[188:191], v[220:223], v[86:89]
	v_mfma_f32_16x16x32_bf16 v[82:85], v[196:199], v[220:223], v[82:85]
	v_mfma_f32_16x16x32_bf16 v[70:73], v[188:191], v[228:231], v[70:73]
	v_mfma_f32_16x16x32_bf16 v[66:69], v[196:199], v[228:231], v[66:69]
	v_mfma_f32_16x16x32_bf16 v[118:121], v[192:195], v[208:211], v[118:121]
	v_mfma_f32_16x16x32_bf16 v[114:117], v[200:203], v[208:211], v[114:117]
	v_mfma_f32_16x16x32_bf16 v[102:105], v[192:195], v[216:219], v[102:105]
	v_mfma_f32_16x16x32_bf16 v[98:101], v[200:203], v[216:219], v[98:101]
	v_mfma_f32_16x16x32_bf16 v[86:89], v[192:195], v[224:227], v[86:89]
	v_mfma_f32_16x16x32_bf16 v[82:85], v[200:203], v[224:227], v[82:85]
	v_mfma_f32_16x16x32_bf16 v[70:73], v[192:195], v[232:235], v[70:73]
	v_mfma_f32_16x16x32_bf16 v[66:69], v[200:203], v[232:235], v[66:69]
	s_barrier
	ds_read_b128 v[204:207], v170 offset:16384
	ds_read_b128 v[208:211], v170 offset:17408
	ds_read_b128 v[212:215], v170 offset:18432
	ds_read_b128 v[216:219], v170 offset:19456
	ds_read_b128 v[220:223], v170 offset:20480
	ds_read_b128 v[224:227], v170 offset:21504
	ds_read_b128 v[228:231], v170 offset:22528
	ds_read_b128 v[232:235], v170 offset:23552
	s_mov_b32 m0, s55
	s_add_u32 s62, s34, 0x4000
	global_load_lds_dwordx4 v134, s[34:35]
	s_mov_b32 m0, s56
	s_addc_u32 s63, s35, 0
	s_add_i32 s61, s52, s40
	global_load_lds_dwordx4 v130, s[34:35]
	s_mov_b32 m0, s61
	s_nop 0
	global_load_lds_dwordx4 v134, s[62:63]
	s_add_i32 m0, s61, 0x2000
	s_nop 0
	global_load_lds_dwordx4 v130, s[62:63]
	s_mov_b32 m0, s25
	s_nop 0
	global_load_lds_dwordx4 v136, s[36:37]
	s_mov_b32 m0, s43
	s_nop 0
	global_load_lds_dwordx4 v132, s[36:37]
	s_waitcnt vmcnt(8) lgkmcnt(0)
	s_barrier
	v_mfma_f32_16x16x32_bf16 v[62:65], v[172:175], v[204:207], v[62:65]
	v_mfma_f32_16x16x32_bf16 v[58:61], v[180:183], v[204:207], v[58:61]
	v_mfma_f32_16x16x32_bf16 v[46:49], v[172:175], v[212:215], v[46:49]
	v_mfma_f32_16x16x32_bf16 v[42:45], v[180:183], v[212:215], v[42:45]
	v_mfma_f32_16x16x32_bf16 v[30:33], v[172:175], v[220:223], v[30:33]
	v_mfma_f32_16x16x32_bf16 v[26:29], v[180:183], v[220:223], v[26:29]
	v_mfma_f32_16x16x32_bf16 v[14:17], v[172:175], v[228:231], v[14:17]
	v_mfma_f32_16x16x32_bf16 v[10:13], v[180:183], v[228:231], v[10:13]
	v_mfma_f32_16x16x32_bf16 v[62:65], v[176:179], v[208:211], v[62:65]
	v_mfma_f32_16x16x32_bf16 v[58:61], v[184:187], v[208:211], v[58:61]
	v_mfma_f32_16x16x32_bf16 v[46:49], v[176:179], v[216:219], v[46:49]
	v_mfma_f32_16x16x32_bf16 v[42:45], v[184:187], v[216:219], v[42:45]
	v_mfma_f32_16x16x32_bf16 v[30:33], v[176:179], v[224:227], v[30:33]
	v_mfma_f32_16x16x32_bf16 v[26:29], v[184:187], v[224:227], v[26:29]
	v_mfma_f32_16x16x32_bf16 v[14:17], v[176:179], v[232:235], v[14:17]
	v_mfma_f32_16x16x32_bf16 v[10:13], v[184:187], v[232:235], v[10:13]
	v_mfma_f32_16x16x32_bf16 v[54:57], v[188:191], v[204:207], v[54:57]
	v_mfma_f32_16x16x32_bf16 v[50:53], v[196:199], v[204:207], v[50:53]
	v_mfma_f32_16x16x32_bf16 v[38:41], v[188:191], v[212:215], v[38:41]
	v_mfma_f32_16x16x32_bf16 v[34:37], v[196:199], v[212:215], v[34:37]
	v_mfma_f32_16x16x32_bf16 v[22:25], v[188:191], v[220:223], v[22:25]
	v_mfma_f32_16x16x32_bf16 v[18:21], v[196:199], v[220:223], v[18:21]
	v_mfma_f32_16x16x32_bf16 v[6:9], v[188:191], v[228:231], v[6:9]
	v_mfma_f32_16x16x32_bf16 v[2:5], v[196:199], v[228:231], v[2:5]
	v_mfma_f32_16x16x32_bf16 v[54:57], v[192:195], v[208:211], v[54:57]
	v_mfma_f32_16x16x32_bf16 v[50:53], v[200:203], v[208:211], v[50:53]
	v_mfma_f32_16x16x32_bf16 v[38:41], v[192:195], v[216:219], v[38:41]
	v_mfma_f32_16x16x32_bf16 v[34:37], v[200:203], v[216:219], v[34:37]
	v_mfma_f32_16x16x32_bf16 v[22:25], v[192:195], v[224:227], v[22:25]
	v_mfma_f32_16x16x32_bf16 v[18:21], v[200:203], v[224:227], v[18:21]
	v_mfma_f32_16x16x32_bf16 v[6:9], v[192:195], v[232:235], v[6:9]
	v_mfma_f32_16x16x32_bf16 v[2:5], v[200:203], v[232:235], v[2:5]
	s_barrier
; #define PG8_STAGE(bufoff, gbase, voff) do { _Pragma("unroll") for (int _i = 0; _i < 2; ++_i) \
;         __builtin_amdgcn_global_load_lds((const unsigned*)((const char*)(gbase) + (voff)[_i]), (LAS unsigned*)(lds + (bufoff) + ldsw + _i * 8192), 16, 0, 0); } while (0)
; #define PG8_LDA(dst, b, h) do { _Pragma("unroll") for (int m = 0; m < 4; ++m) _Pragma("unroll") for (int k = 0; k < 2; ++k) dst[m][k] = *(const LAS bf16x8*)(lds + PG8_SA(b, h) + aoff + m * 2048 + k * 1024); } while (0)
; #define PG8_LDB(dst, b, h) do { _Pragma("unroll") for (int n = 0; n < 2; ++n) _Pragma("unroll") for (int k = 0; k < 2; ++k) dst[n][k] = *(const LAS bf16x8*)(lds + PG8_SB(b, h) + boff + n * 2048 + k * 1024); } while (0)
; #define PG8_MMA(ai, bj, At, Bt) do { __builtin_amdgcn_s_setprio(1); _Pragma("unroll") for (int m = 0; m < 4; ++m) _Pragma("unroll") for (int n = 0; n < 2; ++n) _Pragma("unroll") for (int k = 0; k < 2; ++k) \
;         acc[ai][bj][m][n] = __builtin_amdgcn_mfma_f32_16x16x32_bf16(Bt[n][k], At[m][k], acc[ai][bj][m][n], 0, 0, 0); __builtin_amdgcn_s_setprio(0); } while (0)
; #define PG8_WAIT_V(n) asm volatile("s_waitcnt vmcnt(" #n ")" ::: "memory")
; #define PG8_WAIT_L(n) asm volatile("s_waitcnt lgkmcnt(" #n ")" ::: "memory")
; #define PG8_BAR __builtin_amdgcn_s_barrier()
; #define PG8_SCHED __builtin_amdgcn_sched_barrier(0)
; template <class Epi, class Sched, bool ABLK = false, bool ALIGN_EPI = true, bool SP2 = true, bool BBLK = true>
; __device__ __forceinline__ void gemm_phase(LAS unsigned char* lds, const Gemm g, const Sched& S, const Epi& E) {
;     ...
;             PG8_LDB(B0, 1, 0); PG8_LDB(B1, 1, 1); PG8_SCHED; PG8_LDA(At, 1, 0); PG8_STAGE(PG8_SA(0, 1), a2 + hstepA, voffA);
;             PG8_WAIT_V(8); PG8_WAIT_L(0); PG8_BAR; PG8_MMA(0, 0, At, B0); PG8_MMA(0, 1, At, B1); PG8_BAR; PG8_SCHED;
;             PG8_LDA(At, 1, 1); PG8_STAGE(PG8_SB(1, 0), b3, voffB); PG8_STAGE(PG8_SB(1, 1), b3 + hstepB, voffB); PG8_STAGE(PG8_SA(1, 0), a3, voffA);
;             PG8_WAIT_V(8); PG8_WAIT_L(0); PG8_BAR; PG8_MMA(1, 0, At, B0); PG8_MMA(1, 1, At, B1); PG8_BAR; PG8_SCHED;
;     ...
;         }
;         if constexpr (ALIGN_EPI) { if (wr == 0) PG8_BAR; }
	s_add_i32 s61, 0, 0x18000
	v_add_u32_e32 v171, s61, v1
	s_add_i32 s62, 0, 0x1c000
	ds_read_b128 v[172:175], v171
	ds_read_b128 v[176:179], v171 offset:1024
	ds_read_b128 v[180:183], v171 offset:2048
	ds_read_b128 v[184:187], v171 offset:3072
	v_add_u32_e32 v171, s62, v1
	ds_read_b128 v[188:191], v171
	ds_read_b128 v[192:195], v171 offset:1024
	ds_read_b128 v[196:199], v171 offset:2048
	ds_read_b128 v[200:203], v171 offset:3072
	ds_read_b128 v[204:207], v170 offset:32768
	ds_read_b128 v[208:211], v170 offset:33792
	ds_read_b128 v[212:215], v170 offset:34816
	ds_read_b128 v[216:219], v170 offset:35840
	ds_read_b128 v[220:223], v170 offset:36864
	ds_read_b128 v[224:227], v170 offset:37888
	ds_read_b128 v[228:231], v170 offset:38912
	ds_read_b128 v[232:235], v170 offset:39936
	s_add_u32 s36, s36, 0x80000
	s_addc_u32 s37, s37, 0
	s_mov_b32 m0, s46
	s_nop 0
	global_load_lds_dwordx4 v136, s[36:37]
	s_mov_b32 m0, s47
	s_nop 0
	global_load_lds_dwordx4 v132, s[36:37]
	s_waitcnt vmcnt(8) lgkmcnt(0)
	s_barrier
	v_mfma_f32_16x16x32_bf16 v[126:129], v[172:175], v[204:207], v[126:129]
	v_mfma_f32_16x16x32_bf16 v[122:125], v[180:183], v[204:207], v[122:125]
	v_mfma_f32_16x16x32_bf16 v[110:113], v[172:175], v[212:215], v[110:113]
	v_mfma_f32_16x16x32_bf16 v[106:109], v[180:183], v[212:215], v[106:109]
	v_mfma_f32_16x16x32_bf16 v[94:97], v[172:175], v[220:223], v[94:97]
	v_mfma_f32_16x16x32_bf16 v[90:93], v[180:183], v[220:223], v[90:93]
	v_mfma_f32_16x16x32_bf16 v[78:81], v[172:175], v[228:231], v[78:81]
	v_mfma_f32_16x16x32_bf16 v[74:77], v[180:183], v[228:231], v[74:77]
	v_mfma_f32_16x16x32_bf16 v[126:129], v[176:179], v[208:211], v[126:129]
	v_mfma_f32_16x16x32_bf16 v[122:125], v[184:187], v[208:211], v[122:125]
	v_mfma_f32_16x16x32_bf16 v[110:113], v[176:179], v[216:219], v[110:113]
	v_mfma_f32_16x16x32_bf16 v[106:109], v[184:187], v[216:219], v[106:109]
	v_mfma_f32_16x16x32_bf16 v[94:97], v[176:179], v[224:227], v[94:97]
	v_mfma_f32_16x16x32_bf16 v[90:93], v[184:187], v[224:227], v[90:93]
	v_mfma_f32_16x16x32_bf16 v[78:81], v[176:179], v[232:235], v[78:81]
	v_mfma_f32_16x16x32_bf16 v[74:77], v[184:187], v[232:235], v[74:77]
	v_mfma_f32_16x16x32_bf16 v[118:121], v[188:191], v[204:207], v[118:121]
	v_mfma_f32_16x16x32_bf16 v[114:117], v[196:199], v[204:207], v[114:117]
	v_mfma_f32_16x16x32_bf16 v[102:105], v[188:191], v[212:215], v[102:105]
	v_mfma_f32_16x16x32_bf16 v[98:101], v[196:199], v[212:215], v[98:101]
	v_mfma_f32_16x16x32_bf16 v[86:89], v[188:191], v[220:223], v[86:89]
	v_mfma_f32_16x16x32_bf16 v[82:85], v[196:199], v[220:223], v[82:85]
	v_mfma_f32_16x16x32_bf16 v[70:73], v[188:191], v[228:231], v[70:73]
	v_mfma_f32_16x16x32_bf16 v[66:69], v[196:199], v[228:231], v[66:69]
	v_mfma_f32_16x16x32_bf16 v[118:121], v[192:195], v[208:211], v[118:121]
	v_mfma_f32_16x16x32_bf16 v[114:117], v[200:203], v[208:211], v[114:117]
	v_mfma_f32_16x16x32_bf16 v[102:105], v[192:195], v[216:219], v[102:105]
	v_mfma_f32_16x16x32_bf16 v[98:101], v[200:203], v[216:219], v[98:101]
	v_mfma_f32_16x16x32_bf16 v[86:89], v[192:195], v[224:227], v[86:89]
	v_mfma_f32_16x16x32_bf16 v[82:85], v[200:203], v[224:227], v[82:85]
	v_mfma_f32_16x16x32_bf16 v[70:73], v[192:195], v[232:235], v[70:73]
	v_mfma_f32_16x16x32_bf16 v[66:69], v[200:203], v[232:235], v[66:69]
	s_barrier
	ds_read_b128 v[204:207], v170 offset:49152
	ds_read_b128 v[208:211], v170 offset:50176
	ds_read_b128 v[212:215], v170 offset:51200
	ds_read_b128 v[216:219], v170 offset:52224
	ds_read_b128 v[220:223], v170 offset:53248
	ds_read_b128 v[224:227], v170 offset:54272
	ds_read_b128 v[228:231], v170 offset:55296
	ds_read_b128 v[232:235], v170 offset:56320
	s_add_u32 s36, s34, 0x8000
	s_addc_u32 s37, s35, 0
	s_add_i32 s61, s61, s40
	s_mov_b32 m0, s61
	s_nop 0
	global_load_lds_dwordx4 v134, s[36:37]
	s_add_i32 m0, s61, 0x2000
	s_add_u32 s34, s34, 0xc000
	v_lshl_add_u64 v[236:237], s[36:37], 0, v[130:131]
	s_addc_u32 s35, s35, 0
	s_add_i32 s36, s62, s40
	global_load_lds_dwordx4 v[236:237], off
	s_mov_b32 m0, s36
	s_nop 0
	global_load_lds_dwordx4 v134, s[34:35]
	s_add_i32 m0, s36, 0x2000
	s_nop 0
	global_load_lds_dwordx4 v130, s[34:35]
	s_mov_b32 m0, s50
	s_nop 0
	global_load_lds_dwordx4 v136, s[30:31]
	s_mov_b32 m0, s51
	s_nop 0
	global_load_lds_dwordx4 v132, s[30:31]
	s_waitcnt vmcnt(8) lgkmcnt(0)
	s_barrier
	v_mfma_f32_16x16x32_bf16 v[62:65], v[172:175], v[204:207], v[62:65]
	v_mfma_f32_16x16x32_bf16 v[58:61], v[180:183], v[204:207], v[58:61]
	v_mfma_f32_16x16x32_bf16 v[46:49], v[172:175], v[212:215], v[46:49]
	v_mfma_f32_16x16x32_bf16 v[42:45], v[180:183], v[212:215], v[42:45]
	v_mfma_f32_16x16x32_bf16 v[30:33], v[172:175], v[220:223], v[30:33]
	v_mfma_f32_16x16x32_bf16 v[26:29], v[180:183], v[220:223], v[26:29]
	v_mfma_f32_16x16x32_bf16 v[14:17], v[172:175], v[228:231], v[14:17]
	v_mfma_f32_16x16x32_bf16 v[10:13], v[180:183], v[228:231], v[10:13]
	v_mfma_f32_16x16x32_bf16 v[62:65], v[176:179], v[208:211], v[62:65]
	v_mfma_f32_16x16x32_bf16 v[58:61], v[184:187], v[208:211], v[58:61]
	v_mfma_f32_16x16x32_bf16 v[46:49], v[176:179], v[216:219], v[46:49]
	v_mfma_f32_16x16x32_bf16 v[42:45], v[184:187], v[216:219], v[42:45]
	v_mfma_f32_16x16x32_bf16 v[30:33], v[176:179], v[224:227], v[30:33]
	v_mfma_f32_16x16x32_bf16 v[26:29], v[184:187], v[224:227], v[26:29]
	v_mfma_f32_16x16x32_bf16 v[14:17], v[176:179], v[232:235], v[14:17]
	v_mfma_f32_16x16x32_bf16 v[10:13], v[184:187], v[232:235], v[10:13]
	v_mfma_f32_16x16x32_bf16 v[54:57], v[188:191], v[204:207], v[54:57]
	v_mfma_f32_16x16x32_bf16 v[50:53], v[196:199], v[204:207], v[50:53]
	v_mfma_f32_16x16x32_bf16 v[38:41], v[188:191], v[212:215], v[38:41]
	v_mfma_f32_16x16x32_bf16 v[34:37], v[196:199], v[212:215], v[34:37]
	v_mfma_f32_16x16x32_bf16 v[22:25], v[188:191], v[220:223], v[22:25]
	v_mfma_f32_16x16x32_bf16 v[18:21], v[196:199], v[220:223], v[18:21]
	v_mfma_f32_16x16x32_bf16 v[6:9], v[188:191], v[228:231], v[6:9]
	v_mfma_f32_16x16x32_bf16 v[2:5], v[196:199], v[228:231], v[2:5]
	v_mfma_f32_16x16x32_bf16 v[54:57], v[192:195], v[208:211], v[54:57]
	v_mfma_f32_16x16x32_bf16 v[50:53], v[200:203], v[208:211], v[50:53]
	v_mfma_f32_16x16x32_bf16 v[38:41], v[192:195], v[216:219], v[38:41]
	v_mfma_f32_16x16x32_bf16 v[34:37], v[200:203], v[216:219], v[34:37]
	v_mfma_f32_16x16x32_bf16 v[22:25], v[192:195], v[224:227], v[22:25]
	v_mfma_f32_16x16x32_bf16 v[18:21], v[200:203], v[224:227], v[18:21]
	v_mfma_f32_16x16x32_bf16 v[6:9], v[192:195], v[232:235], v[6:9]
	v_mfma_f32_16x16x32_bf16 v[2:5], v[200:203], v[232:235], v[2:5]
	s_barrier
	s_add_i32 s60, s60, 2
	s_add_u32 s28, s28, 0x100
	s_addc_u32 s29, s29, 0
	s_add_u32 s58, s58, 0x10000
	s_addc_u32 s59, s59, 0
	s_cmp_gt_u32 s60, 29
	s_cbranch_scc0 .LBB0_475
	s_and_b64 vcc, exec, s[8:9]
	s_cbranch_vccz .LBB0_478
	s_barrier

; #define PG8_STAGE(bufoff, gbase, voff) do { _Pragma("unroll") for (int _i = 0; _i < 2; ++_i) \
;         __builtin_amdgcn_global_load_lds((const unsigned*)((const char*)(gbase) + (voff)[_i]), (LAS unsigned*)(lds + (bufoff) + ldsw + _i * 8192), 16, 0, 0); } while (0)
; #define PG8_LDA(dst, b, h) do { _Pragma("unroll") for (int m = 0; m < 4; ++m) _Pragma("unroll") for (int k = 0; k < 2; ++k) dst[m][k] = *(const LAS bf16x8*)(lds + PG8_SA(b, h) + aoff + m * 2048 + k * 1024); } while (0)
; #define PG8_LDB(dst, b, h) do { _Pragma("unroll") for (int n = 0; n < 2; ++n) _Pragma("unroll") for (int k = 0; k < 2; ++k) dst[n][k] = *(const LAS bf16x8*)(lds + PG8_SB(b, h) + boff + n * 2048 + k * 1024); } while (0)
; #define PG8_WAIT_V(n) asm volatile("s_waitcnt vmcnt(" #n ")" ::: "memory")
; #define PG8_WAIT_L(n) asm volatile("s_waitcnt lgkmcnt(" #n ")" ::: "memory")
; template <class Epi, class Sched, bool ABLK = false, bool ALIGN_EPI = true, bool SP2 = true, bool BBLK = true>
; __device__ __forceinline__ void gemm_phase(LAS unsigned char* lds, const Gemm g, const Sched& S, const Epi& E) {
;     ...
;         const bool has_next = S.next(ui + 1, nxt);
;         const int nt = cur.nt;
;         const char* nuA = has_next ? a_unit(nxt) : uA; const int ntbA = has_next ? nxt.k0 / BK : tbA; const char* nB = has_next ? (const char*)g.Bt + (size_t)nxt.pn * tstepB + b_k0(nxt.k0) : cB;
;         for (int t = 0; t < nt; t += 2) {
;             const bool last = (t == nt - 2);
;             const char* a1 = a_tile(uA, tbA + t + 1);
;             const char* a2 = last ? a_tile(nuA, ntbA) : a_tile(uA, tbA + t + 2); const char* b2 = last ? nB : cB + (size_t)(t + 2) * kstepB;
;             const char* a3 = last ? a_tile(nuA, ntbA + 1) : a_tile(uA, tbA + t + 3); const char* b3 = b2 + kstepB;
;             if (last && has_next) S.a_ready(nxt);
;             if constexpr (SP2) {
;             PG8_LDB(B0, 0, 0); PG8_LDB(B1, 0, 1); PG8_SCHED; PG8_LDA(At, 0, 0); PG8_STAGE(PG8_SA(1, 1), a1 + hstepA, voffA);
;             PG8_WAIT_V(8); PG8_WAIT_L(0); PG8_BAR; PG8_MMA(0, 0, At, B0); PG8_MMA(0, 1, At, B1); PG8_BAR; PG8_SCHED;
;             PG8_LDA(At, 0, 1); PG8_STAGE(PG8_SB(0, 0), b2, voffB); PG8_STAGE(PG8_SB(0, 1), b2 + hstepB, voffB); PG8_STAGE(PG8_SA(0, 0), a2, voffA);
;             PG8_WAIT_V(8); PG8_WAIT_L(0); PG8_BAR; PG8_MMA(1, 0, At, B0); PG8_MMA(1, 1, At, B1); PG8_BAR; PG8_SCHED;
.LBB0_539:
	ds_read_b128 v[152:155], v148
	ds_read_b128 v[156:159], v148 offset:1024
	ds_read_b128 v[160:163], v148 offset:2048
	ds_read_b128 v[164:167], v148 offset:3072
	ds_read_b128 v[168:171], v149
	ds_read_b128 v[172:175], v149 offset:1024
	ds_read_b128 v[176:179], v149 offset:2048
	ds_read_b128 v[180:183], v149 offset:3072
	ds_read_b128 v[184:187], v150
	ds_read_b128 v[188:191], v150 offset:1024
	ds_read_b128 v[192:195], v150 offset:2048
	ds_read_b128 v[196:199], v150 offset:3072
	ds_read_b128 v[200:203], v150 offset:4096
	ds_read_b128 v[204:207], v150 offset:5120
	ds_read_b128 v[208:211], v150 offset:6144
	ds_read_b128 v[212:215], v150 offset:7168
	s_ashr_i32 s81, s80, 31
	s_andn2_b64 vcc, exec, s[4:5]
	s_lshl_b64 s[30:31], s[80:81], 22
	s_add_u32 s30, s1, s30
	s_addc_u32 s31, s33, s31
	s_and_b64 s[34:35], s[4:5], exec
	s_cselect_b32 s47, s31, s43
	s_cselect_b32 s60, s30, s42
	s_ashr_i32 s34, s0, 31
	s_lshr_b32 s34, s34, 26
	s_add_i32 s34, s0, s34
	s_ashr_i32 s34, s34, 6
	s_and_b64 s[36:37], s[4:5], exec
	s_cselect_b32 s48, s34, s46
	s_ashr_i32 s79, s78, 31
	s_lshl_b64 s[36:37], s[78:79], 22
	s_add_u32 s49, s39, s36
	s_addc_u32 s61, s50, s37
	s_ashr_i32 s35, s34, 31
	s_lshl_b64 s[36:37], s[34:35], 15
	s_add_u32 s36, s49, s36
	s_addc_u32 s37, s61, s37
	v_cndmask_b32_e64 v2, 0, 1, s[4:5]
	s_and_b64 s[4:5], s[4:5], exec
	s_cselect_b32 s4, s37, s41
	s_cselect_b32 s5, s36, s40
	s_ashr_i32 s49, s48, 31
	s_lshl_b64 s[48:49], s[48:49], 15
	s_add_u32 s35, s60, s48
	s_addc_u32 s63, s47, s49
	s_add_u32 s64, s35, 0x8000
	s_addc_u32 s65, s63, 0
	s_add_u32 s66, s40, 0x10000
	s_addc_u32 s67, s41, 0
	s_ashr_i32 s47, s46, 31
	v_cmp_ne_u32_e64 s[8:9], 1, v2
	s_lshl_b64 s[40:41], s[46:47], 15
	v_lshl_add_u64 v[2:3], s[42:43], 0, v[138:139]
	s_add_u32 s75, s42, s40
	v_lshl_add_u64 v[142:143], v[2:3], 0, s[40:41]
	v_lshl_add_u64 v[2:3], s[42:43], 0, v[140:141]
	s_addc_u32 s76, s43, s41
	v_lshl_add_u64 v[144:145], v[2:3], 0, s[40:41]
	s_lshl_b32 s40, s59, 15
	s_add_i32 s40, s40, 0xfff00000
	v_mov_b32_e32 v2, 0
	s_add_u32 s77, s40, 0xf0000
	s_mov_b32 s79, 0
	s_mov_b64 s[40:41], 0
	s_add_u32 s42, s75, s40
	s_addc_u32 s43, s76, s41
	s_add_u32 s48, s42, 0x10000
	s_addc_u32 s49, s43, 0
	s_add_i32 s79, s79, 2
	s_add_u32 s46, s66, s40
	s_addc_u32 s47, s67, s41
	s_add_u32 s42, s42, 0x18000
	s_addc_u32 s43, s43, 0
	s_cmp_eq_u32 s77, s40
	s_cselect_b32 s43, s65, s43
	s_cselect_b32 s42, s64, s42
	s_cselect_b32 s47, s4, s47
	s_cselect_b32 s46, s5, s46
	s_cselect_b32 s49, s63, s49
	s_cselect_b32 s48, s35, s48
	v_lshl_add_u64 v[216:217], v[142:143], 0, s[40:41]
	s_add_i32 m0, s52, 0xc000
	s_nop 0
	global_load_lds_dwordx4 v[216:217], off
	v_lshl_add_u64 v[216:217], v[144:145], 0, s[40:41]
	s_add_i32 m0, s52, 0xe000
	s_nop 0
	global_load_lds_dwordx4 v[216:217], off
	s_waitcnt vmcnt(8) lgkmcnt(0)
	s_barrier
	v_mfma_f32_16x16x32_bf16 v[126:129], v[152:155], v[184:187], 0
	v_mfma_f32_16x16x32_bf16 v[122:125], v[160:163], v[184:187], 0
	v_mfma_f32_16x16x32_bf16 v[110:113], v[152:155], v[192:195], 0
	v_mfma_f32_16x16x32_bf16 v[106:109], v[160:163], v[192:195], 0
	v_mfma_f32_16x16x32_bf16 v[94:97], v[152:155], v[200:203], 0
	v_mfma_f32_16x16x32_bf16 v[90:93], v[160:163], v[200:203], 0
	v_mfma_f32_16x16x32_bf16 v[78:81], v[152:155], v[208:211], 0
	v_mfma_f32_16x16x32_bf16 v[74:77], v[160:163], v[208:211], 0
	v_mfma_f32_16x16x32_bf16 v[126:129], v[156:159], v[188:191], v[126:129]
	v_mfma_f32_16x16x32_bf16 v[122:125], v[164:167], v[188:191], v[122:125]
	v_mfma_f32_16x16x32_bf16 v[110:113], v[156:159], v[196:199], v[110:113]
	v_mfma_f32_16x16x32_bf16 v[106:109], v[164:167], v[196:199], v[106:109]
	v_mfma_f32_16x16x32_bf16 v[94:97], v[156:159], v[204:207], v[94:97]
	v_mfma_f32_16x16x32_bf16 v[90:93], v[164:167], v[204:207], v[90:93]
	v_mfma_f32_16x16x32_bf16 v[78:81], v[156:159], v[212:215], v[78:81]
	v_mfma_f32_16x16x32_bf16 v[74:77], v[164:167], v[212:215], v[74:77]
	v_mfma_f32_16x16x32_bf16 v[118:121], v[168:171], v[184:187], 0
	v_mfma_f32_16x16x32_bf16 v[114:117], v[176:179], v[184:187], 0
	v_mfma_f32_16x16x32_bf16 v[102:105], v[168:171], v[192:195], 0
	v_mfma_f32_16x16x32_bf16 v[98:101], v[176:179], v[192:195], 0
	v_mfma_f32_16x16x32_bf16 v[86:89], v[168:171], v[200:203], 0
	v_mfma_f32_16x16x32_bf16 v[82:85], v[176:179], v[200:203], 0
	v_mfma_f32_16x16x32_bf16 v[70:73], v[168:171], v[208:211], 0
	v_mfma_f32_16x16x32_bf16 v[66:69], v[176:179], v[208:211], 0
	v_mfma_f32_16x16x32_bf16 v[118:121], v[172:175], v[188:191], v[118:121]
	v_mfma_f32_16x16x32_bf16 v[114:117], v[180:183], v[188:191], v[114:117]
	v_mfma_f32_16x16x32_bf16 v[102:105], v[172:175], v[196:199], v[102:105]
	v_mfma_f32_16x16x32_bf16 v[98:101], v[180:183], v[196:199], v[98:101]
	v_mfma_f32_16x16x32_bf16 v[86:89], v[172:175], v[204:207], v[86:89]
	v_mfma_f32_16x16x32_bf16 v[82:85], v[180:183], v[204:207], v[82:85]
	v_mfma_f32_16x16x32_bf16 v[70:73], v[172:175], v[212:215], v[70:73]
	v_mfma_f32_16x16x32_bf16 v[66:69], v[180:183], v[212:215], v[66:69]
	s_barrier
	ds_read_b128 v[184:187], v150 offset:16384
	ds_read_b128 v[188:191], v150 offset:17408
	ds_read_b128 v[192:195], v150 offset:18432
	ds_read_b128 v[196:199], v150 offset:19456
	ds_read_b128 v[200:203], v150 offset:20480
	ds_read_b128 v[204:207], v150 offset:21504
	ds_read_b128 v[208:211], v150 offset:22528
	ds_read_b128 v[212:215], v150 offset:23552
	s_add_i32 s60, s72, s51
	s_mov_b32 m0, s60
	s_nop 0
	global_load_lds_dwordx4 v130, s[46:47]
	s_add_i32 m0, s60, 0x2000
	s_add_u32 s60, s46, 0x4000
	s_addc_u32 s61, s47, 0
	s_add_i32 s81, s73, s51
	global_load_lds_dwordx4 v132, s[46:47]
	s_mov_b32 m0, s81
	s_nop 0
	global_load_lds_dwordx4 v130, s[60:61]
	s_add_i32 m0, s81, 0x2000
	s_nop 0
	global_load_lds_dwordx4 v132, s[60:61]
	s_mov_b32 m0, s52
	s_nop 0
	global_load_lds_dwordx4 v130, s[48:49]
	s_mov_b32 m0, s53
	s_nop 0
	global_load_lds_dwordx4 v132, s[48:49]
	s_waitcnt vmcnt(8) lgkmcnt(0)
	s_barrier
; #define PG8_STAGE(bufoff, gbase, voff) do { _Pragma("unroll") for (int _i = 0; _i < 2; ++_i) \
;         __builtin_amdgcn_global_load_lds((const unsigned*)((const char*)(gbase) + (voff)[_i]), (LAS unsigned*)(lds + (bufoff) + ldsw + _i * 8192), 16, 0, 0); } while (0)
; #define PG8_LDA(dst, b, h) do { _Pragma("unroll") for (int m = 0; m < 4; ++m) _Pragma("unroll") for (int k = 0; k < 2; ++k) dst[m][k] = *(const LAS bf16x8*)(lds + PG8_SA(b, h) + aoff + m * 2048 + k * 1024); } while (0)
; #define PG8_LDB(dst, b, h) do { _Pragma("unroll") for (int n = 0; n < 2; ++n) _Pragma("unroll") for (int k = 0; k < 2; ++k) dst[n][k] = *(const LAS bf16x8*)(lds + PG8_SB(b, h) + boff + n * 2048 + k * 1024); } while (0)
; #define PG8_MMA(ai, bj, At, Bt) do { __builtin_amdgcn_s_setprio(1); _Pragma("unroll") for (int m = 0; m < 4; ++m) _Pragma("unroll") for (int n = 0; n < 2; ++n) _Pragma("unroll") for (int k = 0; k < 2; ++k) \
;         acc[ai][bj][m][n] = __builtin_amdgcn_mfma_f32_16x16x32_bf16(Bt[n][k], At[m][k], acc[ai][bj][m][n], 0, 0, 0); __builtin_amdgcn_s_setprio(0); } while (0)
; #define PG8_WAIT_V(n) asm volatile("s_waitcnt vmcnt(" #n ")" ::: "memory")
; #define PG8_WAIT_L(n) asm volatile("s_waitcnt lgkmcnt(" #n ")" ::: "memory")
; #define PG8_BAR __builtin_amdgcn_s_barrier()
; #define PG8_SCHED __builtin_amdgcn_sched_barrier(0)
; template <class Epi, class Sched, bool ABLK = false, bool ALIGN_EPI = true, bool SP2 = true, bool BBLK = true>
; __device__ __forceinline__ void gemm_phase(LAS unsigned char* lds, const Gemm g, const Sched& S, const Epi& E) {
;     ...
;             PG8_WAIT_V(8); PG8_WAIT_L(0); PG8_BAR; PG8_MMA(1, 0, At, B0); PG8_MMA(1, 1, At, B1); PG8_BAR; PG8_SCHED;
;             PG8_LDB(B0, 1, 0); PG8_LDB(B1, 1, 1); PG8_SCHED; PG8_LDA(At, 1, 0); PG8_STAGE(PG8_SA(0, 1), a2 + hstepA, voffA);
;             PG8_WAIT_V(8); PG8_WAIT_L(0); PG8_BAR; PG8_MMA(0, 0, At, B0); PG8_MMA(0, 1, At, B1); PG8_BAR; PG8_SCHED;
	v_mfma_f32_16x16x32_bf16 v[62:65], v[152:155], v[184:187], 0
	v_mfma_f32_16x16x32_bf16 v[58:61], v[160:163], v[184:187], 0
	v_mfma_f32_16x16x32_bf16 v[46:49], v[152:155], v[192:195], 0
	v_mfma_f32_16x16x32_bf16 v[42:45], v[160:163], v[192:195], 0
	v_mfma_f32_16x16x32_bf16 v[30:33], v[152:155], v[200:203], 0
	v_mfma_f32_16x16x32_bf16 v[26:29], v[160:163], v[200:203], 0
	v_mfma_f32_16x16x32_bf16 v[14:17], v[152:155], v[208:211], 0
	v_mfma_f32_16x16x32_bf16 v[10:13], v[160:163], v[208:211], 0
	v_mfma_f32_16x16x32_bf16 v[62:65], v[156:159], v[188:191], v[62:65]
	v_mfma_f32_16x16x32_bf16 v[58:61], v[164:167], v[188:191], v[58:61]
	v_mfma_f32_16x16x32_bf16 v[46:49], v[156:159], v[196:199], v[46:49]
	v_mfma_f32_16x16x32_bf16 v[42:45], v[164:167], v[196:199], v[42:45]
	v_mfma_f32_16x16x32_bf16 v[30:33], v[156:159], v[204:207], v[30:33]
	v_mfma_f32_16x16x32_bf16 v[26:29], v[164:167], v[204:207], v[26:29]
	v_mfma_f32_16x16x32_bf16 v[14:17], v[156:159], v[212:215], v[14:17]
	v_mfma_f32_16x16x32_bf16 v[10:13], v[164:167], v[212:215], v[10:13]
	v_mfma_f32_16x16x32_bf16 v[54:57], v[168:171], v[184:187], 0
	v_mfma_f32_16x16x32_bf16 v[50:53], v[176:179], v[184:187], 0
	v_mfma_f32_16x16x32_bf16 v[38:41], v[168:171], v[192:195], 0
	v_mfma_f32_16x16x32_bf16 v[34:37], v[176:179], v[192:195], 0
	v_mfma_f32_16x16x32_bf16 v[22:25], v[168:171], v[200:203], 0
	v_mfma_f32_16x16x32_bf16 v[18:21], v[176:179], v[200:203], 0
	v_mfma_f32_16x16x32_bf16 v[6:9], v[168:171], v[208:211], 0
	v_mfma_f32_16x16x32_bf16 v[2:5], v[176:179], v[208:211], 0
	v_mfma_f32_16x16x32_bf16 v[54:57], v[172:175], v[188:191], v[54:57]
	v_mfma_f32_16x16x32_bf16 v[50:53], v[180:183], v[188:191], v[50:53]
	v_mfma_f32_16x16x32_bf16 v[38:41], v[172:175], v[196:199], v[38:41]
	v_mfma_f32_16x16x32_bf16 v[34:37], v[180:183], v[196:199], v[34:37]
	v_mfma_f32_16x16x32_bf16 v[22:25], v[172:175], v[204:207], v[22:25]
	v_mfma_f32_16x16x32_bf16 v[18:21], v[180:183], v[204:207], v[18:21]
	v_mfma_f32_16x16x32_bf16 v[6:9], v[172:175], v[212:215], v[6:9]
	v_mfma_f32_16x16x32_bf16 v[2:5], v[180:183], v[212:215], v[2:5]
	s_barrier
	s_add_i32 s60, 0, 0x18000
	v_add_u32_e32 v151, s60, v146
	s_add_i32 s61, 0, 0x1c000
	ds_read_b128 v[152:155], v151
	ds_read_b128 v[156:159], v151 offset:1024
	ds_read_b128 v[160:163], v151 offset:2048
	ds_read_b128 v[164:167], v151 offset:3072
	v_add_u32_e32 v151, s61, v146
	ds_read_b128 v[168:171], v151
	ds_read_b128 v[172:175], v151 offset:1024
	ds_read_b128 v[176:179], v151 offset:2048
	ds_read_b128 v[180:183], v151 offset:3072
	ds_read_b128 v[184:187], v150 offset:32768
	ds_read_b128 v[188:191], v150 offset:33792
	ds_read_b128 v[192:195], v150 offset:34816
	ds_read_b128 v[196:199], v150 offset:35840
	ds_read_b128 v[200:203], v150 offset:36864
	ds_read_b128 v[204:207], v150 offset:37888
	ds_read_b128 v[208:211], v150 offset:38912
	ds_read_b128 v[212:215], v150 offset:39936
	s_add_u32 s48, s48, 0x4000
	s_addc_u32 s49, s49, 0
	s_mov_b32 m0, s54
	s_nop 0
	global_load_lds_dwordx4 v130, s[48:49]
	s_mov_b32 m0, s55
	s_nop 0
	global_load_lds_dwordx4 v132, s[48:49]
	s_waitcnt vmcnt(8) lgkmcnt(0)
	s_barrier
	v_mfma_f32_16x16x32_bf16 v[126:129], v[152:155], v[184:187], v[126:129]
	v_mfma_f32_16x16x32_bf16 v[122:125], v[160:163], v[184:187], v[122:125]
	v_mfma_f32_16x16x32_bf16 v[110:113], v[152:155], v[192:195], v[110:113]
	v_mfma_f32_16x16x32_bf16 v[106:109], v[160:163], v[192:195], v[106:109]
	v_mfma_f32_16x16x32_bf16 v[94:97], v[152:155], v[200:203], v[94:97]
	v_mfma_f32_16x16x32_bf16 v[90:93], v[160:163], v[200:203], v[90:93]
	v_mfma_f32_16x16x32_bf16 v[78:81], v[152:155], v[208:211], v[78:81]
	v_mfma_f32_16x16x32_bf16 v[74:77], v[160:163], v[208:211], v[74:77]
	v_mfma_f32_16x16x32_bf16 v[126:129], v[156:159], v[188:191], v[126:129]
	v_mfma_f32_16x16x32_bf16 v[122:125], v[164:167], v[188:191], v[122:125]
	v_mfma_f32_16x16x32_bf16 v[110:113], v[156:159], v[196:199], v[110:113]
	v_mfma_f32_16x16x32_bf16 v[106:109], v[164:167], v[196:199], v[106:109]
	v_mfma_f32_16x16x32_bf16 v[94:97], v[156:159], v[204:207], v[94:97]
	v_mfma_f32_16x16x32_bf16 v[90:93], v[164:167], v[204:207], v[90:93]
	v_mfma_f32_16x16x32_bf16 v[78:81], v[156:159], v[212:215], v[78:81]
	v_mfma_f32_16x16x32_bf16 v[74:77], v[164:167], v[212:215], v[74:77]
	v_mfma_f32_16x16x32_bf16 v[118:121], v[168:171], v[184:187], v[118:121]
	v_mfma_f32_16x16x32_bf16 v[114:117], v[176:179], v[184:187], v[114:117]
	v_mfma_f32_16x16x32_bf16 v[102:105], v[168:171], v[192:195], v[102:105]
	v_mfma_f32_16x16x32_bf16 v[98:101], v[176:179], v[192:195], v[98:101]
	v_mfma_f32_16x16x32_bf16 v[86:89], v[168:171], v[200:203], v[86:89]
	v_mfma_f32_16x16x32_bf16 v[82:85], v[176:179], v[200:203], v[82:85]
	v_mfma_f32_16x16x32_bf16 v[70:73], v[168:171], v[208:211], v[70:73]
	v_mfma_f32_16x16x32_bf16 v[66:69], v[176:179], v[208:211], v[66:69]
	v_mfma_f32_16x16x32_bf16 v[118:121], v[172:175], v[188:191], v[118:121]
	v_mfma_f32_16x16x32_bf16 v[114:117], v[180:183], v[188:191], v[114:117]
	v_mfma_f32_16x16x32_bf16 v[102:105], v[172:175], v[196:199], v[102:105]
	v_mfma_f32_16x16x32_bf16 v[98:101], v[180:183], v[196:199], v[98:101]
	v_mfma_f32_16x16x32_bf16 v[86:89], v[172:175], v[204:207], v[86:89]
	v_mfma_f32_16x16x32_bf16 v[82:85], v[180:183], v[204:207], v[82:85]
	v_mfma_f32_16x16x32_bf16 v[70:73], v[172:175], v[212:215], v[70:73]
	v_mfma_f32_16x16x32_bf16 v[66:69], v[180:183], v[212:215], v[66:69]
	s_barrier
; #define PG8_STAGE(bufoff, gbase, voff) do { _Pragma("unroll") for (int _i = 0; _i < 2; ++_i) \
;         __builtin_amdgcn_global_load_lds((const unsigned*)((const char*)(gbase) + (voff)[_i]), (LAS unsigned*)(lds + (bufoff) + ldsw + _i * 8192), 16, 0, 0); } while (0)
; #define PG8_LDA(dst, b, h) do { _Pragma("unroll") for (int m = 0; m < 4; ++m) _Pragma("unroll") for (int k = 0; k < 2; ++k) dst[m][k] = *(const LAS bf16x8*)(lds + PG8_SA(b, h) + aoff + m * 2048 + k * 1024); } while (0)
; #define PG8_WAIT_V(n) asm volatile("s_waitcnt vmcnt(" #n ")" ::: "memory")
; #define PG8_WAIT_L(n) asm volatile("s_waitcnt lgkmcnt(" #n ")" ::: "memory")
; template <class Epi, class Sched, bool ABLK = false, bool ALIGN_EPI = true, bool SP2 = true, bool BBLK = true>
; __device__ __forceinline__ void gemm_phase(LAS unsigned char* lds, const Gemm g, const Sched& S, const Epi& E) {
;     ...
;             const bool last = (t == nt - 2);
;             const char* a1 = a_tile(uA, tbA + t + 1);
;             const char* a2 = last ? a_tile(nuA, ntbA) : a_tile(uA, tbA + t + 2); const char* b2 = last ? nB : cB + (size_t)(t + 2) * kstepB;
;             const char* a3 = last ? a_tile(nuA, ntbA + 1) : a_tile(uA, tbA + t + 3); const char* b3 = b2 + kstepB;
;             if (last && has_next) S.a_ready(nxt);
;             if constexpr (SP2) {
;             PG8_LDB(B0, 0, 0); PG8_LDB(B1, 0, 1); PG8_SCHED; PG8_LDA(At, 0, 0); PG8_STAGE(PG8_SA(1, 1), a1 + hstepA, voffA);
;             PG8_WAIT_V(8); PG8_WAIT_L(0); PG8_BAR; PG8_MMA(0, 0, At, B0); PG8_MMA(0, 1, At, B1); PG8_BAR; PG8_SCHED;
;             PG8_LDA(At, 0, 1); PG8_STAGE(PG8_SB(0, 0), b2, voffB); PG8_STAGE(PG8_SB(0, 1), b2 + hstepB, voffB); PG8_STAGE(PG8_SA(0, 0), a2, voffA);
;             PG8_WAIT_V(8); PG8_WAIT_L(0); PG8_BAR; PG8_MMA(1, 0, At, B0); PG8_MMA(1, 1, At, B1); PG8_BAR; PG8_SCHED;
;             PG8_LDB(B0, 1, 0); PG8_LDB(B1, 1, 1); PG8_SCHED; PG8_LDA(At, 1, 0); PG8_STAGE(PG8_SA(0, 1), a2 + hstepA, voffA);
;             PG8_WAIT_V(8); PG8_WAIT_L(0); PG8_BAR; PG8_MMA(0, 0, At, B0); PG8_MMA(0, 1, At, B1); PG8_BAR; PG8_SCHED;
;             PG8_LDA(At, 1, 1); PG8_STAGE(PG8_SB(1, 0), b3, voffB); PG8_STAGE(PG8_SB(1, 1), b3 + hstepB, voffB); PG8_STAGE(PG8_SA(1, 0), a3, voffA);
;             PG8_WAIT_V(8); PG8_WAIT_L(0); PG8_BAR; PG8_MMA(1, 0, At, B0); PG8_MMA(1, 1, At, B1); PG8_BAR; PG8_SCHED;
	ds_read_b128 v[184:187], v150 offset:49152
	ds_read_b128 v[188:191], v150 offset:50176
	ds_read_b128 v[192:195], v150 offset:51200
	ds_read_b128 v[196:199], v150 offset:52224
	ds_read_b128 v[200:203], v150 offset:53248
	ds_read_b128 v[204:207], v150 offset:54272
	ds_read_b128 v[208:211], v150 offset:55296
	ds_read_b128 v[212:215], v150 offset:56320
	s_add_u32 s48, s46, 0x8000
	s_addc_u32 s49, s47, 0
	s_add_i32 s81, s60, s51
	s_mov_b32 m0, s81
	s_nop 0
	global_load_lds_dwordx4 v130, s[48:49]
	s_add_i32 m0, s81, 0x2000
	s_add_u32 s46, s46, 0xc000
	v_lshl_add_u64 v[216:217], s[48:49], 0, v[132:133]
	s_addc_u32 s47, s47, 0
	s_add_i32 s48, s61, s51
	global_load_lds_dwordx4 v[216:217], off
	s_mov_b32 m0, s48
	s_nop 0
	global_load_lds_dwordx4 v130, s[46:47]
	s_add_i32 m0, s48, 0x2000
	s_nop 0
	global_load_lds_dwordx4 v132, s[46:47]
	s_mov_b32 m0, s56
	s_nop 0
	global_load_lds_dwordx4 v130, s[42:43]
	s_mov_b32 m0, s57
	s_nop 0
	global_load_lds_dwordx4 v132, s[42:43]
	s_waitcnt vmcnt(8) lgkmcnt(0)
	s_barrier
	v_mfma_f32_16x16x32_bf16 v[62:65], v[152:155], v[184:187], v[62:65]
	v_mfma_f32_16x16x32_bf16 v[58:61], v[160:163], v[184:187], v[58:61]
	v_mfma_f32_16x16x32_bf16 v[46:49], v[152:155], v[192:195], v[46:49]
	v_mfma_f32_16x16x32_bf16 v[42:45], v[160:163], v[192:195], v[42:45]
	v_mfma_f32_16x16x32_bf16 v[30:33], v[152:155], v[200:203], v[30:33]
	v_mfma_f32_16x16x32_bf16 v[26:29], v[160:163], v[200:203], v[26:29]
	v_mfma_f32_16x16x32_bf16 v[14:17], v[152:155], v[208:211], v[14:17]
	v_mfma_f32_16x16x32_bf16 v[10:13], v[160:163], v[208:211], v[10:13]
	v_mfma_f32_16x16x32_bf16 v[62:65], v[156:159], v[188:191], v[62:65]
	v_mfma_f32_16x16x32_bf16 v[58:61], v[164:167], v[188:191], v[58:61]
	v_mfma_f32_16x16x32_bf16 v[46:49], v[156:159], v[196:199], v[46:49]
	v_mfma_f32_16x16x32_bf16 v[42:45], v[164:167], v[196:199], v[42:45]
	v_mfma_f32_16x16x32_bf16 v[30:33], v[156:159], v[204:207], v[30:33]
	v_mfma_f32_16x16x32_bf16 v[26:29], v[164:167], v[204:207], v[26:29]
	v_mfma_f32_16x16x32_bf16 v[14:17], v[156:159], v[212:215], v[14:17]
	v_mfma_f32_16x16x32_bf16 v[10:13], v[164:167], v[212:215], v[10:13]
	v_mfma_f32_16x16x32_bf16 v[54:57], v[168:171], v[184:187], v[54:57]
	v_mfma_f32_16x16x32_bf16 v[50:53], v[176:179], v[184:187], v[50:53]
	v_mfma_f32_16x16x32_bf16 v[38:41], v[168:171], v[192:195], v[38:41]
	v_mfma_f32_16x16x32_bf16 v[34:37], v[176:179], v[192:195], v[34:37]
	v_mfma_f32_16x16x32_bf16 v[22:25], v[168:171], v[200:203], v[22:25]
	v_mfma_f32_16x16x32_bf16 v[18:21], v[176:179], v[200:203], v[18:21]
	v_mfma_f32_16x16x32_bf16 v[6:9], v[168:171], v[208:211], v[6:9]
	v_mfma_f32_16x16x32_bf16 v[2:5], v[176:179], v[208:211], v[2:5]
	v_mfma_f32_16x16x32_bf16 v[54:57], v[172:175], v[188:191], v[54:57]
	v_mfma_f32_16x16x32_bf16 v[50:53], v[180:183], v[188:191], v[50:53]
	v_mfma_f32_16x16x32_bf16 v[38:41], v[172:175], v[196:199], v[38:41]
	v_mfma_f32_16x16x32_bf16 v[34:37], v[180:183], v[196:199], v[34:37]
	v_mfma_f32_16x16x32_bf16 v[22:25], v[172:175], v[204:207], v[22:25]
	v_mfma_f32_16x16x32_bf16 v[18:21], v[180:183], v[204:207], v[18:21]
	v_mfma_f32_16x16x32_bf16 v[6:9], v[172:175], v[212:215], v[6:9]
	v_mfma_f32_16x16x32_bf16 v[2:5], v[180:183], v[212:215], v[2:5]
	s_barrier
	s_add_u32 s40, s40, 0x10000
	s_addc_u32 s41, s41, 0
	s_cmp_ge_u32 s79, s59
.LBB0_540:
	ds_read_b128 v[152:155], v148
	ds_read_b128 v[156:159], v148 offset:1024
	ds_read_b128 v[160:163], v148 offset:2048
	ds_read_b128 v[164:167], v148 offset:3072
	ds_read_b128 v[168:171], v149
	ds_read_b128 v[172:175], v149 offset:1024
	ds_read_b128 v[176:179], v149 offset:2048
	ds_read_b128 v[180:183], v149 offset:3072
	ds_read_b128 v[184:187], v150
	ds_read_b128 v[188:191], v150 offset:1024
	ds_read_b128 v[192:195], v150 offset:2048
	ds_read_b128 v[196:199], v150 offset:3072
	ds_read_b128 v[200:203], v150 offset:4096
	ds_read_b128 v[204:207], v150 offset:5120
	ds_read_b128 v[208:211], v150 offset:6144
	ds_read_b128 v[212:215], v150 offset:7168
	s_add_u32 s42, s75, s40
	s_addc_u32 s43, s76, s41
	s_add_u32 s48, s42, 0x10000
	s_addc_u32 s49, s43, 0
	s_add_i32 s79, s79, 2
	s_add_u32 s46, s66, s40
	s_addc_u32 s47, s67, s41
	s_add_u32 s42, s42, 0x18000
	s_addc_u32 s43, s43, 0
	s_cmp_eq_u32 s77, s40
	s_cselect_b32 s43, s65, s43
	s_cselect_b32 s42, s64, s42
	s_cselect_b32 s47, s4, s47
	s_cselect_b32 s46, s5, s46
	s_cselect_b32 s49, s63, s49
	s_cselect_b32 s48, s35, s48
	v_lshl_add_u64 v[216:217], v[142:143], 0, s[40:41]
	s_add_i32 m0, s52, 0xc000
	s_nop 0
	global_load_lds_dwordx4 v[216:217], off
	v_lshl_add_u64 v[216:217], v[144:145], 0, s[40:41]
	s_add_i32 m0, s52, 0xe000
	s_nop 0
	global_load_lds_dwordx4 v[216:217], off
	s_waitcnt vmcnt(8) lgkmcnt(0)
	s_barrier
; #define PG8_STAGE(bufoff, gbase, voff) do { _Pragma("unroll") for (int _i = 0; _i < 2; ++_i) \
;         __builtin_amdgcn_global_load_lds((const unsigned*)((const char*)(gbase) + (voff)[_i]), (LAS unsigned*)(lds + (bufoff) + ldsw + _i * 8192), 16, 0, 0); } while (0)
; #define PG8_LDA(dst, b, h) do { _Pragma("unroll") for (int m = 0; m < 4; ++m) _Pragma("unroll") for (int k = 0; k < 2; ++k) dst[m][k] = *(const LAS bf16x8*)(lds + PG8_SA(b, h) + aoff + m * 2048 + k * 1024); } while (0)
; #define PG8_LDB(dst, b, h) do { _Pragma("unroll") for (int n = 0; n < 2; ++n) _Pragma("unroll") for (int k = 0; k < 2; ++k) dst[n][k] = *(const LAS bf16x8*)(lds + PG8_SB(b, h) + boff + n * 2048 + k * 1024); } while (0)
; #define PG8_MMA(ai, bj, At, Bt) do { __builtin_amdgcn_s_setprio(1); _Pragma("unroll") for (int m = 0; m < 4; ++m) _Pragma("unroll") for (int n = 0; n < 2; ++n) _Pragma("unroll") for (int k = 0; k < 2; ++k) \
;         acc[ai][bj][m][n] = __builtin_amdgcn_mfma_f32_16x16x32_bf16(Bt[n][k], At[m][k], acc[ai][bj][m][n], 0, 0, 0); __builtin_amdgcn_s_setprio(0); } while (0)
; #define PG8_WAIT_V(n) asm volatile("s_waitcnt vmcnt(" #n ")" ::: "memory")
; #define PG8_WAIT_L(n) asm volatile("s_waitcnt lgkmcnt(" #n ")" ::: "memory")
; #define PG8_BAR __builtin_amdgcn_s_barrier()
; #define PG8_SCHED __builtin_amdgcn_sched_barrier(0)
; template <class Epi, class Sched, bool ABLK = false, bool ALIGN_EPI = true, bool SP2 = true, bool BBLK = true>
; __device__ __forceinline__ void gemm_phase(LAS unsigned char* lds, const Gemm g, const Sched& S, const Epi& E) {
;     ...
;             PG8_LDB(B0, 0, 0); PG8_LDB(B1, 0, 1); PG8_SCHED; PG8_LDA(At, 0, 0); PG8_STAGE(PG8_SA(1, 1), a1 + hstepA, voffA);
;             PG8_WAIT_V(8); PG8_WAIT_L(0); PG8_BAR; PG8_MMA(0, 0, At, B0); PG8_MMA(0, 1, At, B1); PG8_BAR; PG8_SCHED;
;             PG8_LDA(At, 0, 1); PG8_STAGE(PG8_SB(0, 0), b2, voffB); PG8_STAGE(PG8_SB(0, 1), b2 + hstepB, voffB); PG8_STAGE(PG8_SA(0, 0), a2, voffA);
;             PG8_WAIT_V(8); PG8_WAIT_L(0); PG8_BAR; PG8_MMA(1, 0, At, B0); PG8_MMA(1, 1, At, B1); PG8_BAR; PG8_SCHED;
	v_mfma_f32_16x16x32_bf16 v[126:129], v[152:155], v[184:187], v[126:129]
	v_mfma_f32_16x16x32_bf16 v[122:125], v[160:163], v[184:187], v[122:125]
	v_mfma_f32_16x16x32_bf16 v[110:113], v[152:155], v[192:195], v[110:113]
	v_mfma_f32_16x16x32_bf16 v[106:109], v[160:163], v[192:195], v[106:109]
	v_mfma_f32_16x16x32_bf16 v[94:97], v[152:155], v[200:203], v[94:97]
	v_mfma_f32_16x16x32_bf16 v[90:93], v[160:163], v[200:203], v[90:93]
	v_mfma_f32_16x16x32_bf16 v[78:81], v[152:155], v[208:211], v[78:81]
	v_mfma_f32_16x16x32_bf16 v[74:77], v[160:163], v[208:211], v[74:77]
	v_mfma_f32_16x16x32_bf16 v[126:129], v[156:159], v[188:191], v[126:129]
	v_mfma_f32_16x16x32_bf16 v[122:125], v[164:167], v[188:191], v[122:125]
	v_mfma_f32_16x16x32_bf16 v[110:113], v[156:159], v[196:199], v[110:113]
	v_mfma_f32_16x16x32_bf16 v[106:109], v[164:167], v[196:199], v[106:109]
	v_mfma_f32_16x16x32_bf16 v[94:97], v[156:159], v[204:207], v[94:97]
	v_mfma_f32_16x16x32_bf16 v[90:93], v[164:167], v[204:207], v[90:93]
	v_mfma_f32_16x16x32_bf16 v[78:81], v[156:159], v[212:215], v[78:81]
	v_mfma_f32_16x16x32_bf16 v[74:77], v[164:167], v[212:215], v[74:77]
	v_mfma_f32_16x16x32_bf16 v[118:121], v[168:171], v[184:187], v[118:121]
	v_mfma_f32_16x16x32_bf16 v[114:117], v[176:179], v[184:187], v[114:117]
	v_mfma_f32_16x16x32_bf16 v[102:105], v[168:171], v[192:195], v[102:105]
	v_mfma_f32_16x16x32_bf16 v[98:101], v[176:179], v[192:195], v[98:101]
	v_mfma_f32_16x16x32_bf16 v[86:89], v[168:171], v[200:203], v[86:89]
	v_mfma_f32_16x16x32_bf16 v[82:85], v[176:179], v[200:203], v[82:85]
	v_mfma_f32_16x16x32_bf16 v[70:73], v[168:171], v[208:211], v[70:73]
	v_mfma_f32_16x16x32_bf16 v[66:69], v[176:179], v[208:211], v[66:69]
	v_mfma_f32_16x16x32_bf16 v[118:121], v[172:175], v[188:191], v[118:121]
	v_mfma_f32_16x16x32_bf16 v[114:117], v[180:183], v[188:191], v[114:117]
	v_mfma_f32_16x16x32_bf16 v[102:105], v[172:175], v[196:199], v[102:105]
	v_mfma_f32_16x16x32_bf16 v[98:101], v[180:183], v[196:199], v[98:101]
	v_mfma_f32_16x16x32_bf16 v[86:89], v[172:175], v[204:207], v[86:89]
	v_mfma_f32_16x16x32_bf16 v[82:85], v[180:183], v[204:207], v[82:85]
	v_mfma_f32_16x16x32_bf16 v[70:73], v[172:175], v[212:215], v[70:73]
	v_mfma_f32_16x16x32_bf16 v[66:69], v[180:183], v[212:215], v[66:69]
	s_barrier
	ds_read_b128 v[184:187], v150 offset:16384
	ds_read_b128 v[188:191], v150 offset:17408
	ds_read_b128 v[192:195], v150 offset:18432
	ds_read_b128 v[196:199], v150 offset:19456
	ds_read_b128 v[200:203], v150 offset:20480
	ds_read_b128 v[204:207], v150 offset:21504
	ds_read_b128 v[208:211], v150 offset:22528
	ds_read_b128 v[212:215], v150 offset:23552
	s_add_i32 s60, s72, s51
	s_mov_b32 m0, s60
	s_nop 0
	global_load_lds_dwordx4 v130, s[46:47]
	s_add_i32 m0, s60, 0x2000
	s_add_u32 s60, s46, 0x4000
	s_addc_u32 s61, s47, 0
	s_add_i32 s81, s73, s51
	global_load_lds_dwordx4 v132, s[46:47]
	s_mov_b32 m0, s81
	s_nop 0
	global_load_lds_dwordx4 v130, s[60:61]
	s_add_i32 m0, s81, 0x2000
	s_nop 0
	global_load_lds_dwordx4 v132, s[60:61]
	s_mov_b32 m0, s52
	s_nop 0
	global_load_lds_dwordx4 v130, s[48:49]
	s_mov_b32 m0, s53
	s_nop 0
	global_load_lds_dwordx4 v132, s[48:49]
	s_waitcnt vmcnt(8) lgkmcnt(0)
	s_barrier
	v_mfma_f32_16x16x32_bf16 v[62:65], v[152:155], v[184:187], v[62:65]
	v_mfma_f32_16x16x32_bf16 v[58:61], v[160:163], v[184:187], v[58:61]
	v_mfma_f32_16x16x32_bf16 v[46:49], v[152:155], v[192:195], v[46:49]
	v_mfma_f32_16x16x32_bf16 v[42:45], v[160:163], v[192:195], v[42:45]
	v_mfma_f32_16x16x32_bf16 v[30:33], v[152:155], v[200:203], v[30:33]
	v_mfma_f32_16x16x32_bf16 v[26:29], v[160:163], v[200:203], v[26:29]
	v_mfma_f32_16x16x32_bf16 v[14:17], v[152:155], v[208:211], v[14:17]
	v_mfma_f32_16x16x32_bf16 v[10:13], v[160:163], v[208:211], v[10:13]
	v_mfma_f32_16x16x32_bf16 v[62:65], v[156:159], v[188:191], v[62:65]
	v_mfma_f32_16x16x32_bf16 v[58:61], v[164:167], v[188:191], v[58:61]
	v_mfma_f32_16x16x32_bf16 v[46:49], v[156:159], v[196:199], v[46:49]
	v_mfma_f32_16x16x32_bf16 v[42:45], v[164:167], v[196:199], v[42:45]
	v_mfma_f32_16x16x32_bf16 v[30:33], v[156:159], v[204:207], v[30:33]
	v_mfma_f32_16x16x32_bf16 v[26:29], v[164:167], v[204:207], v[26:29]
	v_mfma_f32_16x16x32_bf16 v[14:17], v[156:159], v[212:215], v[14:17]
	v_mfma_f32_16x16x32_bf16 v[10:13], v[164:167], v[212:215], v[10:13]
	v_mfma_f32_16x16x32_bf16 v[54:57], v[168:171], v[184:187], v[54:57]
	v_mfma_f32_16x16x32_bf16 v[50:53], v[176:179], v[184:187], v[50:53]
	v_mfma_f32_16x16x32_bf16 v[38:41], v[168:171], v[192:195], v[38:41]
	v_mfma_f32_16x16x32_bf16 v[34:37], v[176:179], v[192:195], v[34:37]
	v_mfma_f32_16x16x32_bf16 v[22:25], v[168:171], v[200:203], v[22:25]
	v_mfma_f32_16x16x32_bf16 v[18:21], v[176:179], v[200:203], v[18:21]
	v_mfma_f32_16x16x32_bf16 v[6:9], v[168:171], v[208:211], v[6:9]
	v_mfma_f32_16x16x32_bf16 v[2:5], v[176:179], v[208:211], v[2:5]
	v_mfma_f32_16x16x32_bf16 v[54:57], v[172:175], v[188:191], v[54:57]
	v_mfma_f32_16x16x32_bf16 v[50:53], v[180:183], v[188:191], v[50:53]
	v_mfma_f32_16x16x32_bf16 v[38:41], v[172:175], v[196:199], v[38:41]
	v_mfma_f32_16x16x32_bf16 v[34:37], v[180:183], v[196:199], v[34:37]
	v_mfma_f32_16x16x32_bf16 v[22:25], v[172:175], v[204:207], v[22:25]
	v_mfma_f32_16x16x32_bf16 v[18:21], v[180:183], v[204:207], v[18:21]
	v_mfma_f32_16x16x32_bf16 v[6:9], v[172:175], v[212:215], v[6:9]
	v_mfma_f32_16x16x32_bf16 v[2:5], v[180:183], v[212:215], v[2:5]
	s_barrier
; #define PG8_STAGE(bufoff, gbase, voff) do { _Pragma("unroll") for (int _i = 0; _i < 2; ++_i) \
;         __builtin_amdgcn_global_load_lds((const unsigned*)((const char*)(gbase) + (voff)[_i]), (LAS unsigned*)(lds + (bufoff) + ldsw + _i * 8192), 16, 0, 0); } while (0)
; #define PG8_LDA(dst, b, h) do { _Pragma("unroll") for (int m = 0; m < 4; ++m) _Pragma("unroll") for (int k = 0; k < 2; ++k) dst[m][k] = *(const LAS bf16x8*)(lds + PG8_SA(b, h) + aoff + m * 2048 + k * 1024); } while (0)
; #define PG8_LDB(dst, b, h) do { _Pragma("unroll") for (int n = 0; n < 2; ++n) _Pragma("unroll") for (int k = 0; k < 2; ++k) dst[n][k] = *(const LAS bf16x8*)(lds + PG8_SB(b, h) + boff + n * 2048 + k * 1024); } while (0)
; #define PG8_MMA(ai, bj, At, Bt) do { __builtin_amdgcn_s_setprio(1); _Pragma("unroll") for (int m = 0; m < 4; ++m) _Pragma("unroll") for (int n = 0; n < 2; ++n) _Pragma("unroll") for (int k = 0; k < 2; ++k) \
;         acc[ai][bj][m][n] = __builtin_amdgcn_mfma_f32_16x16x32_bf16(Bt[n][k], At[m][k], acc[ai][bj][m][n], 0, 0, 0); __builtin_amdgcn_s_setprio(0); } while (0)
; #define PG8_WAIT_V(n) asm volatile("s_waitcnt vmcnt(" #n ")" ::: "memory")
; #define PG8_WAIT_L(n) asm volatile("s_waitcnt lgkmcnt(" #n ")" ::: "memory")
; #define PG8_BAR __builtin_amdgcn_s_barrier()
; #define PG8_SCHED __builtin_amdgcn_sched_barrier(0)
; template <class Epi, class Sched, bool ABLK = false, bool ALIGN_EPI = true, bool SP2 = true, bool BBLK = true>
; __device__ __forceinline__ void gemm_phase(LAS unsigned char* lds, const Gemm g, const Sched& S, const Epi& E) {
;     ...
;             PG8_LDB(B0, 1, 0); PG8_LDB(B1, 1, 1); PG8_SCHED; PG8_LDA(At, 1, 0); PG8_STAGE(PG8_SA(0, 1), a2 + hstepA, voffA);
;             PG8_WAIT_V(8); PG8_WAIT_L(0); PG8_BAR; PG8_MMA(0, 0, At, B0); PG8_MMA(0, 1, At, B1); PG8_BAR; PG8_SCHED;
;             PG8_LDA(At, 1, 1); PG8_STAGE(PG8_SB(1, 0), b3, voffB); PG8_STAGE(PG8_SB(1, 1), b3 + hstepB, voffB); PG8_STAGE(PG8_SA(1, 0), a3, voffA);
;             PG8_WAIT_V(8); PG8_WAIT_L(0); PG8_BAR; PG8_MMA(1, 0, At, B0); PG8_MMA(1, 1, At, B1); PG8_BAR; PG8_SCHED;
;     ...
;         }
;         if constexpr (ALIGN_EPI) { if (wr == 0) PG8_BAR; }
	s_add_i32 s60, 0, 0x18000
	v_add_u32_e32 v151, s60, v146
	s_add_i32 s61, 0, 0x1c000
	ds_read_b128 v[152:155], v151
	ds_read_b128 v[156:159], v151 offset:1024
	ds_read_b128 v[160:163], v151 offset:2048
	ds_read_b128 v[164:167], v151 offset:3072
	v_add_u32_e32 v151, s61, v146
	ds_read_b128 v[168:171], v151
	ds_read_b128 v[172:175], v151 offset:1024
	ds_read_b128 v[176:179], v151 offset:2048
	ds_read_b128 v[180:183], v151 offset:3072
	ds_read_b128 v[184:187], v150 offset:32768
	ds_read_b128 v[188:191], v150 offset:33792
	ds_read_b128 v[192:195], v150 offset:34816
	ds_read_b128 v[196:199], v150 offset:35840
	ds_read_b128 v[200:203], v150 offset:36864
	ds_read_b128 v[204:207], v150 offset:37888
	ds_read_b128 v[208:211], v150 offset:38912
	ds_read_b128 v[212:215], v150 offset:39936
	s_add_u32 s48, s48, 0x4000
	s_addc_u32 s49, s49, 0
	s_mov_b32 m0, s54
	s_nop 0
	global_load_lds_dwordx4 v130, s[48:49]
	s_mov_b32 m0, s55
	s_nop 0
	global_load_lds_dwordx4 v132, s[48:49]
	s_waitcnt vmcnt(8) lgkmcnt(0)
	s_barrier
	v_mfma_f32_16x16x32_bf16 v[126:129], v[152:155], v[184:187], v[126:129]
	v_mfma_f32_16x16x32_bf16 v[122:125], v[160:163], v[184:187], v[122:125]
	v_mfma_f32_16x16x32_bf16 v[110:113], v[152:155], v[192:195], v[110:113]
	v_mfma_f32_16x16x32_bf16 v[106:109], v[160:163], v[192:195], v[106:109]
	v_mfma_f32_16x16x32_bf16 v[94:97], v[152:155], v[200:203], v[94:97]
	v_mfma_f32_16x16x32_bf16 v[90:93], v[160:163], v[200:203], v[90:93]
	v_mfma_f32_16x16x32_bf16 v[78:81], v[152:155], v[208:211], v[78:81]
	v_mfma_f32_16x16x32_bf16 v[74:77], v[160:163], v[208:211], v[74:77]
	v_mfma_f32_16x16x32_bf16 v[126:129], v[156:159], v[188:191], v[126:129]
	v_mfma_f32_16x16x32_bf16 v[122:125], v[164:167], v[188:191], v[122:125]
	v_mfma_f32_16x16x32_bf16 v[110:113], v[156:159], v[196:199], v[110:113]
	v_mfma_f32_16x16x32_bf16 v[106:109], v[164:167], v[196:199], v[106:109]
	v_mfma_f32_16x16x32_bf16 v[94:97], v[156:159], v[204:207], v[94:97]
	v_mfma_f32_16x16x32_bf16 v[90:93], v[164:167], v[204:207], v[90:93]
	v_mfma_f32_16x16x32_bf16 v[78:81], v[156:159], v[212:215], v[78:81]
	v_mfma_f32_16x16x32_bf16 v[74:77], v[164:167], v[212:215], v[74:77]
	v_mfma_f32_16x16x32_bf16 v[118:121], v[168:171], v[184:187], v[118:121]
	v_mfma_f32_16x16x32_bf16 v[114:117], v[176:179], v[184:187], v[114:117]
	v_mfma_f32_16x16x32_bf16 v[102:105], v[168:171], v[192:195], v[102:105]
	v_mfma_f32_16x16x32_bf16 v[98:101], v[176:179], v[192:195], v[98:101]
	v_mfma_f32_16x16x32_bf16 v[86:89], v[168:171], v[200:203], v[86:89]
	v_mfma_f32_16x16x32_bf16 v[82:85], v[176:179], v[200:203], v[82:85]
	v_mfma_f32_16x16x32_bf16 v[70:73], v[168:171], v[208:211], v[70:73]
	v_mfma_f32_16x16x32_bf16 v[66:69], v[176:179], v[208:211], v[66:69]
	v_mfma_f32_16x16x32_bf16 v[118:121], v[172:175], v[188:191], v[118:121]
	v_mfma_f32_16x16x32_bf16 v[114:117], v[180:183], v[188:191], v[114:117]
	v_mfma_f32_16x16x32_bf16 v[102:105], v[172:175], v[196:199], v[102:105]
	v_mfma_f32_16x16x32_bf16 v[98:101], v[180:183], v[196:199], v[98:101]
	v_mfma_f32_16x16x32_bf16 v[86:89], v[172:175], v[204:207], v[86:89]
	v_mfma_f32_16x16x32_bf16 v[82:85], v[180:183], v[204:207], v[82:85]
	v_mfma_f32_16x16x32_bf16 v[70:73], v[172:175], v[212:215], v[70:73]
	v_mfma_f32_16x16x32_bf16 v[66:69], v[180:183], v[212:215], v[66:69]
	s_barrier
	ds_read_b128 v[184:187], v150 offset:49152
	ds_read_b128 v[188:191], v150 offset:50176
	ds_read_b128 v[192:195], v150 offset:51200
	ds_read_b128 v[196:199], v150 offset:52224
	ds_read_b128 v[200:203], v150 offset:53248
	ds_read_b128 v[204:207], v150 offset:54272
	ds_read_b128 v[208:211], v150 offset:55296
	ds_read_b128 v[212:215], v150 offset:56320
	s_add_u32 s48, s46, 0x8000
	s_addc_u32 s49, s47, 0
	s_add_i32 s81, s60, s51
	s_mov_b32 m0, s81
	s_nop 0
	global_load_lds_dwordx4 v130, s[48:49]
	s_add_i32 m0, s81, 0x2000
	s_add_u32 s46, s46, 0xc000
	v_lshl_add_u64 v[216:217], s[48:49], 0, v[132:133]
	s_addc_u32 s47, s47, 0
	s_add_i32 s48, s61, s51
	global_load_lds_dwordx4 v[216:217], off
	s_mov_b32 m0, s48
	s_nop 0
	global_load_lds_dwordx4 v130, s[46:47]
	s_add_i32 m0, s48, 0x2000
	s_nop 0
	global_load_lds_dwordx4 v132, s[46:47]
	s_mov_b32 m0, s56
	s_nop 0
	global_load_lds_dwordx4 v130, s[42:43]
	s_mov_b32 m0, s57
	s_nop 0
	global_load_lds_dwordx4 v132, s[42:43]
	s_waitcnt vmcnt(8) lgkmcnt(0)
	s_barrier
	v_mfma_f32_16x16x32_bf16 v[62:65], v[152:155], v[184:187], v[62:65]
	v_mfma_f32_16x16x32_bf16 v[58:61], v[160:163], v[184:187], v[58:61]
	v_mfma_f32_16x16x32_bf16 v[46:49], v[152:155], v[192:195], v[46:49]
	v_mfma_f32_16x16x32_bf16 v[42:45], v[160:163], v[192:195], v[42:45]
	v_mfma_f32_16x16x32_bf16 v[30:33], v[152:155], v[200:203], v[30:33]
	v_mfma_f32_16x16x32_bf16 v[26:29], v[160:163], v[200:203], v[26:29]
	v_mfma_f32_16x16x32_bf16 v[14:17], v[152:155], v[208:211], v[14:17]
	v_mfma_f32_16x16x32_bf16 v[10:13], v[160:163], v[208:211], v[10:13]
	v_mfma_f32_16x16x32_bf16 v[62:65], v[156:159], v[188:191], v[62:65]
	v_mfma_f32_16x16x32_bf16 v[58:61], v[164:167], v[188:191], v[58:61]
	v_mfma_f32_16x16x32_bf16 v[46:49], v[156:159], v[196:199], v[46:49]
	v_mfma_f32_16x16x32_bf16 v[42:45], v[164:167], v[196:199], v[42:45]
	v_mfma_f32_16x16x32_bf16 v[30:33], v[156:159], v[204:207], v[30:33]
	v_mfma_f32_16x16x32_bf16 v[26:29], v[164:167], v[204:207], v[26:29]
	v_mfma_f32_16x16x32_bf16 v[14:17], v[156:159], v[212:215], v[14:17]
	v_mfma_f32_16x16x32_bf16 v[10:13], v[164:167], v[212:215], v[10:13]
	v_mfma_f32_16x16x32_bf16 v[54:57], v[168:171], v[184:187], v[54:57]
	v_mfma_f32_16x16x32_bf16 v[50:53], v[176:179], v[184:187], v[50:53]
	v_mfma_f32_16x16x32_bf16 v[38:41], v[168:171], v[192:195], v[38:41]
	v_mfma_f32_16x16x32_bf16 v[34:37], v[176:179], v[192:195], v[34:37]
	v_mfma_f32_16x16x32_bf16 v[22:25], v[168:171], v[200:203], v[22:25]
	v_mfma_f32_16x16x32_bf16 v[18:21], v[176:179], v[200:203], v[18:21]
	v_mfma_f32_16x16x32_bf16 v[6:9], v[168:171], v[208:211], v[6:9]
	v_mfma_f32_16x16x32_bf16 v[2:5], v[176:179], v[208:211], v[2:5]
	v_mfma_f32_16x16x32_bf16 v[54:57], v[172:175], v[188:191], v[54:57]
	v_mfma_f32_16x16x32_bf16 v[50:53], v[180:183], v[188:191], v[50:53]
	v_mfma_f32_16x16x32_bf16 v[38:41], v[172:175], v[196:199], v[38:41]
	v_mfma_f32_16x16x32_bf16 v[34:37], v[180:183], v[196:199], v[34:37]
	v_mfma_f32_16x16x32_bf16 v[22:25], v[172:175], v[204:207], v[22:25]
	v_mfma_f32_16x16x32_bf16 v[18:21], v[180:183], v[204:207], v[18:21]
	v_mfma_f32_16x16x32_bf16 v[6:9], v[172:175], v[212:215], v[6:9]
	v_mfma_f32_16x16x32_bf16 v[2:5], v[180:183], v[212:215], v[2:5]
	s_barrier
	s_add_u32 s40, s40, 0x10000
	s_addc_u32 s41, s41, 0
	s_cmp_ge_u32 s79, s59
	s_cbranch_scc0 .LBB0_540
	s_and_b64 vcc, exec, s[12:13]
	s_cbranch_vccz .LBB0_543
	s_barrier

; #define PG8_STAGE(bufoff, gbase, voff) do { _Pragma("unroll") for (int _i = 0; _i < 2; ++_i) \
;         __builtin_amdgcn_global_load_lds((const unsigned*)((const char*)(gbase) + (voff)[_i]), (LAS unsigned*)(lds + (bufoff) + ldsw + _i * 8192), 16, 0, 0); } while (0)
; #define PG8_LDA(dst, b, h) do { _Pragma("unroll") for (int m = 0; m < 4; ++m) _Pragma("unroll") for (int k = 0; k < 2; ++k) dst[m][k] = *(const LAS bf16x8*)(lds + PG8_SA(b, h) + aoff + m * 2048 + k * 1024); } while (0)
; #define PG8_LDB(dst, b, h) do { _Pragma("unroll") for (int n = 0; n < 2; ++n) _Pragma("unroll") for (int k = 0; k < 2; ++k) dst[n][k] = *(const LAS bf16x8*)(lds + PG8_SB(b, h) + boff + n * 2048 + k * 1024); } while (0)
; #define PG8_WAIT_V(n) asm volatile("s_waitcnt vmcnt(" #n ")" ::: "memory")
; #define PG8_WAIT_L(n) asm volatile("s_waitcnt lgkmcnt(" #n ")" ::: "memory")
; template <class Epi, class Sched, bool ABLK = false, bool ALIGN_EPI = true, bool SP2 = true, bool BBLK = true>
; __device__ __forceinline__ void gemm_phase(LAS unsigned char* lds, const Gemm g, const Sched& S, const Epi& E) {
;     ...
;         const bool has_next = S.next(ui + 1, nxt);
;         const int nt = cur.nt;
;         const char* nuA = has_next ? a_unit(nxt) : uA; const int ntbA = has_next ? nxt.k0 / BK : tbA; const char* nB = has_next ? (const char*)g.Bt + (size_t)nxt.pn * tstepB + b_k0(nxt.k0) : cB;
;         for (int t = 0; t < nt; t += 2) {
;             const bool last = (t == nt - 2);
;             const char* a1 = a_tile(uA, tbA + t + 1);
;             const char* a2 = last ? a_tile(nuA, ntbA) : a_tile(uA, tbA + t + 2); const char* b2 = last ? nB : cB + (size_t)(t + 2) * kstepB;
;             const char* a3 = last ? a_tile(nuA, ntbA + 1) : a_tile(uA, tbA + t + 3); const char* b3 = b2 + kstepB;
;             if (last && has_next) S.a_ready(nxt);
;             if constexpr (SP2) {
;             PG8_LDB(B0, 0, 0); PG8_LDB(B1, 0, 1); PG8_SCHED; PG8_LDA(At, 0, 0); PG8_STAGE(PG8_SA(1, 1), a1 + hstepA, voffA);
;             PG8_WAIT_V(8); PG8_WAIT_L(0); PG8_BAR; PG8_MMA(0, 0, At, B0); PG8_MMA(0, 1, At, B1); PG8_BAR; PG8_SCHED;
;             PG8_LDA(At, 0, 1); PG8_STAGE(PG8_SB(0, 0), b2, voffB); PG8_STAGE(PG8_SB(0, 1), b2 + hstepB, voffB); PG8_STAGE(PG8_SA(0, 0), a2, voffA);
;             PG8_WAIT_V(8); PG8_WAIT_L(0); PG8_BAR; PG8_MMA(1, 0, At, B0); PG8_MMA(1, 1, At, B1); PG8_BAR; PG8_SCHED;
.LBB0_667:
	ds_read_b128 v[184:187], v153
	ds_read_b128 v[188:191], v153 offset:1024
	ds_read_b128 v[192:195], v153 offset:2048
	ds_read_b128 v[196:199], v153 offset:3072
	ds_read_b128 v[200:203], v157
	ds_read_b128 v[204:207], v157 offset:1024
	ds_read_b128 v[208:211], v157 offset:2048
	ds_read_b128 v[212:215], v157 offset:3072
	ds_read_b128 v[216:219], v149
	ds_read_b128 v[220:223], v149 offset:1024
	ds_read_b128 v[224:227], v149 offset:2048
	ds_read_b128 v[228:231], v149 offset:3072
	ds_read_b128 v[232:235], v149 offset:4096
	ds_read_b128 v[236:239], v149 offset:5120
	ds_read_b128 v[240:243], v149 offset:6144
	ds_read_b128 v[244:247], v149 offset:7168
	s_ashr_i32 s15, s14, 31
	s_lshl_b64 s[4:5], s[14:15], 20
	s_add_u32 s18, s59, s4
	s_addc_u32 s19, s62, s5
	s_and_b64 s[4:5], s[20:21], exec
	s_cselect_b32 s2, s19, s27
	s_cselect_b32 s4, s18, s26
	s_ashr_i32 s17, s16, 31
	s_lshl_b64 s[22:23], s[16:17], 20
	s_add_u32 s22, s39, s22
	s_addc_u32 s23, s40, s23
	s_and_b64 s[30:31], s[20:21], exec
	s_cselect_b32 s5, s23, s29
	s_cselect_b32 s9, s22, s28
	s_add_u32 s15, s4, 0x80
	s_addc_u32 s17, s2, 0
	s_add_u32 s52, s28, 0x10000
	v_mov_b32_e32 v2, 0
	s_addc_u32 s53, s29, 0
	v_lshl_add_u64 v[180:181], s[26:27], 0, v[176:177]
	v_lshl_add_u64 v[182:183], s[26:27], 0, v[178:179]
	s_mov_b32 s54, -2
	s_mov_b64 s[28:29], 0
	s_add_u32 s30, s26, s28
	s_addc_u32 s31, s27, s29
	s_add_u32 s36, s30, 0x100
	s_addc_u32 s37, s31, 0
	s_add_u32 s30, s30, 0x180
	s_addc_u32 s31, s31, 0
	s_cmpk_eq_i32 s28, 0xf00
	s_cselect_b32 s31, s17, s31
	s_cselect_b32 s30, s15, s30
	s_cselect_b32 s35, s5, s53
	s_cselect_b32 s34, s9, s52
	s_cselect_b32 s37, s2, s37
	s_cselect_b32 s36, s4, s36
	v_lshl_add_u64 v[248:249], v[180:181], 0, s[28:29]
	s_add_i32 m0, s25, 0xc000
	s_nop 0
	global_load_lds_dwordx4 v[248:249], off
	v_lshl_add_u64 v[248:249], v[182:183], 0, s[28:29]
	s_add_i32 m0, s25, 0xe000
	s_nop 0
	global_load_lds_dwordx4 v[248:249], off
	s_waitcnt vmcnt(8) lgkmcnt(0)
	s_barrier
	v_mfma_f32_16x16x32_bf16 v[126:129], v[184:187], v[216:219], 0
	v_mfma_f32_16x16x32_bf16 v[122:125], v[192:195], v[216:219], 0
	v_mfma_f32_16x16x32_bf16 v[110:113], v[184:187], v[224:227], 0
	v_mfma_f32_16x16x32_bf16 v[106:109], v[192:195], v[224:227], 0
	v_mfma_f32_16x16x32_bf16 v[94:97], v[184:187], v[232:235], 0
	v_mfma_f32_16x16x32_bf16 v[90:93], v[192:195], v[232:235], 0
	v_mfma_f32_16x16x32_bf16 v[78:81], v[184:187], v[240:243], 0
	v_mfma_f32_16x16x32_bf16 v[74:77], v[192:195], v[240:243], 0
	v_mfma_f32_16x16x32_bf16 v[126:129], v[188:191], v[220:223], v[126:129]
	v_mfma_f32_16x16x32_bf16 v[122:125], v[196:199], v[220:223], v[122:125]
	v_mfma_f32_16x16x32_bf16 v[110:113], v[188:191], v[228:231], v[110:113]
	v_mfma_f32_16x16x32_bf16 v[106:109], v[196:199], v[228:231], v[106:109]
	v_mfma_f32_16x16x32_bf16 v[94:97], v[188:191], v[236:239], v[94:97]
	v_mfma_f32_16x16x32_bf16 v[90:93], v[196:199], v[236:239], v[90:93]
	v_mfma_f32_16x16x32_bf16 v[78:81], v[188:191], v[244:247], v[78:81]
	v_mfma_f32_16x16x32_bf16 v[74:77], v[196:199], v[244:247], v[74:77]
	v_mfma_f32_16x16x32_bf16 v[118:121], v[200:203], v[216:219], 0
	v_mfma_f32_16x16x32_bf16 v[114:117], v[208:211], v[216:219], 0
	v_mfma_f32_16x16x32_bf16 v[102:105], v[200:203], v[224:227], 0
	v_mfma_f32_16x16x32_bf16 v[98:101], v[208:211], v[224:227], 0
	v_mfma_f32_16x16x32_bf16 v[86:89], v[200:203], v[232:235], 0
	v_mfma_f32_16x16x32_bf16 v[82:85], v[208:211], v[232:235], 0
	v_mfma_f32_16x16x32_bf16 v[70:73], v[200:203], v[240:243], 0
	v_mfma_f32_16x16x32_bf16 v[66:69], v[208:211], v[240:243], 0
	v_mfma_f32_16x16x32_bf16 v[118:121], v[204:207], v[220:223], v[118:121]
	v_mfma_f32_16x16x32_bf16 v[114:117], v[212:215], v[220:223], v[114:117]
	v_mfma_f32_16x16x32_bf16 v[102:105], v[204:207], v[228:231], v[102:105]
	v_mfma_f32_16x16x32_bf16 v[98:101], v[212:215], v[228:231], v[98:101]
	v_mfma_f32_16x16x32_bf16 v[86:89], v[204:207], v[236:239], v[86:89]
	v_mfma_f32_16x16x32_bf16 v[82:85], v[212:215], v[236:239], v[82:85]
	v_mfma_f32_16x16x32_bf16 v[70:73], v[204:207], v[244:247], v[70:73]
	v_mfma_f32_16x16x32_bf16 v[66:69], v[212:215], v[244:247], v[66:69]
	s_barrier
	ds_read_b128 v[216:219], v149 offset:16384
	ds_read_b128 v[220:223], v149 offset:17408
	ds_read_b128 v[224:227], v149 offset:18432
	ds_read_b128 v[228:231], v149 offset:19456
	ds_read_b128 v[232:235], v149 offset:20480
	ds_read_b128 v[236:239], v149 offset:21504
	ds_read_b128 v[240:243], v149 offset:22528
	ds_read_b128 v[244:247], v149 offset:23552
	s_add_i32 s55, s72, s41
	s_mov_b32 m0, s55
	s_nop 0
	global_load_lds_dwordx4 v132, s[34:35]
	s_add_i32 m0, s55, 0x2000
	s_add_u32 s56, s34, 0x4000
	s_addc_u32 s57, s35, 0
	s_add_i32 s55, s73, s41
	global_load_lds_dwordx4 v136, s[34:35]
	s_mov_b32 m0, s55
	s_nop 0
	global_load_lds_dwordx4 v132, s[56:57]
	s_add_i32 m0, s55, 0x2000
	s_nop 0
	global_load_lds_dwordx4 v136, s[56:57]
	s_mov_b32 m0, s25
	s_nop 0
	global_load_lds_dwordx4 v130, s[36:37]
	s_mov_b32 m0, s42
	s_nop 0
	global_load_lds_dwordx4 v134, s[36:37]
	s_waitcnt vmcnt(8) lgkmcnt(0)
	s_barrier
; #define PG8_STAGE(bufoff, gbase, voff) do { _Pragma("unroll") for (int _i = 0; _i < 2; ++_i) \
;         __builtin_amdgcn_global_load_lds((const unsigned*)((const char*)(gbase) + (voff)[_i]), (LAS unsigned*)(lds + (bufoff) + ldsw + _i * 8192), 16, 0, 0); } while (0)
; #define PG8_LDA(dst, b, h) do { _Pragma("unroll") for (int m = 0; m < 4; ++m) _Pragma("unroll") for (int k = 0; k < 2; ++k) dst[m][k] = *(const LAS bf16x8*)(lds + PG8_SA(b, h) + aoff + m * 2048 + k * 1024); } while (0)
; #define PG8_LDB(dst, b, h) do { _Pragma("unroll") for (int n = 0; n < 2; ++n) _Pragma("unroll") for (int k = 0; k < 2; ++k) dst[n][k] = *(const LAS bf16x8*)(lds + PG8_SB(b, h) + boff + n * 2048 + k * 1024); } while (0)
; #define PG8_MMA(ai, bj, At, Bt) do { __builtin_amdgcn_s_setprio(1); _Pragma("unroll") for (int m = 0; m < 4; ++m) _Pragma("unroll") for (int n = 0; n < 2; ++n) _Pragma("unroll") for (int k = 0; k < 2; ++k) \
;         acc[ai][bj][m][n] = __builtin_amdgcn_mfma_f32_16x16x32_bf16(Bt[n][k], At[m][k], acc[ai][bj][m][n], 0, 0, 0); __builtin_amdgcn_s_setprio(0); } while (0)
; #define PG8_WAIT_V(n) asm volatile("s_waitcnt vmcnt(" #n ")" ::: "memory")
; #define PG8_WAIT_L(n) asm volatile("s_waitcnt lgkmcnt(" #n ")" ::: "memory")
; #define PG8_BAR __builtin_amdgcn_s_barrier()
; #define PG8_SCHED __builtin_amdgcn_sched_barrier(0)
; template <class Epi, class Sched, bool ABLK = false, bool ALIGN_EPI = true, bool SP2 = true, bool BBLK = true>
; __device__ __forceinline__ void gemm_phase(LAS unsigned char* lds, const Gemm g, const Sched& S, const Epi& E) {
;     ...
;             PG8_WAIT_V(8); PG8_WAIT_L(0); PG8_BAR; PG8_MMA(1, 0, At, B0); PG8_MMA(1, 1, At, B1); PG8_BAR; PG8_SCHED;
;             PG8_LDB(B0, 1, 0); PG8_LDB(B1, 1, 1); PG8_SCHED; PG8_LDA(At, 1, 0); PG8_STAGE(PG8_SA(0, 1), a2 + hstepA, voffA);
;             PG8_WAIT_V(8); PG8_WAIT_L(0); PG8_BAR; PG8_MMA(0, 0, At, B0); PG8_MMA(0, 1, At, B1); PG8_BAR; PG8_SCHED;
	v_mfma_f32_16x16x32_bf16 v[62:65], v[184:187], v[216:219], 0
	v_mfma_f32_16x16x32_bf16 v[58:61], v[192:195], v[216:219], 0
	v_mfma_f32_16x16x32_bf16 v[46:49], v[184:187], v[224:227], 0
	v_mfma_f32_16x16x32_bf16 v[42:45], v[192:195], v[224:227], 0
	v_mfma_f32_16x16x32_bf16 v[30:33], v[184:187], v[232:235], 0
	v_mfma_f32_16x16x32_bf16 v[26:29], v[192:195], v[232:235], 0
	v_mfma_f32_16x16x32_bf16 v[14:17], v[184:187], v[240:243], 0
	v_mfma_f32_16x16x32_bf16 v[10:13], v[192:195], v[240:243], 0
	v_mfma_f32_16x16x32_bf16 v[62:65], v[188:191], v[220:223], v[62:65]
	v_mfma_f32_16x16x32_bf16 v[58:61], v[196:199], v[220:223], v[58:61]
	v_mfma_f32_16x16x32_bf16 v[46:49], v[188:191], v[228:231], v[46:49]
	v_mfma_f32_16x16x32_bf16 v[42:45], v[196:199], v[228:231], v[42:45]
	v_mfma_f32_16x16x32_bf16 v[30:33], v[188:191], v[236:239], v[30:33]
	v_mfma_f32_16x16x32_bf16 v[26:29], v[196:199], v[236:239], v[26:29]
	v_mfma_f32_16x16x32_bf16 v[14:17], v[188:191], v[244:247], v[14:17]
	v_mfma_f32_16x16x32_bf16 v[10:13], v[196:199], v[244:247], v[10:13]
	v_mfma_f32_16x16x32_bf16 v[54:57], v[200:203], v[216:219], 0
	v_mfma_f32_16x16x32_bf16 v[50:53], v[208:211], v[216:219], 0
	v_mfma_f32_16x16x32_bf16 v[38:41], v[200:203], v[224:227], 0
	v_mfma_f32_16x16x32_bf16 v[34:37], v[208:211], v[224:227], 0
	v_mfma_f32_16x16x32_bf16 v[22:25], v[200:203], v[232:235], 0
	v_mfma_f32_16x16x32_bf16 v[18:21], v[208:211], v[232:235], 0
	v_mfma_f32_16x16x32_bf16 v[6:9], v[200:203], v[240:243], 0
	v_mfma_f32_16x16x32_bf16 v[2:5], v[208:211], v[240:243], 0
	v_mfma_f32_16x16x32_bf16 v[54:57], v[204:207], v[220:223], v[54:57]
	v_mfma_f32_16x16x32_bf16 v[50:53], v[212:215], v[220:223], v[50:53]
	v_mfma_f32_16x16x32_bf16 v[38:41], v[204:207], v[228:231], v[38:41]
	v_mfma_f32_16x16x32_bf16 v[34:37], v[212:215], v[228:231], v[34:37]
	v_mfma_f32_16x16x32_bf16 v[22:25], v[204:207], v[236:239], v[22:25]
	v_mfma_f32_16x16x32_bf16 v[18:21], v[212:215], v[236:239], v[18:21]
	v_mfma_f32_16x16x32_bf16 v[6:9], v[204:207], v[244:247], v[6:9]
	v_mfma_f32_16x16x32_bf16 v[2:5], v[212:215], v[244:247], v[2:5]
	s_barrier
	v_add_u32_e32 v138, s60, v1
	ds_read_b128 v[184:187], v138
	ds_read_b128 v[188:191], v138 offset:1024
	ds_read_b128 v[192:195], v138 offset:2048
	ds_read_b128 v[196:199], v138 offset:3072
	v_add_u32_e32 v138, s61, v1
	ds_read_b128 v[200:203], v138
	ds_read_b128 v[204:207], v138 offset:1024
	ds_read_b128 v[208:211], v138 offset:2048
	ds_read_b128 v[212:215], v138 offset:3072
	ds_read_b128 v[216:219], v149 offset:32768
	ds_read_b128 v[220:223], v149 offset:33792
	ds_read_b128 v[224:227], v149 offset:34816
	ds_read_b128 v[228:231], v149 offset:35840
	ds_read_b128 v[232:235], v149 offset:36864
	ds_read_b128 v[236:239], v149 offset:37888
	ds_read_b128 v[240:243], v149 offset:38912
	ds_read_b128 v[244:247], v149 offset:39936
	s_add_u32 s36, s36, 0x80000
	s_addc_u32 s37, s37, 0
	s_mov_b32 m0, s43
	s_nop 0
	global_load_lds_dwordx4 v130, s[36:37]
	s_mov_b32 m0, s46
	s_nop 0
	global_load_lds_dwordx4 v134, s[36:37]
	s_waitcnt vmcnt(8) lgkmcnt(0)
	s_barrier
	v_mfma_f32_16x16x32_bf16 v[126:129], v[184:187], v[216:219], v[126:129]
	v_mfma_f32_16x16x32_bf16 v[122:125], v[192:195], v[216:219], v[122:125]
	v_mfma_f32_16x16x32_bf16 v[110:113], v[184:187], v[224:227], v[110:113]
	v_mfma_f32_16x16x32_bf16 v[106:109], v[192:195], v[224:227], v[106:109]
	v_mfma_f32_16x16x32_bf16 v[94:97], v[184:187], v[232:235], v[94:97]
	v_mfma_f32_16x16x32_bf16 v[90:93], v[192:195], v[232:235], v[90:93]
	v_mfma_f32_16x16x32_bf16 v[78:81], v[184:187], v[240:243], v[78:81]
	v_mfma_f32_16x16x32_bf16 v[74:77], v[192:195], v[240:243], v[74:77]
	v_mfma_f32_16x16x32_bf16 v[126:129], v[188:191], v[220:223], v[126:129]
	v_mfma_f32_16x16x32_bf16 v[122:125], v[196:199], v[220:223], v[122:125]
	v_mfma_f32_16x16x32_bf16 v[110:113], v[188:191], v[228:231], v[110:113]
	v_mfma_f32_16x16x32_bf16 v[106:109], v[196:199], v[228:231], v[106:109]
	v_mfma_f32_16x16x32_bf16 v[94:97], v[188:191], v[236:239], v[94:97]
	v_mfma_f32_16x16x32_bf16 v[90:93], v[196:199], v[236:239], v[90:93]
	v_mfma_f32_16x16x32_bf16 v[78:81], v[188:191], v[244:247], v[78:81]
	v_mfma_f32_16x16x32_bf16 v[74:77], v[196:199], v[244:247], v[74:77]
	v_mfma_f32_16x16x32_bf16 v[118:121], v[200:203], v[216:219], v[118:121]
	v_mfma_f32_16x16x32_bf16 v[114:117], v[208:211], v[216:219], v[114:117]
	v_mfma_f32_16x16x32_bf16 v[102:105], v[200:203], v[224:227], v[102:105]
	v_mfma_f32_16x16x32_bf16 v[98:101], v[208:211], v[224:227], v[98:101]
	v_mfma_f32_16x16x32_bf16 v[86:89], v[200:203], v[232:235], v[86:89]
	v_mfma_f32_16x16x32_bf16 v[82:85], v[208:211], v[232:235], v[82:85]
	v_mfma_f32_16x16x32_bf16 v[70:73], v[200:203], v[240:243], v[70:73]
	v_mfma_f32_16x16x32_bf16 v[66:69], v[208:211], v[240:243], v[66:69]
	v_mfma_f32_16x16x32_bf16 v[118:121], v[204:207], v[220:223], v[118:121]
	v_mfma_f32_16x16x32_bf16 v[114:117], v[212:215], v[220:223], v[114:117]
	v_mfma_f32_16x16x32_bf16 v[102:105], v[204:207], v[228:231], v[102:105]
	v_mfma_f32_16x16x32_bf16 v[98:101], v[212:215], v[228:231], v[98:101]
	v_mfma_f32_16x16x32_bf16 v[86:89], v[204:207], v[236:239], v[86:89]
	v_mfma_f32_16x16x32_bf16 v[82:85], v[212:215], v[236:239], v[82:85]
	v_mfma_f32_16x16x32_bf16 v[70:73], v[204:207], v[244:247], v[70:73]
	v_mfma_f32_16x16x32_bf16 v[66:69], v[212:215], v[244:247], v[66:69]
	s_barrier
; #define PG8_STAGE(bufoff, gbase, voff) do { _Pragma("unroll") for (int _i = 0; _i < 2; ++_i) \
;         __builtin_amdgcn_global_load_lds((const unsigned*)((const char*)(gbase) + (voff)[_i]), (LAS unsigned*)(lds + (bufoff) + ldsw + _i * 8192), 16, 0, 0); } while (0)
; #define PG8_LDA(dst, b, h) do { _Pragma("unroll") for (int m = 0; m < 4; ++m) _Pragma("unroll") for (int k = 0; k < 2; ++k) dst[m][k] = *(const LAS bf16x8*)(lds + PG8_SA(b, h) + aoff + m * 2048 + k * 1024); } while (0)
; #define PG8_WAIT_V(n) asm volatile("s_waitcnt vmcnt(" #n ")" ::: "memory")
; #define PG8_WAIT_L(n) asm volatile("s_waitcnt lgkmcnt(" #n ")" ::: "memory")
; template <class Epi, class Sched, bool ABLK = false, bool ALIGN_EPI = true, bool SP2 = true, bool BBLK = true>
; __device__ __forceinline__ void gemm_phase(LAS unsigned char* lds, const Gemm g, const Sched& S, const Epi& E) {
;     ...
;             const bool last = (t == nt - 2);
;             const char* a1 = a_tile(uA, tbA + t + 1);
;             const char* a2 = last ? a_tile(nuA, ntbA) : a_tile(uA, tbA + t + 2); const char* b2 = last ? nB : cB + (size_t)(t + 2) * kstepB;
;             const char* a3 = last ? a_tile(nuA, ntbA + 1) : a_tile(uA, tbA + t + 3); const char* b3 = b2 + kstepB;
;             if (last && has_next) S.a_ready(nxt);
;             if constexpr (SP2) {
;             PG8_LDB(B0, 0, 0); PG8_LDB(B1, 0, 1); PG8_SCHED; PG8_LDA(At, 0, 0); PG8_STAGE(PG8_SA(1, 1), a1 + hstepA, voffA);
;             PG8_WAIT_V(8); PG8_WAIT_L(0); PG8_BAR; PG8_MMA(0, 0, At, B0); PG8_MMA(0, 1, At, B1); PG8_BAR; PG8_SCHED;
;             PG8_LDA(At, 0, 1); PG8_STAGE(PG8_SB(0, 0), b2, voffB); PG8_STAGE(PG8_SB(0, 1), b2 + hstepB, voffB); PG8_STAGE(PG8_SA(0, 0), a2, voffA);
;             PG8_WAIT_V(8); PG8_WAIT_L(0); PG8_BAR; PG8_MMA(1, 0, At, B0); PG8_MMA(1, 1, At, B1); PG8_BAR; PG8_SCHED;
;             PG8_LDB(B0, 1, 0); PG8_LDB(B1, 1, 1); PG8_SCHED; PG8_LDA(At, 1, 0); PG8_STAGE(PG8_SA(0, 1), a2 + hstepA, voffA);
;             PG8_WAIT_V(8); PG8_WAIT_L(0); PG8_BAR; PG8_MMA(0, 0, At, B0); PG8_MMA(0, 1, At, B1); PG8_BAR; PG8_SCHED;
;             PG8_LDA(At, 1, 1); PG8_STAGE(PG8_SB(1, 0), b3, voffB); PG8_STAGE(PG8_SB(1, 1), b3 + hstepB, voffB); PG8_STAGE(PG8_SA(1, 0), a3, voffA);
;             PG8_WAIT_V(8); PG8_WAIT_L(0); PG8_BAR; PG8_MMA(1, 0, At, B0); PG8_MMA(1, 1, At, B1); PG8_BAR; PG8_SCHED;
	ds_read_b128 v[216:219], v149 offset:49152
	ds_read_b128 v[220:223], v149 offset:50176
	ds_read_b128 v[224:227], v149 offset:51200
	ds_read_b128 v[228:231], v149 offset:52224
	ds_read_b128 v[232:235], v149 offset:53248
	ds_read_b128 v[236:239], v149 offset:54272
	ds_read_b128 v[240:243], v149 offset:55296
	ds_read_b128 v[244:247], v149 offset:56320
	s_add_u32 s36, s34, 0x8000
	s_addc_u32 s37, s35, 0
	s_add_i32 s55, s60, s41
	s_mov_b32 m0, s55
	s_nop 0
	global_load_lds_dwordx4 v132, s[36:37]
	s_add_i32 m0, s55, 0x2000
	s_add_u32 s34, s34, 0xc000
	v_lshl_add_u64 v[248:249], s[36:37], 0, v[136:137]
	s_addc_u32 s35, s35, 0
	s_add_i32 s36, s61, s41
	global_load_lds_dwordx4 v[248:249], off
	s_mov_b32 m0, s36
	s_nop 0
	global_load_lds_dwordx4 v132, s[34:35]
	s_add_i32 m0, s36, 0x2000
	s_nop 0
	global_load_lds_dwordx4 v136, s[34:35]
	s_mov_b32 m0, s47
	s_nop 0
	global_load_lds_dwordx4 v130, s[30:31]
	s_mov_b32 m0, s48
	s_nop 0
	global_load_lds_dwordx4 v134, s[30:31]
	s_waitcnt vmcnt(8) lgkmcnt(0)
	s_barrier
	v_mfma_f32_16x16x32_bf16 v[62:65], v[184:187], v[216:219], v[62:65]
	v_mfma_f32_16x16x32_bf16 v[58:61], v[192:195], v[216:219], v[58:61]
	v_mfma_f32_16x16x32_bf16 v[46:49], v[184:187], v[224:227], v[46:49]
	v_mfma_f32_16x16x32_bf16 v[42:45], v[192:195], v[224:227], v[42:45]
	v_mfma_f32_16x16x32_bf16 v[30:33], v[184:187], v[232:235], v[30:33]
	v_mfma_f32_16x16x32_bf16 v[26:29], v[192:195], v[232:235], v[26:29]
	v_mfma_f32_16x16x32_bf16 v[14:17], v[184:187], v[240:243], v[14:17]
	v_mfma_f32_16x16x32_bf16 v[10:13], v[192:195], v[240:243], v[10:13]
	v_mfma_f32_16x16x32_bf16 v[62:65], v[188:191], v[220:223], v[62:65]
	v_mfma_f32_16x16x32_bf16 v[58:61], v[196:199], v[220:223], v[58:61]
	v_mfma_f32_16x16x32_bf16 v[46:49], v[188:191], v[228:231], v[46:49]
	v_mfma_f32_16x16x32_bf16 v[42:45], v[196:199], v[228:231], v[42:45]
	v_mfma_f32_16x16x32_bf16 v[30:33], v[188:191], v[236:239], v[30:33]
	v_mfma_f32_16x16x32_bf16 v[26:29], v[196:199], v[236:239], v[26:29]
	v_mfma_f32_16x16x32_bf16 v[14:17], v[188:191], v[244:247], v[14:17]
	v_mfma_f32_16x16x32_bf16 v[10:13], v[196:199], v[244:247], v[10:13]
	v_mfma_f32_16x16x32_bf16 v[54:57], v[200:203], v[216:219], v[54:57]
	v_mfma_f32_16x16x32_bf16 v[50:53], v[208:211], v[216:219], v[50:53]
	v_mfma_f32_16x16x32_bf16 v[38:41], v[200:203], v[224:227], v[38:41]
	v_mfma_f32_16x16x32_bf16 v[34:37], v[208:211], v[224:227], v[34:37]
	v_mfma_f32_16x16x32_bf16 v[22:25], v[200:203], v[232:235], v[22:25]
	v_mfma_f32_16x16x32_bf16 v[18:21], v[208:211], v[232:235], v[18:21]
	v_mfma_f32_16x16x32_bf16 v[6:9], v[200:203], v[240:243], v[6:9]
	v_mfma_f32_16x16x32_bf16 v[2:5], v[208:211], v[240:243], v[2:5]
	v_mfma_f32_16x16x32_bf16 v[54:57], v[204:207], v[220:223], v[54:57]
	v_mfma_f32_16x16x32_bf16 v[50:53], v[212:215], v[220:223], v[50:53]
	v_mfma_f32_16x16x32_bf16 v[38:41], v[204:207], v[228:231], v[38:41]
	v_mfma_f32_16x16x32_bf16 v[34:37], v[212:215], v[228:231], v[34:37]
	v_mfma_f32_16x16x32_bf16 v[22:25], v[204:207], v[236:239], v[22:25]
	v_mfma_f32_16x16x32_bf16 v[18:21], v[212:215], v[236:239], v[18:21]
	v_mfma_f32_16x16x32_bf16 v[6:9], v[204:207], v[244:247], v[6:9]
	v_mfma_f32_16x16x32_bf16 v[2:5], v[212:215], v[244:247], v[2:5]
	s_barrier
	s_add_i32 s54, s54, 2
	s_add_u32 s28, s28, 0x100
	s_addc_u32 s29, s29, 0
	s_add_u32 s52, s52, 0x10000
	s_addc_u32 s53, s53, 0
	s_cmp_gt_u32 s54, 29
.LBB0_668:
	ds_read_b128 v[184:187], v153
	ds_read_b128 v[188:191], v153 offset:1024
	ds_read_b128 v[192:195], v153 offset:2048
	ds_read_b128 v[196:199], v153 offset:3072
	ds_read_b128 v[200:203], v157
	ds_read_b128 v[204:207], v157 offset:1024
	ds_read_b128 v[208:211], v157 offset:2048
	ds_read_b128 v[212:215], v157 offset:3072
	ds_read_b128 v[216:219], v149
	ds_read_b128 v[220:223], v149 offset:1024
	ds_read_b128 v[224:227], v149 offset:2048
	ds_read_b128 v[228:231], v149 offset:3072
	ds_read_b128 v[232:235], v149 offset:4096
	ds_read_b128 v[236:239], v149 offset:5120
	ds_read_b128 v[240:243], v149 offset:6144
	ds_read_b128 v[244:247], v149 offset:7168
	s_add_u32 s30, s26, s28
	s_addc_u32 s31, s27, s29
	s_add_u32 s36, s30, 0x100
	s_addc_u32 s37, s31, 0
	s_add_u32 s30, s30, 0x180
	s_addc_u32 s31, s31, 0
	s_cmpk_eq_i32 s28, 0xf00
	s_cselect_b32 s31, s17, s31
	s_cselect_b32 s30, s15, s30
	s_cselect_b32 s35, s5, s53
	s_cselect_b32 s34, s9, s52
	s_cselect_b32 s37, s2, s37
	s_cselect_b32 s36, s4, s36
	v_lshl_add_u64 v[248:249], v[180:181], 0, s[28:29]
	s_add_i32 m0, s25, 0xc000
	s_nop 0
	global_load_lds_dwordx4 v[248:249], off
	v_lshl_add_u64 v[248:249], v[182:183], 0, s[28:29]
	s_add_i32 m0, s25, 0xe000
	s_nop 0
	global_load_lds_dwordx4 v[248:249], off
	s_waitcnt vmcnt(8) lgkmcnt(0)
	s_barrier
; #define PG8_STAGE(bufoff, gbase, voff) do { _Pragma("unroll") for (int _i = 0; _i < 2; ++_i) \
;         __builtin_amdgcn_global_load_lds((const unsigned*)((const char*)(gbase) + (voff)[_i]), (LAS unsigned*)(lds + (bufoff) + ldsw + _i * 8192), 16, 0, 0); } while (0)
; #define PG8_LDA(dst, b, h) do { _Pragma("unroll") for (int m = 0; m < 4; ++m) _Pragma("unroll") for (int k = 0; k < 2; ++k) dst[m][k] = *(const LAS bf16x8*)(lds + PG8_SA(b, h) + aoff + m * 2048 + k * 1024); } while (0)
; #define PG8_LDB(dst, b, h) do { _Pragma("unroll") for (int n = 0; n < 2; ++n) _Pragma("unroll") for (int k = 0; k < 2; ++k) dst[n][k] = *(const LAS bf16x8*)(lds + PG8_SB(b, h) + boff + n * 2048 + k * 1024); } while (0)
; #define PG8_MMA(ai, bj, At, Bt) do { __builtin_amdgcn_s_setprio(1); _Pragma("unroll") for (int m = 0; m < 4; ++m) _Pragma("unroll") for (int n = 0; n < 2; ++n) _Pragma("unroll") for (int k = 0; k < 2; ++k) \
;         acc[ai][bj][m][n] = __builtin_amdgcn_mfma_f32_16x16x32_bf16(Bt[n][k], At[m][k], acc[ai][bj][m][n], 0, 0, 0); __builtin_amdgcn_s_setprio(0); } while (0)
; #define PG8_WAIT_V(n) asm volatile("s_waitcnt vmcnt(" #n ")" ::: "memory")
; #define PG8_WAIT_L(n) asm volatile("s_waitcnt lgkmcnt(" #n ")" ::: "memory")
; #define PG8_BAR __builtin_amdgcn_s_barrier()
; #define PG8_SCHED __builtin_amdgcn_sched_barrier(0)
; template <class Epi, class Sched, bool ABLK = false, bool ALIGN_EPI = true, bool SP2 = true, bool BBLK = true>
; __device__ __forceinline__ void gemm_phase(LAS unsigned char* lds, const Gemm g, const Sched& S, const Epi& E) {
;     ...
;             PG8_LDB(B0, 0, 0); PG8_LDB(B1, 0, 1); PG8_SCHED; PG8_LDA(At, 0, 0); PG8_STAGE(PG8_SA(1, 1), a1 + hstepA, voffA);
;             PG8_WAIT_V(8); PG8_WAIT_L(0); PG8_BAR; PG8_MMA(0, 0, At, B0); PG8_MMA(0, 1, At, B1); PG8_BAR; PG8_SCHED;
;             PG8_LDA(At, 0, 1); PG8_STAGE(PG8_SB(0, 0), b2, voffB); PG8_STAGE(PG8_SB(0, 1), b2 + hstepB, voffB); PG8_STAGE(PG8_SA(0, 0), a2, voffA);
;             PG8_WAIT_V(8); PG8_WAIT_L(0); PG8_BAR; PG8_MMA(1, 0, At, B0); PG8_MMA(1, 1, At, B1); PG8_BAR; PG8_SCHED;
	v_mfma_f32_16x16x32_bf16 v[126:129], v[184:187], v[216:219], v[126:129]
	v_mfma_f32_16x16x32_bf16 v[122:125], v[192:195], v[216:219], v[122:125]
	v_mfma_f32_16x16x32_bf16 v[110:113], v[184:187], v[224:227], v[110:113]
	v_mfma_f32_16x16x32_bf16 v[106:109], v[192:195], v[224:227], v[106:109]
	v_mfma_f32_16x16x32_bf16 v[94:97], v[184:187], v[232:235], v[94:97]
	v_mfma_f32_16x16x32_bf16 v[90:93], v[192:195], v[232:235], v[90:93]
	v_mfma_f32_16x16x32_bf16 v[78:81], v[184:187], v[240:243], v[78:81]
	v_mfma_f32_16x16x32_bf16 v[74:77], v[192:195], v[240:243], v[74:77]
	v_mfma_f32_16x16x32_bf16 v[126:129], v[188:191], v[220:223], v[126:129]
	v_mfma_f32_16x16x32_bf16 v[122:125], v[196:199], v[220:223], v[122:125]
	v_mfma_f32_16x16x32_bf16 v[110:113], v[188:191], v[228:231], v[110:113]
	v_mfma_f32_16x16x32_bf16 v[106:109], v[196:199], v[228:231], v[106:109]
	v_mfma_f32_16x16x32_bf16 v[94:97], v[188:191], v[236:239], v[94:97]
	v_mfma_f32_16x16x32_bf16 v[90:93], v[196:199], v[236:239], v[90:93]
	v_mfma_f32_16x16x32_bf16 v[78:81], v[188:191], v[244:247], v[78:81]
	v_mfma_f32_16x16x32_bf16 v[74:77], v[196:199], v[244:247], v[74:77]
	v_mfma_f32_16x16x32_bf16 v[118:121], v[200:203], v[216:219], v[118:121]
	v_mfma_f32_16x16x32_bf16 v[114:117], v[208:211], v[216:219], v[114:117]
	v_mfma_f32_16x16x32_bf16 v[102:105], v[200:203], v[224:227], v[102:105]
	v_mfma_f32_16x16x32_bf16 v[98:101], v[208:211], v[224:227], v[98:101]
	v_mfma_f32_16x16x32_bf16 v[86:89], v[200:203], v[232:235], v[86:89]
	v_mfma_f32_16x16x32_bf16 v[82:85], v[208:211], v[232:235], v[82:85]
	v_mfma_f32_16x16x32_bf16 v[70:73], v[200:203], v[240:243], v[70:73]
	v_mfma_f32_16x16x32_bf16 v[66:69], v[208:211], v[240:243], v[66:69]
	v_mfma_f32_16x16x32_bf16 v[118:121], v[204:207], v[220:223], v[118:121]
	v_mfma_f32_16x16x32_bf16 v[114:117], v[212:215], v[220:223], v[114:117]
	v_mfma_f32_16x16x32_bf16 v[102:105], v[204:207], v[228:231], v[102:105]
	v_mfma_f32_16x16x32_bf16 v[98:101], v[212:215], v[228:231], v[98:101]
	v_mfma_f32_16x16x32_bf16 v[86:89], v[204:207], v[236:239], v[86:89]
	v_mfma_f32_16x16x32_bf16 v[82:85], v[212:215], v[236:239], v[82:85]
	v_mfma_f32_16x16x32_bf16 v[70:73], v[204:207], v[244:247], v[70:73]
	v_mfma_f32_16x16x32_bf16 v[66:69], v[212:215], v[244:247], v[66:69]
	s_barrier
	ds_read_b128 v[216:219], v149 offset:16384
	ds_read_b128 v[220:223], v149 offset:17408
	ds_read_b128 v[224:227], v149 offset:18432
	ds_read_b128 v[228:231], v149 offset:19456
	ds_read_b128 v[232:235], v149 offset:20480
	ds_read_b128 v[236:239], v149 offset:21504
	ds_read_b128 v[240:243], v149 offset:22528
	ds_read_b128 v[244:247], v149 offset:23552
	s_add_i32 s55, s72, s41
	s_mov_b32 m0, s55
	s_nop 0
	global_load_lds_dwordx4 v132, s[34:35]
	s_add_i32 m0, s55, 0x2000
	s_add_u32 s56, s34, 0x4000
	s_addc_u32 s57, s35, 0
	s_add_i32 s55, s73, s41
	global_load_lds_dwordx4 v136, s[34:35]
	s_mov_b32 m0, s55
	s_nop 0
	global_load_lds_dwordx4 v132, s[56:57]
	s_add_i32 m0, s55, 0x2000
	s_nop 0
	global_load_lds_dwordx4 v136, s[56:57]
	s_mov_b32 m0, s25
	s_nop 0
	global_load_lds_dwordx4 v130, s[36:37]
	s_mov_b32 m0, s42
	s_nop 0
	global_load_lds_dwordx4 v134, s[36:37]
	s_waitcnt vmcnt(8) lgkmcnt(0)
	s_barrier
	v_mfma_f32_16x16x32_bf16 v[62:65], v[184:187], v[216:219], v[62:65]
	v_mfma_f32_16x16x32_bf16 v[58:61], v[192:195], v[216:219], v[58:61]
	v_mfma_f32_16x16x32_bf16 v[46:49], v[184:187], v[224:227], v[46:49]
	v_mfma_f32_16x16x32_bf16 v[42:45], v[192:195], v[224:227], v[42:45]
	v_mfma_f32_16x16x32_bf16 v[30:33], v[184:187], v[232:235], v[30:33]
	v_mfma_f32_16x16x32_bf16 v[26:29], v[192:195], v[232:235], v[26:29]
	v_mfma_f32_16x16x32_bf16 v[14:17], v[184:187], v[240:243], v[14:17]
	v_mfma_f32_16x16x32_bf16 v[10:13], v[192:195], v[240:243], v[10:13]
	v_mfma_f32_16x16x32_bf16 v[62:65], v[188:191], v[220:223], v[62:65]
	v_mfma_f32_16x16x32_bf16 v[58:61], v[196:199], v[220:223], v[58:61]
	v_mfma_f32_16x16x32_bf16 v[46:49], v[188:191], v[228:231], v[46:49]
	v_mfma_f32_16x16x32_bf16 v[42:45], v[196:199], v[228:231], v[42:45]
	v_mfma_f32_16x16x32_bf16 v[30:33], v[188:191], v[236:239], v[30:33]
	v_mfma_f32_16x16x32_bf16 v[26:29], v[196:199], v[236:239], v[26:29]
	v_mfma_f32_16x16x32_bf16 v[14:17], v[188:191], v[244:247], v[14:17]
	v_mfma_f32_16x16x32_bf16 v[10:13], v[196:199], v[244:247], v[10:13]
	v_mfma_f32_16x16x32_bf16 v[54:57], v[200:203], v[216:219], v[54:57]
	v_mfma_f32_16x16x32_bf16 v[50:53], v[208:211], v[216:219], v[50:53]
	v_mfma_f32_16x16x32_bf16 v[38:41], v[200:203], v[224:227], v[38:41]
	v_mfma_f32_16x16x32_bf16 v[34:37], v[208:211], v[224:227], v[34:37]
	v_mfma_f32_16x16x32_bf16 v[22:25], v[200:203], v[232:235], v[22:25]
	v_mfma_f32_16x16x32_bf16 v[18:21], v[208:211], v[232:235], v[18:21]
	v_mfma_f32_16x16x32_bf16 v[6:9], v[200:203], v[240:243], v[6:9]
	v_mfma_f32_16x16x32_bf16 v[2:5], v[208:211], v[240:243], v[2:5]
	v_mfma_f32_16x16x32_bf16 v[54:57], v[204:207], v[220:223], v[54:57]
	v_mfma_f32_16x16x32_bf16 v[50:53], v[212:215], v[220:223], v[50:53]
	v_mfma_f32_16x16x32_bf16 v[38:41], v[204:207], v[228:231], v[38:41]
	v_mfma_f32_16x16x32_bf16 v[34:37], v[212:215], v[228:231], v[34:37]
	v_mfma_f32_16x16x32_bf16 v[22:25], v[204:207], v[236:239], v[22:25]
	v_mfma_f32_16x16x32_bf16 v[18:21], v[212:215], v[236:239], v[18:21]
	v_mfma_f32_16x16x32_bf16 v[6:9], v[204:207], v[244:247], v[6:9]
	v_mfma_f32_16x16x32_bf16 v[2:5], v[212:215], v[244:247], v[2:5]
	s_barrier
; #define PG8_STAGE(bufoff, gbase, voff) do { _Pragma("unroll") for (int _i = 0; _i < 2; ++_i) \
;         __builtin_amdgcn_global_load_lds((const unsigned*)((const char*)(gbase) + (voff)[_i]), (LAS unsigned*)(lds + (bufoff) + ldsw + _i * 8192), 16, 0, 0); } while (0)
; #define PG8_LDA(dst, b, h) do { _Pragma("unroll") for (int m = 0; m < 4; ++m) _Pragma("unroll") for (int k = 0; k < 2; ++k) dst[m][k] = *(const LAS bf16x8*)(lds + PG8_SA(b, h) + aoff + m * 2048 + k * 1024); } while (0)
; #define PG8_LDB(dst, b, h) do { _Pragma("unroll") for (int n = 0; n < 2; ++n) _Pragma("unroll") for (int k = 0; k < 2; ++k) dst[n][k] = *(const LAS bf16x8*)(lds + PG8_SB(b, h) + boff + n * 2048 + k * 1024); } while (0)
; #define PG8_MMA(ai, bj, At, Bt) do { __builtin_amdgcn_s_setprio(1); _Pragma("unroll") for (int m = 0; m < 4; ++m) _Pragma("unroll") for (int n = 0; n < 2; ++n) _Pragma("unroll") for (int k = 0; k < 2; ++k) \
;         acc[ai][bj][m][n] = __builtin_amdgcn_mfma_f32_16x16x32_bf16(Bt[n][k], At[m][k], acc[ai][bj][m][n], 0, 0, 0); __builtin_amdgcn_s_setprio(0); } while (0)
; #define PG8_WAIT_V(n) asm volatile("s_waitcnt vmcnt(" #n ")" ::: "memory")
; #define PG8_WAIT_L(n) asm volatile("s_waitcnt lgkmcnt(" #n ")" ::: "memory")
; #define PG8_BAR __builtin_amdgcn_s_barrier()
; #define PG8_SCHED __builtin_amdgcn_sched_barrier(0)
; template <class Epi, class Sched, bool ABLK = false, bool ALIGN_EPI = true, bool SP2 = true, bool BBLK = true>
; __device__ __forceinline__ void gemm_phase(LAS unsigned char* lds, const Gemm g, const Sched& S, const Epi& E) {
;     ...
;             PG8_LDB(B0, 1, 0); PG8_LDB(B1, 1, 1); PG8_SCHED; PG8_LDA(At, 1, 0); PG8_STAGE(PG8_SA(0, 1), a2 + hstepA, voffA);
;             PG8_WAIT_V(8); PG8_WAIT_L(0); PG8_BAR; PG8_MMA(0, 0, At, B0); PG8_MMA(0, 1, At, B1); PG8_BAR; PG8_SCHED;
;             PG8_LDA(At, 1, 1); PG8_STAGE(PG8_SB(1, 0), b3, voffB); PG8_STAGE(PG8_SB(1, 1), b3 + hstepB, voffB); PG8_STAGE(PG8_SA(1, 0), a3, voffA);
;             PG8_WAIT_V(8); PG8_WAIT_L(0); PG8_BAR; PG8_MMA(1, 0, At, B0); PG8_MMA(1, 1, At, B1); PG8_BAR; PG8_SCHED;
;     ...
;         }
;         if constexpr (ALIGN_EPI) { if (wr == 0) PG8_BAR; }
	v_add_u32_e32 v138, s60, v1
	ds_read_b128 v[184:187], v138
	ds_read_b128 v[188:191], v138 offset:1024
	ds_read_b128 v[192:195], v138 offset:2048
	ds_read_b128 v[196:199], v138 offset:3072
	v_add_u32_e32 v138, s61, v1
	ds_read_b128 v[200:203], v138
	ds_read_b128 v[204:207], v138 offset:1024
	ds_read_b128 v[208:211], v138 offset:2048
	ds_read_b128 v[212:215], v138 offset:3072
	ds_read_b128 v[216:219], v149 offset:32768
	ds_read_b128 v[220:223], v149 offset:33792
	ds_read_b128 v[224:227], v149 offset:34816
	ds_read_b128 v[228:231], v149 offset:35840
	ds_read_b128 v[232:235], v149 offset:36864
	ds_read_b128 v[236:239], v149 offset:37888
	ds_read_b128 v[240:243], v149 offset:38912
	ds_read_b128 v[244:247], v149 offset:39936
	s_add_u32 s36, s36, 0x80000
	s_addc_u32 s37, s37, 0
	s_mov_b32 m0, s43
	s_nop 0
	global_load_lds_dwordx4 v130, s[36:37]
	s_mov_b32 m0, s46
	s_nop 0
	global_load_lds_dwordx4 v134, s[36:37]
	s_waitcnt vmcnt(8) lgkmcnt(0)
	s_barrier
	v_mfma_f32_16x16x32_bf16 v[126:129], v[184:187], v[216:219], v[126:129]
	v_mfma_f32_16x16x32_bf16 v[122:125], v[192:195], v[216:219], v[122:125]
	v_mfma_f32_16x16x32_bf16 v[110:113], v[184:187], v[224:227], v[110:113]
	v_mfma_f32_16x16x32_bf16 v[106:109], v[192:195], v[224:227], v[106:109]
	v_mfma_f32_16x16x32_bf16 v[94:97], v[184:187], v[232:235], v[94:97]
	v_mfma_f32_16x16x32_bf16 v[90:93], v[192:195], v[232:235], v[90:93]
	v_mfma_f32_16x16x32_bf16 v[78:81], v[184:187], v[240:243], v[78:81]
	v_mfma_f32_16x16x32_bf16 v[74:77], v[192:195], v[240:243], v[74:77]
	v_mfma_f32_16x16x32_bf16 v[126:129], v[188:191], v[220:223], v[126:129]
	v_mfma_f32_16x16x32_bf16 v[122:125], v[196:199], v[220:223], v[122:125]
	v_mfma_f32_16x16x32_bf16 v[110:113], v[188:191], v[228:231], v[110:113]
	v_mfma_f32_16x16x32_bf16 v[106:109], v[196:199], v[228:231], v[106:109]
	v_mfma_f32_16x16x32_bf16 v[94:97], v[188:191], v[236:239], v[94:97]
	v_mfma_f32_16x16x32_bf16 v[90:93], v[196:199], v[236:239], v[90:93]
	v_mfma_f32_16x16x32_bf16 v[78:81], v[188:191], v[244:247], v[78:81]
	v_mfma_f32_16x16x32_bf16 v[74:77], v[196:199], v[244:247], v[74:77]
	v_mfma_f32_16x16x32_bf16 v[118:121], v[200:203], v[216:219], v[118:121]
	v_mfma_f32_16x16x32_bf16 v[114:117], v[208:211], v[216:219], v[114:117]
	v_mfma_f32_16x16x32_bf16 v[102:105], v[200:203], v[224:227], v[102:105]
	v_mfma_f32_16x16x32_bf16 v[98:101], v[208:211], v[224:227], v[98:101]
	v_mfma_f32_16x16x32_bf16 v[86:89], v[200:203], v[232:235], v[86:89]
	v_mfma_f32_16x16x32_bf16 v[82:85], v[208:211], v[232:235], v[82:85]
	v_mfma_f32_16x16x32_bf16 v[70:73], v[200:203], v[240:243], v[70:73]
	v_mfma_f32_16x16x32_bf16 v[66:69], v[208:211], v[240:243], v[66:69]
	v_mfma_f32_16x16x32_bf16 v[118:121], v[204:207], v[220:223], v[118:121]
	v_mfma_f32_16x16x32_bf16 v[114:117], v[212:215], v[220:223], v[114:117]
	v_mfma_f32_16x16x32_bf16 v[102:105], v[204:207], v[228:231], v[102:105]
	v_mfma_f32_16x16x32_bf16 v[98:101], v[212:215], v[228:231], v[98:101]
	v_mfma_f32_16x16x32_bf16 v[86:89], v[204:207], v[236:239], v[86:89]
	v_mfma_f32_16x16x32_bf16 v[82:85], v[212:215], v[236:239], v[82:85]
	v_mfma_f32_16x16x32_bf16 v[70:73], v[204:207], v[244:247], v[70:73]
	v_mfma_f32_16x16x32_bf16 v[66:69], v[212:215], v[244:247], v[66:69]
	s_barrier
	ds_read_b128 v[216:219], v149 offset:49152
	ds_read_b128 v[220:223], v149 offset:50176
	ds_read_b128 v[224:227], v149 offset:51200
	ds_read_b128 v[228:231], v149 offset:52224
	ds_read_b128 v[232:235], v149 offset:53248
	ds_read_b128 v[236:239], v149 offset:54272
	ds_read_b128 v[240:243], v149 offset:55296
	ds_read_b128 v[244:247], v149 offset:56320
	s_add_u32 s36, s34, 0x8000
	s_addc_u32 s37, s35, 0
	s_add_i32 s55, s60, s41
	s_mov_b32 m0, s55
	s_nop 0
	global_load_lds_dwordx4 v132, s[36:37]
	s_add_i32 m0, s55, 0x2000
	s_add_u32 s34, s34, 0xc000
	v_lshl_add_u64 v[248:249], s[36:37], 0, v[136:137]
	s_addc_u32 s35, s35, 0
	s_add_i32 s36, s61, s41
	global_load_lds_dwordx4 v[248:249], off
	s_mov_b32 m0, s36
	s_nop 0
	global_load_lds_dwordx4 v132, s[34:35]
	s_add_i32 m0, s36, 0x2000
	s_nop 0
	global_load_lds_dwordx4 v136, s[34:35]
	s_mov_b32 m0, s47
	s_nop 0
	global_load_lds_dwordx4 v130, s[30:31]
	s_mov_b32 m0, s48
	s_nop 0
	global_load_lds_dwordx4 v134, s[30:31]
	s_waitcnt vmcnt(8) lgkmcnt(0)
	s_barrier
	v_mfma_f32_16x16x32_bf16 v[62:65], v[184:187], v[216:219], v[62:65]
	v_mfma_f32_16x16x32_bf16 v[58:61], v[192:195], v[216:219], v[58:61]
	v_mfma_f32_16x16x32_bf16 v[46:49], v[184:187], v[224:227], v[46:49]
	v_mfma_f32_16x16x32_bf16 v[42:45], v[192:195], v[224:227], v[42:45]
	v_mfma_f32_16x16x32_bf16 v[30:33], v[184:187], v[232:235], v[30:33]
	v_mfma_f32_16x16x32_bf16 v[26:29], v[192:195], v[232:235], v[26:29]
	v_mfma_f32_16x16x32_bf16 v[14:17], v[184:187], v[240:243], v[14:17]
	v_mfma_f32_16x16x32_bf16 v[10:13], v[192:195], v[240:243], v[10:13]
	v_mfma_f32_16x16x32_bf16 v[62:65], v[188:191], v[220:223], v[62:65]
	v_mfma_f32_16x16x32_bf16 v[58:61], v[196:199], v[220:223], v[58:61]
	v_mfma_f32_16x16x32_bf16 v[46:49], v[188:191], v[228:231], v[46:49]
	v_mfma_f32_16x16x32_bf16 v[42:45], v[196:199], v[228:231], v[42:45]
	v_mfma_f32_16x16x32_bf16 v[30:33], v[188:191], v[236:239], v[30:33]
	v_mfma_f32_16x16x32_bf16 v[26:29], v[196:199], v[236:239], v[26:29]
	v_mfma_f32_16x16x32_bf16 v[14:17], v[188:191], v[244:247], v[14:17]
	v_mfma_f32_16x16x32_bf16 v[10:13], v[196:199], v[244:247], v[10:13]
	v_mfma_f32_16x16x32_bf16 v[54:57], v[200:203], v[216:219], v[54:57]
	v_mfma_f32_16x16x32_bf16 v[50:53], v[208:211], v[216:219], v[50:53]
	v_mfma_f32_16x16x32_bf16 v[38:41], v[200:203], v[224:227], v[38:41]
	v_mfma_f32_16x16x32_bf16 v[34:37], v[208:211], v[224:227], v[34:37]
	v_mfma_f32_16x16x32_bf16 v[22:25], v[200:203], v[232:235], v[22:25]
	v_mfma_f32_16x16x32_bf16 v[18:21], v[208:211], v[232:235], v[18:21]
	v_mfma_f32_16x16x32_bf16 v[6:9], v[200:203], v[240:243], v[6:9]
	v_mfma_f32_16x16x32_bf16 v[2:5], v[208:211], v[240:243], v[2:5]
	v_mfma_f32_16x16x32_bf16 v[54:57], v[204:207], v[220:223], v[54:57]
	v_mfma_f32_16x16x32_bf16 v[50:53], v[212:215], v[220:223], v[50:53]
	v_mfma_f32_16x16x32_bf16 v[38:41], v[204:207], v[228:231], v[38:41]
	v_mfma_f32_16x16x32_bf16 v[34:37], v[212:215], v[228:231], v[34:37]
	v_mfma_f32_16x16x32_bf16 v[22:25], v[204:207], v[236:239], v[22:25]
	v_mfma_f32_16x16x32_bf16 v[18:21], v[212:215], v[236:239], v[18:21]
	v_mfma_f32_16x16x32_bf16 v[6:9], v[204:207], v[244:247], v[6:9]
	v_mfma_f32_16x16x32_bf16 v[2:5], v[212:215], v[244:247], v[2:5]
	s_barrier
	s_add_i32 s54, s54, 2
	s_add_u32 s28, s28, 0x100
	s_addc_u32 s29, s29, 0
	s_add_u32 s52, s52, 0x10000
	s_addc_u32 s53, s53, 0
	s_cmp_gt_u32 s54, 29
	s_cbranch_scc0 .LBB0_668
	s_and_b64 vcc, exec, s[12:13]
	s_cbranch_vccz .LBB0_671
	s_barrier

; #define PG8_STAGE(bufoff, gbase, voff) do { _Pragma("unroll") for (int _i = 0; _i < 2; ++_i) \
;         __builtin_amdgcn_global_load_lds((const unsigned*)((const char*)(gbase) + (voff)[_i]), (LAS unsigned*)(lds + (bufoff) + ldsw + _i * 8192), 16, 0, 0); } while (0)
; #define PG8_LDA(dst, b, h) do { _Pragma("unroll") for (int m = 0; m < 4; ++m) _Pragma("unroll") for (int k = 0; k < 2; ++k) dst[m][k] = *(const LAS bf16x8*)(lds + PG8_SA(b, h) + aoff + m * 2048 + k * 1024); } while (0)
; #define PG8_LDB(dst, b, h) do { _Pragma("unroll") for (int n = 0; n < 2; ++n) _Pragma("unroll") for (int k = 0; k < 2; ++k) dst[n][k] = *(const LAS bf16x8*)(lds + PG8_SB(b, h) + boff + n * 2048 + k * 1024); } while (0)
; #define PG8_WAIT_V(n) asm volatile("s_waitcnt vmcnt(" #n ")" ::: "memory")
; #define PG8_WAIT_L(n) asm volatile("s_waitcnt lgkmcnt(" #n ")" ::: "memory")
; template <class Epi, class Sched, bool ABLK = false, bool ALIGN_EPI = true, bool SP2 = true, bool BBLK = true>
; __device__ __forceinline__ void gemm_phase(LAS unsigned char* lds, const Gemm g, const Sched& S, const Epi& E) {
;     ...
;         const bool has_next = S.next(ui + 1, nxt);
;         const int nt = cur.nt;
;         const char* nuA = has_next ? a_unit(nxt) : uA; const int ntbA = has_next ? nxt.k0 / BK : tbA; const char* nB = has_next ? (const char*)g.Bt + (size_t)nxt.pn * tstepB + b_k0(nxt.k0) : cB;
;         for (int t = 0; t < nt; t += 2) {
;             const bool last = (t == nt - 2);
;             const char* a1 = a_tile(uA, tbA + t + 1);
;             const char* a2 = last ? a_tile(nuA, ntbA) : a_tile(uA, tbA + t + 2); const char* b2 = last ? nB : cB + (size_t)(t + 2) * kstepB;
;             const char* a3 = last ? a_tile(nuA, ntbA + 1) : a_tile(uA, tbA + t + 3); const char* b3 = b2 + kstepB;
;             if (last && has_next) S.a_ready(nxt);
;             if constexpr (SP2) {
;             PG8_LDB(B0, 0, 0); PG8_LDB(B1, 0, 1); PG8_SCHED; PG8_LDA(At, 0, 0); PG8_STAGE(PG8_SA(1, 1), a1 + hstepA, voffA);
;             PG8_WAIT_V(8); PG8_WAIT_L(0); PG8_BAR; PG8_MMA(0, 0, At, B0); PG8_MMA(0, 1, At, B1); PG8_BAR; PG8_SCHED;
;             PG8_LDA(At, 0, 1); PG8_STAGE(PG8_SB(0, 0), b2, voffB); PG8_STAGE(PG8_SB(0, 1), b2 + hstepB, voffB); PG8_STAGE(PG8_SA(0, 0), a2, voffA);
;             PG8_WAIT_V(8); PG8_WAIT_L(0); PG8_BAR; PG8_MMA(1, 0, At, B0); PG8_MMA(1, 1, At, B1); PG8_BAR; PG8_SCHED;
.LBB0_1037:
	ds_read_b128 v[156:159], v153
	ds_read_b128 v[160:163], v153 offset:1024
	ds_read_b128 v[164:167], v153 offset:2048
	ds_read_b128 v[168:171], v153 offset:3072
	ds_read_b128 v[172:175], v154
	ds_read_b128 v[176:179], v154 offset:1024
	ds_read_b128 v[180:183], v154 offset:2048
	ds_read_b128 v[184:187], v154 offset:3072
	ds_read_b128 v[188:191], v155
	ds_read_b128 v[192:195], v155 offset:1024
	ds_read_b128 v[196:199], v155 offset:2048
	ds_read_b128 v[200:203], v155 offset:3072
	ds_read_b128 v[204:207], v155 offset:4096
	ds_read_b128 v[208:211], v155 offset:5120
	ds_read_b128 v[212:215], v155 offset:6144
	ds_read_b128 v[216:219], v155 offset:7168
	s_ashr_i32 s81, s80, 31
	s_andn2_b64 vcc, exec, s[4:5]
	s_lshl_b64 s[14:15], s[80:81], 20
	s_add_u32 s14, s28, s14
	s_addc_u32 s15, s29, s15
	s_and_b64 s[16:17], s[4:5], exec
	s_cselect_b32 s25, s15, s23
	s_cselect_b32 s48, s14, s22
	s_ashr_i32 s16, s63, 31
	s_lshr_b32 s16, s16, 26
	s_add_i32 s16, s63, s16
	s_ashr_i32 s16, s16, 6
	s_and_b64 s[18:19], s[4:5], exec
	s_cselect_b32 s26, s16, s24
	s_ashr_i32 s79, s78, 31
	s_lshl_b64 s[18:19], s[78:79], 20
	s_add_u32 s27, s30, s18
	s_addc_u32 s49, s31, s19
	s_ashr_i32 s17, s16, 31
	s_lshl_b64 s[18:19], s[16:17], 15
	s_add_u32 s18, s27, s18
	s_addc_u32 s19, s49, s19
	v_cndmask_b32_e64 v2, 0, 1, s[4:5]
	s_and_b64 s[4:5], s[4:5], exec
	s_cselect_b32 s4, s19, s21
	s_cselect_b32 s5, s18, s20
	s_ashr_i32 s27, s26, 31
	s_lshl_b64 s[26:27], s[26:27], 7
	s_add_u32 s17, s48, s26
	s_addc_u32 s48, s25, s27
	s_add_u32 s49, s17, 0x80
	s_addc_u32 s50, s48, 0
	s_add_u32 s51, s20, 0x10000
	s_addc_u32 s55, s21, 0
	s_ashr_i32 s25, s24, 31
	v_cmp_ne_u32_e64 s[8:9], 1, v2
	s_lshl_b64 s[20:21], s[24:25], 7
	v_lshl_add_u64 v[2:3], s[22:23], 0, v[142:143]
	s_add_u32 s56, s22, s20
	v_lshl_add_u64 v[146:147], v[2:3], 0, s[20:21]
	v_lshl_add_u64 v[2:3], s[22:23], 0, v[144:145]
	s_addc_u32 s57, s23, s21
	v_lshl_add_u64 v[148:149], v[2:3], 0, s[20:21]
	s_lshl_b32 s20, s46, 7
	s_addk_i32 s20, 0xfc00
	v_mov_b32_e32 v2, 0
	s_add_u32 s64, s20, 0x300
	s_mov_b32 s65, 0
	s_mov_b64 s[20:21], 0
	s_add_u32 s22, s56, s20
	s_addc_u32 s23, s57, s21
	s_add_u32 s26, s22, 0x100
	s_addc_u32 s27, s23, 0
	s_add_i32 s65, s65, 2
	s_add_u32 s22, s22, 0x180
	s_addc_u32 s23, s23, 0
	s_cmp_eq_u32 s64, s20
	s_cselect_b32 s23, s50, s23
	s_cselect_b32 s22, s49, s22
	s_cselect_b32 s25, s4, s55
	s_cselect_b32 s24, s5, s51
	s_cselect_b32 s27, s48, s27
	s_cselect_b32 s26, s17, s26
	v_lshl_add_u64 v[220:221], v[146:147], 0, s[20:21]
	s_add_i32 m0, s35, 0xc000
	s_nop 0
	global_load_lds_dwordx4 v[220:221], off
	v_lshl_add_u64 v[220:221], v[148:149], 0, s[20:21]
	s_add_i32 m0, s35, 0xe000
	s_nop 0
	global_load_lds_dwordx4 v[220:221], off
	s_waitcnt vmcnt(8) lgkmcnt(0)
	s_barrier
	v_mfma_f32_16x16x32_bf16 v[126:129], v[156:159], v[188:191], 0
	v_mfma_f32_16x16x32_bf16 v[122:125], v[164:167], v[188:191], 0
	v_mfma_f32_16x16x32_bf16 v[110:113], v[156:159], v[196:199], 0
	v_mfma_f32_16x16x32_bf16 v[106:109], v[164:167], v[196:199], 0
	v_mfma_f32_16x16x32_bf16 v[94:97], v[156:159], v[204:207], 0
	v_mfma_f32_16x16x32_bf16 v[90:93], v[164:167], v[204:207], 0
	v_mfma_f32_16x16x32_bf16 v[78:81], v[156:159], v[212:215], 0
	v_mfma_f32_16x16x32_bf16 v[74:77], v[164:167], v[212:215], 0
	v_mfma_f32_16x16x32_bf16 v[126:129], v[160:163], v[192:195], v[126:129]
	v_mfma_f32_16x16x32_bf16 v[122:125], v[168:171], v[192:195], v[122:125]
	v_mfma_f32_16x16x32_bf16 v[110:113], v[160:163], v[200:203], v[110:113]
	v_mfma_f32_16x16x32_bf16 v[106:109], v[168:171], v[200:203], v[106:109]
	v_mfma_f32_16x16x32_bf16 v[94:97], v[160:163], v[208:211], v[94:97]
	v_mfma_f32_16x16x32_bf16 v[90:93], v[168:171], v[208:211], v[90:93]
	v_mfma_f32_16x16x32_bf16 v[78:81], v[160:163], v[216:219], v[78:81]
	v_mfma_f32_16x16x32_bf16 v[74:77], v[168:171], v[216:219], v[74:77]
	v_mfma_f32_16x16x32_bf16 v[118:121], v[172:175], v[188:191], 0
	v_mfma_f32_16x16x32_bf16 v[114:117], v[180:183], v[188:191], 0
	v_mfma_f32_16x16x32_bf16 v[102:105], v[172:175], v[196:199], 0
	v_mfma_f32_16x16x32_bf16 v[98:101], v[180:183], v[196:199], 0
	v_mfma_f32_16x16x32_bf16 v[86:89], v[172:175], v[204:207], 0
	v_mfma_f32_16x16x32_bf16 v[82:85], v[180:183], v[204:207], 0
	v_mfma_f32_16x16x32_bf16 v[70:73], v[172:175], v[212:215], 0
	v_mfma_f32_16x16x32_bf16 v[66:69], v[180:183], v[212:215], 0
	v_mfma_f32_16x16x32_bf16 v[118:121], v[176:179], v[192:195], v[118:121]
	v_mfma_f32_16x16x32_bf16 v[114:117], v[184:187], v[192:195], v[114:117]
	v_mfma_f32_16x16x32_bf16 v[102:105], v[176:179], v[200:203], v[102:105]
	v_mfma_f32_16x16x32_bf16 v[98:101], v[184:187], v[200:203], v[98:101]
	v_mfma_f32_16x16x32_bf16 v[86:89], v[176:179], v[208:211], v[86:89]
	v_mfma_f32_16x16x32_bf16 v[82:85], v[184:187], v[208:211], v[82:85]
	v_mfma_f32_16x16x32_bf16 v[70:73], v[176:179], v[216:219], v[70:73]
	v_mfma_f32_16x16x32_bf16 v[66:69], v[184:187], v[216:219], v[66:69]
	s_barrier
	ds_read_b128 v[188:191], v155 offset:16384
	ds_read_b128 v[192:195], v155 offset:17408
	ds_read_b128 v[196:199], v155 offset:18432
	ds_read_b128 v[200:203], v155 offset:19456
	ds_read_b128 v[204:207], v155 offset:20480
	ds_read_b128 v[208:211], v155 offset:21504
	ds_read_b128 v[212:215], v155 offset:22528
	ds_read_b128 v[216:219], v155 offset:23552
	s_add_i32 s66, s72, s34
	s_mov_b32 m0, s66
	s_nop 0
	global_load_lds_dwordx4 v132, s[24:25]
	s_add_i32 m0, s66, 0x2000
	s_add_u32 s66, s24, 0x4000
	s_addc_u32 s67, s25, 0
	s_add_i32 s75, s73, s34
	global_load_lds_dwordx4 v136, s[24:25]
	s_mov_b32 m0, s75
	s_nop 0
	global_load_lds_dwordx4 v132, s[66:67]
	s_add_i32 m0, s75, 0x2000
	s_nop 0
	global_load_lds_dwordx4 v136, s[66:67]
	s_mov_b32 m0, s35
	s_nop 0
	global_load_lds_dwordx4 v130, s[26:27]
	s_mov_b32 m0, s36
	s_nop 0
	global_load_lds_dwordx4 v134, s[26:27]
	s_waitcnt vmcnt(8) lgkmcnt(0)
	s_barrier
; #define PG8_STAGE(bufoff, gbase, voff) do { _Pragma("unroll") for (int _i = 0; _i < 2; ++_i) \
;         __builtin_amdgcn_global_load_lds((const unsigned*)((const char*)(gbase) + (voff)[_i]), (LAS unsigned*)(lds + (bufoff) + ldsw + _i * 8192), 16, 0, 0); } while (0)
; #define PG8_LDA(dst, b, h) do { _Pragma("unroll") for (int m = 0; m < 4; ++m) _Pragma("unroll") for (int k = 0; k < 2; ++k) dst[m][k] = *(const LAS bf16x8*)(lds + PG8_SA(b, h) + aoff + m * 2048 + k * 1024); } while (0)
; #define PG8_LDB(dst, b, h) do { _Pragma("unroll") for (int n = 0; n < 2; ++n) _Pragma("unroll") for (int k = 0; k < 2; ++k) dst[n][k] = *(const LAS bf16x8*)(lds + PG8_SB(b, h) + boff + n * 2048 + k * 1024); } while (0)
; #define PG8_MMA(ai, bj, At, Bt) do { __builtin_amdgcn_s_setprio(1); _Pragma("unroll") for (int m = 0; m < 4; ++m) _Pragma("unroll") for (int n = 0; n < 2; ++n) _Pragma("unroll") for (int k = 0; k < 2; ++k) \
;         acc[ai][bj][m][n] = __builtin_amdgcn_mfma_f32_16x16x32_bf16(Bt[n][k], At[m][k], acc[ai][bj][m][n], 0, 0, 0); __builtin_amdgcn_s_setprio(0); } while (0)
; #define PG8_WAIT_V(n) asm volatile("s_waitcnt vmcnt(" #n ")" ::: "memory")
; #define PG8_WAIT_L(n) asm volatile("s_waitcnt lgkmcnt(" #n ")" ::: "memory")
; #define PG8_BAR __builtin_amdgcn_s_barrier()
; #define PG8_SCHED __builtin_amdgcn_sched_barrier(0)
; template <class Epi, class Sched, bool ABLK = false, bool ALIGN_EPI = true, bool SP2 = true, bool BBLK = true>
; __device__ __forceinline__ void gemm_phase(LAS unsigned char* lds, const Gemm g, const Sched& S, const Epi& E) {
;     ...
;             PG8_WAIT_V(8); PG8_WAIT_L(0); PG8_BAR; PG8_MMA(1, 0, At, B0); PG8_MMA(1, 1, At, B1); PG8_BAR; PG8_SCHED;
;             PG8_LDB(B0, 1, 0); PG8_LDB(B1, 1, 1); PG8_SCHED; PG8_LDA(At, 1, 0); PG8_STAGE(PG8_SA(0, 1), a2 + hstepA, voffA);
;             PG8_WAIT_V(8); PG8_WAIT_L(0); PG8_BAR; PG8_MMA(0, 0, At, B0); PG8_MMA(0, 1, At, B1); PG8_BAR; PG8_SCHED;
	v_mfma_f32_16x16x32_bf16 v[62:65], v[156:159], v[188:191], 0
	v_mfma_f32_16x16x32_bf16 v[58:61], v[164:167], v[188:191], 0
	v_mfma_f32_16x16x32_bf16 v[46:49], v[156:159], v[196:199], 0
	v_mfma_f32_16x16x32_bf16 v[42:45], v[164:167], v[196:199], 0
	v_mfma_f32_16x16x32_bf16 v[30:33], v[156:159], v[204:207], 0
	v_mfma_f32_16x16x32_bf16 v[26:29], v[164:167], v[204:207], 0
	v_mfma_f32_16x16x32_bf16 v[14:17], v[156:159], v[212:215], 0
	v_mfma_f32_16x16x32_bf16 v[10:13], v[164:167], v[212:215], 0
	v_mfma_f32_16x16x32_bf16 v[62:65], v[160:163], v[192:195], v[62:65]
	v_mfma_f32_16x16x32_bf16 v[58:61], v[168:171], v[192:195], v[58:61]
	v_mfma_f32_16x16x32_bf16 v[46:49], v[160:163], v[200:203], v[46:49]
	v_mfma_f32_16x16x32_bf16 v[42:45], v[168:171], v[200:203], v[42:45]
	v_mfma_f32_16x16x32_bf16 v[30:33], v[160:163], v[208:211], v[30:33]
	v_mfma_f32_16x16x32_bf16 v[26:29], v[168:171], v[208:211], v[26:29]
	v_mfma_f32_16x16x32_bf16 v[14:17], v[160:163], v[216:219], v[14:17]
	v_mfma_f32_16x16x32_bf16 v[10:13], v[168:171], v[216:219], v[10:13]
	v_mfma_f32_16x16x32_bf16 v[54:57], v[172:175], v[188:191], 0
	v_mfma_f32_16x16x32_bf16 v[50:53], v[180:183], v[188:191], 0
	v_mfma_f32_16x16x32_bf16 v[38:41], v[172:175], v[196:199], 0
	v_mfma_f32_16x16x32_bf16 v[34:37], v[180:183], v[196:199], 0
	v_mfma_f32_16x16x32_bf16 v[22:25], v[172:175], v[204:207], 0
	v_mfma_f32_16x16x32_bf16 v[18:21], v[180:183], v[204:207], 0
	v_mfma_f32_16x16x32_bf16 v[6:9], v[172:175], v[212:215], 0
	v_mfma_f32_16x16x32_bf16 v[2:5], v[180:183], v[212:215], 0
	v_mfma_f32_16x16x32_bf16 v[54:57], v[176:179], v[192:195], v[54:57]
	v_mfma_f32_16x16x32_bf16 v[50:53], v[184:187], v[192:195], v[50:53]
	v_mfma_f32_16x16x32_bf16 v[38:41], v[176:179], v[200:203], v[38:41]
	v_mfma_f32_16x16x32_bf16 v[34:37], v[184:187], v[200:203], v[34:37]
	v_mfma_f32_16x16x32_bf16 v[22:25], v[176:179], v[208:211], v[22:25]
	v_mfma_f32_16x16x32_bf16 v[18:21], v[184:187], v[208:211], v[18:21]
	v_mfma_f32_16x16x32_bf16 v[6:9], v[176:179], v[216:219], v[6:9]
	v_mfma_f32_16x16x32_bf16 v[2:5], v[184:187], v[216:219], v[2:5]
	s_barrier
	v_add_u32_e32 v168, s60, v151
	v_add_u32_e32 v184, s61, v151
	ds_read_b128 v[156:159], v168
	ds_read_b128 v[160:163], v168 offset:1024
	ds_read_b128 v[164:167], v168 offset:2048
	ds_read_b128 v[168:171], v168 offset:3072
	ds_read_b128 v[172:175], v184
	ds_read_b128 v[176:179], v184 offset:1024
	ds_read_b128 v[180:183], v184 offset:2048
	ds_read_b128 v[184:187], v184 offset:3072
	ds_read_b128 v[188:191], v155 offset:32768
	ds_read_b128 v[192:195], v155 offset:33792
	ds_read_b128 v[196:199], v155 offset:34816
	ds_read_b128 v[200:203], v155 offset:35840
	ds_read_b128 v[204:207], v155 offset:36864
	ds_read_b128 v[208:211], v155 offset:37888
	ds_read_b128 v[212:215], v155 offset:38912
	ds_read_b128 v[216:219], v155 offset:39936
	s_add_u32 s26, s26, 0x80000
	s_addc_u32 s27, s27, 0
	s_mov_b32 m0, s37
	s_nop 0
	global_load_lds_dwordx4 v130, s[26:27]
	s_mov_b32 m0, s40
	s_nop 0
	global_load_lds_dwordx4 v134, s[26:27]
	s_waitcnt vmcnt(8) lgkmcnt(0)
	s_barrier
	v_mfma_f32_16x16x32_bf16 v[126:129], v[156:159], v[188:191], v[126:129]
	v_mfma_f32_16x16x32_bf16 v[122:125], v[164:167], v[188:191], v[122:125]
	v_mfma_f32_16x16x32_bf16 v[110:113], v[156:159], v[196:199], v[110:113]
	v_mfma_f32_16x16x32_bf16 v[106:109], v[164:167], v[196:199], v[106:109]
	v_mfma_f32_16x16x32_bf16 v[94:97], v[156:159], v[204:207], v[94:97]
	v_mfma_f32_16x16x32_bf16 v[90:93], v[164:167], v[204:207], v[90:93]
	v_mfma_f32_16x16x32_bf16 v[78:81], v[156:159], v[212:215], v[78:81]
	v_mfma_f32_16x16x32_bf16 v[74:77], v[164:167], v[212:215], v[74:77]
	v_mfma_f32_16x16x32_bf16 v[126:129], v[160:163], v[192:195], v[126:129]
	v_mfma_f32_16x16x32_bf16 v[122:125], v[168:171], v[192:195], v[122:125]
	v_mfma_f32_16x16x32_bf16 v[110:113], v[160:163], v[200:203], v[110:113]
	v_mfma_f32_16x16x32_bf16 v[106:109], v[168:171], v[200:203], v[106:109]
	v_mfma_f32_16x16x32_bf16 v[94:97], v[160:163], v[208:211], v[94:97]
	v_mfma_f32_16x16x32_bf16 v[90:93], v[168:171], v[208:211], v[90:93]
	v_mfma_f32_16x16x32_bf16 v[78:81], v[160:163], v[216:219], v[78:81]
	v_mfma_f32_16x16x32_bf16 v[74:77], v[168:171], v[216:219], v[74:77]
	v_mfma_f32_16x16x32_bf16 v[118:121], v[172:175], v[188:191], v[118:121]
	v_mfma_f32_16x16x32_bf16 v[114:117], v[180:183], v[188:191], v[114:117]
	v_mfma_f32_16x16x32_bf16 v[102:105], v[172:175], v[196:199], v[102:105]
	v_mfma_f32_16x16x32_bf16 v[98:101], v[180:183], v[196:199], v[98:101]
	v_mfma_f32_16x16x32_bf16 v[86:89], v[172:175], v[204:207], v[86:89]
	v_mfma_f32_16x16x32_bf16 v[82:85], v[180:183], v[204:207], v[82:85]
	v_mfma_f32_16x16x32_bf16 v[70:73], v[172:175], v[212:215], v[70:73]
	v_mfma_f32_16x16x32_bf16 v[66:69], v[180:183], v[212:215], v[66:69]
	v_mfma_f32_16x16x32_bf16 v[118:121], v[176:179], v[192:195], v[118:121]
	v_mfma_f32_16x16x32_bf16 v[114:117], v[184:187], v[192:195], v[114:117]
	v_mfma_f32_16x16x32_bf16 v[102:105], v[176:179], v[200:203], v[102:105]
	v_mfma_f32_16x16x32_bf16 v[98:101], v[184:187], v[200:203], v[98:101]
	v_mfma_f32_16x16x32_bf16 v[86:89], v[176:179], v[208:211], v[86:89]
	v_mfma_f32_16x16x32_bf16 v[82:85], v[184:187], v[208:211], v[82:85]
	v_mfma_f32_16x16x32_bf16 v[70:73], v[176:179], v[216:219], v[70:73]
	v_mfma_f32_16x16x32_bf16 v[66:69], v[184:187], v[216:219], v[66:69]
	s_barrier
; #define PG8_STAGE(bufoff, gbase, voff) do { _Pragma("unroll") for (int _i = 0; _i < 2; ++_i) \
;         __builtin_amdgcn_global_load_lds((const unsigned*)((const char*)(gbase) + (voff)[_i]), (LAS unsigned*)(lds + (bufoff) + ldsw + _i * 8192), 16, 0, 0); } while (0)
; #define PG8_LDA(dst, b, h) do { _Pragma("unroll") for (int m = 0; m < 4; ++m) _Pragma("unroll") for (int k = 0; k < 2; ++k) dst[m][k] = *(const LAS bf16x8*)(lds + PG8_SA(b, h) + aoff + m * 2048 + k * 1024); } while (0)
; #define PG8_WAIT_V(n) asm volatile("s_waitcnt vmcnt(" #n ")" ::: "memory")
; #define PG8_WAIT_L(n) asm volatile("s_waitcnt lgkmcnt(" #n ")" ::: "memory")
; template <class Epi, class Sched, bool ABLK = false, bool ALIGN_EPI = true, bool SP2 = true, bool BBLK = true>
; __device__ __forceinline__ void gemm_phase(LAS unsigned char* lds, const Gemm g, const Sched& S, const Epi& E) {
;     ...
;             const bool last = (t == nt - 2);
;             const char* a1 = a_tile(uA, tbA + t + 1);
;             const char* a2 = last ? a_tile(nuA, ntbA) : a_tile(uA, tbA + t + 2); const char* b2 = last ? nB : cB + (size_t)(t + 2) * kstepB;
;             const char* a3 = last ? a_tile(nuA, ntbA + 1) : a_tile(uA, tbA + t + 3); const char* b3 = b2 + kstepB;
;             if (last && has_next) S.a_ready(nxt);
;             if constexpr (SP2) {
;             PG8_LDB(B0, 0, 0); PG8_LDB(B1, 0, 1); PG8_SCHED; PG8_LDA(At, 0, 0); PG8_STAGE(PG8_SA(1, 1), a1 + hstepA, voffA);
;             PG8_WAIT_V(8); PG8_WAIT_L(0); PG8_BAR; PG8_MMA(0, 0, At, B0); PG8_MMA(0, 1, At, B1); PG8_BAR; PG8_SCHED;
;             PG8_LDA(At, 0, 1); PG8_STAGE(PG8_SB(0, 0), b2, voffB); PG8_STAGE(PG8_SB(0, 1), b2 + hstepB, voffB); PG8_STAGE(PG8_SA(0, 0), a2, voffA);
;             PG8_WAIT_V(8); PG8_WAIT_L(0); PG8_BAR; PG8_MMA(1, 0, At, B0); PG8_MMA(1, 1, At, B1); PG8_BAR; PG8_SCHED;
;             PG8_LDB(B0, 1, 0); PG8_LDB(B1, 1, 1); PG8_SCHED; PG8_LDA(At, 1, 0); PG8_STAGE(PG8_SA(0, 1), a2 + hstepA, voffA);
;             PG8_WAIT_V(8); PG8_WAIT_L(0); PG8_BAR; PG8_MMA(0, 0, At, B0); PG8_MMA(0, 1, At, B1); PG8_BAR; PG8_SCHED;
;             PG8_LDA(At, 1, 1); PG8_STAGE(PG8_SB(1, 0), b3, voffB); PG8_STAGE(PG8_SB(1, 1), b3 + hstepB, voffB); PG8_STAGE(PG8_SA(1, 0), a3, voffA);
;             PG8_WAIT_V(8); PG8_WAIT_L(0); PG8_BAR; PG8_MMA(1, 0, At, B0); PG8_MMA(1, 1, At, B1); PG8_BAR; PG8_SCHED;
	ds_read_b128 v[188:191], v155 offset:49152
	ds_read_b128 v[192:195], v155 offset:50176
	ds_read_b128 v[196:199], v155 offset:51200
	ds_read_b128 v[200:203], v155 offset:52224
	ds_read_b128 v[204:207], v155 offset:53248
	ds_read_b128 v[208:211], v155 offset:54272
	ds_read_b128 v[212:215], v155 offset:55296
	ds_read_b128 v[216:219], v155 offset:56320
	s_add_u32 s26, s24, 0x8000
	s_addc_u32 s27, s25, 0
	s_add_i32 s66, s60, s34
	s_mov_b32 m0, s66
	s_nop 0
	global_load_lds_dwordx4 v132, s[26:27]
	s_add_i32 m0, s66, 0x2000
	s_add_u32 s24, s24, 0xc000
	v_lshl_add_u64 v[220:221], s[26:27], 0, v[136:137]
	s_addc_u32 s25, s25, 0
	s_add_i32 s26, s61, s34
	global_load_lds_dwordx4 v[220:221], off
	s_mov_b32 m0, s26
	s_nop 0
	global_load_lds_dwordx4 v132, s[24:25]
	s_add_i32 m0, s26, 0x2000
	s_nop 0
	global_load_lds_dwordx4 v136, s[24:25]
	s_mov_b32 m0, s41
	s_nop 0
	global_load_lds_dwordx4 v130, s[22:23]
	s_mov_b32 m0, s42
	s_nop 0
	global_load_lds_dwordx4 v134, s[22:23]
	s_waitcnt vmcnt(8) lgkmcnt(0)
	s_barrier
	v_mfma_f32_16x16x32_bf16 v[62:65], v[156:159], v[188:191], v[62:65]
	v_mfma_f32_16x16x32_bf16 v[58:61], v[164:167], v[188:191], v[58:61]
	v_mfma_f32_16x16x32_bf16 v[46:49], v[156:159], v[196:199], v[46:49]
	v_mfma_f32_16x16x32_bf16 v[42:45], v[164:167], v[196:199], v[42:45]
	v_mfma_f32_16x16x32_bf16 v[30:33], v[156:159], v[204:207], v[30:33]
	v_mfma_f32_16x16x32_bf16 v[26:29], v[164:167], v[204:207], v[26:29]
	v_mfma_f32_16x16x32_bf16 v[14:17], v[156:159], v[212:215], v[14:17]
	v_mfma_f32_16x16x32_bf16 v[10:13], v[164:167], v[212:215], v[10:13]
	v_mfma_f32_16x16x32_bf16 v[62:65], v[160:163], v[192:195], v[62:65]
	v_mfma_f32_16x16x32_bf16 v[58:61], v[168:171], v[192:195], v[58:61]
	v_mfma_f32_16x16x32_bf16 v[46:49], v[160:163], v[200:203], v[46:49]
	v_mfma_f32_16x16x32_bf16 v[42:45], v[168:171], v[200:203], v[42:45]
	v_mfma_f32_16x16x32_bf16 v[30:33], v[160:163], v[208:211], v[30:33]
	v_mfma_f32_16x16x32_bf16 v[26:29], v[168:171], v[208:211], v[26:29]
	v_mfma_f32_16x16x32_bf16 v[14:17], v[160:163], v[216:219], v[14:17]
	v_mfma_f32_16x16x32_bf16 v[10:13], v[168:171], v[216:219], v[10:13]
	v_mfma_f32_16x16x32_bf16 v[54:57], v[172:175], v[188:191], v[54:57]
	v_mfma_f32_16x16x32_bf16 v[50:53], v[180:183], v[188:191], v[50:53]
	v_mfma_f32_16x16x32_bf16 v[38:41], v[172:175], v[196:199], v[38:41]
	v_mfma_f32_16x16x32_bf16 v[34:37], v[180:183], v[196:199], v[34:37]
	v_mfma_f32_16x16x32_bf16 v[22:25], v[172:175], v[204:207], v[22:25]
	v_mfma_f32_16x16x32_bf16 v[18:21], v[180:183], v[204:207], v[18:21]
	v_mfma_f32_16x16x32_bf16 v[6:9], v[172:175], v[212:215], v[6:9]
	v_mfma_f32_16x16x32_bf16 v[2:5], v[180:183], v[212:215], v[2:5]
	v_mfma_f32_16x16x32_bf16 v[54:57], v[176:179], v[192:195], v[54:57]
	v_mfma_f32_16x16x32_bf16 v[50:53], v[184:187], v[192:195], v[50:53]
	v_mfma_f32_16x16x32_bf16 v[38:41], v[176:179], v[200:203], v[38:41]
	v_mfma_f32_16x16x32_bf16 v[34:37], v[184:187], v[200:203], v[34:37]
	v_mfma_f32_16x16x32_bf16 v[22:25], v[176:179], v[208:211], v[22:25]
	v_mfma_f32_16x16x32_bf16 v[18:21], v[184:187], v[208:211], v[18:21]
	v_mfma_f32_16x16x32_bf16 v[6:9], v[176:179], v[216:219], v[6:9]
	v_mfma_f32_16x16x32_bf16 v[2:5], v[184:187], v[216:219], v[2:5]
	s_barrier
	s_add_u32 s51, s51, 0x10000
	s_addc_u32 s55, s55, 0
	s_add_u32 s20, s20, 0x100
	s_addc_u32 s21, s21, 0
	s_cmp_ge_u32 s65, s46
.LBB0_1038:
	ds_read_b128 v[156:159], v153
	ds_read_b128 v[160:163], v153 offset:1024
	ds_read_b128 v[164:167], v153 offset:2048
	ds_read_b128 v[168:171], v153 offset:3072
	ds_read_b128 v[172:175], v154
	ds_read_b128 v[176:179], v154 offset:1024
	ds_read_b128 v[180:183], v154 offset:2048
	ds_read_b128 v[184:187], v154 offset:3072
	ds_read_b128 v[188:191], v155
	ds_read_b128 v[192:195], v155 offset:1024
	ds_read_b128 v[196:199], v155 offset:2048
	ds_read_b128 v[200:203], v155 offset:3072
	ds_read_b128 v[204:207], v155 offset:4096
	ds_read_b128 v[208:211], v155 offset:5120
	ds_read_b128 v[212:215], v155 offset:6144
	ds_read_b128 v[216:219], v155 offset:7168
	s_add_u32 s22, s56, s20
	s_addc_u32 s23, s57, s21
	s_add_u32 s26, s22, 0x100
	s_addc_u32 s27, s23, 0
	s_add_i32 s65, s65, 2
	s_add_u32 s22, s22, 0x180
	s_addc_u32 s23, s23, 0
	s_cmp_eq_u32 s64, s20
	s_cselect_b32 s23, s50, s23
	s_cselect_b32 s22, s49, s22
	s_cselect_b32 s25, s4, s55
	s_cselect_b32 s24, s5, s51
	s_cselect_b32 s27, s48, s27
	s_cselect_b32 s26, s17, s26
	v_lshl_add_u64 v[220:221], v[146:147], 0, s[20:21]
	s_add_i32 m0, s35, 0xc000
	s_nop 0
	global_load_lds_dwordx4 v[220:221], off
	v_lshl_add_u64 v[220:221], v[148:149], 0, s[20:21]
	s_add_i32 m0, s35, 0xe000
	s_nop 0
	global_load_lds_dwordx4 v[220:221], off
	s_waitcnt vmcnt(8) lgkmcnt(0)
	s_barrier
; #define PG8_STAGE(bufoff, gbase, voff) do { _Pragma("unroll") for (int _i = 0; _i < 2; ++_i) \
;         __builtin_amdgcn_global_load_lds((const unsigned*)((const char*)(gbase) + (voff)[_i]), (LAS unsigned*)(lds + (bufoff) + ldsw + _i * 8192), 16, 0, 0); } while (0)
; #define PG8_LDA(dst, b, h) do { _Pragma("unroll") for (int m = 0; m < 4; ++m) _Pragma("unroll") for (int k = 0; k < 2; ++k) dst[m][k] = *(const LAS bf16x8*)(lds + PG8_SA(b, h) + aoff + m * 2048 + k * 1024); } while (0)
; #define PG8_LDB(dst, b, h) do { _Pragma("unroll") for (int n = 0; n < 2; ++n) _Pragma("unroll") for (int k = 0; k < 2; ++k) dst[n][k] = *(const LAS bf16x8*)(lds + PG8_SB(b, h) + boff + n * 2048 + k * 1024); } while (0)
; #define PG8_MMA(ai, bj, At, Bt) do { __builtin_amdgcn_s_setprio(1); _Pragma("unroll") for (int m = 0; m < 4; ++m) _Pragma("unroll") for (int n = 0; n < 2; ++n) _Pragma("unroll") for (int k = 0; k < 2; ++k) \
;         acc[ai][bj][m][n] = __builtin_amdgcn_mfma_f32_16x16x32_bf16(Bt[n][k], At[m][k], acc[ai][bj][m][n], 0, 0, 0); __builtin_amdgcn_s_setprio(0); } while (0)
; #define PG8_WAIT_V(n) asm volatile("s_waitcnt vmcnt(" #n ")" ::: "memory")
; #define PG8_WAIT_L(n) asm volatile("s_waitcnt lgkmcnt(" #n ")" ::: "memory")
; #define PG8_BAR __builtin_amdgcn_s_barrier()
; #define PG8_SCHED __builtin_amdgcn_sched_barrier(0)
; template <class Epi, class Sched, bool ABLK = false, bool ALIGN_EPI = true, bool SP2 = true, bool BBLK = true>
; __device__ __forceinline__ void gemm_phase(LAS unsigned char* lds, const Gemm g, const Sched& S, const Epi& E) {
;     ...
;             PG8_LDB(B0, 0, 0); PG8_LDB(B1, 0, 1); PG8_SCHED; PG8_LDA(At, 0, 0); PG8_STAGE(PG8_SA(1, 1), a1 + hstepA, voffA);
;             PG8_WAIT_V(8); PG8_WAIT_L(0); PG8_BAR; PG8_MMA(0, 0, At, B0); PG8_MMA(0, 1, At, B1); PG8_BAR; PG8_SCHED;
;             PG8_LDA(At, 0, 1); PG8_STAGE(PG8_SB(0, 0), b2, voffB); PG8_STAGE(PG8_SB(0, 1), b2 + hstepB, voffB); PG8_STAGE(PG8_SA(0, 0), a2, voffA);
;             PG8_WAIT_V(8); PG8_WAIT_L(0); PG8_BAR; PG8_MMA(1, 0, At, B0); PG8_MMA(1, 1, At, B1); PG8_BAR; PG8_SCHED;
	v_mfma_f32_16x16x32_bf16 v[126:129], v[156:159], v[188:191], v[126:129]
	v_mfma_f32_16x16x32_bf16 v[122:125], v[164:167], v[188:191], v[122:125]
	v_mfma_f32_16x16x32_bf16 v[110:113], v[156:159], v[196:199], v[110:113]
	v_mfma_f32_16x16x32_bf16 v[106:109], v[164:167], v[196:199], v[106:109]
	v_mfma_f32_16x16x32_bf16 v[94:97], v[156:159], v[204:207], v[94:97]
	v_mfma_f32_16x16x32_bf16 v[90:93], v[164:167], v[204:207], v[90:93]
	v_mfma_f32_16x16x32_bf16 v[78:81], v[156:159], v[212:215], v[78:81]
	v_mfma_f32_16x16x32_bf16 v[74:77], v[164:167], v[212:215], v[74:77]
	v_mfma_f32_16x16x32_bf16 v[126:129], v[160:163], v[192:195], v[126:129]
	v_mfma_f32_16x16x32_bf16 v[122:125], v[168:171], v[192:195], v[122:125]
	v_mfma_f32_16x16x32_bf16 v[110:113], v[160:163], v[200:203], v[110:113]
	v_mfma_f32_16x16x32_bf16 v[106:109], v[168:171], v[200:203], v[106:109]
	v_mfma_f32_16x16x32_bf16 v[94:97], v[160:163], v[208:211], v[94:97]
	v_mfma_f32_16x16x32_bf16 v[90:93], v[168:171], v[208:211], v[90:93]
	v_mfma_f32_16x16x32_bf16 v[78:81], v[160:163], v[216:219], v[78:81]
	v_mfma_f32_16x16x32_bf16 v[74:77], v[168:171], v[216:219], v[74:77]
	v_mfma_f32_16x16x32_bf16 v[118:121], v[172:175], v[188:191], v[118:121]
	v_mfma_f32_16x16x32_bf16 v[114:117], v[180:183], v[188:191], v[114:117]
	v_mfma_f32_16x16x32_bf16 v[102:105], v[172:175], v[196:199], v[102:105]
	v_mfma_f32_16x16x32_bf16 v[98:101], v[180:183], v[196:199], v[98:101]
	v_mfma_f32_16x16x32_bf16 v[86:89], v[172:175], v[204:207], v[86:89]
	v_mfma_f32_16x16x32_bf16 v[82:85], v[180:183], v[204:207], v[82:85]
	v_mfma_f32_16x16x32_bf16 v[70:73], v[172:175], v[212:215], v[70:73]
	v_mfma_f32_16x16x32_bf16 v[66:69], v[180:183], v[212:215], v[66:69]
	v_mfma_f32_16x16x32_bf16 v[118:121], v[176:179], v[192:195], v[118:121]
	v_mfma_f32_16x16x32_bf16 v[114:117], v[184:187], v[192:195], v[114:117]
	v_mfma_f32_16x16x32_bf16 v[102:105], v[176:179], v[200:203], v[102:105]
	v_mfma_f32_16x16x32_bf16 v[98:101], v[184:187], v[200:203], v[98:101]
	v_mfma_f32_16x16x32_bf16 v[86:89], v[176:179], v[208:211], v[86:89]
	v_mfma_f32_16x16x32_bf16 v[82:85], v[184:187], v[208:211], v[82:85]
	v_mfma_f32_16x16x32_bf16 v[70:73], v[176:179], v[216:219], v[70:73]
	v_mfma_f32_16x16x32_bf16 v[66:69], v[184:187], v[216:219], v[66:69]
	s_barrier
	ds_read_b128 v[188:191], v155 offset:16384
	ds_read_b128 v[192:195], v155 offset:17408
	ds_read_b128 v[196:199], v155 offset:18432
	ds_read_b128 v[200:203], v155 offset:19456
	ds_read_b128 v[204:207], v155 offset:20480
	ds_read_b128 v[208:211], v155 offset:21504
	ds_read_b128 v[212:215], v155 offset:22528
	ds_read_b128 v[216:219], v155 offset:23552
	s_add_i32 s66, s72, s34
	s_mov_b32 m0, s66
	s_nop 0
	global_load_lds_dwordx4 v132, s[24:25]
	s_add_i32 m0, s66, 0x2000
	s_add_u32 s66, s24, 0x4000
	s_addc_u32 s67, s25, 0
	s_add_i32 s75, s73, s34
	global_load_lds_dwordx4 v136, s[24:25]
	s_mov_b32 m0, s75
	s_nop 0
	global_load_lds_dwordx4 v132, s[66:67]
	s_add_i32 m0, s75, 0x2000
	s_nop 0
	global_load_lds_dwordx4 v136, s[66:67]
	s_mov_b32 m0, s35
	s_nop 0
	global_load_lds_dwordx4 v130, s[26:27]
	s_mov_b32 m0, s36
	s_nop 0
	global_load_lds_dwordx4 v134, s[26:27]
	s_waitcnt vmcnt(8) lgkmcnt(0)
	s_barrier
	v_mfma_f32_16x16x32_bf16 v[62:65], v[156:159], v[188:191], v[62:65]
	v_mfma_f32_16x16x32_bf16 v[58:61], v[164:167], v[188:191], v[58:61]
	v_mfma_f32_16x16x32_bf16 v[46:49], v[156:159], v[196:199], v[46:49]
	v_mfma_f32_16x16x32_bf16 v[42:45], v[164:167], v[196:199], v[42:45]
	v_mfma_f32_16x16x32_bf16 v[30:33], v[156:159], v[204:207], v[30:33]
	v_mfma_f32_16x16x32_bf16 v[26:29], v[164:167], v[204:207], v[26:29]
	v_mfma_f32_16x16x32_bf16 v[14:17], v[156:159], v[212:215], v[14:17]
	v_mfma_f32_16x16x32_bf16 v[10:13], v[164:167], v[212:215], v[10:13]
	v_mfma_f32_16x16x32_bf16 v[62:65], v[160:163], v[192:195], v[62:65]
	v_mfma_f32_16x16x32_bf16 v[58:61], v[168:171], v[192:195], v[58:61]
	v_mfma_f32_16x16x32_bf16 v[46:49], v[160:163], v[200:203], v[46:49]
	v_mfma_f32_16x16x32_bf16 v[42:45], v[168:171], v[200:203], v[42:45]
	v_mfma_f32_16x16x32_bf16 v[30:33], v[160:163], v[208:211], v[30:33]
	v_mfma_f32_16x16x32_bf16 v[26:29], v[168:171], v[208:211], v[26:29]
	v_mfma_f32_16x16x32_bf16 v[14:17], v[160:163], v[216:219], v[14:17]
	v_mfma_f32_16x16x32_bf16 v[10:13], v[168:171], v[216:219], v[10:13]
	v_mfma_f32_16x16x32_bf16 v[54:57], v[172:175], v[188:191], v[54:57]
	v_mfma_f32_16x16x32_bf16 v[50:53], v[180:183], v[188:191], v[50:53]
	v_mfma_f32_16x16x32_bf16 v[38:41], v[172:175], v[196:199], v[38:41]
	v_mfma_f32_16x16x32_bf16 v[34:37], v[180:183], v[196:199], v[34:37]
	v_mfma_f32_16x16x32_bf16 v[22:25], v[172:175], v[204:207], v[22:25]
	v_mfma_f32_16x16x32_bf16 v[18:21], v[180:183], v[204:207], v[18:21]
	v_mfma_f32_16x16x32_bf16 v[6:9], v[172:175], v[212:215], v[6:9]
	v_mfma_f32_16x16x32_bf16 v[2:5], v[180:183], v[212:215], v[2:5]
	v_mfma_f32_16x16x32_bf16 v[54:57], v[176:179], v[192:195], v[54:57]
	v_mfma_f32_16x16x32_bf16 v[50:53], v[184:187], v[192:195], v[50:53]
	v_mfma_f32_16x16x32_bf16 v[38:41], v[176:179], v[200:203], v[38:41]
	v_mfma_f32_16x16x32_bf16 v[34:37], v[184:187], v[200:203], v[34:37]
	v_mfma_f32_16x16x32_bf16 v[22:25], v[176:179], v[208:211], v[22:25]
	v_mfma_f32_16x16x32_bf16 v[18:21], v[184:187], v[208:211], v[18:21]
	v_mfma_f32_16x16x32_bf16 v[6:9], v[176:179], v[216:219], v[6:9]
	v_mfma_f32_16x16x32_bf16 v[2:5], v[184:187], v[216:219], v[2:5]
	s_barrier
; #define PG8_STAGE(bufoff, gbase, voff) do { _Pragma("unroll") for (int _i = 0; _i < 2; ++_i) \
;         __builtin_amdgcn_global_load_lds((const unsigned*)((const char*)(gbase) + (voff)[_i]), (LAS unsigned*)(lds + (bufoff) + ldsw + _i * 8192), 16, 0, 0); } while (0)
; #define PG8_LDA(dst, b, h) do { _Pragma("unroll") for (int m = 0; m < 4; ++m) _Pragma("unroll") for (int k = 0; k < 2; ++k) dst[m][k] = *(const LAS bf16x8*)(lds + PG8_SA(b, h) + aoff + m * 2048 + k * 1024); } while (0)
; #define PG8_LDB(dst, b, h) do { _Pragma("unroll") for (int n = 0; n < 2; ++n) _Pragma("unroll") for (int k = 0; k < 2; ++k) dst[n][k] = *(const LAS bf16x8*)(lds + PG8_SB(b, h) + boff + n * 2048 + k * 1024); } while (0)
; #define PG8_MMA(ai, bj, At, Bt) do { __builtin_amdgcn_s_setprio(1); _Pragma("unroll") for (int m = 0; m < 4; ++m) _Pragma("unroll") for (int n = 0; n < 2; ++n) _Pragma("unroll") for (int k = 0; k < 2; ++k) \
;         acc[ai][bj][m][n] = __builtin_amdgcn_mfma_f32_16x16x32_bf16(Bt[n][k], At[m][k], acc[ai][bj][m][n], 0, 0, 0); __builtin_amdgcn_s_setprio(0); } while (0)
; #define PG8_WAIT_V(n) asm volatile("s_waitcnt vmcnt(" #n ")" ::: "memory")
; #define PG8_WAIT_L(n) asm volatile("s_waitcnt lgkmcnt(" #n ")" ::: "memory")
; #define PG8_BAR __builtin_amdgcn_s_barrier()
; #define PG8_SCHED __builtin_amdgcn_sched_barrier(0)
; template <class Epi, class Sched, bool ABLK = false, bool ALIGN_EPI = true, bool SP2 = true, bool BBLK = true>
; __device__ __forceinline__ void gemm_phase(LAS unsigned char* lds, const Gemm g, const Sched& S, const Epi& E) {
;     ...
;             PG8_LDB(B0, 1, 0); PG8_LDB(B1, 1, 1); PG8_SCHED; PG8_LDA(At, 1, 0); PG8_STAGE(PG8_SA(0, 1), a2 + hstepA, voffA);
;             PG8_WAIT_V(8); PG8_WAIT_L(0); PG8_BAR; PG8_MMA(0, 0, At, B0); PG8_MMA(0, 1, At, B1); PG8_BAR; PG8_SCHED;
;             PG8_LDA(At, 1, 1); PG8_STAGE(PG8_SB(1, 0), b3, voffB); PG8_STAGE(PG8_SB(1, 1), b3 + hstepB, voffB); PG8_STAGE(PG8_SA(1, 0), a3, voffA);
;             PG8_WAIT_V(8); PG8_WAIT_L(0); PG8_BAR; PG8_MMA(1, 0, At, B0); PG8_MMA(1, 1, At, B1); PG8_BAR; PG8_SCHED;
;     ...
;         if constexpr (ALIGN_EPI) { if (wr == 0) PG8_BAR; }
	v_add_u32_e32 v168, s60, v151
	v_add_u32_e32 v184, s61, v151
	ds_read_b128 v[156:159], v168
	ds_read_b128 v[160:163], v168 offset:1024
	ds_read_b128 v[164:167], v168 offset:2048
	ds_read_b128 v[168:171], v168 offset:3072
	ds_read_b128 v[172:175], v184
	ds_read_b128 v[176:179], v184 offset:1024
	ds_read_b128 v[180:183], v184 offset:2048
	ds_read_b128 v[184:187], v184 offset:3072
	ds_read_b128 v[188:191], v155 offset:32768
	ds_read_b128 v[192:195], v155 offset:33792
	ds_read_b128 v[196:199], v155 offset:34816
	ds_read_b128 v[200:203], v155 offset:35840
	ds_read_b128 v[204:207], v155 offset:36864
	ds_read_b128 v[208:211], v155 offset:37888
	ds_read_b128 v[212:215], v155 offset:38912
	ds_read_b128 v[216:219], v155 offset:39936
	s_add_u32 s26, s26, 0x80000
	s_addc_u32 s27, s27, 0
	s_mov_b32 m0, s37
	s_nop 0
	global_load_lds_dwordx4 v130, s[26:27]
	s_mov_b32 m0, s40
	s_nop 0
	global_load_lds_dwordx4 v134, s[26:27]
	s_waitcnt vmcnt(8) lgkmcnt(0)
	s_barrier
	v_mfma_f32_16x16x32_bf16 v[126:129], v[156:159], v[188:191], v[126:129]
	v_mfma_f32_16x16x32_bf16 v[122:125], v[164:167], v[188:191], v[122:125]
	v_mfma_f32_16x16x32_bf16 v[110:113], v[156:159], v[196:199], v[110:113]
	v_mfma_f32_16x16x32_bf16 v[106:109], v[164:167], v[196:199], v[106:109]
	v_mfma_f32_16x16x32_bf16 v[94:97], v[156:159], v[204:207], v[94:97]
	v_mfma_f32_16x16x32_bf16 v[90:93], v[164:167], v[204:207], v[90:93]
	v_mfma_f32_16x16x32_bf16 v[78:81], v[156:159], v[212:215], v[78:81]
	v_mfma_f32_16x16x32_bf16 v[74:77], v[164:167], v[212:215], v[74:77]
	v_mfma_f32_16x16x32_bf16 v[126:129], v[160:163], v[192:195], v[126:129]
	v_mfma_f32_16x16x32_bf16 v[122:125], v[168:171], v[192:195], v[122:125]
	v_mfma_f32_16x16x32_bf16 v[110:113], v[160:163], v[200:203], v[110:113]
	v_mfma_f32_16x16x32_bf16 v[106:109], v[168:171], v[200:203], v[106:109]
	v_mfma_f32_16x16x32_bf16 v[94:97], v[160:163], v[208:211], v[94:97]
	v_mfma_f32_16x16x32_bf16 v[90:93], v[168:171], v[208:211], v[90:93]
	v_mfma_f32_16x16x32_bf16 v[78:81], v[160:163], v[216:219], v[78:81]
	v_mfma_f32_16x16x32_bf16 v[74:77], v[168:171], v[216:219], v[74:77]
	v_mfma_f32_16x16x32_bf16 v[118:121], v[172:175], v[188:191], v[118:121]
	v_mfma_f32_16x16x32_bf16 v[114:117], v[180:183], v[188:191], v[114:117]
	v_mfma_f32_16x16x32_bf16 v[102:105], v[172:175], v[196:199], v[102:105]
	v_mfma_f32_16x16x32_bf16 v[98:101], v[180:183], v[196:199], v[98:101]
	v_mfma_f32_16x16x32_bf16 v[86:89], v[172:175], v[204:207], v[86:89]
	v_mfma_f32_16x16x32_bf16 v[82:85], v[180:183], v[204:207], v[82:85]
	v_mfma_f32_16x16x32_bf16 v[70:73], v[172:175], v[212:215], v[70:73]
	v_mfma_f32_16x16x32_bf16 v[66:69], v[180:183], v[212:215], v[66:69]
	v_mfma_f32_16x16x32_bf16 v[118:121], v[176:179], v[192:195], v[118:121]
	v_mfma_f32_16x16x32_bf16 v[114:117], v[184:187], v[192:195], v[114:117]
	v_mfma_f32_16x16x32_bf16 v[102:105], v[176:179], v[200:203], v[102:105]
	v_mfma_f32_16x16x32_bf16 v[98:101], v[184:187], v[200:203], v[98:101]
	v_mfma_f32_16x16x32_bf16 v[86:89], v[176:179], v[208:211], v[86:89]
	v_mfma_f32_16x16x32_bf16 v[82:85], v[184:187], v[208:211], v[82:85]
	v_mfma_f32_16x16x32_bf16 v[70:73], v[176:179], v[216:219], v[70:73]
	v_mfma_f32_16x16x32_bf16 v[66:69], v[184:187], v[216:219], v[66:69]
	s_barrier
	ds_read_b128 v[188:191], v155 offset:49152
	ds_read_b128 v[192:195], v155 offset:50176
	ds_read_b128 v[196:199], v155 offset:51200
	ds_read_b128 v[200:203], v155 offset:52224
	ds_read_b128 v[204:207], v155 offset:53248
	ds_read_b128 v[208:211], v155 offset:54272
	ds_read_b128 v[212:215], v155 offset:55296
	ds_read_b128 v[216:219], v155 offset:56320
	s_add_u32 s26, s24, 0x8000
	s_addc_u32 s27, s25, 0
	s_add_i32 s66, s60, s34
	s_mov_b32 m0, s66
	s_nop 0
	global_load_lds_dwordx4 v132, s[26:27]
	s_add_i32 m0, s66, 0x2000
	s_add_u32 s24, s24, 0xc000
	v_lshl_add_u64 v[220:221], s[26:27], 0, v[136:137]
	s_addc_u32 s25, s25, 0
	s_add_i32 s26, s61, s34
	global_load_lds_dwordx4 v[220:221], off
	s_mov_b32 m0, s26
	s_nop 0
	global_load_lds_dwordx4 v132, s[24:25]
	s_add_i32 m0, s26, 0x2000
	s_nop 0
	global_load_lds_dwordx4 v136, s[24:25]
	s_mov_b32 m0, s41
	s_nop 0
	global_load_lds_dwordx4 v130, s[22:23]
	s_mov_b32 m0, s42
	s_nop 0
	global_load_lds_dwordx4 v134, s[22:23]
	s_waitcnt vmcnt(8) lgkmcnt(0)
	s_barrier
	v_mfma_f32_16x16x32_bf16 v[62:65], v[156:159], v[188:191], v[62:65]
	v_mfma_f32_16x16x32_bf16 v[58:61], v[164:167], v[188:191], v[58:61]
	v_mfma_f32_16x16x32_bf16 v[46:49], v[156:159], v[196:199], v[46:49]
	v_mfma_f32_16x16x32_bf16 v[42:45], v[164:167], v[196:199], v[42:45]
	v_mfma_f32_16x16x32_bf16 v[30:33], v[156:159], v[204:207], v[30:33]
	v_mfma_f32_16x16x32_bf16 v[26:29], v[164:167], v[204:207], v[26:29]
	v_mfma_f32_16x16x32_bf16 v[14:17], v[156:159], v[212:215], v[14:17]
	v_mfma_f32_16x16x32_bf16 v[10:13], v[164:167], v[212:215], v[10:13]
	v_mfma_f32_16x16x32_bf16 v[62:65], v[160:163], v[192:195], v[62:65]
	v_mfma_f32_16x16x32_bf16 v[58:61], v[168:171], v[192:195], v[58:61]
	v_mfma_f32_16x16x32_bf16 v[46:49], v[160:163], v[200:203], v[46:49]
	v_mfma_f32_16x16x32_bf16 v[42:45], v[168:171], v[200:203], v[42:45]
	v_mfma_f32_16x16x32_bf16 v[30:33], v[160:163], v[208:211], v[30:33]
	v_mfma_f32_16x16x32_bf16 v[26:29], v[168:171], v[208:211], v[26:29]
	v_mfma_f32_16x16x32_bf16 v[14:17], v[160:163], v[216:219], v[14:17]
	v_mfma_f32_16x16x32_bf16 v[10:13], v[168:171], v[216:219], v[10:13]
	v_mfma_f32_16x16x32_bf16 v[54:57], v[172:175], v[188:191], v[54:57]
	v_mfma_f32_16x16x32_bf16 v[50:53], v[180:183], v[188:191], v[50:53]
	v_mfma_f32_16x16x32_bf16 v[38:41], v[172:175], v[196:199], v[38:41]
	v_mfma_f32_16x16x32_bf16 v[34:37], v[180:183], v[196:199], v[34:37]
	v_mfma_f32_16x16x32_bf16 v[22:25], v[172:175], v[204:207], v[22:25]
	v_mfma_f32_16x16x32_bf16 v[18:21], v[180:183], v[204:207], v[18:21]
	v_mfma_f32_16x16x32_bf16 v[6:9], v[172:175], v[212:215], v[6:9]
	v_mfma_f32_16x16x32_bf16 v[2:5], v[180:183], v[212:215], v[2:5]
	v_mfma_f32_16x16x32_bf16 v[54:57], v[176:179], v[192:195], v[54:57]
	v_mfma_f32_16x16x32_bf16 v[50:53], v[184:187], v[192:195], v[50:53]
	v_mfma_f32_16x16x32_bf16 v[38:41], v[176:179], v[200:203], v[38:41]
	v_mfma_f32_16x16x32_bf16 v[34:37], v[184:187], v[200:203], v[34:37]
	v_mfma_f32_16x16x32_bf16 v[22:25], v[176:179], v[208:211], v[22:25]
	v_mfma_f32_16x16x32_bf16 v[18:21], v[184:187], v[208:211], v[18:21]
	v_mfma_f32_16x16x32_bf16 v[6:9], v[176:179], v[216:219], v[6:9]
	v_mfma_f32_16x16x32_bf16 v[2:5], v[184:187], v[216:219], v[2:5]
	s_barrier
	s_add_u32 s51, s51, 0x10000
	s_addc_u32 s55, s55, 0
	s_add_u32 s20, s20, 0x100
	s_addc_u32 s21, s21, 0
	s_cmp_ge_u32 s65, s46
	s_cbranch_scc0 .LBB0_1038
	s_and_b64 vcc, exec, s[10:11]
	s_cbranch_vccz .LBB0_1041
	s_barrier

; #define PG8_STAGE(bufoff, gbase, voff) do { _Pragma("unroll") for (int _i = 0; _i < 2; ++_i) \
;         __builtin_amdgcn_global_load_lds((const unsigned*)((const char*)(gbase) + (voff)[_i]), (LAS unsigned*)(lds + (bufoff) + ldsw + _i * 8192), 16, 0, 0); } while (0)
; #define PG8_LDA(dst, b, h) do { _Pragma("unroll") for (int m = 0; m < 4; ++m) _Pragma("unroll") for (int k = 0; k < 2; ++k) dst[m][k] = *(const LAS bf16x8*)(lds + PG8_SA(b, h) + aoff + m * 2048 + k * 1024); } while (0)
; #define PG8_LDB(dst, b, h) do { _Pragma("unroll") for (int n = 0; n < 2; ++n) _Pragma("unroll") for (int k = 0; k < 2; ++k) dst[n][k] = *(const LAS bf16x8*)(lds + PG8_SB(b, h) + boff + n * 2048 + k * 1024); } while (0)
; #define PG8_WAIT_V(n) asm volatile("s_waitcnt vmcnt(" #n ")" ::: "memory")
; #define PG8_WAIT_L(n) asm volatile("s_waitcnt lgkmcnt(" #n ")" ::: "memory")
; template <class Epi, class Sched, bool ABLK = false, bool ALIGN_EPI = true, bool SP2 = true, bool BBLK = true>
; __device__ __forceinline__ void gemm_phase(LAS unsigned char* lds, const Gemm g, const Sched& S, const Epi& E) {
;     ...
;         const bool has_next = S.next(ui + 1, nxt);
;         const int nt = cur.nt;
;         const char* nuA = has_next ? a_unit(nxt) : uA; const int ntbA = has_next ? nxt.k0 / BK : tbA; const char* nB = has_next ? (const char*)g.Bt + (size_t)nxt.pn * tstepB + b_k0(nxt.k0) : cB;
;         for (int t = 0; t < nt; t += 2) {
;             const bool last = (t == nt - 2);
;             const char* a1 = a_tile(uA, tbA + t + 1);
;             const char* a2 = last ? a_tile(nuA, ntbA) : a_tile(uA, tbA + t + 2); const char* b2 = last ? nB : cB + (size_t)(t + 2) * kstepB;
;             const char* a3 = last ? a_tile(nuA, ntbA + 1) : a_tile(uA, tbA + t + 3); const char* b3 = b2 + kstepB;
;             if (last && has_next) S.a_ready(nxt);
;             if constexpr (SP2) {
;             PG8_LDB(B0, 0, 0); PG8_LDB(B1, 0, 1); PG8_SCHED; PG8_LDA(At, 0, 0); PG8_STAGE(PG8_SA(1, 1), a1 + hstepA, voffA);
;             PG8_WAIT_V(8); PG8_WAIT_L(0); PG8_BAR; PG8_MMA(0, 0, At, B0); PG8_MMA(0, 1, At, B1); PG8_BAR; PG8_SCHED;
;             PG8_LDA(At, 0, 1); PG8_STAGE(PG8_SB(0, 0), b2, voffB); PG8_STAGE(PG8_SB(0, 1), b2 + hstepB, voffB); PG8_STAGE(PG8_SA(0, 0), a2, voffA);
;             PG8_WAIT_V(8); PG8_WAIT_L(0); PG8_BAR; PG8_MMA(1, 0, At, B0); PG8_MMA(1, 1, At, B1); PG8_BAR; PG8_SCHED;
.LBB0_1163:
	ds_read_b128 v[172:175], v169
	ds_read_b128 v[176:179], v169 offset:1024
	ds_read_b128 v[180:183], v169 offset:2048
	ds_read_b128 v[184:187], v169 offset:3072
	ds_read_b128 v[188:191], v170
	ds_read_b128 v[192:195], v170 offset:1024
	ds_read_b128 v[196:199], v170 offset:2048
	ds_read_b128 v[200:203], v170 offset:3072
	ds_read_b128 v[204:207], v171
	ds_read_b128 v[208:211], v171 offset:1024
	ds_read_b128 v[212:215], v171 offset:2048
	ds_read_b128 v[216:219], v171 offset:3072
	ds_read_b128 v[220:223], v171 offset:4096
	ds_read_b128 v[224:227], v171 offset:5120
	ds_read_b128 v[228:231], v171 offset:6144
	ds_read_b128 v[232:235], v171 offset:7168
	s_ashr_i32 s11, s10, 31
	s_lshl_b64 s[4:5], s[10:11], 20
	s_add_u32 s16, s59, s4
	s_addc_u32 s17, s62, s5
	s_and_b64 s[4:5], s[18:19], exec
	s_cselect_b32 s4, s17, s27
	s_cselect_b32 s5, s16, s26
	s_ashr_i32 s15, s14, 31
	s_lshl_b64 s[20:21], s[14:15], 20
	s_add_u32 s20, s40, s20
	s_addc_u32 s21, s41, s21
	s_and_b64 s[30:31], s[18:19], exec
	s_cselect_b32 s11, s21, s29
	s_cselect_b32 s15, s20, s28
	s_add_u32 s23, s5, 0x80
	s_addc_u32 s57, s4, 0
	s_add_u32 s64, s28, 0x10000
	v_mov_b32_e32 v2, 0
	s_addc_u32 s65, s29, 0
	v_lshl_add_u64 v[164:165], s[26:27], 0, v[160:161]
	v_lshl_add_u64 v[166:167], s[26:27], 0, v[162:163]
	s_mov_b32 s66, -2
	s_mov_b64 s[28:29], 0
	s_add_u32 s30, s26, s28
	s_addc_u32 s31, s27, s29
	s_add_u32 s36, s30, 0x100
	s_addc_u32 s37, s31, 0
	s_add_u32 s30, s30, 0x180
	s_addc_u32 s31, s31, 0
	s_cmpk_eq_i32 s28, 0xf00
	s_cselect_b32 s31, s57, s31
	s_cselect_b32 s30, s23, s30
	s_cselect_b32 s35, s11, s65
	s_cselect_b32 s34, s15, s64
	s_cselect_b32 s37, s4, s37
	s_cselect_b32 s36, s5, s36
	s_mov_b32 m0, s50
	v_lshl_add_u64 v[236:237], v[164:165], 0, s[28:29]
	global_load_lds_dwordx4 v[236:237], off
	v_lshl_add_u64 v[236:237], v[166:167], 0, s[28:29]
	s_mov_b32 m0, s51
	s_nop 0
	global_load_lds_dwordx4 v[236:237], off
	s_waitcnt vmcnt(8) lgkmcnt(0)
	s_barrier
	v_mfma_f32_16x16x32_bf16 v[126:129], v[172:175], v[204:207], 0
	v_mfma_f32_16x16x32_bf16 v[122:125], v[180:183], v[204:207], 0
	v_mfma_f32_16x16x32_bf16 v[110:113], v[172:175], v[212:215], 0
	v_mfma_f32_16x16x32_bf16 v[106:109], v[180:183], v[212:215], 0
	v_mfma_f32_16x16x32_bf16 v[94:97], v[172:175], v[220:223], 0
	v_mfma_f32_16x16x32_bf16 v[90:93], v[180:183], v[220:223], 0
	v_mfma_f32_16x16x32_bf16 v[78:81], v[172:175], v[228:231], 0
	v_mfma_f32_16x16x32_bf16 v[74:77], v[180:183], v[228:231], 0
	v_mfma_f32_16x16x32_bf16 v[126:129], v[176:179], v[208:211], v[126:129]
	v_mfma_f32_16x16x32_bf16 v[122:125], v[184:187], v[208:211], v[122:125]
	v_mfma_f32_16x16x32_bf16 v[110:113], v[176:179], v[216:219], v[110:113]
	v_mfma_f32_16x16x32_bf16 v[106:109], v[184:187], v[216:219], v[106:109]
	v_mfma_f32_16x16x32_bf16 v[94:97], v[176:179], v[224:227], v[94:97]
	v_mfma_f32_16x16x32_bf16 v[90:93], v[184:187], v[224:227], v[90:93]
	v_mfma_f32_16x16x32_bf16 v[78:81], v[176:179], v[232:235], v[78:81]
	v_mfma_f32_16x16x32_bf16 v[74:77], v[184:187], v[232:235], v[74:77]
	v_mfma_f32_16x16x32_bf16 v[118:121], v[188:191], v[204:207], 0
	v_mfma_f32_16x16x32_bf16 v[114:117], v[196:199], v[204:207], 0
	v_mfma_f32_16x16x32_bf16 v[102:105], v[188:191], v[212:215], 0
	v_mfma_f32_16x16x32_bf16 v[98:101], v[196:199], v[212:215], 0
	v_mfma_f32_16x16x32_bf16 v[86:89], v[188:191], v[220:223], 0
	v_mfma_f32_16x16x32_bf16 v[82:85], v[196:199], v[220:223], 0
	v_mfma_f32_16x16x32_bf16 v[70:73], v[188:191], v[228:231], 0
	v_mfma_f32_16x16x32_bf16 v[66:69], v[196:199], v[228:231], 0
	v_mfma_f32_16x16x32_bf16 v[118:121], v[192:195], v[208:211], v[118:121]
	v_mfma_f32_16x16x32_bf16 v[114:117], v[200:203], v[208:211], v[114:117]
	v_mfma_f32_16x16x32_bf16 v[102:105], v[192:195], v[216:219], v[102:105]
	v_mfma_f32_16x16x32_bf16 v[98:101], v[200:203], v[216:219], v[98:101]
	v_mfma_f32_16x16x32_bf16 v[86:89], v[192:195], v[224:227], v[86:89]
	v_mfma_f32_16x16x32_bf16 v[82:85], v[200:203], v[224:227], v[82:85]
	v_mfma_f32_16x16x32_bf16 v[70:73], v[192:195], v[232:235], v[70:73]
	v_mfma_f32_16x16x32_bf16 v[66:69], v[200:203], v[232:235], v[66:69]
	s_barrier
	ds_read_b128 v[204:207], v171 offset:16384
	ds_read_b128 v[208:211], v171 offset:17408
	ds_read_b128 v[212:215], v171 offset:18432
	ds_read_b128 v[216:219], v171 offset:19456
	ds_read_b128 v[220:223], v171 offset:20480
	ds_read_b128 v[224:227], v171 offset:21504
	ds_read_b128 v[228:231], v171 offset:22528
	ds_read_b128 v[232:235], v171 offset:23552
	s_mov_b32 m0, s55
	s_add_u32 s76, s34, 0x4000
	global_load_lds_dwordx4 v134, s[34:35]
	s_mov_b32 m0, s56
	s_addc_u32 s77, s35, 0
	s_add_i32 s67, s73, s42
	global_load_lds_dwordx4 v130, s[34:35]
	s_mov_b32 m0, s67
	s_nop 0
	global_load_lds_dwordx4 v134, s[76:77]
	s_add_i32 m0, s67, 0x2000
	s_nop 0
	global_load_lds_dwordx4 v130, s[76:77]
	s_mov_b32 m0, s25
	s_nop 0
	global_load_lds_dwordx4 v136, s[36:37]
	s_mov_b32 m0, s43
	s_nop 0
	global_load_lds_dwordx4 v132, s[36:37]
	s_waitcnt vmcnt(8) lgkmcnt(0)
	s_barrier
; #define PG8_STAGE(bufoff, gbase, voff) do { _Pragma("unroll") for (int _i = 0; _i < 2; ++_i) \
;         __builtin_amdgcn_global_load_lds((const unsigned*)((const char*)(gbase) + (voff)[_i]), (LAS unsigned*)(lds + (bufoff) + ldsw + _i * 8192), 16, 0, 0); } while (0)
; #define PG8_LDA(dst, b, h) do { _Pragma("unroll") for (int m = 0; m < 4; ++m) _Pragma("unroll") for (int k = 0; k < 2; ++k) dst[m][k] = *(const LAS bf16x8*)(lds + PG8_SA(b, h) + aoff + m * 2048 + k * 1024); } while (0)
; #define PG8_LDB(dst, b, h) do { _Pragma("unroll") for (int n = 0; n < 2; ++n) _Pragma("unroll") for (int k = 0; k < 2; ++k) dst[n][k] = *(const LAS bf16x8*)(lds + PG8_SB(b, h) + boff + n * 2048 + k * 1024); } while (0)
; #define PG8_MMA(ai, bj, At, Bt) do { __builtin_amdgcn_s_setprio(1); _Pragma("unroll") for (int m = 0; m < 4; ++m) _Pragma("unroll") for (int n = 0; n < 2; ++n) _Pragma("unroll") for (int k = 0; k < 2; ++k) \
;         acc[ai][bj][m][n] = __builtin_amdgcn_mfma_f32_16x16x32_bf16(Bt[n][k], At[m][k], acc[ai][bj][m][n], 0, 0, 0); __builtin_amdgcn_s_setprio(0); } while (0)
; #define PG8_WAIT_V(n) asm volatile("s_waitcnt vmcnt(" #n ")" ::: "memory")
; #define PG8_WAIT_L(n) asm volatile("s_waitcnt lgkmcnt(" #n ")" ::: "memory")
; #define PG8_BAR __builtin_amdgcn_s_barrier()
; #define PG8_SCHED __builtin_amdgcn_sched_barrier(0)
; template <class Epi, class Sched, bool ABLK = false, bool ALIGN_EPI = true, bool SP2 = true, bool BBLK = true>
; __device__ __forceinline__ void gemm_phase(LAS unsigned char* lds, const Gemm g, const Sched& S, const Epi& E) {
;     ...
;             PG8_WAIT_V(8); PG8_WAIT_L(0); PG8_BAR; PG8_MMA(1, 0, At, B0); PG8_MMA(1, 1, At, B1); PG8_BAR; PG8_SCHED;
;             PG8_LDB(B0, 1, 0); PG8_LDB(B1, 1, 1); PG8_SCHED; PG8_LDA(At, 1, 0); PG8_STAGE(PG8_SA(0, 1), a2 + hstepA, voffA);
;             PG8_WAIT_V(8); PG8_WAIT_L(0); PG8_BAR; PG8_MMA(0, 0, At, B0); PG8_MMA(0, 1, At, B1); PG8_BAR; PG8_SCHED;
	v_mfma_f32_16x16x32_bf16 v[62:65], v[172:175], v[204:207], 0
	v_mfma_f32_16x16x32_bf16 v[58:61], v[180:183], v[204:207], 0
	v_mfma_f32_16x16x32_bf16 v[46:49], v[172:175], v[212:215], 0
	v_mfma_f32_16x16x32_bf16 v[42:45], v[180:183], v[212:215], 0
	v_mfma_f32_16x16x32_bf16 v[30:33], v[172:175], v[220:223], 0
	v_mfma_f32_16x16x32_bf16 v[26:29], v[180:183], v[220:223], 0
	v_mfma_f32_16x16x32_bf16 v[14:17], v[172:175], v[228:231], 0
	v_mfma_f32_16x16x32_bf16 v[10:13], v[180:183], v[228:231], 0
	v_mfma_f32_16x16x32_bf16 v[62:65], v[176:179], v[208:211], v[62:65]
	v_mfma_f32_16x16x32_bf16 v[58:61], v[184:187], v[208:211], v[58:61]
	v_mfma_f32_16x16x32_bf16 v[46:49], v[176:179], v[216:219], v[46:49]
	v_mfma_f32_16x16x32_bf16 v[42:45], v[184:187], v[216:219], v[42:45]
	v_mfma_f32_16x16x32_bf16 v[30:33], v[176:179], v[224:227], v[30:33]
	v_mfma_f32_16x16x32_bf16 v[26:29], v[184:187], v[224:227], v[26:29]
	v_mfma_f32_16x16x32_bf16 v[14:17], v[176:179], v[232:235], v[14:17]
	v_mfma_f32_16x16x32_bf16 v[10:13], v[184:187], v[232:235], v[10:13]
	v_mfma_f32_16x16x32_bf16 v[54:57], v[188:191], v[204:207], 0
	v_mfma_f32_16x16x32_bf16 v[50:53], v[196:199], v[204:207], 0
	v_mfma_f32_16x16x32_bf16 v[38:41], v[188:191], v[212:215], 0
	v_mfma_f32_16x16x32_bf16 v[34:37], v[196:199], v[212:215], 0
	v_mfma_f32_16x16x32_bf16 v[22:25], v[188:191], v[220:223], 0
	v_mfma_f32_16x16x32_bf16 v[18:21], v[196:199], v[220:223], 0
	v_mfma_f32_16x16x32_bf16 v[6:9], v[188:191], v[228:231], 0
	v_mfma_f32_16x16x32_bf16 v[2:5], v[196:199], v[228:231], 0
	v_mfma_f32_16x16x32_bf16 v[54:57], v[192:195], v[208:211], v[54:57]
	v_mfma_f32_16x16x32_bf16 v[50:53], v[200:203], v[208:211], v[50:53]
	v_mfma_f32_16x16x32_bf16 v[38:41], v[192:195], v[216:219], v[38:41]
	v_mfma_f32_16x16x32_bf16 v[34:37], v[200:203], v[216:219], v[34:37]
	v_mfma_f32_16x16x32_bf16 v[22:25], v[192:195], v[224:227], v[22:25]
	v_mfma_f32_16x16x32_bf16 v[18:21], v[200:203], v[224:227], v[18:21]
	v_mfma_f32_16x16x32_bf16 v[6:9], v[192:195], v[232:235], v[6:9]
	v_mfma_f32_16x16x32_bf16 v[2:5], v[200:203], v[232:235], v[2:5]
	s_barrier
	v_add_u32_e32 v184, s60, v168
	v_add_u32_e32 v200, s61, v168
	ds_read_b128 v[172:175], v184
	ds_read_b128 v[176:179], v184 offset:1024
	ds_read_b128 v[180:183], v184 offset:2048
	ds_read_b128 v[184:187], v184 offset:3072
	ds_read_b128 v[188:191], v200
	ds_read_b128 v[192:195], v200 offset:1024
	ds_read_b128 v[196:199], v200 offset:2048
	ds_read_b128 v[200:203], v200 offset:3072
	ds_read_b128 v[204:207], v171 offset:32768
	ds_read_b128 v[208:211], v171 offset:33792
	ds_read_b128 v[212:215], v171 offset:34816
	ds_read_b128 v[216:219], v171 offset:35840
	ds_read_b128 v[220:223], v171 offset:36864
	ds_read_b128 v[224:227], v171 offset:37888
	ds_read_b128 v[228:231], v171 offset:38912
	ds_read_b128 v[232:235], v171 offset:39936
	s_add_u32 s36, s36, 0x80000
	s_addc_u32 s37, s37, 0
	s_mov_b32 m0, s44
	s_nop 0
	global_load_lds_dwordx4 v136, s[36:37]
	s_mov_b32 m0, s45
	s_nop 0
	global_load_lds_dwordx4 v132, s[36:37]
	s_waitcnt vmcnt(8) lgkmcnt(0)
	s_barrier
	v_mfma_f32_16x16x32_bf16 v[126:129], v[172:175], v[204:207], v[126:129]
	v_mfma_f32_16x16x32_bf16 v[122:125], v[180:183], v[204:207], v[122:125]
	v_mfma_f32_16x16x32_bf16 v[110:113], v[172:175], v[212:215], v[110:113]
	v_mfma_f32_16x16x32_bf16 v[106:109], v[180:183], v[212:215], v[106:109]
	v_mfma_f32_16x16x32_bf16 v[94:97], v[172:175], v[220:223], v[94:97]
	v_mfma_f32_16x16x32_bf16 v[90:93], v[180:183], v[220:223], v[90:93]
	v_mfma_f32_16x16x32_bf16 v[78:81], v[172:175], v[228:231], v[78:81]
	v_mfma_f32_16x16x32_bf16 v[74:77], v[180:183], v[228:231], v[74:77]
	v_mfma_f32_16x16x32_bf16 v[126:129], v[176:179], v[208:211], v[126:129]
	v_mfma_f32_16x16x32_bf16 v[122:125], v[184:187], v[208:211], v[122:125]
	v_mfma_f32_16x16x32_bf16 v[110:113], v[176:179], v[216:219], v[110:113]
	v_mfma_f32_16x16x32_bf16 v[106:109], v[184:187], v[216:219], v[106:109]
	v_mfma_f32_16x16x32_bf16 v[94:97], v[176:179], v[224:227], v[94:97]
	v_mfma_f32_16x16x32_bf16 v[90:93], v[184:187], v[224:227], v[90:93]
	v_mfma_f32_16x16x32_bf16 v[78:81], v[176:179], v[232:235], v[78:81]
	v_mfma_f32_16x16x32_bf16 v[74:77], v[184:187], v[232:235], v[74:77]
	v_mfma_f32_16x16x32_bf16 v[118:121], v[188:191], v[204:207], v[118:121]
	v_mfma_f32_16x16x32_bf16 v[114:117], v[196:199], v[204:207], v[114:117]
	v_mfma_f32_16x16x32_bf16 v[102:105], v[188:191], v[212:215], v[102:105]
	v_mfma_f32_16x16x32_bf16 v[98:101], v[196:199], v[212:215], v[98:101]
	v_mfma_f32_16x16x32_bf16 v[86:89], v[188:191], v[220:223], v[86:89]
	v_mfma_f32_16x16x32_bf16 v[82:85], v[196:199], v[220:223], v[82:85]
	v_mfma_f32_16x16x32_bf16 v[70:73], v[188:191], v[228:231], v[70:73]
	v_mfma_f32_16x16x32_bf16 v[66:69], v[196:199], v[228:231], v[66:69]
	v_mfma_f32_16x16x32_bf16 v[118:121], v[192:195], v[208:211], v[118:121]
	v_mfma_f32_16x16x32_bf16 v[114:117], v[200:203], v[208:211], v[114:117]
	v_mfma_f32_16x16x32_bf16 v[102:105], v[192:195], v[216:219], v[102:105]
	v_mfma_f32_16x16x32_bf16 v[98:101], v[200:203], v[216:219], v[98:101]
	v_mfma_f32_16x16x32_bf16 v[86:89], v[192:195], v[224:227], v[86:89]
	v_mfma_f32_16x16x32_bf16 v[82:85], v[200:203], v[224:227], v[82:85]
	v_mfma_f32_16x16x32_bf16 v[70:73], v[192:195], v[232:235], v[70:73]
	v_mfma_f32_16x16x32_bf16 v[66:69], v[200:203], v[232:235], v[66:69]
	s_barrier
; #define PG8_STAGE(bufoff, gbase, voff) do { _Pragma("unroll") for (int _i = 0; _i < 2; ++_i) \
;         __builtin_amdgcn_global_load_lds((const unsigned*)((const char*)(gbase) + (voff)[_i]), (LAS unsigned*)(lds + (bufoff) + ldsw + _i * 8192), 16, 0, 0); } while (0)
; #define PG8_LDA(dst, b, h) do { _Pragma("unroll") for (int m = 0; m < 4; ++m) _Pragma("unroll") for (int k = 0; k < 2; ++k) dst[m][k] = *(const LAS bf16x8*)(lds + PG8_SA(b, h) + aoff + m * 2048 + k * 1024); } while (0)
; #define PG8_WAIT_V(n) asm volatile("s_waitcnt vmcnt(" #n ")" ::: "memory")
; #define PG8_WAIT_L(n) asm volatile("s_waitcnt lgkmcnt(" #n ")" ::: "memory")
; template <class Epi, class Sched, bool ABLK = false, bool ALIGN_EPI = true, bool SP2 = true, bool BBLK = true>
; __device__ __forceinline__ void gemm_phase(LAS unsigned char* lds, const Gemm g, const Sched& S, const Epi& E) {
;     ...
;         for (int t = 0; t < nt; t += 2) {
;             const bool last = (t == nt - 2);
;             const char* a1 = a_tile(uA, tbA + t + 1);
;             const char* a2 = last ? a_tile(nuA, ntbA) : a_tile(uA, tbA + t + 2); const char* b2 = last ? nB : cB + (size_t)(t + 2) * kstepB;
;             const char* a3 = last ? a_tile(nuA, ntbA + 1) : a_tile(uA, tbA + t + 3); const char* b3 = b2 + kstepB;
;             if (last && has_next) S.a_ready(nxt);
;             if constexpr (SP2) {
;             PG8_LDB(B0, 0, 0); PG8_LDB(B1, 0, 1); PG8_SCHED; PG8_LDA(At, 0, 0); PG8_STAGE(PG8_SA(1, 1), a1 + hstepA, voffA);
;             PG8_WAIT_V(8); PG8_WAIT_L(0); PG8_BAR; PG8_MMA(0, 0, At, B0); PG8_MMA(0, 1, At, B1); PG8_BAR; PG8_SCHED;
;             PG8_LDA(At, 0, 1); PG8_STAGE(PG8_SB(0, 0), b2, voffB); PG8_STAGE(PG8_SB(0, 1), b2 + hstepB, voffB); PG8_STAGE(PG8_SA(0, 0), a2, voffA);
;             PG8_WAIT_V(8); PG8_WAIT_L(0); PG8_BAR; PG8_MMA(1, 0, At, B0); PG8_MMA(1, 1, At, B1); PG8_BAR; PG8_SCHED;
;             PG8_LDB(B0, 1, 0); PG8_LDB(B1, 1, 1); PG8_SCHED; PG8_LDA(At, 1, 0); PG8_STAGE(PG8_SA(0, 1), a2 + hstepA, voffA);
;             PG8_WAIT_V(8); PG8_WAIT_L(0); PG8_BAR; PG8_MMA(0, 0, At, B0); PG8_MMA(0, 1, At, B1); PG8_BAR; PG8_SCHED;
;             PG8_LDA(At, 1, 1); PG8_STAGE(PG8_SB(1, 0), b3, voffB); PG8_STAGE(PG8_SB(1, 1), b3 + hstepB, voffB); PG8_STAGE(PG8_SA(1, 0), a3, voffA);
;             PG8_WAIT_V(8); PG8_WAIT_L(0); PG8_BAR; PG8_MMA(1, 0, At, B0); PG8_MMA(1, 1, At, B1); PG8_BAR; PG8_SCHED;
	ds_read_b128 v[204:207], v171 offset:49152
	ds_read_b128 v[208:211], v171 offset:50176
	ds_read_b128 v[212:215], v171 offset:51200
	ds_read_b128 v[216:219], v171 offset:52224
	ds_read_b128 v[220:223], v171 offset:53248
	ds_read_b128 v[224:227], v171 offset:54272
	ds_read_b128 v[228:231], v171 offset:55296
	ds_read_b128 v[232:235], v171 offset:56320
	s_add_u32 s36, s34, 0x8000
	s_addc_u32 s37, s35, 0
	s_add_i32 s67, s60, s42
	s_mov_b32 m0, s67
	s_nop 0
	global_load_lds_dwordx4 v134, s[36:37]
	s_add_i32 m0, s67, 0x2000
	s_add_u32 s34, s34, 0xc000
	v_lshl_add_u64 v[236:237], s[36:37], 0, v[130:131]
	s_addc_u32 s35, s35, 0
	s_add_i32 s36, s61, s42
	global_load_lds_dwordx4 v[236:237], off
	s_mov_b32 m0, s36
	s_nop 0
	global_load_lds_dwordx4 v134, s[34:35]
	s_add_i32 m0, s36, 0x2000
	s_nop 0
	global_load_lds_dwordx4 v130, s[34:35]
	s_mov_b32 m0, s48
	s_nop 0
	global_load_lds_dwordx4 v136, s[30:31]
	s_mov_b32 m0, s49
	s_nop 0
	global_load_lds_dwordx4 v132, s[30:31]
	s_waitcnt vmcnt(8) lgkmcnt(0)
	s_barrier
	v_mfma_f32_16x16x32_bf16 v[62:65], v[172:175], v[204:207], v[62:65]
	v_mfma_f32_16x16x32_bf16 v[58:61], v[180:183], v[204:207], v[58:61]
	v_mfma_f32_16x16x32_bf16 v[46:49], v[172:175], v[212:215], v[46:49]
	v_mfma_f32_16x16x32_bf16 v[42:45], v[180:183], v[212:215], v[42:45]
	v_mfma_f32_16x16x32_bf16 v[30:33], v[172:175], v[220:223], v[30:33]
	v_mfma_f32_16x16x32_bf16 v[26:29], v[180:183], v[220:223], v[26:29]
	v_mfma_f32_16x16x32_bf16 v[14:17], v[172:175], v[228:231], v[14:17]
	v_mfma_f32_16x16x32_bf16 v[10:13], v[180:183], v[228:231], v[10:13]
	v_mfma_f32_16x16x32_bf16 v[62:65], v[176:179], v[208:211], v[62:65]
	v_mfma_f32_16x16x32_bf16 v[58:61], v[184:187], v[208:211], v[58:61]
	v_mfma_f32_16x16x32_bf16 v[46:49], v[176:179], v[216:219], v[46:49]
	v_mfma_f32_16x16x32_bf16 v[42:45], v[184:187], v[216:219], v[42:45]
	v_mfma_f32_16x16x32_bf16 v[30:33], v[176:179], v[224:227], v[30:33]
	v_mfma_f32_16x16x32_bf16 v[26:29], v[184:187], v[224:227], v[26:29]
	v_mfma_f32_16x16x32_bf16 v[14:17], v[176:179], v[232:235], v[14:17]
	v_mfma_f32_16x16x32_bf16 v[10:13], v[184:187], v[232:235], v[10:13]
	v_mfma_f32_16x16x32_bf16 v[54:57], v[188:191], v[204:207], v[54:57]
	v_mfma_f32_16x16x32_bf16 v[50:53], v[196:199], v[204:207], v[50:53]
	v_mfma_f32_16x16x32_bf16 v[38:41], v[188:191], v[212:215], v[38:41]
	v_mfma_f32_16x16x32_bf16 v[34:37], v[196:199], v[212:215], v[34:37]
	v_mfma_f32_16x16x32_bf16 v[22:25], v[188:191], v[220:223], v[22:25]
	v_mfma_f32_16x16x32_bf16 v[18:21], v[196:199], v[220:223], v[18:21]
	v_mfma_f32_16x16x32_bf16 v[6:9], v[188:191], v[228:231], v[6:9]
	v_mfma_f32_16x16x32_bf16 v[2:5], v[196:199], v[228:231], v[2:5]
	v_mfma_f32_16x16x32_bf16 v[54:57], v[192:195], v[208:211], v[54:57]
	v_mfma_f32_16x16x32_bf16 v[50:53], v[200:203], v[208:211], v[50:53]
	v_mfma_f32_16x16x32_bf16 v[38:41], v[192:195], v[216:219], v[38:41]
	v_mfma_f32_16x16x32_bf16 v[34:37], v[200:203], v[216:219], v[34:37]
	v_mfma_f32_16x16x32_bf16 v[22:25], v[192:195], v[224:227], v[22:25]
	v_mfma_f32_16x16x32_bf16 v[18:21], v[200:203], v[224:227], v[18:21]
	v_mfma_f32_16x16x32_bf16 v[6:9], v[192:195], v[232:235], v[6:9]
	v_mfma_f32_16x16x32_bf16 v[2:5], v[200:203], v[232:235], v[2:5]
	s_barrier
	s_add_i32 s66, s66, 2
	s_add_u32 s28, s28, 0x100
	s_addc_u32 s29, s29, 0
	s_add_u32 s64, s64, 0x10000
	s_addc_u32 s65, s65, 0
	s_cmp_gt_u32 s66, 29
.LBB0_1164:
	ds_read_b128 v[172:175], v169
	ds_read_b128 v[176:179], v169 offset:1024
	ds_read_b128 v[180:183], v169 offset:2048
	ds_read_b128 v[184:187], v169 offset:3072
	ds_read_b128 v[188:191], v170
	ds_read_b128 v[192:195], v170 offset:1024
	ds_read_b128 v[196:199], v170 offset:2048
	ds_read_b128 v[200:203], v170 offset:3072
	ds_read_b128 v[204:207], v171
	ds_read_b128 v[208:211], v171 offset:1024
	ds_read_b128 v[212:215], v171 offset:2048
	ds_read_b128 v[216:219], v171 offset:3072
	ds_read_b128 v[220:223], v171 offset:4096
	ds_read_b128 v[224:227], v171 offset:5120
	ds_read_b128 v[228:231], v171 offset:6144
	ds_read_b128 v[232:235], v171 offset:7168
	s_add_u32 s30, s26, s28
	s_addc_u32 s31, s27, s29
	s_add_u32 s36, s30, 0x100
	s_addc_u32 s37, s31, 0
	s_add_u32 s30, s30, 0x180
	s_addc_u32 s31, s31, 0
	s_cmpk_eq_i32 s28, 0xf00
	s_cselect_b32 s31, s57, s31
	s_cselect_b32 s30, s23, s30
	s_cselect_b32 s35, s11, s65
	s_cselect_b32 s34, s15, s64
	s_cselect_b32 s37, s4, s37
	s_cselect_b32 s36, s5, s36
	s_mov_b32 m0, s50
	v_lshl_add_u64 v[236:237], v[164:165], 0, s[28:29]
	global_load_lds_dwordx4 v[236:237], off
	v_lshl_add_u64 v[236:237], v[166:167], 0, s[28:29]
	s_mov_b32 m0, s51
	s_nop 0
	global_load_lds_dwordx4 v[236:237], off
	s_waitcnt vmcnt(8) lgkmcnt(0)
	s_barrier
; #define PG8_STAGE(bufoff, gbase, voff) do { _Pragma("unroll") for (int _i = 0; _i < 2; ++_i) \
;         __builtin_amdgcn_global_load_lds((const unsigned*)((const char*)(gbase) + (voff)[_i]), (LAS unsigned*)(lds + (bufoff) + ldsw + _i * 8192), 16, 0, 0); } while (0)
; #define PG8_LDA(dst, b, h) do { _Pragma("unroll") for (int m = 0; m < 4; ++m) _Pragma("unroll") for (int k = 0; k < 2; ++k) dst[m][k] = *(const LAS bf16x8*)(lds + PG8_SA(b, h) + aoff + m * 2048 + k * 1024); } while (0)
; #define PG8_MMA(ai, bj, At, Bt) do { __builtin_amdgcn_s_setprio(1); _Pragma("unroll") for (int m = 0; m < 4; ++m) _Pragma("unroll") for (int n = 0; n < 2; ++n) _Pragma("unroll") for (int k = 0; k < 2; ++k) \
;         acc[ai][bj][m][n] = __builtin_amdgcn_mfma_f32_16x16x32_bf16(Bt[n][k], At[m][k], acc[ai][bj][m][n], 0, 0, 0); __builtin_amdgcn_s_setprio(0); } while (0)
; #define PG8_WAIT_V(n) asm volatile("s_waitcnt vmcnt(" #n ")" ::: "memory")
; #define PG8_WAIT_L(n) asm volatile("s_waitcnt lgkmcnt(" #n ")" ::: "memory")
; #define PG8_BAR __builtin_amdgcn_s_barrier()
; #define PG8_SCHED __builtin_amdgcn_sched_barrier(0)
; template <class Epi, class Sched, bool ABLK = false, bool ALIGN_EPI = true, bool SP2 = true, bool BBLK = true>
; __device__ __forceinline__ void gemm_phase(LAS unsigned char* lds, const Gemm g, const Sched& S, const Epi& E) {
;     ...
;             PG8_WAIT_V(8); PG8_WAIT_L(0); PG8_BAR; PG8_MMA(0, 0, At, B0); PG8_MMA(0, 1, At, B1); PG8_BAR; PG8_SCHED;
;             PG8_LDA(At, 0, 1); PG8_STAGE(PG8_SB(0, 0), b2, voffB); PG8_STAGE(PG8_SB(0, 1), b2 + hstepB, voffB); PG8_STAGE(PG8_SA(0, 0), a2, voffA);
;             PG8_WAIT_V(8); PG8_WAIT_L(0); PG8_BAR; PG8_MMA(1, 0, At, B0); PG8_MMA(1, 1, At, B1); PG8_BAR; PG8_SCHED;
	v_mfma_f32_16x16x32_bf16 v[126:129], v[172:175], v[204:207], v[126:129]
	v_mfma_f32_16x16x32_bf16 v[122:125], v[180:183], v[204:207], v[122:125]
	v_mfma_f32_16x16x32_bf16 v[110:113], v[172:175], v[212:215], v[110:113]
	v_mfma_f32_16x16x32_bf16 v[106:109], v[180:183], v[212:215], v[106:109]
	v_mfma_f32_16x16x32_bf16 v[94:97], v[172:175], v[220:223], v[94:97]
	v_mfma_f32_16x16x32_bf16 v[90:93], v[180:183], v[220:223], v[90:93]
	v_mfma_f32_16x16x32_bf16 v[78:81], v[172:175], v[228:231], v[78:81]
	v_mfma_f32_16x16x32_bf16 v[74:77], v[180:183], v[228:231], v[74:77]
	v_mfma_f32_16x16x32_bf16 v[126:129], v[176:179], v[208:211], v[126:129]
	v_mfma_f32_16x16x32_bf16 v[122:125], v[184:187], v[208:211], v[122:125]
	v_mfma_f32_16x16x32_bf16 v[110:113], v[176:179], v[216:219], v[110:113]
	v_mfma_f32_16x16x32_bf16 v[106:109], v[184:187], v[216:219], v[106:109]
	v_mfma_f32_16x16x32_bf16 v[94:97], v[176:179], v[224:227], v[94:97]
	v_mfma_f32_16x16x32_bf16 v[90:93], v[184:187], v[224:227], v[90:93]
	v_mfma_f32_16x16x32_bf16 v[78:81], v[176:179], v[232:235], v[78:81]
	v_mfma_f32_16x16x32_bf16 v[74:77], v[184:187], v[232:235], v[74:77]
	v_mfma_f32_16x16x32_bf16 v[118:121], v[188:191], v[204:207], v[118:121]
	v_mfma_f32_16x16x32_bf16 v[114:117], v[196:199], v[204:207], v[114:117]
	v_mfma_f32_16x16x32_bf16 v[102:105], v[188:191], v[212:215], v[102:105]
	v_mfma_f32_16x16x32_bf16 v[98:101], v[196:199], v[212:215], v[98:101]
	v_mfma_f32_16x16x32_bf16 v[86:89], v[188:191], v[220:223], v[86:89]
	v_mfma_f32_16x16x32_bf16 v[82:85], v[196:199], v[220:223], v[82:85]
	v_mfma_f32_16x16x32_bf16 v[70:73], v[188:191], v[228:231], v[70:73]
	v_mfma_f32_16x16x32_bf16 v[66:69], v[196:199], v[228:231], v[66:69]
	v_mfma_f32_16x16x32_bf16 v[118:121], v[192:195], v[208:211], v[118:121]
	v_mfma_f32_16x16x32_bf16 v[114:117], v[200:203], v[208:211], v[114:117]
	v_mfma_f32_16x16x32_bf16 v[102:105], v[192:195], v[216:219], v[102:105]
	v_mfma_f32_16x16x32_bf16 v[98:101], v[200:203], v[216:219], v[98:101]
	v_mfma_f32_16x16x32_bf16 v[86:89], v[192:195], v[224:227], v[86:89]
	v_mfma_f32_16x16x32_bf16 v[82:85], v[200:203], v[224:227], v[82:85]
	v_mfma_f32_16x16x32_bf16 v[70:73], v[192:195], v[232:235], v[70:73]
	v_mfma_f32_16x16x32_bf16 v[66:69], v[200:203], v[232:235], v[66:69]
	s_barrier
	ds_read_b128 v[204:207], v171 offset:16384
	ds_read_b128 v[208:211], v171 offset:17408
	ds_read_b128 v[212:215], v171 offset:18432
	ds_read_b128 v[216:219], v171 offset:19456
	ds_read_b128 v[220:223], v171 offset:20480
	ds_read_b128 v[224:227], v171 offset:21504
	ds_read_b128 v[228:231], v171 offset:22528
	ds_read_b128 v[232:235], v171 offset:23552
	s_mov_b32 m0, s55
	s_add_u32 s76, s34, 0x4000
	global_load_lds_dwordx4 v134, s[34:35]
	s_mov_b32 m0, s56
	s_addc_u32 s77, s35, 0
	s_add_i32 s67, s73, s42
	global_load_lds_dwordx4 v130, s[34:35]
	s_mov_b32 m0, s67
	s_nop 0
	global_load_lds_dwordx4 v134, s[76:77]
	s_add_i32 m0, s67, 0x2000
	s_nop 0
	global_load_lds_dwordx4 v130, s[76:77]
	s_mov_b32 m0, s25
	s_nop 0
	global_load_lds_dwordx4 v136, s[36:37]
	s_mov_b32 m0, s43
	s_nop 0
	global_load_lds_dwordx4 v132, s[36:37]
	s_waitcnt vmcnt(8) lgkmcnt(0)
	s_barrier
	v_mfma_f32_16x16x32_bf16 v[62:65], v[172:175], v[204:207], v[62:65]
	v_mfma_f32_16x16x32_bf16 v[58:61], v[180:183], v[204:207], v[58:61]
	v_mfma_f32_16x16x32_bf16 v[46:49], v[172:175], v[212:215], v[46:49]
	v_mfma_f32_16x16x32_bf16 v[42:45], v[180:183], v[212:215], v[42:45]
	v_mfma_f32_16x16x32_bf16 v[30:33], v[172:175], v[220:223], v[30:33]
	v_mfma_f32_16x16x32_bf16 v[26:29], v[180:183], v[220:223], v[26:29]
	v_mfma_f32_16x16x32_bf16 v[14:17], v[172:175], v[228:231], v[14:17]
	v_mfma_f32_16x16x32_bf16 v[10:13], v[180:183], v[228:231], v[10:13]
	v_mfma_f32_16x16x32_bf16 v[62:65], v[176:179], v[208:211], v[62:65]
	v_mfma_f32_16x16x32_bf16 v[58:61], v[184:187], v[208:211], v[58:61]
	v_mfma_f32_16x16x32_bf16 v[46:49], v[176:179], v[216:219], v[46:49]
	v_mfma_f32_16x16x32_bf16 v[42:45], v[184:187], v[216:219], v[42:45]
	v_mfma_f32_16x16x32_bf16 v[30:33], v[176:179], v[224:227], v[30:33]
	v_mfma_f32_16x16x32_bf16 v[26:29], v[184:187], v[224:227], v[26:29]
	v_mfma_f32_16x16x32_bf16 v[14:17], v[176:179], v[232:235], v[14:17]
	v_mfma_f32_16x16x32_bf16 v[10:13], v[184:187], v[232:235], v[10:13]
	v_mfma_f32_16x16x32_bf16 v[54:57], v[188:191], v[204:207], v[54:57]
	v_mfma_f32_16x16x32_bf16 v[50:53], v[196:199], v[204:207], v[50:53]
	v_mfma_f32_16x16x32_bf16 v[38:41], v[188:191], v[212:215], v[38:41]
	v_mfma_f32_16x16x32_bf16 v[34:37], v[196:199], v[212:215], v[34:37]
	v_mfma_f32_16x16x32_bf16 v[22:25], v[188:191], v[220:223], v[22:25]
	v_mfma_f32_16x16x32_bf16 v[18:21], v[196:199], v[220:223], v[18:21]
	v_mfma_f32_16x16x32_bf16 v[6:9], v[188:191], v[228:231], v[6:9]
	v_mfma_f32_16x16x32_bf16 v[2:5], v[196:199], v[228:231], v[2:5]
	v_mfma_f32_16x16x32_bf16 v[54:57], v[192:195], v[208:211], v[54:57]
	v_mfma_f32_16x16x32_bf16 v[50:53], v[200:203], v[208:211], v[50:53]
	v_mfma_f32_16x16x32_bf16 v[38:41], v[192:195], v[216:219], v[38:41]
	v_mfma_f32_16x16x32_bf16 v[34:37], v[200:203], v[216:219], v[34:37]
	v_mfma_f32_16x16x32_bf16 v[22:25], v[192:195], v[224:227], v[22:25]
	v_mfma_f32_16x16x32_bf16 v[18:21], v[200:203], v[224:227], v[18:21]
	v_mfma_f32_16x16x32_bf16 v[6:9], v[192:195], v[232:235], v[6:9]
	v_mfma_f32_16x16x32_bf16 v[2:5], v[200:203], v[232:235], v[2:5]
	s_barrier
; #define PG8_STAGE(bufoff, gbase, voff) do { _Pragma("unroll") for (int _i = 0; _i < 2; ++_i) \
;         __builtin_amdgcn_global_load_lds((const unsigned*)((const char*)(gbase) + (voff)[_i]), (LAS unsigned*)(lds + (bufoff) + ldsw + _i * 8192), 16, 0, 0); } while (0)
; #define PG8_LDA(dst, b, h) do { _Pragma("unroll") for (int m = 0; m < 4; ++m) _Pragma("unroll") for (int k = 0; k < 2; ++k) dst[m][k] = *(const LAS bf16x8*)(lds + PG8_SA(b, h) + aoff + m * 2048 + k * 1024); } while (0)
; #define PG8_LDB(dst, b, h) do { _Pragma("unroll") for (int n = 0; n < 2; ++n) _Pragma("unroll") for (int k = 0; k < 2; ++k) dst[n][k] = *(const LAS bf16x8*)(lds + PG8_SB(b, h) + boff + n * 2048 + k * 1024); } while (0)
; #define PG8_MMA(ai, bj, At, Bt) do { __builtin_amdgcn_s_setprio(1); _Pragma("unroll") for (int m = 0; m < 4; ++m) _Pragma("unroll") for (int n = 0; n < 2; ++n) _Pragma("unroll") for (int k = 0; k < 2; ++k) \
;         acc[ai][bj][m][n] = __builtin_amdgcn_mfma_f32_16x16x32_bf16(Bt[n][k], At[m][k], acc[ai][bj][m][n], 0, 0, 0); __builtin_amdgcn_s_setprio(0); } while (0)
; #define PG8_WAIT_V(n) asm volatile("s_waitcnt vmcnt(" #n ")" ::: "memory")
; #define PG8_WAIT_L(n) asm volatile("s_waitcnt lgkmcnt(" #n ")" ::: "memory")
; #define PG8_BAR __builtin_amdgcn_s_barrier()
; #define PG8_SCHED __builtin_amdgcn_sched_barrier(0)
; template <class Epi, class Sched, bool ABLK = false, bool ALIGN_EPI = true, bool SP2 = true, bool BBLK = true>
; __device__ __forceinline__ void gemm_phase(LAS unsigned char* lds, const Gemm g, const Sched& S, const Epi& E) {
;     ...
;             PG8_LDB(B0, 1, 0); PG8_LDB(B1, 1, 1); PG8_SCHED; PG8_LDA(At, 1, 0); PG8_STAGE(PG8_SA(0, 1), a2 + hstepA, voffA);
;             PG8_WAIT_V(8); PG8_WAIT_L(0); PG8_BAR; PG8_MMA(0, 0, At, B0); PG8_MMA(0, 1, At, B1); PG8_BAR; PG8_SCHED;
;             PG8_LDA(At, 1, 1); PG8_STAGE(PG8_SB(1, 0), b3, voffB); PG8_STAGE(PG8_SB(1, 1), b3 + hstepB, voffB); PG8_STAGE(PG8_SA(1, 0), a3, voffA);
;             PG8_WAIT_V(8); PG8_WAIT_L(0); PG8_BAR; PG8_MMA(1, 0, At, B0); PG8_MMA(1, 1, At, B1); PG8_BAR; PG8_SCHED;
;     ...
;         if constexpr (ALIGN_EPI) { if (wr == 0) PG8_BAR; }
	v_add_u32_e32 v184, s60, v168
	v_add_u32_e32 v200, s61, v168
	ds_read_b128 v[172:175], v184
	ds_read_b128 v[176:179], v184 offset:1024
	ds_read_b128 v[180:183], v184 offset:2048
	ds_read_b128 v[184:187], v184 offset:3072
	ds_read_b128 v[188:191], v200
	ds_read_b128 v[192:195], v200 offset:1024
	ds_read_b128 v[196:199], v200 offset:2048
	ds_read_b128 v[200:203], v200 offset:3072
	ds_read_b128 v[204:207], v171 offset:32768
	ds_read_b128 v[208:211], v171 offset:33792
	ds_read_b128 v[212:215], v171 offset:34816
	ds_read_b128 v[216:219], v171 offset:35840
	ds_read_b128 v[220:223], v171 offset:36864
	ds_read_b128 v[224:227], v171 offset:37888
	ds_read_b128 v[228:231], v171 offset:38912
	ds_read_b128 v[232:235], v171 offset:39936
	s_add_u32 s36, s36, 0x80000
	s_addc_u32 s37, s37, 0
	s_mov_b32 m0, s44
	s_nop 0
	global_load_lds_dwordx4 v136, s[36:37]
	s_mov_b32 m0, s45
	s_nop 0
	global_load_lds_dwordx4 v132, s[36:37]
	s_waitcnt vmcnt(8) lgkmcnt(0)
	s_barrier
	v_mfma_f32_16x16x32_bf16 v[126:129], v[172:175], v[204:207], v[126:129]
	v_mfma_f32_16x16x32_bf16 v[122:125], v[180:183], v[204:207], v[122:125]
	v_mfma_f32_16x16x32_bf16 v[110:113], v[172:175], v[212:215], v[110:113]
	v_mfma_f32_16x16x32_bf16 v[106:109], v[180:183], v[212:215], v[106:109]
	v_mfma_f32_16x16x32_bf16 v[94:97], v[172:175], v[220:223], v[94:97]
	v_mfma_f32_16x16x32_bf16 v[90:93], v[180:183], v[220:223], v[90:93]
	v_mfma_f32_16x16x32_bf16 v[78:81], v[172:175], v[228:231], v[78:81]
	v_mfma_f32_16x16x32_bf16 v[74:77], v[180:183], v[228:231], v[74:77]
	v_mfma_f32_16x16x32_bf16 v[126:129], v[176:179], v[208:211], v[126:129]
	v_mfma_f32_16x16x32_bf16 v[122:125], v[184:187], v[208:211], v[122:125]
	v_mfma_f32_16x16x32_bf16 v[110:113], v[176:179], v[216:219], v[110:113]
	v_mfma_f32_16x16x32_bf16 v[106:109], v[184:187], v[216:219], v[106:109]
	v_mfma_f32_16x16x32_bf16 v[94:97], v[176:179], v[224:227], v[94:97]
	v_mfma_f32_16x16x32_bf16 v[90:93], v[184:187], v[224:227], v[90:93]
	v_mfma_f32_16x16x32_bf16 v[78:81], v[176:179], v[232:235], v[78:81]
	v_mfma_f32_16x16x32_bf16 v[74:77], v[184:187], v[232:235], v[74:77]
	v_mfma_f32_16x16x32_bf16 v[118:121], v[188:191], v[204:207], v[118:121]
	v_mfma_f32_16x16x32_bf16 v[114:117], v[196:199], v[204:207], v[114:117]
	v_mfma_f32_16x16x32_bf16 v[102:105], v[188:191], v[212:215], v[102:105]
	v_mfma_f32_16x16x32_bf16 v[98:101], v[196:199], v[212:215], v[98:101]
	v_mfma_f32_16x16x32_bf16 v[86:89], v[188:191], v[220:223], v[86:89]
	v_mfma_f32_16x16x32_bf16 v[82:85], v[196:199], v[220:223], v[82:85]
	v_mfma_f32_16x16x32_bf16 v[70:73], v[188:191], v[228:231], v[70:73]
	v_mfma_f32_16x16x32_bf16 v[66:69], v[196:199], v[228:231], v[66:69]
	v_mfma_f32_16x16x32_bf16 v[118:121], v[192:195], v[208:211], v[118:121]
	v_mfma_f32_16x16x32_bf16 v[114:117], v[200:203], v[208:211], v[114:117]
	v_mfma_f32_16x16x32_bf16 v[102:105], v[192:195], v[216:219], v[102:105]
	v_mfma_f32_16x16x32_bf16 v[98:101], v[200:203], v[216:219], v[98:101]
	v_mfma_f32_16x16x32_bf16 v[86:89], v[192:195], v[224:227], v[86:89]
	v_mfma_f32_16x16x32_bf16 v[82:85], v[200:203], v[224:227], v[82:85]
	v_mfma_f32_16x16x32_bf16 v[70:73], v[192:195], v[232:235], v[70:73]
	v_mfma_f32_16x16x32_bf16 v[66:69], v[200:203], v[232:235], v[66:69]
	s_barrier
	ds_read_b128 v[204:207], v171 offset:49152
	ds_read_b128 v[208:211], v171 offset:50176
	ds_read_b128 v[212:215], v171 offset:51200
	ds_read_b128 v[216:219], v171 offset:52224
	ds_read_b128 v[220:223], v171 offset:53248
	ds_read_b128 v[224:227], v171 offset:54272
	ds_read_b128 v[228:231], v171 offset:55296
	ds_read_b128 v[232:235], v171 offset:56320
	s_add_u32 s36, s34, 0x8000
	s_addc_u32 s37, s35, 0
	s_add_i32 s67, s60, s42
	s_mov_b32 m0, s67
	s_nop 0
	global_load_lds_dwordx4 v134, s[36:37]
	s_add_i32 m0, s67, 0x2000
	s_add_u32 s34, s34, 0xc000
	v_lshl_add_u64 v[236:237], s[36:37], 0, v[130:131]
	s_addc_u32 s35, s35, 0
	s_add_i32 s36, s61, s42
	global_load_lds_dwordx4 v[236:237], off
	s_mov_b32 m0, s36
	s_nop 0
	global_load_lds_dwordx4 v134, s[34:35]
	s_add_i32 m0, s36, 0x2000
	s_nop 0
	global_load_lds_dwordx4 v130, s[34:35]
	s_mov_b32 m0, s48
	s_nop 0
	global_load_lds_dwordx4 v136, s[30:31]
	s_mov_b32 m0, s49
	s_nop 0
	global_load_lds_dwordx4 v132, s[30:31]
	s_waitcnt vmcnt(8) lgkmcnt(0)
	s_barrier
	v_mfma_f32_16x16x32_bf16 v[62:65], v[172:175], v[204:207], v[62:65]
	v_mfma_f32_16x16x32_bf16 v[58:61], v[180:183], v[204:207], v[58:61]
	v_mfma_f32_16x16x32_bf16 v[46:49], v[172:175], v[212:215], v[46:49]
	v_mfma_f32_16x16x32_bf16 v[42:45], v[180:183], v[212:215], v[42:45]
	v_mfma_f32_16x16x32_bf16 v[30:33], v[172:175], v[220:223], v[30:33]
	v_mfma_f32_16x16x32_bf16 v[26:29], v[180:183], v[220:223], v[26:29]
	v_mfma_f32_16x16x32_bf16 v[14:17], v[172:175], v[228:231], v[14:17]
	v_mfma_f32_16x16x32_bf16 v[10:13], v[180:183], v[228:231], v[10:13]
	v_mfma_f32_16x16x32_bf16 v[62:65], v[176:179], v[208:211], v[62:65]
	v_mfma_f32_16x16x32_bf16 v[58:61], v[184:187], v[208:211], v[58:61]
	v_mfma_f32_16x16x32_bf16 v[46:49], v[176:179], v[216:219], v[46:49]
	v_mfma_f32_16x16x32_bf16 v[42:45], v[184:187], v[216:219], v[42:45]
	v_mfma_f32_16x16x32_bf16 v[30:33], v[176:179], v[224:227], v[30:33]
	v_mfma_f32_16x16x32_bf16 v[26:29], v[184:187], v[224:227], v[26:29]
	v_mfma_f32_16x16x32_bf16 v[14:17], v[176:179], v[232:235], v[14:17]
	v_mfma_f32_16x16x32_bf16 v[10:13], v[184:187], v[232:235], v[10:13]
	v_mfma_f32_16x16x32_bf16 v[54:57], v[188:191], v[204:207], v[54:57]
	v_mfma_f32_16x16x32_bf16 v[50:53], v[196:199], v[204:207], v[50:53]
	v_mfma_f32_16x16x32_bf16 v[38:41], v[188:191], v[212:215], v[38:41]
	v_mfma_f32_16x16x32_bf16 v[34:37], v[196:199], v[212:215], v[34:37]
	v_mfma_f32_16x16x32_bf16 v[22:25], v[188:191], v[220:223], v[22:25]
	v_mfma_f32_16x16x32_bf16 v[18:21], v[196:199], v[220:223], v[18:21]
	v_mfma_f32_16x16x32_bf16 v[6:9], v[188:191], v[228:231], v[6:9]
	v_mfma_f32_16x16x32_bf16 v[2:5], v[196:199], v[228:231], v[2:5]
	v_mfma_f32_16x16x32_bf16 v[54:57], v[192:195], v[208:211], v[54:57]
	v_mfma_f32_16x16x32_bf16 v[50:53], v[200:203], v[208:211], v[50:53]
	v_mfma_f32_16x16x32_bf16 v[38:41], v[192:195], v[216:219], v[38:41]
	v_mfma_f32_16x16x32_bf16 v[34:37], v[200:203], v[216:219], v[34:37]
	v_mfma_f32_16x16x32_bf16 v[22:25], v[192:195], v[224:227], v[22:25]
	v_mfma_f32_16x16x32_bf16 v[18:21], v[200:203], v[224:227], v[18:21]
	v_mfma_f32_16x16x32_bf16 v[6:9], v[192:195], v[232:235], v[6:9]
	v_mfma_f32_16x16x32_bf16 v[2:5], v[200:203], v[232:235], v[2:5]
	s_barrier
	s_add_i32 s66, s66, 2
	s_add_u32 s28, s28, 0x100
	s_addc_u32 s29, s29, 0
	s_add_u32 s64, s64, 0x10000
	s_addc_u32 s65, s65, 0
	s_cmp_gt_u32 s66, 29
	s_cbranch_scc0 .LBB0_1164
	s_and_b64 vcc, exec, s[6:7]
	s_cbranch_vccz .LBB0_1167
	s_barrier

; #define PG8_STAGE(bufoff, gbase, voff) do { _Pragma("unroll") for (int _i = 0; _i < 2; ++_i) \
;         __builtin_amdgcn_global_load_lds((const unsigned*)((const char*)(gbase) + (voff)[_i]), (LAS unsigned*)(lds + (bufoff) + ldsw + _i * 8192), 16, 0, 0); } while (0)
; #define PG8_LDA(dst, b, h) do { _Pragma("unroll") for (int m = 0; m < 4; ++m) _Pragma("unroll") for (int k = 0; k < 2; ++k) dst[m][k] = *(const LAS bf16x8*)(lds + PG8_SA(b, h) + aoff + m * 2048 + k * 1024); } while (0)
; #define PG8_LDB(dst, b, h) do { _Pragma("unroll") for (int n = 0; n < 2; ++n) _Pragma("unroll") for (int k = 0; k < 2; ++k) dst[n][k] = *(const LAS bf16x8*)(lds + PG8_SB(b, h) + boff + n * 2048 + k * 1024); } while (0)
; #define PG8_WAIT_V(n) asm volatile("s_waitcnt vmcnt(" #n ")" ::: "memory")
; #define PG8_WAIT_L(n) asm volatile("s_waitcnt lgkmcnt(" #n ")" ::: "memory")
; #define PG8_BAR __builtin_amdgcn_s_barrier()
; #define PG8_SCHED __builtin_amdgcn_sched_barrier(0)
; template <class Epi, class Sched, bool ABLK = false, bool ALIGN_EPI = true, bool SP2 = true, bool BBLK = true>
; __device__ __forceinline__ void gemm_phase(LAS unsigned char* lds, const Gemm g, const Sched& S, const Epi& E) {
;     ...
;         const bool has_next = S.next(ui + 1, nxt);
;         const int nt = cur.nt;
;         const char* nuA = has_next ? a_unit(nxt) : uA; const int ntbA = has_next ? nxt.k0 / BK : tbA; const char* nB = has_next ? (const char*)g.Bt + (size_t)nxt.pn * tstepB + b_k0(nxt.k0) : cB;
;         for (int t = 0; t < nt; t += 2) {
;             const bool last = (t == nt - 2);
;             const char* a1 = a_tile(uA, tbA + t + 1);
;             const char* a2 = last ? a_tile(nuA, ntbA) : a_tile(uA, tbA + t + 2); const char* b2 = last ? nB : cB + (size_t)(t + 2) * kstepB;
;             const char* a3 = last ? a_tile(nuA, ntbA + 1) : a_tile(uA, tbA + t + 3); const char* b3 = b2 + kstepB;
;             if (last && has_next) S.a_ready(nxt);
;             if constexpr (SP2) {
;             PG8_LDB(B0, 0, 0); PG8_LDB(B1, 0, 1); PG8_SCHED; PG8_LDA(At, 0, 0); PG8_STAGE(PG8_SA(1, 1), a1 + hstepA, voffA);
;             PG8_WAIT_V(8); PG8_WAIT_L(0); PG8_BAR; PG8_MMA(0, 0, At, B0); PG8_MMA(0, 1, At, B1); PG8_BAR; PG8_SCHED;
;             PG8_LDA(At, 0, 1); PG8_STAGE(PG8_SB(0, 0), b2, voffB); PG8_STAGE(PG8_SB(0, 1), b2 + hstepB, voffB); PG8_STAGE(PG8_SA(0, 0), a2, voffA);
.LBB0_1228:
	ds_read_b128 v[152:155], v149
	ds_read_b128 v[156:159], v149 offset:1024
	ds_read_b128 v[160:163], v149 offset:2048
	ds_read_b128 v[164:167], v149 offset:3072
	ds_read_b128 v[168:171], v150
	ds_read_b128 v[172:175], v150 offset:1024
	ds_read_b128 v[176:179], v150 offset:2048
	ds_read_b128 v[180:183], v150 offset:3072
	ds_read_b128 v[184:187], v151
	ds_read_b128 v[188:191], v151 offset:1024
	ds_read_b128 v[192:195], v151 offset:2048
	ds_read_b128 v[196:199], v151 offset:3072
	ds_read_b128 v[200:203], v151 offset:4096
	ds_read_b128 v[204:207], v151 offset:5120
	ds_read_b128 v[208:211], v151 offset:6144
	ds_read_b128 v[212:215], v151 offset:7168
	s_ashr_i32 s81, s80, 31
	s_andn2_b64 vcc, exec, s[4:5]
	s_lshl_b64 s[16:17], s[80:81], 22
	s_add_u32 s16, s1, s16
	s_addc_u32 s17, s33, s17
	s_and_b64 s[18:19], s[4:5], exec
	s_cselect_b32 s27, s17, s25
	s_cselect_b32 s46, s16, s24
	s_ashr_i32 s18, s0, 31
	s_lshr_b32 s18, s18, 26
	s_add_i32 s18, s0, s18
	s_ashr_i32 s18, s18, 6
	s_and_b64 s[20:21], s[4:5], exec
	s_cselect_b32 s28, s18, s26
	s_ashr_i32 s79, s78, 31
	s_lshl_b64 s[20:21], s[78:79], 22
	s_add_u32 s29, s30, s20
	s_addc_u32 s47, s31, s21
	s_ashr_i32 s19, s18, 31
	s_lshl_b64 s[20:21], s[18:19], 15
	s_add_u32 s20, s29, s20
	s_addc_u32 s21, s47, s21
	v_cndmask_b32_e64 v2, 0, 1, s[4:5]
	s_and_b64 s[4:5], s[4:5], exec
	s_cselect_b32 s4, s21, s23
	s_cselect_b32 s5, s20, s22
	s_ashr_i32 s29, s28, 31
	s_lshl_b64 s[28:29], s[28:29], 15
	s_add_u32 s19, s46, s28
	s_addc_u32 s46, s27, s29
	s_add_u32 s47, s19, 0x8000
	s_addc_u32 s48, s46, 0
	s_add_u32 s49, s22, 0x10000
	s_addc_u32 s50, s23, 0
	s_ashr_i32 s27, s26, 31
	v_cmp_ne_u32_e64 s[10:11], 1, v2
	s_lshl_b64 s[22:23], s[26:27], 15
	v_lshl_add_u64 v[2:3], s[24:25], 0, v[138:139]
	s_add_u32 s51, s24, s22
	v_lshl_add_u64 v[142:143], v[2:3], 0, s[22:23]
	v_lshl_add_u64 v[2:3], s[24:25], 0, v[140:141]
	s_addc_u32 s55, s25, s23
	v_lshl_add_u64 v[144:145], v[2:3], 0, s[22:23]
	s_lshl_b32 s22, s44, 15
	s_add_i32 s22, s22, 0xfff00000
	v_mov_b32_e32 v2, 0
	s_add_u32 s56, s22, 0xf0000
	s_mov_b32 s57, 0
	s_mov_b64 s[22:23], 0
	s_add_u32 s24, s51, s22
	s_addc_u32 s25, s55, s23
	s_add_u32 s28, s24, 0x10000
	s_addc_u32 s29, s25, 0
	s_add_i32 s57, s57, 2
	s_add_u32 s26, s49, s22
	s_addc_u32 s27, s50, s23
	s_add_u32 s24, s24, 0x18000
	s_addc_u32 s25, s25, 0
	s_cmp_eq_u32 s56, s22
	s_cselect_b32 s25, s48, s25
	s_cselect_b32 s24, s47, s24
	s_cselect_b32 s27, s4, s27
	s_cselect_b32 s26, s5, s26
	s_cselect_b32 s29, s46, s29
	s_cselect_b32 s28, s19, s28
	v_lshl_add_u64 v[216:217], v[142:143], 0, s[22:23]
	s_add_i32 m0, s35, 0xc000
	s_nop 0
	global_load_lds_dwordx4 v[216:217], off
	v_lshl_add_u64 v[216:217], v[144:145], 0, s[22:23]
	s_add_i32 m0, s35, 0xe000
	s_nop 0
	global_load_lds_dwordx4 v[216:217], off
	s_waitcnt vmcnt(8) lgkmcnt(0)
	s_barrier
	v_mfma_f32_16x16x32_bf16 v[126:129], v[152:155], v[184:187], 0
	v_mfma_f32_16x16x32_bf16 v[122:125], v[160:163], v[184:187], 0
	v_mfma_f32_16x16x32_bf16 v[110:113], v[152:155], v[192:195], 0
	v_mfma_f32_16x16x32_bf16 v[106:109], v[160:163], v[192:195], 0
	v_mfma_f32_16x16x32_bf16 v[94:97], v[152:155], v[200:203], 0
	v_mfma_f32_16x16x32_bf16 v[90:93], v[160:163], v[200:203], 0
	v_mfma_f32_16x16x32_bf16 v[78:81], v[152:155], v[208:211], 0
	v_mfma_f32_16x16x32_bf16 v[74:77], v[160:163], v[208:211], 0
	v_mfma_f32_16x16x32_bf16 v[126:129], v[156:159], v[188:191], v[126:129]
	v_mfma_f32_16x16x32_bf16 v[122:125], v[164:167], v[188:191], v[122:125]
	v_mfma_f32_16x16x32_bf16 v[110:113], v[156:159], v[196:199], v[110:113]
	v_mfma_f32_16x16x32_bf16 v[106:109], v[164:167], v[196:199], v[106:109]
	v_mfma_f32_16x16x32_bf16 v[94:97], v[156:159], v[204:207], v[94:97]
	v_mfma_f32_16x16x32_bf16 v[90:93], v[164:167], v[204:207], v[90:93]
	v_mfma_f32_16x16x32_bf16 v[78:81], v[156:159], v[212:215], v[78:81]
	v_mfma_f32_16x16x32_bf16 v[74:77], v[164:167], v[212:215], v[74:77]
	v_mfma_f32_16x16x32_bf16 v[118:121], v[168:171], v[184:187], 0
	v_mfma_f32_16x16x32_bf16 v[114:117], v[176:179], v[184:187], 0
	v_mfma_f32_16x16x32_bf16 v[102:105], v[168:171], v[192:195], 0
	v_mfma_f32_16x16x32_bf16 v[98:101], v[176:179], v[192:195], 0
	v_mfma_f32_16x16x32_bf16 v[86:89], v[168:171], v[200:203], 0
	v_mfma_f32_16x16x32_bf16 v[82:85], v[176:179], v[200:203], 0
	v_mfma_f32_16x16x32_bf16 v[70:73], v[168:171], v[208:211], 0
	v_mfma_f32_16x16x32_bf16 v[66:69], v[176:179], v[208:211], 0
	v_mfma_f32_16x16x32_bf16 v[118:121], v[172:175], v[188:191], v[118:121]
	v_mfma_f32_16x16x32_bf16 v[114:117], v[180:183], v[188:191], v[114:117]
	v_mfma_f32_16x16x32_bf16 v[102:105], v[172:175], v[196:199], v[102:105]
	v_mfma_f32_16x16x32_bf16 v[98:101], v[180:183], v[196:199], v[98:101]
	v_mfma_f32_16x16x32_bf16 v[86:89], v[172:175], v[204:207], v[86:89]
	v_mfma_f32_16x16x32_bf16 v[82:85], v[180:183], v[204:207], v[82:85]
	v_mfma_f32_16x16x32_bf16 v[70:73], v[172:175], v[212:215], v[70:73]
	v_mfma_f32_16x16x32_bf16 v[66:69], v[180:183], v[212:215], v[66:69]
	s_barrier
	ds_read_b128 v[184:187], v151 offset:16384
	ds_read_b128 v[188:191], v151 offset:17408
	ds_read_b128 v[192:195], v151 offset:18432
	ds_read_b128 v[196:199], v151 offset:19456
	ds_read_b128 v[200:203], v151 offset:20480
	ds_read_b128 v[204:207], v151 offset:21504
	ds_read_b128 v[208:211], v151 offset:22528
	ds_read_b128 v[212:215], v151 offset:23552
	s_add_i32 s59, s72, s34
	s_mov_b32 m0, s59
	s_nop 0
	global_load_lds_dwordx4 v130, s[26:27]
	s_add_i32 m0, s59, 0x2000
	s_add_u32 s64, s26, 0x4000
	s_addc_u32 s65, s27, 0
	s_add_i32 s59, s73, s34
	global_load_lds_dwordx4 v132, s[26:27]
	s_mov_b32 m0, s59
	s_nop 0
	global_load_lds_dwordx4 v130, s[64:65]
	s_add_i32 m0, s59, 0x2000
	s_nop 0
	global_load_lds_dwordx4 v132, s[64:65]
	s_mov_b32 m0, s35
	s_nop 0
	global_load_lds_dwordx4 v130, s[28:29]
	s_mov_b32 m0, s36
	s_nop 0
	global_load_lds_dwordx4 v132, s[28:29]
	s_waitcnt vmcnt(8) lgkmcnt(0)
	s_barrier
; #define PG8_STAGE(bufoff, gbase, voff) do { _Pragma("unroll") for (int _i = 0; _i < 2; ++_i) \
;         __builtin_amdgcn_global_load_lds((const unsigned*)((const char*)(gbase) + (voff)[_i]), (LAS unsigned*)(lds + (bufoff) + ldsw + _i * 8192), 16, 0, 0); } while (0)
; #define PG8_LDA(dst, b, h) do { _Pragma("unroll") for (int m = 0; m < 4; ++m) _Pragma("unroll") for (int k = 0; k < 2; ++k) dst[m][k] = *(const LAS bf16x8*)(lds + PG8_SA(b, h) + aoff + m * 2048 + k * 1024); } while (0)
; #define PG8_LDB(dst, b, h) do { _Pragma("unroll") for (int n = 0; n < 2; ++n) _Pragma("unroll") for (int k = 0; k < 2; ++k) dst[n][k] = *(const LAS bf16x8*)(lds + PG8_SB(b, h) + boff + n * 2048 + k * 1024); } while (0)
; #define PG8_MMA(ai, bj, At, Bt) do { __builtin_amdgcn_s_setprio(1); _Pragma("unroll") for (int m = 0; m < 4; ++m) _Pragma("unroll") for (int n = 0; n < 2; ++n) _Pragma("unroll") for (int k = 0; k < 2; ++k) \
;         acc[ai][bj][m][n] = __builtin_amdgcn_mfma_f32_16x16x32_bf16(Bt[n][k], At[m][k], acc[ai][bj][m][n], 0, 0, 0); __builtin_amdgcn_s_setprio(0); } while (0)
; #define PG8_WAIT_V(n) asm volatile("s_waitcnt vmcnt(" #n ")" ::: "memory")
; #define PG8_WAIT_L(n) asm volatile("s_waitcnt lgkmcnt(" #n ")" ::: "memory")
; #define PG8_BAR __builtin_amdgcn_s_barrier()
; #define PG8_SCHED __builtin_amdgcn_sched_barrier(0)
; template <class Epi, class Sched, bool ABLK = false, bool ALIGN_EPI = true, bool SP2 = true, bool BBLK = true>
; __device__ __forceinline__ void gemm_phase(LAS unsigned char* lds, const Gemm g, const Sched& S, const Epi& E) {
;     ...
;             PG8_WAIT_V(8); PG8_WAIT_L(0); PG8_BAR; PG8_MMA(1, 0, At, B0); PG8_MMA(1, 1, At, B1); PG8_BAR; PG8_SCHED;
;             PG8_LDB(B0, 1, 0); PG8_LDB(B1, 1, 1); PG8_SCHED; PG8_LDA(At, 1, 0); PG8_STAGE(PG8_SA(0, 1), a2 + hstepA, voffA);
;             PG8_WAIT_V(8); PG8_WAIT_L(0); PG8_BAR; PG8_MMA(0, 0, At, B0); PG8_MMA(0, 1, At, B1); PG8_BAR; PG8_SCHED;
	v_mfma_f32_16x16x32_bf16 v[62:65], v[152:155], v[184:187], 0
	v_mfma_f32_16x16x32_bf16 v[58:61], v[160:163], v[184:187], 0
	v_mfma_f32_16x16x32_bf16 v[46:49], v[152:155], v[192:195], 0
	v_mfma_f32_16x16x32_bf16 v[42:45], v[160:163], v[192:195], 0
	v_mfma_f32_16x16x32_bf16 v[30:33], v[152:155], v[200:203], 0
	v_mfma_f32_16x16x32_bf16 v[26:29], v[160:163], v[200:203], 0
	v_mfma_f32_16x16x32_bf16 v[14:17], v[152:155], v[208:211], 0
	v_mfma_f32_16x16x32_bf16 v[10:13], v[160:163], v[208:211], 0
	v_mfma_f32_16x16x32_bf16 v[62:65], v[156:159], v[188:191], v[62:65]
	v_mfma_f32_16x16x32_bf16 v[58:61], v[164:167], v[188:191], v[58:61]
	v_mfma_f32_16x16x32_bf16 v[46:49], v[156:159], v[196:199], v[46:49]
	v_mfma_f32_16x16x32_bf16 v[42:45], v[164:167], v[196:199], v[42:45]
	v_mfma_f32_16x16x32_bf16 v[30:33], v[156:159], v[204:207], v[30:33]
	v_mfma_f32_16x16x32_bf16 v[26:29], v[164:167], v[204:207], v[26:29]
	v_mfma_f32_16x16x32_bf16 v[14:17], v[156:159], v[212:215], v[14:17]
	v_mfma_f32_16x16x32_bf16 v[10:13], v[164:167], v[212:215], v[10:13]
	v_mfma_f32_16x16x32_bf16 v[54:57], v[168:171], v[184:187], 0
	v_mfma_f32_16x16x32_bf16 v[50:53], v[176:179], v[184:187], 0
	v_mfma_f32_16x16x32_bf16 v[38:41], v[168:171], v[192:195], 0
	v_mfma_f32_16x16x32_bf16 v[34:37], v[176:179], v[192:195], 0
	v_mfma_f32_16x16x32_bf16 v[22:25], v[168:171], v[200:203], 0
	v_mfma_f32_16x16x32_bf16 v[18:21], v[176:179], v[200:203], 0
	v_mfma_f32_16x16x32_bf16 v[6:9], v[168:171], v[208:211], 0
	v_mfma_f32_16x16x32_bf16 v[2:5], v[176:179], v[208:211], 0
	v_mfma_f32_16x16x32_bf16 v[54:57], v[172:175], v[188:191], v[54:57]
	v_mfma_f32_16x16x32_bf16 v[50:53], v[180:183], v[188:191], v[50:53]
	v_mfma_f32_16x16x32_bf16 v[38:41], v[172:175], v[196:199], v[38:41]
	v_mfma_f32_16x16x32_bf16 v[34:37], v[180:183], v[196:199], v[34:37]
	v_mfma_f32_16x16x32_bf16 v[22:25], v[172:175], v[204:207], v[22:25]
	v_mfma_f32_16x16x32_bf16 v[18:21], v[180:183], v[204:207], v[18:21]
	v_mfma_f32_16x16x32_bf16 v[6:9], v[172:175], v[212:215], v[6:9]
	v_mfma_f32_16x16x32_bf16 v[2:5], v[180:183], v[212:215], v[2:5]
	s_barrier
	v_add_u32_e32 v164, s60, v147
	v_add_u32_e32 v180, s61, v147
	ds_read_b128 v[152:155], v164
	ds_read_b128 v[156:159], v164 offset:1024
	ds_read_b128 v[160:163], v164 offset:2048
	ds_read_b128 v[164:167], v164 offset:3072
	ds_read_b128 v[168:171], v180
	ds_read_b128 v[172:175], v180 offset:1024
	ds_read_b128 v[176:179], v180 offset:2048
	ds_read_b128 v[180:183], v180 offset:3072
	ds_read_b128 v[184:187], v151 offset:32768
	ds_read_b128 v[188:191], v151 offset:33792
	ds_read_b128 v[192:195], v151 offset:34816
	ds_read_b128 v[196:199], v151 offset:35840
	ds_read_b128 v[200:203], v151 offset:36864
	ds_read_b128 v[204:207], v151 offset:37888
	ds_read_b128 v[208:211], v151 offset:38912
	ds_read_b128 v[212:215], v151 offset:39936
	s_add_u32 s28, s28, 0x4000
	s_addc_u32 s29, s29, 0
	s_mov_b32 m0, s37
	s_nop 0
	global_load_lds_dwordx4 v130, s[28:29]
	s_mov_b32 m0, s40
	s_nop 0
	global_load_lds_dwordx4 v132, s[28:29]
	s_waitcnt vmcnt(8) lgkmcnt(0)
	s_barrier
	v_mfma_f32_16x16x32_bf16 v[126:129], v[152:155], v[184:187], v[126:129]
	v_mfma_f32_16x16x32_bf16 v[122:125], v[160:163], v[184:187], v[122:125]
	v_mfma_f32_16x16x32_bf16 v[110:113], v[152:155], v[192:195], v[110:113]
	v_mfma_f32_16x16x32_bf16 v[106:109], v[160:163], v[192:195], v[106:109]
	v_mfma_f32_16x16x32_bf16 v[94:97], v[152:155], v[200:203], v[94:97]
	v_mfma_f32_16x16x32_bf16 v[90:93], v[160:163], v[200:203], v[90:93]
	v_mfma_f32_16x16x32_bf16 v[78:81], v[152:155], v[208:211], v[78:81]
	v_mfma_f32_16x16x32_bf16 v[74:77], v[160:163], v[208:211], v[74:77]
	v_mfma_f32_16x16x32_bf16 v[126:129], v[156:159], v[188:191], v[126:129]
	v_mfma_f32_16x16x32_bf16 v[122:125], v[164:167], v[188:191], v[122:125]
	v_mfma_f32_16x16x32_bf16 v[110:113], v[156:159], v[196:199], v[110:113]
	v_mfma_f32_16x16x32_bf16 v[106:109], v[164:167], v[196:199], v[106:109]
	v_mfma_f32_16x16x32_bf16 v[94:97], v[156:159], v[204:207], v[94:97]
	v_mfma_f32_16x16x32_bf16 v[90:93], v[164:167], v[204:207], v[90:93]
	v_mfma_f32_16x16x32_bf16 v[78:81], v[156:159], v[212:215], v[78:81]
	v_mfma_f32_16x16x32_bf16 v[74:77], v[164:167], v[212:215], v[74:77]
	v_mfma_f32_16x16x32_bf16 v[118:121], v[168:171], v[184:187], v[118:121]
	v_mfma_f32_16x16x32_bf16 v[114:117], v[176:179], v[184:187], v[114:117]
	v_mfma_f32_16x16x32_bf16 v[102:105], v[168:171], v[192:195], v[102:105]
	v_mfma_f32_16x16x32_bf16 v[98:101], v[176:179], v[192:195], v[98:101]
	v_mfma_f32_16x16x32_bf16 v[86:89], v[168:171], v[200:203], v[86:89]
	v_mfma_f32_16x16x32_bf16 v[82:85], v[176:179], v[200:203], v[82:85]
	v_mfma_f32_16x16x32_bf16 v[70:73], v[168:171], v[208:211], v[70:73]
	v_mfma_f32_16x16x32_bf16 v[66:69], v[176:179], v[208:211], v[66:69]
	v_mfma_f32_16x16x32_bf16 v[118:121], v[172:175], v[188:191], v[118:121]
	v_mfma_f32_16x16x32_bf16 v[114:117], v[180:183], v[188:191], v[114:117]
	v_mfma_f32_16x16x32_bf16 v[102:105], v[172:175], v[196:199], v[102:105]
	v_mfma_f32_16x16x32_bf16 v[98:101], v[180:183], v[196:199], v[98:101]
	v_mfma_f32_16x16x32_bf16 v[86:89], v[172:175], v[204:207], v[86:89]
	v_mfma_f32_16x16x32_bf16 v[82:85], v[180:183], v[204:207], v[82:85]
	v_mfma_f32_16x16x32_bf16 v[70:73], v[172:175], v[212:215], v[70:73]
	v_mfma_f32_16x16x32_bf16 v[66:69], v[180:183], v[212:215], v[66:69]
	s_barrier
; #define PG8_STAGE(bufoff, gbase, voff) do { _Pragma("unroll") for (int _i = 0; _i < 2; ++_i) \
;         __builtin_amdgcn_global_load_lds((const unsigned*)((const char*)(gbase) + (voff)[_i]), (LAS unsigned*)(lds + (bufoff) + ldsw + _i * 8192), 16, 0, 0); } while (0)
; #define PG8_LDA(dst, b, h) do { _Pragma("unroll") for (int m = 0; m < 4; ++m) _Pragma("unroll") for (int k = 0; k < 2; ++k) dst[m][k] = *(const LAS bf16x8*)(lds + PG8_SA(b, h) + aoff + m * 2048 + k * 1024); } while (0)
; #define PG8_WAIT_V(n) asm volatile("s_waitcnt vmcnt(" #n ")" ::: "memory")
; #define PG8_WAIT_L(n) asm volatile("s_waitcnt lgkmcnt(" #n ")" ::: "memory")
; template <class Epi, class Sched, bool ABLK = false, bool ALIGN_EPI = true, bool SP2 = true, bool BBLK = true>
; __device__ __forceinline__ void gemm_phase(LAS unsigned char* lds, const Gemm g, const Sched& S, const Epi& E) {
;     ...
;         for (int t = 0; t < nt; t += 2) {
;             const bool last = (t == nt - 2);
;             const char* a1 = a_tile(uA, tbA + t + 1);
;             const char* a2 = last ? a_tile(nuA, ntbA) : a_tile(uA, tbA + t + 2); const char* b2 = last ? nB : cB + (size_t)(t + 2) * kstepB;
;             const char* a3 = last ? a_tile(nuA, ntbA + 1) : a_tile(uA, tbA + t + 3); const char* b3 = b2 + kstepB;
;             if (last && has_next) S.a_ready(nxt);
;             if constexpr (SP2) {
;             PG8_LDB(B0, 0, 0); PG8_LDB(B1, 0, 1); PG8_SCHED; PG8_LDA(At, 0, 0); PG8_STAGE(PG8_SA(1, 1), a1 + hstepA, voffA);
;             PG8_WAIT_V(8); PG8_WAIT_L(0); PG8_BAR; PG8_MMA(0, 0, At, B0); PG8_MMA(0, 1, At, B1); PG8_BAR; PG8_SCHED;
;             PG8_LDA(At, 0, 1); PG8_STAGE(PG8_SB(0, 0), b2, voffB); PG8_STAGE(PG8_SB(0, 1), b2 + hstepB, voffB); PG8_STAGE(PG8_SA(0, 0), a2, voffA);
;             PG8_WAIT_V(8); PG8_WAIT_L(0); PG8_BAR; PG8_MMA(1, 0, At, B0); PG8_MMA(1, 1, At, B1); PG8_BAR; PG8_SCHED;
;             PG8_LDB(B0, 1, 0); PG8_LDB(B1, 1, 1); PG8_SCHED; PG8_LDA(At, 1, 0); PG8_STAGE(PG8_SA(0, 1), a2 + hstepA, voffA);
;             PG8_WAIT_V(8); PG8_WAIT_L(0); PG8_BAR; PG8_MMA(0, 0, At, B0); PG8_MMA(0, 1, At, B1); PG8_BAR; PG8_SCHED;
;             PG8_LDA(At, 1, 1); PG8_STAGE(PG8_SB(1, 0), b3, voffB); PG8_STAGE(PG8_SB(1, 1), b3 + hstepB, voffB); PG8_STAGE(PG8_SA(1, 0), a3, voffA);
;             PG8_WAIT_V(8); PG8_WAIT_L(0); PG8_BAR; PG8_MMA(1, 0, At, B0); PG8_MMA(1, 1, At, B1); PG8_BAR; PG8_SCHED;
	ds_read_b128 v[184:187], v151 offset:49152
	ds_read_b128 v[188:191], v151 offset:50176
	ds_read_b128 v[192:195], v151 offset:51200
	ds_read_b128 v[196:199], v151 offset:52224
	ds_read_b128 v[200:203], v151 offset:53248
	ds_read_b128 v[204:207], v151 offset:54272
	ds_read_b128 v[208:211], v151 offset:55296
	ds_read_b128 v[212:215], v151 offset:56320
	s_add_u32 s28, s26, 0x8000
	s_addc_u32 s29, s27, 0
	s_add_i32 s59, s60, s34
	s_mov_b32 m0, s59
	s_nop 0
	global_load_lds_dwordx4 v130, s[28:29]
	s_add_i32 m0, s59, 0x2000
	s_add_u32 s26, s26, 0xc000
	v_lshl_add_u64 v[216:217], s[28:29], 0, v[132:133]
	s_addc_u32 s27, s27, 0
	s_add_i32 s28, s61, s34
	global_load_lds_dwordx4 v[216:217], off
	s_mov_b32 m0, s28
	s_nop 0
	global_load_lds_dwordx4 v130, s[26:27]
	s_add_i32 m0, s28, 0x2000
	s_nop 0
	global_load_lds_dwordx4 v132, s[26:27]
	s_mov_b32 m0, s41
	s_nop 0
	global_load_lds_dwordx4 v130, s[24:25]
	s_mov_b32 m0, s42
	s_nop 0
	global_load_lds_dwordx4 v132, s[24:25]
	s_waitcnt vmcnt(8) lgkmcnt(0)
	s_barrier
	v_mfma_f32_16x16x32_bf16 v[62:65], v[152:155], v[184:187], v[62:65]
	v_mfma_f32_16x16x32_bf16 v[58:61], v[160:163], v[184:187], v[58:61]
	v_mfma_f32_16x16x32_bf16 v[46:49], v[152:155], v[192:195], v[46:49]
	v_mfma_f32_16x16x32_bf16 v[42:45], v[160:163], v[192:195], v[42:45]
	v_mfma_f32_16x16x32_bf16 v[30:33], v[152:155], v[200:203], v[30:33]
	v_mfma_f32_16x16x32_bf16 v[26:29], v[160:163], v[200:203], v[26:29]
	v_mfma_f32_16x16x32_bf16 v[14:17], v[152:155], v[208:211], v[14:17]
	v_mfma_f32_16x16x32_bf16 v[10:13], v[160:163], v[208:211], v[10:13]
	v_mfma_f32_16x16x32_bf16 v[62:65], v[156:159], v[188:191], v[62:65]
	v_mfma_f32_16x16x32_bf16 v[58:61], v[164:167], v[188:191], v[58:61]
	v_mfma_f32_16x16x32_bf16 v[46:49], v[156:159], v[196:199], v[46:49]
	v_mfma_f32_16x16x32_bf16 v[42:45], v[164:167], v[196:199], v[42:45]
	v_mfma_f32_16x16x32_bf16 v[30:33], v[156:159], v[204:207], v[30:33]
	v_mfma_f32_16x16x32_bf16 v[26:29], v[164:167], v[204:207], v[26:29]
	v_mfma_f32_16x16x32_bf16 v[14:17], v[156:159], v[212:215], v[14:17]
	v_mfma_f32_16x16x32_bf16 v[10:13], v[164:167], v[212:215], v[10:13]
	v_mfma_f32_16x16x32_bf16 v[54:57], v[168:171], v[184:187], v[54:57]
	v_mfma_f32_16x16x32_bf16 v[50:53], v[176:179], v[184:187], v[50:53]
	v_mfma_f32_16x16x32_bf16 v[38:41], v[168:171], v[192:195], v[38:41]
	v_mfma_f32_16x16x32_bf16 v[34:37], v[176:179], v[192:195], v[34:37]
	v_mfma_f32_16x16x32_bf16 v[22:25], v[168:171], v[200:203], v[22:25]
	v_mfma_f32_16x16x32_bf16 v[18:21], v[176:179], v[200:203], v[18:21]
	v_mfma_f32_16x16x32_bf16 v[6:9], v[168:171], v[208:211], v[6:9]
	v_mfma_f32_16x16x32_bf16 v[2:5], v[176:179], v[208:211], v[2:5]
	v_mfma_f32_16x16x32_bf16 v[54:57], v[172:175], v[188:191], v[54:57]
	v_mfma_f32_16x16x32_bf16 v[50:53], v[180:183], v[188:191], v[50:53]
	v_mfma_f32_16x16x32_bf16 v[38:41], v[172:175], v[196:199], v[38:41]
	v_mfma_f32_16x16x32_bf16 v[34:37], v[180:183], v[196:199], v[34:37]
	v_mfma_f32_16x16x32_bf16 v[22:25], v[172:175], v[204:207], v[22:25]
	v_mfma_f32_16x16x32_bf16 v[18:21], v[180:183], v[204:207], v[18:21]
	v_mfma_f32_16x16x32_bf16 v[6:9], v[172:175], v[212:215], v[6:9]
	v_mfma_f32_16x16x32_bf16 v[2:5], v[180:183], v[212:215], v[2:5]
	s_barrier
	s_add_u32 s22, s22, 0x10000
	s_addc_u32 s23, s23, 0
	s_cmp_ge_u32 s57, s44
.LBB0_1229:
	ds_read_b128 v[152:155], v149
	ds_read_b128 v[156:159], v149 offset:1024
	ds_read_b128 v[160:163], v149 offset:2048
	ds_read_b128 v[164:167], v149 offset:3072
	ds_read_b128 v[168:171], v150
	ds_read_b128 v[172:175], v150 offset:1024
	ds_read_b128 v[176:179], v150 offset:2048
	ds_read_b128 v[180:183], v150 offset:3072
	ds_read_b128 v[184:187], v151
	ds_read_b128 v[188:191], v151 offset:1024
	ds_read_b128 v[192:195], v151 offset:2048
	ds_read_b128 v[196:199], v151 offset:3072
	ds_read_b128 v[200:203], v151 offset:4096
	ds_read_b128 v[204:207], v151 offset:5120
	ds_read_b128 v[208:211], v151 offset:6144
	ds_read_b128 v[212:215], v151 offset:7168
	s_add_u32 s24, s51, s22
	s_addc_u32 s25, s55, s23
	s_add_u32 s28, s24, 0x10000
	s_addc_u32 s29, s25, 0
	s_add_i32 s57, s57, 2
	s_add_u32 s26, s49, s22
	s_addc_u32 s27, s50, s23
	s_add_u32 s24, s24, 0x18000
	s_addc_u32 s25, s25, 0
	s_cmp_eq_u32 s56, s22
	s_cselect_b32 s25, s48, s25
	s_cselect_b32 s24, s47, s24
	s_cselect_b32 s27, s4, s27
	s_cselect_b32 s26, s5, s26
	s_cselect_b32 s29, s46, s29
	s_cselect_b32 s28, s19, s28
	v_lshl_add_u64 v[216:217], v[142:143], 0, s[22:23]
	s_add_i32 m0, s35, 0xc000
	s_nop 0
	global_load_lds_dwordx4 v[216:217], off
	v_lshl_add_u64 v[216:217], v[144:145], 0, s[22:23]
	s_add_i32 m0, s35, 0xe000
	s_nop 0
	global_load_lds_dwordx4 v[216:217], off
	s_waitcnt vmcnt(8) lgkmcnt(0)
	s_barrier
; #define PG8_STAGE(bufoff, gbase, voff) do { _Pragma("unroll") for (int _i = 0; _i < 2; ++_i) \
;         __builtin_amdgcn_global_load_lds((const unsigned*)((const char*)(gbase) + (voff)[_i]), (LAS unsigned*)(lds + (bufoff) + ldsw + _i * 8192), 16, 0, 0); } while (0)
; #define PG8_LDA(dst, b, h) do { _Pragma("unroll") for (int m = 0; m < 4; ++m) _Pragma("unroll") for (int k = 0; k < 2; ++k) dst[m][k] = *(const LAS bf16x8*)(lds + PG8_SA(b, h) + aoff + m * 2048 + k * 1024); } while (0)
; #define PG8_MMA(ai, bj, At, Bt) do { __builtin_amdgcn_s_setprio(1); _Pragma("unroll") for (int m = 0; m < 4; ++m) _Pragma("unroll") for (int n = 0; n < 2; ++n) _Pragma("unroll") for (int k = 0; k < 2; ++k) \
;         acc[ai][bj][m][n] = __builtin_amdgcn_mfma_f32_16x16x32_bf16(Bt[n][k], At[m][k], acc[ai][bj][m][n], 0, 0, 0); __builtin_amdgcn_s_setprio(0); } while (0)
; #define PG8_WAIT_V(n) asm volatile("s_waitcnt vmcnt(" #n ")" ::: "memory")
; #define PG8_WAIT_L(n) asm volatile("s_waitcnt lgkmcnt(" #n ")" ::: "memory")
; #define PG8_BAR __builtin_amdgcn_s_barrier()
; #define PG8_SCHED __builtin_amdgcn_sched_barrier(0)
; template <class Epi, class Sched, bool ABLK = false, bool ALIGN_EPI = true, bool SP2 = true, bool BBLK = true>
; __device__ __forceinline__ void gemm_phase(LAS unsigned char* lds, const Gemm g, const Sched& S, const Epi& E) {
;     ...
;             PG8_WAIT_V(8); PG8_WAIT_L(0); PG8_BAR; PG8_MMA(0, 0, At, B0); PG8_MMA(0, 1, At, B1); PG8_BAR; PG8_SCHED;
;             PG8_LDA(At, 0, 1); PG8_STAGE(PG8_SB(0, 0), b2, voffB); PG8_STAGE(PG8_SB(0, 1), b2 + hstepB, voffB); PG8_STAGE(PG8_SA(0, 0), a2, voffA);
;             PG8_WAIT_V(8); PG8_WAIT_L(0); PG8_BAR; PG8_MMA(1, 0, At, B0); PG8_MMA(1, 1, At, B1); PG8_BAR; PG8_SCHED;
	v_mfma_f32_16x16x32_bf16 v[126:129], v[152:155], v[184:187], v[126:129]
	v_mfma_f32_16x16x32_bf16 v[122:125], v[160:163], v[184:187], v[122:125]
	v_mfma_f32_16x16x32_bf16 v[110:113], v[152:155], v[192:195], v[110:113]
	v_mfma_f32_16x16x32_bf16 v[106:109], v[160:163], v[192:195], v[106:109]
	v_mfma_f32_16x16x32_bf16 v[94:97], v[152:155], v[200:203], v[94:97]
	v_mfma_f32_16x16x32_bf16 v[90:93], v[160:163], v[200:203], v[90:93]
	v_mfma_f32_16x16x32_bf16 v[78:81], v[152:155], v[208:211], v[78:81]
	v_mfma_f32_16x16x32_bf16 v[74:77], v[160:163], v[208:211], v[74:77]
	v_mfma_f32_16x16x32_bf16 v[126:129], v[156:159], v[188:191], v[126:129]
	v_mfma_f32_16x16x32_bf16 v[122:125], v[164:167], v[188:191], v[122:125]
	v_mfma_f32_16x16x32_bf16 v[110:113], v[156:159], v[196:199], v[110:113]
	v_mfma_f32_16x16x32_bf16 v[106:109], v[164:167], v[196:199], v[106:109]
	v_mfma_f32_16x16x32_bf16 v[94:97], v[156:159], v[204:207], v[94:97]
	v_mfma_f32_16x16x32_bf16 v[90:93], v[164:167], v[204:207], v[90:93]
	v_mfma_f32_16x16x32_bf16 v[78:81], v[156:159], v[212:215], v[78:81]
	v_mfma_f32_16x16x32_bf16 v[74:77], v[164:167], v[212:215], v[74:77]
	v_mfma_f32_16x16x32_bf16 v[118:121], v[168:171], v[184:187], v[118:121]
	v_mfma_f32_16x16x32_bf16 v[114:117], v[176:179], v[184:187], v[114:117]
	v_mfma_f32_16x16x32_bf16 v[102:105], v[168:171], v[192:195], v[102:105]
	v_mfma_f32_16x16x32_bf16 v[98:101], v[176:179], v[192:195], v[98:101]
	v_mfma_f32_16x16x32_bf16 v[86:89], v[168:171], v[200:203], v[86:89]
	v_mfma_f32_16x16x32_bf16 v[82:85], v[176:179], v[200:203], v[82:85]
	v_mfma_f32_16x16x32_bf16 v[70:73], v[168:171], v[208:211], v[70:73]
	v_mfma_f32_16x16x32_bf16 v[66:69], v[176:179], v[208:211], v[66:69]
	v_mfma_f32_16x16x32_bf16 v[118:121], v[172:175], v[188:191], v[118:121]
	v_mfma_f32_16x16x32_bf16 v[114:117], v[180:183], v[188:191], v[114:117]
	v_mfma_f32_16x16x32_bf16 v[102:105], v[172:175], v[196:199], v[102:105]
	v_mfma_f32_16x16x32_bf16 v[98:101], v[180:183], v[196:199], v[98:101]
	v_mfma_f32_16x16x32_bf16 v[86:89], v[172:175], v[204:207], v[86:89]
	v_mfma_f32_16x16x32_bf16 v[82:85], v[180:183], v[204:207], v[82:85]
	v_mfma_f32_16x16x32_bf16 v[70:73], v[172:175], v[212:215], v[70:73]
	v_mfma_f32_16x16x32_bf16 v[66:69], v[180:183], v[212:215], v[66:69]
	s_barrier
	ds_read_b128 v[184:187], v151 offset:16384
	ds_read_b128 v[188:191], v151 offset:17408
	ds_read_b128 v[192:195], v151 offset:18432
	ds_read_b128 v[196:199], v151 offset:19456
	ds_read_b128 v[200:203], v151 offset:20480
	ds_read_b128 v[204:207], v151 offset:21504
	ds_read_b128 v[208:211], v151 offset:22528
	ds_read_b128 v[212:215], v151 offset:23552
	s_add_i32 s59, s72, s34
	s_mov_b32 m0, s59
	s_nop 0
	global_load_lds_dwordx4 v130, s[26:27]
	s_add_i32 m0, s59, 0x2000
	s_add_u32 s64, s26, 0x4000
	s_addc_u32 s65, s27, 0
	s_add_i32 s59, s73, s34
	global_load_lds_dwordx4 v132, s[26:27]
	s_mov_b32 m0, s59
	s_nop 0
	global_load_lds_dwordx4 v130, s[64:65]
	s_add_i32 m0, s59, 0x2000
	s_nop 0
	global_load_lds_dwordx4 v132, s[64:65]
	s_mov_b32 m0, s35
	s_nop 0
	global_load_lds_dwordx4 v130, s[28:29]
	s_mov_b32 m0, s36
	s_nop 0
	global_load_lds_dwordx4 v132, s[28:29]
	s_waitcnt vmcnt(8) lgkmcnt(0)
	s_barrier
	v_mfma_f32_16x16x32_bf16 v[62:65], v[152:155], v[184:187], v[62:65]
	v_mfma_f32_16x16x32_bf16 v[58:61], v[160:163], v[184:187], v[58:61]
	v_mfma_f32_16x16x32_bf16 v[46:49], v[152:155], v[192:195], v[46:49]
	v_mfma_f32_16x16x32_bf16 v[42:45], v[160:163], v[192:195], v[42:45]
	v_mfma_f32_16x16x32_bf16 v[30:33], v[152:155], v[200:203], v[30:33]
	v_mfma_f32_16x16x32_bf16 v[26:29], v[160:163], v[200:203], v[26:29]
	v_mfma_f32_16x16x32_bf16 v[14:17], v[152:155], v[208:211], v[14:17]
	v_mfma_f32_16x16x32_bf16 v[10:13], v[160:163], v[208:211], v[10:13]
	v_mfma_f32_16x16x32_bf16 v[62:65], v[156:159], v[188:191], v[62:65]
	v_mfma_f32_16x16x32_bf16 v[58:61], v[164:167], v[188:191], v[58:61]
	v_mfma_f32_16x16x32_bf16 v[46:49], v[156:159], v[196:199], v[46:49]
	v_mfma_f32_16x16x32_bf16 v[42:45], v[164:167], v[196:199], v[42:45]
	v_mfma_f32_16x16x32_bf16 v[30:33], v[156:159], v[204:207], v[30:33]
	v_mfma_f32_16x16x32_bf16 v[26:29], v[164:167], v[204:207], v[26:29]
	v_mfma_f32_16x16x32_bf16 v[14:17], v[156:159], v[212:215], v[14:17]
	v_mfma_f32_16x16x32_bf16 v[10:13], v[164:167], v[212:215], v[10:13]
	v_mfma_f32_16x16x32_bf16 v[54:57], v[168:171], v[184:187], v[54:57]
	v_mfma_f32_16x16x32_bf16 v[50:53], v[176:179], v[184:187], v[50:53]
	v_mfma_f32_16x16x32_bf16 v[38:41], v[168:171], v[192:195], v[38:41]
	v_mfma_f32_16x16x32_bf16 v[34:37], v[176:179], v[192:195], v[34:37]
	v_mfma_f32_16x16x32_bf16 v[22:25], v[168:171], v[200:203], v[22:25]
	v_mfma_f32_16x16x32_bf16 v[18:21], v[176:179], v[200:203], v[18:21]
	v_mfma_f32_16x16x32_bf16 v[6:9], v[168:171], v[208:211], v[6:9]
	v_mfma_f32_16x16x32_bf16 v[2:5], v[176:179], v[208:211], v[2:5]
	v_mfma_f32_16x16x32_bf16 v[54:57], v[172:175], v[188:191], v[54:57]
	v_mfma_f32_16x16x32_bf16 v[50:53], v[180:183], v[188:191], v[50:53]
	v_mfma_f32_16x16x32_bf16 v[38:41], v[172:175], v[196:199], v[38:41]
	v_mfma_f32_16x16x32_bf16 v[34:37], v[180:183], v[196:199], v[34:37]
	v_mfma_f32_16x16x32_bf16 v[22:25], v[172:175], v[204:207], v[22:25]
	v_mfma_f32_16x16x32_bf16 v[18:21], v[180:183], v[204:207], v[18:21]
	v_mfma_f32_16x16x32_bf16 v[6:9], v[172:175], v[212:215], v[6:9]
	v_mfma_f32_16x16x32_bf16 v[2:5], v[180:183], v[212:215], v[2:5]
	s_barrier
; #define PG8_STAGE(bufoff, gbase, voff) do { _Pragma("unroll") for (int _i = 0; _i < 2; ++_i) \
;         __builtin_amdgcn_global_load_lds((const unsigned*)((const char*)(gbase) + (voff)[_i]), (LAS unsigned*)(lds + (bufoff) + ldsw + _i * 8192), 16, 0, 0); } while (0)
; #define PG8_LDA(dst, b, h) do { _Pragma("unroll") for (int m = 0; m < 4; ++m) _Pragma("unroll") for (int k = 0; k < 2; ++k) dst[m][k] = *(const LAS bf16x8*)(lds + PG8_SA(b, h) + aoff + m * 2048 + k * 1024); } while (0)
; #define PG8_LDB(dst, b, h) do { _Pragma("unroll") for (int n = 0; n < 2; ++n) _Pragma("unroll") for (int k = 0; k < 2; ++k) dst[n][k] = *(const LAS bf16x8*)(lds + PG8_SB(b, h) + boff + n * 2048 + k * 1024); } while (0)
; #define PG8_MMA(ai, bj, At, Bt) do { __builtin_amdgcn_s_setprio(1); _Pragma("unroll") for (int m = 0; m < 4; ++m) _Pragma("unroll") for (int n = 0; n < 2; ++n) _Pragma("unroll") for (int k = 0; k < 2; ++k) \
;         acc[ai][bj][m][n] = __builtin_amdgcn_mfma_f32_16x16x32_bf16(Bt[n][k], At[m][k], acc[ai][bj][m][n], 0, 0, 0); __builtin_amdgcn_s_setprio(0); } while (0)
; #define PG8_WAIT_V(n) asm volatile("s_waitcnt vmcnt(" #n ")" ::: "memory")
; #define PG8_WAIT_L(n) asm volatile("s_waitcnt lgkmcnt(" #n ")" ::: "memory")
; #define PG8_BAR __builtin_amdgcn_s_barrier()
; #define PG8_SCHED __builtin_amdgcn_sched_barrier(0)
; template <class Epi, class Sched, bool ABLK = false, bool ALIGN_EPI = true, bool SP2 = true, bool BBLK = true>
; __device__ __forceinline__ void gemm_phase(LAS unsigned char* lds, const Gemm g, const Sched& S, const Epi& E) {
;     ...
;             PG8_LDB(B0, 1, 0); PG8_LDB(B1, 1, 1); PG8_SCHED; PG8_LDA(At, 1, 0); PG8_STAGE(PG8_SA(0, 1), a2 + hstepA, voffA);
;             PG8_WAIT_V(8); PG8_WAIT_L(0); PG8_BAR; PG8_MMA(0, 0, At, B0); PG8_MMA(0, 1, At, B1); PG8_BAR; PG8_SCHED;
;             PG8_LDA(At, 1, 1); PG8_STAGE(PG8_SB(1, 0), b3, voffB); PG8_STAGE(PG8_SB(1, 1), b3 + hstepB, voffB); PG8_STAGE(PG8_SA(1, 0), a3, voffA);
;             PG8_WAIT_V(8); PG8_WAIT_L(0); PG8_BAR; PG8_MMA(1, 0, At, B0); PG8_MMA(1, 1, At, B1); PG8_BAR; PG8_SCHED;
;     ...
;         if constexpr (ALIGN_EPI) { if (wr == 0) PG8_BAR; }
	v_add_u32_e32 v164, s60, v147
	v_add_u32_e32 v180, s61, v147
	ds_read_b128 v[152:155], v164
	ds_read_b128 v[156:159], v164 offset:1024
	ds_read_b128 v[160:163], v164 offset:2048
	ds_read_b128 v[164:167], v164 offset:3072
	ds_read_b128 v[168:171], v180
	ds_read_b128 v[172:175], v180 offset:1024
	ds_read_b128 v[176:179], v180 offset:2048
	ds_read_b128 v[180:183], v180 offset:3072
	ds_read_b128 v[184:187], v151 offset:32768
	ds_read_b128 v[188:191], v151 offset:33792
	ds_read_b128 v[192:195], v151 offset:34816
	ds_read_b128 v[196:199], v151 offset:35840
	ds_read_b128 v[200:203], v151 offset:36864
	ds_read_b128 v[204:207], v151 offset:37888
	ds_read_b128 v[208:211], v151 offset:38912
	ds_read_b128 v[212:215], v151 offset:39936
	s_add_u32 s28, s28, 0x4000
	s_addc_u32 s29, s29, 0
	s_mov_b32 m0, s37
	s_nop 0
	global_load_lds_dwordx4 v130, s[28:29]
	s_mov_b32 m0, s40
	s_nop 0
	global_load_lds_dwordx4 v132, s[28:29]
	s_waitcnt vmcnt(8) lgkmcnt(0)
	s_barrier
	v_mfma_f32_16x16x32_bf16 v[126:129], v[152:155], v[184:187], v[126:129]
	v_mfma_f32_16x16x32_bf16 v[122:125], v[160:163], v[184:187], v[122:125]
	v_mfma_f32_16x16x32_bf16 v[110:113], v[152:155], v[192:195], v[110:113]
	v_mfma_f32_16x16x32_bf16 v[106:109], v[160:163], v[192:195], v[106:109]
	v_mfma_f32_16x16x32_bf16 v[94:97], v[152:155], v[200:203], v[94:97]
	v_mfma_f32_16x16x32_bf16 v[90:93], v[160:163], v[200:203], v[90:93]
	v_mfma_f32_16x16x32_bf16 v[78:81], v[152:155], v[208:211], v[78:81]
	v_mfma_f32_16x16x32_bf16 v[74:77], v[160:163], v[208:211], v[74:77]
	v_mfma_f32_16x16x32_bf16 v[126:129], v[156:159], v[188:191], v[126:129]
	v_mfma_f32_16x16x32_bf16 v[122:125], v[164:167], v[188:191], v[122:125]
	v_mfma_f32_16x16x32_bf16 v[110:113], v[156:159], v[196:199], v[110:113]
	v_mfma_f32_16x16x32_bf16 v[106:109], v[164:167], v[196:199], v[106:109]
	v_mfma_f32_16x16x32_bf16 v[94:97], v[156:159], v[204:207], v[94:97]
	v_mfma_f32_16x16x32_bf16 v[90:93], v[164:167], v[204:207], v[90:93]
	v_mfma_f32_16x16x32_bf16 v[78:81], v[156:159], v[212:215], v[78:81]
	v_mfma_f32_16x16x32_bf16 v[74:77], v[164:167], v[212:215], v[74:77]
	v_mfma_f32_16x16x32_bf16 v[118:121], v[168:171], v[184:187], v[118:121]
	v_mfma_f32_16x16x32_bf16 v[114:117], v[176:179], v[184:187], v[114:117]
	v_mfma_f32_16x16x32_bf16 v[102:105], v[168:171], v[192:195], v[102:105]
	v_mfma_f32_16x16x32_bf16 v[98:101], v[176:179], v[192:195], v[98:101]
	v_mfma_f32_16x16x32_bf16 v[86:89], v[168:171], v[200:203], v[86:89]
	v_mfma_f32_16x16x32_bf16 v[82:85], v[176:179], v[200:203], v[82:85]
	v_mfma_f32_16x16x32_bf16 v[70:73], v[168:171], v[208:211], v[70:73]
	v_mfma_f32_16x16x32_bf16 v[66:69], v[176:179], v[208:211], v[66:69]
	v_mfma_f32_16x16x32_bf16 v[118:121], v[172:175], v[188:191], v[118:121]
	v_mfma_f32_16x16x32_bf16 v[114:117], v[180:183], v[188:191], v[114:117]
	v_mfma_f32_16x16x32_bf16 v[102:105], v[172:175], v[196:199], v[102:105]
	v_mfma_f32_16x16x32_bf16 v[98:101], v[180:183], v[196:199], v[98:101]
	v_mfma_f32_16x16x32_bf16 v[86:89], v[172:175], v[204:207], v[86:89]
	v_mfma_f32_16x16x32_bf16 v[82:85], v[180:183], v[204:207], v[82:85]
	v_mfma_f32_16x16x32_bf16 v[70:73], v[172:175], v[212:215], v[70:73]
	v_mfma_f32_16x16x32_bf16 v[66:69], v[180:183], v[212:215], v[66:69]
	s_barrier
	ds_read_b128 v[184:187], v151 offset:49152
	ds_read_b128 v[188:191], v151 offset:50176
	ds_read_b128 v[192:195], v151 offset:51200
	ds_read_b128 v[196:199], v151 offset:52224
	ds_read_b128 v[200:203], v151 offset:53248
	ds_read_b128 v[204:207], v151 offset:54272
	ds_read_b128 v[208:211], v151 offset:55296
	ds_read_b128 v[212:215], v151 offset:56320
	s_add_u32 s28, s26, 0x8000
	s_addc_u32 s29, s27, 0
	s_add_i32 s59, s60, s34
	s_mov_b32 m0, s59
	s_nop 0
	global_load_lds_dwordx4 v130, s[28:29]
	s_add_i32 m0, s59, 0x2000
	s_add_u32 s26, s26, 0xc000
	v_lshl_add_u64 v[216:217], s[28:29], 0, v[132:133]
	s_addc_u32 s27, s27, 0
	s_add_i32 s28, s61, s34
	global_load_lds_dwordx4 v[216:217], off
	s_mov_b32 m0, s28
	s_nop 0
	global_load_lds_dwordx4 v130, s[26:27]
	s_add_i32 m0, s28, 0x2000
	s_nop 0
	global_load_lds_dwordx4 v132, s[26:27]
	s_mov_b32 m0, s41
	s_nop 0
	global_load_lds_dwordx4 v130, s[24:25]
	s_mov_b32 m0, s42
	s_nop 0
	global_load_lds_dwordx4 v132, s[24:25]
	s_waitcnt vmcnt(8) lgkmcnt(0)
	s_barrier
	v_mfma_f32_16x16x32_bf16 v[62:65], v[152:155], v[184:187], v[62:65]
	v_mfma_f32_16x16x32_bf16 v[58:61], v[160:163], v[184:187], v[58:61]
	v_mfma_f32_16x16x32_bf16 v[46:49], v[152:155], v[192:195], v[46:49]
	v_mfma_f32_16x16x32_bf16 v[42:45], v[160:163], v[192:195], v[42:45]
	v_mfma_f32_16x16x32_bf16 v[30:33], v[152:155], v[200:203], v[30:33]
	v_mfma_f32_16x16x32_bf16 v[26:29], v[160:163], v[200:203], v[26:29]
	v_mfma_f32_16x16x32_bf16 v[14:17], v[152:155], v[208:211], v[14:17]
	v_mfma_f32_16x16x32_bf16 v[10:13], v[160:163], v[208:211], v[10:13]
	v_mfma_f32_16x16x32_bf16 v[62:65], v[156:159], v[188:191], v[62:65]
	v_mfma_f32_16x16x32_bf16 v[58:61], v[164:167], v[188:191], v[58:61]
	v_mfma_f32_16x16x32_bf16 v[46:49], v[156:159], v[196:199], v[46:49]
	v_mfma_f32_16x16x32_bf16 v[42:45], v[164:167], v[196:199], v[42:45]
	v_mfma_f32_16x16x32_bf16 v[30:33], v[156:159], v[204:207], v[30:33]
	v_mfma_f32_16x16x32_bf16 v[26:29], v[164:167], v[204:207], v[26:29]
	v_mfma_f32_16x16x32_bf16 v[14:17], v[156:159], v[212:215], v[14:17]
	v_mfma_f32_16x16x32_bf16 v[10:13], v[164:167], v[212:215], v[10:13]
	v_mfma_f32_16x16x32_bf16 v[54:57], v[168:171], v[184:187], v[54:57]
	v_mfma_f32_16x16x32_bf16 v[50:53], v[176:179], v[184:187], v[50:53]
	v_mfma_f32_16x16x32_bf16 v[38:41], v[168:171], v[192:195], v[38:41]
	v_mfma_f32_16x16x32_bf16 v[34:37], v[176:179], v[192:195], v[34:37]
	v_mfma_f32_16x16x32_bf16 v[22:25], v[168:171], v[200:203], v[22:25]
	v_mfma_f32_16x16x32_bf16 v[18:21], v[176:179], v[200:203], v[18:21]
	v_mfma_f32_16x16x32_bf16 v[6:9], v[168:171], v[208:211], v[6:9]
	v_mfma_f32_16x16x32_bf16 v[2:5], v[176:179], v[208:211], v[2:5]
	v_mfma_f32_16x16x32_bf16 v[54:57], v[172:175], v[188:191], v[54:57]
	v_mfma_f32_16x16x32_bf16 v[50:53], v[180:183], v[188:191], v[50:53]
	v_mfma_f32_16x16x32_bf16 v[38:41], v[172:175], v[196:199], v[38:41]
	v_mfma_f32_16x16x32_bf16 v[34:37], v[180:183], v[196:199], v[34:37]
	v_mfma_f32_16x16x32_bf16 v[22:25], v[172:175], v[204:207], v[22:25]
	v_mfma_f32_16x16x32_bf16 v[18:21], v[180:183], v[204:207], v[18:21]
	v_mfma_f32_16x16x32_bf16 v[6:9], v[172:175], v[212:215], v[6:9]
	v_mfma_f32_16x16x32_bf16 v[2:5], v[180:183], v[212:215], v[2:5]
	s_barrier
	s_add_u32 s22, s22, 0x10000
	s_addc_u32 s23, s23, 0
	s_cmp_ge_u32 s57, s44
	s_cbranch_scc0 .LBB0_1229
	s_and_b64 vcc, exec, s[6:7]
	s_cbranch_vccz .LBB0_1232
	s_barrier

; #define PG8_STAGE(bufoff, gbase, voff) do { _Pragma("unroll") for (int _i = 0; _i < 2; ++_i) \
;         __builtin_amdgcn_global_load_lds((const unsigned*)((const char*)(gbase) + (voff)[_i]), (LAS unsigned*)(lds + (bufoff) + ldsw + _i * 8192), 16, 0, 0); } while (0)
; #define PG8_LDA(dst, b, h) do { _Pragma("unroll") for (int m = 0; m < 4; ++m) _Pragma("unroll") for (int k = 0; k < 2; ++k) dst[m][k] = *(const LAS bf16x8*)(lds + PG8_SA(b, h) + aoff + m * 2048 + k * 1024); } while (0)
; #define PG8_LDB(dst, b, h) do { _Pragma("unroll") for (int n = 0; n < 2; ++n) _Pragma("unroll") for (int k = 0; k < 2; ++k) dst[n][k] = *(const LAS bf16x8*)(lds + PG8_SB(b, h) + boff + n * 2048 + k * 1024); } while (0)
; #define PG8_WAIT_V(n) asm volatile("s_waitcnt vmcnt(" #n ")" ::: "memory")
; #define PG8_WAIT_L(n) asm volatile("s_waitcnt lgkmcnt(" #n ")" ::: "memory")
; #define PG8_BAR __builtin_amdgcn_s_barrier()
; #define PG8_SCHED __builtin_amdgcn_sched_barrier(0)
; template <class Epi, class Sched, bool ABLK = false, bool ALIGN_EPI = true, bool SP2 = true, bool BBLK = true>
; __device__ __forceinline__ void gemm_phase(LAS unsigned char* lds, const Gemm g, const Sched& S, const Epi& E) {
;     ...
;         const bool has_next = S.next(ui + 1, nxt);
;         const int nt = cur.nt;
;         const char* nuA = has_next ? a_unit(nxt) : uA; const int ntbA = has_next ? nxt.k0 / BK : tbA; const char* nB = has_next ? (const char*)g.Bt + (size_t)nxt.pn * tstepB + b_k0(nxt.k0) : cB;
;         for (int t = 0; t < nt; t += 2) {
;             const bool last = (t == nt - 2);
;             const char* a1 = a_tile(uA, tbA + t + 1);
;             const char* a2 = last ? a_tile(nuA, ntbA) : a_tile(uA, tbA + t + 2); const char* b2 = last ? nB : cB + (size_t)(t + 2) * kstepB;
;             const char* a3 = last ? a_tile(nuA, ntbA + 1) : a_tile(uA, tbA + t + 3); const char* b3 = b2 + kstepB;
;             if (last && has_next) S.a_ready(nxt);
;             if constexpr (SP2) {
;             PG8_LDB(B0, 0, 0); PG8_LDB(B1, 0, 1); PG8_SCHED; PG8_LDA(At, 0, 0); PG8_STAGE(PG8_SA(1, 1), a1 + hstepA, voffA);
;             PG8_WAIT_V(8); PG8_WAIT_L(0); PG8_BAR; PG8_MMA(0, 0, At, B0); PG8_MMA(0, 1, At, B1); PG8_BAR; PG8_SCHED;
;             PG8_LDA(At, 0, 1); PG8_STAGE(PG8_SB(0, 0), b2, voffB); PG8_STAGE(PG8_SB(0, 1), b2 + hstepB, voffB); PG8_STAGE(PG8_SA(0, 0), a2, voffA);
.LBB0_1354:
	ds_read_b128 v[152:155], v163
	ds_read_b128 v[156:159], v163 offset:1024
	ds_read_b128 v[166:169], v163 offset:2048
	ds_read_b128 v[170:173], v163 offset:3072
	ds_read_b128 v[174:177], v164
	ds_read_b128 v[178:181], v164 offset:1024
	ds_read_b128 v[182:185], v164 offset:2048
	ds_read_b128 v[186:189], v164 offset:3072
	ds_read_b128 v[190:193], v165
	ds_read_b128 v[194:197], v165 offset:1024
	ds_read_b128 v[198:201], v165 offset:2048
	ds_read_b128 v[202:205], v165 offset:3072
	ds_read_b128 v[206:209], v165 offset:4096
	ds_read_b128 v[210:213], v165 offset:5120
	ds_read_b128 v[214:217], v165 offset:6144
	ds_read_b128 v[218:221], v165 offset:7168
	s_ashr_i32 s21, s20, 31
	s_lshl_b64 s[4:5], s[20:21], 20
	s_add_u32 s24, s76, s4
	s_addc_u32 s25, s33, s5
	s_and_b64 s[4:5], s[26:27], exec
	s_cselect_b32 s4, s25, s37
	s_cselect_b32 s5, s24, s36
	s_ashr_i32 s23, s22, 31
	s_lshl_b64 s[28:29], s[22:23], 20
	s_add_u32 s28, s1, s28
	s_addc_u32 s29, s48, s29
	s_and_b64 s[42:43], s[26:27], exec
	s_cselect_b32 s21, s29, s41
	s_cselect_b32 s23, s28, s40
	s_add_u32 s56, s5, 0x80
	s_addc_u32 s57, s4, 0
	s_add_u32 s59, s40, 0x10000
	v_mov_b32_e32 v2, 0
	s_addc_u32 s64, s41, 0
	v_lshl_add_u64 v[148:149], s[36:37], 0, v[144:145]
	v_lshl_add_u64 v[150:151], s[36:37], 0, v[146:147]
	s_mov_b32 s65, -2
	s_mov_b64 s[40:41], 0
	s_add_u32 s42, s36, s40
	s_addc_u32 s43, s37, s41
	s_add_u32 s46, s42, 0x100
	s_addc_u32 s47, s43, 0
	s_add_u32 s42, s42, 0x180
	s_addc_u32 s43, s43, 0
	s_cmpk_eq_i32 s40, 0xf00
	s_cselect_b32 s43, s57, s43
	s_cselect_b32 s42, s56, s42
	s_cselect_b32 s45, s21, s64
	s_cselect_b32 s44, s23, s59
	s_cselect_b32 s47, s4, s47
	s_cselect_b32 s46, s5, s46
	v_lshl_add_u64 v[222:223], v[148:149], 0, s[40:41]
	s_add_i32 m0, s31, 0xc000
	s_nop 0
	global_load_lds_dwordx4 v[222:223], off
	v_lshl_add_u64 v[222:223], v[150:151], 0, s[40:41]
	s_add_i32 m0, s31, 0xe000
	s_nop 0
	global_load_lds_dwordx4 v[222:223], off
	s_waitcnt vmcnt(8) lgkmcnt(0)
	s_barrier
	v_mfma_f32_16x16x32_bf16 v[126:129], v[152:155], v[190:193], 0
	v_mfma_f32_16x16x32_bf16 v[122:125], v[166:169], v[190:193], 0
	v_mfma_f32_16x16x32_bf16 v[110:113], v[152:155], v[198:201], 0
	v_mfma_f32_16x16x32_bf16 v[106:109], v[166:169], v[198:201], 0
	v_mfma_f32_16x16x32_bf16 v[94:97], v[152:155], v[206:209], 0
	v_mfma_f32_16x16x32_bf16 v[90:93], v[166:169], v[206:209], 0
	v_mfma_f32_16x16x32_bf16 v[78:81], v[152:155], v[214:217], 0
	v_mfma_f32_16x16x32_bf16 v[74:77], v[166:169], v[214:217], 0
	v_mfma_f32_16x16x32_bf16 v[126:129], v[156:159], v[194:197], v[126:129]
	v_mfma_f32_16x16x32_bf16 v[122:125], v[170:173], v[194:197], v[122:125]
	v_mfma_f32_16x16x32_bf16 v[110:113], v[156:159], v[202:205], v[110:113]
	v_mfma_f32_16x16x32_bf16 v[106:109], v[170:173], v[202:205], v[106:109]
	v_mfma_f32_16x16x32_bf16 v[94:97], v[156:159], v[210:213], v[94:97]
	v_mfma_f32_16x16x32_bf16 v[90:93], v[170:173], v[210:213], v[90:93]
	v_mfma_f32_16x16x32_bf16 v[78:81], v[156:159], v[218:221], v[78:81]
	v_mfma_f32_16x16x32_bf16 v[74:77], v[170:173], v[218:221], v[74:77]
	v_mfma_f32_16x16x32_bf16 v[118:121], v[174:177], v[190:193], 0
	v_mfma_f32_16x16x32_bf16 v[114:117], v[182:185], v[190:193], 0
	v_mfma_f32_16x16x32_bf16 v[102:105], v[174:177], v[198:201], 0
	v_mfma_f32_16x16x32_bf16 v[98:101], v[182:185], v[198:201], 0
	v_mfma_f32_16x16x32_bf16 v[86:89], v[174:177], v[206:209], 0
	v_mfma_f32_16x16x32_bf16 v[82:85], v[182:185], v[206:209], 0
	v_mfma_f32_16x16x32_bf16 v[70:73], v[174:177], v[214:217], 0
	v_mfma_f32_16x16x32_bf16 v[66:69], v[182:185], v[214:217], 0
	v_mfma_f32_16x16x32_bf16 v[118:121], v[178:181], v[194:197], v[118:121]
	v_mfma_f32_16x16x32_bf16 v[114:117], v[186:189], v[194:197], v[114:117]
	v_mfma_f32_16x16x32_bf16 v[102:105], v[178:181], v[202:205], v[102:105]
	v_mfma_f32_16x16x32_bf16 v[98:101], v[186:189], v[202:205], v[98:101]
	v_mfma_f32_16x16x32_bf16 v[86:89], v[178:181], v[210:213], v[86:89]
	v_mfma_f32_16x16x32_bf16 v[82:85], v[186:189], v[210:213], v[82:85]
	v_mfma_f32_16x16x32_bf16 v[70:73], v[178:181], v[218:221], v[70:73]
	v_mfma_f32_16x16x32_bf16 v[66:69], v[186:189], v[218:221], v[66:69]
	s_barrier
	ds_read_b128 v[190:193], v165 offset:16384
	ds_read_b128 v[194:197], v165 offset:17408
	ds_read_b128 v[198:201], v165 offset:18432
	ds_read_b128 v[202:205], v165 offset:19456
	ds_read_b128 v[206:209], v165 offset:20480
	ds_read_b128 v[210:213], v165 offset:21504
	ds_read_b128 v[214:217], v165 offset:22528
	ds_read_b128 v[218:221], v165 offset:23552
	s_add_i32 s66, s72, s49
	s_mov_b32 m0, s66
	s_nop 0
	global_load_lds_dwordx4 v134, s[44:45]
	s_add_i32 m0, s66, 0x2000
	s_add_u32 s66, s44, 0x4000
	s_addc_u32 s67, s45, 0
	s_add_i32 s75, s73, s49
	global_load_lds_dwordx4 v130, s[44:45]
	s_mov_b32 m0, s75
	s_nop 0
	global_load_lds_dwordx4 v134, s[66:67]
	s_add_i32 m0, s75, 0x2000
	s_nop 0
	global_load_lds_dwordx4 v130, s[66:67]
	s_mov_b32 m0, s31
	s_nop 0
	global_load_lds_dwordx4 v136, s[46:47]
	s_mov_b32 m0, s35
	s_nop 0
	global_load_lds_dwordx4 v132, s[46:47]
	s_waitcnt vmcnt(8) lgkmcnt(0)
	s_barrier
; #define PG8_STAGE(bufoff, gbase, voff) do { _Pragma("unroll") for (int _i = 0; _i < 2; ++_i) \
;         __builtin_amdgcn_global_load_lds((const unsigned*)((const char*)(gbase) + (voff)[_i]), (LAS unsigned*)(lds + (bufoff) + ldsw + _i * 8192), 16, 0, 0); } while (0)
; #define PG8_LDA(dst, b, h) do { _Pragma("unroll") for (int m = 0; m < 4; ++m) _Pragma("unroll") for (int k = 0; k < 2; ++k) dst[m][k] = *(const LAS bf16x8*)(lds + PG8_SA(b, h) + aoff + m * 2048 + k * 1024); } while (0)
; #define PG8_LDB(dst, b, h) do { _Pragma("unroll") for (int n = 0; n < 2; ++n) _Pragma("unroll") for (int k = 0; k < 2; ++k) dst[n][k] = *(const LAS bf16x8*)(lds + PG8_SB(b, h) + boff + n * 2048 + k * 1024); } while (0)
; #define PG8_MMA(ai, bj, At, Bt) do { __builtin_amdgcn_s_setprio(1); _Pragma("unroll") for (int m = 0; m < 4; ++m) _Pragma("unroll") for (int n = 0; n < 2; ++n) _Pragma("unroll") for (int k = 0; k < 2; ++k) \
;         acc[ai][bj][m][n] = __builtin_amdgcn_mfma_f32_16x16x32_bf16(Bt[n][k], At[m][k], acc[ai][bj][m][n], 0, 0, 0); __builtin_amdgcn_s_setprio(0); } while (0)
; #define PG8_WAIT_V(n) asm volatile("s_waitcnt vmcnt(" #n ")" ::: "memory")
; #define PG8_WAIT_L(n) asm volatile("s_waitcnt lgkmcnt(" #n ")" ::: "memory")
; #define PG8_BAR __builtin_amdgcn_s_barrier()
; #define PG8_SCHED __builtin_amdgcn_sched_barrier(0)
; template <class Epi, class Sched, bool ABLK = false, bool ALIGN_EPI = true, bool SP2 = true, bool BBLK = true>
; __device__ __forceinline__ void gemm_phase(LAS unsigned char* lds, const Gemm g, const Sched& S, const Epi& E) {
;     ...
;             PG8_WAIT_V(8); PG8_WAIT_L(0); PG8_BAR; PG8_MMA(1, 0, At, B0); PG8_MMA(1, 1, At, B1); PG8_BAR; PG8_SCHED;
;             PG8_LDB(B0, 1, 0); PG8_LDB(B1, 1, 1); PG8_SCHED; PG8_LDA(At, 1, 0); PG8_STAGE(PG8_SA(0, 1), a2 + hstepA, voffA);
;             PG8_WAIT_V(8); PG8_WAIT_L(0); PG8_BAR; PG8_MMA(0, 0, At, B0); PG8_MMA(0, 1, At, B1); PG8_BAR; PG8_SCHED;
	v_mfma_f32_16x16x32_bf16 v[62:65], v[152:155], v[190:193], 0
	v_mfma_f32_16x16x32_bf16 v[58:61], v[166:169], v[190:193], 0
	v_mfma_f32_16x16x32_bf16 v[46:49], v[152:155], v[198:201], 0
	v_mfma_f32_16x16x32_bf16 v[42:45], v[166:169], v[198:201], 0
	v_mfma_f32_16x16x32_bf16 v[30:33], v[152:155], v[206:209], 0
	v_mfma_f32_16x16x32_bf16 v[26:29], v[166:169], v[206:209], 0
	v_mfma_f32_16x16x32_bf16 v[14:17], v[152:155], v[214:217], 0
	v_mfma_f32_16x16x32_bf16 v[10:13], v[166:169], v[214:217], 0
	v_mfma_f32_16x16x32_bf16 v[62:65], v[156:159], v[194:197], v[62:65]
	v_mfma_f32_16x16x32_bf16 v[58:61], v[170:173], v[194:197], v[58:61]
	v_mfma_f32_16x16x32_bf16 v[46:49], v[156:159], v[202:205], v[46:49]
	v_mfma_f32_16x16x32_bf16 v[42:45], v[170:173], v[202:205], v[42:45]
	v_mfma_f32_16x16x32_bf16 v[30:33], v[156:159], v[210:213], v[30:33]
	v_mfma_f32_16x16x32_bf16 v[26:29], v[170:173], v[210:213], v[26:29]
	v_mfma_f32_16x16x32_bf16 v[14:17], v[156:159], v[218:221], v[14:17]
	v_mfma_f32_16x16x32_bf16 v[10:13], v[170:173], v[218:221], v[10:13]
	v_mfma_f32_16x16x32_bf16 v[54:57], v[174:177], v[190:193], 0
	v_mfma_f32_16x16x32_bf16 v[50:53], v[182:185], v[190:193], 0
	v_mfma_f32_16x16x32_bf16 v[38:41], v[174:177], v[198:201], 0
	v_mfma_f32_16x16x32_bf16 v[34:37], v[182:185], v[198:201], 0
	v_mfma_f32_16x16x32_bf16 v[22:25], v[174:177], v[206:209], 0
	v_mfma_f32_16x16x32_bf16 v[18:21], v[182:185], v[206:209], 0
	v_mfma_f32_16x16x32_bf16 v[6:9], v[174:177], v[214:217], 0
	v_mfma_f32_16x16x32_bf16 v[2:5], v[182:185], v[214:217], 0
	v_mfma_f32_16x16x32_bf16 v[54:57], v[178:181], v[194:197], v[54:57]
	v_mfma_f32_16x16x32_bf16 v[50:53], v[186:189], v[194:197], v[50:53]
	v_mfma_f32_16x16x32_bf16 v[38:41], v[178:181], v[202:205], v[38:41]
	v_mfma_f32_16x16x32_bf16 v[34:37], v[186:189], v[202:205], v[34:37]
	v_mfma_f32_16x16x32_bf16 v[22:25], v[178:181], v[210:213], v[22:25]
	v_mfma_f32_16x16x32_bf16 v[18:21], v[186:189], v[210:213], v[18:21]
	v_mfma_f32_16x16x32_bf16 v[6:9], v[178:181], v[218:221], v[6:9]
	v_mfma_f32_16x16x32_bf16 v[2:5], v[186:189], v[218:221], v[2:5]
	s_barrier
	v_add_u32_e32 v138, s60, v161
	ds_read_b128 v[152:155], v138
	ds_read_b128 v[156:159], v138 offset:1024
	ds_read_b128 v[166:169], v138 offset:2048
	ds_read_b128 v[170:173], v138 offset:3072
	v_add_u32_e32 v138, s61, v161
	ds_read_b128 v[174:177], v138
	ds_read_b128 v[178:181], v138 offset:1024
	ds_read_b128 v[182:185], v138 offset:2048
	ds_read_b128 v[186:189], v138 offset:3072
	ds_read_b128 v[190:193], v165 offset:32768
	ds_read_b128 v[194:197], v165 offset:33792
	ds_read_b128 v[198:201], v165 offset:34816
	ds_read_b128 v[202:205], v165 offset:35840
	ds_read_b128 v[206:209], v165 offset:36864
	ds_read_b128 v[210:213], v165 offset:37888
	ds_read_b128 v[214:217], v165 offset:38912
	ds_read_b128 v[218:221], v165 offset:39936
	s_add_u32 s46, s46, 0x80000
	s_addc_u32 s47, s47, 0
	s_mov_b32 m0, s50
	s_nop 0
	global_load_lds_dwordx4 v136, s[46:47]
	s_mov_b32 m0, s51
	s_nop 0
	global_load_lds_dwordx4 v132, s[46:47]
	s_waitcnt vmcnt(8) lgkmcnt(0)
	s_barrier
	v_mfma_f32_16x16x32_bf16 v[126:129], v[152:155], v[190:193], v[126:129]
	v_mfma_f32_16x16x32_bf16 v[122:125], v[166:169], v[190:193], v[122:125]
	v_mfma_f32_16x16x32_bf16 v[110:113], v[152:155], v[198:201], v[110:113]
	v_mfma_f32_16x16x32_bf16 v[106:109], v[166:169], v[198:201], v[106:109]
	v_mfma_f32_16x16x32_bf16 v[94:97], v[152:155], v[206:209], v[94:97]
	v_mfma_f32_16x16x32_bf16 v[90:93], v[166:169], v[206:209], v[90:93]
	v_mfma_f32_16x16x32_bf16 v[78:81], v[152:155], v[214:217], v[78:81]
	v_mfma_f32_16x16x32_bf16 v[74:77], v[166:169], v[214:217], v[74:77]
	v_mfma_f32_16x16x32_bf16 v[126:129], v[156:159], v[194:197], v[126:129]
	v_mfma_f32_16x16x32_bf16 v[122:125], v[170:173], v[194:197], v[122:125]
	v_mfma_f32_16x16x32_bf16 v[110:113], v[156:159], v[202:205], v[110:113]
	v_mfma_f32_16x16x32_bf16 v[106:109], v[170:173], v[202:205], v[106:109]
	v_mfma_f32_16x16x32_bf16 v[94:97], v[156:159], v[210:213], v[94:97]
	v_mfma_f32_16x16x32_bf16 v[90:93], v[170:173], v[210:213], v[90:93]
	v_mfma_f32_16x16x32_bf16 v[78:81], v[156:159], v[218:221], v[78:81]
	v_mfma_f32_16x16x32_bf16 v[74:77], v[170:173], v[218:221], v[74:77]
	v_mfma_f32_16x16x32_bf16 v[118:121], v[174:177], v[190:193], v[118:121]
	v_mfma_f32_16x16x32_bf16 v[114:117], v[182:185], v[190:193], v[114:117]
	v_mfma_f32_16x16x32_bf16 v[102:105], v[174:177], v[198:201], v[102:105]
	v_mfma_f32_16x16x32_bf16 v[98:101], v[182:185], v[198:201], v[98:101]
	v_mfma_f32_16x16x32_bf16 v[86:89], v[174:177], v[206:209], v[86:89]
	v_mfma_f32_16x16x32_bf16 v[82:85], v[182:185], v[206:209], v[82:85]
	v_mfma_f32_16x16x32_bf16 v[70:73], v[174:177], v[214:217], v[70:73]
	v_mfma_f32_16x16x32_bf16 v[66:69], v[182:185], v[214:217], v[66:69]
	v_mfma_f32_16x16x32_bf16 v[118:121], v[178:181], v[194:197], v[118:121]
	v_mfma_f32_16x16x32_bf16 v[114:117], v[186:189], v[194:197], v[114:117]
	v_mfma_f32_16x16x32_bf16 v[102:105], v[178:181], v[202:205], v[102:105]
	v_mfma_f32_16x16x32_bf16 v[98:101], v[186:189], v[202:205], v[98:101]
	v_mfma_f32_16x16x32_bf16 v[86:89], v[178:181], v[210:213], v[86:89]
	v_mfma_f32_16x16x32_bf16 v[82:85], v[186:189], v[210:213], v[82:85]
	v_mfma_f32_16x16x32_bf16 v[70:73], v[178:181], v[218:221], v[70:73]
	v_mfma_f32_16x16x32_bf16 v[66:69], v[186:189], v[218:221], v[66:69]
	s_barrier
; #define PG8_STAGE(bufoff, gbase, voff) do { _Pragma("unroll") for (int _i = 0; _i < 2; ++_i) \
;         __builtin_amdgcn_global_load_lds((const unsigned*)((const char*)(gbase) + (voff)[_i]), (LAS unsigned*)(lds + (bufoff) + ldsw + _i * 8192), 16, 0, 0); } while (0)
; #define PG8_LDA(dst, b, h) do { _Pragma("unroll") for (int m = 0; m < 4; ++m) _Pragma("unroll") for (int k = 0; k < 2; ++k) dst[m][k] = *(const LAS bf16x8*)(lds + PG8_SA(b, h) + aoff + m * 2048 + k * 1024); } while (0)
; #define PG8_WAIT_V(n) asm volatile("s_waitcnt vmcnt(" #n ")" ::: "memory")
; #define PG8_WAIT_L(n) asm volatile("s_waitcnt lgkmcnt(" #n ")" ::: "memory")
; template <class Epi, class Sched, bool ABLK = false, bool ALIGN_EPI = true, bool SP2 = true, bool BBLK = true>
; __device__ __forceinline__ void gemm_phase(LAS unsigned char* lds, const Gemm g, const Sched& S, const Epi& E) {
;     ...
;         for (int t = 0; t < nt; t += 2) {
;             const bool last = (t == nt - 2);
;             const char* a1 = a_tile(uA, tbA + t + 1);
;             const char* a2 = last ? a_tile(nuA, ntbA) : a_tile(uA, tbA + t + 2); const char* b2 = last ? nB : cB + (size_t)(t + 2) * kstepB;
;             const char* a3 = last ? a_tile(nuA, ntbA + 1) : a_tile(uA, tbA + t + 3); const char* b3 = b2 + kstepB;
;             if (last && has_next) S.a_ready(nxt);
;             if constexpr (SP2) {
;             PG8_LDB(B0, 0, 0); PG8_LDB(B1, 0, 1); PG8_SCHED; PG8_LDA(At, 0, 0); PG8_STAGE(PG8_SA(1, 1), a1 + hstepA, voffA);
;             PG8_WAIT_V(8); PG8_WAIT_L(0); PG8_BAR; PG8_MMA(0, 0, At, B0); PG8_MMA(0, 1, At, B1); PG8_BAR; PG8_SCHED;
;             PG8_LDA(At, 0, 1); PG8_STAGE(PG8_SB(0, 0), b2, voffB); PG8_STAGE(PG8_SB(0, 1), b2 + hstepB, voffB); PG8_STAGE(PG8_SA(0, 0), a2, voffA);
;             PG8_WAIT_V(8); PG8_WAIT_L(0); PG8_BAR; PG8_MMA(1, 0, At, B0); PG8_MMA(1, 1, At, B1); PG8_BAR; PG8_SCHED;
;             PG8_LDB(B0, 1, 0); PG8_LDB(B1, 1, 1); PG8_SCHED; PG8_LDA(At, 1, 0); PG8_STAGE(PG8_SA(0, 1), a2 + hstepA, voffA);
;             PG8_WAIT_V(8); PG8_WAIT_L(0); PG8_BAR; PG8_MMA(0, 0, At, B0); PG8_MMA(0, 1, At, B1); PG8_BAR; PG8_SCHED;
;             PG8_LDA(At, 1, 1); PG8_STAGE(PG8_SB(1, 0), b3, voffB); PG8_STAGE(PG8_SB(1, 1), b3 + hstepB, voffB); PG8_STAGE(PG8_SA(1, 0), a3, voffA);
;             PG8_WAIT_V(8); PG8_WAIT_L(0); PG8_BAR; PG8_MMA(1, 0, At, B0); PG8_MMA(1, 1, At, B1); PG8_BAR; PG8_SCHED;
	ds_read_b128 v[190:193], v165 offset:49152
	ds_read_b128 v[194:197], v165 offset:50176
	ds_read_b128 v[198:201], v165 offset:51200
	ds_read_b128 v[202:205], v165 offset:52224
	ds_read_b128 v[206:209], v165 offset:53248
	ds_read_b128 v[210:213], v165 offset:54272
	ds_read_b128 v[214:217], v165 offset:55296
	ds_read_b128 v[218:221], v165 offset:56320
	s_add_u32 s46, s44, 0x8000
	s_addc_u32 s47, s45, 0
	s_add_i32 s66, s60, s49
	s_mov_b32 m0, s66
	s_nop 0
	global_load_lds_dwordx4 v134, s[46:47]
	s_add_i32 m0, s66, 0x2000
	s_add_u32 s44, s44, 0xc000
	v_lshl_add_u64 v[222:223], s[46:47], 0, v[130:131]
	s_addc_u32 s45, s45, 0
	s_add_i32 s46, s61, s49
	global_load_lds_dwordx4 v[222:223], off
	s_mov_b32 m0, s46
	s_nop 0
	global_load_lds_dwordx4 v134, s[44:45]
	s_add_i32 m0, s46, 0x2000
	s_nop 0
	global_load_lds_dwordx4 v130, s[44:45]
	s_mov_b32 m0, s54
	s_nop 0
	global_load_lds_dwordx4 v136, s[42:43]
	s_mov_b32 m0, s55
	s_nop 0
	global_load_lds_dwordx4 v132, s[42:43]
	s_waitcnt vmcnt(8) lgkmcnt(0)
	s_barrier
	v_mfma_f32_16x16x32_bf16 v[62:65], v[152:155], v[190:193], v[62:65]
	v_mfma_f32_16x16x32_bf16 v[58:61], v[166:169], v[190:193], v[58:61]
	v_mfma_f32_16x16x32_bf16 v[46:49], v[152:155], v[198:201], v[46:49]
	v_mfma_f32_16x16x32_bf16 v[42:45], v[166:169], v[198:201], v[42:45]
	v_mfma_f32_16x16x32_bf16 v[30:33], v[152:155], v[206:209], v[30:33]
	v_mfma_f32_16x16x32_bf16 v[26:29], v[166:169], v[206:209], v[26:29]
	v_mfma_f32_16x16x32_bf16 v[14:17], v[152:155], v[214:217], v[14:17]
	v_mfma_f32_16x16x32_bf16 v[10:13], v[166:169], v[214:217], v[10:13]
	v_mfma_f32_16x16x32_bf16 v[62:65], v[156:159], v[194:197], v[62:65]
	v_mfma_f32_16x16x32_bf16 v[58:61], v[170:173], v[194:197], v[58:61]
	v_mfma_f32_16x16x32_bf16 v[46:49], v[156:159], v[202:205], v[46:49]
	v_mfma_f32_16x16x32_bf16 v[42:45], v[170:173], v[202:205], v[42:45]
	v_mfma_f32_16x16x32_bf16 v[30:33], v[156:159], v[210:213], v[30:33]
	v_mfma_f32_16x16x32_bf16 v[26:29], v[170:173], v[210:213], v[26:29]
	v_mfma_f32_16x16x32_bf16 v[14:17], v[156:159], v[218:221], v[14:17]
	v_mfma_f32_16x16x32_bf16 v[10:13], v[170:173], v[218:221], v[10:13]
	v_mfma_f32_16x16x32_bf16 v[54:57], v[174:177], v[190:193], v[54:57]
	v_mfma_f32_16x16x32_bf16 v[50:53], v[182:185], v[190:193], v[50:53]
	v_mfma_f32_16x16x32_bf16 v[38:41], v[174:177], v[198:201], v[38:41]
	v_mfma_f32_16x16x32_bf16 v[34:37], v[182:185], v[198:201], v[34:37]
	v_mfma_f32_16x16x32_bf16 v[22:25], v[174:177], v[206:209], v[22:25]
	v_mfma_f32_16x16x32_bf16 v[18:21], v[182:185], v[206:209], v[18:21]
	v_mfma_f32_16x16x32_bf16 v[6:9], v[174:177], v[214:217], v[6:9]
	v_mfma_f32_16x16x32_bf16 v[2:5], v[182:185], v[214:217], v[2:5]
	v_mfma_f32_16x16x32_bf16 v[54:57], v[178:181], v[194:197], v[54:57]
	v_mfma_f32_16x16x32_bf16 v[50:53], v[186:189], v[194:197], v[50:53]
	v_mfma_f32_16x16x32_bf16 v[38:41], v[178:181], v[202:205], v[38:41]
	v_mfma_f32_16x16x32_bf16 v[34:37], v[186:189], v[202:205], v[34:37]
	v_mfma_f32_16x16x32_bf16 v[22:25], v[178:181], v[210:213], v[22:25]
	v_mfma_f32_16x16x32_bf16 v[18:21], v[186:189], v[210:213], v[18:21]
	v_mfma_f32_16x16x32_bf16 v[6:9], v[178:181], v[218:221], v[6:9]
	v_mfma_f32_16x16x32_bf16 v[2:5], v[186:189], v[218:221], v[2:5]
	s_barrier
	s_add_i32 s65, s65, 2
	s_add_u32 s40, s40, 0x100
	s_addc_u32 s41, s41, 0
	s_add_u32 s59, s59, 0x10000
	s_addc_u32 s64, s64, 0
	s_cmp_gt_u32 s65, 29
.LBB0_1355:
	ds_read_b128 v[152:155], v163
	ds_read_b128 v[156:159], v163 offset:1024
	ds_read_b128 v[166:169], v163 offset:2048
	ds_read_b128 v[170:173], v163 offset:3072
	ds_read_b128 v[174:177], v164
	ds_read_b128 v[178:181], v164 offset:1024
	ds_read_b128 v[182:185], v164 offset:2048
	ds_read_b128 v[186:189], v164 offset:3072
	ds_read_b128 v[190:193], v165
	ds_read_b128 v[194:197], v165 offset:1024
	ds_read_b128 v[198:201], v165 offset:2048
	ds_read_b128 v[202:205], v165 offset:3072
	ds_read_b128 v[206:209], v165 offset:4096
	ds_read_b128 v[210:213], v165 offset:5120
	ds_read_b128 v[214:217], v165 offset:6144
	ds_read_b128 v[218:221], v165 offset:7168
	s_add_u32 s42, s36, s40
	s_addc_u32 s43, s37, s41
	s_add_u32 s46, s42, 0x100
	s_addc_u32 s47, s43, 0
	s_add_u32 s42, s42, 0x180
	s_addc_u32 s43, s43, 0
	s_cmpk_eq_i32 s40, 0xf00
	s_cselect_b32 s43, s57, s43
	s_cselect_b32 s42, s56, s42
	s_cselect_b32 s45, s21, s64
	s_cselect_b32 s44, s23, s59
	s_cselect_b32 s47, s4, s47
	s_cselect_b32 s46, s5, s46
	v_lshl_add_u64 v[222:223], v[148:149], 0, s[40:41]
	s_add_i32 m0, s31, 0xc000
	s_nop 0
	global_load_lds_dwordx4 v[222:223], off
	v_lshl_add_u64 v[222:223], v[150:151], 0, s[40:41]
	s_add_i32 m0, s31, 0xe000
	s_nop 0
	global_load_lds_dwordx4 v[222:223], off
	s_waitcnt vmcnt(8) lgkmcnt(0)
	s_barrier
; #define PG8_STAGE(bufoff, gbase, voff) do { _Pragma("unroll") for (int _i = 0; _i < 2; ++_i) \
;         __builtin_amdgcn_global_load_lds((const unsigned*)((const char*)(gbase) + (voff)[_i]), (LAS unsigned*)(lds + (bufoff) + ldsw + _i * 8192), 16, 0, 0); } while (0)
; #define PG8_LDA(dst, b, h) do { _Pragma("unroll") for (int m = 0; m < 4; ++m) _Pragma("unroll") for (int k = 0; k < 2; ++k) dst[m][k] = *(const LAS bf16x8*)(lds + PG8_SA(b, h) + aoff + m * 2048 + k * 1024); } while (0)
; #define PG8_MMA(ai, bj, At, Bt) do { __builtin_amdgcn_s_setprio(1); _Pragma("unroll") for (int m = 0; m < 4; ++m) _Pragma("unroll") for (int n = 0; n < 2; ++n) _Pragma("unroll") for (int k = 0; k < 2; ++k) \
;         acc[ai][bj][m][n] = __builtin_amdgcn_mfma_f32_16x16x32_bf16(Bt[n][k], At[m][k], acc[ai][bj][m][n], 0, 0, 0); __builtin_amdgcn_s_setprio(0); } while (0)
; #define PG8_WAIT_V(n) asm volatile("s_waitcnt vmcnt(" #n ")" ::: "memory")
; #define PG8_WAIT_L(n) asm volatile("s_waitcnt lgkmcnt(" #n ")" ::: "memory")
; #define PG8_BAR __builtin_amdgcn_s_barrier()
; #define PG8_SCHED __builtin_amdgcn_sched_barrier(0)
; template <class Epi, class Sched, bool ABLK = false, bool ALIGN_EPI = true, bool SP2 = true, bool BBLK = true>
; __device__ __forceinline__ void gemm_phase(LAS unsigned char* lds, const Gemm g, const Sched& S, const Epi& E) {
;     ...
;             PG8_WAIT_V(8); PG8_WAIT_L(0); PG8_BAR; PG8_MMA(0, 0, At, B0); PG8_MMA(0, 1, At, B1); PG8_BAR; PG8_SCHED;
;             PG8_LDA(At, 0, 1); PG8_STAGE(PG8_SB(0, 0), b2, voffB); PG8_STAGE(PG8_SB(0, 1), b2 + hstepB, voffB); PG8_STAGE(PG8_SA(0, 0), a2, voffA);
;             PG8_WAIT_V(8); PG8_WAIT_L(0); PG8_BAR; PG8_MMA(1, 0, At, B0); PG8_MMA(1, 1, At, B1); PG8_BAR; PG8_SCHED;
	v_mfma_f32_16x16x32_bf16 v[126:129], v[152:155], v[190:193], v[126:129]
	v_mfma_f32_16x16x32_bf16 v[122:125], v[166:169], v[190:193], v[122:125]
	v_mfma_f32_16x16x32_bf16 v[110:113], v[152:155], v[198:201], v[110:113]
	v_mfma_f32_16x16x32_bf16 v[106:109], v[166:169], v[198:201], v[106:109]
	v_mfma_f32_16x16x32_bf16 v[94:97], v[152:155], v[206:209], v[94:97]
	v_mfma_f32_16x16x32_bf16 v[90:93], v[166:169], v[206:209], v[90:93]
	v_mfma_f32_16x16x32_bf16 v[78:81], v[152:155], v[214:217], v[78:81]
	v_mfma_f32_16x16x32_bf16 v[74:77], v[166:169], v[214:217], v[74:77]
	v_mfma_f32_16x16x32_bf16 v[126:129], v[156:159], v[194:197], v[126:129]
	v_mfma_f32_16x16x32_bf16 v[122:125], v[170:173], v[194:197], v[122:125]
	v_mfma_f32_16x16x32_bf16 v[110:113], v[156:159], v[202:205], v[110:113]
	v_mfma_f32_16x16x32_bf16 v[106:109], v[170:173], v[202:205], v[106:109]
	v_mfma_f32_16x16x32_bf16 v[94:97], v[156:159], v[210:213], v[94:97]
	v_mfma_f32_16x16x32_bf16 v[90:93], v[170:173], v[210:213], v[90:93]
	v_mfma_f32_16x16x32_bf16 v[78:81], v[156:159], v[218:221], v[78:81]
	v_mfma_f32_16x16x32_bf16 v[74:77], v[170:173], v[218:221], v[74:77]
	v_mfma_f32_16x16x32_bf16 v[118:121], v[174:177], v[190:193], v[118:121]
	v_mfma_f32_16x16x32_bf16 v[114:117], v[182:185], v[190:193], v[114:117]
	v_mfma_f32_16x16x32_bf16 v[102:105], v[174:177], v[198:201], v[102:105]
	v_mfma_f32_16x16x32_bf16 v[98:101], v[182:185], v[198:201], v[98:101]
	v_mfma_f32_16x16x32_bf16 v[86:89], v[174:177], v[206:209], v[86:89]
	v_mfma_f32_16x16x32_bf16 v[82:85], v[182:185], v[206:209], v[82:85]
	v_mfma_f32_16x16x32_bf16 v[70:73], v[174:177], v[214:217], v[70:73]
	v_mfma_f32_16x16x32_bf16 v[66:69], v[182:185], v[214:217], v[66:69]
	v_mfma_f32_16x16x32_bf16 v[118:121], v[178:181], v[194:197], v[118:121]
	v_mfma_f32_16x16x32_bf16 v[114:117], v[186:189], v[194:197], v[114:117]
	v_mfma_f32_16x16x32_bf16 v[102:105], v[178:181], v[202:205], v[102:105]
	v_mfma_f32_16x16x32_bf16 v[98:101], v[186:189], v[202:205], v[98:101]
	v_mfma_f32_16x16x32_bf16 v[86:89], v[178:181], v[210:213], v[86:89]
	v_mfma_f32_16x16x32_bf16 v[82:85], v[186:189], v[210:213], v[82:85]
	v_mfma_f32_16x16x32_bf16 v[70:73], v[178:181], v[218:221], v[70:73]
	v_mfma_f32_16x16x32_bf16 v[66:69], v[186:189], v[218:221], v[66:69]
	s_barrier
	ds_read_b128 v[190:193], v165 offset:16384
	ds_read_b128 v[194:197], v165 offset:17408
	ds_read_b128 v[198:201], v165 offset:18432
	ds_read_b128 v[202:205], v165 offset:19456
	ds_read_b128 v[206:209], v165 offset:20480
	ds_read_b128 v[210:213], v165 offset:21504
	ds_read_b128 v[214:217], v165 offset:22528
	ds_read_b128 v[218:221], v165 offset:23552
	s_add_i32 s66, s72, s49
	s_mov_b32 m0, s66
	s_nop 0
	global_load_lds_dwordx4 v134, s[44:45]
	s_add_i32 m0, s66, 0x2000
	s_add_u32 s66, s44, 0x4000
	s_addc_u32 s67, s45, 0
	s_add_i32 s75, s73, s49
	global_load_lds_dwordx4 v130, s[44:45]
	s_mov_b32 m0, s75
	s_nop 0
	global_load_lds_dwordx4 v134, s[66:67]
	s_add_i32 m0, s75, 0x2000
	s_nop 0
	global_load_lds_dwordx4 v130, s[66:67]
	s_mov_b32 m0, s31
	s_nop 0
	global_load_lds_dwordx4 v136, s[46:47]
	s_mov_b32 m0, s35
	s_nop 0
	global_load_lds_dwordx4 v132, s[46:47]
	s_waitcnt vmcnt(8) lgkmcnt(0)
	s_barrier
	v_mfma_f32_16x16x32_bf16 v[62:65], v[152:155], v[190:193], v[62:65]
	v_mfma_f32_16x16x32_bf16 v[58:61], v[166:169], v[190:193], v[58:61]
	v_mfma_f32_16x16x32_bf16 v[46:49], v[152:155], v[198:201], v[46:49]
	v_mfma_f32_16x16x32_bf16 v[42:45], v[166:169], v[198:201], v[42:45]
	v_mfma_f32_16x16x32_bf16 v[30:33], v[152:155], v[206:209], v[30:33]
	v_mfma_f32_16x16x32_bf16 v[26:29], v[166:169], v[206:209], v[26:29]
	v_mfma_f32_16x16x32_bf16 v[14:17], v[152:155], v[214:217], v[14:17]
	v_mfma_f32_16x16x32_bf16 v[10:13], v[166:169], v[214:217], v[10:13]
	v_mfma_f32_16x16x32_bf16 v[62:65], v[156:159], v[194:197], v[62:65]
	v_mfma_f32_16x16x32_bf16 v[58:61], v[170:173], v[194:197], v[58:61]
	v_mfma_f32_16x16x32_bf16 v[46:49], v[156:159], v[202:205], v[46:49]
	v_mfma_f32_16x16x32_bf16 v[42:45], v[170:173], v[202:205], v[42:45]
	v_mfma_f32_16x16x32_bf16 v[30:33], v[156:159], v[210:213], v[30:33]
	v_mfma_f32_16x16x32_bf16 v[26:29], v[170:173], v[210:213], v[26:29]
	v_mfma_f32_16x16x32_bf16 v[14:17], v[156:159], v[218:221], v[14:17]
	v_mfma_f32_16x16x32_bf16 v[10:13], v[170:173], v[218:221], v[10:13]
	v_mfma_f32_16x16x32_bf16 v[54:57], v[174:177], v[190:193], v[54:57]
	v_mfma_f32_16x16x32_bf16 v[50:53], v[182:185], v[190:193], v[50:53]
	v_mfma_f32_16x16x32_bf16 v[38:41], v[174:177], v[198:201], v[38:41]
	v_mfma_f32_16x16x32_bf16 v[34:37], v[182:185], v[198:201], v[34:37]
	v_mfma_f32_16x16x32_bf16 v[22:25], v[174:177], v[206:209], v[22:25]
	v_mfma_f32_16x16x32_bf16 v[18:21], v[182:185], v[206:209], v[18:21]
	v_mfma_f32_16x16x32_bf16 v[6:9], v[174:177], v[214:217], v[6:9]
	v_mfma_f32_16x16x32_bf16 v[2:5], v[182:185], v[214:217], v[2:5]
	v_mfma_f32_16x16x32_bf16 v[54:57], v[178:181], v[194:197], v[54:57]
	v_mfma_f32_16x16x32_bf16 v[50:53], v[186:189], v[194:197], v[50:53]
	v_mfma_f32_16x16x32_bf16 v[38:41], v[178:181], v[202:205], v[38:41]
	v_mfma_f32_16x16x32_bf16 v[34:37], v[186:189], v[202:205], v[34:37]
	v_mfma_f32_16x16x32_bf16 v[22:25], v[178:181], v[210:213], v[22:25]
	v_mfma_f32_16x16x32_bf16 v[18:21], v[186:189], v[210:213], v[18:21]
	v_mfma_f32_16x16x32_bf16 v[6:9], v[178:181], v[218:221], v[6:9]
	v_mfma_f32_16x16x32_bf16 v[2:5], v[186:189], v[218:221], v[2:5]
	s_barrier
; #define PG8_STAGE(bufoff, gbase, voff) do { _Pragma("unroll") for (int _i = 0; _i < 2; ++_i) \
;         __builtin_amdgcn_global_load_lds((const unsigned*)((const char*)(gbase) + (voff)[_i]), (LAS unsigned*)(lds + (bufoff) + ldsw + _i * 8192), 16, 0, 0); } while (0)
; #define PG8_LDA(dst, b, h) do { _Pragma("unroll") for (int m = 0; m < 4; ++m) _Pragma("unroll") for (int k = 0; k < 2; ++k) dst[m][k] = *(const LAS bf16x8*)(lds + PG8_SA(b, h) + aoff + m * 2048 + k * 1024); } while (0)
; #define PG8_LDB(dst, b, h) do { _Pragma("unroll") for (int n = 0; n < 2; ++n) _Pragma("unroll") for (int k = 0; k < 2; ++k) dst[n][k] = *(const LAS bf16x8*)(lds + PG8_SB(b, h) + boff + n * 2048 + k * 1024); } while (0)
; #define PG8_MMA(ai, bj, At, Bt) do { __builtin_amdgcn_s_setprio(1); _Pragma("unroll") for (int m = 0; m < 4; ++m) _Pragma("unroll") for (int n = 0; n < 2; ++n) _Pragma("unroll") for (int k = 0; k < 2; ++k) \
;         acc[ai][bj][m][n] = __builtin_amdgcn_mfma_f32_16x16x32_bf16(Bt[n][k], At[m][k], acc[ai][bj][m][n], 0, 0, 0); __builtin_amdgcn_s_setprio(0); } while (0)
; #define PG8_WAIT_V(n) asm volatile("s_waitcnt vmcnt(" #n ")" ::: "memory")
; #define PG8_WAIT_L(n) asm volatile("s_waitcnt lgkmcnt(" #n ")" ::: "memory")
; #define PG8_BAR __builtin_amdgcn_s_barrier()
; #define PG8_SCHED __builtin_amdgcn_sched_barrier(0)
; template <class Epi, class Sched, bool ABLK = false, bool ALIGN_EPI = true, bool SP2 = true, bool BBLK = true>
; __device__ __forceinline__ void gemm_phase(LAS unsigned char* lds, const Gemm g, const Sched& S, const Epi& E) {
;     ...
;             PG8_LDB(B0, 1, 0); PG8_LDB(B1, 1, 1); PG8_SCHED; PG8_LDA(At, 1, 0); PG8_STAGE(PG8_SA(0, 1), a2 + hstepA, voffA);
;             PG8_WAIT_V(8); PG8_WAIT_L(0); PG8_BAR; PG8_MMA(0, 0, At, B0); PG8_MMA(0, 1, At, B1); PG8_BAR; PG8_SCHED;
;             PG8_LDA(At, 1, 1); PG8_STAGE(PG8_SB(1, 0), b3, voffB); PG8_STAGE(PG8_SB(1, 1), b3 + hstepB, voffB); PG8_STAGE(PG8_SA(1, 0), a3, voffA);
;             PG8_WAIT_V(8); PG8_WAIT_L(0); PG8_BAR; PG8_MMA(1, 0, At, B0); PG8_MMA(1, 1, At, B1); PG8_BAR; PG8_SCHED;
;     ...
;         if constexpr (ALIGN_EPI) { if (wr == 0) PG8_BAR; }
	v_add_u32_e32 v138, s60, v161
	ds_read_b128 v[152:155], v138
	ds_read_b128 v[156:159], v138 offset:1024
	ds_read_b128 v[166:169], v138 offset:2048
	ds_read_b128 v[170:173], v138 offset:3072
	v_add_u32_e32 v138, s61, v161
	ds_read_b128 v[174:177], v138
	ds_read_b128 v[178:181], v138 offset:1024
	ds_read_b128 v[182:185], v138 offset:2048
	ds_read_b128 v[186:189], v138 offset:3072
	ds_read_b128 v[190:193], v165 offset:32768
	ds_read_b128 v[194:197], v165 offset:33792
	ds_read_b128 v[198:201], v165 offset:34816
	ds_read_b128 v[202:205], v165 offset:35840
	ds_read_b128 v[206:209], v165 offset:36864
	ds_read_b128 v[210:213], v165 offset:37888
	ds_read_b128 v[214:217], v165 offset:38912
	ds_read_b128 v[218:221], v165 offset:39936
	s_add_u32 s46, s46, 0x80000
	s_addc_u32 s47, s47, 0
	s_mov_b32 m0, s50
	s_nop 0
	global_load_lds_dwordx4 v136, s[46:47]
	s_mov_b32 m0, s51
	s_nop 0
	global_load_lds_dwordx4 v132, s[46:47]
	s_waitcnt vmcnt(8) lgkmcnt(0)
	s_barrier
	v_mfma_f32_16x16x32_bf16 v[126:129], v[152:155], v[190:193], v[126:129]
	v_mfma_f32_16x16x32_bf16 v[122:125], v[166:169], v[190:193], v[122:125]
	v_mfma_f32_16x16x32_bf16 v[110:113], v[152:155], v[198:201], v[110:113]
	v_mfma_f32_16x16x32_bf16 v[106:109], v[166:169], v[198:201], v[106:109]
	v_mfma_f32_16x16x32_bf16 v[94:97], v[152:155], v[206:209], v[94:97]
	v_mfma_f32_16x16x32_bf16 v[90:93], v[166:169], v[206:209], v[90:93]
	v_mfma_f32_16x16x32_bf16 v[78:81], v[152:155], v[214:217], v[78:81]
	v_mfma_f32_16x16x32_bf16 v[74:77], v[166:169], v[214:217], v[74:77]
	v_mfma_f32_16x16x32_bf16 v[126:129], v[156:159], v[194:197], v[126:129]
	v_mfma_f32_16x16x32_bf16 v[122:125], v[170:173], v[194:197], v[122:125]
	v_mfma_f32_16x16x32_bf16 v[110:113], v[156:159], v[202:205], v[110:113]
	v_mfma_f32_16x16x32_bf16 v[106:109], v[170:173], v[202:205], v[106:109]
	v_mfma_f32_16x16x32_bf16 v[94:97], v[156:159], v[210:213], v[94:97]
	v_mfma_f32_16x16x32_bf16 v[90:93], v[170:173], v[210:213], v[90:93]
	v_mfma_f32_16x16x32_bf16 v[78:81], v[156:159], v[218:221], v[78:81]
	v_mfma_f32_16x16x32_bf16 v[74:77], v[170:173], v[218:221], v[74:77]
	v_mfma_f32_16x16x32_bf16 v[118:121], v[174:177], v[190:193], v[118:121]
	v_mfma_f32_16x16x32_bf16 v[114:117], v[182:185], v[190:193], v[114:117]
	v_mfma_f32_16x16x32_bf16 v[102:105], v[174:177], v[198:201], v[102:105]
	v_mfma_f32_16x16x32_bf16 v[98:101], v[182:185], v[198:201], v[98:101]
	v_mfma_f32_16x16x32_bf16 v[86:89], v[174:177], v[206:209], v[86:89]
	v_mfma_f32_16x16x32_bf16 v[82:85], v[182:185], v[206:209], v[82:85]
	v_mfma_f32_16x16x32_bf16 v[70:73], v[174:177], v[214:217], v[70:73]
	v_mfma_f32_16x16x32_bf16 v[66:69], v[182:185], v[214:217], v[66:69]
	v_mfma_f32_16x16x32_bf16 v[118:121], v[178:181], v[194:197], v[118:121]
	v_mfma_f32_16x16x32_bf16 v[114:117], v[186:189], v[194:197], v[114:117]
	v_mfma_f32_16x16x32_bf16 v[102:105], v[178:181], v[202:205], v[102:105]
	v_mfma_f32_16x16x32_bf16 v[98:101], v[186:189], v[202:205], v[98:101]
	v_mfma_f32_16x16x32_bf16 v[86:89], v[178:181], v[210:213], v[86:89]
	v_mfma_f32_16x16x32_bf16 v[82:85], v[186:189], v[210:213], v[82:85]
	v_mfma_f32_16x16x32_bf16 v[70:73], v[178:181], v[218:221], v[70:73]
	v_mfma_f32_16x16x32_bf16 v[66:69], v[186:189], v[218:221], v[66:69]
	s_barrier
	ds_read_b128 v[190:193], v165 offset:49152
	ds_read_b128 v[194:197], v165 offset:50176
	ds_read_b128 v[198:201], v165 offset:51200
	ds_read_b128 v[202:205], v165 offset:52224
	ds_read_b128 v[206:209], v165 offset:53248
	ds_read_b128 v[210:213], v165 offset:54272
	ds_read_b128 v[214:217], v165 offset:55296
	ds_read_b128 v[218:221], v165 offset:56320
	s_add_u32 s46, s44, 0x8000
	s_addc_u32 s47, s45, 0
	s_add_i32 s66, s60, s49
	s_mov_b32 m0, s66
	s_nop 0
	global_load_lds_dwordx4 v134, s[46:47]
	s_add_i32 m0, s66, 0x2000
	s_add_u32 s44, s44, 0xc000
	v_lshl_add_u64 v[222:223], s[46:47], 0, v[130:131]
	s_addc_u32 s45, s45, 0
	s_add_i32 s46, s61, s49
	global_load_lds_dwordx4 v[222:223], off
	s_mov_b32 m0, s46
	s_nop 0
	global_load_lds_dwordx4 v134, s[44:45]
	s_add_i32 m0, s46, 0x2000
	s_nop 0
	global_load_lds_dwordx4 v130, s[44:45]
	s_mov_b32 m0, s54
	s_nop 0
	global_load_lds_dwordx4 v136, s[42:43]
	s_mov_b32 m0, s55
	s_nop 0
	global_load_lds_dwordx4 v132, s[42:43]
	s_waitcnt vmcnt(8) lgkmcnt(0)
	s_barrier
	v_mfma_f32_16x16x32_bf16 v[62:65], v[152:155], v[190:193], v[62:65]
	v_mfma_f32_16x16x32_bf16 v[58:61], v[166:169], v[190:193], v[58:61]
	v_mfma_f32_16x16x32_bf16 v[46:49], v[152:155], v[198:201], v[46:49]
	v_mfma_f32_16x16x32_bf16 v[42:45], v[166:169], v[198:201], v[42:45]
	v_mfma_f32_16x16x32_bf16 v[30:33], v[152:155], v[206:209], v[30:33]
	v_mfma_f32_16x16x32_bf16 v[26:29], v[166:169], v[206:209], v[26:29]
	v_mfma_f32_16x16x32_bf16 v[14:17], v[152:155], v[214:217], v[14:17]
	v_mfma_f32_16x16x32_bf16 v[10:13], v[166:169], v[214:217], v[10:13]
	v_mfma_f32_16x16x32_bf16 v[62:65], v[156:159], v[194:197], v[62:65]
	v_mfma_f32_16x16x32_bf16 v[58:61], v[170:173], v[194:197], v[58:61]
	v_mfma_f32_16x16x32_bf16 v[46:49], v[156:159], v[202:205], v[46:49]
	v_mfma_f32_16x16x32_bf16 v[42:45], v[170:173], v[202:205], v[42:45]
	v_mfma_f32_16x16x32_bf16 v[30:33], v[156:159], v[210:213], v[30:33]
	v_mfma_f32_16x16x32_bf16 v[26:29], v[170:173], v[210:213], v[26:29]
	v_mfma_f32_16x16x32_bf16 v[14:17], v[156:159], v[218:221], v[14:17]
	v_mfma_f32_16x16x32_bf16 v[10:13], v[170:173], v[218:221], v[10:13]
	v_mfma_f32_16x16x32_bf16 v[54:57], v[174:177], v[190:193], v[54:57]
	v_mfma_f32_16x16x32_bf16 v[50:53], v[182:185], v[190:193], v[50:53]
	v_mfma_f32_16x16x32_bf16 v[38:41], v[174:177], v[198:201], v[38:41]
	v_mfma_f32_16x16x32_bf16 v[34:37], v[182:185], v[198:201], v[34:37]
	v_mfma_f32_16x16x32_bf16 v[22:25], v[174:177], v[206:209], v[22:25]
	v_mfma_f32_16x16x32_bf16 v[18:21], v[182:185], v[206:209], v[18:21]
	v_mfma_f32_16x16x32_bf16 v[6:9], v[174:177], v[214:217], v[6:9]
	v_mfma_f32_16x16x32_bf16 v[2:5], v[182:185], v[214:217], v[2:5]
	v_mfma_f32_16x16x32_bf16 v[54:57], v[178:181], v[194:197], v[54:57]
	v_mfma_f32_16x16x32_bf16 v[50:53], v[186:189], v[194:197], v[50:53]
	v_mfma_f32_16x16x32_bf16 v[38:41], v[178:181], v[202:205], v[38:41]
	v_mfma_f32_16x16x32_bf16 v[34:37], v[186:189], v[202:205], v[34:37]
	v_mfma_f32_16x16x32_bf16 v[22:25], v[178:181], v[210:213], v[22:25]
	v_mfma_f32_16x16x32_bf16 v[18:21], v[186:189], v[210:213], v[18:21]
	v_mfma_f32_16x16x32_bf16 v[6:9], v[178:181], v[218:221], v[6:9]
	v_mfma_f32_16x16x32_bf16 v[2:5], v[186:189], v[218:221], v[2:5]
	s_barrier
	s_add_i32 s65, s65, 2
	s_add_u32 s40, s40, 0x100
	s_addc_u32 s41, s41, 0
	s_add_u32 s59, s59, 0x10000
	s_addc_u32 s64, s64, 0
	s_cmp_gt_u32 s65, 29
	s_cbranch_scc0 .LBB0_1355
	s_and_b64 vcc, exec, s[12:13]
	s_cbranch_vccz .LBB0_1358
	s_barrier

; #define PG8_STAGE(bufoff, gbase, voff) do { _Pragma("unroll") for (int _i = 0; _i < 2; ++_i) \
;         __builtin_amdgcn_global_load_lds((const unsigned*)((const char*)(gbase) + (voff)[_i]), (LAS unsigned*)(lds + (bufoff) + ldsw + _i * 8192), 16, 0, 0); } while (0)
; #define PG8_LDA(dst, b, h) do { _Pragma("unroll") for (int m = 0; m < 4; ++m) _Pragma("unroll") for (int k = 0; k < 2; ++k) dst[m][k] = *(const LAS bf16x8*)(lds + PG8_SA(b, h) + aoff + m * 2048 + k * 1024); } while (0)
; #define PG8_LDB(dst, b, h) do { _Pragma("unroll") for (int n = 0; n < 2; ++n) _Pragma("unroll") for (int k = 0; k < 2; ++k) dst[n][k] = *(const LAS bf16x8*)(lds + PG8_SB(b, h) + boff + n * 2048 + k * 1024); } while (0)
; #define PG8_WAIT_V(n) asm volatile("s_waitcnt vmcnt(" #n ")" ::: "memory")
; #define PG8_WAIT_L(n) asm volatile("s_waitcnt lgkmcnt(" #n ")" ::: "memory")
; #define PG8_BAR __builtin_amdgcn_s_barrier()
; #define PG8_SCHED __builtin_amdgcn_sched_barrier(0)
; template <class Epi, class Sched, bool ABLK = false, bool ALIGN_EPI = true, bool SP2 = true, bool BBLK = true>
; __device__ __forceinline__ void gemm_phase(LAS unsigned char* lds, const Gemm g, const Sched& S, const Epi& E) {
;     ...
;         const bool has_next = S.next(ui + 1, nxt);
;         const int nt = cur.nt;
;         const char* nuA = has_next ? a_unit(nxt) : uA; const int ntbA = has_next ? nxt.k0 / BK : tbA; const char* nB = has_next ? (const char*)g.Bt + (size_t)nxt.pn * tstepB + b_k0(nxt.k0) : cB;
;         for (int t = 0; t < nt; t += 2) {
;             const bool last = (t == nt - 2);
;             const char* a1 = a_tile(uA, tbA + t + 1);
;             const char* a2 = last ? a_tile(nuA, ntbA) : a_tile(uA, tbA + t + 2); const char* b2 = last ? nB : cB + (size_t)(t + 2) * kstepB;
;             const char* a3 = last ? a_tile(nuA, ntbA + 1) : a_tile(uA, tbA + t + 3); const char* b3 = b2 + kstepB;
;             if (last && has_next) S.a_ready(nxt);
;             if constexpr (SP2) {
;             PG8_LDB(B0, 0, 0); PG8_LDB(B1, 0, 1); PG8_SCHED; PG8_LDA(At, 0, 0); PG8_STAGE(PG8_SA(1, 1), a1 + hstepA, voffA);
;             PG8_WAIT_V(8); PG8_WAIT_L(0); PG8_BAR; PG8_MMA(0, 0, At, B0); PG8_MMA(0, 1, At, B1); PG8_BAR; PG8_SCHED;
;             PG8_LDA(At, 0, 1); PG8_STAGE(PG8_SB(0, 0), b2, voffB); PG8_STAGE(PG8_SB(0, 1), b2 + hstepB, voffB); PG8_STAGE(PG8_SA(0, 0), a2, voffA);
.LBB0_1715:
	ds_read_b128 v[156:159], v152
	ds_read_b128 v[160:163], v152 offset:1024
	ds_read_b128 v[164:167], v152 offset:2048
	ds_read_b128 v[168:171], v152 offset:3072
	ds_read_b128 v[172:175], v153
	ds_read_b128 v[176:179], v153 offset:1024
	ds_read_b128 v[180:183], v153 offset:2048
	ds_read_b128 v[184:187], v153 offset:3072
	ds_read_b128 v[188:191], v154
	ds_read_b128 v[192:195], v154 offset:1024
	ds_read_b128 v[196:199], v154 offset:2048
	ds_read_b128 v[200:203], v154 offset:3072
	ds_read_b128 v[204:207], v154 offset:4096
	ds_read_b128 v[208:211], v154 offset:5120
	ds_read_b128 v[212:215], v154 offset:6144
	ds_read_b128 v[216:219], v154 offset:7168
	s_ashr_i32 s81, s80, 31
	s_andn2_b64 vcc, exec, s[4:5]
	s_lshl_b64 s[20:21], s[80:81], 20
	s_add_u32 s20, s1, s20
	s_addc_u32 s21, s36, s21
	s_and_b64 s[22:23], s[4:5], exec
	s_cselect_b32 s31, s21, s29
	s_cselect_b32 s49, s20, s28
	s_ashr_i32 s22, s63, 31
	s_lshr_b32 s22, s22, 26
	s_add_i32 s22, s63, s22
	s_ashr_i32 s22, s22, 6
	s_and_b64 s[24:25], s[4:5], exec
	s_cselect_b32 s34, s22, s30
	s_ashr_i32 s79, s78, 31
	s_lshl_b64 s[24:25], s[78:79], 20
	s_add_u32 s35, s37, s24
	s_addc_u32 s50, s38, s25
	s_ashr_i32 s23, s22, 31
	s_lshl_b64 s[24:25], s[22:23], 15
	s_add_u32 s24, s35, s24
	s_addc_u32 s25, s50, s25
	v_cndmask_b32_e64 v2, 0, 1, s[4:5]
	s_and_b64 s[4:5], s[4:5], exec
	s_cselect_b32 s4, s25, s27
	s_cselect_b32 s5, s24, s26
	s_ashr_i32 s35, s34, 31
	s_lshl_b64 s[34:35], s[34:35], 7
	s_add_u32 s23, s49, s34
	s_addc_u32 s49, s31, s35
	s_add_u32 s50, s23, 0x80
	s_addc_u32 s51, s49, 0
	s_add_u32 s52, s26, 0x10000
	s_addc_u32 s53, s27, 0
	s_ashr_i32 s31, s30, 31
	v_cmp_ne_u32_e64 s[10:11], 1, v2
	s_lshl_b64 s[26:27], s[30:31], 7
	v_lshl_add_u64 v[2:3], s[28:29], 0, v[142:143]
	s_add_u32 s54, s28, s26
	v_lshl_add_u64 v[146:147], v[2:3], 0, s[26:27]
	v_lshl_add_u64 v[2:3], s[28:29], 0, v[144:145]
	s_addc_u32 s55, s29, s27
	v_lshl_add_u64 v[148:149], v[2:3], 0, s[26:27]
	s_lshl_b32 s26, s47, 7
	s_addk_i32 s26, 0xfc00
	v_mov_b32_e32 v2, 0
	s_add_u32 s56, s26, 0x300
	s_mov_b32 s57, 0
	s_mov_b64 s[26:27], 0
	s_add_u32 s28, s54, s26
	s_addc_u32 s29, s55, s27
	s_add_u32 s34, s28, 0x100
	s_addc_u32 s35, s29, 0
	s_add_i32 s57, s57, 2
	s_add_u32 s28, s28, 0x180
	s_addc_u32 s29, s29, 0
	s_cmp_eq_u32 s56, s26
	s_cselect_b32 s29, s51, s29
	s_cselect_b32 s28, s50, s28
	s_cselect_b32 s31, s4, s53
	s_cselect_b32 s30, s5, s52
	s_cselect_b32 s35, s49, s35
	s_cselect_b32 s34, s23, s34
	v_lshl_add_u64 v[220:221], v[146:147], 0, s[26:27]
	s_add_i32 m0, s40, 0xc000
	s_nop 0
	global_load_lds_dwordx4 v[220:221], off
	v_lshl_add_u64 v[220:221], v[148:149], 0, s[26:27]
	s_add_i32 m0, s40, 0xe000
	s_nop 0
	global_load_lds_dwordx4 v[220:221], off
	s_waitcnt vmcnt(8) lgkmcnt(0)
	s_barrier
	v_mfma_f32_16x16x32_bf16 v[126:129], v[156:159], v[188:191], 0
	v_mfma_f32_16x16x32_bf16 v[122:125], v[164:167], v[188:191], 0
	v_mfma_f32_16x16x32_bf16 v[110:113], v[156:159], v[196:199], 0
	v_mfma_f32_16x16x32_bf16 v[106:109], v[164:167], v[196:199], 0
	v_mfma_f32_16x16x32_bf16 v[94:97], v[156:159], v[204:207], 0
	v_mfma_f32_16x16x32_bf16 v[90:93], v[164:167], v[204:207], 0
	v_mfma_f32_16x16x32_bf16 v[78:81], v[156:159], v[212:215], 0
	v_mfma_f32_16x16x32_bf16 v[74:77], v[164:167], v[212:215], 0
	v_mfma_f32_16x16x32_bf16 v[126:129], v[160:163], v[192:195], v[126:129]
	v_mfma_f32_16x16x32_bf16 v[122:125], v[168:171], v[192:195], v[122:125]
	v_mfma_f32_16x16x32_bf16 v[110:113], v[160:163], v[200:203], v[110:113]
	v_mfma_f32_16x16x32_bf16 v[106:109], v[168:171], v[200:203], v[106:109]
	v_mfma_f32_16x16x32_bf16 v[94:97], v[160:163], v[208:211], v[94:97]
	v_mfma_f32_16x16x32_bf16 v[90:93], v[168:171], v[208:211], v[90:93]
	v_mfma_f32_16x16x32_bf16 v[78:81], v[160:163], v[216:219], v[78:81]
	v_mfma_f32_16x16x32_bf16 v[74:77], v[168:171], v[216:219], v[74:77]
	v_mfma_f32_16x16x32_bf16 v[118:121], v[172:175], v[188:191], 0
	v_mfma_f32_16x16x32_bf16 v[114:117], v[180:183], v[188:191], 0
	v_mfma_f32_16x16x32_bf16 v[102:105], v[172:175], v[196:199], 0
	v_mfma_f32_16x16x32_bf16 v[98:101], v[180:183], v[196:199], 0
	v_mfma_f32_16x16x32_bf16 v[86:89], v[172:175], v[204:207], 0
	v_mfma_f32_16x16x32_bf16 v[82:85], v[180:183], v[204:207], 0
	v_mfma_f32_16x16x32_bf16 v[70:73], v[172:175], v[212:215], 0
	v_mfma_f32_16x16x32_bf16 v[66:69], v[180:183], v[212:215], 0
	v_mfma_f32_16x16x32_bf16 v[118:121], v[176:179], v[192:195], v[118:121]
	v_mfma_f32_16x16x32_bf16 v[114:117], v[184:187], v[192:195], v[114:117]
	v_mfma_f32_16x16x32_bf16 v[102:105], v[176:179], v[200:203], v[102:105]
	v_mfma_f32_16x16x32_bf16 v[98:101], v[184:187], v[200:203], v[98:101]
	v_mfma_f32_16x16x32_bf16 v[86:89], v[176:179], v[208:211], v[86:89]
	v_mfma_f32_16x16x32_bf16 v[82:85], v[184:187], v[208:211], v[82:85]
	v_mfma_f32_16x16x32_bf16 v[70:73], v[176:179], v[216:219], v[70:73]
	v_mfma_f32_16x16x32_bf16 v[66:69], v[184:187], v[216:219], v[66:69]
	s_barrier
	ds_read_b128 v[188:191], v154 offset:16384
	ds_read_b128 v[192:195], v154 offset:17408
	ds_read_b128 v[196:199], v154 offset:18432
	ds_read_b128 v[200:203], v154 offset:19456
	ds_read_b128 v[204:207], v154 offset:20480
	ds_read_b128 v[208:211], v154 offset:21504
	ds_read_b128 v[212:215], v154 offset:22528
	ds_read_b128 v[216:219], v154 offset:23552
	s_add_i32 s58, s72, s39
	s_mov_b32 m0, s58
	s_nop 0
	global_load_lds_dwordx4 v132, s[30:31]
	s_add_i32 m0, s58, 0x2000
	s_add_u32 s58, s30, 0x4000
	s_addc_u32 s59, s31, 0
	s_add_i32 s64, s73, s39
	global_load_lds_dwordx4 v136, s[30:31]
	s_mov_b32 m0, s64
	s_nop 0
	global_load_lds_dwordx4 v132, s[58:59]
	s_add_i32 m0, s64, 0x2000
	s_nop 0
	global_load_lds_dwordx4 v136, s[58:59]
	s_mov_b32 m0, s40
	s_nop 0
	global_load_lds_dwordx4 v130, s[34:35]
	s_mov_b32 m0, s41
	s_nop 0
	global_load_lds_dwordx4 v134, s[34:35]
	s_waitcnt vmcnt(8) lgkmcnt(0)
	s_barrier
; #define PG8_STAGE(bufoff, gbase, voff) do { _Pragma("unroll") for (int _i = 0; _i < 2; ++_i) \
;         __builtin_amdgcn_global_load_lds((const unsigned*)((const char*)(gbase) + (voff)[_i]), (LAS unsigned*)(lds + (bufoff) + ldsw + _i * 8192), 16, 0, 0); } while (0)
; #define PG8_LDA(dst, b, h) do { _Pragma("unroll") for (int m = 0; m < 4; ++m) _Pragma("unroll") for (int k = 0; k < 2; ++k) dst[m][k] = *(const LAS bf16x8*)(lds + PG8_SA(b, h) + aoff + m * 2048 + k * 1024); } while (0)
; #define PG8_LDB(dst, b, h) do { _Pragma("unroll") for (int n = 0; n < 2; ++n) _Pragma("unroll") for (int k = 0; k < 2; ++k) dst[n][k] = *(const LAS bf16x8*)(lds + PG8_SB(b, h) + boff + n * 2048 + k * 1024); } while (0)
; #define PG8_MMA(ai, bj, At, Bt) do { __builtin_amdgcn_s_setprio(1); _Pragma("unroll") for (int m = 0; m < 4; ++m) _Pragma("unroll") for (int n = 0; n < 2; ++n) _Pragma("unroll") for (int k = 0; k < 2; ++k) \
;         acc[ai][bj][m][n] = __builtin_amdgcn_mfma_f32_16x16x32_bf16(Bt[n][k], At[m][k], acc[ai][bj][m][n], 0, 0, 0); __builtin_amdgcn_s_setprio(0); } while (0)
; #define PG8_WAIT_V(n) asm volatile("s_waitcnt vmcnt(" #n ")" ::: "memory")
; #define PG8_WAIT_L(n) asm volatile("s_waitcnt lgkmcnt(" #n ")" ::: "memory")
; #define PG8_BAR __builtin_amdgcn_s_barrier()
; #define PG8_SCHED __builtin_amdgcn_sched_barrier(0)
; template <class Epi, class Sched, bool ABLK = false, bool ALIGN_EPI = true, bool SP2 = true, bool BBLK = true>
; __device__ __forceinline__ void gemm_phase(LAS unsigned char* lds, const Gemm g, const Sched& S, const Epi& E) {
;     ...
;             PG8_WAIT_V(8); PG8_WAIT_L(0); PG8_BAR; PG8_MMA(1, 0, At, B0); PG8_MMA(1, 1, At, B1); PG8_BAR; PG8_SCHED;
;             PG8_LDB(B0, 1, 0); PG8_LDB(B1, 1, 1); PG8_SCHED; PG8_LDA(At, 1, 0); PG8_STAGE(PG8_SA(0, 1), a2 + hstepA, voffA);
;             PG8_WAIT_V(8); PG8_WAIT_L(0); PG8_BAR; PG8_MMA(0, 0, At, B0); PG8_MMA(0, 1, At, B1); PG8_BAR; PG8_SCHED;
	v_mfma_f32_16x16x32_bf16 v[62:65], v[156:159], v[188:191], 0
	v_mfma_f32_16x16x32_bf16 v[58:61], v[164:167], v[188:191], 0
	v_mfma_f32_16x16x32_bf16 v[46:49], v[156:159], v[196:199], 0
	v_mfma_f32_16x16x32_bf16 v[42:45], v[164:167], v[196:199], 0
	v_mfma_f32_16x16x32_bf16 v[30:33], v[156:159], v[204:207], 0
	v_mfma_f32_16x16x32_bf16 v[26:29], v[164:167], v[204:207], 0
	v_mfma_f32_16x16x32_bf16 v[14:17], v[156:159], v[212:215], 0
	v_mfma_f32_16x16x32_bf16 v[10:13], v[164:167], v[212:215], 0
	v_mfma_f32_16x16x32_bf16 v[62:65], v[160:163], v[192:195], v[62:65]
	v_mfma_f32_16x16x32_bf16 v[58:61], v[168:171], v[192:195], v[58:61]
	v_mfma_f32_16x16x32_bf16 v[46:49], v[160:163], v[200:203], v[46:49]
	v_mfma_f32_16x16x32_bf16 v[42:45], v[168:171], v[200:203], v[42:45]
	v_mfma_f32_16x16x32_bf16 v[30:33], v[160:163], v[208:211], v[30:33]
	v_mfma_f32_16x16x32_bf16 v[26:29], v[168:171], v[208:211], v[26:29]
	v_mfma_f32_16x16x32_bf16 v[14:17], v[160:163], v[216:219], v[14:17]
	v_mfma_f32_16x16x32_bf16 v[10:13], v[168:171], v[216:219], v[10:13]
	v_mfma_f32_16x16x32_bf16 v[54:57], v[172:175], v[188:191], 0
	v_mfma_f32_16x16x32_bf16 v[50:53], v[180:183], v[188:191], 0
	v_mfma_f32_16x16x32_bf16 v[38:41], v[172:175], v[196:199], 0
	v_mfma_f32_16x16x32_bf16 v[34:37], v[180:183], v[196:199], 0
	v_mfma_f32_16x16x32_bf16 v[22:25], v[172:175], v[204:207], 0
	v_mfma_f32_16x16x32_bf16 v[18:21], v[180:183], v[204:207], 0
	v_mfma_f32_16x16x32_bf16 v[6:9], v[172:175], v[212:215], 0
	v_mfma_f32_16x16x32_bf16 v[2:5], v[180:183], v[212:215], 0
	v_mfma_f32_16x16x32_bf16 v[54:57], v[176:179], v[192:195], v[54:57]
	v_mfma_f32_16x16x32_bf16 v[50:53], v[184:187], v[192:195], v[50:53]
	v_mfma_f32_16x16x32_bf16 v[38:41], v[176:179], v[200:203], v[38:41]
	v_mfma_f32_16x16x32_bf16 v[34:37], v[184:187], v[200:203], v[34:37]
	v_mfma_f32_16x16x32_bf16 v[22:25], v[176:179], v[208:211], v[22:25]
	v_mfma_f32_16x16x32_bf16 v[18:21], v[184:187], v[208:211], v[18:21]
	v_mfma_f32_16x16x32_bf16 v[6:9], v[176:179], v[216:219], v[6:9]
	v_mfma_f32_16x16x32_bf16 v[2:5], v[184:187], v[216:219], v[2:5]
	s_barrier
	v_add_u32_e32 v155, s60, v150
	ds_read_b128 v[156:159], v155
	ds_read_b128 v[160:163], v155 offset:1024
	ds_read_b128 v[164:167], v155 offset:2048
	ds_read_b128 v[168:171], v155 offset:3072
	v_add_u32_e32 v155, s61, v150
	ds_read_b128 v[172:175], v155
	ds_read_b128 v[176:179], v155 offset:1024
	ds_read_b128 v[180:183], v155 offset:2048
	ds_read_b128 v[184:187], v155 offset:3072
	ds_read_b128 v[188:191], v154 offset:32768
	ds_read_b128 v[192:195], v154 offset:33792
	ds_read_b128 v[196:199], v154 offset:34816
	ds_read_b128 v[200:203], v154 offset:35840
	ds_read_b128 v[204:207], v154 offset:36864
	ds_read_b128 v[208:211], v154 offset:37888
	ds_read_b128 v[212:215], v154 offset:38912
	ds_read_b128 v[216:219], v154 offset:39936
	s_add_u32 s34, s34, 0x80000
	s_addc_u32 s35, s35, 0
	s_mov_b32 m0, s42
	s_nop 0
	global_load_lds_dwordx4 v130, s[34:35]
	s_mov_b32 m0, s43
	s_nop 0
	global_load_lds_dwordx4 v134, s[34:35]
	s_waitcnt vmcnt(8) lgkmcnt(0)
	s_barrier
	v_mfma_f32_16x16x32_bf16 v[126:129], v[156:159], v[188:191], v[126:129]
	v_mfma_f32_16x16x32_bf16 v[122:125], v[164:167], v[188:191], v[122:125]
	v_mfma_f32_16x16x32_bf16 v[110:113], v[156:159], v[196:199], v[110:113]
	v_mfma_f32_16x16x32_bf16 v[106:109], v[164:167], v[196:199], v[106:109]
	v_mfma_f32_16x16x32_bf16 v[94:97], v[156:159], v[204:207], v[94:97]
	v_mfma_f32_16x16x32_bf16 v[90:93], v[164:167], v[204:207], v[90:93]
	v_mfma_f32_16x16x32_bf16 v[78:81], v[156:159], v[212:215], v[78:81]
	v_mfma_f32_16x16x32_bf16 v[74:77], v[164:167], v[212:215], v[74:77]
	v_mfma_f32_16x16x32_bf16 v[126:129], v[160:163], v[192:195], v[126:129]
	v_mfma_f32_16x16x32_bf16 v[122:125], v[168:171], v[192:195], v[122:125]
	v_mfma_f32_16x16x32_bf16 v[110:113], v[160:163], v[200:203], v[110:113]
	v_mfma_f32_16x16x32_bf16 v[106:109], v[168:171], v[200:203], v[106:109]
	v_mfma_f32_16x16x32_bf16 v[94:97], v[160:163], v[208:211], v[94:97]
	v_mfma_f32_16x16x32_bf16 v[90:93], v[168:171], v[208:211], v[90:93]
	v_mfma_f32_16x16x32_bf16 v[78:81], v[160:163], v[216:219], v[78:81]
	v_mfma_f32_16x16x32_bf16 v[74:77], v[168:171], v[216:219], v[74:77]
	v_mfma_f32_16x16x32_bf16 v[118:121], v[172:175], v[188:191], v[118:121]
	v_mfma_f32_16x16x32_bf16 v[114:117], v[180:183], v[188:191], v[114:117]
	v_mfma_f32_16x16x32_bf16 v[102:105], v[172:175], v[196:199], v[102:105]
	v_mfma_f32_16x16x32_bf16 v[98:101], v[180:183], v[196:199], v[98:101]
	v_mfma_f32_16x16x32_bf16 v[86:89], v[172:175], v[204:207], v[86:89]
	v_mfma_f32_16x16x32_bf16 v[82:85], v[180:183], v[204:207], v[82:85]
	v_mfma_f32_16x16x32_bf16 v[70:73], v[172:175], v[212:215], v[70:73]
	v_mfma_f32_16x16x32_bf16 v[66:69], v[180:183], v[212:215], v[66:69]
	v_mfma_f32_16x16x32_bf16 v[118:121], v[176:179], v[192:195], v[118:121]
	v_mfma_f32_16x16x32_bf16 v[114:117], v[184:187], v[192:195], v[114:117]
	v_mfma_f32_16x16x32_bf16 v[102:105], v[176:179], v[200:203], v[102:105]
	v_mfma_f32_16x16x32_bf16 v[98:101], v[184:187], v[200:203], v[98:101]
	v_mfma_f32_16x16x32_bf16 v[86:89], v[176:179], v[208:211], v[86:89]
	v_mfma_f32_16x16x32_bf16 v[82:85], v[184:187], v[208:211], v[82:85]
	v_mfma_f32_16x16x32_bf16 v[70:73], v[176:179], v[216:219], v[70:73]
	v_mfma_f32_16x16x32_bf16 v[66:69], v[184:187], v[216:219], v[66:69]
	s_barrier
; #define PG8_STAGE(bufoff, gbase, voff) do { _Pragma("unroll") for (int _i = 0; _i < 2; ++_i) \
;         __builtin_amdgcn_global_load_lds((const unsigned*)((const char*)(gbase) + (voff)[_i]), (LAS unsigned*)(lds + (bufoff) + ldsw + _i * 8192), 16, 0, 0); } while (0)
; #define PG8_LDA(dst, b, h) do { _Pragma("unroll") for (int m = 0; m < 4; ++m) _Pragma("unroll") for (int k = 0; k < 2; ++k) dst[m][k] = *(const LAS bf16x8*)(lds + PG8_SA(b, h) + aoff + m * 2048 + k * 1024); } while (0)
; #define PG8_WAIT_V(n) asm volatile("s_waitcnt vmcnt(" #n ")" ::: "memory")
; #define PG8_WAIT_L(n) asm volatile("s_waitcnt lgkmcnt(" #n ")" ::: "memory")
; template <class Epi, class Sched, bool ABLK = false, bool ALIGN_EPI = true, bool SP2 = true, bool BBLK = true>
; __device__ __forceinline__ void gemm_phase(LAS unsigned char* lds, const Gemm g, const Sched& S, const Epi& E) {
;     ...
;         for (int t = 0; t < nt; t += 2) {
;             const bool last = (t == nt - 2);
;             const char* a1 = a_tile(uA, tbA + t + 1);
;             const char* a2 = last ? a_tile(nuA, ntbA) : a_tile(uA, tbA + t + 2); const char* b2 = last ? nB : cB + (size_t)(t + 2) * kstepB;
;             const char* a3 = last ? a_tile(nuA, ntbA + 1) : a_tile(uA, tbA + t + 3); const char* b3 = b2 + kstepB;
;             if (last && has_next) S.a_ready(nxt);
;             if constexpr (SP2) {
;             PG8_LDB(B0, 0, 0); PG8_LDB(B1, 0, 1); PG8_SCHED; PG8_LDA(At, 0, 0); PG8_STAGE(PG8_SA(1, 1), a1 + hstepA, voffA);
;             PG8_WAIT_V(8); PG8_WAIT_L(0); PG8_BAR; PG8_MMA(0, 0, At, B0); PG8_MMA(0, 1, At, B1); PG8_BAR; PG8_SCHED;
;             PG8_LDA(At, 0, 1); PG8_STAGE(PG8_SB(0, 0), b2, voffB); PG8_STAGE(PG8_SB(0, 1), b2 + hstepB, voffB); PG8_STAGE(PG8_SA(0, 0), a2, voffA);
;             PG8_WAIT_V(8); PG8_WAIT_L(0); PG8_BAR; PG8_MMA(1, 0, At, B0); PG8_MMA(1, 1, At, B1); PG8_BAR; PG8_SCHED;
;             PG8_LDB(B0, 1, 0); PG8_LDB(B1, 1, 1); PG8_SCHED; PG8_LDA(At, 1, 0); PG8_STAGE(PG8_SA(0, 1), a2 + hstepA, voffA);
;             PG8_WAIT_V(8); PG8_WAIT_L(0); PG8_BAR; PG8_MMA(0, 0, At, B0); PG8_MMA(0, 1, At, B1); PG8_BAR; PG8_SCHED;
;             PG8_LDA(At, 1, 1); PG8_STAGE(PG8_SB(1, 0), b3, voffB); PG8_STAGE(PG8_SB(1, 1), b3 + hstepB, voffB); PG8_STAGE(PG8_SA(1, 0), a3, voffA);
;             PG8_WAIT_V(8); PG8_WAIT_L(0); PG8_BAR; PG8_MMA(1, 0, At, B0); PG8_MMA(1, 1, At, B1); PG8_BAR; PG8_SCHED;
	ds_read_b128 v[188:191], v154 offset:49152
	ds_read_b128 v[192:195], v154 offset:50176
	ds_read_b128 v[196:199], v154 offset:51200
	ds_read_b128 v[200:203], v154 offset:52224
	ds_read_b128 v[204:207], v154 offset:53248
	ds_read_b128 v[208:211], v154 offset:54272
	ds_read_b128 v[212:215], v154 offset:55296
	ds_read_b128 v[216:219], v154 offset:56320
	s_add_u32 s34, s30, 0x8000
	s_addc_u32 s35, s31, 0
	s_add_i32 s58, s60, s39
	s_mov_b32 m0, s58
	s_nop 0
	global_load_lds_dwordx4 v132, s[34:35]
	s_add_i32 m0, s58, 0x2000
	s_add_u32 s30, s30, 0xc000
	v_lshl_add_u64 v[220:221], s[34:35], 0, v[136:137]
	s_addc_u32 s31, s31, 0
	s_add_i32 s34, s61, s39
	global_load_lds_dwordx4 v[220:221], off
	s_mov_b32 m0, s34
	s_nop 0
	global_load_lds_dwordx4 v132, s[30:31]
	s_add_i32 m0, s34, 0x2000
	s_nop 0
	global_load_lds_dwordx4 v136, s[30:31]
	s_mov_b32 m0, s44
	s_nop 0
	global_load_lds_dwordx4 v130, s[28:29]
	s_mov_b32 m0, s45
	s_nop 0
	global_load_lds_dwordx4 v134, s[28:29]
	s_waitcnt vmcnt(8) lgkmcnt(0)
	s_barrier
	v_mfma_f32_16x16x32_bf16 v[62:65], v[156:159], v[188:191], v[62:65]
	v_mfma_f32_16x16x32_bf16 v[58:61], v[164:167], v[188:191], v[58:61]
	v_mfma_f32_16x16x32_bf16 v[46:49], v[156:159], v[196:199], v[46:49]
	v_mfma_f32_16x16x32_bf16 v[42:45], v[164:167], v[196:199], v[42:45]
	v_mfma_f32_16x16x32_bf16 v[30:33], v[156:159], v[204:207], v[30:33]
	v_mfma_f32_16x16x32_bf16 v[26:29], v[164:167], v[204:207], v[26:29]
	v_mfma_f32_16x16x32_bf16 v[14:17], v[156:159], v[212:215], v[14:17]
	v_mfma_f32_16x16x32_bf16 v[10:13], v[164:167], v[212:215], v[10:13]
	v_mfma_f32_16x16x32_bf16 v[62:65], v[160:163], v[192:195], v[62:65]
	v_mfma_f32_16x16x32_bf16 v[58:61], v[168:171], v[192:195], v[58:61]
	v_mfma_f32_16x16x32_bf16 v[46:49], v[160:163], v[200:203], v[46:49]
	v_mfma_f32_16x16x32_bf16 v[42:45], v[168:171], v[200:203], v[42:45]
	v_mfma_f32_16x16x32_bf16 v[30:33], v[160:163], v[208:211], v[30:33]
	v_mfma_f32_16x16x32_bf16 v[26:29], v[168:171], v[208:211], v[26:29]
	v_mfma_f32_16x16x32_bf16 v[14:17], v[160:163], v[216:219], v[14:17]
	v_mfma_f32_16x16x32_bf16 v[10:13], v[168:171], v[216:219], v[10:13]
	v_mfma_f32_16x16x32_bf16 v[54:57], v[172:175], v[188:191], v[54:57]
	v_mfma_f32_16x16x32_bf16 v[50:53], v[180:183], v[188:191], v[50:53]
	v_mfma_f32_16x16x32_bf16 v[38:41], v[172:175], v[196:199], v[38:41]
	v_mfma_f32_16x16x32_bf16 v[34:37], v[180:183], v[196:199], v[34:37]
	v_mfma_f32_16x16x32_bf16 v[22:25], v[172:175], v[204:207], v[22:25]
	v_mfma_f32_16x16x32_bf16 v[18:21], v[180:183], v[204:207], v[18:21]
	v_mfma_f32_16x16x32_bf16 v[6:9], v[172:175], v[212:215], v[6:9]
	v_mfma_f32_16x16x32_bf16 v[2:5], v[180:183], v[212:215], v[2:5]
	v_mfma_f32_16x16x32_bf16 v[54:57], v[176:179], v[192:195], v[54:57]
	v_mfma_f32_16x16x32_bf16 v[50:53], v[184:187], v[192:195], v[50:53]
	v_mfma_f32_16x16x32_bf16 v[38:41], v[176:179], v[200:203], v[38:41]
	v_mfma_f32_16x16x32_bf16 v[34:37], v[184:187], v[200:203], v[34:37]
	v_mfma_f32_16x16x32_bf16 v[22:25], v[176:179], v[208:211], v[22:25]
	v_mfma_f32_16x16x32_bf16 v[18:21], v[184:187], v[208:211], v[18:21]
	v_mfma_f32_16x16x32_bf16 v[6:9], v[176:179], v[216:219], v[6:9]
	v_mfma_f32_16x16x32_bf16 v[2:5], v[184:187], v[216:219], v[2:5]
	s_barrier
	s_add_u32 s52, s52, 0x10000
	s_addc_u32 s53, s53, 0
	s_add_u32 s26, s26, 0x100
	s_addc_u32 s27, s27, 0
	s_cmp_ge_u32 s57, s47
.LBB0_1716:
	ds_read_b128 v[156:159], v152
	ds_read_b128 v[160:163], v152 offset:1024
	ds_read_b128 v[164:167], v152 offset:2048
	ds_read_b128 v[168:171], v152 offset:3072
	ds_read_b128 v[172:175], v153
	ds_read_b128 v[176:179], v153 offset:1024
	ds_read_b128 v[180:183], v153 offset:2048
	ds_read_b128 v[184:187], v153 offset:3072
	ds_read_b128 v[188:191], v154
	ds_read_b128 v[192:195], v154 offset:1024
	ds_read_b128 v[196:199], v154 offset:2048
	ds_read_b128 v[200:203], v154 offset:3072
	ds_read_b128 v[204:207], v154 offset:4096
	ds_read_b128 v[208:211], v154 offset:5120
	ds_read_b128 v[212:215], v154 offset:6144
	ds_read_b128 v[216:219], v154 offset:7168
	s_add_u32 s28, s54, s26
	s_addc_u32 s29, s55, s27
	s_add_u32 s34, s28, 0x100
	s_addc_u32 s35, s29, 0
	s_add_i32 s57, s57, 2
	s_add_u32 s28, s28, 0x180
	s_addc_u32 s29, s29, 0
	s_cmp_eq_u32 s56, s26
	s_cselect_b32 s29, s51, s29
	s_cselect_b32 s28, s50, s28
	s_cselect_b32 s31, s4, s53
	s_cselect_b32 s30, s5, s52
	s_cselect_b32 s35, s49, s35
	s_cselect_b32 s34, s23, s34
	v_lshl_add_u64 v[220:221], v[146:147], 0, s[26:27]
	s_add_i32 m0, s40, 0xc000
	s_nop 0
	global_load_lds_dwordx4 v[220:221], off
	v_lshl_add_u64 v[220:221], v[148:149], 0, s[26:27]
	s_add_i32 m0, s40, 0xe000
	s_nop 0
	global_load_lds_dwordx4 v[220:221], off
	s_waitcnt vmcnt(8) lgkmcnt(0)
	s_barrier
; #define PG8_STAGE(bufoff, gbase, voff) do { _Pragma("unroll") for (int _i = 0; _i < 2; ++_i) \
;         __builtin_amdgcn_global_load_lds((const unsigned*)((const char*)(gbase) + (voff)[_i]), (LAS unsigned*)(lds + (bufoff) + ldsw + _i * 8192), 16, 0, 0); } while (0)
; #define PG8_LDA(dst, b, h) do { _Pragma("unroll") for (int m = 0; m < 4; ++m) _Pragma("unroll") for (int k = 0; k < 2; ++k) dst[m][k] = *(const LAS bf16x8*)(lds + PG8_SA(b, h) + aoff + m * 2048 + k * 1024); } while (0)
; #define PG8_MMA(ai, bj, At, Bt) do { __builtin_amdgcn_s_setprio(1); _Pragma("unroll") for (int m = 0; m < 4; ++m) _Pragma("unroll") for (int n = 0; n < 2; ++n) _Pragma("unroll") for (int k = 0; k < 2; ++k) \
;         acc[ai][bj][m][n] = __builtin_amdgcn_mfma_f32_16x16x32_bf16(Bt[n][k], At[m][k], acc[ai][bj][m][n], 0, 0, 0); __builtin_amdgcn_s_setprio(0); } while (0)
; #define PG8_WAIT_V(n) asm volatile("s_waitcnt vmcnt(" #n ")" ::: "memory")
; #define PG8_WAIT_L(n) asm volatile("s_waitcnt lgkmcnt(" #n ")" ::: "memory")
; #define PG8_BAR __builtin_amdgcn_s_barrier()
; #define PG8_SCHED __builtin_amdgcn_sched_barrier(0)
; template <class Epi, class Sched, bool ABLK = false, bool ALIGN_EPI = true, bool SP2 = true, bool BBLK = true>
; __device__ __forceinline__ void gemm_phase(LAS unsigned char* lds, const Gemm g, const Sched& S, const Epi& E) {
;     ...
;             PG8_WAIT_V(8); PG8_WAIT_L(0); PG8_BAR; PG8_MMA(0, 0, At, B0); PG8_MMA(0, 1, At, B1); PG8_BAR; PG8_SCHED;
;             PG8_LDA(At, 0, 1); PG8_STAGE(PG8_SB(0, 0), b2, voffB); PG8_STAGE(PG8_SB(0, 1), b2 + hstepB, voffB); PG8_STAGE(PG8_SA(0, 0), a2, voffA);
;             PG8_WAIT_V(8); PG8_WAIT_L(0); PG8_BAR; PG8_MMA(1, 0, At, B0); PG8_MMA(1, 1, At, B1); PG8_BAR; PG8_SCHED;
	v_mfma_f32_16x16x32_bf16 v[126:129], v[156:159], v[188:191], v[126:129]
	v_mfma_f32_16x16x32_bf16 v[122:125], v[164:167], v[188:191], v[122:125]
	v_mfma_f32_16x16x32_bf16 v[110:113], v[156:159], v[196:199], v[110:113]
	v_mfma_f32_16x16x32_bf16 v[106:109], v[164:167], v[196:199], v[106:109]
	v_mfma_f32_16x16x32_bf16 v[94:97], v[156:159], v[204:207], v[94:97]
	v_mfma_f32_16x16x32_bf16 v[90:93], v[164:167], v[204:207], v[90:93]
	v_mfma_f32_16x16x32_bf16 v[78:81], v[156:159], v[212:215], v[78:81]
	v_mfma_f32_16x16x32_bf16 v[74:77], v[164:167], v[212:215], v[74:77]
	v_mfma_f32_16x16x32_bf16 v[126:129], v[160:163], v[192:195], v[126:129]
	v_mfma_f32_16x16x32_bf16 v[122:125], v[168:171], v[192:195], v[122:125]
	v_mfma_f32_16x16x32_bf16 v[110:113], v[160:163], v[200:203], v[110:113]
	v_mfma_f32_16x16x32_bf16 v[106:109], v[168:171], v[200:203], v[106:109]
	v_mfma_f32_16x16x32_bf16 v[94:97], v[160:163], v[208:211], v[94:97]
	v_mfma_f32_16x16x32_bf16 v[90:93], v[168:171], v[208:211], v[90:93]
	v_mfma_f32_16x16x32_bf16 v[78:81], v[160:163], v[216:219], v[78:81]
	v_mfma_f32_16x16x32_bf16 v[74:77], v[168:171], v[216:219], v[74:77]
	v_mfma_f32_16x16x32_bf16 v[118:121], v[172:175], v[188:191], v[118:121]
	v_mfma_f32_16x16x32_bf16 v[114:117], v[180:183], v[188:191], v[114:117]
	v_mfma_f32_16x16x32_bf16 v[102:105], v[172:175], v[196:199], v[102:105]
	v_mfma_f32_16x16x32_bf16 v[98:101], v[180:183], v[196:199], v[98:101]
	v_mfma_f32_16x16x32_bf16 v[86:89], v[172:175], v[204:207], v[86:89]
	v_mfma_f32_16x16x32_bf16 v[82:85], v[180:183], v[204:207], v[82:85]
	v_mfma_f32_16x16x32_bf16 v[70:73], v[172:175], v[212:215], v[70:73]
	v_mfma_f32_16x16x32_bf16 v[66:69], v[180:183], v[212:215], v[66:69]
	v_mfma_f32_16x16x32_bf16 v[118:121], v[176:179], v[192:195], v[118:121]
	v_mfma_f32_16x16x32_bf16 v[114:117], v[184:187], v[192:195], v[114:117]
	v_mfma_f32_16x16x32_bf16 v[102:105], v[176:179], v[200:203], v[102:105]
	v_mfma_f32_16x16x32_bf16 v[98:101], v[184:187], v[200:203], v[98:101]
	v_mfma_f32_16x16x32_bf16 v[86:89], v[176:179], v[208:211], v[86:89]
	v_mfma_f32_16x16x32_bf16 v[82:85], v[184:187], v[208:211], v[82:85]
	v_mfma_f32_16x16x32_bf16 v[70:73], v[176:179], v[216:219], v[70:73]
	v_mfma_f32_16x16x32_bf16 v[66:69], v[184:187], v[216:219], v[66:69]
	s_barrier
	ds_read_b128 v[188:191], v154 offset:16384
	ds_read_b128 v[192:195], v154 offset:17408
	ds_read_b128 v[196:199], v154 offset:18432
	ds_read_b128 v[200:203], v154 offset:19456
	ds_read_b128 v[204:207], v154 offset:20480
	ds_read_b128 v[208:211], v154 offset:21504
	ds_read_b128 v[212:215], v154 offset:22528
	ds_read_b128 v[216:219], v154 offset:23552
	s_add_i32 s58, s72, s39
	s_mov_b32 m0, s58
	s_nop 0
	global_load_lds_dwordx4 v132, s[30:31]
	s_add_i32 m0, s58, 0x2000
	s_add_u32 s58, s30, 0x4000
	s_addc_u32 s59, s31, 0
	s_add_i32 s64, s73, s39
	global_load_lds_dwordx4 v136, s[30:31]
	s_mov_b32 m0, s64
	s_nop 0
	global_load_lds_dwordx4 v132, s[58:59]
	s_add_i32 m0, s64, 0x2000
	s_nop 0
	global_load_lds_dwordx4 v136, s[58:59]
	s_mov_b32 m0, s40
	s_nop 0
	global_load_lds_dwordx4 v130, s[34:35]
	s_mov_b32 m0, s41
	s_nop 0
	global_load_lds_dwordx4 v134, s[34:35]
	s_waitcnt vmcnt(8) lgkmcnt(0)
	s_barrier
	v_mfma_f32_16x16x32_bf16 v[62:65], v[156:159], v[188:191], v[62:65]
	v_mfma_f32_16x16x32_bf16 v[58:61], v[164:167], v[188:191], v[58:61]
	v_mfma_f32_16x16x32_bf16 v[46:49], v[156:159], v[196:199], v[46:49]
	v_mfma_f32_16x16x32_bf16 v[42:45], v[164:167], v[196:199], v[42:45]
	v_mfma_f32_16x16x32_bf16 v[30:33], v[156:159], v[204:207], v[30:33]
	v_mfma_f32_16x16x32_bf16 v[26:29], v[164:167], v[204:207], v[26:29]
	v_mfma_f32_16x16x32_bf16 v[14:17], v[156:159], v[212:215], v[14:17]
	v_mfma_f32_16x16x32_bf16 v[10:13], v[164:167], v[212:215], v[10:13]
	v_mfma_f32_16x16x32_bf16 v[62:65], v[160:163], v[192:195], v[62:65]
	v_mfma_f32_16x16x32_bf16 v[58:61], v[168:171], v[192:195], v[58:61]
	v_mfma_f32_16x16x32_bf16 v[46:49], v[160:163], v[200:203], v[46:49]
	v_mfma_f32_16x16x32_bf16 v[42:45], v[168:171], v[200:203], v[42:45]
	v_mfma_f32_16x16x32_bf16 v[30:33], v[160:163], v[208:211], v[30:33]
	v_mfma_f32_16x16x32_bf16 v[26:29], v[168:171], v[208:211], v[26:29]
	v_mfma_f32_16x16x32_bf16 v[14:17], v[160:163], v[216:219], v[14:17]
	v_mfma_f32_16x16x32_bf16 v[10:13], v[168:171], v[216:219], v[10:13]
	v_mfma_f32_16x16x32_bf16 v[54:57], v[172:175], v[188:191], v[54:57]
	v_mfma_f32_16x16x32_bf16 v[50:53], v[180:183], v[188:191], v[50:53]
	v_mfma_f32_16x16x32_bf16 v[38:41], v[172:175], v[196:199], v[38:41]
	v_mfma_f32_16x16x32_bf16 v[34:37], v[180:183], v[196:199], v[34:37]
	v_mfma_f32_16x16x32_bf16 v[22:25], v[172:175], v[204:207], v[22:25]
	v_mfma_f32_16x16x32_bf16 v[18:21], v[180:183], v[204:207], v[18:21]
	v_mfma_f32_16x16x32_bf16 v[6:9], v[172:175], v[212:215], v[6:9]
	v_mfma_f32_16x16x32_bf16 v[2:5], v[180:183], v[212:215], v[2:5]
	v_mfma_f32_16x16x32_bf16 v[54:57], v[176:179], v[192:195], v[54:57]
	v_mfma_f32_16x16x32_bf16 v[50:53], v[184:187], v[192:195], v[50:53]
	v_mfma_f32_16x16x32_bf16 v[38:41], v[176:179], v[200:203], v[38:41]
	v_mfma_f32_16x16x32_bf16 v[34:37], v[184:187], v[200:203], v[34:37]
	v_mfma_f32_16x16x32_bf16 v[22:25], v[176:179], v[208:211], v[22:25]
	v_mfma_f32_16x16x32_bf16 v[18:21], v[184:187], v[208:211], v[18:21]
	v_mfma_f32_16x16x32_bf16 v[6:9], v[176:179], v[216:219], v[6:9]
	v_mfma_f32_16x16x32_bf16 v[2:5], v[184:187], v[216:219], v[2:5]
	s_barrier
; #define PG8_STAGE(bufoff, gbase, voff) do { _Pragma("unroll") for (int _i = 0; _i < 2; ++_i) \
;         __builtin_amdgcn_global_load_lds((const unsigned*)((const char*)(gbase) + (voff)[_i]), (LAS unsigned*)(lds + (bufoff) + ldsw + _i * 8192), 16, 0, 0); } while (0)
; #define PG8_LDA(dst, b, h) do { _Pragma("unroll") for (int m = 0; m < 4; ++m) _Pragma("unroll") for (int k = 0; k < 2; ++k) dst[m][k] = *(const LAS bf16x8*)(lds + PG8_SA(b, h) + aoff + m * 2048 + k * 1024); } while (0)
; #define PG8_LDB(dst, b, h) do { _Pragma("unroll") for (int n = 0; n < 2; ++n) _Pragma("unroll") for (int k = 0; k < 2; ++k) dst[n][k] = *(const LAS bf16x8*)(lds + PG8_SB(b, h) + boff + n * 2048 + k * 1024); } while (0)
; #define PG8_MMA(ai, bj, At, Bt) do { __builtin_amdgcn_s_setprio(1); _Pragma("unroll") for (int m = 0; m < 4; ++m) _Pragma("unroll") for (int n = 0; n < 2; ++n) _Pragma("unroll") for (int k = 0; k < 2; ++k) \
;         acc[ai][bj][m][n] = __builtin_amdgcn_mfma_f32_16x16x32_bf16(Bt[n][k], At[m][k], acc[ai][bj][m][n], 0, 0, 0); __builtin_amdgcn_s_setprio(0); } while (0)
; #define PG8_WAIT_V(n) asm volatile("s_waitcnt vmcnt(" #n ")" ::: "memory")
; #define PG8_WAIT_L(n) asm volatile("s_waitcnt lgkmcnt(" #n ")" ::: "memory")
; #define PG8_BAR __builtin_amdgcn_s_barrier()
; #define PG8_SCHED __builtin_amdgcn_sched_barrier(0)
; template <class Epi, class Sched, bool ABLK = false, bool ALIGN_EPI = true, bool SP2 = true, bool BBLK = true>
; __device__ __forceinline__ void gemm_phase(LAS unsigned char* lds, const Gemm g, const Sched& S, const Epi& E) {
;     ...
;             PG8_LDB(B0, 1, 0); PG8_LDB(B1, 1, 1); PG8_SCHED; PG8_LDA(At, 1, 0); PG8_STAGE(PG8_SA(0, 1), a2 + hstepA, voffA);
;             PG8_WAIT_V(8); PG8_WAIT_L(0); PG8_BAR; PG8_MMA(0, 0, At, B0); PG8_MMA(0, 1, At, B1); PG8_BAR; PG8_SCHED;
;             PG8_LDA(At, 1, 1); PG8_STAGE(PG8_SB(1, 0), b3, voffB); PG8_STAGE(PG8_SB(1, 1), b3 + hstepB, voffB); PG8_STAGE(PG8_SA(1, 0), a3, voffA);
;             PG8_WAIT_V(8); PG8_WAIT_L(0); PG8_BAR; PG8_MMA(1, 0, At, B0); PG8_MMA(1, 1, At, B1); PG8_BAR; PG8_SCHED;
;     ...
;         if constexpr (ALIGN_EPI) { if (wr == 0) PG8_BAR; }
	v_add_u32_e32 v155, s60, v150
	ds_read_b128 v[156:159], v155
	ds_read_b128 v[160:163], v155 offset:1024
	ds_read_b128 v[164:167], v155 offset:2048
	ds_read_b128 v[168:171], v155 offset:3072
	v_add_u32_e32 v155, s61, v150
	ds_read_b128 v[172:175], v155
	ds_read_b128 v[176:179], v155 offset:1024
	ds_read_b128 v[180:183], v155 offset:2048
	ds_read_b128 v[184:187], v155 offset:3072
	ds_read_b128 v[188:191], v154 offset:32768
	ds_read_b128 v[192:195], v154 offset:33792
	ds_read_b128 v[196:199], v154 offset:34816
	ds_read_b128 v[200:203], v154 offset:35840
	ds_read_b128 v[204:207], v154 offset:36864
	ds_read_b128 v[208:211], v154 offset:37888
	ds_read_b128 v[212:215], v154 offset:38912
	ds_read_b128 v[216:219], v154 offset:39936
	s_add_u32 s34, s34, 0x80000
	s_addc_u32 s35, s35, 0
	s_mov_b32 m0, s42
	s_nop 0
	global_load_lds_dwordx4 v130, s[34:35]
	s_mov_b32 m0, s43
	s_nop 0
	global_load_lds_dwordx4 v134, s[34:35]
	s_waitcnt vmcnt(8) lgkmcnt(0)
	s_barrier
	v_mfma_f32_16x16x32_bf16 v[126:129], v[156:159], v[188:191], v[126:129]
	v_mfma_f32_16x16x32_bf16 v[122:125], v[164:167], v[188:191], v[122:125]
	v_mfma_f32_16x16x32_bf16 v[110:113], v[156:159], v[196:199], v[110:113]
	v_mfma_f32_16x16x32_bf16 v[106:109], v[164:167], v[196:199], v[106:109]
	v_mfma_f32_16x16x32_bf16 v[94:97], v[156:159], v[204:207], v[94:97]
	v_mfma_f32_16x16x32_bf16 v[90:93], v[164:167], v[204:207], v[90:93]
	v_mfma_f32_16x16x32_bf16 v[78:81], v[156:159], v[212:215], v[78:81]
	v_mfma_f32_16x16x32_bf16 v[74:77], v[164:167], v[212:215], v[74:77]
	v_mfma_f32_16x16x32_bf16 v[126:129], v[160:163], v[192:195], v[126:129]
	v_mfma_f32_16x16x32_bf16 v[122:125], v[168:171], v[192:195], v[122:125]
	v_mfma_f32_16x16x32_bf16 v[110:113], v[160:163], v[200:203], v[110:113]
	v_mfma_f32_16x16x32_bf16 v[106:109], v[168:171], v[200:203], v[106:109]
	v_mfma_f32_16x16x32_bf16 v[94:97], v[160:163], v[208:211], v[94:97]
	v_mfma_f32_16x16x32_bf16 v[90:93], v[168:171], v[208:211], v[90:93]
	v_mfma_f32_16x16x32_bf16 v[78:81], v[160:163], v[216:219], v[78:81]
	v_mfma_f32_16x16x32_bf16 v[74:77], v[168:171], v[216:219], v[74:77]
	v_mfma_f32_16x16x32_bf16 v[118:121], v[172:175], v[188:191], v[118:121]
	v_mfma_f32_16x16x32_bf16 v[114:117], v[180:183], v[188:191], v[114:117]
	v_mfma_f32_16x16x32_bf16 v[102:105], v[172:175], v[196:199], v[102:105]
	v_mfma_f32_16x16x32_bf16 v[98:101], v[180:183], v[196:199], v[98:101]
	v_mfma_f32_16x16x32_bf16 v[86:89], v[172:175], v[204:207], v[86:89]
	v_mfma_f32_16x16x32_bf16 v[82:85], v[180:183], v[204:207], v[82:85]
	v_mfma_f32_16x16x32_bf16 v[70:73], v[172:175], v[212:215], v[70:73]
	v_mfma_f32_16x16x32_bf16 v[66:69], v[180:183], v[212:215], v[66:69]
	v_mfma_f32_16x16x32_bf16 v[118:121], v[176:179], v[192:195], v[118:121]
	v_mfma_f32_16x16x32_bf16 v[114:117], v[184:187], v[192:195], v[114:117]
	v_mfma_f32_16x16x32_bf16 v[102:105], v[176:179], v[200:203], v[102:105]
	v_mfma_f32_16x16x32_bf16 v[98:101], v[184:187], v[200:203], v[98:101]
	v_mfma_f32_16x16x32_bf16 v[86:89], v[176:179], v[208:211], v[86:89]
	v_mfma_f32_16x16x32_bf16 v[82:85], v[184:187], v[208:211], v[82:85]
	v_mfma_f32_16x16x32_bf16 v[70:73], v[176:179], v[216:219], v[70:73]
	v_mfma_f32_16x16x32_bf16 v[66:69], v[184:187], v[216:219], v[66:69]
	s_barrier
	ds_read_b128 v[188:191], v154 offset:49152
	ds_read_b128 v[192:195], v154 offset:50176
	ds_read_b128 v[196:199], v154 offset:51200
	ds_read_b128 v[200:203], v154 offset:52224
	ds_read_b128 v[204:207], v154 offset:53248
	ds_read_b128 v[208:211], v154 offset:54272
	ds_read_b128 v[212:215], v154 offset:55296
	ds_read_b128 v[216:219], v154 offset:56320
	s_add_u32 s34, s30, 0x8000
	s_addc_u32 s35, s31, 0
	s_add_i32 s58, s60, s39
	s_mov_b32 m0, s58
	s_nop 0
	global_load_lds_dwordx4 v132, s[34:35]
	s_add_i32 m0, s58, 0x2000
	s_add_u32 s30, s30, 0xc000
	v_lshl_add_u64 v[220:221], s[34:35], 0, v[136:137]
	s_addc_u32 s31, s31, 0
	s_add_i32 s34, s61, s39
	global_load_lds_dwordx4 v[220:221], off
	s_mov_b32 m0, s34
	s_nop 0
	global_load_lds_dwordx4 v132, s[30:31]
	s_add_i32 m0, s34, 0x2000
	s_nop 0
	global_load_lds_dwordx4 v136, s[30:31]
	s_mov_b32 m0, s44
	s_nop 0
	global_load_lds_dwordx4 v130, s[28:29]
	s_mov_b32 m0, s45
	s_nop 0
	global_load_lds_dwordx4 v134, s[28:29]
	s_waitcnt vmcnt(8) lgkmcnt(0)
	s_barrier
	v_mfma_f32_16x16x32_bf16 v[62:65], v[156:159], v[188:191], v[62:65]
	v_mfma_f32_16x16x32_bf16 v[58:61], v[164:167], v[188:191], v[58:61]
	v_mfma_f32_16x16x32_bf16 v[46:49], v[156:159], v[196:199], v[46:49]
	v_mfma_f32_16x16x32_bf16 v[42:45], v[164:167], v[196:199], v[42:45]
	v_mfma_f32_16x16x32_bf16 v[30:33], v[156:159], v[204:207], v[30:33]
	v_mfma_f32_16x16x32_bf16 v[26:29], v[164:167], v[204:207], v[26:29]
	v_mfma_f32_16x16x32_bf16 v[14:17], v[156:159], v[212:215], v[14:17]
	v_mfma_f32_16x16x32_bf16 v[10:13], v[164:167], v[212:215], v[10:13]
	v_mfma_f32_16x16x32_bf16 v[62:65], v[160:163], v[192:195], v[62:65]
	v_mfma_f32_16x16x32_bf16 v[58:61], v[168:171], v[192:195], v[58:61]
	v_mfma_f32_16x16x32_bf16 v[46:49], v[160:163], v[200:203], v[46:49]
	v_mfma_f32_16x16x32_bf16 v[42:45], v[168:171], v[200:203], v[42:45]
	v_mfma_f32_16x16x32_bf16 v[30:33], v[160:163], v[208:211], v[30:33]
	v_mfma_f32_16x16x32_bf16 v[26:29], v[168:171], v[208:211], v[26:29]
	v_mfma_f32_16x16x32_bf16 v[14:17], v[160:163], v[216:219], v[14:17]
	v_mfma_f32_16x16x32_bf16 v[10:13], v[168:171], v[216:219], v[10:13]
	v_mfma_f32_16x16x32_bf16 v[54:57], v[172:175], v[188:191], v[54:57]
	v_mfma_f32_16x16x32_bf16 v[50:53], v[180:183], v[188:191], v[50:53]
	v_mfma_f32_16x16x32_bf16 v[38:41], v[172:175], v[196:199], v[38:41]
	v_mfma_f32_16x16x32_bf16 v[34:37], v[180:183], v[196:199], v[34:37]
	v_mfma_f32_16x16x32_bf16 v[22:25], v[172:175], v[204:207], v[22:25]
	v_mfma_f32_16x16x32_bf16 v[18:21], v[180:183], v[204:207], v[18:21]
	v_mfma_f32_16x16x32_bf16 v[6:9], v[172:175], v[212:215], v[6:9]
	v_mfma_f32_16x16x32_bf16 v[2:5], v[180:183], v[212:215], v[2:5]
	v_mfma_f32_16x16x32_bf16 v[54:57], v[176:179], v[192:195], v[54:57]
	v_mfma_f32_16x16x32_bf16 v[50:53], v[184:187], v[192:195], v[50:53]
	v_mfma_f32_16x16x32_bf16 v[38:41], v[176:179], v[200:203], v[38:41]
	v_mfma_f32_16x16x32_bf16 v[34:37], v[184:187], v[200:203], v[34:37]
	v_mfma_f32_16x16x32_bf16 v[22:25], v[176:179], v[208:211], v[22:25]
	v_mfma_f32_16x16x32_bf16 v[18:21], v[184:187], v[208:211], v[18:21]
	v_mfma_f32_16x16x32_bf16 v[6:9], v[176:179], v[216:219], v[6:9]
	v_mfma_f32_16x16x32_bf16 v[2:5], v[184:187], v[216:219], v[2:5]
	s_barrier
	s_add_u32 s52, s52, 0x10000
	s_addc_u32 s53, s53, 0
	s_add_u32 s26, s26, 0x100
	s_addc_u32 s27, s27, 0
	s_cmp_ge_u32 s57, s47
	s_cbranch_scc0 .LBB0_1716
	s_and_b64 vcc, exec, s[6:7]
	s_cbranch_vccz .LBB0_1719
	s_barrier

; #define PG8_STAGE(bufoff, gbase, voff) do { _Pragma("unroll") for (int _i = 0; _i < 2; ++_i) \
;         __builtin_amdgcn_global_load_lds((const unsigned*)((const char*)(gbase) + (voff)[_i]), (LAS unsigned*)(lds + (bufoff) + ldsw + _i * 8192), 16, 0, 0); } while (0)
; #define PG8_LDA(dst, b, h) do { _Pragma("unroll") for (int m = 0; m < 4; ++m) _Pragma("unroll") for (int k = 0; k < 2; ++k) dst[m][k] = *(const LAS bf16x8*)(lds + PG8_SA(b, h) + aoff + m * 2048 + k * 1024); } while (0)
; #define PG8_LDB(dst, b, h) do { _Pragma("unroll") for (int n = 0; n < 2; ++n) _Pragma("unroll") for (int k = 0; k < 2; ++k) dst[n][k] = *(const LAS bf16x8*)(lds + PG8_SB(b, h) + boff + n * 2048 + k * 1024); } while (0)
; #define PG8_WAIT_V(n) asm volatile("s_waitcnt vmcnt(" #n ")" ::: "memory")
; #define PG8_WAIT_L(n) asm volatile("s_waitcnt lgkmcnt(" #n ")" ::: "memory")
; template <class Epi, class Sched, bool ABLK = false, bool ALIGN_EPI = true, bool SP2 = true, bool BBLK = true>
; __device__ __forceinline__ void gemm_phase(LAS unsigned char* lds, const Gemm g, const Sched& S, const Epi& E) {
;     ...
;         const bool has_next = S.next(ui + 1, nxt);
;         const int nt = cur.nt;
;         const char* nuA = has_next ? a_unit(nxt) : uA; const int ntbA = has_next ? nxt.k0 / BK : tbA; const char* nB = has_next ? (const char*)g.Bt + (size_t)nxt.pn * tstepB + b_k0(nxt.k0) : cB;
;         for (int t = 0; t < nt; t += 2) {
;             const bool last = (t == nt - 2);
;             const char* a1 = a_tile(uA, tbA + t + 1);
;             const char* a2 = last ? a_tile(nuA, ntbA) : a_tile(uA, tbA + t + 2); const char* b2 = last ? nB : cB + (size_t)(t + 2) * kstepB;
;             const char* a3 = last ? a_tile(nuA, ntbA + 1) : a_tile(uA, tbA + t + 3); const char* b3 = b2 + kstepB;
;             if (last && has_next) S.a_ready(nxt);
;             if constexpr (SP2) {
;             PG8_LDB(B0, 0, 0); PG8_LDB(B1, 0, 1); PG8_SCHED; PG8_LDA(At, 0, 0); PG8_STAGE(PG8_SA(1, 1), a1 + hstepA, voffA);
;             PG8_WAIT_V(8); PG8_WAIT_L(0); PG8_BAR; PG8_MMA(0, 0, At, B0); PG8_MMA(0, 1, At, B1); PG8_BAR; PG8_SCHED;
;             PG8_LDA(At, 0, 1); PG8_STAGE(PG8_SB(0, 0), b2, voffB); PG8_STAGE(PG8_SB(0, 1), b2 + hstepB, voffB); PG8_STAGE(PG8_SA(0, 0), a2, voffA);
;             PG8_WAIT_V(8); PG8_WAIT_L(0); PG8_BAR; PG8_MMA(1, 0, At, B0); PG8_MMA(1, 1, At, B1); PG8_BAR; PG8_SCHED;
.LBB0_1841:
	ds_read_b128 v[172:175], v168
	ds_read_b128 v[176:179], v168 offset:1024
	ds_read_b128 v[180:183], v168 offset:2048
	ds_read_b128 v[184:187], v168 offset:3072
	ds_read_b128 v[188:191], v169
	ds_read_b128 v[192:195], v169 offset:1024
	ds_read_b128 v[196:199], v169 offset:2048
	ds_read_b128 v[200:203], v169 offset:3072
	ds_read_b128 v[204:207], v170
	ds_read_b128 v[208:211], v170 offset:1024
	ds_read_b128 v[212:215], v170 offset:2048
	ds_read_b128 v[216:219], v170 offset:3072
	ds_read_b128 v[220:223], v170 offset:4096
	ds_read_b128 v[224:227], v170 offset:5120
	ds_read_b128 v[228:231], v170 offset:6144
	ds_read_b128 v[232:235], v170 offset:7168
	s_ashr_i32 s11, s10, 31
	s_lshl_b64 s[4:5], s[10:11], 20
	s_add_u32 s16, s76, s4
	s_addc_u32 s17, s33, s5
	s_and_b64 s[4:5], s[18:19], exec
	s_cselect_b32 s4, s17, s27
	s_cselect_b32 s5, s16, s26
	s_ashr_i32 s15, s14, 31
	s_lshl_b64 s[20:21], s[14:15], 20
	s_add_u32 s20, s1, s20
	s_addc_u32 s21, s38, s21
	s_and_b64 s[30:31], s[18:19], exec
	s_cselect_b32 s11, s21, s29
	s_cselect_b32 s15, s20, s28
	s_add_u32 s23, s5, 0x80
	s_addc_u32 s51, s4, 0
	s_add_u32 s52, s28, 0x10000
	v_mov_b32_e32 v2, 0
	s_addc_u32 s53, s29, 0
	v_lshl_add_u64 v[164:165], s[26:27], 0, v[160:161]
	v_lshl_add_u64 v[166:167], s[26:27], 0, v[162:163]
	s_mov_b32 s54, -2
	s_mov_b64 s[28:29], 0
	s_add_u32 s30, s26, s28
	s_addc_u32 s31, s27, s29
	s_add_u32 s36, s30, 0x100
	s_addc_u32 s37, s31, 0
	s_add_u32 s30, s30, 0x180
	s_addc_u32 s31, s31, 0
	s_cmpk_eq_i32 s28, 0xf00
	s_cselect_b32 s31, s51, s31
	s_cselect_b32 s30, s23, s30
	s_cselect_b32 s35, s11, s53
	s_cselect_b32 s34, s15, s52
	s_cselect_b32 s37, s4, s37
	s_cselect_b32 s36, s5, s36
	s_mov_b32 m0, s47
	v_lshl_add_u64 v[236:237], v[164:165], 0, s[28:29]
	global_load_lds_dwordx4 v[236:237], off
	v_lshl_add_u64 v[236:237], v[166:167], 0, s[28:29]
	s_mov_b32 m0, s48
	s_nop 0
	global_load_lds_dwordx4 v[236:237], off
	s_waitcnt vmcnt(8) lgkmcnt(0)
	s_barrier
	v_mfma_f32_16x16x32_bf16 v[126:129], v[172:175], v[204:207], 0
	v_mfma_f32_16x16x32_bf16 v[122:125], v[180:183], v[204:207], 0
	v_mfma_f32_16x16x32_bf16 v[110:113], v[172:175], v[212:215], 0
	v_mfma_f32_16x16x32_bf16 v[106:109], v[180:183], v[212:215], 0
	v_mfma_f32_16x16x32_bf16 v[94:97], v[172:175], v[220:223], 0
	v_mfma_f32_16x16x32_bf16 v[90:93], v[180:183], v[220:223], 0
	v_mfma_f32_16x16x32_bf16 v[78:81], v[172:175], v[228:231], 0
	v_mfma_f32_16x16x32_bf16 v[74:77], v[180:183], v[228:231], 0
	v_mfma_f32_16x16x32_bf16 v[126:129], v[176:179], v[208:211], v[126:129]
	v_mfma_f32_16x16x32_bf16 v[122:125], v[184:187], v[208:211], v[122:125]
	v_mfma_f32_16x16x32_bf16 v[110:113], v[176:179], v[216:219], v[110:113]
	v_mfma_f32_16x16x32_bf16 v[106:109], v[184:187], v[216:219], v[106:109]
	v_mfma_f32_16x16x32_bf16 v[94:97], v[176:179], v[224:227], v[94:97]
	v_mfma_f32_16x16x32_bf16 v[90:93], v[184:187], v[224:227], v[90:93]
	v_mfma_f32_16x16x32_bf16 v[78:81], v[176:179], v[232:235], v[78:81]
	v_mfma_f32_16x16x32_bf16 v[74:77], v[184:187], v[232:235], v[74:77]
	v_mfma_f32_16x16x32_bf16 v[118:121], v[188:191], v[204:207], 0
	v_mfma_f32_16x16x32_bf16 v[114:117], v[196:199], v[204:207], 0
	v_mfma_f32_16x16x32_bf16 v[102:105], v[188:191], v[212:215], 0
	v_mfma_f32_16x16x32_bf16 v[98:101], v[196:199], v[212:215], 0
	v_mfma_f32_16x16x32_bf16 v[86:89], v[188:191], v[220:223], 0
	v_mfma_f32_16x16x32_bf16 v[82:85], v[196:199], v[220:223], 0
	v_mfma_f32_16x16x32_bf16 v[70:73], v[188:191], v[228:231], 0
	v_mfma_f32_16x16x32_bf16 v[66:69], v[196:199], v[228:231], 0
	v_mfma_f32_16x16x32_bf16 v[118:121], v[192:195], v[208:211], v[118:121]
	v_mfma_f32_16x16x32_bf16 v[114:117], v[200:203], v[208:211], v[114:117]
	v_mfma_f32_16x16x32_bf16 v[102:105], v[192:195], v[216:219], v[102:105]
	v_mfma_f32_16x16x32_bf16 v[98:101], v[200:203], v[216:219], v[98:101]
	v_mfma_f32_16x16x32_bf16 v[86:89], v[192:195], v[224:227], v[86:89]
	v_mfma_f32_16x16x32_bf16 v[82:85], v[200:203], v[224:227], v[82:85]
	v_mfma_f32_16x16x32_bf16 v[70:73], v[192:195], v[232:235], v[70:73]
	v_mfma_f32_16x16x32_bf16 v[66:69], v[200:203], v[232:235], v[66:69]
	s_barrier
	ds_read_b128 v[204:207], v170 offset:16384
	ds_read_b128 v[208:211], v170 offset:17408
	ds_read_b128 v[212:215], v170 offset:18432
	ds_read_b128 v[216:219], v170 offset:19456
	ds_read_b128 v[220:223], v170 offset:20480
	ds_read_b128 v[224:227], v170 offset:21504
	ds_read_b128 v[228:231], v170 offset:22528
	ds_read_b128 v[232:235], v170 offset:23552
	s_mov_b32 m0, s49
	s_add_u32 s56, s34, 0x4000
	global_load_lds_dwordx4 v134, s[34:35]
	s_mov_b32 m0, s50
	s_addc_u32 s57, s35, 0
	s_add_i32 s55, s73, s39
	global_load_lds_dwordx4 v130, s[34:35]
	s_mov_b32 m0, s55
	s_nop 0
	global_load_lds_dwordx4 v134, s[56:57]
	s_add_i32 m0, s55, 0x2000
	s_nop 0
	global_load_lds_dwordx4 v130, s[56:57]
	s_mov_b32 m0, s25
	s_nop 0
	global_load_lds_dwordx4 v136, s[36:37]
	s_mov_b32 m0, s40
	s_nop 0
	global_load_lds_dwordx4 v132, s[36:37]
	s_waitcnt vmcnt(8) lgkmcnt(0)
	s_barrier
; #define PG8_STAGE(bufoff, gbase, voff) do { _Pragma("unroll") for (int _i = 0; _i < 2; ++_i) \
;         __builtin_amdgcn_global_load_lds((const unsigned*)((const char*)(gbase) + (voff)[_i]), (LAS unsigned*)(lds + (bufoff) + ldsw + _i * 8192), 16, 0, 0); } while (0)
; #define PG8_LDA(dst, b, h) do { _Pragma("unroll") for (int m = 0; m < 4; ++m) _Pragma("unroll") for (int k = 0; k < 2; ++k) dst[m][k] = *(const LAS bf16x8*)(lds + PG8_SA(b, h) + aoff + m * 2048 + k * 1024); } while (0)
; #define PG8_LDB(dst, b, h) do { _Pragma("unroll") for (int n = 0; n < 2; ++n) _Pragma("unroll") for (int k = 0; k < 2; ++k) dst[n][k] = *(const LAS bf16x8*)(lds + PG8_SB(b, h) + boff + n * 2048 + k * 1024); } while (0)
; #define PG8_MMA(ai, bj, At, Bt) do { __builtin_amdgcn_s_setprio(1); _Pragma("unroll") for (int m = 0; m < 4; ++m) _Pragma("unroll") for (int n = 0; n < 2; ++n) _Pragma("unroll") for (int k = 0; k < 2; ++k) \
;         acc[ai][bj][m][n] = __builtin_amdgcn_mfma_f32_16x16x32_bf16(Bt[n][k], At[m][k], acc[ai][bj][m][n], 0, 0, 0); __builtin_amdgcn_s_setprio(0); } while (0)
; #define PG8_WAIT_V(n) asm volatile("s_waitcnt vmcnt(" #n ")" ::: "memory")
; #define PG8_WAIT_L(n) asm volatile("s_waitcnt lgkmcnt(" #n ")" ::: "memory")
; #define PG8_BAR __builtin_amdgcn_s_barrier()
; #define PG8_SCHED __builtin_amdgcn_sched_barrier(0)
; template <class Epi, class Sched, bool ABLK = false, bool ALIGN_EPI = true, bool SP2 = true, bool BBLK = true>
; __device__ __forceinline__ void gemm_phase(LAS unsigned char* lds, const Gemm g, const Sched& S, const Epi& E) {
;     ...
;             PG8_WAIT_V(8); PG8_WAIT_L(0); PG8_BAR; PG8_MMA(1, 0, At, B0); PG8_MMA(1, 1, At, B1); PG8_BAR; PG8_SCHED;
;             PG8_LDB(B0, 1, 0); PG8_LDB(B1, 1, 1); PG8_SCHED; PG8_LDA(At, 1, 0); PG8_STAGE(PG8_SA(0, 1), a2 + hstepA, voffA);
;             PG8_WAIT_V(8); PG8_WAIT_L(0); PG8_BAR; PG8_MMA(0, 0, At, B0); PG8_MMA(0, 1, At, B1); PG8_BAR; PG8_SCHED;
	v_mfma_f32_16x16x32_bf16 v[62:65], v[172:175], v[204:207], 0
	v_mfma_f32_16x16x32_bf16 v[58:61], v[180:183], v[204:207], 0
	v_mfma_f32_16x16x32_bf16 v[46:49], v[172:175], v[212:215], 0
	v_mfma_f32_16x16x32_bf16 v[42:45], v[180:183], v[212:215], 0
	v_mfma_f32_16x16x32_bf16 v[30:33], v[172:175], v[220:223], 0
	v_mfma_f32_16x16x32_bf16 v[26:29], v[180:183], v[220:223], 0
	v_mfma_f32_16x16x32_bf16 v[14:17], v[172:175], v[228:231], 0
	v_mfma_f32_16x16x32_bf16 v[10:13], v[180:183], v[228:231], 0
	v_mfma_f32_16x16x32_bf16 v[62:65], v[176:179], v[208:211], v[62:65]
	v_mfma_f32_16x16x32_bf16 v[58:61], v[184:187], v[208:211], v[58:61]
	v_mfma_f32_16x16x32_bf16 v[46:49], v[176:179], v[216:219], v[46:49]
	v_mfma_f32_16x16x32_bf16 v[42:45], v[184:187], v[216:219], v[42:45]
	v_mfma_f32_16x16x32_bf16 v[30:33], v[176:179], v[224:227], v[30:33]
	v_mfma_f32_16x16x32_bf16 v[26:29], v[184:187], v[224:227], v[26:29]
	v_mfma_f32_16x16x32_bf16 v[14:17], v[176:179], v[232:235], v[14:17]
	v_mfma_f32_16x16x32_bf16 v[10:13], v[184:187], v[232:235], v[10:13]
	v_mfma_f32_16x16x32_bf16 v[54:57], v[188:191], v[204:207], 0
	v_mfma_f32_16x16x32_bf16 v[50:53], v[196:199], v[204:207], 0
	v_mfma_f32_16x16x32_bf16 v[38:41], v[188:191], v[212:215], 0
	v_mfma_f32_16x16x32_bf16 v[34:37], v[196:199], v[212:215], 0
	v_mfma_f32_16x16x32_bf16 v[22:25], v[188:191], v[220:223], 0
	v_mfma_f32_16x16x32_bf16 v[18:21], v[196:199], v[220:223], 0
	v_mfma_f32_16x16x32_bf16 v[6:9], v[188:191], v[228:231], 0
	v_mfma_f32_16x16x32_bf16 v[2:5], v[196:199], v[228:231], 0
	v_mfma_f32_16x16x32_bf16 v[54:57], v[192:195], v[208:211], v[54:57]
	v_mfma_f32_16x16x32_bf16 v[50:53], v[200:203], v[208:211], v[50:53]
	v_mfma_f32_16x16x32_bf16 v[38:41], v[192:195], v[216:219], v[38:41]
	v_mfma_f32_16x16x32_bf16 v[34:37], v[200:203], v[216:219], v[34:37]
	v_mfma_f32_16x16x32_bf16 v[22:25], v[192:195], v[224:227], v[22:25]
	v_mfma_f32_16x16x32_bf16 v[18:21], v[200:203], v[224:227], v[18:21]
	v_mfma_f32_16x16x32_bf16 v[6:9], v[192:195], v[232:235], v[6:9]
	v_mfma_f32_16x16x32_bf16 v[2:5], v[200:203], v[232:235], v[2:5]
	s_barrier
	v_add_u32_e32 v171, s60, v1
	ds_read_b128 v[172:175], v171
	ds_read_b128 v[176:179], v171 offset:1024
	ds_read_b128 v[180:183], v171 offset:2048
	ds_read_b128 v[184:187], v171 offset:3072
	v_add_u32_e32 v171, s61, v1
	ds_read_b128 v[188:191], v171
	ds_read_b128 v[192:195], v171 offset:1024
	ds_read_b128 v[196:199], v171 offset:2048
	ds_read_b128 v[200:203], v171 offset:3072
	ds_read_b128 v[204:207], v170 offset:32768
	ds_read_b128 v[208:211], v170 offset:33792
	ds_read_b128 v[212:215], v170 offset:34816
	ds_read_b128 v[216:219], v170 offset:35840
	ds_read_b128 v[220:223], v170 offset:36864
	ds_read_b128 v[224:227], v170 offset:37888
	ds_read_b128 v[228:231], v170 offset:38912
	ds_read_b128 v[232:235], v170 offset:39936
	s_add_u32 s36, s36, 0x80000
	s_addc_u32 s37, s37, 0
	s_mov_b32 m0, s41
	s_nop 0
	global_load_lds_dwordx4 v136, s[36:37]
	s_mov_b32 m0, s42
	s_nop 0
	global_load_lds_dwordx4 v132, s[36:37]
	s_waitcnt vmcnt(8) lgkmcnt(0)
	s_barrier
	v_mfma_f32_16x16x32_bf16 v[126:129], v[172:175], v[204:207], v[126:129]
	v_mfma_f32_16x16x32_bf16 v[122:125], v[180:183], v[204:207], v[122:125]
	v_mfma_f32_16x16x32_bf16 v[110:113], v[172:175], v[212:215], v[110:113]
	v_mfma_f32_16x16x32_bf16 v[106:109], v[180:183], v[212:215], v[106:109]
	v_mfma_f32_16x16x32_bf16 v[94:97], v[172:175], v[220:223], v[94:97]
	v_mfma_f32_16x16x32_bf16 v[90:93], v[180:183], v[220:223], v[90:93]
	v_mfma_f32_16x16x32_bf16 v[78:81], v[172:175], v[228:231], v[78:81]
	v_mfma_f32_16x16x32_bf16 v[74:77], v[180:183], v[228:231], v[74:77]
	v_mfma_f32_16x16x32_bf16 v[126:129], v[176:179], v[208:211], v[126:129]
	v_mfma_f32_16x16x32_bf16 v[122:125], v[184:187], v[208:211], v[122:125]
	v_mfma_f32_16x16x32_bf16 v[110:113], v[176:179], v[216:219], v[110:113]
	v_mfma_f32_16x16x32_bf16 v[106:109], v[184:187], v[216:219], v[106:109]
	v_mfma_f32_16x16x32_bf16 v[94:97], v[176:179], v[224:227], v[94:97]
	v_mfma_f32_16x16x32_bf16 v[90:93], v[184:187], v[224:227], v[90:93]
	v_mfma_f32_16x16x32_bf16 v[78:81], v[176:179], v[232:235], v[78:81]
	v_mfma_f32_16x16x32_bf16 v[74:77], v[184:187], v[232:235], v[74:77]
	v_mfma_f32_16x16x32_bf16 v[118:121], v[188:191], v[204:207], v[118:121]
	v_mfma_f32_16x16x32_bf16 v[114:117], v[196:199], v[204:207], v[114:117]
	v_mfma_f32_16x16x32_bf16 v[102:105], v[188:191], v[212:215], v[102:105]
	v_mfma_f32_16x16x32_bf16 v[98:101], v[196:199], v[212:215], v[98:101]
	v_mfma_f32_16x16x32_bf16 v[86:89], v[188:191], v[220:223], v[86:89]
	v_mfma_f32_16x16x32_bf16 v[82:85], v[196:199], v[220:223], v[82:85]
	v_mfma_f32_16x16x32_bf16 v[70:73], v[188:191], v[228:231], v[70:73]
	v_mfma_f32_16x16x32_bf16 v[66:69], v[196:199], v[228:231], v[66:69]
	v_mfma_f32_16x16x32_bf16 v[118:121], v[192:195], v[208:211], v[118:121]
	v_mfma_f32_16x16x32_bf16 v[114:117], v[200:203], v[208:211], v[114:117]
	v_mfma_f32_16x16x32_bf16 v[102:105], v[192:195], v[216:219], v[102:105]
	v_mfma_f32_16x16x32_bf16 v[98:101], v[200:203], v[216:219], v[98:101]
	v_mfma_f32_16x16x32_bf16 v[86:89], v[192:195], v[224:227], v[86:89]
	v_mfma_f32_16x16x32_bf16 v[82:85], v[200:203], v[224:227], v[82:85]
	v_mfma_f32_16x16x32_bf16 v[70:73], v[192:195], v[232:235], v[70:73]
	v_mfma_f32_16x16x32_bf16 v[66:69], v[200:203], v[232:235], v[66:69]
	s_barrier
; #define PG8_STAGE(bufoff, gbase, voff) do { _Pragma("unroll") for (int _i = 0; _i < 2; ++_i) \
;         __builtin_amdgcn_global_load_lds((const unsigned*)((const char*)(gbase) + (voff)[_i]), (LAS unsigned*)(lds + (bufoff) + ldsw + _i * 8192), 16, 0, 0); } while (0)
; #define PG8_LDA(dst, b, h) do { _Pragma("unroll") for (int m = 0; m < 4; ++m) _Pragma("unroll") for (int k = 0; k < 2; ++k) dst[m][k] = *(const LAS bf16x8*)(lds + PG8_SA(b, h) + aoff + m * 2048 + k * 1024); } while (0)
; #define PG8_LDB(dst, b, h) do { _Pragma("unroll") for (int n = 0; n < 2; ++n) _Pragma("unroll") for (int k = 0; k < 2; ++k) dst[n][k] = *(const LAS bf16x8*)(lds + PG8_SB(b, h) + boff + n * 2048 + k * 1024); } while (0)
; #define PG8_MMA(ai, bj, At, Bt) do { __builtin_amdgcn_s_setprio(1); _Pragma("unroll") for (int m = 0; m < 4; ++m) _Pragma("unroll") for (int n = 0; n < 2; ++n) _Pragma("unroll") for (int k = 0; k < 2; ++k) \
;         acc[ai][bj][m][n] = __builtin_amdgcn_mfma_f32_16x16x32_bf16(Bt[n][k], At[m][k], acc[ai][bj][m][n], 0, 0, 0); __builtin_amdgcn_s_setprio(0); } while (0)
; #define PG8_BAR __builtin_amdgcn_s_barrier()
; template <class Epi, class Sched, bool ABLK = false, bool ALIGN_EPI = true, bool SP2 = true, bool BBLK = true>
; __device__ __forceinline__ void gemm_phase(LAS unsigned char* lds, const Gemm g, const Sched& S, const Epi& E) {
;     ...
;             PG8_LDB(B0, 0, 0); PG8_LDB(B1, 0, 1); PG8_SCHED; PG8_LDA(At, 0, 0); PG8_STAGE(PG8_SA(1, 1), a1 + hstepA, voffA);
;             PG8_WAIT_V(8); PG8_WAIT_L(0); PG8_BAR; PG8_MMA(0, 0, At, B0); PG8_MMA(0, 1, At, B1); PG8_BAR; PG8_SCHED;
;             PG8_LDA(At, 0, 1); PG8_STAGE(PG8_SB(0, 0), b2, voffB); PG8_STAGE(PG8_SB(0, 1), b2 + hstepB, voffB); PG8_STAGE(PG8_SA(0, 0), a2, voffA);
;             PG8_WAIT_V(8); PG8_WAIT_L(0); PG8_BAR; PG8_MMA(1, 0, At, B0); PG8_MMA(1, 1, At, B1); PG8_BAR; PG8_SCHED;
;             PG8_LDB(B0, 1, 0); PG8_LDB(B1, 1, 1); PG8_SCHED; PG8_LDA(At, 1, 0); PG8_STAGE(PG8_SA(0, 1), a2 + hstepA, voffA);
;             PG8_WAIT_V(8); PG8_WAIT_L(0); PG8_BAR; PG8_MMA(0, 0, At, B0); PG8_MMA(0, 1, At, B1); PG8_BAR; PG8_SCHED;
;             PG8_LDA(At, 1, 1); PG8_STAGE(PG8_SB(1, 0), b3, voffB); PG8_STAGE(PG8_SB(1, 1), b3 + hstepB, voffB); PG8_STAGE(PG8_SA(1, 0), a3, voffA);
;             PG8_WAIT_V(8); PG8_WAIT_L(0); PG8_BAR; PG8_MMA(1, 0, At, B0); PG8_MMA(1, 1, At, B1); PG8_BAR; PG8_SCHED;
	ds_read_b128 v[204:207], v170 offset:49152
	ds_read_b128 v[208:211], v170 offset:50176
	ds_read_b128 v[212:215], v170 offset:51200
	ds_read_b128 v[216:219], v170 offset:52224
	ds_read_b128 v[220:223], v170 offset:53248
	ds_read_b128 v[224:227], v170 offset:54272
	ds_read_b128 v[228:231], v170 offset:55296
	ds_read_b128 v[232:235], v170 offset:56320
	s_add_u32 s36, s34, 0x8000
	s_addc_u32 s37, s35, 0
	s_add_i32 s55, s60, s39
	s_mov_b32 m0, s55
	s_nop 0
	global_load_lds_dwordx4 v134, s[36:37]
	s_add_i32 m0, s55, 0x2000
	s_add_u32 s34, s34, 0xc000
	v_lshl_add_u64 v[236:237], s[36:37], 0, v[130:131]
	s_addc_u32 s35, s35, 0
	s_add_i32 s36, s61, s39
	global_load_lds_dwordx4 v[236:237], off
	s_mov_b32 m0, s36
	s_nop 0
	global_load_lds_dwordx4 v134, s[34:35]
	s_add_i32 m0, s36, 0x2000
	s_nop 0
	global_load_lds_dwordx4 v130, s[34:35]
	s_mov_b32 m0, s45
	s_nop 0
	global_load_lds_dwordx4 v136, s[30:31]
	s_mov_b32 m0, s46
	s_nop 0
	global_load_lds_dwordx4 v132, s[30:31]
	s_waitcnt vmcnt(8) lgkmcnt(0)
	s_barrier
	v_mfma_f32_16x16x32_bf16 v[62:65], v[172:175], v[204:207], v[62:65]
	v_mfma_f32_16x16x32_bf16 v[58:61], v[180:183], v[204:207], v[58:61]
	v_mfma_f32_16x16x32_bf16 v[46:49], v[172:175], v[212:215], v[46:49]
	v_mfma_f32_16x16x32_bf16 v[42:45], v[180:183], v[212:215], v[42:45]
	v_mfma_f32_16x16x32_bf16 v[30:33], v[172:175], v[220:223], v[30:33]
	v_mfma_f32_16x16x32_bf16 v[26:29], v[180:183], v[220:223], v[26:29]
	v_mfma_f32_16x16x32_bf16 v[14:17], v[172:175], v[228:231], v[14:17]
	v_mfma_f32_16x16x32_bf16 v[10:13], v[180:183], v[228:231], v[10:13]
	v_mfma_f32_16x16x32_bf16 v[62:65], v[176:179], v[208:211], v[62:65]
	v_mfma_f32_16x16x32_bf16 v[58:61], v[184:187], v[208:211], v[58:61]
	v_mfma_f32_16x16x32_bf16 v[46:49], v[176:179], v[216:219], v[46:49]
	v_mfma_f32_16x16x32_bf16 v[42:45], v[184:187], v[216:219], v[42:45]
	v_mfma_f32_16x16x32_bf16 v[30:33], v[176:179], v[224:227], v[30:33]
	v_mfma_f32_16x16x32_bf16 v[26:29], v[184:187], v[224:227], v[26:29]
	v_mfma_f32_16x16x32_bf16 v[14:17], v[176:179], v[232:235], v[14:17]
	v_mfma_f32_16x16x32_bf16 v[10:13], v[184:187], v[232:235], v[10:13]
	v_mfma_f32_16x16x32_bf16 v[54:57], v[188:191], v[204:207], v[54:57]
	v_mfma_f32_16x16x32_bf16 v[50:53], v[196:199], v[204:207], v[50:53]
	v_mfma_f32_16x16x32_bf16 v[38:41], v[188:191], v[212:215], v[38:41]
	v_mfma_f32_16x16x32_bf16 v[34:37], v[196:199], v[212:215], v[34:37]
	v_mfma_f32_16x16x32_bf16 v[22:25], v[188:191], v[220:223], v[22:25]
	v_mfma_f32_16x16x32_bf16 v[18:21], v[196:199], v[220:223], v[18:21]
	v_mfma_f32_16x16x32_bf16 v[6:9], v[188:191], v[228:231], v[6:9]
	v_mfma_f32_16x16x32_bf16 v[2:5], v[196:199], v[228:231], v[2:5]
	v_mfma_f32_16x16x32_bf16 v[54:57], v[192:195], v[208:211], v[54:57]
	v_mfma_f32_16x16x32_bf16 v[50:53], v[200:203], v[208:211], v[50:53]
	v_mfma_f32_16x16x32_bf16 v[38:41], v[192:195], v[216:219], v[38:41]
	v_mfma_f32_16x16x32_bf16 v[34:37], v[200:203], v[216:219], v[34:37]
	v_mfma_f32_16x16x32_bf16 v[22:25], v[192:195], v[224:227], v[22:25]
	v_mfma_f32_16x16x32_bf16 v[18:21], v[200:203], v[224:227], v[18:21]
	v_mfma_f32_16x16x32_bf16 v[6:9], v[192:195], v[232:235], v[6:9]
	v_mfma_f32_16x16x32_bf16 v[2:5], v[200:203], v[232:235], v[2:5]
	s_barrier
	s_add_i32 s54, s54, 2
	s_add_u32 s28, s28, 0x100
	s_addc_u32 s29, s29, 0
	s_add_u32 s52, s52, 0x10000
	s_addc_u32 s53, s53, 0
	s_cmp_gt_u32 s54, 29
.LBB0_1842:
	ds_read_b128 v[172:175], v168
	ds_read_b128 v[176:179], v168 offset:1024
	ds_read_b128 v[180:183], v168 offset:2048
	ds_read_b128 v[184:187], v168 offset:3072
	ds_read_b128 v[188:191], v169
	ds_read_b128 v[192:195], v169 offset:1024
	ds_read_b128 v[196:199], v169 offset:2048
	ds_read_b128 v[200:203], v169 offset:3072
	ds_read_b128 v[204:207], v170
	ds_read_b128 v[208:211], v170 offset:1024
	ds_read_b128 v[212:215], v170 offset:2048
	ds_read_b128 v[216:219], v170 offset:3072
	ds_read_b128 v[220:223], v170 offset:4096
	ds_read_b128 v[224:227], v170 offset:5120
	ds_read_b128 v[228:231], v170 offset:6144
	ds_read_b128 v[232:235], v170 offset:7168
	s_add_u32 s30, s26, s28
	s_addc_u32 s31, s27, s29
	s_add_u32 s36, s30, 0x100
	s_addc_u32 s37, s31, 0
	s_add_u32 s30, s30, 0x180
	s_addc_u32 s31, s31, 0
	s_cmpk_eq_i32 s28, 0xf00
	s_cselect_b32 s31, s51, s31
	s_cselect_b32 s30, s23, s30
	s_cselect_b32 s35, s11, s53
	s_cselect_b32 s34, s15, s52
	s_cselect_b32 s37, s4, s37
	s_cselect_b32 s36, s5, s36
	s_mov_b32 m0, s47
	v_lshl_add_u64 v[236:237], v[164:165], 0, s[28:29]
	global_load_lds_dwordx4 v[236:237], off
	v_lshl_add_u64 v[236:237], v[166:167], 0, s[28:29]
	s_mov_b32 m0, s48
	s_nop 0
	global_load_lds_dwordx4 v[236:237], off
	s_waitcnt vmcnt(8) lgkmcnt(0)
	s_barrier
; #define PG8_STAGE(bufoff, gbase, voff) do { _Pragma("unroll") for (int _i = 0; _i < 2; ++_i) \
;         __builtin_amdgcn_global_load_lds((const unsigned*)((const char*)(gbase) + (voff)[_i]), (LAS unsigned*)(lds + (bufoff) + ldsw + _i * 8192), 16, 0, 0); } while (0)
; #define PG8_LDA(dst, b, h) do { _Pragma("unroll") for (int m = 0; m < 4; ++m) _Pragma("unroll") for (int k = 0; k < 2; ++k) dst[m][k] = *(const LAS bf16x8*)(lds + PG8_SA(b, h) + aoff + m * 2048 + k * 1024); } while (0)
; #define PG8_MMA(ai, bj, At, Bt) do { __builtin_amdgcn_s_setprio(1); _Pragma("unroll") for (int m = 0; m < 4; ++m) _Pragma("unroll") for (int n = 0; n < 2; ++n) _Pragma("unroll") for (int k = 0; k < 2; ++k) \
;         acc[ai][bj][m][n] = __builtin_amdgcn_mfma_f32_16x16x32_bf16(Bt[n][k], At[m][k], acc[ai][bj][m][n], 0, 0, 0); __builtin_amdgcn_s_setprio(0); } while (0)
; #define PG8_WAIT_V(n) asm volatile("s_waitcnt vmcnt(" #n ")" ::: "memory")
; #define PG8_WAIT_L(n) asm volatile("s_waitcnt lgkmcnt(" #n ")" ::: "memory")
; #define PG8_BAR __builtin_amdgcn_s_barrier()
; #define PG8_SCHED __builtin_amdgcn_sched_barrier(0)
; template <class Epi, class Sched, bool ABLK = false, bool ALIGN_EPI = true, bool SP2 = true, bool BBLK = true>
; __device__ __forceinline__ void gemm_phase(LAS unsigned char* lds, const Gemm g, const Sched& S, const Epi& E) {
;     ...
;             PG8_WAIT_V(8); PG8_WAIT_L(0); PG8_BAR; PG8_MMA(0, 0, At, B0); PG8_MMA(0, 1, At, B1); PG8_BAR; PG8_SCHED;
;             PG8_LDA(At, 0, 1); PG8_STAGE(PG8_SB(0, 0), b2, voffB); PG8_STAGE(PG8_SB(0, 1), b2 + hstepB, voffB); PG8_STAGE(PG8_SA(0, 0), a2, voffA);
;             PG8_WAIT_V(8); PG8_WAIT_L(0); PG8_BAR; PG8_MMA(1, 0, At, B0); PG8_MMA(1, 1, At, B1); PG8_BAR; PG8_SCHED;
	v_mfma_f32_16x16x32_bf16 v[126:129], v[172:175], v[204:207], v[126:129]
	v_mfma_f32_16x16x32_bf16 v[122:125], v[180:183], v[204:207], v[122:125]
	v_mfma_f32_16x16x32_bf16 v[110:113], v[172:175], v[212:215], v[110:113]
	v_mfma_f32_16x16x32_bf16 v[106:109], v[180:183], v[212:215], v[106:109]
	v_mfma_f32_16x16x32_bf16 v[94:97], v[172:175], v[220:223], v[94:97]
	v_mfma_f32_16x16x32_bf16 v[90:93], v[180:183], v[220:223], v[90:93]
	v_mfma_f32_16x16x32_bf16 v[78:81], v[172:175], v[228:231], v[78:81]
	v_mfma_f32_16x16x32_bf16 v[74:77], v[180:183], v[228:231], v[74:77]
	v_mfma_f32_16x16x32_bf16 v[126:129], v[176:179], v[208:211], v[126:129]
	v_mfma_f32_16x16x32_bf16 v[122:125], v[184:187], v[208:211], v[122:125]
	v_mfma_f32_16x16x32_bf16 v[110:113], v[176:179], v[216:219], v[110:113]
	v_mfma_f32_16x16x32_bf16 v[106:109], v[184:187], v[216:219], v[106:109]
	v_mfma_f32_16x16x32_bf16 v[94:97], v[176:179], v[224:227], v[94:97]
	v_mfma_f32_16x16x32_bf16 v[90:93], v[184:187], v[224:227], v[90:93]
	v_mfma_f32_16x16x32_bf16 v[78:81], v[176:179], v[232:235], v[78:81]
	v_mfma_f32_16x16x32_bf16 v[74:77], v[184:187], v[232:235], v[74:77]
	v_mfma_f32_16x16x32_bf16 v[118:121], v[188:191], v[204:207], v[118:121]
	v_mfma_f32_16x16x32_bf16 v[114:117], v[196:199], v[204:207], v[114:117]
	v_mfma_f32_16x16x32_bf16 v[102:105], v[188:191], v[212:215], v[102:105]
	v_mfma_f32_16x16x32_bf16 v[98:101], v[196:199], v[212:215], v[98:101]
	v_mfma_f32_16x16x32_bf16 v[86:89], v[188:191], v[220:223], v[86:89]
	v_mfma_f32_16x16x32_bf16 v[82:85], v[196:199], v[220:223], v[82:85]
	v_mfma_f32_16x16x32_bf16 v[70:73], v[188:191], v[228:231], v[70:73]
	v_mfma_f32_16x16x32_bf16 v[66:69], v[196:199], v[228:231], v[66:69]
	v_mfma_f32_16x16x32_bf16 v[118:121], v[192:195], v[208:211], v[118:121]
	v_mfma_f32_16x16x32_bf16 v[114:117], v[200:203], v[208:211], v[114:117]
	v_mfma_f32_16x16x32_bf16 v[102:105], v[192:195], v[216:219], v[102:105]
	v_mfma_f32_16x16x32_bf16 v[98:101], v[200:203], v[216:219], v[98:101]
	v_mfma_f32_16x16x32_bf16 v[86:89], v[192:195], v[224:227], v[86:89]
	v_mfma_f32_16x16x32_bf16 v[82:85], v[200:203], v[224:227], v[82:85]
	v_mfma_f32_16x16x32_bf16 v[70:73], v[192:195], v[232:235], v[70:73]
	v_mfma_f32_16x16x32_bf16 v[66:69], v[200:203], v[232:235], v[66:69]
	s_barrier
	ds_read_b128 v[204:207], v170 offset:16384
	ds_read_b128 v[208:211], v170 offset:17408
	ds_read_b128 v[212:215], v170 offset:18432
	ds_read_b128 v[216:219], v170 offset:19456
	ds_read_b128 v[220:223], v170 offset:20480
	ds_read_b128 v[224:227], v170 offset:21504
	ds_read_b128 v[228:231], v170 offset:22528
	ds_read_b128 v[232:235], v170 offset:23552
	s_mov_b32 m0, s49
	s_add_u32 s56, s34, 0x4000
	global_load_lds_dwordx4 v134, s[34:35]
	s_mov_b32 m0, s50
	s_addc_u32 s57, s35, 0
	s_add_i32 s55, s73, s39
	global_load_lds_dwordx4 v130, s[34:35]
	s_mov_b32 m0, s55
	s_nop 0
	global_load_lds_dwordx4 v134, s[56:57]
	s_add_i32 m0, s55, 0x2000
	s_nop 0
	global_load_lds_dwordx4 v130, s[56:57]
	s_mov_b32 m0, s25
	s_nop 0
	global_load_lds_dwordx4 v136, s[36:37]
	s_mov_b32 m0, s40
	s_nop 0
	global_load_lds_dwordx4 v132, s[36:37]
	s_waitcnt vmcnt(8) lgkmcnt(0)
	s_barrier
	v_mfma_f32_16x16x32_bf16 v[62:65], v[172:175], v[204:207], v[62:65]
	v_mfma_f32_16x16x32_bf16 v[58:61], v[180:183], v[204:207], v[58:61]
	v_mfma_f32_16x16x32_bf16 v[46:49], v[172:175], v[212:215], v[46:49]
	v_mfma_f32_16x16x32_bf16 v[42:45], v[180:183], v[212:215], v[42:45]
	v_mfma_f32_16x16x32_bf16 v[30:33], v[172:175], v[220:223], v[30:33]
	v_mfma_f32_16x16x32_bf16 v[26:29], v[180:183], v[220:223], v[26:29]
	v_mfma_f32_16x16x32_bf16 v[14:17], v[172:175], v[228:231], v[14:17]
	v_mfma_f32_16x16x32_bf16 v[10:13], v[180:183], v[228:231], v[10:13]
	v_mfma_f32_16x16x32_bf16 v[62:65], v[176:179], v[208:211], v[62:65]
	v_mfma_f32_16x16x32_bf16 v[58:61], v[184:187], v[208:211], v[58:61]
	v_mfma_f32_16x16x32_bf16 v[46:49], v[176:179], v[216:219], v[46:49]
	v_mfma_f32_16x16x32_bf16 v[42:45], v[184:187], v[216:219], v[42:45]
	v_mfma_f32_16x16x32_bf16 v[30:33], v[176:179], v[224:227], v[30:33]
	v_mfma_f32_16x16x32_bf16 v[26:29], v[184:187], v[224:227], v[26:29]
	v_mfma_f32_16x16x32_bf16 v[14:17], v[176:179], v[232:235], v[14:17]
	v_mfma_f32_16x16x32_bf16 v[10:13], v[184:187], v[232:235], v[10:13]
	v_mfma_f32_16x16x32_bf16 v[54:57], v[188:191], v[204:207], v[54:57]
	v_mfma_f32_16x16x32_bf16 v[50:53], v[196:199], v[204:207], v[50:53]
	v_mfma_f32_16x16x32_bf16 v[38:41], v[188:191], v[212:215], v[38:41]
	v_mfma_f32_16x16x32_bf16 v[34:37], v[196:199], v[212:215], v[34:37]
	v_mfma_f32_16x16x32_bf16 v[22:25], v[188:191], v[220:223], v[22:25]
	v_mfma_f32_16x16x32_bf16 v[18:21], v[196:199], v[220:223], v[18:21]
	v_mfma_f32_16x16x32_bf16 v[6:9], v[188:191], v[228:231], v[6:9]
	v_mfma_f32_16x16x32_bf16 v[2:5], v[196:199], v[228:231], v[2:5]
	v_mfma_f32_16x16x32_bf16 v[54:57], v[192:195], v[208:211], v[54:57]
	v_mfma_f32_16x16x32_bf16 v[50:53], v[200:203], v[208:211], v[50:53]
	v_mfma_f32_16x16x32_bf16 v[38:41], v[192:195], v[216:219], v[38:41]
	v_mfma_f32_16x16x32_bf16 v[34:37], v[200:203], v[216:219], v[34:37]
	v_mfma_f32_16x16x32_bf16 v[22:25], v[192:195], v[224:227], v[22:25]
	v_mfma_f32_16x16x32_bf16 v[18:21], v[200:203], v[224:227], v[18:21]
	v_mfma_f32_16x16x32_bf16 v[6:9], v[192:195], v[232:235], v[6:9]
	v_mfma_f32_16x16x32_bf16 v[2:5], v[200:203], v[232:235], v[2:5]
	s_barrier
; #define PG8_STAGE(bufoff, gbase, voff) do { _Pragma("unroll") for (int _i = 0; _i < 2; ++_i) \
;         __builtin_amdgcn_global_load_lds((const unsigned*)((const char*)(gbase) + (voff)[_i]), (LAS unsigned*)(lds + (bufoff) + ldsw + _i * 8192), 16, 0, 0); } while (0)
; #define PG8_LDA(dst, b, h) do { _Pragma("unroll") for (int m = 0; m < 4; ++m) _Pragma("unroll") for (int k = 0; k < 2; ++k) dst[m][k] = *(const LAS bf16x8*)(lds + PG8_SA(b, h) + aoff + m * 2048 + k * 1024); } while (0)
; #define PG8_LDB(dst, b, h) do { _Pragma("unroll") for (int n = 0; n < 2; ++n) _Pragma("unroll") for (int k = 0; k < 2; ++k) dst[n][k] = *(const LAS bf16x8*)(lds + PG8_SB(b, h) + boff + n * 2048 + k * 1024); } while (0)
; #define PG8_MMA(ai, bj, At, Bt) do { __builtin_amdgcn_s_setprio(1); _Pragma("unroll") for (int m = 0; m < 4; ++m) _Pragma("unroll") for (int n = 0; n < 2; ++n) _Pragma("unroll") for (int k = 0; k < 2; ++k) \
;         acc[ai][bj][m][n] = __builtin_amdgcn_mfma_f32_16x16x32_bf16(Bt[n][k], At[m][k], acc[ai][bj][m][n], 0, 0, 0); __builtin_amdgcn_s_setprio(0); } while (0)
; #define PG8_WAIT_V(n) asm volatile("s_waitcnt vmcnt(" #n ")" ::: "memory")
; #define PG8_WAIT_L(n) asm volatile("s_waitcnt lgkmcnt(" #n ")" ::: "memory")
; #define PG8_BAR __builtin_amdgcn_s_barrier()
; #define PG8_SCHED __builtin_amdgcn_sched_barrier(0)
; template <class Epi, class Sched, bool ABLK = false, bool ALIGN_EPI = true, bool SP2 = true, bool BBLK = true>
; __device__ __forceinline__ void gemm_phase(LAS unsigned char* lds, const Gemm g, const Sched& S, const Epi& E) {
;     ...
;             PG8_LDB(B0, 1, 0); PG8_LDB(B1, 1, 1); PG8_SCHED; PG8_LDA(At, 1, 0); PG8_STAGE(PG8_SA(0, 1), a2 + hstepA, voffA);
;             PG8_WAIT_V(8); PG8_WAIT_L(0); PG8_BAR; PG8_MMA(0, 0, At, B0); PG8_MMA(0, 1, At, B1); PG8_BAR; PG8_SCHED;
;             PG8_LDA(At, 1, 1); PG8_STAGE(PG8_SB(1, 0), b3, voffB); PG8_STAGE(PG8_SB(1, 1), b3 + hstepB, voffB); PG8_STAGE(PG8_SA(1, 0), a3, voffA);
;             PG8_WAIT_V(8); PG8_WAIT_L(0); PG8_BAR; PG8_MMA(1, 0, At, B0); PG8_MMA(1, 1, At, B1); PG8_BAR; PG8_SCHED;
;     ...
;         if constexpr (ALIGN_EPI) { if (wr == 0) PG8_BAR; }
	v_add_u32_e32 v171, s60, v1
	ds_read_b128 v[172:175], v171
	ds_read_b128 v[176:179], v171 offset:1024
	ds_read_b128 v[180:183], v171 offset:2048
	ds_read_b128 v[184:187], v171 offset:3072
	v_add_u32_e32 v171, s61, v1
	ds_read_b128 v[188:191], v171
	ds_read_b128 v[192:195], v171 offset:1024
	ds_read_b128 v[196:199], v171 offset:2048
	ds_read_b128 v[200:203], v171 offset:3072
	ds_read_b128 v[204:207], v170 offset:32768
	ds_read_b128 v[208:211], v170 offset:33792
	ds_read_b128 v[212:215], v170 offset:34816
	ds_read_b128 v[216:219], v170 offset:35840
	ds_read_b128 v[220:223], v170 offset:36864
	ds_read_b128 v[224:227], v170 offset:37888
	ds_read_b128 v[228:231], v170 offset:38912
	ds_read_b128 v[232:235], v170 offset:39936
	s_add_u32 s36, s36, 0x80000
	s_addc_u32 s37, s37, 0
	s_mov_b32 m0, s41
	s_nop 0
	global_load_lds_dwordx4 v136, s[36:37]
	s_mov_b32 m0, s42
	s_nop 0
	global_load_lds_dwordx4 v132, s[36:37]
	s_waitcnt vmcnt(8) lgkmcnt(0)
	s_barrier
	v_mfma_f32_16x16x32_bf16 v[126:129], v[172:175], v[204:207], v[126:129]
	v_mfma_f32_16x16x32_bf16 v[122:125], v[180:183], v[204:207], v[122:125]
	v_mfma_f32_16x16x32_bf16 v[110:113], v[172:175], v[212:215], v[110:113]
	v_mfma_f32_16x16x32_bf16 v[106:109], v[180:183], v[212:215], v[106:109]
	v_mfma_f32_16x16x32_bf16 v[94:97], v[172:175], v[220:223], v[94:97]
	v_mfma_f32_16x16x32_bf16 v[90:93], v[180:183], v[220:223], v[90:93]
	v_mfma_f32_16x16x32_bf16 v[78:81], v[172:175], v[228:231], v[78:81]
	v_mfma_f32_16x16x32_bf16 v[74:77], v[180:183], v[228:231], v[74:77]
	v_mfma_f32_16x16x32_bf16 v[126:129], v[176:179], v[208:211], v[126:129]
	v_mfma_f32_16x16x32_bf16 v[122:125], v[184:187], v[208:211], v[122:125]
	v_mfma_f32_16x16x32_bf16 v[110:113], v[176:179], v[216:219], v[110:113]
	v_mfma_f32_16x16x32_bf16 v[106:109], v[184:187], v[216:219], v[106:109]
	v_mfma_f32_16x16x32_bf16 v[94:97], v[176:179], v[224:227], v[94:97]
	v_mfma_f32_16x16x32_bf16 v[90:93], v[184:187], v[224:227], v[90:93]
	v_mfma_f32_16x16x32_bf16 v[78:81], v[176:179], v[232:235], v[78:81]
	v_mfma_f32_16x16x32_bf16 v[74:77], v[184:187], v[232:235], v[74:77]
	v_mfma_f32_16x16x32_bf16 v[118:121], v[188:191], v[204:207], v[118:121]
	v_mfma_f32_16x16x32_bf16 v[114:117], v[196:199], v[204:207], v[114:117]
	v_mfma_f32_16x16x32_bf16 v[102:105], v[188:191], v[212:215], v[102:105]
	v_mfma_f32_16x16x32_bf16 v[98:101], v[196:199], v[212:215], v[98:101]
	v_mfma_f32_16x16x32_bf16 v[86:89], v[188:191], v[220:223], v[86:89]
	v_mfma_f32_16x16x32_bf16 v[82:85], v[196:199], v[220:223], v[82:85]
	v_mfma_f32_16x16x32_bf16 v[70:73], v[188:191], v[228:231], v[70:73]
	v_mfma_f32_16x16x32_bf16 v[66:69], v[196:199], v[228:231], v[66:69]
	v_mfma_f32_16x16x32_bf16 v[118:121], v[192:195], v[208:211], v[118:121]
	v_mfma_f32_16x16x32_bf16 v[114:117], v[200:203], v[208:211], v[114:117]
	v_mfma_f32_16x16x32_bf16 v[102:105], v[192:195], v[216:219], v[102:105]
	v_mfma_f32_16x16x32_bf16 v[98:101], v[200:203], v[216:219], v[98:101]
	v_mfma_f32_16x16x32_bf16 v[86:89], v[192:195], v[224:227], v[86:89]
	v_mfma_f32_16x16x32_bf16 v[82:85], v[200:203], v[224:227], v[82:85]
	v_mfma_f32_16x16x32_bf16 v[70:73], v[192:195], v[232:235], v[70:73]
	v_mfma_f32_16x16x32_bf16 v[66:69], v[200:203], v[232:235], v[66:69]
	s_barrier
	ds_read_b128 v[204:207], v170 offset:49152
	ds_read_b128 v[208:211], v170 offset:50176
	ds_read_b128 v[212:215], v170 offset:51200
	ds_read_b128 v[216:219], v170 offset:52224
	ds_read_b128 v[220:223], v170 offset:53248
	ds_read_b128 v[224:227], v170 offset:54272
	ds_read_b128 v[228:231], v170 offset:55296
	ds_read_b128 v[232:235], v170 offset:56320
	s_add_u32 s36, s34, 0x8000
	s_addc_u32 s37, s35, 0
	s_add_i32 s55, s60, s39
	s_mov_b32 m0, s55
	s_nop 0
	global_load_lds_dwordx4 v134, s[36:37]
	s_add_i32 m0, s55, 0x2000
	s_add_u32 s34, s34, 0xc000
	v_lshl_add_u64 v[236:237], s[36:37], 0, v[130:131]
	s_addc_u32 s35, s35, 0
	s_add_i32 s36, s61, s39
	global_load_lds_dwordx4 v[236:237], off
	s_mov_b32 m0, s36
	s_nop 0
	global_load_lds_dwordx4 v134, s[34:35]
	s_add_i32 m0, s36, 0x2000
	s_nop 0
	global_load_lds_dwordx4 v130, s[34:35]
	s_mov_b32 m0, s45
	s_nop 0
	global_load_lds_dwordx4 v136, s[30:31]
	s_mov_b32 m0, s46
	s_nop 0
	global_load_lds_dwordx4 v132, s[30:31]
	s_waitcnt vmcnt(8) lgkmcnt(0)
	s_barrier
	v_mfma_f32_16x16x32_bf16 v[62:65], v[172:175], v[204:207], v[62:65]
	v_mfma_f32_16x16x32_bf16 v[58:61], v[180:183], v[204:207], v[58:61]
	v_mfma_f32_16x16x32_bf16 v[46:49], v[172:175], v[212:215], v[46:49]
	v_mfma_f32_16x16x32_bf16 v[42:45], v[180:183], v[212:215], v[42:45]
	v_mfma_f32_16x16x32_bf16 v[30:33], v[172:175], v[220:223], v[30:33]
	v_mfma_f32_16x16x32_bf16 v[26:29], v[180:183], v[220:223], v[26:29]
	v_mfma_f32_16x16x32_bf16 v[14:17], v[172:175], v[228:231], v[14:17]
	v_mfma_f32_16x16x32_bf16 v[10:13], v[180:183], v[228:231], v[10:13]
	v_mfma_f32_16x16x32_bf16 v[62:65], v[176:179], v[208:211], v[62:65]
	v_mfma_f32_16x16x32_bf16 v[58:61], v[184:187], v[208:211], v[58:61]
	v_mfma_f32_16x16x32_bf16 v[46:49], v[176:179], v[216:219], v[46:49]
	v_mfma_f32_16x16x32_bf16 v[42:45], v[184:187], v[216:219], v[42:45]
	v_mfma_f32_16x16x32_bf16 v[30:33], v[176:179], v[224:227], v[30:33]
	v_mfma_f32_16x16x32_bf16 v[26:29], v[184:187], v[224:227], v[26:29]
	v_mfma_f32_16x16x32_bf16 v[14:17], v[176:179], v[232:235], v[14:17]
	v_mfma_f32_16x16x32_bf16 v[10:13], v[184:187], v[232:235], v[10:13]
	v_mfma_f32_16x16x32_bf16 v[54:57], v[188:191], v[204:207], v[54:57]
	v_mfma_f32_16x16x32_bf16 v[50:53], v[196:199], v[204:207], v[50:53]
	v_mfma_f32_16x16x32_bf16 v[38:41], v[188:191], v[212:215], v[38:41]
	v_mfma_f32_16x16x32_bf16 v[34:37], v[196:199], v[212:215], v[34:37]
	v_mfma_f32_16x16x32_bf16 v[22:25], v[188:191], v[220:223], v[22:25]
	v_mfma_f32_16x16x32_bf16 v[18:21], v[196:199], v[220:223], v[18:21]
	v_mfma_f32_16x16x32_bf16 v[6:9], v[188:191], v[228:231], v[6:9]
	v_mfma_f32_16x16x32_bf16 v[2:5], v[196:199], v[228:231], v[2:5]
	v_mfma_f32_16x16x32_bf16 v[54:57], v[192:195], v[208:211], v[54:57]
	v_mfma_f32_16x16x32_bf16 v[50:53], v[200:203], v[208:211], v[50:53]
	v_mfma_f32_16x16x32_bf16 v[38:41], v[192:195], v[216:219], v[38:41]
	v_mfma_f32_16x16x32_bf16 v[34:37], v[200:203], v[216:219], v[34:37]
	v_mfma_f32_16x16x32_bf16 v[22:25], v[192:195], v[224:227], v[22:25]
	v_mfma_f32_16x16x32_bf16 v[18:21], v[200:203], v[224:227], v[18:21]
	v_mfma_f32_16x16x32_bf16 v[6:9], v[192:195], v[232:235], v[6:9]
	v_mfma_f32_16x16x32_bf16 v[2:5], v[200:203], v[232:235], v[2:5]
	s_barrier
	s_add_i32 s54, s54, 2
	s_add_u32 s28, s28, 0x100
	s_addc_u32 s29, s29, 0
	s_add_u32 s52, s52, 0x10000
	s_addc_u32 s53, s53, 0
	s_cmp_gt_u32 s54, 29
	s_cbranch_scc0 .LBB0_1842
	s_and_b64 vcc, exec, s[6:7]
	s_cbranch_vccz .LBB0_1845
	s_barrier

; #define PG8_STAGE(bufoff, gbase, voff) do { _Pragma("unroll") for (int _i = 0; _i < 2; ++_i) \
;         __builtin_amdgcn_global_load_lds((const unsigned*)((const char*)(gbase) + (voff)[_i]), (LAS unsigned*)(lds + (bufoff) + ldsw + _i * 8192), 16, 0, 0); } while (0)
; #define PG8_LDA(dst, b, h) do { _Pragma("unroll") for (int m = 0; m < 4; ++m) _Pragma("unroll") for (int k = 0; k < 2; ++k) dst[m][k] = *(const LAS bf16x8*)(lds + PG8_SA(b, h) + aoff + m * 2048 + k * 1024); } while (0)
; #define PG8_LDB(dst, b, h) do { _Pragma("unroll") for (int n = 0; n < 2; ++n) _Pragma("unroll") for (int k = 0; k < 2; ++k) dst[n][k] = *(const LAS bf16x8*)(lds + PG8_SB(b, h) + boff + n * 2048 + k * 1024); } while (0)
; #define PG8_WAIT_V(n) asm volatile("s_waitcnt vmcnt(" #n ")" ::: "memory")
; #define PG8_WAIT_L(n) asm volatile("s_waitcnt lgkmcnt(" #n ")" ::: "memory")
; template <class Epi, class Sched, bool ABLK = false, bool ALIGN_EPI = true, bool SP2 = true, bool BBLK = true>
; __device__ __forceinline__ void gemm_phase(LAS unsigned char* lds, const Gemm g, const Sched& S, const Epi& E) {
;     ...
;         const bool has_next = S.next(ui + 1, nxt);
;         const int nt = cur.nt;
;         const char* nuA = has_next ? a_unit(nxt) : uA; const int ntbA = has_next ? nxt.k0 / BK : tbA; const char* nB = has_next ? (const char*)g.Bt + (size_t)nxt.pn * tstepB + b_k0(nxt.k0) : cB;
;         for (int t = 0; t < nt; t += 2) {
;             const bool last = (t == nt - 2);
;             const char* a1 = a_tile(uA, tbA + t + 1);
;             const char* a2 = last ? a_tile(nuA, ntbA) : a_tile(uA, tbA + t + 2); const char* b2 = last ? nB : cB + (size_t)(t + 2) * kstepB;
;             const char* a3 = last ? a_tile(nuA, ntbA + 1) : a_tile(uA, tbA + t + 3); const char* b3 = b2 + kstepB;
;             if (last && has_next) S.a_ready(nxt);
;             if constexpr (SP2) {
;             PG8_LDB(B0, 0, 0); PG8_LDB(B1, 0, 1); PG8_SCHED; PG8_LDA(At, 0, 0); PG8_STAGE(PG8_SA(1, 1), a1 + hstepA, voffA);
;             PG8_WAIT_V(8); PG8_WAIT_L(0); PG8_BAR; PG8_MMA(0, 0, At, B0); PG8_MMA(0, 1, At, B1); PG8_BAR; PG8_SCHED;
;             PG8_LDA(At, 0, 1); PG8_STAGE(PG8_SB(0, 0), b2, voffB); PG8_STAGE(PG8_SB(0, 1), b2 + hstepB, voffB); PG8_STAGE(PG8_SA(0, 0), a2, voffA);
;             PG8_WAIT_V(8); PG8_WAIT_L(0); PG8_BAR; PG8_MMA(1, 0, At, B0); PG8_MMA(1, 1, At, B1); PG8_BAR; PG8_SCHED;
.LBB0_1906:
	ds_read_b128 v[152:155], v148
	ds_read_b128 v[156:159], v148 offset:1024
	ds_read_b128 v[160:163], v148 offset:2048
	ds_read_b128 v[164:167], v148 offset:3072
	ds_read_b128 v[168:171], v149
	ds_read_b128 v[172:175], v149 offset:1024
	ds_read_b128 v[176:179], v149 offset:2048
	ds_read_b128 v[180:183], v149 offset:3072
	ds_read_b128 v[184:187], v150
	ds_read_b128 v[188:191], v150 offset:1024
	ds_read_b128 v[192:195], v150 offset:2048
	ds_read_b128 v[196:199], v150 offset:3072
	ds_read_b128 v[200:203], v150 offset:4096
	ds_read_b128 v[204:207], v150 offset:5120
	ds_read_b128 v[208:211], v150 offset:6144
	ds_read_b128 v[212:215], v150 offset:7168
	s_ashr_i32 s81, s80, 31
	s_andn2_b64 vcc, exec, s[4:5]
	s_lshl_b64 s[24:25], s[80:81], 22
	s_add_u32 s24, s62, s24
	s_addc_u32 s25, s83, s25
	s_and_b64 s[26:27], s[4:5], exec
	s_cselect_b32 s37, s25, s35
	s_cselect_b32 s50, s24, s34
	s_ashr_i32 s26, s0, 31
	s_lshr_b32 s26, s26, 26
	s_add_i32 s26, s0, s26
	s_ashr_i32 s26, s26, 6
	s_and_b64 s[28:29], s[4:5], exec
	s_cselect_b32 s38, s26, s36
	s_ashr_i32 s79, s78, 31
	s_lshl_b64 s[28:29], s[78:79], 22
	s_add_u32 s39, s1, s28
	s_addc_u32 s51, s33, s29
	s_ashr_i32 s27, s26, 31
	s_lshl_b64 s[28:29], s[26:27], 15
	s_add_u32 s28, s39, s28
	s_addc_u32 s29, s51, s29
	v_cndmask_b32_e64 v2, 0, 1, s[4:5]
	s_and_b64 s[4:5], s[4:5], exec
	s_cselect_b32 s4, s29, s31
	s_cselect_b32 s5, s28, s30
	s_ashr_i32 s39, s38, 31
	s_lshl_b64 s[38:39], s[38:39], 15
	s_add_u32 s27, s50, s38
	s_addc_u32 s50, s37, s39
	s_add_u32 s51, s27, 0x8000
	s_addc_u32 s52, s50, 0
	s_add_u32 s53, s30, 0x10000
	s_addc_u32 s54, s31, 0
	s_ashr_i32 s37, s36, 31
	v_cmp_ne_u32_e64 s[10:11], 1, v2
	s_lshl_b64 s[30:31], s[36:37], 15
	v_lshl_add_u64 v[2:3], s[34:35], 0, v[138:139]
	s_add_u32 s55, s34, s30
	v_lshl_add_u64 v[142:143], v[2:3], 0, s[30:31]
	v_lshl_add_u64 v[2:3], s[34:35], 0, v[140:141]
	s_addc_u32 s56, s35, s31
	v_lshl_add_u64 v[144:145], v[2:3], 0, s[30:31]
	s_lshl_b32 s30, s48, 15
	s_add_i32 s30, s30, 0xfff00000
	v_mov_b32_e32 v2, 0
	s_add_u32 s57, s30, 0xf0000
	s_mov_b32 s58, 0
	s_mov_b64 s[30:31], 0
	s_add_u32 s34, s55, s30
	s_addc_u32 s35, s56, s31
	s_add_u32 s38, s34, 0x10000
	s_addc_u32 s39, s35, 0
	s_add_i32 s58, s58, 2
	s_add_u32 s36, s53, s30
	s_addc_u32 s37, s54, s31
	s_add_u32 s34, s34, 0x18000
	s_addc_u32 s35, s35, 0
	s_cmp_eq_u32 s57, s30
	s_cselect_b32 s35, s52, s35
	s_cselect_b32 s34, s51, s34
	s_cselect_b32 s37, s4, s37
	s_cselect_b32 s36, s5, s36
	s_cselect_b32 s39, s50, s39
	s_cselect_b32 s38, s27, s38
	v_lshl_add_u64 v[216:217], v[142:143], 0, s[30:31]
	s_add_i32 m0, s41, 0xc000
	s_nop 0
	global_load_lds_dwordx4 v[216:217], off
	v_lshl_add_u64 v[216:217], v[144:145], 0, s[30:31]
	s_add_i32 m0, s41, 0xe000
	s_nop 0
	global_load_lds_dwordx4 v[216:217], off
	s_waitcnt vmcnt(8) lgkmcnt(0)
	s_barrier
	v_mfma_f32_16x16x32_bf16 v[126:129], v[152:155], v[184:187], 0
	v_mfma_f32_16x16x32_bf16 v[122:125], v[160:163], v[184:187], 0
	v_mfma_f32_16x16x32_bf16 v[110:113], v[152:155], v[192:195], 0
	v_mfma_f32_16x16x32_bf16 v[106:109], v[160:163], v[192:195], 0
	v_mfma_f32_16x16x32_bf16 v[94:97], v[152:155], v[200:203], 0
	v_mfma_f32_16x16x32_bf16 v[90:93], v[160:163], v[200:203], 0
	v_mfma_f32_16x16x32_bf16 v[78:81], v[152:155], v[208:211], 0
	v_mfma_f32_16x16x32_bf16 v[74:77], v[160:163], v[208:211], 0
	v_mfma_f32_16x16x32_bf16 v[126:129], v[156:159], v[188:191], v[126:129]
	v_mfma_f32_16x16x32_bf16 v[122:125], v[164:167], v[188:191], v[122:125]
	v_mfma_f32_16x16x32_bf16 v[110:113], v[156:159], v[196:199], v[110:113]
	v_mfma_f32_16x16x32_bf16 v[106:109], v[164:167], v[196:199], v[106:109]
	v_mfma_f32_16x16x32_bf16 v[94:97], v[156:159], v[204:207], v[94:97]
	v_mfma_f32_16x16x32_bf16 v[90:93], v[164:167], v[204:207], v[90:93]
	v_mfma_f32_16x16x32_bf16 v[78:81], v[156:159], v[212:215], v[78:81]
	v_mfma_f32_16x16x32_bf16 v[74:77], v[164:167], v[212:215], v[74:77]
	v_mfma_f32_16x16x32_bf16 v[118:121], v[168:171], v[184:187], 0
	v_mfma_f32_16x16x32_bf16 v[114:117], v[176:179], v[184:187], 0
	v_mfma_f32_16x16x32_bf16 v[102:105], v[168:171], v[192:195], 0
	v_mfma_f32_16x16x32_bf16 v[98:101], v[176:179], v[192:195], 0
	v_mfma_f32_16x16x32_bf16 v[86:89], v[168:171], v[200:203], 0
	v_mfma_f32_16x16x32_bf16 v[82:85], v[176:179], v[200:203], 0
	v_mfma_f32_16x16x32_bf16 v[70:73], v[168:171], v[208:211], 0
	v_mfma_f32_16x16x32_bf16 v[66:69], v[176:179], v[208:211], 0
	v_mfma_f32_16x16x32_bf16 v[118:121], v[172:175], v[188:191], v[118:121]
	v_mfma_f32_16x16x32_bf16 v[114:117], v[180:183], v[188:191], v[114:117]
	v_mfma_f32_16x16x32_bf16 v[102:105], v[172:175], v[196:199], v[102:105]
	v_mfma_f32_16x16x32_bf16 v[98:101], v[180:183], v[196:199], v[98:101]
	v_mfma_f32_16x16x32_bf16 v[86:89], v[172:175], v[204:207], v[86:89]
	v_mfma_f32_16x16x32_bf16 v[82:85], v[180:183], v[204:207], v[82:85]
	v_mfma_f32_16x16x32_bf16 v[70:73], v[172:175], v[212:215], v[70:73]
	v_mfma_f32_16x16x32_bf16 v[66:69], v[180:183], v[212:215], v[66:69]
	s_barrier
	ds_read_b128 v[184:187], v150 offset:16384
	ds_read_b128 v[188:191], v150 offset:17408
	ds_read_b128 v[192:195], v150 offset:18432
	ds_read_b128 v[196:199], v150 offset:19456
	ds_read_b128 v[200:203], v150 offset:20480
	ds_read_b128 v[204:207], v150 offset:21504
	ds_read_b128 v[208:211], v150 offset:22528
	ds_read_b128 v[212:215], v150 offset:23552
	s_add_i32 s59, s72, s40
	s_mov_b32 m0, s59
	s_nop 0
	global_load_lds_dwordx4 v130, s[36:37]
	s_add_i32 m0, s59, 0x2000
	s_add_u32 s64, s36, 0x4000
	s_addc_u32 s65, s37, 0
	s_add_i32 s59, s73, s40
	global_load_lds_dwordx4 v132, s[36:37]
	s_mov_b32 m0, s59
	s_nop 0
	global_load_lds_dwordx4 v130, s[64:65]
	s_add_i32 m0, s59, 0x2000
	s_nop 0
	global_load_lds_dwordx4 v132, s[64:65]
	s_mov_b32 m0, s41
	s_nop 0
	global_load_lds_dwordx4 v130, s[38:39]
	s_mov_b32 m0, s42
	s_nop 0
	global_load_lds_dwordx4 v132, s[38:39]
	s_waitcnt vmcnt(8) lgkmcnt(0)
	s_barrier
; #define PG8_STAGE(bufoff, gbase, voff) do { _Pragma("unroll") for (int _i = 0; _i < 2; ++_i) \
;         __builtin_amdgcn_global_load_lds((const unsigned*)((const char*)(gbase) + (voff)[_i]), (LAS unsigned*)(lds + (bufoff) + ldsw + _i * 8192), 16, 0, 0); } while (0)
; #define PG8_LDA(dst, b, h) do { _Pragma("unroll") for (int m = 0; m < 4; ++m) _Pragma("unroll") for (int k = 0; k < 2; ++k) dst[m][k] = *(const LAS bf16x8*)(lds + PG8_SA(b, h) + aoff + m * 2048 + k * 1024); } while (0)
; #define PG8_LDB(dst, b, h) do { _Pragma("unroll") for (int n = 0; n < 2; ++n) _Pragma("unroll") for (int k = 0; k < 2; ++k) dst[n][k] = *(const LAS bf16x8*)(lds + PG8_SB(b, h) + boff + n * 2048 + k * 1024); } while (0)
; #define PG8_MMA(ai, bj, At, Bt) do { __builtin_amdgcn_s_setprio(1); _Pragma("unroll") for (int m = 0; m < 4; ++m) _Pragma("unroll") for (int n = 0; n < 2; ++n) _Pragma("unroll") for (int k = 0; k < 2; ++k) \
;         acc[ai][bj][m][n] = __builtin_amdgcn_mfma_f32_16x16x32_bf16(Bt[n][k], At[m][k], acc[ai][bj][m][n], 0, 0, 0); __builtin_amdgcn_s_setprio(0); } while (0)
; #define PG8_WAIT_V(n) asm volatile("s_waitcnt vmcnt(" #n ")" ::: "memory")
; #define PG8_WAIT_L(n) asm volatile("s_waitcnt lgkmcnt(" #n ")" ::: "memory")
; #define PG8_BAR __builtin_amdgcn_s_barrier()
; #define PG8_SCHED __builtin_amdgcn_sched_barrier(0)
; template <class Epi, class Sched, bool ABLK = false, bool ALIGN_EPI = true, bool SP2 = true, bool BBLK = true>
; __device__ __forceinline__ void gemm_phase(LAS unsigned char* lds, const Gemm g, const Sched& S, const Epi& E) {
;     ...
;             PG8_WAIT_V(8); PG8_WAIT_L(0); PG8_BAR; PG8_MMA(1, 0, At, B0); PG8_MMA(1, 1, At, B1); PG8_BAR; PG8_SCHED;
;             PG8_LDB(B0, 1, 0); PG8_LDB(B1, 1, 1); PG8_SCHED; PG8_LDA(At, 1, 0); PG8_STAGE(PG8_SA(0, 1), a2 + hstepA, voffA);
;             PG8_WAIT_V(8); PG8_WAIT_L(0); PG8_BAR; PG8_MMA(0, 0, At, B0); PG8_MMA(0, 1, At, B1); PG8_BAR; PG8_SCHED;
	v_mfma_f32_16x16x32_bf16 v[62:65], v[152:155], v[184:187], 0
	v_mfma_f32_16x16x32_bf16 v[58:61], v[160:163], v[184:187], 0
	v_mfma_f32_16x16x32_bf16 v[46:49], v[152:155], v[192:195], 0
	v_mfma_f32_16x16x32_bf16 v[42:45], v[160:163], v[192:195], 0
	v_mfma_f32_16x16x32_bf16 v[30:33], v[152:155], v[200:203], 0
	v_mfma_f32_16x16x32_bf16 v[26:29], v[160:163], v[200:203], 0
	v_mfma_f32_16x16x32_bf16 v[14:17], v[152:155], v[208:211], 0
	v_mfma_f32_16x16x32_bf16 v[10:13], v[160:163], v[208:211], 0
	v_mfma_f32_16x16x32_bf16 v[62:65], v[156:159], v[188:191], v[62:65]
	v_mfma_f32_16x16x32_bf16 v[58:61], v[164:167], v[188:191], v[58:61]
	v_mfma_f32_16x16x32_bf16 v[46:49], v[156:159], v[196:199], v[46:49]
	v_mfma_f32_16x16x32_bf16 v[42:45], v[164:167], v[196:199], v[42:45]
	v_mfma_f32_16x16x32_bf16 v[30:33], v[156:159], v[204:207], v[30:33]
	v_mfma_f32_16x16x32_bf16 v[26:29], v[164:167], v[204:207], v[26:29]
	v_mfma_f32_16x16x32_bf16 v[14:17], v[156:159], v[212:215], v[14:17]
	v_mfma_f32_16x16x32_bf16 v[10:13], v[164:167], v[212:215], v[10:13]
	v_mfma_f32_16x16x32_bf16 v[54:57], v[168:171], v[184:187], 0
	v_mfma_f32_16x16x32_bf16 v[50:53], v[176:179], v[184:187], 0
	v_mfma_f32_16x16x32_bf16 v[38:41], v[168:171], v[192:195], 0
	v_mfma_f32_16x16x32_bf16 v[34:37], v[176:179], v[192:195], 0
	v_mfma_f32_16x16x32_bf16 v[22:25], v[168:171], v[200:203], 0
	v_mfma_f32_16x16x32_bf16 v[18:21], v[176:179], v[200:203], 0
	v_mfma_f32_16x16x32_bf16 v[6:9], v[168:171], v[208:211], 0
	v_mfma_f32_16x16x32_bf16 v[2:5], v[176:179], v[208:211], 0
	v_mfma_f32_16x16x32_bf16 v[54:57], v[172:175], v[188:191], v[54:57]
	v_mfma_f32_16x16x32_bf16 v[50:53], v[180:183], v[188:191], v[50:53]
	v_mfma_f32_16x16x32_bf16 v[38:41], v[172:175], v[196:199], v[38:41]
	v_mfma_f32_16x16x32_bf16 v[34:37], v[180:183], v[196:199], v[34:37]
	v_mfma_f32_16x16x32_bf16 v[22:25], v[172:175], v[204:207], v[22:25]
	v_mfma_f32_16x16x32_bf16 v[18:21], v[180:183], v[204:207], v[18:21]
	v_mfma_f32_16x16x32_bf16 v[6:9], v[172:175], v[212:215], v[6:9]
	v_mfma_f32_16x16x32_bf16 v[2:5], v[180:183], v[212:215], v[2:5]
	s_barrier
	v_add_u32_e32 v151, s60, v146
	ds_read_b128 v[152:155], v151
	ds_read_b128 v[156:159], v151 offset:1024
	ds_read_b128 v[160:163], v151 offset:2048
	ds_read_b128 v[164:167], v151 offset:3072
	v_add_u32_e32 v151, s61, v146
	ds_read_b128 v[168:171], v151
	ds_read_b128 v[172:175], v151 offset:1024
	ds_read_b128 v[176:179], v151 offset:2048
	ds_read_b128 v[180:183], v151 offset:3072
	ds_read_b128 v[184:187], v150 offset:32768
	ds_read_b128 v[188:191], v150 offset:33792
	ds_read_b128 v[192:195], v150 offset:34816
	ds_read_b128 v[196:199], v150 offset:35840
	ds_read_b128 v[200:203], v150 offset:36864
	ds_read_b128 v[204:207], v150 offset:37888
	ds_read_b128 v[208:211], v150 offset:38912
	ds_read_b128 v[212:215], v150 offset:39936
	s_add_u32 s38, s38, 0x4000
	s_addc_u32 s39, s39, 0
	s_mov_b32 m0, s43
	s_nop 0
	global_load_lds_dwordx4 v130, s[38:39]
	s_mov_b32 m0, s44
	s_nop 0
	global_load_lds_dwordx4 v132, s[38:39]
	s_waitcnt vmcnt(8) lgkmcnt(0)
	s_barrier
	v_mfma_f32_16x16x32_bf16 v[126:129], v[152:155], v[184:187], v[126:129]
	v_mfma_f32_16x16x32_bf16 v[122:125], v[160:163], v[184:187], v[122:125]
	v_mfma_f32_16x16x32_bf16 v[110:113], v[152:155], v[192:195], v[110:113]
	v_mfma_f32_16x16x32_bf16 v[106:109], v[160:163], v[192:195], v[106:109]
	v_mfma_f32_16x16x32_bf16 v[94:97], v[152:155], v[200:203], v[94:97]
	v_mfma_f32_16x16x32_bf16 v[90:93], v[160:163], v[200:203], v[90:93]
	v_mfma_f32_16x16x32_bf16 v[78:81], v[152:155], v[208:211], v[78:81]
	v_mfma_f32_16x16x32_bf16 v[74:77], v[160:163], v[208:211], v[74:77]
	v_mfma_f32_16x16x32_bf16 v[126:129], v[156:159], v[188:191], v[126:129]
	v_mfma_f32_16x16x32_bf16 v[122:125], v[164:167], v[188:191], v[122:125]
	v_mfma_f32_16x16x32_bf16 v[110:113], v[156:159], v[196:199], v[110:113]
	v_mfma_f32_16x16x32_bf16 v[106:109], v[164:167], v[196:199], v[106:109]
	v_mfma_f32_16x16x32_bf16 v[94:97], v[156:159], v[204:207], v[94:97]
	v_mfma_f32_16x16x32_bf16 v[90:93], v[164:167], v[204:207], v[90:93]
	v_mfma_f32_16x16x32_bf16 v[78:81], v[156:159], v[212:215], v[78:81]
	v_mfma_f32_16x16x32_bf16 v[74:77], v[164:167], v[212:215], v[74:77]
	v_mfma_f32_16x16x32_bf16 v[118:121], v[168:171], v[184:187], v[118:121]
	v_mfma_f32_16x16x32_bf16 v[114:117], v[176:179], v[184:187], v[114:117]
	v_mfma_f32_16x16x32_bf16 v[102:105], v[168:171], v[192:195], v[102:105]
	v_mfma_f32_16x16x32_bf16 v[98:101], v[176:179], v[192:195], v[98:101]
	v_mfma_f32_16x16x32_bf16 v[86:89], v[168:171], v[200:203], v[86:89]
	v_mfma_f32_16x16x32_bf16 v[82:85], v[176:179], v[200:203], v[82:85]
	v_mfma_f32_16x16x32_bf16 v[70:73], v[168:171], v[208:211], v[70:73]
	v_mfma_f32_16x16x32_bf16 v[66:69], v[176:179], v[208:211], v[66:69]
	v_mfma_f32_16x16x32_bf16 v[118:121], v[172:175], v[188:191], v[118:121]
	v_mfma_f32_16x16x32_bf16 v[114:117], v[180:183], v[188:191], v[114:117]
	v_mfma_f32_16x16x32_bf16 v[102:105], v[172:175], v[196:199], v[102:105]
	v_mfma_f32_16x16x32_bf16 v[98:101], v[180:183], v[196:199], v[98:101]
	v_mfma_f32_16x16x32_bf16 v[86:89], v[172:175], v[204:207], v[86:89]
	v_mfma_f32_16x16x32_bf16 v[82:85], v[180:183], v[204:207], v[82:85]
	v_mfma_f32_16x16x32_bf16 v[70:73], v[172:175], v[212:215], v[70:73]
	v_mfma_f32_16x16x32_bf16 v[66:69], v[180:183], v[212:215], v[66:69]
	s_barrier
; #define PG8_STAGE(bufoff, gbase, voff) do { _Pragma("unroll") for (int _i = 0; _i < 2; ++_i) \
;         __builtin_amdgcn_global_load_lds((const unsigned*)((const char*)(gbase) + (voff)[_i]), (LAS unsigned*)(lds + (bufoff) + ldsw + _i * 8192), 16, 0, 0); } while (0)
; #define PG8_LDA(dst, b, h) do { _Pragma("unroll") for (int m = 0; m < 4; ++m) _Pragma("unroll") for (int k = 0; k < 2; ++k) dst[m][k] = *(const LAS bf16x8*)(lds + PG8_SA(b, h) + aoff + m * 2048 + k * 1024); } while (0)
; #define PG8_LDB(dst, b, h) do { _Pragma("unroll") for (int n = 0; n < 2; ++n) _Pragma("unroll") for (int k = 0; k < 2; ++k) dst[n][k] = *(const LAS bf16x8*)(lds + PG8_SB(b, h) + boff + n * 2048 + k * 1024); } while (0)
; #define PG8_MMA(ai, bj, At, Bt) do { __builtin_amdgcn_s_setprio(1); _Pragma("unroll") for (int m = 0; m < 4; ++m) _Pragma("unroll") for (int n = 0; n < 2; ++n) _Pragma("unroll") for (int k = 0; k < 2; ++k) \
;         acc[ai][bj][m][n] = __builtin_amdgcn_mfma_f32_16x16x32_bf16(Bt[n][k], At[m][k], acc[ai][bj][m][n], 0, 0, 0); __builtin_amdgcn_s_setprio(0); } while (0)
; #define PG8_BAR __builtin_amdgcn_s_barrier()
; template <class Epi, class Sched, bool ABLK = false, bool ALIGN_EPI = true, bool SP2 = true, bool BBLK = true>
; __device__ __forceinline__ void gemm_phase(LAS unsigned char* lds, const Gemm g, const Sched& S, const Epi& E) {
;     ...
;             PG8_LDB(B0, 0, 0); PG8_LDB(B1, 0, 1); PG8_SCHED; PG8_LDA(At, 0, 0); PG8_STAGE(PG8_SA(1, 1), a1 + hstepA, voffA);
;             PG8_WAIT_V(8); PG8_WAIT_L(0); PG8_BAR; PG8_MMA(0, 0, At, B0); PG8_MMA(0, 1, At, B1); PG8_BAR; PG8_SCHED;
;             PG8_LDA(At, 0, 1); PG8_STAGE(PG8_SB(0, 0), b2, voffB); PG8_STAGE(PG8_SB(0, 1), b2 + hstepB, voffB); PG8_STAGE(PG8_SA(0, 0), a2, voffA);
;             PG8_WAIT_V(8); PG8_WAIT_L(0); PG8_BAR; PG8_MMA(1, 0, At, B0); PG8_MMA(1, 1, At, B1); PG8_BAR; PG8_SCHED;
;             PG8_LDB(B0, 1, 0); PG8_LDB(B1, 1, 1); PG8_SCHED; PG8_LDA(At, 1, 0); PG8_STAGE(PG8_SA(0, 1), a2 + hstepA, voffA);
;             PG8_WAIT_V(8); PG8_WAIT_L(0); PG8_BAR; PG8_MMA(0, 0, At, B0); PG8_MMA(0, 1, At, B1); PG8_BAR; PG8_SCHED;
;             PG8_LDA(At, 1, 1); PG8_STAGE(PG8_SB(1, 0), b3, voffB); PG8_STAGE(PG8_SB(1, 1), b3 + hstepB, voffB); PG8_STAGE(PG8_SA(1, 0), a3, voffA);
;             PG8_WAIT_V(8); PG8_WAIT_L(0); PG8_BAR; PG8_MMA(1, 0, At, B0); PG8_MMA(1, 1, At, B1); PG8_BAR; PG8_SCHED;
	ds_read_b128 v[184:187], v150 offset:49152
	ds_read_b128 v[188:191], v150 offset:50176
	ds_read_b128 v[192:195], v150 offset:51200
	ds_read_b128 v[196:199], v150 offset:52224
	ds_read_b128 v[200:203], v150 offset:53248
	ds_read_b128 v[204:207], v150 offset:54272
	ds_read_b128 v[208:211], v150 offset:55296
	ds_read_b128 v[212:215], v150 offset:56320
	s_add_u32 s38, s36, 0x8000
	s_addc_u32 s39, s37, 0
	s_add_i32 s59, s60, s40
	s_mov_b32 m0, s59
	s_nop 0
	global_load_lds_dwordx4 v130, s[38:39]
	s_add_i32 m0, s59, 0x2000
	s_add_u32 s36, s36, 0xc000
	v_lshl_add_u64 v[216:217], s[38:39], 0, v[132:133]
	s_addc_u32 s37, s37, 0
	s_add_i32 s38, s61, s40
	global_load_lds_dwordx4 v[216:217], off
	s_mov_b32 m0, s38
	s_nop 0
	global_load_lds_dwordx4 v130, s[36:37]
	s_add_i32 m0, s38, 0x2000
	s_nop 0
	global_load_lds_dwordx4 v132, s[36:37]
	s_mov_b32 m0, s45
	s_nop 0
	global_load_lds_dwordx4 v130, s[34:35]
	s_mov_b32 m0, s46
	s_nop 0
	global_load_lds_dwordx4 v132, s[34:35]
	s_waitcnt vmcnt(8) lgkmcnt(0)
	s_barrier
	v_mfma_f32_16x16x32_bf16 v[62:65], v[152:155], v[184:187], v[62:65]
	v_mfma_f32_16x16x32_bf16 v[58:61], v[160:163], v[184:187], v[58:61]
	v_mfma_f32_16x16x32_bf16 v[46:49], v[152:155], v[192:195], v[46:49]
	v_mfma_f32_16x16x32_bf16 v[42:45], v[160:163], v[192:195], v[42:45]
	v_mfma_f32_16x16x32_bf16 v[30:33], v[152:155], v[200:203], v[30:33]
	v_mfma_f32_16x16x32_bf16 v[26:29], v[160:163], v[200:203], v[26:29]
	v_mfma_f32_16x16x32_bf16 v[14:17], v[152:155], v[208:211], v[14:17]
	v_mfma_f32_16x16x32_bf16 v[10:13], v[160:163], v[208:211], v[10:13]
	v_mfma_f32_16x16x32_bf16 v[62:65], v[156:159], v[188:191], v[62:65]
	v_mfma_f32_16x16x32_bf16 v[58:61], v[164:167], v[188:191], v[58:61]
	v_mfma_f32_16x16x32_bf16 v[46:49], v[156:159], v[196:199], v[46:49]
	v_mfma_f32_16x16x32_bf16 v[42:45], v[164:167], v[196:199], v[42:45]
	v_mfma_f32_16x16x32_bf16 v[30:33], v[156:159], v[204:207], v[30:33]
	v_mfma_f32_16x16x32_bf16 v[26:29], v[164:167], v[204:207], v[26:29]
	v_mfma_f32_16x16x32_bf16 v[14:17], v[156:159], v[212:215], v[14:17]
	v_mfma_f32_16x16x32_bf16 v[10:13], v[164:167], v[212:215], v[10:13]
	v_mfma_f32_16x16x32_bf16 v[54:57], v[168:171], v[184:187], v[54:57]
	v_mfma_f32_16x16x32_bf16 v[50:53], v[176:179], v[184:187], v[50:53]
	v_mfma_f32_16x16x32_bf16 v[38:41], v[168:171], v[192:195], v[38:41]
	v_mfma_f32_16x16x32_bf16 v[34:37], v[176:179], v[192:195], v[34:37]
	v_mfma_f32_16x16x32_bf16 v[22:25], v[168:171], v[200:203], v[22:25]
	v_mfma_f32_16x16x32_bf16 v[18:21], v[176:179], v[200:203], v[18:21]
	v_mfma_f32_16x16x32_bf16 v[6:9], v[168:171], v[208:211], v[6:9]
	v_mfma_f32_16x16x32_bf16 v[2:5], v[176:179], v[208:211], v[2:5]
	v_mfma_f32_16x16x32_bf16 v[54:57], v[172:175], v[188:191], v[54:57]
	v_mfma_f32_16x16x32_bf16 v[50:53], v[180:183], v[188:191], v[50:53]
	v_mfma_f32_16x16x32_bf16 v[38:41], v[172:175], v[196:199], v[38:41]
	v_mfma_f32_16x16x32_bf16 v[34:37], v[180:183], v[196:199], v[34:37]
	v_mfma_f32_16x16x32_bf16 v[22:25], v[172:175], v[204:207], v[22:25]
	v_mfma_f32_16x16x32_bf16 v[18:21], v[180:183], v[204:207], v[18:21]
	v_mfma_f32_16x16x32_bf16 v[6:9], v[172:175], v[212:215], v[6:9]
	v_mfma_f32_16x16x32_bf16 v[2:5], v[180:183], v[212:215], v[2:5]
	s_barrier
	s_add_u32 s30, s30, 0x10000
	s_addc_u32 s31, s31, 0
	s_cmp_ge_u32 s58, s48
.LBB0_1907:
	ds_read_b128 v[152:155], v148
	ds_read_b128 v[156:159], v148 offset:1024
	ds_read_b128 v[160:163], v148 offset:2048
	ds_read_b128 v[164:167], v148 offset:3072
	ds_read_b128 v[168:171], v149
	ds_read_b128 v[172:175], v149 offset:1024
	ds_read_b128 v[176:179], v149 offset:2048
	ds_read_b128 v[180:183], v149 offset:3072
	ds_read_b128 v[184:187], v150
	ds_read_b128 v[188:191], v150 offset:1024
	ds_read_b128 v[192:195], v150 offset:2048
	ds_read_b128 v[196:199], v150 offset:3072
	ds_read_b128 v[200:203], v150 offset:4096
	ds_read_b128 v[204:207], v150 offset:5120
	ds_read_b128 v[208:211], v150 offset:6144
	ds_read_b128 v[212:215], v150 offset:7168
	s_add_u32 s34, s55, s30
	s_addc_u32 s35, s56, s31
	s_add_u32 s38, s34, 0x10000
	s_addc_u32 s39, s35, 0
	s_add_i32 s58, s58, 2
	s_add_u32 s36, s53, s30
	s_addc_u32 s37, s54, s31
	s_add_u32 s34, s34, 0x18000
	s_addc_u32 s35, s35, 0
	s_cmp_eq_u32 s57, s30
	s_cselect_b32 s35, s52, s35
	s_cselect_b32 s34, s51, s34
	s_cselect_b32 s37, s4, s37
	s_cselect_b32 s36, s5, s36
	s_cselect_b32 s39, s50, s39
	s_cselect_b32 s38, s27, s38
	v_lshl_add_u64 v[216:217], v[142:143], 0, s[30:31]
	s_add_i32 m0, s41, 0xc000
	s_nop 0
	global_load_lds_dwordx4 v[216:217], off
	v_lshl_add_u64 v[216:217], v[144:145], 0, s[30:31]
	s_add_i32 m0, s41, 0xe000
	s_nop 0
	global_load_lds_dwordx4 v[216:217], off
	s_waitcnt vmcnt(8) lgkmcnt(0)
	s_barrier
; #define PG8_STAGE(bufoff, gbase, voff) do { _Pragma("unroll") for (int _i = 0; _i < 2; ++_i) \
;         __builtin_amdgcn_global_load_lds((const unsigned*)((const char*)(gbase) + (voff)[_i]), (LAS unsigned*)(lds + (bufoff) + ldsw + _i * 8192), 16, 0, 0); } while (0)
; #define PG8_LDA(dst, b, h) do { _Pragma("unroll") for (int m = 0; m < 4; ++m) _Pragma("unroll") for (int k = 0; k < 2; ++k) dst[m][k] = *(const LAS bf16x8*)(lds + PG8_SA(b, h) + aoff + m * 2048 + k * 1024); } while (0)
; #define PG8_MMA(ai, bj, At, Bt) do { __builtin_amdgcn_s_setprio(1); _Pragma("unroll") for (int m = 0; m < 4; ++m) _Pragma("unroll") for (int n = 0; n < 2; ++n) _Pragma("unroll") for (int k = 0; k < 2; ++k) \
;         acc[ai][bj][m][n] = __builtin_amdgcn_mfma_f32_16x16x32_bf16(Bt[n][k], At[m][k], acc[ai][bj][m][n], 0, 0, 0); __builtin_amdgcn_s_setprio(0); } while (0)
; #define PG8_WAIT_V(n) asm volatile("s_waitcnt vmcnt(" #n ")" ::: "memory")
; #define PG8_WAIT_L(n) asm volatile("s_waitcnt lgkmcnt(" #n ")" ::: "memory")
; #define PG8_BAR __builtin_amdgcn_s_barrier()
; #define PG8_SCHED __builtin_amdgcn_sched_barrier(0)
; template <class Epi, class Sched, bool ABLK = false, bool ALIGN_EPI = true, bool SP2 = true, bool BBLK = true>
; __device__ __forceinline__ void gemm_phase(LAS unsigned char* lds, const Gemm g, const Sched& S, const Epi& E) {
;     ...
;             PG8_WAIT_V(8); PG8_WAIT_L(0); PG8_BAR; PG8_MMA(0, 0, At, B0); PG8_MMA(0, 1, At, B1); PG8_BAR; PG8_SCHED;
;             PG8_LDA(At, 0, 1); PG8_STAGE(PG8_SB(0, 0), b2, voffB); PG8_STAGE(PG8_SB(0, 1), b2 + hstepB, voffB); PG8_STAGE(PG8_SA(0, 0), a2, voffA);
;             PG8_WAIT_V(8); PG8_WAIT_L(0); PG8_BAR; PG8_MMA(1, 0, At, B0); PG8_MMA(1, 1, At, B1); PG8_BAR; PG8_SCHED;
	v_mfma_f32_16x16x32_bf16 v[126:129], v[152:155], v[184:187], v[126:129]
	v_mfma_f32_16x16x32_bf16 v[122:125], v[160:163], v[184:187], v[122:125]
	v_mfma_f32_16x16x32_bf16 v[110:113], v[152:155], v[192:195], v[110:113]
	v_mfma_f32_16x16x32_bf16 v[106:109], v[160:163], v[192:195], v[106:109]
	v_mfma_f32_16x16x32_bf16 v[94:97], v[152:155], v[200:203], v[94:97]
	v_mfma_f32_16x16x32_bf16 v[90:93], v[160:163], v[200:203], v[90:93]
	v_mfma_f32_16x16x32_bf16 v[78:81], v[152:155], v[208:211], v[78:81]
	v_mfma_f32_16x16x32_bf16 v[74:77], v[160:163], v[208:211], v[74:77]
	v_mfma_f32_16x16x32_bf16 v[126:129], v[156:159], v[188:191], v[126:129]
	v_mfma_f32_16x16x32_bf16 v[122:125], v[164:167], v[188:191], v[122:125]
	v_mfma_f32_16x16x32_bf16 v[110:113], v[156:159], v[196:199], v[110:113]
	v_mfma_f32_16x16x32_bf16 v[106:109], v[164:167], v[196:199], v[106:109]
	v_mfma_f32_16x16x32_bf16 v[94:97], v[156:159], v[204:207], v[94:97]
	v_mfma_f32_16x16x32_bf16 v[90:93], v[164:167], v[204:207], v[90:93]
	v_mfma_f32_16x16x32_bf16 v[78:81], v[156:159], v[212:215], v[78:81]
	v_mfma_f32_16x16x32_bf16 v[74:77], v[164:167], v[212:215], v[74:77]
	v_mfma_f32_16x16x32_bf16 v[118:121], v[168:171], v[184:187], v[118:121]
	v_mfma_f32_16x16x32_bf16 v[114:117], v[176:179], v[184:187], v[114:117]
	v_mfma_f32_16x16x32_bf16 v[102:105], v[168:171], v[192:195], v[102:105]
	v_mfma_f32_16x16x32_bf16 v[98:101], v[176:179], v[192:195], v[98:101]
	v_mfma_f32_16x16x32_bf16 v[86:89], v[168:171], v[200:203], v[86:89]
	v_mfma_f32_16x16x32_bf16 v[82:85], v[176:179], v[200:203], v[82:85]
	v_mfma_f32_16x16x32_bf16 v[70:73], v[168:171], v[208:211], v[70:73]
	v_mfma_f32_16x16x32_bf16 v[66:69], v[176:179], v[208:211], v[66:69]
	v_mfma_f32_16x16x32_bf16 v[118:121], v[172:175], v[188:191], v[118:121]
	v_mfma_f32_16x16x32_bf16 v[114:117], v[180:183], v[188:191], v[114:117]
	v_mfma_f32_16x16x32_bf16 v[102:105], v[172:175], v[196:199], v[102:105]
	v_mfma_f32_16x16x32_bf16 v[98:101], v[180:183], v[196:199], v[98:101]
	v_mfma_f32_16x16x32_bf16 v[86:89], v[172:175], v[204:207], v[86:89]
	v_mfma_f32_16x16x32_bf16 v[82:85], v[180:183], v[204:207], v[82:85]
	v_mfma_f32_16x16x32_bf16 v[70:73], v[172:175], v[212:215], v[70:73]
	v_mfma_f32_16x16x32_bf16 v[66:69], v[180:183], v[212:215], v[66:69]
	s_barrier
	ds_read_b128 v[184:187], v150 offset:16384
	ds_read_b128 v[188:191], v150 offset:17408
	ds_read_b128 v[192:195], v150 offset:18432
	ds_read_b128 v[196:199], v150 offset:19456
	ds_read_b128 v[200:203], v150 offset:20480
	ds_read_b128 v[204:207], v150 offset:21504
	ds_read_b128 v[208:211], v150 offset:22528
	ds_read_b128 v[212:215], v150 offset:23552
	s_add_i32 s59, s72, s40
	s_mov_b32 m0, s59
	s_nop 0
	global_load_lds_dwordx4 v130, s[36:37]
	s_add_i32 m0, s59, 0x2000
	s_add_u32 s64, s36, 0x4000
	s_addc_u32 s65, s37, 0
	s_add_i32 s59, s73, s40
	global_load_lds_dwordx4 v132, s[36:37]
	s_mov_b32 m0, s59
	s_nop 0
	global_load_lds_dwordx4 v130, s[64:65]
	s_add_i32 m0, s59, 0x2000
	s_nop 0
	global_load_lds_dwordx4 v132, s[64:65]
	s_mov_b32 m0, s41
	s_nop 0
	global_load_lds_dwordx4 v130, s[38:39]
	s_mov_b32 m0, s42
	s_nop 0
	global_load_lds_dwordx4 v132, s[38:39]
	s_waitcnt vmcnt(8) lgkmcnt(0)
	s_barrier
	v_mfma_f32_16x16x32_bf16 v[62:65], v[152:155], v[184:187], v[62:65]
	v_mfma_f32_16x16x32_bf16 v[58:61], v[160:163], v[184:187], v[58:61]
	v_mfma_f32_16x16x32_bf16 v[46:49], v[152:155], v[192:195], v[46:49]
	v_mfma_f32_16x16x32_bf16 v[42:45], v[160:163], v[192:195], v[42:45]
	v_mfma_f32_16x16x32_bf16 v[30:33], v[152:155], v[200:203], v[30:33]
	v_mfma_f32_16x16x32_bf16 v[26:29], v[160:163], v[200:203], v[26:29]
	v_mfma_f32_16x16x32_bf16 v[14:17], v[152:155], v[208:211], v[14:17]
	v_mfma_f32_16x16x32_bf16 v[10:13], v[160:163], v[208:211], v[10:13]
	v_mfma_f32_16x16x32_bf16 v[62:65], v[156:159], v[188:191], v[62:65]
	v_mfma_f32_16x16x32_bf16 v[58:61], v[164:167], v[188:191], v[58:61]
	v_mfma_f32_16x16x32_bf16 v[46:49], v[156:159], v[196:199], v[46:49]
	v_mfma_f32_16x16x32_bf16 v[42:45], v[164:167], v[196:199], v[42:45]
	v_mfma_f32_16x16x32_bf16 v[30:33], v[156:159], v[204:207], v[30:33]
	v_mfma_f32_16x16x32_bf16 v[26:29], v[164:167], v[204:207], v[26:29]
	v_mfma_f32_16x16x32_bf16 v[14:17], v[156:159], v[212:215], v[14:17]
	v_mfma_f32_16x16x32_bf16 v[10:13], v[164:167], v[212:215], v[10:13]
	v_mfma_f32_16x16x32_bf16 v[54:57], v[168:171], v[184:187], v[54:57]
	v_mfma_f32_16x16x32_bf16 v[50:53], v[176:179], v[184:187], v[50:53]
	v_mfma_f32_16x16x32_bf16 v[38:41], v[168:171], v[192:195], v[38:41]
	v_mfma_f32_16x16x32_bf16 v[34:37], v[176:179], v[192:195], v[34:37]
	v_mfma_f32_16x16x32_bf16 v[22:25], v[168:171], v[200:203], v[22:25]
	v_mfma_f32_16x16x32_bf16 v[18:21], v[176:179], v[200:203], v[18:21]
	v_mfma_f32_16x16x32_bf16 v[6:9], v[168:171], v[208:211], v[6:9]
	v_mfma_f32_16x16x32_bf16 v[2:5], v[176:179], v[208:211], v[2:5]
	v_mfma_f32_16x16x32_bf16 v[54:57], v[172:175], v[188:191], v[54:57]
	v_mfma_f32_16x16x32_bf16 v[50:53], v[180:183], v[188:191], v[50:53]
	v_mfma_f32_16x16x32_bf16 v[38:41], v[172:175], v[196:199], v[38:41]
	v_mfma_f32_16x16x32_bf16 v[34:37], v[180:183], v[196:199], v[34:37]
	v_mfma_f32_16x16x32_bf16 v[22:25], v[172:175], v[204:207], v[22:25]
	v_mfma_f32_16x16x32_bf16 v[18:21], v[180:183], v[204:207], v[18:21]
	v_mfma_f32_16x16x32_bf16 v[6:9], v[172:175], v[212:215], v[6:9]
	v_mfma_f32_16x16x32_bf16 v[2:5], v[180:183], v[212:215], v[2:5]
	s_barrier
; #define PG8_STAGE(bufoff, gbase, voff) do { _Pragma("unroll") for (int _i = 0; _i < 2; ++_i) \
;         __builtin_amdgcn_global_load_lds((const unsigned*)((const char*)(gbase) + (voff)[_i]), (LAS unsigned*)(lds + (bufoff) + ldsw + _i * 8192), 16, 0, 0); } while (0)
; #define PG8_LDA(dst, b, h) do { _Pragma("unroll") for (int m = 0; m < 4; ++m) _Pragma("unroll") for (int k = 0; k < 2; ++k) dst[m][k] = *(const LAS bf16x8*)(lds + PG8_SA(b, h) + aoff + m * 2048 + k * 1024); } while (0)
; #define PG8_LDB(dst, b, h) do { _Pragma("unroll") for (int n = 0; n < 2; ++n) _Pragma("unroll") for (int k = 0; k < 2; ++k) dst[n][k] = *(const LAS bf16x8*)(lds + PG8_SB(b, h) + boff + n * 2048 + k * 1024); } while (0)
; #define PG8_MMA(ai, bj, At, Bt) do { __builtin_amdgcn_s_setprio(1); _Pragma("unroll") for (int m = 0; m < 4; ++m) _Pragma("unroll") for (int n = 0; n < 2; ++n) _Pragma("unroll") for (int k = 0; k < 2; ++k) \
;         acc[ai][bj][m][n] = __builtin_amdgcn_mfma_f32_16x16x32_bf16(Bt[n][k], At[m][k], acc[ai][bj][m][n], 0, 0, 0); __builtin_amdgcn_s_setprio(0); } while (0)
; #define PG8_WAIT_V(n) asm volatile("s_waitcnt vmcnt(" #n ")" ::: "memory")
; #define PG8_WAIT_L(n) asm volatile("s_waitcnt lgkmcnt(" #n ")" ::: "memory")
; #define PG8_BAR __builtin_amdgcn_s_barrier()
; #define PG8_SCHED __builtin_amdgcn_sched_barrier(0)
; template <class Epi, class Sched, bool ABLK = false, bool ALIGN_EPI = true, bool SP2 = true, bool BBLK = true>
; __device__ __forceinline__ void gemm_phase(LAS unsigned char* lds, const Gemm g, const Sched& S, const Epi& E) {
;     ...
;             PG8_LDB(B0, 1, 0); PG8_LDB(B1, 1, 1); PG8_SCHED; PG8_LDA(At, 1, 0); PG8_STAGE(PG8_SA(0, 1), a2 + hstepA, voffA);
;             PG8_WAIT_V(8); PG8_WAIT_L(0); PG8_BAR; PG8_MMA(0, 0, At, B0); PG8_MMA(0, 1, At, B1); PG8_BAR; PG8_SCHED;
;             PG8_LDA(At, 1, 1); PG8_STAGE(PG8_SB(1, 0), b3, voffB); PG8_STAGE(PG8_SB(1, 1), b3 + hstepB, voffB); PG8_STAGE(PG8_SA(1, 0), a3, voffA);
;             PG8_WAIT_V(8); PG8_WAIT_L(0); PG8_BAR; PG8_MMA(1, 0, At, B0); PG8_MMA(1, 1, At, B1); PG8_BAR; PG8_SCHED;
;     ...
;         if constexpr (ALIGN_EPI) { if (wr == 0) PG8_BAR; }
	v_add_u32_e32 v151, s60, v146
	ds_read_b128 v[152:155], v151
	ds_read_b128 v[156:159], v151 offset:1024
	ds_read_b128 v[160:163], v151 offset:2048
	ds_read_b128 v[164:167], v151 offset:3072
	v_add_u32_e32 v151, s61, v146
	ds_read_b128 v[168:171], v151
	ds_read_b128 v[172:175], v151 offset:1024
	ds_read_b128 v[176:179], v151 offset:2048
	ds_read_b128 v[180:183], v151 offset:3072
	ds_read_b128 v[184:187], v150 offset:32768
	ds_read_b128 v[188:191], v150 offset:33792
	ds_read_b128 v[192:195], v150 offset:34816
	ds_read_b128 v[196:199], v150 offset:35840
	ds_read_b128 v[200:203], v150 offset:36864
	ds_read_b128 v[204:207], v150 offset:37888
	ds_read_b128 v[208:211], v150 offset:38912
	ds_read_b128 v[212:215], v150 offset:39936
	s_add_u32 s38, s38, 0x4000
	s_addc_u32 s39, s39, 0
	s_mov_b32 m0, s43
	s_nop 0
	global_load_lds_dwordx4 v130, s[38:39]
	s_mov_b32 m0, s44
	s_nop 0
	global_load_lds_dwordx4 v132, s[38:39]
	s_waitcnt vmcnt(8) lgkmcnt(0)
	s_barrier
	v_mfma_f32_16x16x32_bf16 v[126:129], v[152:155], v[184:187], v[126:129]
	v_mfma_f32_16x16x32_bf16 v[122:125], v[160:163], v[184:187], v[122:125]
	v_mfma_f32_16x16x32_bf16 v[110:113], v[152:155], v[192:195], v[110:113]
	v_mfma_f32_16x16x32_bf16 v[106:109], v[160:163], v[192:195], v[106:109]
	v_mfma_f32_16x16x32_bf16 v[94:97], v[152:155], v[200:203], v[94:97]
	v_mfma_f32_16x16x32_bf16 v[90:93], v[160:163], v[200:203], v[90:93]
	v_mfma_f32_16x16x32_bf16 v[78:81], v[152:155], v[208:211], v[78:81]
	v_mfma_f32_16x16x32_bf16 v[74:77], v[160:163], v[208:211], v[74:77]
	v_mfma_f32_16x16x32_bf16 v[126:129], v[156:159], v[188:191], v[126:129]
	v_mfma_f32_16x16x32_bf16 v[122:125], v[164:167], v[188:191], v[122:125]
	v_mfma_f32_16x16x32_bf16 v[110:113], v[156:159], v[196:199], v[110:113]
	v_mfma_f32_16x16x32_bf16 v[106:109], v[164:167], v[196:199], v[106:109]
	v_mfma_f32_16x16x32_bf16 v[94:97], v[156:159], v[204:207], v[94:97]
	v_mfma_f32_16x16x32_bf16 v[90:93], v[164:167], v[204:207], v[90:93]
	v_mfma_f32_16x16x32_bf16 v[78:81], v[156:159], v[212:215], v[78:81]
	v_mfma_f32_16x16x32_bf16 v[74:77], v[164:167], v[212:215], v[74:77]
	v_mfma_f32_16x16x32_bf16 v[118:121], v[168:171], v[184:187], v[118:121]
	v_mfma_f32_16x16x32_bf16 v[114:117], v[176:179], v[184:187], v[114:117]
	v_mfma_f32_16x16x32_bf16 v[102:105], v[168:171], v[192:195], v[102:105]
	v_mfma_f32_16x16x32_bf16 v[98:101], v[176:179], v[192:195], v[98:101]
	v_mfma_f32_16x16x32_bf16 v[86:89], v[168:171], v[200:203], v[86:89]
	v_mfma_f32_16x16x32_bf16 v[82:85], v[176:179], v[200:203], v[82:85]
	v_mfma_f32_16x16x32_bf16 v[70:73], v[168:171], v[208:211], v[70:73]
	v_mfma_f32_16x16x32_bf16 v[66:69], v[176:179], v[208:211], v[66:69]
	v_mfma_f32_16x16x32_bf16 v[118:121], v[172:175], v[188:191], v[118:121]
	v_mfma_f32_16x16x32_bf16 v[114:117], v[180:183], v[188:191], v[114:117]
	v_mfma_f32_16x16x32_bf16 v[102:105], v[172:175], v[196:199], v[102:105]
	v_mfma_f32_16x16x32_bf16 v[98:101], v[180:183], v[196:199], v[98:101]
	v_mfma_f32_16x16x32_bf16 v[86:89], v[172:175], v[204:207], v[86:89]
	v_mfma_f32_16x16x32_bf16 v[82:85], v[180:183], v[204:207], v[82:85]
	v_mfma_f32_16x16x32_bf16 v[70:73], v[172:175], v[212:215], v[70:73]
	v_mfma_f32_16x16x32_bf16 v[66:69], v[180:183], v[212:215], v[66:69]
	s_barrier
	ds_read_b128 v[184:187], v150 offset:49152
	ds_read_b128 v[188:191], v150 offset:50176
	ds_read_b128 v[192:195], v150 offset:51200
	ds_read_b128 v[196:199], v150 offset:52224
	ds_read_b128 v[200:203], v150 offset:53248
	ds_read_b128 v[204:207], v150 offset:54272
	ds_read_b128 v[208:211], v150 offset:55296
	ds_read_b128 v[212:215], v150 offset:56320
	s_add_u32 s38, s36, 0x8000
	s_addc_u32 s39, s37, 0
	s_add_i32 s59, s60, s40
	s_mov_b32 m0, s59
	s_nop 0
	global_load_lds_dwordx4 v130, s[38:39]
	s_add_i32 m0, s59, 0x2000
	s_add_u32 s36, s36, 0xc000
	v_lshl_add_u64 v[216:217], s[38:39], 0, v[132:133]
	s_addc_u32 s37, s37, 0
	s_add_i32 s38, s61, s40
	global_load_lds_dwordx4 v[216:217], off
	s_mov_b32 m0, s38
	s_nop 0
	global_load_lds_dwordx4 v130, s[36:37]
	s_add_i32 m0, s38, 0x2000
	s_nop 0
	global_load_lds_dwordx4 v132, s[36:37]
	s_mov_b32 m0, s45
	s_nop 0
	global_load_lds_dwordx4 v130, s[34:35]
	s_mov_b32 m0, s46
	s_nop 0
	global_load_lds_dwordx4 v132, s[34:35]
	s_waitcnt vmcnt(8) lgkmcnt(0)
	s_barrier
	v_mfma_f32_16x16x32_bf16 v[62:65], v[152:155], v[184:187], v[62:65]
	v_mfma_f32_16x16x32_bf16 v[58:61], v[160:163], v[184:187], v[58:61]
	v_mfma_f32_16x16x32_bf16 v[46:49], v[152:155], v[192:195], v[46:49]
	v_mfma_f32_16x16x32_bf16 v[42:45], v[160:163], v[192:195], v[42:45]
	v_mfma_f32_16x16x32_bf16 v[30:33], v[152:155], v[200:203], v[30:33]
	v_mfma_f32_16x16x32_bf16 v[26:29], v[160:163], v[200:203], v[26:29]
	v_mfma_f32_16x16x32_bf16 v[14:17], v[152:155], v[208:211], v[14:17]
	v_mfma_f32_16x16x32_bf16 v[10:13], v[160:163], v[208:211], v[10:13]
	v_mfma_f32_16x16x32_bf16 v[62:65], v[156:159], v[188:191], v[62:65]
	v_mfma_f32_16x16x32_bf16 v[58:61], v[164:167], v[188:191], v[58:61]
	v_mfma_f32_16x16x32_bf16 v[46:49], v[156:159], v[196:199], v[46:49]
	v_mfma_f32_16x16x32_bf16 v[42:45], v[164:167], v[196:199], v[42:45]
	v_mfma_f32_16x16x32_bf16 v[30:33], v[156:159], v[204:207], v[30:33]
	v_mfma_f32_16x16x32_bf16 v[26:29], v[164:167], v[204:207], v[26:29]
	v_mfma_f32_16x16x32_bf16 v[14:17], v[156:159], v[212:215], v[14:17]
	v_mfma_f32_16x16x32_bf16 v[10:13], v[164:167], v[212:215], v[10:13]
	v_mfma_f32_16x16x32_bf16 v[54:57], v[168:171], v[184:187], v[54:57]
	v_mfma_f32_16x16x32_bf16 v[50:53], v[176:179], v[184:187], v[50:53]
	v_mfma_f32_16x16x32_bf16 v[38:41], v[168:171], v[192:195], v[38:41]
	v_mfma_f32_16x16x32_bf16 v[34:37], v[176:179], v[192:195], v[34:37]
	v_mfma_f32_16x16x32_bf16 v[22:25], v[168:171], v[200:203], v[22:25]
	v_mfma_f32_16x16x32_bf16 v[18:21], v[176:179], v[200:203], v[18:21]
	v_mfma_f32_16x16x32_bf16 v[6:9], v[168:171], v[208:211], v[6:9]
	v_mfma_f32_16x16x32_bf16 v[2:5], v[176:179], v[208:211], v[2:5]
	v_mfma_f32_16x16x32_bf16 v[54:57], v[172:175], v[188:191], v[54:57]
	v_mfma_f32_16x16x32_bf16 v[50:53], v[180:183], v[188:191], v[50:53]
	v_mfma_f32_16x16x32_bf16 v[38:41], v[172:175], v[196:199], v[38:41]
	v_mfma_f32_16x16x32_bf16 v[34:37], v[180:183], v[196:199], v[34:37]
	v_mfma_f32_16x16x32_bf16 v[22:25], v[172:175], v[204:207], v[22:25]
	v_mfma_f32_16x16x32_bf16 v[18:21], v[180:183], v[204:207], v[18:21]
	v_mfma_f32_16x16x32_bf16 v[6:9], v[172:175], v[212:215], v[6:9]
	v_mfma_f32_16x16x32_bf16 v[2:5], v[180:183], v[212:215], v[2:5]
	s_barrier
	s_add_u32 s30, s30, 0x10000
	s_addc_u32 s31, s31, 0
	s_cmp_ge_u32 s58, s48
	s_cbranch_scc0 .LBB0_1907
	s_and_b64 vcc, exec, s[6:7]
	s_cbranch_vccz .LBB0_1910
	s_barrier

; #define PG8_STAGE(bufoff, gbase, voff) do { _Pragma("unroll") for (int _i = 0; _i < 2; ++_i) \
;         __builtin_amdgcn_global_load_lds((const unsigned*)((const char*)(gbase) + (voff)[_i]), (LAS unsigned*)(lds + (bufoff) + ldsw + _i * 8192), 16, 0, 0); } while (0)
; #define PG8_LDA(dst, b, h) do { _Pragma("unroll") for (int m = 0; m < 4; ++m) _Pragma("unroll") for (int k = 0; k < 2; ++k) dst[m][k] = *(const LAS bf16x8*)(lds + PG8_SA(b, h) + aoff + m * 2048 + k * 1024); } while (0)
; #define PG8_LDB(dst, b, h) do { _Pragma("unroll") for (int n = 0; n < 2; ++n) _Pragma("unroll") for (int k = 0; k < 2; ++k) dst[n][k] = *(const LAS bf16x8*)(lds + PG8_SB(b, h) + boff + n * 2048 + k * 1024); } while (0)
; #define PG8_WAIT_V(n) asm volatile("s_waitcnt vmcnt(" #n ")" ::: "memory")
; #define PG8_WAIT_L(n) asm volatile("s_waitcnt lgkmcnt(" #n ")" ::: "memory")
; template <class Epi, class Sched, bool ABLK = false, bool ALIGN_EPI = true, bool SP2 = true, bool BBLK = true>
; __device__ __forceinline__ void gemm_phase(LAS unsigned char* lds, const Gemm g, const Sched& S, const Epi& E) {
;     ...
;         const bool has_next = S.next(ui + 1, nxt);
;         const int nt = cur.nt;
;         const char* nuA = has_next ? a_unit(nxt) : uA; const int ntbA = has_next ? nxt.k0 / BK : tbA; const char* nB = has_next ? (const char*)g.Bt + (size_t)nxt.pn * tstepB + b_k0(nxt.k0) : cB;
;         for (int t = 0; t < nt; t += 2) {
;             const bool last = (t == nt - 2);
;             const char* a1 = a_tile(uA, tbA + t + 1);
;             const char* a2 = last ? a_tile(nuA, ntbA) : a_tile(uA, tbA + t + 2); const char* b2 = last ? nB : cB + (size_t)(t + 2) * kstepB;
;             const char* a3 = last ? a_tile(nuA, ntbA + 1) : a_tile(uA, tbA + t + 3); const char* b3 = b2 + kstepB;
;             if (last && has_next) S.a_ready(nxt);
;             if constexpr (SP2) {
;             PG8_LDB(B0, 0, 0); PG8_LDB(B1, 0, 1); PG8_SCHED; PG8_LDA(At, 0, 0); PG8_STAGE(PG8_SA(1, 1), a1 + hstepA, voffA);
;             PG8_WAIT_V(8); PG8_WAIT_L(0); PG8_BAR; PG8_MMA(0, 0, At, B0); PG8_MMA(0, 1, At, B1); PG8_BAR; PG8_SCHED;
;             PG8_LDA(At, 0, 1); PG8_STAGE(PG8_SB(0, 0), b2, voffB); PG8_STAGE(PG8_SB(0, 1), b2 + hstepB, voffB); PG8_STAGE(PG8_SA(0, 0), a2, voffA);
;             PG8_WAIT_V(8); PG8_WAIT_L(0); PG8_BAR; PG8_MMA(1, 0, At, B0); PG8_MMA(1, 1, At, B1); PG8_BAR; PG8_SCHED;
.LBB0_2137:
	ds_read_b128 v[152:155], v148
	ds_read_b128 v[156:159], v148 offset:1024
	ds_read_b128 v[160:163], v148 offset:2048
	ds_read_b128 v[164:167], v148 offset:3072
	ds_read_b128 v[168:171], v149
	ds_read_b128 v[172:175], v149 offset:1024
	ds_read_b128 v[176:179], v149 offset:2048
	ds_read_b128 v[180:183], v149 offset:3072
	ds_read_b128 v[184:187], v150
	ds_read_b128 v[188:191], v150 offset:1024
	ds_read_b128 v[192:195], v150 offset:2048
	ds_read_b128 v[196:199], v150 offset:3072
	ds_read_b128 v[200:203], v150 offset:4096
	ds_read_b128 v[204:207], v150 offset:5120
	ds_read_b128 v[208:211], v150 offset:6144
	ds_read_b128 v[212:215], v150 offset:7168
	s_ashr_i32 s11, s10, 31
	s_lshl_b64 s[4:5], s[10:11], 20
	s_add_u32 s14, s37, s4
	s_addc_u32 s15, s38, s5
	s_and_b64 s[4:5], s[16:17], exec
	s_cselect_b32 s4, s15, s25
	s_cselect_b32 s5, s14, s24
	s_ashr_i32 s13, s12, 31
	s_lshl_b64 s[18:19], s[12:13], 20
	s_add_u32 s18, s1, s18
	s_addc_u32 s19, s33, s19
	s_and_b64 s[28:29], s[16:17], exec
	s_cselect_b32 s11, s19, s27
	s_cselect_b32 s13, s18, s26
	s_add_u32 s48, s5, 0x80
	s_addc_u32 s49, s4, 0
	s_add_u32 s50, s26, 0x10000
	v_mov_b32_e32 v2, 0
	s_addc_u32 s51, s27, 0
	v_lshl_add_u64 v[142:143], s[24:25], 0, v[138:139]
	v_lshl_add_u64 v[144:145], s[24:25], 0, v[140:141]
	s_mov_b32 s52, -2
	s_mov_b64 s[26:27], 0
	s_add_u32 s28, s24, s26
	s_addc_u32 s29, s25, s27
	s_add_u32 s34, s28, 0x100
	s_addc_u32 s35, s29, 0
	s_add_u32 s28, s28, 0x180
	s_addc_u32 s29, s29, 0
	s_cmpk_eq_i32 s26, 0xf00
	s_cselect_b32 s29, s49, s29
	s_cselect_b32 s28, s48, s28
	s_cselect_b32 s31, s11, s51
	s_cselect_b32 s30, s13, s50
	s_cselect_b32 s35, s4, s35
	s_cselect_b32 s34, s5, s34
	s_mov_b32 m0, s47
	v_lshl_add_u64 v[216:217], v[142:143], 0, s[26:27]
	global_load_lds_dwordx4 v[216:217], off
	v_lshl_add_u64 v[216:217], v[144:145], 0, s[26:27]
	s_add_i32 m0, s21, 0xe000
	s_nop 0
	global_load_lds_dwordx4 v[216:217], off
	s_waitcnt vmcnt(8) lgkmcnt(0)
	s_barrier
	v_mfma_f32_16x16x32_bf16 v[122:125], v[152:155], v[184:187], 0
	v_mfma_f32_16x16x32_bf16 v[118:121], v[160:163], v[184:187], 0
	v_mfma_f32_16x16x32_bf16 v[106:109], v[152:155], v[192:195], 0
	v_mfma_f32_16x16x32_bf16 v[102:105], v[160:163], v[192:195], 0
	v_mfma_f32_16x16x32_bf16 v[90:93], v[152:155], v[200:203], 0
	v_mfma_f32_16x16x32_bf16 v[86:89], v[160:163], v[200:203], 0
	v_mfma_f32_16x16x32_bf16 v[74:77], v[152:155], v[208:211], 0
	v_mfma_f32_16x16x32_bf16 v[70:73], v[160:163], v[208:211], 0
	v_mfma_f32_16x16x32_bf16 v[122:125], v[156:159], v[188:191], v[122:125]
	v_mfma_f32_16x16x32_bf16 v[118:121], v[164:167], v[188:191], v[118:121]
	v_mfma_f32_16x16x32_bf16 v[106:109], v[156:159], v[196:199], v[106:109]
	v_mfma_f32_16x16x32_bf16 v[102:105], v[164:167], v[196:199], v[102:105]
	v_mfma_f32_16x16x32_bf16 v[90:93], v[156:159], v[204:207], v[90:93]
	v_mfma_f32_16x16x32_bf16 v[86:89], v[164:167], v[204:207], v[86:89]
	v_mfma_f32_16x16x32_bf16 v[74:77], v[156:159], v[212:215], v[74:77]
	v_mfma_f32_16x16x32_bf16 v[70:73], v[164:167], v[212:215], v[70:73]
	v_mfma_f32_16x16x32_bf16 v[126:129], v[168:171], v[184:187], 0
	v_mfma_f32_16x16x32_bf16 v[114:117], v[176:179], v[184:187], 0
	v_mfma_f32_16x16x32_bf16 v[110:113], v[168:171], v[192:195], 0
	v_mfma_f32_16x16x32_bf16 v[98:101], v[176:179], v[192:195], 0
	v_mfma_f32_16x16x32_bf16 v[94:97], v[168:171], v[200:203], 0
	v_mfma_f32_16x16x32_bf16 v[82:85], v[176:179], v[200:203], 0
	v_mfma_f32_16x16x32_bf16 v[78:81], v[168:171], v[208:211], 0
	v_mfma_f32_16x16x32_bf16 v[66:69], v[176:179], v[208:211], 0
	v_mfma_f32_16x16x32_bf16 v[126:129], v[172:175], v[188:191], v[126:129]
	v_mfma_f32_16x16x32_bf16 v[114:117], v[180:183], v[188:191], v[114:117]
	v_mfma_f32_16x16x32_bf16 v[110:113], v[172:175], v[196:199], v[110:113]
	v_mfma_f32_16x16x32_bf16 v[98:101], v[180:183], v[196:199], v[98:101]
	v_mfma_f32_16x16x32_bf16 v[94:97], v[172:175], v[204:207], v[94:97]
	v_mfma_f32_16x16x32_bf16 v[82:85], v[180:183], v[204:207], v[82:85]
	v_mfma_f32_16x16x32_bf16 v[78:81], v[172:175], v[212:215], v[78:81]
	v_mfma_f32_16x16x32_bf16 v[66:69], v[180:183], v[212:215], v[66:69]
	s_barrier
	ds_read_b128 v[184:187], v150 offset:16384
	ds_read_b128 v[188:191], v150 offset:17408
	ds_read_b128 v[192:195], v150 offset:18432
	ds_read_b128 v[196:199], v150 offset:19456
	ds_read_b128 v[200:203], v150 offset:20480
	ds_read_b128 v[204:207], v150 offset:21504
	ds_read_b128 v[208:211], v150 offset:22528
	ds_read_b128 v[212:215], v150 offset:23552
	s_add_i32 s53, s72, s36
	s_mov_b32 m0, s53
	s_nop 0
	global_load_lds_dwordx4 v134, s[30:31]
	s_add_i32 m0, s53, 0x2000
	s_add_u32 s54, s30, 0x4000
	s_addc_u32 s55, s31, 0
	s_add_i32 s53, s73, s36
	global_load_lds_dwordx4 v130, s[30:31]
	s_mov_b32 m0, s53
	s_nop 0
	global_load_lds_dwordx4 v134, s[54:55]
	s_add_i32 m0, s53, 0x2000
	s_nop 0
	global_load_lds_dwordx4 v130, s[54:55]
	s_mov_b32 m0, s21
	s_nop 0
	global_load_lds_dwordx4 v136, s[34:35]
	s_mov_b32 m0, s23
	s_nop 0
	global_load_lds_dwordx4 v132, s[34:35]
	s_waitcnt vmcnt(8) lgkmcnt(0)
	s_barrier
; #define PG8_STAGE(bufoff, gbase, voff) do { _Pragma("unroll") for (int _i = 0; _i < 2; ++_i) \
;         __builtin_amdgcn_global_load_lds((const unsigned*)((const char*)(gbase) + (voff)[_i]), (LAS unsigned*)(lds + (bufoff) + ldsw + _i * 8192), 16, 0, 0); } while (0)
; #define PG8_LDA(dst, b, h) do { _Pragma("unroll") for (int m = 0; m < 4; ++m) _Pragma("unroll") for (int k = 0; k < 2; ++k) dst[m][k] = *(const LAS bf16x8*)(lds + PG8_SA(b, h) + aoff + m * 2048 + k * 1024); } while (0)
; #define PG8_LDB(dst, b, h) do { _Pragma("unroll") for (int n = 0; n < 2; ++n) _Pragma("unroll") for (int k = 0; k < 2; ++k) dst[n][k] = *(const LAS bf16x8*)(lds + PG8_SB(b, h) + boff + n * 2048 + k * 1024); } while (0)
; #define PG8_MMA(ai, bj, At, Bt) do { __builtin_amdgcn_s_setprio(1); _Pragma("unroll") for (int m = 0; m < 4; ++m) _Pragma("unroll") for (int n = 0; n < 2; ++n) _Pragma("unroll") for (int k = 0; k < 2; ++k) \
;         acc[ai][bj][m][n] = __builtin_amdgcn_mfma_f32_16x16x32_bf16(Bt[n][k], At[m][k], acc[ai][bj][m][n], 0, 0, 0); __builtin_amdgcn_s_setprio(0); } while (0)
; #define PG8_WAIT_V(n) asm volatile("s_waitcnt vmcnt(" #n ")" ::: "memory")
; #define PG8_WAIT_L(n) asm volatile("s_waitcnt lgkmcnt(" #n ")" ::: "memory")
; #define PG8_BAR __builtin_amdgcn_s_barrier()
; #define PG8_SCHED __builtin_amdgcn_sched_barrier(0)
; template <class Epi, class Sched, bool ABLK = false, bool ALIGN_EPI = true, bool SP2 = true, bool BBLK = true>
; __device__ __forceinline__ void gemm_phase(LAS unsigned char* lds, const Gemm g, const Sched& S, const Epi& E) {
;     ...
;             PG8_WAIT_V(8); PG8_WAIT_L(0); PG8_BAR; PG8_MMA(1, 0, At, B0); PG8_MMA(1, 1, At, B1); PG8_BAR; PG8_SCHED;
;             PG8_LDB(B0, 1, 0); PG8_LDB(B1, 1, 1); PG8_SCHED; PG8_LDA(At, 1, 0); PG8_STAGE(PG8_SA(0, 1), a2 + hstepA, voffA);
;             PG8_WAIT_V(8); PG8_WAIT_L(0); PG8_BAR; PG8_MMA(0, 0, At, B0); PG8_MMA(0, 1, At, B1); PG8_BAR; PG8_SCHED;
	v_mfma_f32_16x16x32_bf16 v[58:61], v[152:155], v[184:187], 0
	v_mfma_f32_16x16x32_bf16 v[54:57], v[160:163], v[184:187], 0
	v_mfma_f32_16x16x32_bf16 v[42:45], v[152:155], v[192:195], 0
	v_mfma_f32_16x16x32_bf16 v[38:41], v[160:163], v[192:195], 0
	v_mfma_f32_16x16x32_bf16 v[26:29], v[152:155], v[200:203], 0
	v_mfma_f32_16x16x32_bf16 v[22:25], v[160:163], v[200:203], 0
	v_mfma_f32_16x16x32_bf16 v[10:13], v[152:155], v[208:211], 0
	v_mfma_f32_16x16x32_bf16 v[6:9], v[160:163], v[208:211], 0
	v_mfma_f32_16x16x32_bf16 v[58:61], v[156:159], v[188:191], v[58:61]
	v_mfma_f32_16x16x32_bf16 v[54:57], v[164:167], v[188:191], v[54:57]
	v_mfma_f32_16x16x32_bf16 v[42:45], v[156:159], v[196:199], v[42:45]
	v_mfma_f32_16x16x32_bf16 v[38:41], v[164:167], v[196:199], v[38:41]
	v_mfma_f32_16x16x32_bf16 v[26:29], v[156:159], v[204:207], v[26:29]
	v_mfma_f32_16x16x32_bf16 v[22:25], v[164:167], v[204:207], v[22:25]
	v_mfma_f32_16x16x32_bf16 v[10:13], v[156:159], v[212:215], v[10:13]
	v_mfma_f32_16x16x32_bf16 v[6:9], v[164:167], v[212:215], v[6:9]
	v_mfma_f32_16x16x32_bf16 v[62:65], v[168:171], v[184:187], 0
	v_mfma_f32_16x16x32_bf16 v[50:53], v[176:179], v[184:187], 0
	v_mfma_f32_16x16x32_bf16 v[46:49], v[168:171], v[192:195], 0
	v_mfma_f32_16x16x32_bf16 v[34:37], v[176:179], v[192:195], 0
	v_mfma_f32_16x16x32_bf16 v[30:33], v[168:171], v[200:203], 0
	v_mfma_f32_16x16x32_bf16 v[18:21], v[176:179], v[200:203], 0
	v_mfma_f32_16x16x32_bf16 v[14:17], v[168:171], v[208:211], 0
	v_mfma_f32_16x16x32_bf16 v[2:5], v[176:179], v[208:211], 0
	v_mfma_f32_16x16x32_bf16 v[62:65], v[172:175], v[188:191], v[62:65]
	v_mfma_f32_16x16x32_bf16 v[50:53], v[180:183], v[188:191], v[50:53]
	v_mfma_f32_16x16x32_bf16 v[46:49], v[172:175], v[196:199], v[46:49]
	v_mfma_f32_16x16x32_bf16 v[34:37], v[180:183], v[196:199], v[34:37]
	v_mfma_f32_16x16x32_bf16 v[30:33], v[172:175], v[204:207], v[30:33]
	v_mfma_f32_16x16x32_bf16 v[18:21], v[180:183], v[204:207], v[18:21]
	v_mfma_f32_16x16x32_bf16 v[14:17], v[172:175], v[212:215], v[14:17]
	v_mfma_f32_16x16x32_bf16 v[2:5], v[180:183], v[212:215], v[2:5]
	s_barrier
	v_add_u32_e32 v151, s60, v146
	ds_read_b128 v[152:155], v151
	ds_read_b128 v[156:159], v151 offset:1024
	ds_read_b128 v[160:163], v151 offset:2048
	ds_read_b128 v[164:167], v151 offset:3072
	v_add_u32_e32 v151, s61, v146
	ds_read_b128 v[168:171], v151
	ds_read_b128 v[172:175], v151 offset:1024
	ds_read_b128 v[176:179], v151 offset:2048
	ds_read_b128 v[180:183], v151 offset:3072
	ds_read_b128 v[184:187], v150 offset:32768
	ds_read_b128 v[188:191], v150 offset:33792
	ds_read_b128 v[192:195], v150 offset:34816
	ds_read_b128 v[196:199], v150 offset:35840
	ds_read_b128 v[200:203], v150 offset:36864
	ds_read_b128 v[204:207], v150 offset:37888
	ds_read_b128 v[208:211], v150 offset:38912
	ds_read_b128 v[212:215], v150 offset:39936
	s_add_u32 s34, s34, 0x80000
	s_addc_u32 s35, s35, 0
	s_mov_b32 m0, s39
	s_nop 0
	global_load_lds_dwordx4 v136, s[34:35]
	s_mov_b32 m0, s40
	s_nop 0
	global_load_lds_dwordx4 v132, s[34:35]
	s_waitcnt vmcnt(8) lgkmcnt(0)
	s_barrier
	v_mfma_f32_16x16x32_bf16 v[122:125], v[152:155], v[184:187], v[122:125]
	v_mfma_f32_16x16x32_bf16 v[118:121], v[160:163], v[184:187], v[118:121]
	v_mfma_f32_16x16x32_bf16 v[106:109], v[152:155], v[192:195], v[106:109]
	v_mfma_f32_16x16x32_bf16 v[102:105], v[160:163], v[192:195], v[102:105]
	v_mfma_f32_16x16x32_bf16 v[90:93], v[152:155], v[200:203], v[90:93]
	v_mfma_f32_16x16x32_bf16 v[86:89], v[160:163], v[200:203], v[86:89]
	v_mfma_f32_16x16x32_bf16 v[74:77], v[152:155], v[208:211], v[74:77]
	v_mfma_f32_16x16x32_bf16 v[70:73], v[160:163], v[208:211], v[70:73]
	v_mfma_f32_16x16x32_bf16 v[122:125], v[156:159], v[188:191], v[122:125]
	v_mfma_f32_16x16x32_bf16 v[118:121], v[164:167], v[188:191], v[118:121]
	v_mfma_f32_16x16x32_bf16 v[106:109], v[156:159], v[196:199], v[106:109]
	v_mfma_f32_16x16x32_bf16 v[102:105], v[164:167], v[196:199], v[102:105]
	v_mfma_f32_16x16x32_bf16 v[90:93], v[156:159], v[204:207], v[90:93]
	v_mfma_f32_16x16x32_bf16 v[86:89], v[164:167], v[204:207], v[86:89]
	v_mfma_f32_16x16x32_bf16 v[74:77], v[156:159], v[212:215], v[74:77]
	v_mfma_f32_16x16x32_bf16 v[70:73], v[164:167], v[212:215], v[70:73]
	v_mfma_f32_16x16x32_bf16 v[126:129], v[168:171], v[184:187], v[126:129]
	v_mfma_f32_16x16x32_bf16 v[114:117], v[176:179], v[184:187], v[114:117]
	v_mfma_f32_16x16x32_bf16 v[110:113], v[168:171], v[192:195], v[110:113]
	v_mfma_f32_16x16x32_bf16 v[98:101], v[176:179], v[192:195], v[98:101]
	v_mfma_f32_16x16x32_bf16 v[94:97], v[168:171], v[200:203], v[94:97]
	v_mfma_f32_16x16x32_bf16 v[82:85], v[176:179], v[200:203], v[82:85]
	v_mfma_f32_16x16x32_bf16 v[78:81], v[168:171], v[208:211], v[78:81]
	v_mfma_f32_16x16x32_bf16 v[66:69], v[176:179], v[208:211], v[66:69]
	v_mfma_f32_16x16x32_bf16 v[126:129], v[172:175], v[188:191], v[126:129]
	v_mfma_f32_16x16x32_bf16 v[114:117], v[180:183], v[188:191], v[114:117]
	v_mfma_f32_16x16x32_bf16 v[110:113], v[172:175], v[196:199], v[110:113]
	v_mfma_f32_16x16x32_bf16 v[98:101], v[180:183], v[196:199], v[98:101]
	v_mfma_f32_16x16x32_bf16 v[94:97], v[172:175], v[204:207], v[94:97]
	v_mfma_f32_16x16x32_bf16 v[82:85], v[180:183], v[204:207], v[82:85]
	v_mfma_f32_16x16x32_bf16 v[78:81], v[172:175], v[212:215], v[78:81]
	v_mfma_f32_16x16x32_bf16 v[66:69], v[180:183], v[212:215], v[66:69]
	s_barrier
; #define PG8_STAGE(bufoff, gbase, voff) do { _Pragma("unroll") for (int _i = 0; _i < 2; ++_i) \
;         __builtin_amdgcn_global_load_lds((const unsigned*)((const char*)(gbase) + (voff)[_i]), (LAS unsigned*)(lds + (bufoff) + ldsw + _i * 8192), 16, 0, 0); } while (0)
; #define PG8_LDA(dst, b, h) do { _Pragma("unroll") for (int m = 0; m < 4; ++m) _Pragma("unroll") for (int k = 0; k < 2; ++k) dst[m][k] = *(const LAS bf16x8*)(lds + PG8_SA(b, h) + aoff + m * 2048 + k * 1024); } while (0)
; #define PG8_LDB(dst, b, h) do { _Pragma("unroll") for (int n = 0; n < 2; ++n) _Pragma("unroll") for (int k = 0; k < 2; ++k) dst[n][k] = *(const LAS bf16x8*)(lds + PG8_SB(b, h) + boff + n * 2048 + k * 1024); } while (0)
; #define PG8_MMA(ai, bj, At, Bt) do { __builtin_amdgcn_s_setprio(1); _Pragma("unroll") for (int m = 0; m < 4; ++m) _Pragma("unroll") for (int n = 0; n < 2; ++n) _Pragma("unroll") for (int k = 0; k < 2; ++k) \
;         acc[ai][bj][m][n] = __builtin_amdgcn_mfma_f32_16x16x32_bf16(Bt[n][k], At[m][k], acc[ai][bj][m][n], 0, 0, 0); __builtin_amdgcn_s_setprio(0); } while (0)
; #define PG8_BAR __builtin_amdgcn_s_barrier()
; template <class Epi, class Sched, bool ABLK = false, bool ALIGN_EPI = true, bool SP2 = true, bool BBLK = true>
; __device__ __forceinline__ void gemm_phase(LAS unsigned char* lds, const Gemm g, const Sched& S, const Epi& E) {
;     ...
;             PG8_LDB(B0, 0, 0); PG8_LDB(B1, 0, 1); PG8_SCHED; PG8_LDA(At, 0, 0); PG8_STAGE(PG8_SA(1, 1), a1 + hstepA, voffA);
;             PG8_WAIT_V(8); PG8_WAIT_L(0); PG8_BAR; PG8_MMA(0, 0, At, B0); PG8_MMA(0, 1, At, B1); PG8_BAR; PG8_SCHED;
;             PG8_LDA(At, 0, 1); PG8_STAGE(PG8_SB(0, 0), b2, voffB); PG8_STAGE(PG8_SB(0, 1), b2 + hstepB, voffB); PG8_STAGE(PG8_SA(0, 0), a2, voffA);
;             PG8_WAIT_V(8); PG8_WAIT_L(0); PG8_BAR; PG8_MMA(1, 0, At, B0); PG8_MMA(1, 1, At, B1); PG8_BAR; PG8_SCHED;
;             PG8_LDB(B0, 1, 0); PG8_LDB(B1, 1, 1); PG8_SCHED; PG8_LDA(At, 1, 0); PG8_STAGE(PG8_SA(0, 1), a2 + hstepA, voffA);
;             PG8_WAIT_V(8); PG8_WAIT_L(0); PG8_BAR; PG8_MMA(0, 0, At, B0); PG8_MMA(0, 1, At, B1); PG8_BAR; PG8_SCHED;
;             PG8_LDA(At, 1, 1); PG8_STAGE(PG8_SB(1, 0), b3, voffB); PG8_STAGE(PG8_SB(1, 1), b3 + hstepB, voffB); PG8_STAGE(PG8_SA(1, 0), a3, voffA);
;             PG8_WAIT_V(8); PG8_WAIT_L(0); PG8_BAR; PG8_MMA(1, 0, At, B0); PG8_MMA(1, 1, At, B1); PG8_BAR; PG8_SCHED;
	ds_read_b128 v[184:187], v150 offset:49152
	ds_read_b128 v[188:191], v150 offset:50176
	ds_read_b128 v[192:195], v150 offset:51200
	ds_read_b128 v[196:199], v150 offset:52224
	ds_read_b128 v[200:203], v150 offset:53248
	ds_read_b128 v[204:207], v150 offset:54272
	ds_read_b128 v[208:211], v150 offset:55296
	ds_read_b128 v[212:215], v150 offset:56320
	s_add_u32 s34, s30, 0x8000
	s_addc_u32 s35, s31, 0
	s_add_i32 s53, s60, s36
	s_mov_b32 m0, s53
	s_nop 0
	global_load_lds_dwordx4 v134, s[34:35]
	s_add_i32 m0, s53, 0x2000
	s_add_u32 s30, s30, 0xc000
	v_lshl_add_u64 v[216:217], s[34:35], 0, v[130:131]
	s_addc_u32 s31, s31, 0
	s_add_i32 s34, s61, s36
	global_load_lds_dwordx4 v[216:217], off
	s_mov_b32 m0, s34
	s_nop 0
	global_load_lds_dwordx4 v134, s[30:31]
	s_add_i32 m0, s34, 0x2000
	s_nop 0
	global_load_lds_dwordx4 v130, s[30:31]
	s_mov_b32 m0, s42
	s_nop 0
	global_load_lds_dwordx4 v136, s[28:29]
	s_mov_b32 m0, s43
	s_nop 0
	global_load_lds_dwordx4 v132, s[28:29]
	s_waitcnt vmcnt(8) lgkmcnt(0)
	s_barrier
	v_mfma_f32_16x16x32_bf16 v[58:61], v[152:155], v[184:187], v[58:61]
	v_mfma_f32_16x16x32_bf16 v[54:57], v[160:163], v[184:187], v[54:57]
	v_mfma_f32_16x16x32_bf16 v[42:45], v[152:155], v[192:195], v[42:45]
	v_mfma_f32_16x16x32_bf16 v[38:41], v[160:163], v[192:195], v[38:41]
	v_mfma_f32_16x16x32_bf16 v[26:29], v[152:155], v[200:203], v[26:29]
	v_mfma_f32_16x16x32_bf16 v[22:25], v[160:163], v[200:203], v[22:25]
	v_mfma_f32_16x16x32_bf16 v[10:13], v[152:155], v[208:211], v[10:13]
	v_mfma_f32_16x16x32_bf16 v[6:9], v[160:163], v[208:211], v[6:9]
	v_mfma_f32_16x16x32_bf16 v[58:61], v[156:159], v[188:191], v[58:61]
	v_mfma_f32_16x16x32_bf16 v[54:57], v[164:167], v[188:191], v[54:57]
	v_mfma_f32_16x16x32_bf16 v[42:45], v[156:159], v[196:199], v[42:45]
	v_mfma_f32_16x16x32_bf16 v[38:41], v[164:167], v[196:199], v[38:41]
	v_mfma_f32_16x16x32_bf16 v[26:29], v[156:159], v[204:207], v[26:29]
	v_mfma_f32_16x16x32_bf16 v[22:25], v[164:167], v[204:207], v[22:25]
	v_mfma_f32_16x16x32_bf16 v[10:13], v[156:159], v[212:215], v[10:13]
	v_mfma_f32_16x16x32_bf16 v[6:9], v[164:167], v[212:215], v[6:9]
	v_mfma_f32_16x16x32_bf16 v[62:65], v[168:171], v[184:187], v[62:65]
	v_mfma_f32_16x16x32_bf16 v[50:53], v[176:179], v[184:187], v[50:53]
	v_mfma_f32_16x16x32_bf16 v[46:49], v[168:171], v[192:195], v[46:49]
	v_mfma_f32_16x16x32_bf16 v[34:37], v[176:179], v[192:195], v[34:37]
	v_mfma_f32_16x16x32_bf16 v[30:33], v[168:171], v[200:203], v[30:33]
	v_mfma_f32_16x16x32_bf16 v[18:21], v[176:179], v[200:203], v[18:21]
	v_mfma_f32_16x16x32_bf16 v[14:17], v[168:171], v[208:211], v[14:17]
	v_mfma_f32_16x16x32_bf16 v[2:5], v[176:179], v[208:211], v[2:5]
	v_mfma_f32_16x16x32_bf16 v[62:65], v[172:175], v[188:191], v[62:65]
	v_mfma_f32_16x16x32_bf16 v[50:53], v[180:183], v[188:191], v[50:53]
	v_mfma_f32_16x16x32_bf16 v[46:49], v[172:175], v[196:199], v[46:49]
	v_mfma_f32_16x16x32_bf16 v[34:37], v[180:183], v[196:199], v[34:37]
	v_mfma_f32_16x16x32_bf16 v[30:33], v[172:175], v[204:207], v[30:33]
	v_mfma_f32_16x16x32_bf16 v[18:21], v[180:183], v[204:207], v[18:21]
	v_mfma_f32_16x16x32_bf16 v[14:17], v[172:175], v[212:215], v[14:17]
	v_mfma_f32_16x16x32_bf16 v[2:5], v[180:183], v[212:215], v[2:5]
	s_barrier
	s_add_i32 s52, s52, 2
	s_add_u32 s26, s26, 0x100
	s_addc_u32 s27, s27, 0
	s_add_u32 s50, s50, 0x10000
	s_addc_u32 s51, s51, 0
	s_cmp_gt_u32 s52, 29
.LBB0_2138:
	ds_read_b128 v[152:155], v148
	ds_read_b128 v[156:159], v148 offset:1024
	ds_read_b128 v[160:163], v148 offset:2048
	ds_read_b128 v[164:167], v148 offset:3072
	ds_read_b128 v[168:171], v149
	ds_read_b128 v[172:175], v149 offset:1024
	ds_read_b128 v[176:179], v149 offset:2048
	ds_read_b128 v[180:183], v149 offset:3072
	ds_read_b128 v[184:187], v150
	ds_read_b128 v[188:191], v150 offset:1024
	ds_read_b128 v[192:195], v150 offset:2048
	ds_read_b128 v[196:199], v150 offset:3072
	ds_read_b128 v[200:203], v150 offset:4096
	ds_read_b128 v[204:207], v150 offset:5120
	ds_read_b128 v[208:211], v150 offset:6144
	ds_read_b128 v[212:215], v150 offset:7168
	s_add_u32 s28, s24, s26
	s_addc_u32 s29, s25, s27
	s_add_u32 s34, s28, 0x100
	s_addc_u32 s35, s29, 0
	s_add_u32 s28, s28, 0x180
	s_addc_u32 s29, s29, 0
	s_cmpk_eq_i32 s26, 0xf00
	s_cselect_b32 s29, s49, s29
	s_cselect_b32 s28, s48, s28
	s_cselect_b32 s31, s11, s51
	s_cselect_b32 s30, s13, s50
	s_cselect_b32 s35, s4, s35
	s_cselect_b32 s34, s5, s34
	s_mov_b32 m0, s47
	v_lshl_add_u64 v[216:217], v[142:143], 0, s[26:27]
	global_load_lds_dwordx4 v[216:217], off
	v_lshl_add_u64 v[216:217], v[144:145], 0, s[26:27]
	s_add_i32 m0, s21, 0xe000
	s_nop 0
	global_load_lds_dwordx4 v[216:217], off
	s_waitcnt vmcnt(8) lgkmcnt(0)
	s_barrier
; #define PG8_STAGE(bufoff, gbase, voff) do { _Pragma("unroll") for (int _i = 0; _i < 2; ++_i) \
;         __builtin_amdgcn_global_load_lds((const unsigned*)((const char*)(gbase) + (voff)[_i]), (LAS unsigned*)(lds + (bufoff) + ldsw + _i * 8192), 16, 0, 0); } while (0)
; #define PG8_LDA(dst, b, h) do { _Pragma("unroll") for (int m = 0; m < 4; ++m) _Pragma("unroll") for (int k = 0; k < 2; ++k) dst[m][k] = *(const LAS bf16x8*)(lds + PG8_SA(b, h) + aoff + m * 2048 + k * 1024); } while (0)
; #define PG8_MMA(ai, bj, At, Bt) do { __builtin_amdgcn_s_setprio(1); _Pragma("unroll") for (int m = 0; m < 4; ++m) _Pragma("unroll") for (int n = 0; n < 2; ++n) _Pragma("unroll") for (int k = 0; k < 2; ++k) \
;         acc[ai][bj][m][n] = __builtin_amdgcn_mfma_f32_16x16x32_bf16(Bt[n][k], At[m][k], acc[ai][bj][m][n], 0, 0, 0); __builtin_amdgcn_s_setprio(0); } while (0)
; #define PG8_WAIT_V(n) asm volatile("s_waitcnt vmcnt(" #n ")" ::: "memory")
; #define PG8_WAIT_L(n) asm volatile("s_waitcnt lgkmcnt(" #n ")" ::: "memory")
; #define PG8_BAR __builtin_amdgcn_s_barrier()
; #define PG8_SCHED __builtin_amdgcn_sched_barrier(0)
; template <class Epi, class Sched, bool ABLK = false, bool ALIGN_EPI = true, bool SP2 = true, bool BBLK = true>
; __device__ __forceinline__ void gemm_phase(LAS unsigned char* lds, const Gemm g, const Sched& S, const Epi& E) {
;     ...
;             PG8_WAIT_V(8); PG8_WAIT_L(0); PG8_BAR; PG8_MMA(0, 0, At, B0); PG8_MMA(0, 1, At, B1); PG8_BAR; PG8_SCHED;
;             PG8_LDA(At, 0, 1); PG8_STAGE(PG8_SB(0, 0), b2, voffB); PG8_STAGE(PG8_SB(0, 1), b2 + hstepB, voffB); PG8_STAGE(PG8_SA(0, 0), a2, voffA);
;             PG8_WAIT_V(8); PG8_WAIT_L(0); PG8_BAR; PG8_MMA(1, 0, At, B0); PG8_MMA(1, 1, At, B1); PG8_BAR; PG8_SCHED;
	v_mfma_f32_16x16x32_bf16 v[122:125], v[152:155], v[184:187], v[122:125]
	v_mfma_f32_16x16x32_bf16 v[118:121], v[160:163], v[184:187], v[118:121]
	v_mfma_f32_16x16x32_bf16 v[106:109], v[152:155], v[192:195], v[106:109]
	v_mfma_f32_16x16x32_bf16 v[102:105], v[160:163], v[192:195], v[102:105]
	v_mfma_f32_16x16x32_bf16 v[90:93], v[152:155], v[200:203], v[90:93]
	v_mfma_f32_16x16x32_bf16 v[86:89], v[160:163], v[200:203], v[86:89]
	v_mfma_f32_16x16x32_bf16 v[74:77], v[152:155], v[208:211], v[74:77]
	v_mfma_f32_16x16x32_bf16 v[70:73], v[160:163], v[208:211], v[70:73]
	v_mfma_f32_16x16x32_bf16 v[122:125], v[156:159], v[188:191], v[122:125]
	v_mfma_f32_16x16x32_bf16 v[118:121], v[164:167], v[188:191], v[118:121]
	v_mfma_f32_16x16x32_bf16 v[106:109], v[156:159], v[196:199], v[106:109]
	v_mfma_f32_16x16x32_bf16 v[102:105], v[164:167], v[196:199], v[102:105]
	v_mfma_f32_16x16x32_bf16 v[90:93], v[156:159], v[204:207], v[90:93]
	v_mfma_f32_16x16x32_bf16 v[86:89], v[164:167], v[204:207], v[86:89]
	v_mfma_f32_16x16x32_bf16 v[74:77], v[156:159], v[212:215], v[74:77]
	v_mfma_f32_16x16x32_bf16 v[70:73], v[164:167], v[212:215], v[70:73]
	v_mfma_f32_16x16x32_bf16 v[126:129], v[168:171], v[184:187], v[126:129]
	v_mfma_f32_16x16x32_bf16 v[114:117], v[176:179], v[184:187], v[114:117]
	v_mfma_f32_16x16x32_bf16 v[110:113], v[168:171], v[192:195], v[110:113]
	v_mfma_f32_16x16x32_bf16 v[98:101], v[176:179], v[192:195], v[98:101]
	v_mfma_f32_16x16x32_bf16 v[94:97], v[168:171], v[200:203], v[94:97]
	v_mfma_f32_16x16x32_bf16 v[82:85], v[176:179], v[200:203], v[82:85]
	v_mfma_f32_16x16x32_bf16 v[78:81], v[168:171], v[208:211], v[78:81]
	v_mfma_f32_16x16x32_bf16 v[66:69], v[176:179], v[208:211], v[66:69]
	v_mfma_f32_16x16x32_bf16 v[126:129], v[172:175], v[188:191], v[126:129]
	v_mfma_f32_16x16x32_bf16 v[114:117], v[180:183], v[188:191], v[114:117]
	v_mfma_f32_16x16x32_bf16 v[110:113], v[172:175], v[196:199], v[110:113]
	v_mfma_f32_16x16x32_bf16 v[98:101], v[180:183], v[196:199], v[98:101]
	v_mfma_f32_16x16x32_bf16 v[94:97], v[172:175], v[204:207], v[94:97]
	v_mfma_f32_16x16x32_bf16 v[82:85], v[180:183], v[204:207], v[82:85]
	v_mfma_f32_16x16x32_bf16 v[78:81], v[172:175], v[212:215], v[78:81]
	v_mfma_f32_16x16x32_bf16 v[66:69], v[180:183], v[212:215], v[66:69]
	s_barrier
	ds_read_b128 v[184:187], v150 offset:16384
	ds_read_b128 v[188:191], v150 offset:17408
	ds_read_b128 v[192:195], v150 offset:18432
	ds_read_b128 v[196:199], v150 offset:19456
	ds_read_b128 v[200:203], v150 offset:20480
	ds_read_b128 v[204:207], v150 offset:21504
	ds_read_b128 v[208:211], v150 offset:22528
	ds_read_b128 v[212:215], v150 offset:23552
	s_add_i32 s53, s72, s36
	s_mov_b32 m0, s53
	s_nop 0
	global_load_lds_dwordx4 v134, s[30:31]
	s_add_i32 m0, s53, 0x2000
	s_add_u32 s54, s30, 0x4000
	s_addc_u32 s55, s31, 0
	s_add_i32 s53, s73, s36
	global_load_lds_dwordx4 v130, s[30:31]
	s_mov_b32 m0, s53
	s_nop 0
	global_load_lds_dwordx4 v134, s[54:55]
	s_add_i32 m0, s53, 0x2000
	s_nop 0
	global_load_lds_dwordx4 v130, s[54:55]
	s_mov_b32 m0, s21
	s_nop 0
	global_load_lds_dwordx4 v136, s[34:35]
	s_mov_b32 m0, s23
	s_nop 0
	global_load_lds_dwordx4 v132, s[34:35]
	s_waitcnt vmcnt(8) lgkmcnt(0)
	s_barrier
	v_mfma_f32_16x16x32_bf16 v[58:61], v[152:155], v[184:187], v[58:61]
	v_mfma_f32_16x16x32_bf16 v[54:57], v[160:163], v[184:187], v[54:57]
	v_mfma_f32_16x16x32_bf16 v[42:45], v[152:155], v[192:195], v[42:45]
	v_mfma_f32_16x16x32_bf16 v[38:41], v[160:163], v[192:195], v[38:41]
	v_mfma_f32_16x16x32_bf16 v[26:29], v[152:155], v[200:203], v[26:29]
	v_mfma_f32_16x16x32_bf16 v[22:25], v[160:163], v[200:203], v[22:25]
	v_mfma_f32_16x16x32_bf16 v[10:13], v[152:155], v[208:211], v[10:13]
	v_mfma_f32_16x16x32_bf16 v[6:9], v[160:163], v[208:211], v[6:9]
	v_mfma_f32_16x16x32_bf16 v[58:61], v[156:159], v[188:191], v[58:61]
	v_mfma_f32_16x16x32_bf16 v[54:57], v[164:167], v[188:191], v[54:57]
	v_mfma_f32_16x16x32_bf16 v[42:45], v[156:159], v[196:199], v[42:45]
	v_mfma_f32_16x16x32_bf16 v[38:41], v[164:167], v[196:199], v[38:41]
	v_mfma_f32_16x16x32_bf16 v[26:29], v[156:159], v[204:207], v[26:29]
	v_mfma_f32_16x16x32_bf16 v[22:25], v[164:167], v[204:207], v[22:25]
	v_mfma_f32_16x16x32_bf16 v[10:13], v[156:159], v[212:215], v[10:13]
	v_mfma_f32_16x16x32_bf16 v[6:9], v[164:167], v[212:215], v[6:9]
	v_mfma_f32_16x16x32_bf16 v[62:65], v[168:171], v[184:187], v[62:65]
	v_mfma_f32_16x16x32_bf16 v[50:53], v[176:179], v[184:187], v[50:53]
	v_mfma_f32_16x16x32_bf16 v[46:49], v[168:171], v[192:195], v[46:49]
	v_mfma_f32_16x16x32_bf16 v[34:37], v[176:179], v[192:195], v[34:37]
	v_mfma_f32_16x16x32_bf16 v[30:33], v[168:171], v[200:203], v[30:33]
	v_mfma_f32_16x16x32_bf16 v[18:21], v[176:179], v[200:203], v[18:21]
	v_mfma_f32_16x16x32_bf16 v[14:17], v[168:171], v[208:211], v[14:17]
	v_mfma_f32_16x16x32_bf16 v[2:5], v[176:179], v[208:211], v[2:5]
	v_mfma_f32_16x16x32_bf16 v[62:65], v[172:175], v[188:191], v[62:65]
	v_mfma_f32_16x16x32_bf16 v[50:53], v[180:183], v[188:191], v[50:53]
	v_mfma_f32_16x16x32_bf16 v[46:49], v[172:175], v[196:199], v[46:49]
	v_mfma_f32_16x16x32_bf16 v[34:37], v[180:183], v[196:199], v[34:37]
	v_mfma_f32_16x16x32_bf16 v[30:33], v[172:175], v[204:207], v[30:33]
	v_mfma_f32_16x16x32_bf16 v[18:21], v[180:183], v[204:207], v[18:21]
	v_mfma_f32_16x16x32_bf16 v[14:17], v[172:175], v[212:215], v[14:17]
	v_mfma_f32_16x16x32_bf16 v[2:5], v[180:183], v[212:215], v[2:5]
	s_barrier
; #define PG8_STAGE(bufoff, gbase, voff) do { _Pragma("unroll") for (int _i = 0; _i < 2; ++_i) \
;         __builtin_amdgcn_global_load_lds((const unsigned*)((const char*)(gbase) + (voff)[_i]), (LAS unsigned*)(lds + (bufoff) + ldsw + _i * 8192), 16, 0, 0); } while (0)
; #define PG8_LDA(dst, b, h) do { _Pragma("unroll") for (int m = 0; m < 4; ++m) _Pragma("unroll") for (int k = 0; k < 2; ++k) dst[m][k] = *(const LAS bf16x8*)(lds + PG8_SA(b, h) + aoff + m * 2048 + k * 1024); } while (0)
; #define PG8_LDB(dst, b, h) do { _Pragma("unroll") for (int n = 0; n < 2; ++n) _Pragma("unroll") for (int k = 0; k < 2; ++k) dst[n][k] = *(const LAS bf16x8*)(lds + PG8_SB(b, h) + boff + n * 2048 + k * 1024); } while (0)
; #define PG8_MMA(ai, bj, At, Bt) do { __builtin_amdgcn_s_setprio(1); _Pragma("unroll") for (int m = 0; m < 4; ++m) _Pragma("unroll") for (int n = 0; n < 2; ++n) _Pragma("unroll") for (int k = 0; k < 2; ++k) \
;         acc[ai][bj][m][n] = __builtin_amdgcn_mfma_f32_16x16x32_bf16(Bt[n][k], At[m][k], acc[ai][bj][m][n], 0, 0, 0); __builtin_amdgcn_s_setprio(0); } while (0)
; #define PG8_WAIT_V(n) asm volatile("s_waitcnt vmcnt(" #n ")" ::: "memory")
; #define PG8_WAIT_L(n) asm volatile("s_waitcnt lgkmcnt(" #n ")" ::: "memory")
; #define PG8_BAR __builtin_amdgcn_s_barrier()
; #define PG8_SCHED __builtin_amdgcn_sched_barrier(0)
; template <class Epi, class Sched, bool ABLK = false, bool ALIGN_EPI = true, bool SP2 = true, bool BBLK = true>
; __device__ __forceinline__ void gemm_phase(LAS unsigned char* lds, const Gemm g, const Sched& S, const Epi& E) {
;     ...
;             PG8_LDB(B0, 1, 0); PG8_LDB(B1, 1, 1); PG8_SCHED; PG8_LDA(At, 1, 0); PG8_STAGE(PG8_SA(0, 1), a2 + hstepA, voffA);
;             PG8_WAIT_V(8); PG8_WAIT_L(0); PG8_BAR; PG8_MMA(0, 0, At, B0); PG8_MMA(0, 1, At, B1); PG8_BAR; PG8_SCHED;
;             PG8_LDA(At, 1, 1); PG8_STAGE(PG8_SB(1, 0), b3, voffB); PG8_STAGE(PG8_SB(1, 1), b3 + hstepB, voffB); PG8_STAGE(PG8_SA(1, 0), a3, voffA);
;             PG8_WAIT_V(8); PG8_WAIT_L(0); PG8_BAR; PG8_MMA(1, 0, At, B0); PG8_MMA(1, 1, At, B1); PG8_BAR; PG8_SCHED;
;     ...
;         if constexpr (ALIGN_EPI) { if (wr == 0) PG8_BAR; }
	v_add_u32_e32 v151, s60, v146
	ds_read_b128 v[152:155], v151
	ds_read_b128 v[156:159], v151 offset:1024
	ds_read_b128 v[160:163], v151 offset:2048
	ds_read_b128 v[164:167], v151 offset:3072
	v_add_u32_e32 v151, s61, v146
	ds_read_b128 v[168:171], v151
	ds_read_b128 v[172:175], v151 offset:1024
	ds_read_b128 v[176:179], v151 offset:2048
	ds_read_b128 v[180:183], v151 offset:3072
	ds_read_b128 v[184:187], v150 offset:32768
	ds_read_b128 v[188:191], v150 offset:33792
	ds_read_b128 v[192:195], v150 offset:34816
	ds_read_b128 v[196:199], v150 offset:35840
	ds_read_b128 v[200:203], v150 offset:36864
	ds_read_b128 v[204:207], v150 offset:37888
	ds_read_b128 v[208:211], v150 offset:38912
	ds_read_b128 v[212:215], v150 offset:39936
	s_add_u32 s34, s34, 0x80000
	s_addc_u32 s35, s35, 0
	s_mov_b32 m0, s39
	s_nop 0
	global_load_lds_dwordx4 v136, s[34:35]
	s_mov_b32 m0, s40
	s_nop 0
	global_load_lds_dwordx4 v132, s[34:35]
	s_waitcnt vmcnt(8) lgkmcnt(0)
	s_barrier
	v_mfma_f32_16x16x32_bf16 v[122:125], v[152:155], v[184:187], v[122:125]
	v_mfma_f32_16x16x32_bf16 v[118:121], v[160:163], v[184:187], v[118:121]
	v_mfma_f32_16x16x32_bf16 v[106:109], v[152:155], v[192:195], v[106:109]
	v_mfma_f32_16x16x32_bf16 v[102:105], v[160:163], v[192:195], v[102:105]
	v_mfma_f32_16x16x32_bf16 v[90:93], v[152:155], v[200:203], v[90:93]
	v_mfma_f32_16x16x32_bf16 v[86:89], v[160:163], v[200:203], v[86:89]
	v_mfma_f32_16x16x32_bf16 v[74:77], v[152:155], v[208:211], v[74:77]
	v_mfma_f32_16x16x32_bf16 v[70:73], v[160:163], v[208:211], v[70:73]
	v_mfma_f32_16x16x32_bf16 v[122:125], v[156:159], v[188:191], v[122:125]
	v_mfma_f32_16x16x32_bf16 v[118:121], v[164:167], v[188:191], v[118:121]
	v_mfma_f32_16x16x32_bf16 v[106:109], v[156:159], v[196:199], v[106:109]
	v_mfma_f32_16x16x32_bf16 v[102:105], v[164:167], v[196:199], v[102:105]
	v_mfma_f32_16x16x32_bf16 v[90:93], v[156:159], v[204:207], v[90:93]
	v_mfma_f32_16x16x32_bf16 v[86:89], v[164:167], v[204:207], v[86:89]
	v_mfma_f32_16x16x32_bf16 v[74:77], v[156:159], v[212:215], v[74:77]
	v_mfma_f32_16x16x32_bf16 v[70:73], v[164:167], v[212:215], v[70:73]
	v_mfma_f32_16x16x32_bf16 v[126:129], v[168:171], v[184:187], v[126:129]
	v_mfma_f32_16x16x32_bf16 v[114:117], v[176:179], v[184:187], v[114:117]
	v_mfma_f32_16x16x32_bf16 v[110:113], v[168:171], v[192:195], v[110:113]
	v_mfma_f32_16x16x32_bf16 v[98:101], v[176:179], v[192:195], v[98:101]
	v_mfma_f32_16x16x32_bf16 v[94:97], v[168:171], v[200:203], v[94:97]
	v_mfma_f32_16x16x32_bf16 v[82:85], v[176:179], v[200:203], v[82:85]
	v_mfma_f32_16x16x32_bf16 v[78:81], v[168:171], v[208:211], v[78:81]
	v_mfma_f32_16x16x32_bf16 v[66:69], v[176:179], v[208:211], v[66:69]
	v_mfma_f32_16x16x32_bf16 v[126:129], v[172:175], v[188:191], v[126:129]
	v_mfma_f32_16x16x32_bf16 v[114:117], v[180:183], v[188:191], v[114:117]
	v_mfma_f32_16x16x32_bf16 v[110:113], v[172:175], v[196:199], v[110:113]
	v_mfma_f32_16x16x32_bf16 v[98:101], v[180:183], v[196:199], v[98:101]
	v_mfma_f32_16x16x32_bf16 v[94:97], v[172:175], v[204:207], v[94:97]
	v_mfma_f32_16x16x32_bf16 v[82:85], v[180:183], v[204:207], v[82:85]
	v_mfma_f32_16x16x32_bf16 v[78:81], v[172:175], v[212:215], v[78:81]
	v_mfma_f32_16x16x32_bf16 v[66:69], v[180:183], v[212:215], v[66:69]
	s_barrier
	ds_read_b128 v[184:187], v150 offset:49152
	ds_read_b128 v[188:191], v150 offset:50176
	ds_read_b128 v[192:195], v150 offset:51200
	ds_read_b128 v[196:199], v150 offset:52224
	ds_read_b128 v[200:203], v150 offset:53248
	ds_read_b128 v[204:207], v150 offset:54272
	ds_read_b128 v[208:211], v150 offset:55296
	ds_read_b128 v[212:215], v150 offset:56320
	s_add_u32 s34, s30, 0x8000
	s_addc_u32 s35, s31, 0
	s_add_i32 s53, s60, s36
	s_mov_b32 m0, s53
	s_nop 0
	global_load_lds_dwordx4 v134, s[34:35]
	s_add_i32 m0, s53, 0x2000
	s_add_u32 s30, s30, 0xc000
	v_lshl_add_u64 v[216:217], s[34:35], 0, v[130:131]
	s_addc_u32 s31, s31, 0
	s_add_i32 s34, s61, s36
	global_load_lds_dwordx4 v[216:217], off
	s_mov_b32 m0, s34
	s_nop 0
	global_load_lds_dwordx4 v134, s[30:31]
	s_add_i32 m0, s34, 0x2000
	s_nop 0
	global_load_lds_dwordx4 v130, s[30:31]
	s_mov_b32 m0, s42
	s_nop 0
	global_load_lds_dwordx4 v136, s[28:29]
	s_mov_b32 m0, s43
	s_nop 0
	global_load_lds_dwordx4 v132, s[28:29]
	s_waitcnt vmcnt(8) lgkmcnt(0)
	s_barrier
	v_mfma_f32_16x16x32_bf16 v[58:61], v[152:155], v[184:187], v[58:61]
	v_mfma_f32_16x16x32_bf16 v[54:57], v[160:163], v[184:187], v[54:57]
	v_mfma_f32_16x16x32_bf16 v[42:45], v[152:155], v[192:195], v[42:45]
	v_mfma_f32_16x16x32_bf16 v[38:41], v[160:163], v[192:195], v[38:41]
	v_mfma_f32_16x16x32_bf16 v[26:29], v[152:155], v[200:203], v[26:29]
	v_mfma_f32_16x16x32_bf16 v[22:25], v[160:163], v[200:203], v[22:25]
	v_mfma_f32_16x16x32_bf16 v[10:13], v[152:155], v[208:211], v[10:13]
	v_mfma_f32_16x16x32_bf16 v[6:9], v[160:163], v[208:211], v[6:9]
	v_mfma_f32_16x16x32_bf16 v[58:61], v[156:159], v[188:191], v[58:61]
	v_mfma_f32_16x16x32_bf16 v[54:57], v[164:167], v[188:191], v[54:57]
	v_mfma_f32_16x16x32_bf16 v[42:45], v[156:159], v[196:199], v[42:45]
	v_mfma_f32_16x16x32_bf16 v[38:41], v[164:167], v[196:199], v[38:41]
	v_mfma_f32_16x16x32_bf16 v[26:29], v[156:159], v[204:207], v[26:29]
	v_mfma_f32_16x16x32_bf16 v[22:25], v[164:167], v[204:207], v[22:25]
	v_mfma_f32_16x16x32_bf16 v[10:13], v[156:159], v[212:215], v[10:13]
	v_mfma_f32_16x16x32_bf16 v[6:9], v[164:167], v[212:215], v[6:9]
	v_mfma_f32_16x16x32_bf16 v[62:65], v[168:171], v[184:187], v[62:65]
	v_mfma_f32_16x16x32_bf16 v[50:53], v[176:179], v[184:187], v[50:53]
	v_mfma_f32_16x16x32_bf16 v[46:49], v[168:171], v[192:195], v[46:49]
	v_mfma_f32_16x16x32_bf16 v[34:37], v[176:179], v[192:195], v[34:37]
	v_mfma_f32_16x16x32_bf16 v[30:33], v[168:171], v[200:203], v[30:33]
	v_mfma_f32_16x16x32_bf16 v[18:21], v[176:179], v[200:203], v[18:21]
	v_mfma_f32_16x16x32_bf16 v[14:17], v[168:171], v[208:211], v[14:17]
	v_mfma_f32_16x16x32_bf16 v[2:5], v[176:179], v[208:211], v[2:5]
	v_mfma_f32_16x16x32_bf16 v[62:65], v[172:175], v[188:191], v[62:65]
	v_mfma_f32_16x16x32_bf16 v[50:53], v[180:183], v[188:191], v[50:53]
	v_mfma_f32_16x16x32_bf16 v[46:49], v[172:175], v[196:199], v[46:49]
	v_mfma_f32_16x16x32_bf16 v[34:37], v[180:183], v[196:199], v[34:37]
	v_mfma_f32_16x16x32_bf16 v[30:33], v[172:175], v[204:207], v[30:33]
	v_mfma_f32_16x16x32_bf16 v[18:21], v[180:183], v[204:207], v[18:21]
	v_mfma_f32_16x16x32_bf16 v[14:17], v[172:175], v[212:215], v[14:17]
	v_mfma_f32_16x16x32_bf16 v[2:5], v[180:183], v[212:215], v[2:5]
	s_barrier
	s_add_i32 s52, s52, 2
	s_add_u32 s26, s26, 0x100
	s_addc_u32 s27, s27, 0
	s_add_u32 s50, s50, 0x10000
	s_addc_u32 s51, s51, 0
	s_cmp_gt_u32 s52, 29
	s_cbranch_scc0 .LBB0_2138
	s_and_b64 vcc, exec, s[6:7]
	s_cbranch_vccz .LBB0_2141
	s_barrier

; #define PG8_STAGE(bufoff, gbase, voff) do { _Pragma("unroll") for (int _i = 0; _i < 2; ++_i) \
;         __builtin_amdgcn_global_load_lds((const unsigned*)((const char*)(gbase) + (voff)[_i]), (LAS unsigned*)(lds + (bufoff) + ldsw + _i * 8192), 16, 0, 0); } while (0)
; #define PG8_LDA(dst, b, h) do { _Pragma("unroll") for (int m = 0; m < 4; ++m) _Pragma("unroll") for (int k = 0; k < 2; ++k) dst[m][k] = *(const LAS bf16x8*)(lds + PG8_SA(b, h) + aoff + m * 2048 + k * 1024); } while (0)
; #define PG8_LDB(dst, b, h) do { _Pragma("unroll") for (int n = 0; n < 2; ++n) _Pragma("unroll") for (int k = 0; k < 2; ++k) dst[n][k] = *(const LAS bf16x8*)(lds + PG8_SB(b, h) + boff + n * 2048 + k * 1024); } while (0)
; #define PG8_WAIT_V(n) asm volatile("s_waitcnt vmcnt(" #n ")" ::: "memory")
; #define PG8_WAIT_L(n) asm volatile("s_waitcnt lgkmcnt(" #n ")" ::: "memory")
; template <class Epi, class Sched, bool ABLK = false, bool ALIGN_EPI = true, bool SP2 = true, bool BBLK = true>
; __device__ __forceinline__ void gemm_phase(LAS unsigned char* lds, const Gemm g, const Sched& S, const Epi& E) {
;     ...
;         const bool has_next = S.next(ui + 1, nxt);
;         const int nt = cur.nt;
;         const char* nuA = has_next ? a_unit(nxt) : uA; const int ntbA = has_next ? nxt.k0 / BK : tbA; const char* nB = has_next ? (const char*)g.Bt + (size_t)nxt.pn * tstepB + b_k0(nxt.k0) : cB;
;         for (int t = 0; t < nt; t += 2) {
;             const bool last = (t == nt - 2);
;             const char* a1 = a_tile(uA, tbA + t + 1);
;             const char* a2 = last ? a_tile(nuA, ntbA) : a_tile(uA, tbA + t + 2); const char* b2 = last ? nB : cB + (size_t)(t + 2) * kstepB;
;             const char* a3 = last ? a_tile(nuA, ntbA + 1) : a_tile(uA, tbA + t + 3); const char* b3 = b2 + kstepB;
;             if (last && has_next) S.a_ready(nxt);
;             if constexpr (SP2) {
;             PG8_LDB(B0, 0, 0); PG8_LDB(B1, 0, 1); PG8_SCHED; PG8_LDA(At, 0, 0); PG8_STAGE(PG8_SA(1, 1), a1 + hstepA, voffA);
;             PG8_WAIT_V(8); PG8_WAIT_L(0); PG8_BAR; PG8_MMA(0, 0, At, B0); PG8_MMA(0, 1, At, B1); PG8_BAR; PG8_SCHED;
;             PG8_LDA(At, 0, 1); PG8_STAGE(PG8_SB(0, 0), b2, voffB); PG8_STAGE(PG8_SB(0, 1), b2 + hstepB, voffB); PG8_STAGE(PG8_SA(0, 0), a2, voffA);
;             PG8_WAIT_V(8); PG8_WAIT_L(0); PG8_BAR; PG8_MMA(1, 0, At, B0); PG8_MMA(1, 1, At, B1); PG8_BAR; PG8_SCHED;
.LBB0_2262:
	ds_read_b128 v[172:175], v168
	ds_read_b128 v[176:179], v168 offset:1024
	ds_read_b128 v[180:183], v168 offset:2048
	ds_read_b128 v[184:187], v168 offset:3072
	ds_read_b128 v[188:191], v169
	ds_read_b128 v[192:195], v169 offset:1024
	ds_read_b128 v[196:199], v169 offset:2048
	ds_read_b128 v[200:203], v169 offset:3072
	ds_read_b128 v[204:207], v170
	ds_read_b128 v[208:211], v170 offset:1024
	ds_read_b128 v[212:215], v170 offset:2048
	ds_read_b128 v[216:219], v170 offset:3072
	ds_read_b128 v[220:223], v170 offset:4096
	ds_read_b128 v[224:227], v170 offset:5120
	ds_read_b128 v[228:231], v170 offset:6144
	ds_read_b128 v[232:235], v170 offset:7168
	s_ashr_i32 s13, s12, 31
	s_lshl_b64 s[4:5], s[12:13], 20
	s_add_u32 s16, s41, s4
	s_addc_u32 s17, s42, s5
	s_and_b64 s[4:5], s[18:19], exec
	s_cselect_b32 s4, s17, s27
	s_cselect_b32 s5, s16, s26
	s_ashr_i32 s15, s14, 31
	s_lshl_b64 s[20:21], s[14:15], 20
	s_add_u32 s20, s38, s20
	s_addc_u32 s21, s39, s21
	s_and_b64 s[30:31], s[18:19], exec
	s_cselect_b32 s13, s21, s29
	s_cselect_b32 s15, s20, s28
	s_add_u32 s23, s5, 0x80
	s_addc_u32 s54, s4, 0
	s_add_u32 s55, s28, 0x10000
	v_mov_b32_e32 v2, 0
	s_addc_u32 s56, s29, 0
	v_lshl_add_u64 v[164:165], s[26:27], 0, v[160:161]
	v_lshl_add_u64 v[166:167], s[26:27], 0, v[162:163]
	s_mov_b32 s57, -2
	s_mov_b64 s[28:29], 0
	s_add_u32 s30, s26, s28
	s_addc_u32 s31, s27, s29
	s_add_u32 s36, s30, 0x100
	s_addc_u32 s37, s31, 0
	s_add_u32 s30, s30, 0x180
	s_addc_u32 s31, s31, 0
	s_cmpk_eq_i32 s28, 0xf00
	s_cselect_b32 s31, s54, s31
	s_cselect_b32 s30, s23, s30
	s_cselect_b32 s35, s13, s56
	s_cselect_b32 s34, s15, s55
	s_cselect_b32 s37, s4, s37
	s_cselect_b32 s36, s5, s36
	s_mov_b32 m0, s50
	v_lshl_add_u64 v[236:237], v[164:165], 0, s[28:29]
	global_load_lds_dwordx4 v[236:237], off
	v_lshl_add_u64 v[236:237], v[166:167], 0, s[28:29]
	s_mov_b32 m0, s51
	s_nop 0
	global_load_lds_dwordx4 v[236:237], off
	s_waitcnt vmcnt(8) lgkmcnt(0)
	s_barrier
	v_mfma_f32_16x16x32_bf16 v[126:129], v[172:175], v[204:207], 0
	v_mfma_f32_16x16x32_bf16 v[122:125], v[180:183], v[204:207], 0
	v_mfma_f32_16x16x32_bf16 v[110:113], v[172:175], v[212:215], 0
	v_mfma_f32_16x16x32_bf16 v[106:109], v[180:183], v[212:215], 0
	v_mfma_f32_16x16x32_bf16 v[94:97], v[172:175], v[220:223], 0
	v_mfma_f32_16x16x32_bf16 v[90:93], v[180:183], v[220:223], 0
	v_mfma_f32_16x16x32_bf16 v[78:81], v[172:175], v[228:231], 0
	v_mfma_f32_16x16x32_bf16 v[74:77], v[180:183], v[228:231], 0
	v_mfma_f32_16x16x32_bf16 v[126:129], v[176:179], v[208:211], v[126:129]
	v_mfma_f32_16x16x32_bf16 v[122:125], v[184:187], v[208:211], v[122:125]
	v_mfma_f32_16x16x32_bf16 v[110:113], v[176:179], v[216:219], v[110:113]
	v_mfma_f32_16x16x32_bf16 v[106:109], v[184:187], v[216:219], v[106:109]
	v_mfma_f32_16x16x32_bf16 v[94:97], v[176:179], v[224:227], v[94:97]
	v_mfma_f32_16x16x32_bf16 v[90:93], v[184:187], v[224:227], v[90:93]
	v_mfma_f32_16x16x32_bf16 v[78:81], v[176:179], v[232:235], v[78:81]
	v_mfma_f32_16x16x32_bf16 v[74:77], v[184:187], v[232:235], v[74:77]
	v_mfma_f32_16x16x32_bf16 v[118:121], v[188:191], v[204:207], 0
	v_mfma_f32_16x16x32_bf16 v[114:117], v[196:199], v[204:207], 0
	v_mfma_f32_16x16x32_bf16 v[102:105], v[188:191], v[212:215], 0
	v_mfma_f32_16x16x32_bf16 v[98:101], v[196:199], v[212:215], 0
	v_mfma_f32_16x16x32_bf16 v[86:89], v[188:191], v[220:223], 0
	v_mfma_f32_16x16x32_bf16 v[82:85], v[196:199], v[220:223], 0
	v_mfma_f32_16x16x32_bf16 v[70:73], v[188:191], v[228:231], 0
	v_mfma_f32_16x16x32_bf16 v[66:69], v[196:199], v[228:231], 0
	v_mfma_f32_16x16x32_bf16 v[118:121], v[192:195], v[208:211], v[118:121]
	v_mfma_f32_16x16x32_bf16 v[114:117], v[200:203], v[208:211], v[114:117]
	v_mfma_f32_16x16x32_bf16 v[102:105], v[192:195], v[216:219], v[102:105]
	v_mfma_f32_16x16x32_bf16 v[98:101], v[200:203], v[216:219], v[98:101]
	v_mfma_f32_16x16x32_bf16 v[86:89], v[192:195], v[224:227], v[86:89]
	v_mfma_f32_16x16x32_bf16 v[82:85], v[200:203], v[224:227], v[82:85]
	v_mfma_f32_16x16x32_bf16 v[70:73], v[192:195], v[232:235], v[70:73]
	v_mfma_f32_16x16x32_bf16 v[66:69], v[200:203], v[232:235], v[66:69]
	s_barrier
	ds_read_b128 v[204:207], v170 offset:16384
	ds_read_b128 v[208:211], v170 offset:17408
	ds_read_b128 v[212:215], v170 offset:18432
	ds_read_b128 v[216:219], v170 offset:19456
	ds_read_b128 v[220:223], v170 offset:20480
	ds_read_b128 v[224:227], v170 offset:21504
	ds_read_b128 v[228:231], v170 offset:22528
	ds_read_b128 v[232:235], v170 offset:23552
	s_mov_b32 m0, s52
	s_add_u32 s58, s34, 0x4000
	global_load_lds_dwordx4 v134, s[34:35]
	s_mov_b32 m0, s53
	s_addc_u32 s59, s35, 0
	s_add_i32 s62, s73, s40
	global_load_lds_dwordx4 v130, s[34:35]
	s_mov_b32 m0, s62
	s_nop 0
	global_load_lds_dwordx4 v134, s[58:59]
	s_add_i32 m0, s62, 0x2000
	s_nop 0
	global_load_lds_dwordx4 v130, s[58:59]
	s_mov_b32 m0, s25
	s_nop 0
	global_load_lds_dwordx4 v136, s[36:37]
	s_mov_b32 m0, s43
	s_nop 0
	global_load_lds_dwordx4 v132, s[36:37]
	s_waitcnt vmcnt(8) lgkmcnt(0)
	s_barrier
; #define PG8_STAGE(bufoff, gbase, voff) do { _Pragma("unroll") for (int _i = 0; _i < 2; ++_i) \
;         __builtin_amdgcn_global_load_lds((const unsigned*)((const char*)(gbase) + (voff)[_i]), (LAS unsigned*)(lds + (bufoff) + ldsw + _i * 8192), 16, 0, 0); } while (0)
; #define PG8_LDA(dst, b, h) do { _Pragma("unroll") for (int m = 0; m < 4; ++m) _Pragma("unroll") for (int k = 0; k < 2; ++k) dst[m][k] = *(const LAS bf16x8*)(lds + PG8_SA(b, h) + aoff + m * 2048 + k * 1024); } while (0)
; #define PG8_LDB(dst, b, h) do { _Pragma("unroll") for (int n = 0; n < 2; ++n) _Pragma("unroll") for (int k = 0; k < 2; ++k) dst[n][k] = *(const LAS bf16x8*)(lds + PG8_SB(b, h) + boff + n * 2048 + k * 1024); } while (0)
; #define PG8_MMA(ai, bj, At, Bt) do { __builtin_amdgcn_s_setprio(1); _Pragma("unroll") for (int m = 0; m < 4; ++m) _Pragma("unroll") for (int n = 0; n < 2; ++n) _Pragma("unroll") for (int k = 0; k < 2; ++k) \
;         acc[ai][bj][m][n] = __builtin_amdgcn_mfma_f32_16x16x32_bf16(Bt[n][k], At[m][k], acc[ai][bj][m][n], 0, 0, 0); __builtin_amdgcn_s_setprio(0); } while (0)
; #define PG8_WAIT_V(n) asm volatile("s_waitcnt vmcnt(" #n ")" ::: "memory")
; #define PG8_WAIT_L(n) asm volatile("s_waitcnt lgkmcnt(" #n ")" ::: "memory")
; #define PG8_BAR __builtin_amdgcn_s_barrier()
; #define PG8_SCHED __builtin_amdgcn_sched_barrier(0)
; template <class Epi, class Sched, bool ABLK = false, bool ALIGN_EPI = true, bool SP2 = true, bool BBLK = true>
; __device__ __forceinline__ void gemm_phase(LAS unsigned char* lds, const Gemm g, const Sched& S, const Epi& E) {
;     ...
;             PG8_WAIT_V(8); PG8_WAIT_L(0); PG8_BAR; PG8_MMA(1, 0, At, B0); PG8_MMA(1, 1, At, B1); PG8_BAR; PG8_SCHED;
;             PG8_LDB(B0, 1, 0); PG8_LDB(B1, 1, 1); PG8_SCHED; PG8_LDA(At, 1, 0); PG8_STAGE(PG8_SA(0, 1), a2 + hstepA, voffA);
;             PG8_WAIT_V(8); PG8_WAIT_L(0); PG8_BAR; PG8_MMA(0, 0, At, B0); PG8_MMA(0, 1, At, B1); PG8_BAR; PG8_SCHED;
	v_mfma_f32_16x16x32_bf16 v[62:65], v[172:175], v[204:207], 0
	v_mfma_f32_16x16x32_bf16 v[58:61], v[180:183], v[204:207], 0
	v_mfma_f32_16x16x32_bf16 v[46:49], v[172:175], v[212:215], 0
	v_mfma_f32_16x16x32_bf16 v[42:45], v[180:183], v[212:215], 0
	v_mfma_f32_16x16x32_bf16 v[30:33], v[172:175], v[220:223], 0
	v_mfma_f32_16x16x32_bf16 v[26:29], v[180:183], v[220:223], 0
	v_mfma_f32_16x16x32_bf16 v[14:17], v[172:175], v[228:231], 0
	v_mfma_f32_16x16x32_bf16 v[10:13], v[180:183], v[228:231], 0
	v_mfma_f32_16x16x32_bf16 v[62:65], v[176:179], v[208:211], v[62:65]
	v_mfma_f32_16x16x32_bf16 v[58:61], v[184:187], v[208:211], v[58:61]
	v_mfma_f32_16x16x32_bf16 v[46:49], v[176:179], v[216:219], v[46:49]
	v_mfma_f32_16x16x32_bf16 v[42:45], v[184:187], v[216:219], v[42:45]
	v_mfma_f32_16x16x32_bf16 v[30:33], v[176:179], v[224:227], v[30:33]
	v_mfma_f32_16x16x32_bf16 v[26:29], v[184:187], v[224:227], v[26:29]
	v_mfma_f32_16x16x32_bf16 v[14:17], v[176:179], v[232:235], v[14:17]
	v_mfma_f32_16x16x32_bf16 v[10:13], v[184:187], v[232:235], v[10:13]
	v_mfma_f32_16x16x32_bf16 v[54:57], v[188:191], v[204:207], 0
	v_mfma_f32_16x16x32_bf16 v[50:53], v[196:199], v[204:207], 0
	v_mfma_f32_16x16x32_bf16 v[38:41], v[188:191], v[212:215], 0
	v_mfma_f32_16x16x32_bf16 v[34:37], v[196:199], v[212:215], 0
	v_mfma_f32_16x16x32_bf16 v[22:25], v[188:191], v[220:223], 0
	v_mfma_f32_16x16x32_bf16 v[18:21], v[196:199], v[220:223], 0
	v_mfma_f32_16x16x32_bf16 v[6:9], v[188:191], v[228:231], 0
	v_mfma_f32_16x16x32_bf16 v[2:5], v[196:199], v[228:231], 0
	v_mfma_f32_16x16x32_bf16 v[54:57], v[192:195], v[208:211], v[54:57]
	v_mfma_f32_16x16x32_bf16 v[50:53], v[200:203], v[208:211], v[50:53]
	v_mfma_f32_16x16x32_bf16 v[38:41], v[192:195], v[216:219], v[38:41]
	v_mfma_f32_16x16x32_bf16 v[34:37], v[200:203], v[216:219], v[34:37]
	v_mfma_f32_16x16x32_bf16 v[22:25], v[192:195], v[224:227], v[22:25]
	v_mfma_f32_16x16x32_bf16 v[18:21], v[200:203], v[224:227], v[18:21]
	v_mfma_f32_16x16x32_bf16 v[6:9], v[192:195], v[232:235], v[6:9]
	v_mfma_f32_16x16x32_bf16 v[2:5], v[200:203], v[232:235], v[2:5]
	s_barrier
	v_add_u32_e32 v171, s60, v1
	ds_read_b128 v[172:175], v171
	ds_read_b128 v[176:179], v171 offset:1024
	ds_read_b128 v[180:183], v171 offset:2048
	ds_read_b128 v[184:187], v171 offset:3072
	v_add_u32_e32 v171, s61, v1
	ds_read_b128 v[188:191], v171
	ds_read_b128 v[192:195], v171 offset:1024
	ds_read_b128 v[196:199], v171 offset:2048
	ds_read_b128 v[200:203], v171 offset:3072
	ds_read_b128 v[204:207], v170 offset:32768
	ds_read_b128 v[208:211], v170 offset:33792
	ds_read_b128 v[212:215], v170 offset:34816
	ds_read_b128 v[216:219], v170 offset:35840
	ds_read_b128 v[220:223], v170 offset:36864
	ds_read_b128 v[224:227], v170 offset:37888
	ds_read_b128 v[228:231], v170 offset:38912
	ds_read_b128 v[232:235], v170 offset:39936
	s_add_u32 s36, s36, 0x80000
	s_addc_u32 s37, s37, 0
	s_mov_b32 m0, s44
	s_nop 0
	global_load_lds_dwordx4 v136, s[36:37]
	s_mov_b32 m0, s45
	s_nop 0
	global_load_lds_dwordx4 v132, s[36:37]
	s_waitcnt vmcnt(8) lgkmcnt(0)
	s_barrier
	v_mfma_f32_16x16x32_bf16 v[126:129], v[172:175], v[204:207], v[126:129]
	v_mfma_f32_16x16x32_bf16 v[122:125], v[180:183], v[204:207], v[122:125]
	v_mfma_f32_16x16x32_bf16 v[110:113], v[172:175], v[212:215], v[110:113]
	v_mfma_f32_16x16x32_bf16 v[106:109], v[180:183], v[212:215], v[106:109]
	v_mfma_f32_16x16x32_bf16 v[94:97], v[172:175], v[220:223], v[94:97]
	v_mfma_f32_16x16x32_bf16 v[90:93], v[180:183], v[220:223], v[90:93]
	v_mfma_f32_16x16x32_bf16 v[78:81], v[172:175], v[228:231], v[78:81]
	v_mfma_f32_16x16x32_bf16 v[74:77], v[180:183], v[228:231], v[74:77]
	v_mfma_f32_16x16x32_bf16 v[126:129], v[176:179], v[208:211], v[126:129]
	v_mfma_f32_16x16x32_bf16 v[122:125], v[184:187], v[208:211], v[122:125]
	v_mfma_f32_16x16x32_bf16 v[110:113], v[176:179], v[216:219], v[110:113]
	v_mfma_f32_16x16x32_bf16 v[106:109], v[184:187], v[216:219], v[106:109]
	v_mfma_f32_16x16x32_bf16 v[94:97], v[176:179], v[224:227], v[94:97]
	v_mfma_f32_16x16x32_bf16 v[90:93], v[184:187], v[224:227], v[90:93]
	v_mfma_f32_16x16x32_bf16 v[78:81], v[176:179], v[232:235], v[78:81]
	v_mfma_f32_16x16x32_bf16 v[74:77], v[184:187], v[232:235], v[74:77]
	v_mfma_f32_16x16x32_bf16 v[118:121], v[188:191], v[204:207], v[118:121]
	v_mfma_f32_16x16x32_bf16 v[114:117], v[196:199], v[204:207], v[114:117]
	v_mfma_f32_16x16x32_bf16 v[102:105], v[188:191], v[212:215], v[102:105]
	v_mfma_f32_16x16x32_bf16 v[98:101], v[196:199], v[212:215], v[98:101]
	v_mfma_f32_16x16x32_bf16 v[86:89], v[188:191], v[220:223], v[86:89]
	v_mfma_f32_16x16x32_bf16 v[82:85], v[196:199], v[220:223], v[82:85]
	v_mfma_f32_16x16x32_bf16 v[70:73], v[188:191], v[228:231], v[70:73]
	v_mfma_f32_16x16x32_bf16 v[66:69], v[196:199], v[228:231], v[66:69]
	v_mfma_f32_16x16x32_bf16 v[118:121], v[192:195], v[208:211], v[118:121]
	v_mfma_f32_16x16x32_bf16 v[114:117], v[200:203], v[208:211], v[114:117]
	v_mfma_f32_16x16x32_bf16 v[102:105], v[192:195], v[216:219], v[102:105]
	v_mfma_f32_16x16x32_bf16 v[98:101], v[200:203], v[216:219], v[98:101]
	v_mfma_f32_16x16x32_bf16 v[86:89], v[192:195], v[224:227], v[86:89]
	v_mfma_f32_16x16x32_bf16 v[82:85], v[200:203], v[224:227], v[82:85]
	v_mfma_f32_16x16x32_bf16 v[70:73], v[192:195], v[232:235], v[70:73]
	v_mfma_f32_16x16x32_bf16 v[66:69], v[200:203], v[232:235], v[66:69]
	s_barrier
; #define PG8_STAGE(bufoff, gbase, voff) do { _Pragma("unroll") for (int _i = 0; _i < 2; ++_i) \
;         __builtin_amdgcn_global_load_lds((const unsigned*)((const char*)(gbase) + (voff)[_i]), (LAS unsigned*)(lds + (bufoff) + ldsw + _i * 8192), 16, 0, 0); } while (0)
; #define PG8_LDA(dst, b, h) do { _Pragma("unroll") for (int m = 0; m < 4; ++m) _Pragma("unroll") for (int k = 0; k < 2; ++k) dst[m][k] = *(const LAS bf16x8*)(lds + PG8_SA(b, h) + aoff + m * 2048 + k * 1024); } while (0)
; #define PG8_LDB(dst, b, h) do { _Pragma("unroll") for (int n = 0; n < 2; ++n) _Pragma("unroll") for (int k = 0; k < 2; ++k) dst[n][k] = *(const LAS bf16x8*)(lds + PG8_SB(b, h) + boff + n * 2048 + k * 1024); } while (0)
; #define PG8_MMA(ai, bj, At, Bt) do { __builtin_amdgcn_s_setprio(1); _Pragma("unroll") for (int m = 0; m < 4; ++m) _Pragma("unroll") for (int n = 0; n < 2; ++n) _Pragma("unroll") for (int k = 0; k < 2; ++k) \
;         acc[ai][bj][m][n] = __builtin_amdgcn_mfma_f32_16x16x32_bf16(Bt[n][k], At[m][k], acc[ai][bj][m][n], 0, 0, 0); __builtin_amdgcn_s_setprio(0); } while (0)
; #define PG8_BAR __builtin_amdgcn_s_barrier()
; template <class Epi, class Sched, bool ABLK = false, bool ALIGN_EPI = true, bool SP2 = true, bool BBLK = true>
; __device__ __forceinline__ void gemm_phase(LAS unsigned char* lds, const Gemm g, const Sched& S, const Epi& E) {
;     ...
;             PG8_LDB(B0, 0, 0); PG8_LDB(B1, 0, 1); PG8_SCHED; PG8_LDA(At, 0, 0); PG8_STAGE(PG8_SA(1, 1), a1 + hstepA, voffA);
;             PG8_WAIT_V(8); PG8_WAIT_L(0); PG8_BAR; PG8_MMA(0, 0, At, B0); PG8_MMA(0, 1, At, B1); PG8_BAR; PG8_SCHED;
;             PG8_LDA(At, 0, 1); PG8_STAGE(PG8_SB(0, 0), b2, voffB); PG8_STAGE(PG8_SB(0, 1), b2 + hstepB, voffB); PG8_STAGE(PG8_SA(0, 0), a2, voffA);
;             PG8_WAIT_V(8); PG8_WAIT_L(0); PG8_BAR; PG8_MMA(1, 0, At, B0); PG8_MMA(1, 1, At, B1); PG8_BAR; PG8_SCHED;
;             PG8_LDB(B0, 1, 0); PG8_LDB(B1, 1, 1); PG8_SCHED; PG8_LDA(At, 1, 0); PG8_STAGE(PG8_SA(0, 1), a2 + hstepA, voffA);
;             PG8_WAIT_V(8); PG8_WAIT_L(0); PG8_BAR; PG8_MMA(0, 0, At, B0); PG8_MMA(0, 1, At, B1); PG8_BAR; PG8_SCHED;
;             PG8_LDA(At, 1, 1); PG8_STAGE(PG8_SB(1, 0), b3, voffB); PG8_STAGE(PG8_SB(1, 1), b3 + hstepB, voffB); PG8_STAGE(PG8_SA(1, 0), a3, voffA);
;             PG8_WAIT_V(8); PG8_WAIT_L(0); PG8_BAR; PG8_MMA(1, 0, At, B0); PG8_MMA(1, 1, At, B1); PG8_BAR; PG8_SCHED;
	ds_read_b128 v[204:207], v170 offset:49152
	ds_read_b128 v[208:211], v170 offset:50176
	ds_read_b128 v[212:215], v170 offset:51200
	ds_read_b128 v[216:219], v170 offset:52224
	ds_read_b128 v[220:223], v170 offset:53248
	ds_read_b128 v[224:227], v170 offset:54272
	ds_read_b128 v[228:231], v170 offset:55296
	ds_read_b128 v[232:235], v170 offset:56320
	s_add_u32 s36, s34, 0x8000
	s_addc_u32 s37, s35, 0
	s_add_i32 s58, s60, s40
	s_mov_b32 m0, s58
	s_nop 0
	global_load_lds_dwordx4 v134, s[36:37]
	s_add_i32 m0, s58, 0x2000
	s_add_u32 s34, s34, 0xc000
	v_lshl_add_u64 v[236:237], s[36:37], 0, v[130:131]
	s_addc_u32 s35, s35, 0
	s_add_i32 s36, s61, s40
	global_load_lds_dwordx4 v[236:237], off
	s_mov_b32 m0, s36
	s_nop 0
	global_load_lds_dwordx4 v134, s[34:35]
	s_add_i32 m0, s36, 0x2000
	s_nop 0
	global_load_lds_dwordx4 v130, s[34:35]
	s_mov_b32 m0, s48
	s_nop 0
	global_load_lds_dwordx4 v136, s[30:31]
	s_mov_b32 m0, s49
	s_nop 0
	global_load_lds_dwordx4 v132, s[30:31]
	s_waitcnt vmcnt(8) lgkmcnt(0)
	s_barrier
	v_mfma_f32_16x16x32_bf16 v[62:65], v[172:175], v[204:207], v[62:65]
	v_mfma_f32_16x16x32_bf16 v[58:61], v[180:183], v[204:207], v[58:61]
	v_mfma_f32_16x16x32_bf16 v[46:49], v[172:175], v[212:215], v[46:49]
	v_mfma_f32_16x16x32_bf16 v[42:45], v[180:183], v[212:215], v[42:45]
	v_mfma_f32_16x16x32_bf16 v[30:33], v[172:175], v[220:223], v[30:33]
	v_mfma_f32_16x16x32_bf16 v[26:29], v[180:183], v[220:223], v[26:29]
	v_mfma_f32_16x16x32_bf16 v[14:17], v[172:175], v[228:231], v[14:17]
	v_mfma_f32_16x16x32_bf16 v[10:13], v[180:183], v[228:231], v[10:13]
	v_mfma_f32_16x16x32_bf16 v[62:65], v[176:179], v[208:211], v[62:65]
	v_mfma_f32_16x16x32_bf16 v[58:61], v[184:187], v[208:211], v[58:61]
	v_mfma_f32_16x16x32_bf16 v[46:49], v[176:179], v[216:219], v[46:49]
	v_mfma_f32_16x16x32_bf16 v[42:45], v[184:187], v[216:219], v[42:45]
	v_mfma_f32_16x16x32_bf16 v[30:33], v[176:179], v[224:227], v[30:33]
	v_mfma_f32_16x16x32_bf16 v[26:29], v[184:187], v[224:227], v[26:29]
	v_mfma_f32_16x16x32_bf16 v[14:17], v[176:179], v[232:235], v[14:17]
	v_mfma_f32_16x16x32_bf16 v[10:13], v[184:187], v[232:235], v[10:13]
	v_mfma_f32_16x16x32_bf16 v[54:57], v[188:191], v[204:207], v[54:57]
	v_mfma_f32_16x16x32_bf16 v[50:53], v[196:199], v[204:207], v[50:53]
	v_mfma_f32_16x16x32_bf16 v[38:41], v[188:191], v[212:215], v[38:41]
	v_mfma_f32_16x16x32_bf16 v[34:37], v[196:199], v[212:215], v[34:37]
	v_mfma_f32_16x16x32_bf16 v[22:25], v[188:191], v[220:223], v[22:25]
	v_mfma_f32_16x16x32_bf16 v[18:21], v[196:199], v[220:223], v[18:21]
	v_mfma_f32_16x16x32_bf16 v[6:9], v[188:191], v[228:231], v[6:9]
	v_mfma_f32_16x16x32_bf16 v[2:5], v[196:199], v[228:231], v[2:5]
	v_mfma_f32_16x16x32_bf16 v[54:57], v[192:195], v[208:211], v[54:57]
	v_mfma_f32_16x16x32_bf16 v[50:53], v[200:203], v[208:211], v[50:53]
	v_mfma_f32_16x16x32_bf16 v[38:41], v[192:195], v[216:219], v[38:41]
	v_mfma_f32_16x16x32_bf16 v[34:37], v[200:203], v[216:219], v[34:37]
	v_mfma_f32_16x16x32_bf16 v[22:25], v[192:195], v[224:227], v[22:25]
	v_mfma_f32_16x16x32_bf16 v[18:21], v[200:203], v[224:227], v[18:21]
	v_mfma_f32_16x16x32_bf16 v[6:9], v[192:195], v[232:235], v[6:9]
	v_mfma_f32_16x16x32_bf16 v[2:5], v[200:203], v[232:235], v[2:5]
	s_barrier
	s_add_i32 s57, s57, 2
	s_add_u32 s28, s28, 0x100
	s_addc_u32 s29, s29, 0
	s_add_u32 s55, s55, 0x10000
	s_addc_u32 s56, s56, 0
	s_cmp_gt_u32 s57, 29
.LBB0_2263:
	ds_read_b128 v[172:175], v168
	ds_read_b128 v[176:179], v168 offset:1024
	ds_read_b128 v[180:183], v168 offset:2048
	ds_read_b128 v[184:187], v168 offset:3072
	ds_read_b128 v[188:191], v169
	ds_read_b128 v[192:195], v169 offset:1024
	ds_read_b128 v[196:199], v169 offset:2048
	ds_read_b128 v[200:203], v169 offset:3072
	ds_read_b128 v[204:207], v170
	ds_read_b128 v[208:211], v170 offset:1024
	ds_read_b128 v[212:215], v170 offset:2048
	ds_read_b128 v[216:219], v170 offset:3072
	ds_read_b128 v[220:223], v170 offset:4096
	ds_read_b128 v[224:227], v170 offset:5120
	ds_read_b128 v[228:231], v170 offset:6144
	ds_read_b128 v[232:235], v170 offset:7168
	s_add_u32 s30, s26, s28
	s_addc_u32 s31, s27, s29
	s_add_u32 s36, s30, 0x100
	s_addc_u32 s37, s31, 0
	s_add_u32 s30, s30, 0x180
	s_addc_u32 s31, s31, 0
	s_cmpk_eq_i32 s28, 0xf00
	s_cselect_b32 s31, s54, s31
	s_cselect_b32 s30, s23, s30
	s_cselect_b32 s35, s13, s56
	s_cselect_b32 s34, s15, s55
	s_cselect_b32 s37, s4, s37
	s_cselect_b32 s36, s5, s36
	s_mov_b32 m0, s50
	v_lshl_add_u64 v[236:237], v[164:165], 0, s[28:29]
	global_load_lds_dwordx4 v[236:237], off
	v_lshl_add_u64 v[236:237], v[166:167], 0, s[28:29]
	s_mov_b32 m0, s51
	s_nop 0
	global_load_lds_dwordx4 v[236:237], off
	s_waitcnt vmcnt(8) lgkmcnt(0)
	s_barrier
; #define PG8_STAGE(bufoff, gbase, voff) do { _Pragma("unroll") for (int _i = 0; _i < 2; ++_i) \
;         __builtin_amdgcn_global_load_lds((const unsigned*)((const char*)(gbase) + (voff)[_i]), (LAS unsigned*)(lds + (bufoff) + ldsw + _i * 8192), 16, 0, 0); } while (0)
; #define PG8_LDA(dst, b, h) do { _Pragma("unroll") for (int m = 0; m < 4; ++m) _Pragma("unroll") for (int k = 0; k < 2; ++k) dst[m][k] = *(const LAS bf16x8*)(lds + PG8_SA(b, h) + aoff + m * 2048 + k * 1024); } while (0)
; #define PG8_MMA(ai, bj, At, Bt) do { __builtin_amdgcn_s_setprio(1); _Pragma("unroll") for (int m = 0; m < 4; ++m) _Pragma("unroll") for (int n = 0; n < 2; ++n) _Pragma("unroll") for (int k = 0; k < 2; ++k) \
;         acc[ai][bj][m][n] = __builtin_amdgcn_mfma_f32_16x16x32_bf16(Bt[n][k], At[m][k], acc[ai][bj][m][n], 0, 0, 0); __builtin_amdgcn_s_setprio(0); } while (0)
; #define PG8_WAIT_V(n) asm volatile("s_waitcnt vmcnt(" #n ")" ::: "memory")
; #define PG8_WAIT_L(n) asm volatile("s_waitcnt lgkmcnt(" #n ")" ::: "memory")
; #define PG8_BAR __builtin_amdgcn_s_barrier()
; #define PG8_SCHED __builtin_amdgcn_sched_barrier(0)
; template <class Epi, class Sched, bool ABLK = false, bool ALIGN_EPI = true, bool SP2 = true, bool BBLK = true>
; __device__ __forceinline__ void gemm_phase(LAS unsigned char* lds, const Gemm g, const Sched& S, const Epi& E) {
;     ...
;             PG8_WAIT_V(8); PG8_WAIT_L(0); PG8_BAR; PG8_MMA(0, 0, At, B0); PG8_MMA(0, 1, At, B1); PG8_BAR; PG8_SCHED;
;             PG8_LDA(At, 0, 1); PG8_STAGE(PG8_SB(0, 0), b2, voffB); PG8_STAGE(PG8_SB(0, 1), b2 + hstepB, voffB); PG8_STAGE(PG8_SA(0, 0), a2, voffA);
;             PG8_WAIT_V(8); PG8_WAIT_L(0); PG8_BAR; PG8_MMA(1, 0, At, B0); PG8_MMA(1, 1, At, B1); PG8_BAR; PG8_SCHED;
	v_mfma_f32_16x16x32_bf16 v[126:129], v[172:175], v[204:207], v[126:129]
	v_mfma_f32_16x16x32_bf16 v[122:125], v[180:183], v[204:207], v[122:125]
	v_mfma_f32_16x16x32_bf16 v[110:113], v[172:175], v[212:215], v[110:113]
	v_mfma_f32_16x16x32_bf16 v[106:109], v[180:183], v[212:215], v[106:109]
	v_mfma_f32_16x16x32_bf16 v[94:97], v[172:175], v[220:223], v[94:97]
	v_mfma_f32_16x16x32_bf16 v[90:93], v[180:183], v[220:223], v[90:93]
	v_mfma_f32_16x16x32_bf16 v[78:81], v[172:175], v[228:231], v[78:81]
	v_mfma_f32_16x16x32_bf16 v[74:77], v[180:183], v[228:231], v[74:77]
	v_mfma_f32_16x16x32_bf16 v[126:129], v[176:179], v[208:211], v[126:129]
	v_mfma_f32_16x16x32_bf16 v[122:125], v[184:187], v[208:211], v[122:125]
	v_mfma_f32_16x16x32_bf16 v[110:113], v[176:179], v[216:219], v[110:113]
	v_mfma_f32_16x16x32_bf16 v[106:109], v[184:187], v[216:219], v[106:109]
	v_mfma_f32_16x16x32_bf16 v[94:97], v[176:179], v[224:227], v[94:97]
	v_mfma_f32_16x16x32_bf16 v[90:93], v[184:187], v[224:227], v[90:93]
	v_mfma_f32_16x16x32_bf16 v[78:81], v[176:179], v[232:235], v[78:81]
	v_mfma_f32_16x16x32_bf16 v[74:77], v[184:187], v[232:235], v[74:77]
	v_mfma_f32_16x16x32_bf16 v[118:121], v[188:191], v[204:207], v[118:121]
	v_mfma_f32_16x16x32_bf16 v[114:117], v[196:199], v[204:207], v[114:117]
	v_mfma_f32_16x16x32_bf16 v[102:105], v[188:191], v[212:215], v[102:105]
	v_mfma_f32_16x16x32_bf16 v[98:101], v[196:199], v[212:215], v[98:101]
	v_mfma_f32_16x16x32_bf16 v[86:89], v[188:191], v[220:223], v[86:89]
	v_mfma_f32_16x16x32_bf16 v[82:85], v[196:199], v[220:223], v[82:85]
	v_mfma_f32_16x16x32_bf16 v[70:73], v[188:191], v[228:231], v[70:73]
	v_mfma_f32_16x16x32_bf16 v[66:69], v[196:199], v[228:231], v[66:69]
	v_mfma_f32_16x16x32_bf16 v[118:121], v[192:195], v[208:211], v[118:121]
	v_mfma_f32_16x16x32_bf16 v[114:117], v[200:203], v[208:211], v[114:117]
	v_mfma_f32_16x16x32_bf16 v[102:105], v[192:195], v[216:219], v[102:105]
	v_mfma_f32_16x16x32_bf16 v[98:101], v[200:203], v[216:219], v[98:101]
	v_mfma_f32_16x16x32_bf16 v[86:89], v[192:195], v[224:227], v[86:89]
	v_mfma_f32_16x16x32_bf16 v[82:85], v[200:203], v[224:227], v[82:85]
	v_mfma_f32_16x16x32_bf16 v[70:73], v[192:195], v[232:235], v[70:73]
	v_mfma_f32_16x16x32_bf16 v[66:69], v[200:203], v[232:235], v[66:69]
	s_barrier
	ds_read_b128 v[204:207], v170 offset:16384
	ds_read_b128 v[208:211], v170 offset:17408
	ds_read_b128 v[212:215], v170 offset:18432
	ds_read_b128 v[216:219], v170 offset:19456
	ds_read_b128 v[220:223], v170 offset:20480
	ds_read_b128 v[224:227], v170 offset:21504
	ds_read_b128 v[228:231], v170 offset:22528
	ds_read_b128 v[232:235], v170 offset:23552
	s_mov_b32 m0, s52
	s_add_u32 s58, s34, 0x4000
	global_load_lds_dwordx4 v134, s[34:35]
	s_mov_b32 m0, s53
	s_addc_u32 s59, s35, 0
	s_add_i32 s62, s73, s40
	global_load_lds_dwordx4 v130, s[34:35]
	s_mov_b32 m0, s62
	s_nop 0
	global_load_lds_dwordx4 v134, s[58:59]
	s_add_i32 m0, s62, 0x2000
	s_nop 0
	global_load_lds_dwordx4 v130, s[58:59]
	s_mov_b32 m0, s25
	s_nop 0
	global_load_lds_dwordx4 v136, s[36:37]
	s_mov_b32 m0, s43
	s_nop 0
	global_load_lds_dwordx4 v132, s[36:37]
	s_waitcnt vmcnt(8) lgkmcnt(0)
	s_barrier
	v_mfma_f32_16x16x32_bf16 v[62:65], v[172:175], v[204:207], v[62:65]
	v_mfma_f32_16x16x32_bf16 v[58:61], v[180:183], v[204:207], v[58:61]
	v_mfma_f32_16x16x32_bf16 v[46:49], v[172:175], v[212:215], v[46:49]
	v_mfma_f32_16x16x32_bf16 v[42:45], v[180:183], v[212:215], v[42:45]
	v_mfma_f32_16x16x32_bf16 v[30:33], v[172:175], v[220:223], v[30:33]
	v_mfma_f32_16x16x32_bf16 v[26:29], v[180:183], v[220:223], v[26:29]
	v_mfma_f32_16x16x32_bf16 v[14:17], v[172:175], v[228:231], v[14:17]
	v_mfma_f32_16x16x32_bf16 v[10:13], v[180:183], v[228:231], v[10:13]
	v_mfma_f32_16x16x32_bf16 v[62:65], v[176:179], v[208:211], v[62:65]
	v_mfma_f32_16x16x32_bf16 v[58:61], v[184:187], v[208:211], v[58:61]
	v_mfma_f32_16x16x32_bf16 v[46:49], v[176:179], v[216:219], v[46:49]
	v_mfma_f32_16x16x32_bf16 v[42:45], v[184:187], v[216:219], v[42:45]
	v_mfma_f32_16x16x32_bf16 v[30:33], v[176:179], v[224:227], v[30:33]
	v_mfma_f32_16x16x32_bf16 v[26:29], v[184:187], v[224:227], v[26:29]
	v_mfma_f32_16x16x32_bf16 v[14:17], v[176:179], v[232:235], v[14:17]
	v_mfma_f32_16x16x32_bf16 v[10:13], v[184:187], v[232:235], v[10:13]
	v_mfma_f32_16x16x32_bf16 v[54:57], v[188:191], v[204:207], v[54:57]
	v_mfma_f32_16x16x32_bf16 v[50:53], v[196:199], v[204:207], v[50:53]
	v_mfma_f32_16x16x32_bf16 v[38:41], v[188:191], v[212:215], v[38:41]
	v_mfma_f32_16x16x32_bf16 v[34:37], v[196:199], v[212:215], v[34:37]
	v_mfma_f32_16x16x32_bf16 v[22:25], v[188:191], v[220:223], v[22:25]
	v_mfma_f32_16x16x32_bf16 v[18:21], v[196:199], v[220:223], v[18:21]
	v_mfma_f32_16x16x32_bf16 v[6:9], v[188:191], v[228:231], v[6:9]
	v_mfma_f32_16x16x32_bf16 v[2:5], v[196:199], v[228:231], v[2:5]
	v_mfma_f32_16x16x32_bf16 v[54:57], v[192:195], v[208:211], v[54:57]
	v_mfma_f32_16x16x32_bf16 v[50:53], v[200:203], v[208:211], v[50:53]
	v_mfma_f32_16x16x32_bf16 v[38:41], v[192:195], v[216:219], v[38:41]
	v_mfma_f32_16x16x32_bf16 v[34:37], v[200:203], v[216:219], v[34:37]
	v_mfma_f32_16x16x32_bf16 v[22:25], v[192:195], v[224:227], v[22:25]
	v_mfma_f32_16x16x32_bf16 v[18:21], v[200:203], v[224:227], v[18:21]
	v_mfma_f32_16x16x32_bf16 v[6:9], v[192:195], v[232:235], v[6:9]
	v_mfma_f32_16x16x32_bf16 v[2:5], v[200:203], v[232:235], v[2:5]
	s_barrier
; #define PG8_STAGE(bufoff, gbase, voff) do { _Pragma("unroll") for (int _i = 0; _i < 2; ++_i) \
;         __builtin_amdgcn_global_load_lds((const unsigned*)((const char*)(gbase) + (voff)[_i]), (LAS unsigned*)(lds + (bufoff) + ldsw + _i * 8192), 16, 0, 0); } while (0)
; #define PG8_LDA(dst, b, h) do { _Pragma("unroll") for (int m = 0; m < 4; ++m) _Pragma("unroll") for (int k = 0; k < 2; ++k) dst[m][k] = *(const LAS bf16x8*)(lds + PG8_SA(b, h) + aoff + m * 2048 + k * 1024); } while (0)
; #define PG8_LDB(dst, b, h) do { _Pragma("unroll") for (int n = 0; n < 2; ++n) _Pragma("unroll") for (int k = 0; k < 2; ++k) dst[n][k] = *(const LAS bf16x8*)(lds + PG8_SB(b, h) + boff + n * 2048 + k * 1024); } while (0)
; #define PG8_MMA(ai, bj, At, Bt) do { __builtin_amdgcn_s_setprio(1); _Pragma("unroll") for (int m = 0; m < 4; ++m) _Pragma("unroll") for (int n = 0; n < 2; ++n) _Pragma("unroll") for (int k = 0; k < 2; ++k) \
;         acc[ai][bj][m][n] = __builtin_amdgcn_mfma_f32_16x16x32_bf16(Bt[n][k], At[m][k], acc[ai][bj][m][n], 0, 0, 0); __builtin_amdgcn_s_setprio(0); } while (0)
; #define PG8_WAIT_V(n) asm volatile("s_waitcnt vmcnt(" #n ")" ::: "memory")
; #define PG8_WAIT_L(n) asm volatile("s_waitcnt lgkmcnt(" #n ")" ::: "memory")
; #define PG8_BAR __builtin_amdgcn_s_barrier()
; #define PG8_SCHED __builtin_amdgcn_sched_barrier(0)
; template <class Epi, class Sched, bool ABLK = false, bool ALIGN_EPI = true, bool SP2 = true, bool BBLK = true>
; __device__ __forceinline__ void gemm_phase(LAS unsigned char* lds, const Gemm g, const Sched& S, const Epi& E) {
;     ...
;             PG8_LDB(B0, 1, 0); PG8_LDB(B1, 1, 1); PG8_SCHED; PG8_LDA(At, 1, 0); PG8_STAGE(PG8_SA(0, 1), a2 + hstepA, voffA);
;             PG8_WAIT_V(8); PG8_WAIT_L(0); PG8_BAR; PG8_MMA(0, 0, At, B0); PG8_MMA(0, 1, At, B1); PG8_BAR; PG8_SCHED;
;             PG8_LDA(At, 1, 1); PG8_STAGE(PG8_SB(1, 0), b3, voffB); PG8_STAGE(PG8_SB(1, 1), b3 + hstepB, voffB); PG8_STAGE(PG8_SA(1, 0), a3, voffA);
;             PG8_WAIT_V(8); PG8_WAIT_L(0); PG8_BAR; PG8_MMA(1, 0, At, B0); PG8_MMA(1, 1, At, B1); PG8_BAR; PG8_SCHED;
;     ...
;         if constexpr (ALIGN_EPI) { if (wr == 0) PG8_BAR; }
	v_add_u32_e32 v171, s60, v1
	ds_read_b128 v[172:175], v171
	ds_read_b128 v[176:179], v171 offset:1024
	ds_read_b128 v[180:183], v171 offset:2048
	ds_read_b128 v[184:187], v171 offset:3072
	v_add_u32_e32 v171, s61, v1
	ds_read_b128 v[188:191], v171
	ds_read_b128 v[192:195], v171 offset:1024
	ds_read_b128 v[196:199], v171 offset:2048
	ds_read_b128 v[200:203], v171 offset:3072
	ds_read_b128 v[204:207], v170 offset:32768
	ds_read_b128 v[208:211], v170 offset:33792
	ds_read_b128 v[212:215], v170 offset:34816
	ds_read_b128 v[216:219], v170 offset:35840
	ds_read_b128 v[220:223], v170 offset:36864
	ds_read_b128 v[224:227], v170 offset:37888
	ds_read_b128 v[228:231], v170 offset:38912
	ds_read_b128 v[232:235], v170 offset:39936
	s_add_u32 s36, s36, 0x80000
	s_addc_u32 s37, s37, 0
	s_mov_b32 m0, s44
	s_nop 0
	global_load_lds_dwordx4 v136, s[36:37]
	s_mov_b32 m0, s45
	s_nop 0
	global_load_lds_dwordx4 v132, s[36:37]
	s_waitcnt vmcnt(8) lgkmcnt(0)
	s_barrier
	v_mfma_f32_16x16x32_bf16 v[126:129], v[172:175], v[204:207], v[126:129]
	v_mfma_f32_16x16x32_bf16 v[122:125], v[180:183], v[204:207], v[122:125]
	v_mfma_f32_16x16x32_bf16 v[110:113], v[172:175], v[212:215], v[110:113]
	v_mfma_f32_16x16x32_bf16 v[106:109], v[180:183], v[212:215], v[106:109]
	v_mfma_f32_16x16x32_bf16 v[94:97], v[172:175], v[220:223], v[94:97]
	v_mfma_f32_16x16x32_bf16 v[90:93], v[180:183], v[220:223], v[90:93]
	v_mfma_f32_16x16x32_bf16 v[78:81], v[172:175], v[228:231], v[78:81]
	v_mfma_f32_16x16x32_bf16 v[74:77], v[180:183], v[228:231], v[74:77]
	v_mfma_f32_16x16x32_bf16 v[126:129], v[176:179], v[208:211], v[126:129]
	v_mfma_f32_16x16x32_bf16 v[122:125], v[184:187], v[208:211], v[122:125]
	v_mfma_f32_16x16x32_bf16 v[110:113], v[176:179], v[216:219], v[110:113]
	v_mfma_f32_16x16x32_bf16 v[106:109], v[184:187], v[216:219], v[106:109]
	v_mfma_f32_16x16x32_bf16 v[94:97], v[176:179], v[224:227], v[94:97]
	v_mfma_f32_16x16x32_bf16 v[90:93], v[184:187], v[224:227], v[90:93]
	v_mfma_f32_16x16x32_bf16 v[78:81], v[176:179], v[232:235], v[78:81]
	v_mfma_f32_16x16x32_bf16 v[74:77], v[184:187], v[232:235], v[74:77]
	v_mfma_f32_16x16x32_bf16 v[118:121], v[188:191], v[204:207], v[118:121]
	v_mfma_f32_16x16x32_bf16 v[114:117], v[196:199], v[204:207], v[114:117]
	v_mfma_f32_16x16x32_bf16 v[102:105], v[188:191], v[212:215], v[102:105]
	v_mfma_f32_16x16x32_bf16 v[98:101], v[196:199], v[212:215], v[98:101]
	v_mfma_f32_16x16x32_bf16 v[86:89], v[188:191], v[220:223], v[86:89]
	v_mfma_f32_16x16x32_bf16 v[82:85], v[196:199], v[220:223], v[82:85]
	v_mfma_f32_16x16x32_bf16 v[70:73], v[188:191], v[228:231], v[70:73]
	v_mfma_f32_16x16x32_bf16 v[66:69], v[196:199], v[228:231], v[66:69]
	v_mfma_f32_16x16x32_bf16 v[118:121], v[192:195], v[208:211], v[118:121]
	v_mfma_f32_16x16x32_bf16 v[114:117], v[200:203], v[208:211], v[114:117]
	v_mfma_f32_16x16x32_bf16 v[102:105], v[192:195], v[216:219], v[102:105]
	v_mfma_f32_16x16x32_bf16 v[98:101], v[200:203], v[216:219], v[98:101]
	v_mfma_f32_16x16x32_bf16 v[86:89], v[192:195], v[224:227], v[86:89]
	v_mfma_f32_16x16x32_bf16 v[82:85], v[200:203], v[224:227], v[82:85]
	v_mfma_f32_16x16x32_bf16 v[70:73], v[192:195], v[232:235], v[70:73]
	v_mfma_f32_16x16x32_bf16 v[66:69], v[200:203], v[232:235], v[66:69]
	s_barrier
	ds_read_b128 v[204:207], v170 offset:49152
	ds_read_b128 v[208:211], v170 offset:50176
	ds_read_b128 v[212:215], v170 offset:51200
	ds_read_b128 v[216:219], v170 offset:52224
	ds_read_b128 v[220:223], v170 offset:53248
	ds_read_b128 v[224:227], v170 offset:54272
	ds_read_b128 v[228:231], v170 offset:55296
	ds_read_b128 v[232:235], v170 offset:56320
	s_add_u32 s36, s34, 0x8000
	s_addc_u32 s37, s35, 0
	s_add_i32 s58, s60, s40
	s_mov_b32 m0, s58
	s_nop 0
	global_load_lds_dwordx4 v134, s[36:37]
	s_add_i32 m0, s58, 0x2000
	s_add_u32 s34, s34, 0xc000
	v_lshl_add_u64 v[236:237], s[36:37], 0, v[130:131]
	s_addc_u32 s35, s35, 0
	s_add_i32 s36, s61, s40
	global_load_lds_dwordx4 v[236:237], off
	s_mov_b32 m0, s36
	s_nop 0
	global_load_lds_dwordx4 v134, s[34:35]
	s_add_i32 m0, s36, 0x2000
	s_nop 0
	global_load_lds_dwordx4 v130, s[34:35]
	s_mov_b32 m0, s48
	s_nop 0
	global_load_lds_dwordx4 v136, s[30:31]
	s_mov_b32 m0, s49
	s_nop 0
	global_load_lds_dwordx4 v132, s[30:31]
	s_waitcnt vmcnt(8) lgkmcnt(0)
	s_barrier
	v_mfma_f32_16x16x32_bf16 v[62:65], v[172:175], v[204:207], v[62:65]
	v_mfma_f32_16x16x32_bf16 v[58:61], v[180:183], v[204:207], v[58:61]
	v_mfma_f32_16x16x32_bf16 v[46:49], v[172:175], v[212:215], v[46:49]
	v_mfma_f32_16x16x32_bf16 v[42:45], v[180:183], v[212:215], v[42:45]
	v_mfma_f32_16x16x32_bf16 v[30:33], v[172:175], v[220:223], v[30:33]
	v_mfma_f32_16x16x32_bf16 v[26:29], v[180:183], v[220:223], v[26:29]
	v_mfma_f32_16x16x32_bf16 v[14:17], v[172:175], v[228:231], v[14:17]
	v_mfma_f32_16x16x32_bf16 v[10:13], v[180:183], v[228:231], v[10:13]
	v_mfma_f32_16x16x32_bf16 v[62:65], v[176:179], v[208:211], v[62:65]
	v_mfma_f32_16x16x32_bf16 v[58:61], v[184:187], v[208:211], v[58:61]
	v_mfma_f32_16x16x32_bf16 v[46:49], v[176:179], v[216:219], v[46:49]
	v_mfma_f32_16x16x32_bf16 v[42:45], v[184:187], v[216:219], v[42:45]
	v_mfma_f32_16x16x32_bf16 v[30:33], v[176:179], v[224:227], v[30:33]
	v_mfma_f32_16x16x32_bf16 v[26:29], v[184:187], v[224:227], v[26:29]
	v_mfma_f32_16x16x32_bf16 v[14:17], v[176:179], v[232:235], v[14:17]
	v_mfma_f32_16x16x32_bf16 v[10:13], v[184:187], v[232:235], v[10:13]
	v_mfma_f32_16x16x32_bf16 v[54:57], v[188:191], v[204:207], v[54:57]
	v_mfma_f32_16x16x32_bf16 v[50:53], v[196:199], v[204:207], v[50:53]
	v_mfma_f32_16x16x32_bf16 v[38:41], v[188:191], v[212:215], v[38:41]
	v_mfma_f32_16x16x32_bf16 v[34:37], v[196:199], v[212:215], v[34:37]
	v_mfma_f32_16x16x32_bf16 v[22:25], v[188:191], v[220:223], v[22:25]
	v_mfma_f32_16x16x32_bf16 v[18:21], v[196:199], v[220:223], v[18:21]
	v_mfma_f32_16x16x32_bf16 v[6:9], v[188:191], v[228:231], v[6:9]
	v_mfma_f32_16x16x32_bf16 v[2:5], v[196:199], v[228:231], v[2:5]
	v_mfma_f32_16x16x32_bf16 v[54:57], v[192:195], v[208:211], v[54:57]
	v_mfma_f32_16x16x32_bf16 v[50:53], v[200:203], v[208:211], v[50:53]
	v_mfma_f32_16x16x32_bf16 v[38:41], v[192:195], v[216:219], v[38:41]
	v_mfma_f32_16x16x32_bf16 v[34:37], v[200:203], v[216:219], v[34:37]
	v_mfma_f32_16x16x32_bf16 v[22:25], v[192:195], v[224:227], v[22:25]
	v_mfma_f32_16x16x32_bf16 v[18:21], v[200:203], v[224:227], v[18:21]
	v_mfma_f32_16x16x32_bf16 v[6:9], v[192:195], v[232:235], v[6:9]
	v_mfma_f32_16x16x32_bf16 v[2:5], v[200:203], v[232:235], v[2:5]
	s_barrier
	s_add_i32 s57, s57, 2
	s_add_u32 s28, s28, 0x100
	s_addc_u32 s29, s29, 0
	s_add_u32 s55, s55, 0x10000
	s_addc_u32 s56, s56, 0
	s_cmp_gt_u32 s57, 29
	s_cbranch_scc0 .LBB0_2263
	s_and_b64 vcc, exec, s[10:11]
	s_cbranch_vccz .LBB0_2266
	s_barrier

; #define PG8_STAGE(bufoff, gbase, voff) do { _Pragma("unroll") for (int _i = 0; _i < 2; ++_i) \
;         __builtin_amdgcn_global_load_lds((const unsigned*)((const char*)(gbase) + (voff)[_i]), (LAS unsigned*)(lds + (bufoff) + ldsw + _i * 8192), 16, 0, 0); } while (0)
; #define PG8_LDA(dst, b, h) do { _Pragma("unroll") for (int m = 0; m < 4; ++m) _Pragma("unroll") for (int k = 0; k < 2; ++k) dst[m][k] = *(const LAS bf16x8*)(lds + PG8_SA(b, h) + aoff + m * 2048 + k * 1024); } while (0)
; #define PG8_LDB(dst, b, h) do { _Pragma("unroll") for (int n = 0; n < 2; ++n) _Pragma("unroll") for (int k = 0; k < 2; ++k) dst[n][k] = *(const LAS bf16x8*)(lds + PG8_SB(b, h) + boff + n * 2048 + k * 1024); } while (0)
; #define PG8_WAIT_V(n) asm volatile("s_waitcnt vmcnt(" #n ")" ::: "memory")
; #define PG8_WAIT_L(n) asm volatile("s_waitcnt lgkmcnt(" #n ")" ::: "memory")
; template <class Epi, class Sched, bool ABLK = false, bool ALIGN_EPI = true, bool SP2 = true, bool BBLK = true>
; __device__ __forceinline__ void gemm_phase(LAS unsigned char* lds, const Gemm g, const Sched& S, const Epi& E) {
;     ...
;         const bool has_next = S.next(ui + 1, nxt);
;         const int nt = cur.nt;
;         const char* nuA = has_next ? a_unit(nxt) : uA; const int ntbA = has_next ? nxt.k0 / BK : tbA; const char* nB = has_next ? (const char*)g.Bt + (size_t)nxt.pn * tstepB + b_k0(nxt.k0) : cB;
;         for (int t = 0; t < nt; t += 2) {
;             const bool last = (t == nt - 2);
;             const char* a1 = a_tile(uA, tbA + t + 1);
;             const char* a2 = last ? a_tile(nuA, ntbA) : a_tile(uA, tbA + t + 2); const char* b2 = last ? nB : cB + (size_t)(t + 2) * kstepB;
;             const char* a3 = last ? a_tile(nuA, ntbA + 1) : a_tile(uA, tbA + t + 3); const char* b3 = b2 + kstepB;
;             if (last && has_next) S.a_ready(nxt);
;             if constexpr (SP2) {
;             PG8_LDB(B0, 0, 0); PG8_LDB(B1, 0, 1); PG8_SCHED; PG8_LDA(At, 0, 0); PG8_STAGE(PG8_SA(1, 1), a1 + hstepA, voffA);
;             PG8_WAIT_V(8); PG8_WAIT_L(0); PG8_BAR; PG8_MMA(0, 0, At, B0); PG8_MMA(0, 1, At, B1); PG8_BAR; PG8_SCHED;
;             PG8_LDA(At, 0, 1); PG8_STAGE(PG8_SB(0, 0), b2, voffB); PG8_STAGE(PG8_SB(0, 1), b2 + hstepB, voffB); PG8_STAGE(PG8_SA(0, 0), a2, voffA);
;             PG8_WAIT_V(8); PG8_WAIT_L(0); PG8_BAR; PG8_MMA(1, 0, At, B0); PG8_MMA(1, 1, At, B1); PG8_BAR; PG8_SCHED;
.LBB0_2327:
	ds_read_b128 v[152:155], v148
	ds_read_b128 v[156:159], v148 offset:1024
	ds_read_b128 v[160:163], v148 offset:2048
	ds_read_b128 v[164:167], v148 offset:3072
	ds_read_b128 v[168:171], v149
	ds_read_b128 v[172:175], v149 offset:1024
	ds_read_b128 v[176:179], v149 offset:2048
	ds_read_b128 v[180:183], v149 offset:3072
	ds_read_b128 v[184:187], v150
	ds_read_b128 v[188:191], v150 offset:1024
	ds_read_b128 v[192:195], v150 offset:2048
	ds_read_b128 v[196:199], v150 offset:3072
	ds_read_b128 v[200:203], v150 offset:4096
	ds_read_b128 v[204:207], v150 offset:5120
	ds_read_b128 v[208:211], v150 offset:6144
	ds_read_b128 v[212:215], v150 offset:7168
	s_ashr_i32 s81, s80, 31
	s_andn2_b64 vcc, exec, s[4:5]
	s_lshl_b64 s[30:31], s[80:81], 22
	s_add_u32 s30, s1, s30
	s_addc_u32 s31, s33, s31
	s_and_b64 s[34:35], s[4:5], exec
	s_cselect_b32 s43, s31, s41
	s_cselect_b32 s57, s30, s40
	s_ashr_i32 s34, s0, 31
	s_lshr_b32 s34, s34, 26
	s_add_i32 s34, s0, s34
	s_ashr_i32 s34, s34, 6
	s_and_b64 s[36:37], s[4:5], exec
	s_cselect_b32 s44, s34, s42
	s_ashr_i32 s79, s78, 31
	s_lshl_b64 s[36:37], s[78:79], 22
	s_add_u32 s45, s46, s36
	s_addc_u32 s58, s47, s37
	s_ashr_i32 s35, s34, 31
	s_lshl_b64 s[36:37], s[34:35], 15
	s_add_u32 s36, s45, s36
	s_addc_u32 s37, s58, s37
	v_cndmask_b32_e64 v2, 0, 1, s[4:5]
	s_and_b64 s[4:5], s[4:5], exec
	s_cselect_b32 s4, s37, s39
	s_cselect_b32 s5, s36, s38
	s_ashr_i32 s45, s44, 31
	s_lshl_b64 s[44:45], s[44:45], 15
	s_add_u32 s35, s57, s44
	s_addc_u32 s57, s43, s45
	s_add_u32 s58, s35, 0x8000
	s_addc_u32 s59, s57, 0
	s_add_u32 s62, s38, 0x10000
	s_addc_u32 s63, s39, 0
	s_ashr_i32 s43, s42, 31
	v_cmp_ne_u32_e64 s[6:7], 1, v2
	s_lshl_b64 s[38:39], s[42:43], 15
	v_lshl_add_u64 v[2:3], s[40:41], 0, v[138:139]
	s_add_u32 s64, s40, s38
	v_lshl_add_u64 v[142:143], v[2:3], 0, s[38:39]
	v_lshl_add_u64 v[2:3], s[40:41], 0, v[140:141]
	s_addc_u32 s65, s41, s39
	v_lshl_add_u64 v[144:145], v[2:3], 0, s[38:39]
	s_lshl_b32 s38, s56, 15
	s_add_i32 s38, s38, 0xfff00000
	v_mov_b32_e32 v2, 0
	s_add_u32 s66, s38, 0xf0000
	s_mov_b32 s67, 0
	s_mov_b64 s[38:39], 0
	s_add_u32 s40, s64, s38
	s_addc_u32 s41, s65, s39
	s_add_u32 s44, s40, 0x10000
	s_addc_u32 s45, s41, 0
	s_add_i32 s67, s67, 2
	s_add_u32 s42, s62, s38
	s_addc_u32 s43, s63, s39
	s_add_u32 s40, s40, 0x18000
	s_addc_u32 s41, s41, 0
	s_cmp_eq_u32 s66, s38
	s_cselect_b32 s41, s59, s41
	s_cselect_b32 s40, s58, s40
	s_cselect_b32 s43, s4, s43
	s_cselect_b32 s42, s5, s42
	s_cselect_b32 s45, s57, s45
	s_cselect_b32 s44, s35, s44
	v_lshl_add_u64 v[216:217], v[142:143], 0, s[38:39]
	s_add_i32 m0, s49, 0xc000
	s_nop 0
	global_load_lds_dwordx4 v[216:217], off
	v_lshl_add_u64 v[216:217], v[144:145], 0, s[38:39]
	s_add_i32 m0, s49, 0xe000
	s_nop 0
	global_load_lds_dwordx4 v[216:217], off
	s_waitcnt vmcnt(8) lgkmcnt(0)
	s_barrier
	v_mfma_f32_16x16x32_bf16 v[126:129], v[152:155], v[184:187], 0
	v_mfma_f32_16x16x32_bf16 v[122:125], v[160:163], v[184:187], 0
	v_mfma_f32_16x16x32_bf16 v[110:113], v[152:155], v[192:195], 0
	v_mfma_f32_16x16x32_bf16 v[106:109], v[160:163], v[192:195], 0
	v_mfma_f32_16x16x32_bf16 v[94:97], v[152:155], v[200:203], 0
	v_mfma_f32_16x16x32_bf16 v[90:93], v[160:163], v[200:203], 0
	v_mfma_f32_16x16x32_bf16 v[78:81], v[152:155], v[208:211], 0
	v_mfma_f32_16x16x32_bf16 v[74:77], v[160:163], v[208:211], 0
	v_mfma_f32_16x16x32_bf16 v[126:129], v[156:159], v[188:191], v[126:129]
	v_mfma_f32_16x16x32_bf16 v[122:125], v[164:167], v[188:191], v[122:125]
	v_mfma_f32_16x16x32_bf16 v[110:113], v[156:159], v[196:199], v[110:113]
	v_mfma_f32_16x16x32_bf16 v[106:109], v[164:167], v[196:199], v[106:109]
	v_mfma_f32_16x16x32_bf16 v[94:97], v[156:159], v[204:207], v[94:97]
	v_mfma_f32_16x16x32_bf16 v[90:93], v[164:167], v[204:207], v[90:93]
	v_mfma_f32_16x16x32_bf16 v[78:81], v[156:159], v[212:215], v[78:81]
	v_mfma_f32_16x16x32_bf16 v[74:77], v[164:167], v[212:215], v[74:77]
	v_mfma_f32_16x16x32_bf16 v[118:121], v[168:171], v[184:187], 0
	v_mfma_f32_16x16x32_bf16 v[114:117], v[176:179], v[184:187], 0
	v_mfma_f32_16x16x32_bf16 v[102:105], v[168:171], v[192:195], 0
	v_mfma_f32_16x16x32_bf16 v[98:101], v[176:179], v[192:195], 0
	v_mfma_f32_16x16x32_bf16 v[86:89], v[168:171], v[200:203], 0
	v_mfma_f32_16x16x32_bf16 v[82:85], v[176:179], v[200:203], 0
	v_mfma_f32_16x16x32_bf16 v[70:73], v[168:171], v[208:211], 0
	v_mfma_f32_16x16x32_bf16 v[66:69], v[176:179], v[208:211], 0
	v_mfma_f32_16x16x32_bf16 v[118:121], v[172:175], v[188:191], v[118:121]
	v_mfma_f32_16x16x32_bf16 v[114:117], v[180:183], v[188:191], v[114:117]
	v_mfma_f32_16x16x32_bf16 v[102:105], v[172:175], v[196:199], v[102:105]
	v_mfma_f32_16x16x32_bf16 v[98:101], v[180:183], v[196:199], v[98:101]
	v_mfma_f32_16x16x32_bf16 v[86:89], v[172:175], v[204:207], v[86:89]
	v_mfma_f32_16x16x32_bf16 v[82:85], v[180:183], v[204:207], v[82:85]
	v_mfma_f32_16x16x32_bf16 v[70:73], v[172:175], v[212:215], v[70:73]
	v_mfma_f32_16x16x32_bf16 v[66:69], v[180:183], v[212:215], v[66:69]
	s_barrier
	ds_read_b128 v[184:187], v150 offset:16384
	ds_read_b128 v[188:191], v150 offset:17408
	ds_read_b128 v[192:195], v150 offset:18432
	ds_read_b128 v[196:199], v150 offset:19456
	ds_read_b128 v[200:203], v150 offset:20480
	ds_read_b128 v[204:207], v150 offset:21504
	ds_read_b128 v[208:211], v150 offset:22528
	ds_read_b128 v[212:215], v150 offset:23552
	s_add_i32 s70, s72, s48
	s_mov_b32 m0, s70
	s_nop 0
	global_load_lds_dwordx4 v130, s[42:43]
	s_add_i32 m0, s70, 0x2000
	s_add_u32 s76, s42, 0x4000
	s_addc_u32 s77, s43, 0
	s_add_i32 s70, s73, s48
	global_load_lds_dwordx4 v132, s[42:43]
	s_mov_b32 m0, s70
	s_nop 0
	global_load_lds_dwordx4 v130, s[76:77]
	s_add_i32 m0, s70, 0x2000
	s_nop 0
	global_load_lds_dwordx4 v132, s[76:77]
	s_mov_b32 m0, s49
	s_nop 0
	global_load_lds_dwordx4 v130, s[44:45]
	s_mov_b32 m0, s50
	s_nop 0
	global_load_lds_dwordx4 v132, s[44:45]
	s_waitcnt vmcnt(8) lgkmcnt(0)
	s_barrier
; #define PG8_STAGE(bufoff, gbase, voff) do { _Pragma("unroll") for (int _i = 0; _i < 2; ++_i) \
;         __builtin_amdgcn_global_load_lds((const unsigned*)((const char*)(gbase) + (voff)[_i]), (LAS unsigned*)(lds + (bufoff) + ldsw + _i * 8192), 16, 0, 0); } while (0)
; #define PG8_LDA(dst, b, h) do { _Pragma("unroll") for (int m = 0; m < 4; ++m) _Pragma("unroll") for (int k = 0; k < 2; ++k) dst[m][k] = *(const LAS bf16x8*)(lds + PG8_SA(b, h) + aoff + m * 2048 + k * 1024); } while (0)
; #define PG8_LDB(dst, b, h) do { _Pragma("unroll") for (int n = 0; n < 2; ++n) _Pragma("unroll") for (int k = 0; k < 2; ++k) dst[n][k] = *(const LAS bf16x8*)(lds + PG8_SB(b, h) + boff + n * 2048 + k * 1024); } while (0)
; #define PG8_MMA(ai, bj, At, Bt) do { __builtin_amdgcn_s_setprio(1); _Pragma("unroll") for (int m = 0; m < 4; ++m) _Pragma("unroll") for (int n = 0; n < 2; ++n) _Pragma("unroll") for (int k = 0; k < 2; ++k) \
;         acc[ai][bj][m][n] = __builtin_amdgcn_mfma_f32_16x16x32_bf16(Bt[n][k], At[m][k], acc[ai][bj][m][n], 0, 0, 0); __builtin_amdgcn_s_setprio(0); } while (0)
; #define PG8_WAIT_V(n) asm volatile("s_waitcnt vmcnt(" #n ")" ::: "memory")
; #define PG8_WAIT_L(n) asm volatile("s_waitcnt lgkmcnt(" #n ")" ::: "memory")
; #define PG8_BAR __builtin_amdgcn_s_barrier()
; #define PG8_SCHED __builtin_amdgcn_sched_barrier(0)
; template <class Epi, class Sched, bool ABLK = false, bool ALIGN_EPI = true, bool SP2 = true, bool BBLK = true>
; __device__ __forceinline__ void gemm_phase(LAS unsigned char* lds, const Gemm g, const Sched& S, const Epi& E) {
;     ...
;             PG8_LDA(At, 0, 1); PG8_STAGE(PG8_SB(0, 0), b2, voffB); PG8_STAGE(PG8_SB(0, 1), b2 + hstepB, voffB); PG8_STAGE(PG8_SA(0, 0), a2, voffA);
;             PG8_WAIT_V(8); PG8_WAIT_L(0); PG8_BAR; PG8_MMA(1, 0, At, B0); PG8_MMA(1, 1, At, B1); PG8_BAR; PG8_SCHED;
;             PG8_LDB(B0, 1, 0); PG8_LDB(B1, 1, 1); PG8_SCHED; PG8_LDA(At, 1, 0); PG8_STAGE(PG8_SA(0, 1), a2 + hstepA, voffA);
;             PG8_WAIT_V(8); PG8_WAIT_L(0); PG8_BAR; PG8_MMA(0, 0, At, B0); PG8_MMA(0, 1, At, B1); PG8_BAR; PG8_SCHED;
	v_mfma_f32_16x16x32_bf16 v[62:65], v[152:155], v[184:187], 0
	v_mfma_f32_16x16x32_bf16 v[58:61], v[160:163], v[184:187], 0
	v_mfma_f32_16x16x32_bf16 v[46:49], v[152:155], v[192:195], 0
	v_mfma_f32_16x16x32_bf16 v[42:45], v[160:163], v[192:195], 0
	v_mfma_f32_16x16x32_bf16 v[30:33], v[152:155], v[200:203], 0
	v_mfma_f32_16x16x32_bf16 v[26:29], v[160:163], v[200:203], 0
	v_mfma_f32_16x16x32_bf16 v[14:17], v[152:155], v[208:211], 0
	v_mfma_f32_16x16x32_bf16 v[10:13], v[160:163], v[208:211], 0
	v_mfma_f32_16x16x32_bf16 v[62:65], v[156:159], v[188:191], v[62:65]
	v_mfma_f32_16x16x32_bf16 v[58:61], v[164:167], v[188:191], v[58:61]
	v_mfma_f32_16x16x32_bf16 v[46:49], v[156:159], v[196:199], v[46:49]
	v_mfma_f32_16x16x32_bf16 v[42:45], v[164:167], v[196:199], v[42:45]
	v_mfma_f32_16x16x32_bf16 v[30:33], v[156:159], v[204:207], v[30:33]
	v_mfma_f32_16x16x32_bf16 v[26:29], v[164:167], v[204:207], v[26:29]
	v_mfma_f32_16x16x32_bf16 v[14:17], v[156:159], v[212:215], v[14:17]
	v_mfma_f32_16x16x32_bf16 v[10:13], v[164:167], v[212:215], v[10:13]
	v_mfma_f32_16x16x32_bf16 v[54:57], v[168:171], v[184:187], 0
	v_mfma_f32_16x16x32_bf16 v[50:53], v[176:179], v[184:187], 0
	v_mfma_f32_16x16x32_bf16 v[38:41], v[168:171], v[192:195], 0
	v_mfma_f32_16x16x32_bf16 v[34:37], v[176:179], v[192:195], 0
	v_mfma_f32_16x16x32_bf16 v[22:25], v[168:171], v[200:203], 0
	v_mfma_f32_16x16x32_bf16 v[18:21], v[176:179], v[200:203], 0
	v_mfma_f32_16x16x32_bf16 v[6:9], v[168:171], v[208:211], 0
	v_mfma_f32_16x16x32_bf16 v[2:5], v[176:179], v[208:211], 0
	v_mfma_f32_16x16x32_bf16 v[54:57], v[172:175], v[188:191], v[54:57]
	v_mfma_f32_16x16x32_bf16 v[50:53], v[180:183], v[188:191], v[50:53]
	v_mfma_f32_16x16x32_bf16 v[38:41], v[172:175], v[196:199], v[38:41]
	v_mfma_f32_16x16x32_bf16 v[34:37], v[180:183], v[196:199], v[34:37]
	v_mfma_f32_16x16x32_bf16 v[22:25], v[172:175], v[204:207], v[22:25]
	v_mfma_f32_16x16x32_bf16 v[18:21], v[180:183], v[204:207], v[18:21]
	v_mfma_f32_16x16x32_bf16 v[6:9], v[172:175], v[212:215], v[6:9]
	v_mfma_f32_16x16x32_bf16 v[2:5], v[180:183], v[212:215], v[2:5]
	s_barrier
	v_add_u32_e32 v151, s60, v146
	ds_read_b128 v[152:155], v151
	ds_read_b128 v[156:159], v151 offset:1024
	ds_read_b128 v[160:163], v151 offset:2048
	ds_read_b128 v[164:167], v151 offset:3072
	v_add_u32_e32 v151, s61, v146
	ds_read_b128 v[168:171], v151
	ds_read_b128 v[172:175], v151 offset:1024
	ds_read_b128 v[176:179], v151 offset:2048
	ds_read_b128 v[180:183], v151 offset:3072
	ds_read_b128 v[184:187], v150 offset:32768
	ds_read_b128 v[188:191], v150 offset:33792
	ds_read_b128 v[192:195], v150 offset:34816
	ds_read_b128 v[196:199], v150 offset:35840
	ds_read_b128 v[200:203], v150 offset:36864
	ds_read_b128 v[204:207], v150 offset:37888
	ds_read_b128 v[208:211], v150 offset:38912
	ds_read_b128 v[212:215], v150 offset:39936
	s_add_u32 s44, s44, 0x4000
	s_addc_u32 s45, s45, 0
	s_mov_b32 m0, s51
	s_nop 0
	global_load_lds_dwordx4 v130, s[44:45]
	s_mov_b32 m0, s52
	s_nop 0
	global_load_lds_dwordx4 v132, s[44:45]
	s_waitcnt vmcnt(8) lgkmcnt(0)
	s_barrier
	v_mfma_f32_16x16x32_bf16 v[126:129], v[152:155], v[184:187], v[126:129]
	v_mfma_f32_16x16x32_bf16 v[122:125], v[160:163], v[184:187], v[122:125]
	v_mfma_f32_16x16x32_bf16 v[110:113], v[152:155], v[192:195], v[110:113]
	v_mfma_f32_16x16x32_bf16 v[106:109], v[160:163], v[192:195], v[106:109]
	v_mfma_f32_16x16x32_bf16 v[94:97], v[152:155], v[200:203], v[94:97]
	v_mfma_f32_16x16x32_bf16 v[90:93], v[160:163], v[200:203], v[90:93]
	v_mfma_f32_16x16x32_bf16 v[78:81], v[152:155], v[208:211], v[78:81]
	v_mfma_f32_16x16x32_bf16 v[74:77], v[160:163], v[208:211], v[74:77]
	v_mfma_f32_16x16x32_bf16 v[126:129], v[156:159], v[188:191], v[126:129]
	v_mfma_f32_16x16x32_bf16 v[122:125], v[164:167], v[188:191], v[122:125]
	v_mfma_f32_16x16x32_bf16 v[110:113], v[156:159], v[196:199], v[110:113]
	v_mfma_f32_16x16x32_bf16 v[106:109], v[164:167], v[196:199], v[106:109]
	v_mfma_f32_16x16x32_bf16 v[94:97], v[156:159], v[204:207], v[94:97]
	v_mfma_f32_16x16x32_bf16 v[90:93], v[164:167], v[204:207], v[90:93]
	v_mfma_f32_16x16x32_bf16 v[78:81], v[156:159], v[212:215], v[78:81]
	v_mfma_f32_16x16x32_bf16 v[74:77], v[164:167], v[212:215], v[74:77]
	v_mfma_f32_16x16x32_bf16 v[118:121], v[168:171], v[184:187], v[118:121]
	v_mfma_f32_16x16x32_bf16 v[114:117], v[176:179], v[184:187], v[114:117]
	v_mfma_f32_16x16x32_bf16 v[102:105], v[168:171], v[192:195], v[102:105]
	v_mfma_f32_16x16x32_bf16 v[98:101], v[176:179], v[192:195], v[98:101]
	v_mfma_f32_16x16x32_bf16 v[86:89], v[168:171], v[200:203], v[86:89]
	v_mfma_f32_16x16x32_bf16 v[82:85], v[176:179], v[200:203], v[82:85]
	v_mfma_f32_16x16x32_bf16 v[70:73], v[168:171], v[208:211], v[70:73]
	v_mfma_f32_16x16x32_bf16 v[66:69], v[176:179], v[208:211], v[66:69]
	v_mfma_f32_16x16x32_bf16 v[118:121], v[172:175], v[188:191], v[118:121]
	v_mfma_f32_16x16x32_bf16 v[114:117], v[180:183], v[188:191], v[114:117]
	v_mfma_f32_16x16x32_bf16 v[102:105], v[172:175], v[196:199], v[102:105]
	v_mfma_f32_16x16x32_bf16 v[98:101], v[180:183], v[196:199], v[98:101]
	v_mfma_f32_16x16x32_bf16 v[86:89], v[172:175], v[204:207], v[86:89]
	v_mfma_f32_16x16x32_bf16 v[82:85], v[180:183], v[204:207], v[82:85]
	v_mfma_f32_16x16x32_bf16 v[70:73], v[172:175], v[212:215], v[70:73]
	v_mfma_f32_16x16x32_bf16 v[66:69], v[180:183], v[212:215], v[66:69]
	s_barrier
; #define PG8_STAGE(bufoff, gbase, voff) do { _Pragma("unroll") for (int _i = 0; _i < 2; ++_i) \
;         __builtin_amdgcn_global_load_lds((const unsigned*)((const char*)(gbase) + (voff)[_i]), (LAS unsigned*)(lds + (bufoff) + ldsw + _i * 8192), 16, 0, 0); } while (0)
; #define PG8_LDA(dst, b, h) do { _Pragma("unroll") for (int m = 0; m < 4; ++m) _Pragma("unroll") for (int k = 0; k < 2; ++k) dst[m][k] = *(const LAS bf16x8*)(lds + PG8_SA(b, h) + aoff + m * 2048 + k * 1024); } while (0)
; #define PG8_WAIT_V(n) asm volatile("s_waitcnt vmcnt(" #n ")" ::: "memory")
; #define PG8_WAIT_L(n) asm volatile("s_waitcnt lgkmcnt(" #n ")" ::: "memory")
; template <class Epi, class Sched, bool ABLK = false, bool ALIGN_EPI = true, bool SP2 = true, bool BBLK = true>
; __device__ __forceinline__ void gemm_phase(LAS unsigned char* lds, const Gemm g, const Sched& S, const Epi& E) {
;     ...
;         for (int t = 0; t < nt; t += 2) {
;             const bool last = (t == nt - 2);
;             const char* a1 = a_tile(uA, tbA + t + 1);
;             const char* a2 = last ? a_tile(nuA, ntbA) : a_tile(uA, tbA + t + 2); const char* b2 = last ? nB : cB + (size_t)(t + 2) * kstepB;
;             const char* a3 = last ? a_tile(nuA, ntbA + 1) : a_tile(uA, tbA + t + 3); const char* b3 = b2 + kstepB;
;             if (last && has_next) S.a_ready(nxt);
;             if constexpr (SP2) {
;             PG8_LDB(B0, 0, 0); PG8_LDB(B1, 0, 1); PG8_SCHED; PG8_LDA(At, 0, 0); PG8_STAGE(PG8_SA(1, 1), a1 + hstepA, voffA);
;             PG8_WAIT_V(8); PG8_WAIT_L(0); PG8_BAR; PG8_MMA(0, 0, At, B0); PG8_MMA(0, 1, At, B1); PG8_BAR; PG8_SCHED;
;             PG8_LDA(At, 0, 1); PG8_STAGE(PG8_SB(0, 0), b2, voffB); PG8_STAGE(PG8_SB(0, 1), b2 + hstepB, voffB); PG8_STAGE(PG8_SA(0, 0), a2, voffA);
;             PG8_WAIT_V(8); PG8_WAIT_L(0); PG8_BAR; PG8_MMA(1, 0, At, B0); PG8_MMA(1, 1, At, B1); PG8_BAR; PG8_SCHED;
;             PG8_LDB(B0, 1, 0); PG8_LDB(B1, 1, 1); PG8_SCHED; PG8_LDA(At, 1, 0); PG8_STAGE(PG8_SA(0, 1), a2 + hstepA, voffA);
;             PG8_WAIT_V(8); PG8_WAIT_L(0); PG8_BAR; PG8_MMA(0, 0, At, B0); PG8_MMA(0, 1, At, B1); PG8_BAR; PG8_SCHED;
;             PG8_LDA(At, 1, 1); PG8_STAGE(PG8_SB(1, 0), b3, voffB); PG8_STAGE(PG8_SB(1, 1), b3 + hstepB, voffB); PG8_STAGE(PG8_SA(1, 0), a3, voffA);
;             PG8_WAIT_V(8); PG8_WAIT_L(0); PG8_BAR; PG8_MMA(1, 0, At, B0); PG8_MMA(1, 1, At, B1); PG8_BAR; PG8_SCHED;
	ds_read_b128 v[184:187], v150 offset:49152
	ds_read_b128 v[188:191], v150 offset:50176
	ds_read_b128 v[192:195], v150 offset:51200
	ds_read_b128 v[196:199], v150 offset:52224
	ds_read_b128 v[200:203], v150 offset:53248
	ds_read_b128 v[204:207], v150 offset:54272
	ds_read_b128 v[208:211], v150 offset:55296
	ds_read_b128 v[212:215], v150 offset:56320
	s_add_u32 s44, s42, 0x8000
	s_addc_u32 s45, s43, 0
	s_add_i32 s70, s60, s48
	s_mov_b32 m0, s70
	s_nop 0
	global_load_lds_dwordx4 v130, s[44:45]
	s_add_i32 m0, s70, 0x2000
	s_add_u32 s42, s42, 0xc000
	v_lshl_add_u64 v[216:217], s[44:45], 0, v[132:133]
	s_addc_u32 s43, s43, 0
	s_add_i32 s44, s61, s48
	global_load_lds_dwordx4 v[216:217], off
	s_mov_b32 m0, s44
	s_nop 0
	global_load_lds_dwordx4 v130, s[42:43]
	s_add_i32 m0, s44, 0x2000
	s_nop 0
	global_load_lds_dwordx4 v132, s[42:43]
	s_mov_b32 m0, s53
	s_nop 0
	global_load_lds_dwordx4 v130, s[40:41]
	s_mov_b32 m0, s54
	s_nop 0
	global_load_lds_dwordx4 v132, s[40:41]
	s_waitcnt vmcnt(8) lgkmcnt(0)
	s_barrier
	v_mfma_f32_16x16x32_bf16 v[62:65], v[152:155], v[184:187], v[62:65]
	v_mfma_f32_16x16x32_bf16 v[58:61], v[160:163], v[184:187], v[58:61]
	v_mfma_f32_16x16x32_bf16 v[46:49], v[152:155], v[192:195], v[46:49]
	v_mfma_f32_16x16x32_bf16 v[42:45], v[160:163], v[192:195], v[42:45]
	v_mfma_f32_16x16x32_bf16 v[30:33], v[152:155], v[200:203], v[30:33]
	v_mfma_f32_16x16x32_bf16 v[26:29], v[160:163], v[200:203], v[26:29]
	v_mfma_f32_16x16x32_bf16 v[14:17], v[152:155], v[208:211], v[14:17]
	v_mfma_f32_16x16x32_bf16 v[10:13], v[160:163], v[208:211], v[10:13]
	v_mfma_f32_16x16x32_bf16 v[62:65], v[156:159], v[188:191], v[62:65]
	v_mfma_f32_16x16x32_bf16 v[58:61], v[164:167], v[188:191], v[58:61]
	v_mfma_f32_16x16x32_bf16 v[46:49], v[156:159], v[196:199], v[46:49]
	v_mfma_f32_16x16x32_bf16 v[42:45], v[164:167], v[196:199], v[42:45]
	v_mfma_f32_16x16x32_bf16 v[30:33], v[156:159], v[204:207], v[30:33]
	v_mfma_f32_16x16x32_bf16 v[26:29], v[164:167], v[204:207], v[26:29]
	v_mfma_f32_16x16x32_bf16 v[14:17], v[156:159], v[212:215], v[14:17]
	v_mfma_f32_16x16x32_bf16 v[10:13], v[164:167], v[212:215], v[10:13]
	v_mfma_f32_16x16x32_bf16 v[54:57], v[168:171], v[184:187], v[54:57]
	v_mfma_f32_16x16x32_bf16 v[50:53], v[176:179], v[184:187], v[50:53]
	v_mfma_f32_16x16x32_bf16 v[38:41], v[168:171], v[192:195], v[38:41]
	v_mfma_f32_16x16x32_bf16 v[34:37], v[176:179], v[192:195], v[34:37]
	v_mfma_f32_16x16x32_bf16 v[22:25], v[168:171], v[200:203], v[22:25]
	v_mfma_f32_16x16x32_bf16 v[18:21], v[176:179], v[200:203], v[18:21]
	v_mfma_f32_16x16x32_bf16 v[6:9], v[168:171], v[208:211], v[6:9]
	v_mfma_f32_16x16x32_bf16 v[2:5], v[176:179], v[208:211], v[2:5]
	v_mfma_f32_16x16x32_bf16 v[54:57], v[172:175], v[188:191], v[54:57]
	v_mfma_f32_16x16x32_bf16 v[50:53], v[180:183], v[188:191], v[50:53]
	v_mfma_f32_16x16x32_bf16 v[38:41], v[172:175], v[196:199], v[38:41]
	v_mfma_f32_16x16x32_bf16 v[34:37], v[180:183], v[196:199], v[34:37]
	v_mfma_f32_16x16x32_bf16 v[22:25], v[172:175], v[204:207], v[22:25]
	v_mfma_f32_16x16x32_bf16 v[18:21], v[180:183], v[204:207], v[18:21]
	v_mfma_f32_16x16x32_bf16 v[6:9], v[172:175], v[212:215], v[6:9]
	v_mfma_f32_16x16x32_bf16 v[2:5], v[180:183], v[212:215], v[2:5]
	s_barrier
	s_add_u32 s38, s38, 0x10000
	s_addc_u32 s39, s39, 0
	s_cmp_ge_u32 s67, s56
.LBB0_2328:
	ds_read_b128 v[152:155], v148
	ds_read_b128 v[156:159], v148 offset:1024
	ds_read_b128 v[160:163], v148 offset:2048
	ds_read_b128 v[164:167], v148 offset:3072
	ds_read_b128 v[168:171], v149
	ds_read_b128 v[172:175], v149 offset:1024
	ds_read_b128 v[176:179], v149 offset:2048
	ds_read_b128 v[180:183], v149 offset:3072
	ds_read_b128 v[184:187], v150
	ds_read_b128 v[188:191], v150 offset:1024
	ds_read_b128 v[192:195], v150 offset:2048
	ds_read_b128 v[196:199], v150 offset:3072
	ds_read_b128 v[200:203], v150 offset:4096
	ds_read_b128 v[204:207], v150 offset:5120
	ds_read_b128 v[208:211], v150 offset:6144
	ds_read_b128 v[212:215], v150 offset:7168
	s_add_u32 s40, s64, s38
	s_addc_u32 s41, s65, s39
	s_add_u32 s44, s40, 0x10000
	s_addc_u32 s45, s41, 0
	s_add_i32 s67, s67, 2
	s_add_u32 s42, s62, s38
	s_addc_u32 s43, s63, s39
	s_add_u32 s40, s40, 0x18000
	s_addc_u32 s41, s41, 0
	s_cmp_eq_u32 s66, s38
	s_cselect_b32 s41, s59, s41
	s_cselect_b32 s40, s58, s40
	s_cselect_b32 s43, s4, s43
	s_cselect_b32 s42, s5, s42
	s_cselect_b32 s45, s57, s45
	s_cselect_b32 s44, s35, s44
	v_lshl_add_u64 v[216:217], v[142:143], 0, s[38:39]
	s_add_i32 m0, s49, 0xc000
	s_nop 0
	global_load_lds_dwordx4 v[216:217], off
	v_lshl_add_u64 v[216:217], v[144:145], 0, s[38:39]
	s_add_i32 m0, s49, 0xe000
	s_nop 0
	global_load_lds_dwordx4 v[216:217], off
	s_waitcnt vmcnt(8) lgkmcnt(0)
	s_barrier
; #define PG8_STAGE(bufoff, gbase, voff) do { _Pragma("unroll") for (int _i = 0; _i < 2; ++_i) \
;         __builtin_amdgcn_global_load_lds((const unsigned*)((const char*)(gbase) + (voff)[_i]), (LAS unsigned*)(lds + (bufoff) + ldsw + _i * 8192), 16, 0, 0); } while (0)
; #define PG8_LDA(dst, b, h) do { _Pragma("unroll") for (int m = 0; m < 4; ++m) _Pragma("unroll") for (int k = 0; k < 2; ++k) dst[m][k] = *(const LAS bf16x8*)(lds + PG8_SA(b, h) + aoff + m * 2048 + k * 1024); } while (0)
; #define PG8_LDB(dst, b, h) do { _Pragma("unroll") for (int n = 0; n < 2; ++n) _Pragma("unroll") for (int k = 0; k < 2; ++k) dst[n][k] = *(const LAS bf16x8*)(lds + PG8_SB(b, h) + boff + n * 2048 + k * 1024); } while (0)
; #define PG8_MMA(ai, bj, At, Bt) do { __builtin_amdgcn_s_setprio(1); _Pragma("unroll") for (int m = 0; m < 4; ++m) _Pragma("unroll") for (int n = 0; n < 2; ++n) _Pragma("unroll") for (int k = 0; k < 2; ++k) \
;         acc[ai][bj][m][n] = __builtin_amdgcn_mfma_f32_16x16x32_bf16(Bt[n][k], At[m][k], acc[ai][bj][m][n], 0, 0, 0); __builtin_amdgcn_s_setprio(0); } while (0)
; #define PG8_WAIT_V(n) asm volatile("s_waitcnt vmcnt(" #n ")" ::: "memory")
; #define PG8_WAIT_L(n) asm volatile("s_waitcnt lgkmcnt(" #n ")" ::: "memory")
; #define PG8_BAR __builtin_amdgcn_s_barrier()
; #define PG8_SCHED __builtin_amdgcn_sched_barrier(0)
; template <class Epi, class Sched, bool ABLK = false, bool ALIGN_EPI = true, bool SP2 = true, bool BBLK = true>
; __device__ __forceinline__ void gemm_phase(LAS unsigned char* lds, const Gemm g, const Sched& S, const Epi& E) {
;     ...
;             PG8_LDB(B0, 0, 0); PG8_LDB(B1, 0, 1); PG8_SCHED; PG8_LDA(At, 0, 0); PG8_STAGE(PG8_SA(1, 1), a1 + hstepA, voffA);
;             PG8_WAIT_V(8); PG8_WAIT_L(0); PG8_BAR; PG8_MMA(0, 0, At, B0); PG8_MMA(0, 1, At, B1); PG8_BAR; PG8_SCHED;
;             PG8_LDA(At, 0, 1); PG8_STAGE(PG8_SB(0, 0), b2, voffB); PG8_STAGE(PG8_SB(0, 1), b2 + hstepB, voffB); PG8_STAGE(PG8_SA(0, 0), a2, voffA);
;             PG8_WAIT_V(8); PG8_WAIT_L(0); PG8_BAR; PG8_MMA(1, 0, At, B0); PG8_MMA(1, 1, At, B1); PG8_BAR; PG8_SCHED;
	v_mfma_f32_16x16x32_bf16 v[126:129], v[152:155], v[184:187], v[126:129]
	v_mfma_f32_16x16x32_bf16 v[122:125], v[160:163], v[184:187], v[122:125]
	v_mfma_f32_16x16x32_bf16 v[110:113], v[152:155], v[192:195], v[110:113]
	v_mfma_f32_16x16x32_bf16 v[106:109], v[160:163], v[192:195], v[106:109]
	v_mfma_f32_16x16x32_bf16 v[94:97], v[152:155], v[200:203], v[94:97]
	v_mfma_f32_16x16x32_bf16 v[90:93], v[160:163], v[200:203], v[90:93]
	v_mfma_f32_16x16x32_bf16 v[78:81], v[152:155], v[208:211], v[78:81]
	v_mfma_f32_16x16x32_bf16 v[74:77], v[160:163], v[208:211], v[74:77]
	v_mfma_f32_16x16x32_bf16 v[126:129], v[156:159], v[188:191], v[126:129]
	v_mfma_f32_16x16x32_bf16 v[122:125], v[164:167], v[188:191], v[122:125]
	v_mfma_f32_16x16x32_bf16 v[110:113], v[156:159], v[196:199], v[110:113]
	v_mfma_f32_16x16x32_bf16 v[106:109], v[164:167], v[196:199], v[106:109]
	v_mfma_f32_16x16x32_bf16 v[94:97], v[156:159], v[204:207], v[94:97]
	v_mfma_f32_16x16x32_bf16 v[90:93], v[164:167], v[204:207], v[90:93]
	v_mfma_f32_16x16x32_bf16 v[78:81], v[156:159], v[212:215], v[78:81]
	v_mfma_f32_16x16x32_bf16 v[74:77], v[164:167], v[212:215], v[74:77]
	v_mfma_f32_16x16x32_bf16 v[118:121], v[168:171], v[184:187], v[118:121]
	v_mfma_f32_16x16x32_bf16 v[114:117], v[176:179], v[184:187], v[114:117]
	v_mfma_f32_16x16x32_bf16 v[102:105], v[168:171], v[192:195], v[102:105]
	v_mfma_f32_16x16x32_bf16 v[98:101], v[176:179], v[192:195], v[98:101]
	v_mfma_f32_16x16x32_bf16 v[86:89], v[168:171], v[200:203], v[86:89]
	v_mfma_f32_16x16x32_bf16 v[82:85], v[176:179], v[200:203], v[82:85]
	v_mfma_f32_16x16x32_bf16 v[70:73], v[168:171], v[208:211], v[70:73]
	v_mfma_f32_16x16x32_bf16 v[66:69], v[176:179], v[208:211], v[66:69]
	v_mfma_f32_16x16x32_bf16 v[118:121], v[172:175], v[188:191], v[118:121]
	v_mfma_f32_16x16x32_bf16 v[114:117], v[180:183], v[188:191], v[114:117]
	v_mfma_f32_16x16x32_bf16 v[102:105], v[172:175], v[196:199], v[102:105]
	v_mfma_f32_16x16x32_bf16 v[98:101], v[180:183], v[196:199], v[98:101]
	v_mfma_f32_16x16x32_bf16 v[86:89], v[172:175], v[204:207], v[86:89]
	v_mfma_f32_16x16x32_bf16 v[82:85], v[180:183], v[204:207], v[82:85]
	v_mfma_f32_16x16x32_bf16 v[70:73], v[172:175], v[212:215], v[70:73]
	v_mfma_f32_16x16x32_bf16 v[66:69], v[180:183], v[212:215], v[66:69]
	s_barrier
	ds_read_b128 v[184:187], v150 offset:16384
	ds_read_b128 v[188:191], v150 offset:17408
	ds_read_b128 v[192:195], v150 offset:18432
	ds_read_b128 v[196:199], v150 offset:19456
	ds_read_b128 v[200:203], v150 offset:20480
	ds_read_b128 v[204:207], v150 offset:21504
	ds_read_b128 v[208:211], v150 offset:22528
	ds_read_b128 v[212:215], v150 offset:23552
	s_add_i32 s70, s72, s48
	s_mov_b32 m0, s70
	s_nop 0
	global_load_lds_dwordx4 v130, s[42:43]
	s_add_i32 m0, s70, 0x2000
	s_add_u32 s76, s42, 0x4000
	s_addc_u32 s77, s43, 0
	s_add_i32 s70, s73, s48
	global_load_lds_dwordx4 v132, s[42:43]
	s_mov_b32 m0, s70
	s_nop 0
	global_load_lds_dwordx4 v130, s[76:77]
	s_add_i32 m0, s70, 0x2000
	s_nop 0
	global_load_lds_dwordx4 v132, s[76:77]
	s_mov_b32 m0, s49
	s_nop 0
	global_load_lds_dwordx4 v130, s[44:45]
	s_mov_b32 m0, s50
	s_nop 0
	global_load_lds_dwordx4 v132, s[44:45]
	s_waitcnt vmcnt(8) lgkmcnt(0)
	s_barrier
	v_mfma_f32_16x16x32_bf16 v[62:65], v[152:155], v[184:187], v[62:65]
	v_mfma_f32_16x16x32_bf16 v[58:61], v[160:163], v[184:187], v[58:61]
	v_mfma_f32_16x16x32_bf16 v[46:49], v[152:155], v[192:195], v[46:49]
	v_mfma_f32_16x16x32_bf16 v[42:45], v[160:163], v[192:195], v[42:45]
	v_mfma_f32_16x16x32_bf16 v[30:33], v[152:155], v[200:203], v[30:33]
	v_mfma_f32_16x16x32_bf16 v[26:29], v[160:163], v[200:203], v[26:29]
	v_mfma_f32_16x16x32_bf16 v[14:17], v[152:155], v[208:211], v[14:17]
	v_mfma_f32_16x16x32_bf16 v[10:13], v[160:163], v[208:211], v[10:13]
	v_mfma_f32_16x16x32_bf16 v[62:65], v[156:159], v[188:191], v[62:65]
	v_mfma_f32_16x16x32_bf16 v[58:61], v[164:167], v[188:191], v[58:61]
	v_mfma_f32_16x16x32_bf16 v[46:49], v[156:159], v[196:199], v[46:49]
	v_mfma_f32_16x16x32_bf16 v[42:45], v[164:167], v[196:199], v[42:45]
	v_mfma_f32_16x16x32_bf16 v[30:33], v[156:159], v[204:207], v[30:33]
	v_mfma_f32_16x16x32_bf16 v[26:29], v[164:167], v[204:207], v[26:29]
	v_mfma_f32_16x16x32_bf16 v[14:17], v[156:159], v[212:215], v[14:17]
	v_mfma_f32_16x16x32_bf16 v[10:13], v[164:167], v[212:215], v[10:13]
	v_mfma_f32_16x16x32_bf16 v[54:57], v[168:171], v[184:187], v[54:57]
	v_mfma_f32_16x16x32_bf16 v[50:53], v[176:179], v[184:187], v[50:53]
	v_mfma_f32_16x16x32_bf16 v[38:41], v[168:171], v[192:195], v[38:41]
	v_mfma_f32_16x16x32_bf16 v[34:37], v[176:179], v[192:195], v[34:37]
	v_mfma_f32_16x16x32_bf16 v[22:25], v[168:171], v[200:203], v[22:25]
	v_mfma_f32_16x16x32_bf16 v[18:21], v[176:179], v[200:203], v[18:21]
	v_mfma_f32_16x16x32_bf16 v[6:9], v[168:171], v[208:211], v[6:9]
	v_mfma_f32_16x16x32_bf16 v[2:5], v[176:179], v[208:211], v[2:5]
	v_mfma_f32_16x16x32_bf16 v[54:57], v[172:175], v[188:191], v[54:57]
	v_mfma_f32_16x16x32_bf16 v[50:53], v[180:183], v[188:191], v[50:53]
	v_mfma_f32_16x16x32_bf16 v[38:41], v[172:175], v[196:199], v[38:41]
	v_mfma_f32_16x16x32_bf16 v[34:37], v[180:183], v[196:199], v[34:37]
	v_mfma_f32_16x16x32_bf16 v[22:25], v[172:175], v[204:207], v[22:25]
	v_mfma_f32_16x16x32_bf16 v[18:21], v[180:183], v[204:207], v[18:21]
	v_mfma_f32_16x16x32_bf16 v[6:9], v[172:175], v[212:215], v[6:9]
	v_mfma_f32_16x16x32_bf16 v[2:5], v[180:183], v[212:215], v[2:5]
	s_barrier
; #define PG8_STAGE(bufoff, gbase, voff) do { _Pragma("unroll") for (int _i = 0; _i < 2; ++_i) \
;         __builtin_amdgcn_global_load_lds((const unsigned*)((const char*)(gbase) + (voff)[_i]), (LAS unsigned*)(lds + (bufoff) + ldsw + _i * 8192), 16, 0, 0); } while (0)
; #define PG8_LDA(dst, b, h) do { _Pragma("unroll") for (int m = 0; m < 4; ++m) _Pragma("unroll") for (int k = 0; k < 2; ++k) dst[m][k] = *(const LAS bf16x8*)(lds + PG8_SA(b, h) + aoff + m * 2048 + k * 1024); } while (0)
; #define PG8_LDB(dst, b, h) do { _Pragma("unroll") for (int n = 0; n < 2; ++n) _Pragma("unroll") for (int k = 0; k < 2; ++k) dst[n][k] = *(const LAS bf16x8*)(lds + PG8_SB(b, h) + boff + n * 2048 + k * 1024); } while (0)
; #define PG8_MMA(ai, bj, At, Bt) do { __builtin_amdgcn_s_setprio(1); _Pragma("unroll") for (int m = 0; m < 4; ++m) _Pragma("unroll") for (int n = 0; n < 2; ++n) _Pragma("unroll") for (int k = 0; k < 2; ++k) \
;         acc[ai][bj][m][n] = __builtin_amdgcn_mfma_f32_16x16x32_bf16(Bt[n][k], At[m][k], acc[ai][bj][m][n], 0, 0, 0); __builtin_amdgcn_s_setprio(0); } while (0)
; #define PG8_WAIT_V(n) asm volatile("s_waitcnt vmcnt(" #n ")" ::: "memory")
; #define PG8_WAIT_L(n) asm volatile("s_waitcnt lgkmcnt(" #n ")" ::: "memory")
; #define PG8_BAR __builtin_amdgcn_s_barrier()
; #define PG8_SCHED __builtin_amdgcn_sched_barrier(0)
; template <class Epi, class Sched, bool ABLK = false, bool ALIGN_EPI = true, bool SP2 = true, bool BBLK = true>
; __device__ __forceinline__ void gemm_phase(LAS unsigned char* lds, const Gemm g, const Sched& S, const Epi& E) {
;     ...
;             PG8_LDB(B0, 1, 0); PG8_LDB(B1, 1, 1); PG8_SCHED; PG8_LDA(At, 1, 0); PG8_STAGE(PG8_SA(0, 1), a2 + hstepA, voffA);
;             PG8_WAIT_V(8); PG8_WAIT_L(0); PG8_BAR; PG8_MMA(0, 0, At, B0); PG8_MMA(0, 1, At, B1); PG8_BAR; PG8_SCHED;
;             PG8_LDA(At, 1, 1); PG8_STAGE(PG8_SB(1, 0), b3, voffB); PG8_STAGE(PG8_SB(1, 1), b3 + hstepB, voffB); PG8_STAGE(PG8_SA(1, 0), a3, voffA);
;             PG8_WAIT_V(8); PG8_WAIT_L(0); PG8_BAR; PG8_MMA(1, 0, At, B0); PG8_MMA(1, 1, At, B1); PG8_BAR; PG8_SCHED;
;     ...
;         if constexpr (ALIGN_EPI) { if (wr == 0) PG8_BAR; }
	v_add_u32_e32 v151, s60, v146
	ds_read_b128 v[152:155], v151
	ds_read_b128 v[156:159], v151 offset:1024
	ds_read_b128 v[160:163], v151 offset:2048
	ds_read_b128 v[164:167], v151 offset:3072
	v_add_u32_e32 v151, s61, v146
	ds_read_b128 v[168:171], v151
	ds_read_b128 v[172:175], v151 offset:1024
	ds_read_b128 v[176:179], v151 offset:2048
	ds_read_b128 v[180:183], v151 offset:3072
	ds_read_b128 v[184:187], v150 offset:32768
	ds_read_b128 v[188:191], v150 offset:33792
	ds_read_b128 v[192:195], v150 offset:34816
	ds_read_b128 v[196:199], v150 offset:35840
	ds_read_b128 v[200:203], v150 offset:36864
	ds_read_b128 v[204:207], v150 offset:37888
	ds_read_b128 v[208:211], v150 offset:38912
	ds_read_b128 v[212:215], v150 offset:39936
	s_add_u32 s44, s44, 0x4000
	s_addc_u32 s45, s45, 0
	s_mov_b32 m0, s51
	s_nop 0
	global_load_lds_dwordx4 v130, s[44:45]
	s_mov_b32 m0, s52
	s_nop 0
	global_load_lds_dwordx4 v132, s[44:45]
	s_waitcnt vmcnt(8) lgkmcnt(0)
	s_barrier
	v_mfma_f32_16x16x32_bf16 v[126:129], v[152:155], v[184:187], v[126:129]
	v_mfma_f32_16x16x32_bf16 v[122:125], v[160:163], v[184:187], v[122:125]
	v_mfma_f32_16x16x32_bf16 v[110:113], v[152:155], v[192:195], v[110:113]
	v_mfma_f32_16x16x32_bf16 v[106:109], v[160:163], v[192:195], v[106:109]
	v_mfma_f32_16x16x32_bf16 v[94:97], v[152:155], v[200:203], v[94:97]
	v_mfma_f32_16x16x32_bf16 v[90:93], v[160:163], v[200:203], v[90:93]
	v_mfma_f32_16x16x32_bf16 v[78:81], v[152:155], v[208:211], v[78:81]
	v_mfma_f32_16x16x32_bf16 v[74:77], v[160:163], v[208:211], v[74:77]
	v_mfma_f32_16x16x32_bf16 v[126:129], v[156:159], v[188:191], v[126:129]
	v_mfma_f32_16x16x32_bf16 v[122:125], v[164:167], v[188:191], v[122:125]
	v_mfma_f32_16x16x32_bf16 v[110:113], v[156:159], v[196:199], v[110:113]
	v_mfma_f32_16x16x32_bf16 v[106:109], v[164:167], v[196:199], v[106:109]
	v_mfma_f32_16x16x32_bf16 v[94:97], v[156:159], v[204:207], v[94:97]
	v_mfma_f32_16x16x32_bf16 v[90:93], v[164:167], v[204:207], v[90:93]
	v_mfma_f32_16x16x32_bf16 v[78:81], v[156:159], v[212:215], v[78:81]
	v_mfma_f32_16x16x32_bf16 v[74:77], v[164:167], v[212:215], v[74:77]
	v_mfma_f32_16x16x32_bf16 v[118:121], v[168:171], v[184:187], v[118:121]
	v_mfma_f32_16x16x32_bf16 v[114:117], v[176:179], v[184:187], v[114:117]
	v_mfma_f32_16x16x32_bf16 v[102:105], v[168:171], v[192:195], v[102:105]
	v_mfma_f32_16x16x32_bf16 v[98:101], v[176:179], v[192:195], v[98:101]
	v_mfma_f32_16x16x32_bf16 v[86:89], v[168:171], v[200:203], v[86:89]
	v_mfma_f32_16x16x32_bf16 v[82:85], v[176:179], v[200:203], v[82:85]
	v_mfma_f32_16x16x32_bf16 v[70:73], v[168:171], v[208:211], v[70:73]
	v_mfma_f32_16x16x32_bf16 v[66:69], v[176:179], v[208:211], v[66:69]
	v_mfma_f32_16x16x32_bf16 v[118:121], v[172:175], v[188:191], v[118:121]
	v_mfma_f32_16x16x32_bf16 v[114:117], v[180:183], v[188:191], v[114:117]
	v_mfma_f32_16x16x32_bf16 v[102:105], v[172:175], v[196:199], v[102:105]
	v_mfma_f32_16x16x32_bf16 v[98:101], v[180:183], v[196:199], v[98:101]
	v_mfma_f32_16x16x32_bf16 v[86:89], v[172:175], v[204:207], v[86:89]
	v_mfma_f32_16x16x32_bf16 v[82:85], v[180:183], v[204:207], v[82:85]
	v_mfma_f32_16x16x32_bf16 v[70:73], v[172:175], v[212:215], v[70:73]
	v_mfma_f32_16x16x32_bf16 v[66:69], v[180:183], v[212:215], v[66:69]
	s_barrier
	ds_read_b128 v[184:187], v150 offset:49152
	ds_read_b128 v[188:191], v150 offset:50176
	ds_read_b128 v[192:195], v150 offset:51200
	ds_read_b128 v[196:199], v150 offset:52224
	ds_read_b128 v[200:203], v150 offset:53248
	ds_read_b128 v[204:207], v150 offset:54272
	ds_read_b128 v[208:211], v150 offset:55296
	ds_read_b128 v[212:215], v150 offset:56320
	s_add_u32 s44, s42, 0x8000
	s_addc_u32 s45, s43, 0
	s_add_i32 s70, s60, s48
	s_mov_b32 m0, s70
	s_nop 0
	global_load_lds_dwordx4 v130, s[44:45]
	s_add_i32 m0, s70, 0x2000
	s_add_u32 s42, s42, 0xc000
	v_lshl_add_u64 v[216:217], s[44:45], 0, v[132:133]
	s_addc_u32 s43, s43, 0
	s_add_i32 s44, s61, s48
	global_load_lds_dwordx4 v[216:217], off
	s_mov_b32 m0, s44
	s_nop 0
	global_load_lds_dwordx4 v130, s[42:43]
	s_add_i32 m0, s44, 0x2000
	s_nop 0
	global_load_lds_dwordx4 v132, s[42:43]
	s_mov_b32 m0, s53
	s_nop 0
	global_load_lds_dwordx4 v130, s[40:41]
	s_mov_b32 m0, s54
	s_nop 0
	global_load_lds_dwordx4 v132, s[40:41]
	s_waitcnt vmcnt(8) lgkmcnt(0)
	s_barrier
	v_mfma_f32_16x16x32_bf16 v[62:65], v[152:155], v[184:187], v[62:65]
	v_mfma_f32_16x16x32_bf16 v[58:61], v[160:163], v[184:187], v[58:61]
	v_mfma_f32_16x16x32_bf16 v[46:49], v[152:155], v[192:195], v[46:49]
	v_mfma_f32_16x16x32_bf16 v[42:45], v[160:163], v[192:195], v[42:45]
	v_mfma_f32_16x16x32_bf16 v[30:33], v[152:155], v[200:203], v[30:33]
	v_mfma_f32_16x16x32_bf16 v[26:29], v[160:163], v[200:203], v[26:29]
	v_mfma_f32_16x16x32_bf16 v[14:17], v[152:155], v[208:211], v[14:17]
	v_mfma_f32_16x16x32_bf16 v[10:13], v[160:163], v[208:211], v[10:13]
	v_mfma_f32_16x16x32_bf16 v[62:65], v[156:159], v[188:191], v[62:65]
	v_mfma_f32_16x16x32_bf16 v[58:61], v[164:167], v[188:191], v[58:61]
	v_mfma_f32_16x16x32_bf16 v[46:49], v[156:159], v[196:199], v[46:49]
	v_mfma_f32_16x16x32_bf16 v[42:45], v[164:167], v[196:199], v[42:45]
	v_mfma_f32_16x16x32_bf16 v[30:33], v[156:159], v[204:207], v[30:33]
	v_mfma_f32_16x16x32_bf16 v[26:29], v[164:167], v[204:207], v[26:29]
	v_mfma_f32_16x16x32_bf16 v[14:17], v[156:159], v[212:215], v[14:17]
	v_mfma_f32_16x16x32_bf16 v[10:13], v[164:167], v[212:215], v[10:13]
	v_mfma_f32_16x16x32_bf16 v[54:57], v[168:171], v[184:187], v[54:57]
	v_mfma_f32_16x16x32_bf16 v[50:53], v[176:179], v[184:187], v[50:53]
	v_mfma_f32_16x16x32_bf16 v[38:41], v[168:171], v[192:195], v[38:41]
	v_mfma_f32_16x16x32_bf16 v[34:37], v[176:179], v[192:195], v[34:37]
	v_mfma_f32_16x16x32_bf16 v[22:25], v[168:171], v[200:203], v[22:25]
	v_mfma_f32_16x16x32_bf16 v[18:21], v[176:179], v[200:203], v[18:21]
	v_mfma_f32_16x16x32_bf16 v[6:9], v[168:171], v[208:211], v[6:9]
	v_mfma_f32_16x16x32_bf16 v[2:5], v[176:179], v[208:211], v[2:5]
	v_mfma_f32_16x16x32_bf16 v[54:57], v[172:175], v[188:191], v[54:57]
	v_mfma_f32_16x16x32_bf16 v[50:53], v[180:183], v[188:191], v[50:53]
	v_mfma_f32_16x16x32_bf16 v[38:41], v[172:175], v[196:199], v[38:41]
	v_mfma_f32_16x16x32_bf16 v[34:37], v[180:183], v[196:199], v[34:37]
	v_mfma_f32_16x16x32_bf16 v[22:25], v[172:175], v[204:207], v[22:25]
	v_mfma_f32_16x16x32_bf16 v[18:21], v[180:183], v[204:207], v[18:21]
	v_mfma_f32_16x16x32_bf16 v[6:9], v[172:175], v[212:215], v[6:9]
	v_mfma_f32_16x16x32_bf16 v[2:5], v[180:183], v[212:215], v[2:5]
	s_barrier
	s_add_u32 s38, s38, 0x10000
	s_addc_u32 s39, s39, 0
	s_cmp_ge_u32 s67, s56
	s_cbranch_scc0 .LBB0_2328
	s_and_b64 vcc, exec, s[14:15]
	s_cbranch_vccz .LBB0_2331
	s_barrier
